# GEMM loops: the lgkmcnt(0) for the phase's fragments is waited before the pre-MFMA barrier so the first MFMA issues right at release; on top of v20
# baseline (speedup 1.0000x reference)
; #define PG8_STAGE(bufoff, gbase, voff) do { _Pragma("unroll") for (int _i = 0; _i < 2; ++_i) \
;         __builtin_amdgcn_global_load_lds((const unsigned*)((const char*)(gbase) + (voff)[_i]), (LAS unsigned*)(lds + (bufoff) + ldsw + _i * 8192), 16, 0, 0); } while (0)
; #define PG8_LDA(dst, b, h) do { _Pragma("unroll") for (int m = 0; m < 4; ++m) _Pragma("unroll") for (int k = 0; k < 2; ++k) dst[m][k] = *(const LAS bf16x8*)(lds + PG8_SA(b, h) + aoff + m * 2048 + k * 1024); } while (0)
; #define PG8_LDB(dst, b, h) do { _Pragma("unroll") for (int n = 0; n < 2; ++n) _Pragma("unroll") for (int k = 0; k < 2; ++k) dst[n][k] = *(const LAS bf16x8*)(lds + PG8_SB(b, h) + boff + n * 2048 + k * 1024); } while (0)
; #define PG8_WAIT_V(n) asm volatile("s_waitcnt vmcnt(" #n ")" ::: "memory")
; #define PG8_WAIT_L(n) asm volatile("s_waitcnt lgkmcnt(" #n ")" ::: "memory")
; #define PG8_BAR __builtin_amdgcn_s_barrier()
; #define PG8_SCHED __builtin_amdgcn_sched_barrier(0)
; template <class Epi, class Sched>
; __device__ __forceinline__ void gemm_phase(LAS unsigned char* lds, const Gemm g, const Sched& S, const Epi& E) {
;     ...
;         const bool has_next = S.next(ui + 1, nxt);
;         const char* nA = has_next ? (const char*)g.A + (size_t)nxt.pm * tstep : cA; const char* nB = has_next ? (const char*)g.Bt + (size_t)nxt.pn * tstep : cB;
;         for (int t = 0; t < nt; t += 2) {
;             const bool last = (t == nt - 2);
;             const char* a1 = cA + (size_t)(t + 1) * kstep;
;             const char* a2 = last ? nA : cA + (size_t)(t + 2) * kstep; const char* b2 = last ? nB : cB + (size_t)(t + 2) * kstep;
;             const char* a3 = a2 + kstep; const char* b3 = b2 + kstep;
;             PG8_LDB(B0, 0, 0); PG8_SCHED; PG8_LDA(At, 0, 0); PG8_STAGE(PG8_SA(1, 1), a1 + hstep, voffA);
;             PG8_WAIT_L(8); PG8_BAR; PG8_WAIT_L(0); PG8_MMA(0, 0, At, B0); PG8_BAR; PG8_SCHED;
;             PG8_LDB(B1, 0, 1); PG8_STAGE(PG8_SB(0, 0), b2, voffB);
;             PG8_BAR; PG8_WAIT_L(0); PG8_MMA(0, 1, At, B1); PG8_BAR;
;             PG8_LDA(At, 0, 1); PG8_STAGE(PG8_SA(0, 0), a2, voffA);
;             PG8_BAR; PG8_WAIT_L(0); PG8_MMA(1, 0, At, B0); PG8_BAR; PG8_SCHED;
;             PG8_STAGE(PG8_SB(0, 1), b2 + hstep, voffB);
;             PG8_WAIT_V(6); PG8_BAR; PG8_MMA(1, 1, At, B1); PG8_BAR;
.LBB0_234:
	s_ashr_i32 s7, s6, 31
	v_cmp_lt_i64_e32 vcc, s[8:9], v[140:141]
	s_lshl_b64 s[8:9], s[6:7], 19
	s_add_u32 s8, s96, s8
	s_addc_u32 s9, s97, s9
	s_and_b64 s[10:11], vcc, exec
	s_cselect_b32 s7, s9, s15
	s_cselect_b32 s44, s8, s14
	s_ashr_i32 s5, s4, 31
	s_lshl_b64 s[10:11], s[4:5], 19
	s_add_u32 s10, s72, s10
	s_addc_u32 s11, s73, s11
	s_and_b64 s[16:17], vcc, exec
	s_cselect_b32 s5, s11, s19
	s_cselect_b32 s45, s10, s18
	s_add_u32 s14, s14, 0x40080
	s_addc_u32 s15, s15, 0
	s_add_u32 s46, s18, 0x100
	s_addc_u32 s47, s19, 0
	s_mov_b32 s48, -2
	ds_read_b128 v[150:153], v147
	ds_read_b128 v[154:157], v147 offset:1024
	ds_read_b128 v[158:161], v147 offset:2048
	ds_read_b128 v[162:165], v147 offset:3072
	s_add_u32 s16, s14, 0xfffc0080
	s_addc_u32 s17, s15, -1
	s_cmp_eq_u32 s48, 12
	s_cselect_b32 s23, s7, s17
	s_cselect_b32 s22, s44, s16
	s_cselect_b32 s19, s5, s47
	s_cselect_b32 s18, s45, s46
	s_add_i32 m0, s13, 0xc000
	ds_read_b128 v[166:169], v148
	ds_read_b128 v[170:173], v148 offset:1024
	ds_read_b128 v[174:177], v148 offset:2048
	ds_read_b128 v[178:181], v148 offset:3072
	ds_read_b128 v[182:185], v148 offset:4096
	ds_read_b128 v[186:189], v148 offset:5120
	ds_read_b128 v[190:193], v148 offset:6144
	ds_read_b128 v[194:197], v148 offset:7168
	global_load_lds_dwordx4 v136, s[14:15]
	s_add_i32 m0, s13, 0xe000
	s_nop 0
	global_load_lds_dwordx4 v138, s[14:15]
	s_waitcnt lgkmcnt(8)
	s_waitcnt vmcnt(8)
	s_waitcnt lgkmcnt(0)
	s_setprio 1
	s_barrier
	v_mfma_f32_16x16x32_bf16 v[124:127], v[150:153], v[166:169], 0
	v_mfma_f32_16x16x32_bf16 v[116:119], v[158:161], v[166:169], 0
	v_mfma_f32_16x16x32_bf16 v[108:111], v[150:153], v[174:177], 0
	v_mfma_f32_16x16x32_bf16 v[100:103], v[158:161], v[174:177], 0
	v_mfma_f32_16x16x32_bf16 v[92:95], v[150:153], v[182:185], 0
	v_mfma_f32_16x16x32_bf16 v[84:87], v[158:161], v[182:185], 0
	v_mfma_f32_16x16x32_bf16 v[76:79], v[150:153], v[190:193], 0
	v_mfma_f32_16x16x32_bf16 v[68:71], v[158:161], v[190:193], 0
	v_mfma_f32_16x16x32_bf16 v[124:127], v[154:157], v[170:173], v[124:127]
	v_mfma_f32_16x16x32_bf16 v[116:119], v[162:165], v[170:173], v[116:119]
	v_mfma_f32_16x16x32_bf16 v[108:111], v[154:157], v[178:181], v[108:111]
	v_mfma_f32_16x16x32_bf16 v[100:103], v[162:165], v[178:181], v[100:103]
	v_mfma_f32_16x16x32_bf16 v[92:95], v[154:157], v[186:189], v[92:95]
	v_mfma_f32_16x16x32_bf16 v[84:87], v[162:165], v[186:189], v[84:87]
	v_mfma_f32_16x16x32_bf16 v[76:79], v[154:157], v[194:197], v[76:79]
	v_mfma_f32_16x16x32_bf16 v[68:71], v[162:165], v[194:197], v[68:71]
	s_barrier
	s_setprio 0
	s_add_i32 s16, s40, s25
	s_mov_b32 m0, s16
	ds_read_b128 v[202:205], v149
	ds_read_b128 v[206:209], v149 offset:1024
	ds_read_b128 v[210:213], v149 offset:2048
	ds_read_b128 v[214:217], v149 offset:3072
	global_load_lds_dwordx4 v132, s[18:19]
	s_add_i32 m0, s16, 0x2000
	s_nop 0
	global_load_lds_dwordx4 v128, s[18:19]
	s_waitcnt vmcnt(8)
	s_waitcnt lgkmcnt(0)
	s_setprio 1
	s_barrier
	v_mfma_f32_16x16x32_bf16 v[120:123], v[202:205], v[166:169], 0
	v_mfma_f32_16x16x32_bf16 v[112:115], v[210:213], v[166:169], 0
	v_mfma_f32_16x16x32_bf16 v[104:107], v[202:205], v[174:177], 0
	v_mfma_f32_16x16x32_bf16 v[96:99], v[210:213], v[174:177], 0
	v_mfma_f32_16x16x32_bf16 v[88:91], v[202:205], v[182:185], 0
	v_mfma_f32_16x16x32_bf16 v[80:83], v[210:213], v[182:185], 0
	v_mfma_f32_16x16x32_bf16 v[72:75], v[202:205], v[190:193], 0
	v_mfma_f32_16x16x32_bf16 v[64:67], v[210:213], v[190:193], 0
	v_mfma_f32_16x16x32_bf16 v[120:123], v[206:209], v[170:173], v[120:123]
	v_mfma_f32_16x16x32_bf16 v[112:115], v[214:217], v[170:173], v[112:115]
	v_mfma_f32_16x16x32_bf16 v[104:107], v[206:209], v[178:181], v[104:107]
	v_mfma_f32_16x16x32_bf16 v[96:99], v[214:217], v[178:181], v[96:99]
	v_mfma_f32_16x16x32_bf16 v[88:91], v[206:209], v[186:189], v[88:91]
	v_mfma_f32_16x16x32_bf16 v[80:83], v[214:217], v[186:189], v[80:83]
	v_mfma_f32_16x16x32_bf16 v[72:75], v[206:209], v[194:197], v[72:75]
	v_mfma_f32_16x16x32_bf16 v[64:67], v[214:217], v[194:197], v[64:67]
	s_mov_b32 m0, s13
	s_barrier
	s_setprio 0
	ds_read_b128 v[166:169], v148 offset:16384
	ds_read_b128 v[170:173], v148 offset:17408
	ds_read_b128 v[174:177], v148 offset:18432
	ds_read_b128 v[178:181], v148 offset:19456
	ds_read_b128 v[182:185], v148 offset:20480
	ds_read_b128 v[186:189], v148 offset:21504
	ds_read_b128 v[190:193], v148 offset:22528
	ds_read_b128 v[194:197], v148 offset:23552
	global_load_lds_dwordx4 v134, s[22:23]
	s_mov_b32 m0, s28
	s_nop 0
	global_load_lds_dwordx4 v130, s[22:23]
	s_waitcnt lgkmcnt(0)
	s_setprio 1
	s_barrier
	v_mfma_f32_16x16x32_bf16 v[60:63], v[150:153], v[166:169], 0
	v_mfma_f32_16x16x32_bf16 v[56:59], v[158:161], v[166:169], 0
	v_mfma_f32_16x16x32_bf16 v[44:47], v[150:153], v[174:177], 0
	v_mfma_f32_16x16x32_bf16 v[40:43], v[158:161], v[174:177], 0
	v_mfma_f32_16x16x32_bf16 v[28:31], v[150:153], v[182:185], 0
	v_mfma_f32_16x16x32_bf16 v[24:27], v[158:161], v[182:185], 0
	v_mfma_f32_16x16x32_bf16 v[12:15], v[150:153], v[190:193], 0
	v_mfma_f32_16x16x32_bf16 v[8:11], v[158:161], v[190:193], 0
	v_mfma_f32_16x16x32_bf16 v[60:63], v[154:157], v[170:173], v[60:63]
	v_mfma_f32_16x16x32_bf16 v[56:59], v[162:165], v[170:173], v[56:59]
	v_mfma_f32_16x16x32_bf16 v[44:47], v[154:157], v[178:181], v[44:47]
	v_mfma_f32_16x16x32_bf16 v[40:43], v[162:165], v[178:181], v[40:43]
	v_mfma_f32_16x16x32_bf16 v[28:31], v[154:157], v[186:189], v[28:31]
	v_mfma_f32_16x16x32_bf16 v[24:27], v[162:165], v[186:189], v[24:27]
	v_mfma_f32_16x16x32_bf16 v[12:15], v[154:157], v[194:197], v[12:15]
	v_mfma_f32_16x16x32_bf16 v[8:11], v[162:165], v[194:197], v[8:11]
	s_barrier
; #define PG8_STAGE(bufoff, gbase, voff) do { _Pragma("unroll") for (int _i = 0; _i < 2; ++_i) \
;         __builtin_amdgcn_global_load_lds((const unsigned*)((const char*)(gbase) + (voff)[_i]), (LAS unsigned*)(lds + (bufoff) + ldsw + _i * 8192), 16, 0, 0); } while (0)
; #define PG8_LDA(dst, b, h) do { _Pragma("unroll") for (int m = 0; m < 4; ++m) _Pragma("unroll") for (int k = 0; k < 2; ++k) dst[m][k] = *(const LAS bf16x8*)(lds + PG8_SA(b, h) + aoff + m * 2048 + k * 1024); } while (0)
; #define PG8_LDB(dst, b, h) do { _Pragma("unroll") for (int n = 0; n < 2; ++n) _Pragma("unroll") for (int k = 0; k < 2; ++k) dst[n][k] = *(const LAS bf16x8*)(lds + PG8_SB(b, h) + boff + n * 2048 + k * 1024); } while (0)
; #define PG8_MMA(ai, bj, At, Bt) do { __builtin_amdgcn_s_setprio(1); _Pragma("unroll") for (int m = 0; m < 4; ++m) _Pragma("unroll") for (int n = 0; n < 2; ++n) _Pragma("unroll") for (int k = 0; k < 2; ++k) \
;         acc[ai][bj][m][n] = __builtin_amdgcn_mfma_f32_16x16x32_bf16(Bt[n][k], At[m][k], acc[ai][bj][m][n], 0, 0, 0); __builtin_amdgcn_s_setprio(0); } while (0)
; #define PG8_WAIT_V(n) asm volatile("s_waitcnt vmcnt(" #n ")" ::: "memory")
; #define PG8_WAIT_L(n) asm volatile("s_waitcnt lgkmcnt(" #n ")" ::: "memory")
; #define PG8_BAR __builtin_amdgcn_s_barrier()
; #define PG8_SCHED __builtin_amdgcn_sched_barrier(0)
; template <class Epi, class Sched>
; __device__ __forceinline__ void gemm_phase(LAS unsigned char* lds, const Gemm g, const Sched& S, const Epi& E) {
;     ...
;             PG8_BAR; PG8_WAIT_L(0); PG8_MMA(1, 0, At, B0); PG8_BAR; PG8_SCHED;
;             PG8_STAGE(PG8_SB(0, 1), b2 + hstep, voffB);
;             PG8_WAIT_V(6); PG8_BAR; PG8_MMA(1, 1, At, B1); PG8_BAR;
;             PG8_LDB(B0, 1, 0); PG8_SCHED; PG8_LDA(At, 1, 0); PG8_STAGE(PG8_SA(0, 1), a2 + hstep, voffA);
;             PG8_WAIT_L(8); PG8_BAR; PG8_WAIT_L(0); PG8_MMA(0, 0, At, B0); PG8_BAR; PG8_SCHED;
;             PG8_LDB(B1, 1, 1); PG8_STAGE(PG8_SB(1, 0), b3, voffB);
;             PG8_BAR; PG8_WAIT_L(0); PG8_MMA(0, 1, At, B1); PG8_BAR;
;             PG8_LDA(At, 1, 1); PG8_STAGE(PG8_SA(1, 0), a3, voffA);
;             PG8_BAR; PG8_WAIT_L(0); PG8_MMA(1, 0, At, B0); PG8_BAR; PG8_SCHED;
	s_setprio 0
	s_add_u32 s16, s18, 0x40000
	s_addc_u32 s17, s19, 0
	s_add_i32 s20, s41, s25
	s_mov_b32 m0, s20
	s_nop 0
	global_load_lds_dwordx4 v132, s[16:17]
	s_add_i32 m0, s20, 0x2000
	s_nop 0
	global_load_lds_dwordx4 v128, s[16:17]
	s_add_u32 s16, s22, 0x40000
	s_addc_u32 s17, s23, 0
	s_mov_b32 m0, s29
	s_nop 0
	global_load_lds_dwordx4 v134, s[16:17]
	s_mov_b32 m0, s33
	s_nop 0
	global_load_lds_dwordx4 v130, s[16:17]
	s_waitcnt vmcnt(10)
	s_setprio 1
	s_barrier
	v_mfma_f32_16x16x32_bf16 v[52:55], v[202:205], v[166:169], 0
	v_mfma_f32_16x16x32_bf16 v[48:51], v[210:213], v[166:169], 0
	v_mfma_f32_16x16x32_bf16 v[36:39], v[202:205], v[174:177], 0
	v_mfma_f32_16x16x32_bf16 v[32:35], v[210:213], v[174:177], 0
	v_mfma_f32_16x16x32_bf16 v[20:23], v[202:205], v[182:185], 0
	v_mfma_f32_16x16x32_bf16 v[16:19], v[210:213], v[182:185], 0
	v_mfma_f32_16x16x32_bf16 v[4:7], v[202:205], v[190:193], 0
	v_mfma_f32_16x16x32_bf16 v[0:3], v[210:213], v[190:193], 0
	v_mfma_f32_16x16x32_bf16 v[52:55], v[206:209], v[170:173], v[52:55]
	v_mfma_f32_16x16x32_bf16 v[48:51], v[214:217], v[170:173], v[48:51]
	v_mfma_f32_16x16x32_bf16 v[36:39], v[206:209], v[178:181], v[36:39]
	v_mfma_f32_16x16x32_bf16 v[32:35], v[214:217], v[178:181], v[32:35]
	v_mfma_f32_16x16x32_bf16 v[20:23], v[206:209], v[186:189], v[20:23]
	v_mfma_f32_16x16x32_bf16 v[16:19], v[214:217], v[186:189], v[16:19]
	v_mfma_f32_16x16x32_bf16 v[4:7], v[206:209], v[194:197], v[4:7]
	v_mfma_f32_16x16x32_bf16 v[0:3], v[214:217], v[194:197], v[0:3]
	s_add_i32 s20, 0, 0x18000
	v_add_u32_e32 v162, s20, v146
	s_barrier
	s_setprio 0
	ds_read_b128 v[150:153], v162
	ds_read_b128 v[154:157], v162 offset:1024
	ds_read_b128 v[158:161], v162 offset:2048
	ds_read_b128 v[162:165], v162 offset:3072
	ds_read_b128 v[166:169], v148 offset:32768
	ds_read_b128 v[170:173], v148 offset:33792
	ds_read_b128 v[174:177], v148 offset:34816
	ds_read_b128 v[178:181], v148 offset:35840
	ds_read_b128 v[182:185], v148 offset:36864
	ds_read_b128 v[186:189], v148 offset:37888
	ds_read_b128 v[190:193], v148 offset:38912
	ds_read_b128 v[194:197], v148 offset:39936
	s_waitcnt lgkmcnt(8)
	s_waitcnt vmcnt(8)
	s_waitcnt lgkmcnt(0)
	s_setprio 1
	s_barrier
	v_mfma_f32_16x16x32_bf16 v[124:127], v[150:153], v[166:169], v[124:127]
	v_mfma_f32_16x16x32_bf16 v[116:119], v[158:161], v[166:169], v[116:119]
	v_mfma_f32_16x16x32_bf16 v[108:111], v[150:153], v[174:177], v[108:111]
	v_mfma_f32_16x16x32_bf16 v[100:103], v[158:161], v[174:177], v[100:103]
	v_mfma_f32_16x16x32_bf16 v[92:95], v[150:153], v[182:185], v[92:95]
	v_mfma_f32_16x16x32_bf16 v[84:87], v[158:161], v[182:185], v[84:87]
	v_mfma_f32_16x16x32_bf16 v[76:79], v[150:153], v[190:193], v[76:79]
	v_mfma_f32_16x16x32_bf16 v[68:71], v[158:161], v[190:193], v[68:71]
	v_mfma_f32_16x16x32_bf16 v[124:127], v[154:157], v[170:173], v[124:127]
	v_mfma_f32_16x16x32_bf16 v[116:119], v[162:165], v[170:173], v[116:119]
	v_mfma_f32_16x16x32_bf16 v[108:111], v[154:157], v[178:181], v[108:111]
	v_mfma_f32_16x16x32_bf16 v[100:103], v[162:165], v[178:181], v[100:103]
	v_mfma_f32_16x16x32_bf16 v[92:95], v[154:157], v[186:189], v[92:95]
	v_mfma_f32_16x16x32_bf16 v[84:87], v[162:165], v[186:189], v[84:87]
	v_mfma_f32_16x16x32_bf16 v[76:79], v[154:157], v[194:197], v[76:79]
	v_mfma_f32_16x16x32_bf16 v[68:71], v[162:165], v[194:197], v[68:71]
	s_barrier
	s_setprio 0
	s_add_i32 s21, 0, 0x1c000
	s_add_i32 s16, s20, s25
	v_add_u32_e32 v214, s21, v146
	s_add_u32 s0, s18, 0x80
	s_addc_u32 s1, s19, 0
	s_mov_b32 m0, s16
	ds_read_b128 v[202:205], v214
	ds_read_b128 v[206:209], v214 offset:1024
	ds_read_b128 v[210:213], v214 offset:2048
	ds_read_b128 v[214:217], v214 offset:3072
	global_load_lds_dwordx4 v132, s[0:1]
	s_add_i32 m0, s16, 0x2000
	s_nop 0
	global_load_lds_dwordx4 v128, s[0:1]
	s_waitcnt vmcnt(8)
	s_waitcnt lgkmcnt(0)
	s_setprio 1
	s_barrier
	v_mfma_f32_16x16x32_bf16 v[120:123], v[202:205], v[166:169], v[120:123]
	v_mfma_f32_16x16x32_bf16 v[112:115], v[210:213], v[166:169], v[112:115]
	v_mfma_f32_16x16x32_bf16 v[104:107], v[202:205], v[174:177], v[104:107]
	v_mfma_f32_16x16x32_bf16 v[96:99], v[210:213], v[174:177], v[96:99]
	v_mfma_f32_16x16x32_bf16 v[88:91], v[202:205], v[182:185], v[88:91]
	v_mfma_f32_16x16x32_bf16 v[80:83], v[210:213], v[182:185], v[80:83]
	v_mfma_f32_16x16x32_bf16 v[72:75], v[202:205], v[190:193], v[72:75]
	v_mfma_f32_16x16x32_bf16 v[64:67], v[210:213], v[190:193], v[64:67]
	v_mfma_f32_16x16x32_bf16 v[120:123], v[206:209], v[170:173], v[120:123]
	v_mfma_f32_16x16x32_bf16 v[112:115], v[214:217], v[170:173], v[112:115]
	v_mfma_f32_16x16x32_bf16 v[104:107], v[206:209], v[178:181], v[104:107]
	v_mfma_f32_16x16x32_bf16 v[96:99], v[214:217], v[178:181], v[96:99]
	v_mfma_f32_16x16x32_bf16 v[88:91], v[206:209], v[186:189], v[88:91]
	v_mfma_f32_16x16x32_bf16 v[80:83], v[214:217], v[186:189], v[80:83]
	v_mfma_f32_16x16x32_bf16 v[72:75], v[206:209], v[194:197], v[72:75]
	v_mfma_f32_16x16x32_bf16 v[64:67], v[214:217], v[194:197], v[64:67]
	s_mov_b32 m0, s36
	s_add_u32 s0, s22, 0x80
	s_addc_u32 s1, s23, 0
	s_barrier
	s_setprio 0
	ds_read_b128 v[166:169], v148 offset:49152
	ds_read_b128 v[170:173], v148 offset:50176
	ds_read_b128 v[174:177], v148 offset:51200
	ds_read_b128 v[178:181], v148 offset:52224
	ds_read_b128 v[182:185], v148 offset:53248
	ds_read_b128 v[186:189], v148 offset:54272
	ds_read_b128 v[190:193], v148 offset:55296
	ds_read_b128 v[194:197], v148 offset:56320
	global_load_lds_dwordx4 v134, s[0:1]
	s_mov_b32 m0, s37
	s_nop 0
	global_load_lds_dwordx4 v130, s[0:1]
	s_waitcnt lgkmcnt(0)
	s_setprio 1
	s_barrier
; #define PG8_STAGE(bufoff, gbase, voff) do { _Pragma("unroll") for (int _i = 0; _i < 2; ++_i) \
;         __builtin_amdgcn_global_load_lds((const unsigned*)((const char*)(gbase) + (voff)[_i]), (LAS unsigned*)(lds + (bufoff) + ldsw + _i * 8192), 16, 0, 0); } while (0)
; #define PG8_LDA(dst, b, h) do { _Pragma("unroll") for (int m = 0; m < 4; ++m) _Pragma("unroll") for (int k = 0; k < 2; ++k) dst[m][k] = *(const LAS bf16x8*)(lds + PG8_SA(b, h) + aoff + m * 2048 + k * 1024); } while (0)
; #define PG8_LDB(dst, b, h) do { _Pragma("unroll") for (int n = 0; n < 2; ++n) _Pragma("unroll") for (int k = 0; k < 2; ++k) dst[n][k] = *(const LAS bf16x8*)(lds + PG8_SB(b, h) + boff + n * 2048 + k * 1024); } while (0)
; #define PG8_MMA(ai, bj, At, Bt) do { __builtin_amdgcn_s_setprio(1); _Pragma("unroll") for (int m = 0; m < 4; ++m) _Pragma("unroll") for (int n = 0; n < 2; ++n) _Pragma("unroll") for (int k = 0; k < 2; ++k) \
;         acc[ai][bj][m][n] = __builtin_amdgcn_mfma_f32_16x16x32_bf16(Bt[n][k], At[m][k], acc[ai][bj][m][n], 0, 0, 0); __builtin_amdgcn_s_setprio(0); } while (0)
; #define PG8_WAIT_V(n) asm volatile("s_waitcnt vmcnt(" #n ")" ::: "memory")
; #define PG8_WAIT_L(n) asm volatile("s_waitcnt lgkmcnt(" #n ")" ::: "memory")
; #define PG8_BAR __builtin_amdgcn_s_barrier()
; #define PG8_SCHED __builtin_amdgcn_sched_barrier(0)
; template <class Epi, class Sched>
; __device__ __forceinline__ void gemm_phase(LAS unsigned char* lds, const Gemm g, const Sched& S, const Epi& E) {
;     ...
;             PG8_LDB(B0, 0, 0); PG8_SCHED; PG8_LDA(At, 0, 0); PG8_STAGE(PG8_SA(1, 1), a1 + hstep, voffA);
;             PG8_WAIT_L(8); PG8_BAR; PG8_WAIT_L(0); PG8_MMA(0, 0, At, B0); PG8_BAR; PG8_SCHED;
;             PG8_LDB(B1, 0, 1); PG8_STAGE(PG8_SB(0, 0), b2, voffB);
;             PG8_BAR; PG8_WAIT_L(0); PG8_MMA(0, 1, At, B1); PG8_BAR;
;             PG8_LDA(At, 0, 1); PG8_STAGE(PG8_SA(0, 0), a2, voffA);
;             PG8_BAR; PG8_WAIT_L(0); PG8_MMA(1, 0, At, B0); PG8_BAR; PG8_SCHED;
;     ...
;             PG8_BAR; PG8_WAIT_L(0); PG8_MMA(0, 1, At, B1); PG8_BAR;
;             PG8_LDA(At, 1, 1); PG8_STAGE(PG8_SA(1, 0), a3, voffA);
;             PG8_BAR; PG8_WAIT_L(0); PG8_MMA(1, 0, At, B0); PG8_BAR; PG8_SCHED;
;             PG8_STAGE(PG8_SB(1, 1), b3 + hstep, voffB);
;             PG8_WAIT_V(6); PG8_BAR; PG8_MMA(1, 1, At, B1); PG8_BAR;
	v_mfma_f32_16x16x32_bf16 v[60:63], v[150:153], v[166:169], v[60:63]
	v_mfma_f32_16x16x32_bf16 v[56:59], v[158:161], v[166:169], v[56:59]
	v_mfma_f32_16x16x32_bf16 v[44:47], v[150:153], v[174:177], v[44:47]
	v_mfma_f32_16x16x32_bf16 v[40:43], v[158:161], v[174:177], v[40:43]
	v_mfma_f32_16x16x32_bf16 v[28:31], v[150:153], v[182:185], v[28:31]
	v_mfma_f32_16x16x32_bf16 v[24:27], v[158:161], v[182:185], v[24:27]
	v_mfma_f32_16x16x32_bf16 v[12:15], v[150:153], v[190:193], v[12:15]
	v_mfma_f32_16x16x32_bf16 v[8:11], v[158:161], v[190:193], v[8:11]
	v_mfma_f32_16x16x32_bf16 v[60:63], v[154:157], v[170:173], v[60:63]
	v_mfma_f32_16x16x32_bf16 v[56:59], v[162:165], v[170:173], v[56:59]
	v_mfma_f32_16x16x32_bf16 v[44:47], v[154:157], v[178:181], v[44:47]
	v_mfma_f32_16x16x32_bf16 v[40:43], v[162:165], v[178:181], v[40:43]
	v_mfma_f32_16x16x32_bf16 v[28:31], v[154:157], v[186:189], v[28:31]
	v_mfma_f32_16x16x32_bf16 v[24:27], v[162:165], v[186:189], v[24:27]
	v_mfma_f32_16x16x32_bf16 v[12:15], v[154:157], v[194:197], v[12:15]
	v_mfma_f32_16x16x32_bf16 v[8:11], v[162:165], v[194:197], v[8:11]
	s_barrier
	s_setprio 0
	s_add_u32 s16, s18, 0x40080
	s_addc_u32 s17, s19, 0
	s_add_i32 s18, s21, s25
	s_mov_b32 m0, s18
	s_nop 0
	global_load_lds_dwordx4 v132, s[16:17]
	s_add_i32 m0, s18, 0x2000
	s_nop 0
	global_load_lds_dwordx4 v128, s[16:17]
	s_waitcnt vmcnt(8)
	s_setprio 1
	s_barrier
	v_mfma_f32_16x16x32_bf16 v[52:55], v[202:205], v[166:169], v[52:55]
	v_mfma_f32_16x16x32_bf16 v[48:51], v[210:213], v[166:169], v[48:51]
	v_mfma_f32_16x16x32_bf16 v[36:39], v[202:205], v[174:177], v[36:39]
	v_mfma_f32_16x16x32_bf16 v[32:35], v[210:213], v[174:177], v[32:35]
	v_mfma_f32_16x16x32_bf16 v[20:23], v[202:205], v[182:185], v[20:23]
	v_mfma_f32_16x16x32_bf16 v[16:19], v[210:213], v[182:185], v[16:19]
	v_mfma_f32_16x16x32_bf16 v[4:7], v[202:205], v[190:193], v[4:7]
	v_mfma_f32_16x16x32_bf16 v[0:3], v[210:213], v[190:193], v[0:3]
	v_mfma_f32_16x16x32_bf16 v[52:55], v[206:209], v[170:173], v[52:55]
	v_mfma_f32_16x16x32_bf16 v[48:51], v[214:217], v[170:173], v[48:51]
	v_mfma_f32_16x16x32_bf16 v[36:39], v[206:209], v[178:181], v[36:39]
	v_mfma_f32_16x16x32_bf16 v[32:35], v[214:217], v[178:181], v[32:35]
	v_mfma_f32_16x16x32_bf16 v[20:23], v[206:209], v[186:189], v[20:23]
	v_mfma_f32_16x16x32_bf16 v[16:19], v[214:217], v[186:189], v[16:19]
	v_mfma_f32_16x16x32_bf16 v[4:7], v[206:209], v[194:197], v[4:7]
	v_mfma_f32_16x16x32_bf16 v[0:3], v[214:217], v[194:197], v[0:3]
	s_add_i32 s48, s48, 2
	s_add_u32 s14, s14, 0x100
	s_addc_u32 s15, s15, 0
	s_add_u32 s46, s46, 0x100
	s_addc_u32 s47, s47, 0
	s_cmp_gt_u32 s48, 13
	s_barrier
	s_setprio 0
.LBB0_235:
	ds_read_b128 v[150:153], v147
	ds_read_b128 v[154:157], v147 offset:1024
	ds_read_b128 v[158:161], v147 offset:2048
	ds_read_b128 v[162:165], v147 offset:3072
	s_add_u32 s16, s14, 0xfffc0080
	s_addc_u32 s17, s15, -1
	s_cmp_eq_u32 s48, 12
	s_cselect_b32 s23, s7, s17
	s_cselect_b32 s22, s44, s16
	s_cselect_b32 s19, s5, s47
	s_cselect_b32 s18, s45, s46
	s_add_i32 m0, s13, 0xc000
	ds_read_b128 v[166:169], v148
	ds_read_b128 v[170:173], v148 offset:1024
	ds_read_b128 v[174:177], v148 offset:2048
	ds_read_b128 v[178:181], v148 offset:3072
	ds_read_b128 v[182:185], v148 offset:4096
	ds_read_b128 v[186:189], v148 offset:5120
	ds_read_b128 v[190:193], v148 offset:6144
	ds_read_b128 v[194:197], v148 offset:7168
	global_load_lds_dwordx4 v136, s[14:15]
	s_add_i32 m0, s13, 0xe000
	s_nop 0
	global_load_lds_dwordx4 v138, s[14:15]
	s_waitcnt lgkmcnt(8)
	s_waitcnt vmcnt(8)
	s_waitcnt lgkmcnt(0)
	s_setprio 1
	s_barrier
	v_mfma_f32_16x16x32_bf16 v[124:127], v[150:153], v[166:169], v[124:127]
	v_mfma_f32_16x16x32_bf16 v[116:119], v[158:161], v[166:169], v[116:119]
	v_mfma_f32_16x16x32_bf16 v[108:111], v[150:153], v[174:177], v[108:111]
	v_mfma_f32_16x16x32_bf16 v[100:103], v[158:161], v[174:177], v[100:103]
	v_mfma_f32_16x16x32_bf16 v[92:95], v[150:153], v[182:185], v[92:95]
	v_mfma_f32_16x16x32_bf16 v[84:87], v[158:161], v[182:185], v[84:87]
	v_mfma_f32_16x16x32_bf16 v[76:79], v[150:153], v[190:193], v[76:79]
	v_mfma_f32_16x16x32_bf16 v[68:71], v[158:161], v[190:193], v[68:71]
	v_mfma_f32_16x16x32_bf16 v[124:127], v[154:157], v[170:173], v[124:127]
	v_mfma_f32_16x16x32_bf16 v[116:119], v[162:165], v[170:173], v[116:119]
	v_mfma_f32_16x16x32_bf16 v[108:111], v[154:157], v[178:181], v[108:111]
	v_mfma_f32_16x16x32_bf16 v[100:103], v[162:165], v[178:181], v[100:103]
	v_mfma_f32_16x16x32_bf16 v[92:95], v[154:157], v[186:189], v[92:95]
	v_mfma_f32_16x16x32_bf16 v[84:87], v[162:165], v[186:189], v[84:87]
	v_mfma_f32_16x16x32_bf16 v[76:79], v[154:157], v[194:197], v[76:79]
	v_mfma_f32_16x16x32_bf16 v[68:71], v[162:165], v[194:197], v[68:71]
	s_barrier
	s_setprio 0
	s_add_i32 s16, s40, s25
	s_mov_b32 m0, s16
	ds_read_b128 v[202:205], v149
	ds_read_b128 v[206:209], v149 offset:1024
	ds_read_b128 v[210:213], v149 offset:2048
	ds_read_b128 v[214:217], v149 offset:3072
	global_load_lds_dwordx4 v132, s[18:19]
	s_add_i32 m0, s16, 0x2000
	s_nop 0
	global_load_lds_dwordx4 v128, s[18:19]
	s_waitcnt vmcnt(8)
	s_waitcnt lgkmcnt(0)
	s_setprio 1
	s_barrier
; #define PG8_STAGE(bufoff, gbase, voff) do { _Pragma("unroll") for (int _i = 0; _i < 2; ++_i) \
;         __builtin_amdgcn_global_load_lds((const unsigned*)((const char*)(gbase) + (voff)[_i]), (LAS unsigned*)(lds + (bufoff) + ldsw + _i * 8192), 16, 0, 0); } while (0)
; #define PG8_LDA(dst, b, h) do { _Pragma("unroll") for (int m = 0; m < 4; ++m) _Pragma("unroll") for (int k = 0; k < 2; ++k) dst[m][k] = *(const LAS bf16x8*)(lds + PG8_SA(b, h) + aoff + m * 2048 + k * 1024); } while (0)
; #define PG8_LDB(dst, b, h) do { _Pragma("unroll") for (int n = 0; n < 2; ++n) _Pragma("unroll") for (int k = 0; k < 2; ++k) dst[n][k] = *(const LAS bf16x8*)(lds + PG8_SB(b, h) + boff + n * 2048 + k * 1024); } while (0)
; #define PG8_MMA(ai, bj, At, Bt) do { __builtin_amdgcn_s_setprio(1); _Pragma("unroll") for (int m = 0; m < 4; ++m) _Pragma("unroll") for (int n = 0; n < 2; ++n) _Pragma("unroll") for (int k = 0; k < 2; ++k) \
;         acc[ai][bj][m][n] = __builtin_amdgcn_mfma_f32_16x16x32_bf16(Bt[n][k], At[m][k], acc[ai][bj][m][n], 0, 0, 0); __builtin_amdgcn_s_setprio(0); } while (0)
; #define PG8_WAIT_V(n) asm volatile("s_waitcnt vmcnt(" #n ")" ::: "memory")
; #define PG8_WAIT_L(n) asm volatile("s_waitcnt lgkmcnt(" #n ")" ::: "memory")
; #define PG8_BAR __builtin_amdgcn_s_barrier()
; #define PG8_SCHED __builtin_amdgcn_sched_barrier(0)
; template <class Epi, class Sched>
; __device__ __forceinline__ void gemm_phase(LAS unsigned char* lds, const Gemm g, const Sched& S, const Epi& E) {
;     ...
;             PG8_LDA(At, 0, 1); PG8_STAGE(PG8_SA(0, 0), a2, voffA);
;             PG8_BAR; PG8_WAIT_L(0); PG8_MMA(1, 0, At, B0); PG8_BAR; PG8_SCHED;
;             PG8_STAGE(PG8_SB(0, 1), b2 + hstep, voffB);
;             PG8_WAIT_V(6); PG8_BAR; PG8_MMA(1, 1, At, B1); PG8_BAR;
;             PG8_LDB(B0, 1, 0); PG8_SCHED; PG8_LDA(At, 1, 0); PG8_STAGE(PG8_SA(0, 1), a2 + hstep, voffA);
;             PG8_WAIT_L(8); PG8_BAR; PG8_WAIT_L(0); PG8_MMA(0, 0, At, B0); PG8_BAR; PG8_SCHED;
;             PG8_LDB(B1, 1, 1); PG8_STAGE(PG8_SB(1, 0), b3, voffB);
;             PG8_BAR; PG8_WAIT_L(0); PG8_MMA(0, 1, At, B1); PG8_BAR;
	v_mfma_f32_16x16x32_bf16 v[120:123], v[202:205], v[166:169], v[120:123]
	v_mfma_f32_16x16x32_bf16 v[112:115], v[210:213], v[166:169], v[112:115]
	v_mfma_f32_16x16x32_bf16 v[104:107], v[202:205], v[174:177], v[104:107]
	v_mfma_f32_16x16x32_bf16 v[96:99], v[210:213], v[174:177], v[96:99]
	v_mfma_f32_16x16x32_bf16 v[88:91], v[202:205], v[182:185], v[88:91]
	v_mfma_f32_16x16x32_bf16 v[80:83], v[210:213], v[182:185], v[80:83]
	v_mfma_f32_16x16x32_bf16 v[72:75], v[202:205], v[190:193], v[72:75]
	v_mfma_f32_16x16x32_bf16 v[64:67], v[210:213], v[190:193], v[64:67]
	v_mfma_f32_16x16x32_bf16 v[120:123], v[206:209], v[170:173], v[120:123]
	v_mfma_f32_16x16x32_bf16 v[112:115], v[214:217], v[170:173], v[112:115]
	v_mfma_f32_16x16x32_bf16 v[104:107], v[206:209], v[178:181], v[104:107]
	v_mfma_f32_16x16x32_bf16 v[96:99], v[214:217], v[178:181], v[96:99]
	v_mfma_f32_16x16x32_bf16 v[88:91], v[206:209], v[186:189], v[88:91]
	v_mfma_f32_16x16x32_bf16 v[80:83], v[214:217], v[186:189], v[80:83]
	v_mfma_f32_16x16x32_bf16 v[72:75], v[206:209], v[194:197], v[72:75]
	v_mfma_f32_16x16x32_bf16 v[64:67], v[214:217], v[194:197], v[64:67]
	s_mov_b32 m0, s13
	s_barrier
	s_setprio 0
	ds_read_b128 v[166:169], v148 offset:16384
	ds_read_b128 v[170:173], v148 offset:17408
	ds_read_b128 v[174:177], v148 offset:18432
	ds_read_b128 v[178:181], v148 offset:19456
	ds_read_b128 v[182:185], v148 offset:20480
	ds_read_b128 v[186:189], v148 offset:21504
	ds_read_b128 v[190:193], v148 offset:22528
	ds_read_b128 v[194:197], v148 offset:23552
	global_load_lds_dwordx4 v134, s[22:23]
	s_mov_b32 m0, s28
	s_nop 0
	global_load_lds_dwordx4 v130, s[22:23]
	s_waitcnt lgkmcnt(0)
	s_setprio 1
	s_barrier
	v_mfma_f32_16x16x32_bf16 v[60:63], v[150:153], v[166:169], v[60:63]
	v_mfma_f32_16x16x32_bf16 v[56:59], v[158:161], v[166:169], v[56:59]
	v_mfma_f32_16x16x32_bf16 v[44:47], v[150:153], v[174:177], v[44:47]
	v_mfma_f32_16x16x32_bf16 v[40:43], v[158:161], v[174:177], v[40:43]
	v_mfma_f32_16x16x32_bf16 v[28:31], v[150:153], v[182:185], v[28:31]
	v_mfma_f32_16x16x32_bf16 v[24:27], v[158:161], v[182:185], v[24:27]
	v_mfma_f32_16x16x32_bf16 v[12:15], v[150:153], v[190:193], v[12:15]
	v_mfma_f32_16x16x32_bf16 v[8:11], v[158:161], v[190:193], v[8:11]
	v_mfma_f32_16x16x32_bf16 v[60:63], v[154:157], v[170:173], v[60:63]
	v_mfma_f32_16x16x32_bf16 v[56:59], v[162:165], v[170:173], v[56:59]
	v_mfma_f32_16x16x32_bf16 v[44:47], v[154:157], v[178:181], v[44:47]
	v_mfma_f32_16x16x32_bf16 v[40:43], v[162:165], v[178:181], v[40:43]
	v_mfma_f32_16x16x32_bf16 v[28:31], v[154:157], v[186:189], v[28:31]
	v_mfma_f32_16x16x32_bf16 v[24:27], v[162:165], v[186:189], v[24:27]
	v_mfma_f32_16x16x32_bf16 v[12:15], v[154:157], v[194:197], v[12:15]
	v_mfma_f32_16x16x32_bf16 v[8:11], v[162:165], v[194:197], v[8:11]
	s_barrier
	s_setprio 0
	s_add_u32 s16, s18, 0x40000
	s_addc_u32 s17, s19, 0
	s_add_i32 s20, s41, s25
	s_mov_b32 m0, s20
	s_nop 0
	global_load_lds_dwordx4 v132, s[16:17]
	s_add_i32 m0, s20, 0x2000
	s_nop 0
	global_load_lds_dwordx4 v128, s[16:17]
	s_add_u32 s16, s22, 0x40000
	s_addc_u32 s17, s23, 0
	s_mov_b32 m0, s29
	s_nop 0
	global_load_lds_dwordx4 v134, s[16:17]
	s_mov_b32 m0, s33
	s_nop 0
	global_load_lds_dwordx4 v130, s[16:17]
	s_waitcnt vmcnt(10)
	s_setprio 1
	s_barrier
	v_mfma_f32_16x16x32_bf16 v[52:55], v[202:205], v[166:169], v[52:55]
	v_mfma_f32_16x16x32_bf16 v[48:51], v[210:213], v[166:169], v[48:51]
	v_mfma_f32_16x16x32_bf16 v[36:39], v[202:205], v[174:177], v[36:39]
	v_mfma_f32_16x16x32_bf16 v[32:35], v[210:213], v[174:177], v[32:35]
	v_mfma_f32_16x16x32_bf16 v[20:23], v[202:205], v[182:185], v[20:23]
	v_mfma_f32_16x16x32_bf16 v[16:19], v[210:213], v[182:185], v[16:19]
	v_mfma_f32_16x16x32_bf16 v[4:7], v[202:205], v[190:193], v[4:7]
	v_mfma_f32_16x16x32_bf16 v[0:3], v[210:213], v[190:193], v[0:3]
	v_mfma_f32_16x16x32_bf16 v[52:55], v[206:209], v[170:173], v[52:55]
	v_mfma_f32_16x16x32_bf16 v[48:51], v[214:217], v[170:173], v[48:51]
	v_mfma_f32_16x16x32_bf16 v[36:39], v[206:209], v[178:181], v[36:39]
	v_mfma_f32_16x16x32_bf16 v[32:35], v[214:217], v[178:181], v[32:35]
	v_mfma_f32_16x16x32_bf16 v[20:23], v[206:209], v[186:189], v[20:23]
	v_mfma_f32_16x16x32_bf16 v[16:19], v[214:217], v[186:189], v[16:19]
	v_mfma_f32_16x16x32_bf16 v[4:7], v[206:209], v[194:197], v[4:7]
	v_mfma_f32_16x16x32_bf16 v[0:3], v[214:217], v[194:197], v[0:3]
	s_add_i32 s20, 0, 0x18000
	v_add_u32_e32 v162, s20, v146
	s_barrier
	s_setprio 0
	ds_read_b128 v[150:153], v162
	ds_read_b128 v[154:157], v162 offset:1024
	ds_read_b128 v[158:161], v162 offset:2048
	ds_read_b128 v[162:165], v162 offset:3072
	ds_read_b128 v[166:169], v148 offset:32768
	ds_read_b128 v[170:173], v148 offset:33792
	ds_read_b128 v[174:177], v148 offset:34816
	ds_read_b128 v[178:181], v148 offset:35840
	ds_read_b128 v[182:185], v148 offset:36864
	ds_read_b128 v[186:189], v148 offset:37888
	ds_read_b128 v[190:193], v148 offset:38912
	ds_read_b128 v[194:197], v148 offset:39936
	s_waitcnt lgkmcnt(8)
	s_waitcnt vmcnt(8)
	s_waitcnt lgkmcnt(0)
	s_setprio 1
	s_barrier
; #define PG8_STAGE(bufoff, gbase, voff) do { _Pragma("unroll") for (int _i = 0; _i < 2; ++_i) \
;         __builtin_amdgcn_global_load_lds((const unsigned*)((const char*)(gbase) + (voff)[_i]), (LAS unsigned*)(lds + (bufoff) + ldsw + _i * 8192), 16, 0, 0); } while (0)
; #define PG8_LDA(dst, b, h) do { _Pragma("unroll") for (int m = 0; m < 4; ++m) _Pragma("unroll") for (int k = 0; k < 2; ++k) dst[m][k] = *(const LAS bf16x8*)(lds + PG8_SA(b, h) + aoff + m * 2048 + k * 1024); } while (0)
; #define PG8_LDB(dst, b, h) do { _Pragma("unroll") for (int n = 0; n < 2; ++n) _Pragma("unroll") for (int k = 0; k < 2; ++k) dst[n][k] = *(const LAS bf16x8*)(lds + PG8_SB(b, h) + boff + n * 2048 + k * 1024); } while (0)
; #define PG8_MMA(ai, bj, At, Bt) do { __builtin_amdgcn_s_setprio(1); _Pragma("unroll") for (int m = 0; m < 4; ++m) _Pragma("unroll") for (int n = 0; n < 2; ++n) _Pragma("unroll") for (int k = 0; k < 2; ++k) \
;         acc[ai][bj][m][n] = __builtin_amdgcn_mfma_f32_16x16x32_bf16(Bt[n][k], At[m][k], acc[ai][bj][m][n], 0, 0, 0); __builtin_amdgcn_s_setprio(0); } while (0)
; #define PG8_WAIT_V(n) asm volatile("s_waitcnt vmcnt(" #n ")" ::: "memory")
; #define PG8_WAIT_L(n) asm volatile("s_waitcnt lgkmcnt(" #n ")" ::: "memory")
; #define PG8_BAR __builtin_amdgcn_s_barrier()
; #define PG8_SCHED __builtin_amdgcn_sched_barrier(0)
; template <class Epi, class Sched>
; __device__ __forceinline__ void gemm_phase(LAS unsigned char* lds, const Gemm g, const Sched& S, const Epi& E) {
;     ...
;             PG8_WAIT_V(6); PG8_BAR; PG8_MMA(1, 1, At, B1); PG8_BAR;
;             PG8_LDB(B0, 1, 0); PG8_SCHED; PG8_LDA(At, 1, 0); PG8_STAGE(PG8_SA(0, 1), a2 + hstep, voffA);
;             PG8_WAIT_L(8); PG8_BAR; PG8_WAIT_L(0); PG8_MMA(0, 0, At, B0); PG8_BAR; PG8_SCHED;
;             PG8_LDB(B1, 1, 1); PG8_STAGE(PG8_SB(1, 0), b3, voffB);
;             PG8_BAR; PG8_WAIT_L(0); PG8_MMA(0, 1, At, B1); PG8_BAR;
;             PG8_LDA(At, 1, 1); PG8_STAGE(PG8_SA(1, 0), a3, voffA);
;             PG8_BAR; PG8_WAIT_L(0); PG8_MMA(1, 0, At, B0); PG8_BAR; PG8_SCHED;
;             PG8_STAGE(PG8_SB(1, 1), b3 + hstep, voffB);
;             PG8_WAIT_V(6); PG8_BAR; PG8_MMA(1, 1, At, B1); PG8_BAR;
	v_mfma_f32_16x16x32_bf16 v[124:127], v[150:153], v[166:169], v[124:127]
	v_mfma_f32_16x16x32_bf16 v[116:119], v[158:161], v[166:169], v[116:119]
	v_mfma_f32_16x16x32_bf16 v[108:111], v[150:153], v[174:177], v[108:111]
	v_mfma_f32_16x16x32_bf16 v[100:103], v[158:161], v[174:177], v[100:103]
	v_mfma_f32_16x16x32_bf16 v[92:95], v[150:153], v[182:185], v[92:95]
	v_mfma_f32_16x16x32_bf16 v[84:87], v[158:161], v[182:185], v[84:87]
	v_mfma_f32_16x16x32_bf16 v[76:79], v[150:153], v[190:193], v[76:79]
	v_mfma_f32_16x16x32_bf16 v[68:71], v[158:161], v[190:193], v[68:71]
	v_mfma_f32_16x16x32_bf16 v[124:127], v[154:157], v[170:173], v[124:127]
	v_mfma_f32_16x16x32_bf16 v[116:119], v[162:165], v[170:173], v[116:119]
	v_mfma_f32_16x16x32_bf16 v[108:111], v[154:157], v[178:181], v[108:111]
	v_mfma_f32_16x16x32_bf16 v[100:103], v[162:165], v[178:181], v[100:103]
	v_mfma_f32_16x16x32_bf16 v[92:95], v[154:157], v[186:189], v[92:95]
	v_mfma_f32_16x16x32_bf16 v[84:87], v[162:165], v[186:189], v[84:87]
	v_mfma_f32_16x16x32_bf16 v[76:79], v[154:157], v[194:197], v[76:79]
	v_mfma_f32_16x16x32_bf16 v[68:71], v[162:165], v[194:197], v[68:71]
	s_barrier
	s_setprio 0
	s_add_i32 s21, 0, 0x1c000
	s_add_i32 s16, s20, s25
	v_add_u32_e32 v214, s21, v146
	s_add_u32 s0, s18, 0x80
	s_addc_u32 s1, s19, 0
	s_mov_b32 m0, s16
	ds_read_b128 v[202:205], v214
	ds_read_b128 v[206:209], v214 offset:1024
	ds_read_b128 v[210:213], v214 offset:2048
	ds_read_b128 v[214:217], v214 offset:3072
	global_load_lds_dwordx4 v132, s[0:1]
	s_add_i32 m0, s16, 0x2000
	s_nop 0
	global_load_lds_dwordx4 v128, s[0:1]
	s_waitcnt vmcnt(8)
	s_waitcnt lgkmcnt(0)
	s_setprio 1
	s_barrier
	v_mfma_f32_16x16x32_bf16 v[120:123], v[202:205], v[166:169], v[120:123]
	v_mfma_f32_16x16x32_bf16 v[112:115], v[210:213], v[166:169], v[112:115]
	v_mfma_f32_16x16x32_bf16 v[104:107], v[202:205], v[174:177], v[104:107]
	v_mfma_f32_16x16x32_bf16 v[96:99], v[210:213], v[174:177], v[96:99]
	v_mfma_f32_16x16x32_bf16 v[88:91], v[202:205], v[182:185], v[88:91]
	v_mfma_f32_16x16x32_bf16 v[80:83], v[210:213], v[182:185], v[80:83]
	v_mfma_f32_16x16x32_bf16 v[72:75], v[202:205], v[190:193], v[72:75]
	v_mfma_f32_16x16x32_bf16 v[64:67], v[210:213], v[190:193], v[64:67]
	v_mfma_f32_16x16x32_bf16 v[120:123], v[206:209], v[170:173], v[120:123]
	v_mfma_f32_16x16x32_bf16 v[112:115], v[214:217], v[170:173], v[112:115]
	v_mfma_f32_16x16x32_bf16 v[104:107], v[206:209], v[178:181], v[104:107]
	v_mfma_f32_16x16x32_bf16 v[96:99], v[214:217], v[178:181], v[96:99]
	v_mfma_f32_16x16x32_bf16 v[88:91], v[206:209], v[186:189], v[88:91]
	v_mfma_f32_16x16x32_bf16 v[80:83], v[214:217], v[186:189], v[80:83]
	v_mfma_f32_16x16x32_bf16 v[72:75], v[206:209], v[194:197], v[72:75]
	v_mfma_f32_16x16x32_bf16 v[64:67], v[214:217], v[194:197], v[64:67]
	s_mov_b32 m0, s36
	s_add_u32 s0, s22, 0x80
	s_addc_u32 s1, s23, 0
	s_barrier
	s_setprio 0
	ds_read_b128 v[166:169], v148 offset:49152
	ds_read_b128 v[170:173], v148 offset:50176
	ds_read_b128 v[174:177], v148 offset:51200
	ds_read_b128 v[178:181], v148 offset:52224
	ds_read_b128 v[182:185], v148 offset:53248
	ds_read_b128 v[186:189], v148 offset:54272
	ds_read_b128 v[190:193], v148 offset:55296
	ds_read_b128 v[194:197], v148 offset:56320
	global_load_lds_dwordx4 v134, s[0:1]
	s_mov_b32 m0, s37
	s_nop 0
	global_load_lds_dwordx4 v130, s[0:1]
	s_waitcnt lgkmcnt(0)
	s_setprio 1
	s_barrier
	v_mfma_f32_16x16x32_bf16 v[60:63], v[150:153], v[166:169], v[60:63]
	v_mfma_f32_16x16x32_bf16 v[56:59], v[158:161], v[166:169], v[56:59]
	v_mfma_f32_16x16x32_bf16 v[44:47], v[150:153], v[174:177], v[44:47]
	v_mfma_f32_16x16x32_bf16 v[40:43], v[158:161], v[174:177], v[40:43]
	v_mfma_f32_16x16x32_bf16 v[28:31], v[150:153], v[182:185], v[28:31]
	v_mfma_f32_16x16x32_bf16 v[24:27], v[158:161], v[182:185], v[24:27]
	v_mfma_f32_16x16x32_bf16 v[12:15], v[150:153], v[190:193], v[12:15]
	v_mfma_f32_16x16x32_bf16 v[8:11], v[158:161], v[190:193], v[8:11]
	v_mfma_f32_16x16x32_bf16 v[60:63], v[154:157], v[170:173], v[60:63]
	v_mfma_f32_16x16x32_bf16 v[56:59], v[162:165], v[170:173], v[56:59]
	v_mfma_f32_16x16x32_bf16 v[44:47], v[154:157], v[178:181], v[44:47]
	v_mfma_f32_16x16x32_bf16 v[40:43], v[162:165], v[178:181], v[40:43]
	v_mfma_f32_16x16x32_bf16 v[28:31], v[154:157], v[186:189], v[28:31]
	v_mfma_f32_16x16x32_bf16 v[24:27], v[162:165], v[186:189], v[24:27]
	v_mfma_f32_16x16x32_bf16 v[12:15], v[154:157], v[194:197], v[12:15]
	v_mfma_f32_16x16x32_bf16 v[8:11], v[162:165], v[194:197], v[8:11]
	s_barrier
	s_setprio 0
	s_add_u32 s16, s18, 0x40080
	s_addc_u32 s17, s19, 0
	s_add_i32 s18, s21, s25
	s_mov_b32 m0, s18
	s_nop 0
	global_load_lds_dwordx4 v132, s[16:17]
	s_add_i32 m0, s18, 0x2000
	s_nop 0
	global_load_lds_dwordx4 v128, s[16:17]
	s_waitcnt vmcnt(8)
	s_setprio 1
	s_barrier
	v_mfma_f32_16x16x32_bf16 v[52:55], v[202:205], v[166:169], v[52:55]
	v_mfma_f32_16x16x32_bf16 v[48:51], v[210:213], v[166:169], v[48:51]
	v_mfma_f32_16x16x32_bf16 v[36:39], v[202:205], v[174:177], v[36:39]
	v_mfma_f32_16x16x32_bf16 v[32:35], v[210:213], v[174:177], v[32:35]
	v_mfma_f32_16x16x32_bf16 v[20:23], v[202:205], v[182:185], v[20:23]
	v_mfma_f32_16x16x32_bf16 v[16:19], v[210:213], v[182:185], v[16:19]
	v_mfma_f32_16x16x32_bf16 v[4:7], v[202:205], v[190:193], v[4:7]
	v_mfma_f32_16x16x32_bf16 v[0:3], v[210:213], v[190:193], v[0:3]
	v_mfma_f32_16x16x32_bf16 v[52:55], v[206:209], v[170:173], v[52:55]
	v_mfma_f32_16x16x32_bf16 v[48:51], v[214:217], v[170:173], v[48:51]
	v_mfma_f32_16x16x32_bf16 v[36:39], v[206:209], v[178:181], v[36:39]
	v_mfma_f32_16x16x32_bf16 v[32:35], v[214:217], v[178:181], v[32:35]
	v_mfma_f32_16x16x32_bf16 v[20:23], v[206:209], v[186:189], v[20:23]
	v_mfma_f32_16x16x32_bf16 v[16:19], v[214:217], v[186:189], v[16:19]
	v_mfma_f32_16x16x32_bf16 v[4:7], v[206:209], v[194:197], v[4:7]
	v_mfma_f32_16x16x32_bf16 v[0:3], v[214:217], v[194:197], v[0:3]
	s_setprio 0
	s_add_i32 s48, s48, 2
	s_add_u32 s14, s14, 0x100
	s_addc_u32 s15, s15, 0
	s_add_u32 s46, s46, 0x100
	s_addc_u32 s47, s47, 0
	s_cmp_gt_u32 s48, 13
	s_cbranch_scc1 .Lconc_last_g0
	s_barrier
	s_branch .LBB0_235

; #define PG8_STAGE(bufoff, gbase, voff) do { _Pragma("unroll") for (int _i = 0; _i < 2; ++_i) \
;         __builtin_amdgcn_global_load_lds((const unsigned*)((const char*)(gbase) + (voff)[_i]), (LAS unsigned*)(lds + (bufoff) + ldsw + _i * 8192), 16, 0, 0); } while (0)
; #define PG8_LDA(dst, b, h) do { _Pragma("unroll") for (int m = 0; m < 4; ++m) _Pragma("unroll") for (int k = 0; k < 2; ++k) dst[m][k] = *(const LAS bf16x8*)(lds + PG8_SA(b, h) + aoff + m * 2048 + k * 1024); } while (0)
; #define PG8_LDB(dst, b, h) do { _Pragma("unroll") for (int n = 0; n < 2; ++n) _Pragma("unroll") for (int k = 0; k < 2; ++k) dst[n][k] = *(const LAS bf16x8*)(lds + PG8_SB(b, h) + boff + n * 2048 + k * 1024); } while (0)
; #define PG8_MMA(ai, bj, At, Bt) do { __builtin_amdgcn_s_setprio(1); _Pragma("unroll") for (int m = 0; m < 4; ++m) _Pragma("unroll") for (int n = 0; n < 2; ++n) _Pragma("unroll") for (int k = 0; k < 2; ++k) \
;         acc[ai][bj][m][n] = __builtin_amdgcn_mfma_f32_16x16x32_bf16(Bt[n][k], At[m][k], acc[ai][bj][m][n], 0, 0, 0); __builtin_amdgcn_s_setprio(0); } while (0)
; #define PG8_WAIT_V(n) asm volatile("s_waitcnt vmcnt(" #n ")" ::: "memory")
; #define PG8_WAIT_L(n) asm volatile("s_waitcnt lgkmcnt(" #n ")" ::: "memory")
; template <class Epi, class Sched>
; __device__ __forceinline__ void gemm_phase(LAS unsigned char* lds, const Gemm g, const Sched& S, const Epi& E) {
;     ...
;         for (int t = 0; t < nt; t += 2) {
;             const bool last = (t == nt - 2);
;             const char* a1 = cA + (size_t)(t + 1) * kstep;
;             const char* a2 = last ? nA : cA + (size_t)(t + 2) * kstep; const char* b2 = last ? nB : cB + (size_t)(t + 2) * kstep;
;             const char* a3 = a2 + kstep; const char* b3 = b2 + kstep;
;             PG8_LDB(B0, 0, 0); PG8_SCHED; PG8_LDA(At, 0, 0); PG8_STAGE(PG8_SA(1, 1), a1 + hstep, voffA);
;             PG8_WAIT_L(8); PG8_BAR; PG8_WAIT_L(0); PG8_MMA(0, 0, At, B0); PG8_BAR; PG8_SCHED;
;             PG8_LDB(B1, 0, 1); PG8_STAGE(PG8_SB(0, 0), b2, voffB);
;             PG8_BAR; PG8_WAIT_L(0); PG8_MMA(0, 1, At, B1); PG8_BAR;
;             PG8_LDA(At, 0, 1); PG8_STAGE(PG8_SA(0, 0), a2, voffA);
;             PG8_BAR; PG8_WAIT_L(0); PG8_MMA(1, 0, At, B0); PG8_BAR; PG8_SCHED;
;             PG8_STAGE(PG8_SB(0, 1), b2 + hstep, voffB);
;             PG8_WAIT_V(6); PG8_BAR; PG8_MMA(1, 1, At, B1); PG8_BAR;
.LBB0_304:
	s_add_u32 s0, s28, 0x100
	s_addc_u32 s67, s29, 0
	s_mov_b32 s68, -2
	ds_read_b128 v[144:147], v165
	ds_read_b128 v[148:151], v165 offset:1024
	ds_read_b128 v[152:155], v165 offset:2048
	ds_read_b128 v[156:159], v165 offset:3072
	s_add_u32 s28, s26, 0x100
	s_addc_u32 s29, s27, 0
	s_cmp_eq_u32 s68, 40
	s_cselect_b32 s37, s5, s29
	s_cselect_b32 s36, s4, s28
	s_cselect_b32 s35, s7, s67
	s_cselect_b32 s34, s6, s0
	v_lshl_add_u64 v[160:161], s[26:27], 0, v[136:137]
	s_add_i32 m0, s42, 0xc000
	ds_read_b128 v[168:171], v166
	ds_read_b128 v[172:175], v166 offset:1024
	ds_read_b128 v[176:179], v166 offset:2048
	ds_read_b128 v[180:183], v166 offset:3072
	ds_read_b128 v[184:187], v166 offset:4096
	ds_read_b128 v[188:191], v166 offset:5120
	ds_read_b128 v[192:195], v166 offset:6144
	ds_read_b128 v[196:199], v166 offset:7168
	global_load_lds_dwordx4 v[160:161], off
	v_lshl_add_u64 v[160:161], s[26:27], 0, v[138:139]
	s_add_i32 m0, s42, 0xe000
	s_nop 0
	global_load_lds_dwordx4 v[160:161], off
	s_waitcnt lgkmcnt(8)
	s_waitcnt vmcnt(8)
	s_waitcnt lgkmcnt(0)
	s_setprio 1
	s_barrier
	v_mfma_f32_16x16x32_bf16 v[124:127], v[144:147], v[168:171], 0
	v_mfma_f32_16x16x32_bf16 v[120:123], v[152:155], v[168:171], 0
	v_mfma_f32_16x16x32_bf16 v[116:119], v[144:147], v[176:179], 0
	v_mfma_f32_16x16x32_bf16 v[104:107], v[152:155], v[176:179], 0
	v_mfma_f32_16x16x32_bf16 v[96:99], v[144:147], v[184:187], 0
	v_mfma_f32_16x16x32_bf16 v[88:91], v[152:155], v[184:187], 0
	v_mfma_f32_16x16x32_bf16 v[80:83], v[144:147], v[192:195], 0
	v_mfma_f32_16x16x32_bf16 v[72:75], v[152:155], v[192:195], 0
	v_mfma_f32_16x16x32_bf16 v[124:127], v[148:151], v[172:175], v[124:127]
	v_mfma_f32_16x16x32_bf16 v[120:123], v[156:159], v[172:175], v[120:123]
	v_mfma_f32_16x16x32_bf16 v[116:119], v[148:151], v[180:183], v[116:119]
	v_mfma_f32_16x16x32_bf16 v[104:107], v[156:159], v[180:183], v[104:107]
	v_mfma_f32_16x16x32_bf16 v[96:99], v[148:151], v[188:191], v[96:99]
	v_mfma_f32_16x16x32_bf16 v[88:91], v[156:159], v[188:191], v[88:91]
	v_mfma_f32_16x16x32_bf16 v[80:83], v[148:151], v[196:199], v[80:83]
	v_mfma_f32_16x16x32_bf16 v[72:75], v[156:159], v[196:199], v[72:75]
	s_barrier
	s_setprio 0
	s_add_i32 s16, s58, s40
	s_mov_b32 m0, s16
	ds_read_b128 v[202:205], v167
	ds_read_b128 v[206:209], v167 offset:1024
	ds_read_b128 v[210:213], v167 offset:2048
	ds_read_b128 v[214:217], v167 offset:3072
	global_load_lds_dwordx4 v132, s[34:35]
	s_add_i32 m0, s16, 0x2000
	s_nop 0
	global_load_lds_dwordx4 v128, s[34:35]
	s_waitcnt vmcnt(8)
	s_waitcnt lgkmcnt(0)
	s_setprio 1
	s_barrier
	v_mfma_f32_16x16x32_bf16 v[112:115], v[202:205], v[168:171], 0
	v_mfma_f32_16x16x32_bf16 v[108:111], v[210:213], v[168:171], 0
	v_mfma_f32_16x16x32_bf16 v[100:103], v[202:205], v[176:179], 0
	v_mfma_f32_16x16x32_bf16 v[92:95], v[210:213], v[176:179], 0
	v_mfma_f32_16x16x32_bf16 v[84:87], v[202:205], v[184:187], 0
	v_mfma_f32_16x16x32_bf16 v[76:79], v[210:213], v[184:187], 0
	v_mfma_f32_16x16x32_bf16 v[68:71], v[202:205], v[192:195], 0
	v_mfma_f32_16x16x32_bf16 v[64:67], v[210:213], v[192:195], 0
	v_mfma_f32_16x16x32_bf16 v[112:115], v[206:209], v[172:175], v[112:115]
	v_mfma_f32_16x16x32_bf16 v[108:111], v[214:217], v[172:175], v[108:111]
	v_mfma_f32_16x16x32_bf16 v[100:103], v[206:209], v[180:183], v[100:103]
	v_mfma_f32_16x16x32_bf16 v[92:95], v[214:217], v[180:183], v[92:95]
	v_mfma_f32_16x16x32_bf16 v[84:87], v[206:209], v[188:191], v[84:87]
	v_mfma_f32_16x16x32_bf16 v[76:79], v[214:217], v[188:191], v[76:79]
	v_mfma_f32_16x16x32_bf16 v[68:71], v[206:209], v[196:199], v[68:71]
	v_mfma_f32_16x16x32_bf16 v[64:67], v[214:217], v[196:199], v[64:67]
	s_mov_b32 m0, s42
	s_barrier
	s_setprio 0
	ds_read_b128 v[168:171], v166 offset:16384
	ds_read_b128 v[172:175], v166 offset:17408
	ds_read_b128 v[176:179], v166 offset:18432
	ds_read_b128 v[180:183], v166 offset:19456
	ds_read_b128 v[184:187], v166 offset:20480
	ds_read_b128 v[188:191], v166 offset:21504
	ds_read_b128 v[192:195], v166 offset:22528
	ds_read_b128 v[196:199], v166 offset:23552
	global_load_lds_dwordx4 v134, s[36:37]
	s_mov_b32 m0, s43
	s_nop 0
	global_load_lds_dwordx4 v130, s[36:37]
	s_waitcnt lgkmcnt(0)
	s_setprio 1
	s_barrier
	v_mfma_f32_16x16x32_bf16 v[60:63], v[144:147], v[168:171], 0
	v_mfma_f32_16x16x32_bf16 v[56:59], v[152:155], v[168:171], 0
	v_mfma_f32_16x16x32_bf16 v[48:51], v[144:147], v[176:179], 0
	v_mfma_f32_16x16x32_bf16 v[40:43], v[152:155], v[176:179], 0
	v_mfma_f32_16x16x32_bf16 v[32:35], v[144:147], v[184:187], 0
	v_mfma_f32_16x16x32_bf16 v[24:27], v[152:155], v[184:187], 0
	v_mfma_f32_16x16x32_bf16 v[16:19], v[144:147], v[192:195], 0
	v_mfma_f32_16x16x32_bf16 v[8:11], v[152:155], v[192:195], 0
	v_mfma_f32_16x16x32_bf16 v[60:63], v[148:151], v[172:175], v[60:63]
	v_mfma_f32_16x16x32_bf16 v[56:59], v[156:159], v[172:175], v[56:59]
	v_mfma_f32_16x16x32_bf16 v[48:51], v[148:151], v[180:183], v[48:51]
	v_mfma_f32_16x16x32_bf16 v[40:43], v[156:159], v[180:183], v[40:43]
	v_mfma_f32_16x16x32_bf16 v[32:35], v[148:151], v[188:191], v[32:35]
	v_mfma_f32_16x16x32_bf16 v[24:27], v[156:159], v[188:191], v[24:27]
	v_mfma_f32_16x16x32_bf16 v[16:19], v[148:151], v[196:199], v[16:19]
	v_mfma_f32_16x16x32_bf16 v[8:11], v[156:159], v[196:199], v[8:11]
	s_barrier
	s_setprio 0
	s_add_u32 s16, s34, 0xb0000
	s_addc_u32 s17, s35, 0
	s_add_i32 s20, s59, s40
	s_mov_b32 m0, s20
	s_nop 0
	global_load_lds_dwordx4 v132, s[16:17]
	s_add_i32 m0, s20, 0x2000
	s_nop 0
	global_load_lds_dwordx4 v128, s[16:17]
	s_add_u32 s16, s36, 0xb0000
	s_addc_u32 s17, s37, 0
	s_mov_b32 m0, s44
	s_nop 0
	global_load_lds_dwordx4 v134, s[16:17]
	s_mov_b32 m0, s45
	s_nop 0
	global_load_lds_dwordx4 v130, s[16:17]
	s_waitcnt vmcnt(10)
	s_setprio 1
	s_barrier
; #define PG8_STAGE(bufoff, gbase, voff) do { _Pragma("unroll") for (int _i = 0; _i < 2; ++_i) \
;         __builtin_amdgcn_global_load_lds((const unsigned*)((const char*)(gbase) + (voff)[_i]), (LAS unsigned*)(lds + (bufoff) + ldsw + _i * 8192), 16, 0, 0); } while (0)
; #define PG8_LDA(dst, b, h) do { _Pragma("unroll") for (int m = 0; m < 4; ++m) _Pragma("unroll") for (int k = 0; k < 2; ++k) dst[m][k] = *(const LAS bf16x8*)(lds + PG8_SA(b, h) + aoff + m * 2048 + k * 1024); } while (0)
; #define PG8_LDB(dst, b, h) do { _Pragma("unroll") for (int n = 0; n < 2; ++n) _Pragma("unroll") for (int k = 0; k < 2; ++k) dst[n][k] = *(const LAS bf16x8*)(lds + PG8_SB(b, h) + boff + n * 2048 + k * 1024); } while (0)
; #define PG8_MMA(ai, bj, At, Bt) do { __builtin_amdgcn_s_setprio(1); _Pragma("unroll") for (int m = 0; m < 4; ++m) _Pragma("unroll") for (int n = 0; n < 2; ++n) _Pragma("unroll") for (int k = 0; k < 2; ++k) \
;         acc[ai][bj][m][n] = __builtin_amdgcn_mfma_f32_16x16x32_bf16(Bt[n][k], At[m][k], acc[ai][bj][m][n], 0, 0, 0); __builtin_amdgcn_s_setprio(0); } while (0)
; #define PG8_WAIT_V(n) asm volatile("s_waitcnt vmcnt(" #n ")" ::: "memory")
; #define PG8_WAIT_L(n) asm volatile("s_waitcnt lgkmcnt(" #n ")" ::: "memory")
; #define PG8_BAR __builtin_amdgcn_s_barrier()
; #define PG8_SCHED __builtin_amdgcn_sched_barrier(0)
; template <class Epi, class Sched>
; __device__ __forceinline__ void gemm_phase(LAS unsigned char* lds, const Gemm g, const Sched& S, const Epi& E) {
;     ...
;             PG8_WAIT_V(6); PG8_BAR; PG8_MMA(1, 1, At, B1); PG8_BAR;
;             PG8_LDB(B0, 1, 0); PG8_SCHED; PG8_LDA(At, 1, 0); PG8_STAGE(PG8_SA(0, 1), a2 + hstep, voffA);
;             PG8_WAIT_L(8); PG8_BAR; PG8_WAIT_L(0); PG8_MMA(0, 0, At, B0); PG8_BAR; PG8_SCHED;
;             PG8_LDB(B1, 1, 1); PG8_STAGE(PG8_SB(1, 0), b3, voffB);
;             PG8_BAR; PG8_WAIT_L(0); PG8_MMA(0, 1, At, B1); PG8_BAR;
;             PG8_LDA(At, 1, 1); PG8_STAGE(PG8_SA(1, 0), a3, voffA);
;             PG8_BAR; PG8_WAIT_L(0); PG8_MMA(1, 0, At, B0); PG8_BAR; PG8_SCHED;
	v_mfma_f32_16x16x32_bf16 v[52:55], v[202:205], v[168:171], 0
	v_mfma_f32_16x16x32_bf16 v[44:47], v[210:213], v[168:171], 0
	v_mfma_f32_16x16x32_bf16 v[36:39], v[202:205], v[176:179], 0
	v_mfma_f32_16x16x32_bf16 v[28:31], v[210:213], v[176:179], 0
	v_mfma_f32_16x16x32_bf16 v[20:23], v[202:205], v[184:187], 0
	v_mfma_f32_16x16x32_bf16 v[12:15], v[210:213], v[184:187], 0
	v_mfma_f32_16x16x32_bf16 v[4:7], v[202:205], v[192:195], 0
	v_mfma_f32_16x16x32_bf16 v[0:3], v[210:213], v[192:195], 0
	v_mfma_f32_16x16x32_bf16 v[52:55], v[206:209], v[172:175], v[52:55]
	v_mfma_f32_16x16x32_bf16 v[44:47], v[214:217], v[172:175], v[44:47]
	v_mfma_f32_16x16x32_bf16 v[36:39], v[206:209], v[180:183], v[36:39]
	v_mfma_f32_16x16x32_bf16 v[28:31], v[214:217], v[180:183], v[28:31]
	v_mfma_f32_16x16x32_bf16 v[20:23], v[206:209], v[188:191], v[20:23]
	v_mfma_f32_16x16x32_bf16 v[12:15], v[214:217], v[188:191], v[12:15]
	v_mfma_f32_16x16x32_bf16 v[4:7], v[206:209], v[196:199], v[4:7]
	v_mfma_f32_16x16x32_bf16 v[0:3], v[214:217], v[196:199], v[0:3]
	s_add_i32 s20, 0, 0x18000
	v_add_u32_e32 v156, s20, v164
	s_barrier
	s_setprio 0
	ds_read_b128 v[144:147], v156
	ds_read_b128 v[148:151], v156 offset:1024
	ds_read_b128 v[152:155], v156 offset:2048
	ds_read_b128 v[156:159], v156 offset:3072
	ds_read_b128 v[168:171], v166 offset:32768
	ds_read_b128 v[172:175], v166 offset:33792
	ds_read_b128 v[176:179], v166 offset:34816
	ds_read_b128 v[180:183], v166 offset:35840
	ds_read_b128 v[184:187], v166 offset:36864
	ds_read_b128 v[188:191], v166 offset:37888
	ds_read_b128 v[192:195], v166 offset:38912
	ds_read_b128 v[196:199], v166 offset:39936
	s_waitcnt lgkmcnt(8)
	s_waitcnt vmcnt(8)
	s_waitcnt lgkmcnt(0)
	s_setprio 1
	s_barrier
	v_mfma_f32_16x16x32_bf16 v[124:127], v[144:147], v[168:171], v[124:127]
	v_mfma_f32_16x16x32_bf16 v[120:123], v[152:155], v[168:171], v[120:123]
	v_mfma_f32_16x16x32_bf16 v[116:119], v[144:147], v[176:179], v[116:119]
	v_mfma_f32_16x16x32_bf16 v[104:107], v[152:155], v[176:179], v[104:107]
	v_mfma_f32_16x16x32_bf16 v[96:99], v[144:147], v[184:187], v[96:99]
	v_mfma_f32_16x16x32_bf16 v[88:91], v[152:155], v[184:187], v[88:91]
	v_mfma_f32_16x16x32_bf16 v[80:83], v[144:147], v[192:195], v[80:83]
	v_mfma_f32_16x16x32_bf16 v[72:75], v[152:155], v[192:195], v[72:75]
	v_mfma_f32_16x16x32_bf16 v[124:127], v[148:151], v[172:175], v[124:127]
	v_mfma_f32_16x16x32_bf16 v[120:123], v[156:159], v[172:175], v[120:123]
	v_mfma_f32_16x16x32_bf16 v[116:119], v[148:151], v[180:183], v[116:119]
	v_mfma_f32_16x16x32_bf16 v[104:107], v[156:159], v[180:183], v[104:107]
	v_mfma_f32_16x16x32_bf16 v[96:99], v[148:151], v[188:191], v[96:99]
	v_mfma_f32_16x16x32_bf16 v[88:91], v[156:159], v[188:191], v[88:91]
	v_mfma_f32_16x16x32_bf16 v[80:83], v[148:151], v[196:199], v[80:83]
	v_mfma_f32_16x16x32_bf16 v[72:75], v[156:159], v[196:199], v[72:75]
	s_barrier
	s_setprio 0
	s_add_i32 s21, 0, 0x1c000
	s_add_i32 s16, s20, s40
	v_add_u32_e32 v214, s21, v164
	s_add_u32 s8, s34, 0x80
	s_addc_u32 s9, s35, 0
	s_mov_b32 m0, s16
	ds_read_b128 v[202:205], v214
	ds_read_b128 v[206:209], v214 offset:1024
	ds_read_b128 v[210:213], v214 offset:2048
	ds_read_b128 v[214:217], v214 offset:3072
	global_load_lds_dwordx4 v132, s[8:9]
	s_add_i32 m0, s16, 0x2000
	s_nop 0
	global_load_lds_dwordx4 v128, s[8:9]
	s_waitcnt vmcnt(8)
	s_waitcnt lgkmcnt(0)
	s_setprio 1
	s_barrier
	v_mfma_f32_16x16x32_bf16 v[112:115], v[202:205], v[168:171], v[112:115]
	v_mfma_f32_16x16x32_bf16 v[108:111], v[210:213], v[168:171], v[108:111]
	v_mfma_f32_16x16x32_bf16 v[100:103], v[202:205], v[176:179], v[100:103]
	v_mfma_f32_16x16x32_bf16 v[92:95], v[210:213], v[176:179], v[92:95]
	v_mfma_f32_16x16x32_bf16 v[84:87], v[202:205], v[184:187], v[84:87]
	v_mfma_f32_16x16x32_bf16 v[76:79], v[210:213], v[184:187], v[76:79]
	v_mfma_f32_16x16x32_bf16 v[68:71], v[202:205], v[192:195], v[68:71]
	v_mfma_f32_16x16x32_bf16 v[64:67], v[210:213], v[192:195], v[64:67]
	v_mfma_f32_16x16x32_bf16 v[112:115], v[206:209], v[172:175], v[112:115]
	v_mfma_f32_16x16x32_bf16 v[108:111], v[214:217], v[172:175], v[108:111]
	v_mfma_f32_16x16x32_bf16 v[100:103], v[206:209], v[180:183], v[100:103]
	v_mfma_f32_16x16x32_bf16 v[92:95], v[214:217], v[180:183], v[92:95]
	v_mfma_f32_16x16x32_bf16 v[84:87], v[206:209], v[188:191], v[84:87]
	v_mfma_f32_16x16x32_bf16 v[76:79], v[214:217], v[188:191], v[76:79]
	v_mfma_f32_16x16x32_bf16 v[68:71], v[206:209], v[196:199], v[68:71]
	v_mfma_f32_16x16x32_bf16 v[64:67], v[214:217], v[196:199], v[64:67]
	s_mov_b32 m0, s52
	s_add_u32 s8, s36, 0x80
	s_addc_u32 s9, s37, 0
	s_barrier
	s_setprio 0
	ds_read_b128 v[168:171], v166 offset:49152
	ds_read_b128 v[172:175], v166 offset:50176
	ds_read_b128 v[176:179], v166 offset:51200
	ds_read_b128 v[180:183], v166 offset:52224
	ds_read_b128 v[184:187], v166 offset:53248
	ds_read_b128 v[188:191], v166 offset:54272
	ds_read_b128 v[192:195], v166 offset:55296
	ds_read_b128 v[196:199], v166 offset:56320
	global_load_lds_dwordx4 v134, s[8:9]
	s_mov_b32 m0, s53
	s_nop 0
	global_load_lds_dwordx4 v130, s[8:9]
	s_waitcnt lgkmcnt(0)
	s_setprio 1
	s_barrier
; #define PG8_STAGE(bufoff, gbase, voff) do { _Pragma("unroll") for (int _i = 0; _i < 2; ++_i) \
;         __builtin_amdgcn_global_load_lds((const unsigned*)((const char*)(gbase) + (voff)[_i]), (LAS unsigned*)(lds + (bufoff) + ldsw + _i * 8192), 16, 0, 0); } while (0)
; #define PG8_LDA(dst, b, h) do { _Pragma("unroll") for (int m = 0; m < 4; ++m) _Pragma("unroll") for (int k = 0; k < 2; ++k) dst[m][k] = *(const LAS bf16x8*)(lds + PG8_SA(b, h) + aoff + m * 2048 + k * 1024); } while (0)
; #define PG8_WAIT_V(n) asm volatile("s_waitcnt vmcnt(" #n ")" ::: "memory")
; #define PG8_WAIT_L(n) asm volatile("s_waitcnt lgkmcnt(" #n ")" ::: "memory")
; template <class Epi, class Sched>
; __device__ __forceinline__ void gemm_phase(LAS unsigned char* lds, const Gemm g, const Sched& S, const Epi& E) {
;     ...
;         for (int t = 0; t < nt; t += 2) {
;             const bool last = (t == nt - 2);
;             const char* a1 = cA + (size_t)(t + 1) * kstep;
;             const char* a2 = last ? nA : cA + (size_t)(t + 2) * kstep; const char* b2 = last ? nB : cB + (size_t)(t + 2) * kstep;
;             const char* a3 = a2 + kstep; const char* b3 = b2 + kstep;
;             PG8_LDB(B0, 0, 0); PG8_SCHED; PG8_LDA(At, 0, 0); PG8_STAGE(PG8_SA(1, 1), a1 + hstep, voffA);
;             PG8_WAIT_L(8); PG8_BAR; PG8_WAIT_L(0); PG8_MMA(0, 0, At, B0); PG8_BAR; PG8_SCHED;
;             PG8_LDB(B1, 0, 1); PG8_STAGE(PG8_SB(0, 0), b2, voffB);
;             PG8_BAR; PG8_WAIT_L(0); PG8_MMA(0, 1, At, B1); PG8_BAR;
;             PG8_LDA(At, 0, 1); PG8_STAGE(PG8_SA(0, 0), a2, voffA);
;             PG8_BAR; PG8_WAIT_L(0); PG8_MMA(1, 0, At, B0); PG8_BAR; PG8_SCHED;
;             PG8_STAGE(PG8_SB(0, 1), b2 + hstep, voffB);
;             PG8_WAIT_V(6); PG8_BAR; PG8_MMA(1, 1, At, B1); PG8_BAR;
;             PG8_LDB(B0, 1, 0); PG8_SCHED; PG8_LDA(At, 1, 0); PG8_STAGE(PG8_SA(0, 1), a2 + hstep, voffA);
;             PG8_WAIT_L(8); PG8_BAR; PG8_WAIT_L(0); PG8_MMA(0, 0, At, B0); PG8_BAR; PG8_SCHED;
;             PG8_LDB(B1, 1, 1); PG8_STAGE(PG8_SB(1, 0), b3, voffB);
;             PG8_BAR; PG8_WAIT_L(0); PG8_MMA(0, 1, At, B1); PG8_BAR;
;             PG8_LDA(At, 1, 1); PG8_STAGE(PG8_SA(1, 0), a3, voffA);
;             PG8_BAR; PG8_WAIT_L(0); PG8_MMA(1, 0, At, B0); PG8_BAR; PG8_SCHED;
;             PG8_STAGE(PG8_SB(1, 1), b3 + hstep, voffB);
;             PG8_WAIT_V(6); PG8_BAR; PG8_MMA(1, 1, At, B1); PG8_BAR;
	v_mfma_f32_16x16x32_bf16 v[60:63], v[144:147], v[168:171], v[60:63]
	v_mfma_f32_16x16x32_bf16 v[56:59], v[152:155], v[168:171], v[56:59]
	v_mfma_f32_16x16x32_bf16 v[48:51], v[144:147], v[176:179], v[48:51]
	v_mfma_f32_16x16x32_bf16 v[40:43], v[152:155], v[176:179], v[40:43]
	v_mfma_f32_16x16x32_bf16 v[32:35], v[144:147], v[184:187], v[32:35]
	v_mfma_f32_16x16x32_bf16 v[24:27], v[152:155], v[184:187], v[24:27]
	v_mfma_f32_16x16x32_bf16 v[16:19], v[144:147], v[192:195], v[16:19]
	v_mfma_f32_16x16x32_bf16 v[8:11], v[152:155], v[192:195], v[8:11]
	v_mfma_f32_16x16x32_bf16 v[60:63], v[148:151], v[172:175], v[60:63]
	v_mfma_f32_16x16x32_bf16 v[56:59], v[156:159], v[172:175], v[56:59]
	v_mfma_f32_16x16x32_bf16 v[48:51], v[148:151], v[180:183], v[48:51]
	v_mfma_f32_16x16x32_bf16 v[40:43], v[156:159], v[180:183], v[40:43]
	v_mfma_f32_16x16x32_bf16 v[32:35], v[148:151], v[188:191], v[32:35]
	v_mfma_f32_16x16x32_bf16 v[24:27], v[156:159], v[188:191], v[24:27]
	v_mfma_f32_16x16x32_bf16 v[16:19], v[148:151], v[196:199], v[16:19]
	v_mfma_f32_16x16x32_bf16 v[8:11], v[156:159], v[196:199], v[8:11]
	s_barrier
	s_setprio 0
	s_add_u32 s16, s34, 0xb0080
	s_addc_u32 s17, s35, 0
	s_add_i32 s20, s21, s40
	s_mov_b32 m0, s20
	s_nop 0
	global_load_lds_dwordx4 v132, s[16:17]
	s_add_i32 m0, s20, 0x2000
	s_nop 0
	global_load_lds_dwordx4 v128, s[16:17]
	s_waitcnt vmcnt(8)
	s_setprio 1
	s_barrier
	v_mfma_f32_16x16x32_bf16 v[52:55], v[202:205], v[168:171], v[52:55]
	v_mfma_f32_16x16x32_bf16 v[44:47], v[210:213], v[168:171], v[44:47]
	v_mfma_f32_16x16x32_bf16 v[36:39], v[202:205], v[176:179], v[36:39]
	v_mfma_f32_16x16x32_bf16 v[28:31], v[210:213], v[176:179], v[28:31]
	v_mfma_f32_16x16x32_bf16 v[20:23], v[202:205], v[184:187], v[20:23]
	v_mfma_f32_16x16x32_bf16 v[12:15], v[210:213], v[184:187], v[12:15]
	v_mfma_f32_16x16x32_bf16 v[4:7], v[202:205], v[192:195], v[4:7]
	v_mfma_f32_16x16x32_bf16 v[0:3], v[210:213], v[192:195], v[0:3]
	v_mfma_f32_16x16x32_bf16 v[52:55], v[206:209], v[172:175], v[52:55]
	v_mfma_f32_16x16x32_bf16 v[44:47], v[214:217], v[172:175], v[44:47]
	v_mfma_f32_16x16x32_bf16 v[36:39], v[206:209], v[180:183], v[36:39]
	v_mfma_f32_16x16x32_bf16 v[28:31], v[214:217], v[180:183], v[28:31]
	v_mfma_f32_16x16x32_bf16 v[20:23], v[206:209], v[188:191], v[20:23]
	v_mfma_f32_16x16x32_bf16 v[12:15], v[214:217], v[188:191], v[12:15]
	v_mfma_f32_16x16x32_bf16 v[4:7], v[206:209], v[196:199], v[4:7]
	v_mfma_f32_16x16x32_bf16 v[0:3], v[214:217], v[196:199], v[0:3]
	s_add_i32 s68, s68, 2
	s_add_u32 s0, s0, 0x100
	s_addc_u32 s67, s67, 0
	s_cmp_gt_u32 s68, 41
	s_mov_b64 s[26:27], s[28:29]
	s_barrier
	s_setprio 0
.LBB0_305:
	ds_read_b128 v[144:147], v165
	ds_read_b128 v[148:151], v165 offset:1024
	ds_read_b128 v[152:155], v165 offset:2048
	ds_read_b128 v[156:159], v165 offset:3072
	s_add_u32 s28, s26, 0x100
	s_addc_u32 s29, s27, 0
	s_cmp_eq_u32 s68, 40
	s_cselect_b32 s37, s5, s29
	s_cselect_b32 s36, s4, s28
	s_cselect_b32 s35, s7, s67
	s_cselect_b32 s34, s6, s0
	v_lshl_add_u64 v[160:161], s[26:27], 0, v[136:137]
	s_add_i32 m0, s42, 0xc000
	ds_read_b128 v[168:171], v166
	ds_read_b128 v[172:175], v166 offset:1024
	ds_read_b128 v[176:179], v166 offset:2048
	ds_read_b128 v[180:183], v166 offset:3072
	ds_read_b128 v[184:187], v166 offset:4096
	ds_read_b128 v[188:191], v166 offset:5120
	ds_read_b128 v[192:195], v166 offset:6144
	ds_read_b128 v[196:199], v166 offset:7168
	global_load_lds_dwordx4 v[160:161], off
	v_lshl_add_u64 v[160:161], s[26:27], 0, v[138:139]
	s_add_i32 m0, s42, 0xe000
	s_nop 0
	global_load_lds_dwordx4 v[160:161], off
	s_waitcnt lgkmcnt(8)
	s_waitcnt vmcnt(8)
	s_waitcnt lgkmcnt(0)
	s_setprio 1
	s_barrier
	v_mfma_f32_16x16x32_bf16 v[124:127], v[144:147], v[168:171], v[124:127]
	v_mfma_f32_16x16x32_bf16 v[120:123], v[152:155], v[168:171], v[120:123]
	v_mfma_f32_16x16x32_bf16 v[116:119], v[144:147], v[176:179], v[116:119]
	v_mfma_f32_16x16x32_bf16 v[104:107], v[152:155], v[176:179], v[104:107]
	v_mfma_f32_16x16x32_bf16 v[96:99], v[144:147], v[184:187], v[96:99]
	v_mfma_f32_16x16x32_bf16 v[88:91], v[152:155], v[184:187], v[88:91]
	v_mfma_f32_16x16x32_bf16 v[80:83], v[144:147], v[192:195], v[80:83]
	v_mfma_f32_16x16x32_bf16 v[72:75], v[152:155], v[192:195], v[72:75]
	v_mfma_f32_16x16x32_bf16 v[124:127], v[148:151], v[172:175], v[124:127]
	v_mfma_f32_16x16x32_bf16 v[120:123], v[156:159], v[172:175], v[120:123]
	v_mfma_f32_16x16x32_bf16 v[116:119], v[148:151], v[180:183], v[116:119]
	v_mfma_f32_16x16x32_bf16 v[104:107], v[156:159], v[180:183], v[104:107]
	v_mfma_f32_16x16x32_bf16 v[96:99], v[148:151], v[188:191], v[96:99]
	v_mfma_f32_16x16x32_bf16 v[88:91], v[156:159], v[188:191], v[88:91]
	v_mfma_f32_16x16x32_bf16 v[80:83], v[148:151], v[196:199], v[80:83]
	v_mfma_f32_16x16x32_bf16 v[72:75], v[156:159], v[196:199], v[72:75]
	s_barrier
	s_setprio 0
	s_add_i32 s16, s58, s40
	s_mov_b32 m0, s16
	ds_read_b128 v[202:205], v167
	ds_read_b128 v[206:209], v167 offset:1024
	ds_read_b128 v[210:213], v167 offset:2048
	ds_read_b128 v[214:217], v167 offset:3072
	global_load_lds_dwordx4 v132, s[34:35]
	s_add_i32 m0, s16, 0x2000
	s_nop 0
	global_load_lds_dwordx4 v128, s[34:35]
	s_waitcnt vmcnt(8)
	s_waitcnt lgkmcnt(0)
	s_setprio 1
	s_barrier
; #define PG8_STAGE(bufoff, gbase, voff) do { _Pragma("unroll") for (int _i = 0; _i < 2; ++_i) \
;         __builtin_amdgcn_global_load_lds((const unsigned*)((const char*)(gbase) + (voff)[_i]), (LAS unsigned*)(lds + (bufoff) + ldsw + _i * 8192), 16, 0, 0); } while (0)
; #define PG8_LDA(dst, b, h) do { _Pragma("unroll") for (int m = 0; m < 4; ++m) _Pragma("unroll") for (int k = 0; k < 2; ++k) dst[m][k] = *(const LAS bf16x8*)(lds + PG8_SA(b, h) + aoff + m * 2048 + k * 1024); } while (0)
; #define PG8_LDB(dst, b, h) do { _Pragma("unroll") for (int n = 0; n < 2; ++n) _Pragma("unroll") for (int k = 0; k < 2; ++k) dst[n][k] = *(const LAS bf16x8*)(lds + PG8_SB(b, h) + boff + n * 2048 + k * 1024); } while (0)
; #define PG8_MMA(ai, bj, At, Bt) do { __builtin_amdgcn_s_setprio(1); _Pragma("unroll") for (int m = 0; m < 4; ++m) _Pragma("unroll") for (int n = 0; n < 2; ++n) _Pragma("unroll") for (int k = 0; k < 2; ++k) \
;         acc[ai][bj][m][n] = __builtin_amdgcn_mfma_f32_16x16x32_bf16(Bt[n][k], At[m][k], acc[ai][bj][m][n], 0, 0, 0); __builtin_amdgcn_s_setprio(0); } while (0)
; #define PG8_WAIT_V(n) asm volatile("s_waitcnt vmcnt(" #n ")" ::: "memory")
; #define PG8_WAIT_L(n) asm volatile("s_waitcnt lgkmcnt(" #n ")" ::: "memory")
; #define PG8_BAR __builtin_amdgcn_s_barrier()
; #define PG8_SCHED __builtin_amdgcn_sched_barrier(0)
; template <class Epi, class Sched>
; __device__ __forceinline__ void gemm_phase(LAS unsigned char* lds, const Gemm g, const Sched& S, const Epi& E) {
;     ...
;             PG8_LDB(B1, 0, 1); PG8_STAGE(PG8_SB(0, 0), b2, voffB);
;             PG8_BAR; PG8_WAIT_L(0); PG8_MMA(0, 1, At, B1); PG8_BAR;
;             PG8_LDA(At, 0, 1); PG8_STAGE(PG8_SA(0, 0), a2, voffA);
;             PG8_BAR; PG8_WAIT_L(0); PG8_MMA(1, 0, At, B0); PG8_BAR; PG8_SCHED;
;             PG8_STAGE(PG8_SB(0, 1), b2 + hstep, voffB);
;             PG8_WAIT_V(6); PG8_BAR; PG8_MMA(1, 1, At, B1); PG8_BAR;
;             PG8_LDB(B0, 1, 0); PG8_SCHED; PG8_LDA(At, 1, 0); PG8_STAGE(PG8_SA(0, 1), a2 + hstep, voffA);
;             PG8_WAIT_L(8); PG8_BAR; PG8_WAIT_L(0); PG8_MMA(0, 0, At, B0); PG8_BAR; PG8_SCHED;
	v_mfma_f32_16x16x32_bf16 v[112:115], v[202:205], v[168:171], v[112:115]
	v_mfma_f32_16x16x32_bf16 v[108:111], v[210:213], v[168:171], v[108:111]
	v_mfma_f32_16x16x32_bf16 v[100:103], v[202:205], v[176:179], v[100:103]
	v_mfma_f32_16x16x32_bf16 v[92:95], v[210:213], v[176:179], v[92:95]
	v_mfma_f32_16x16x32_bf16 v[84:87], v[202:205], v[184:187], v[84:87]
	v_mfma_f32_16x16x32_bf16 v[76:79], v[210:213], v[184:187], v[76:79]
	v_mfma_f32_16x16x32_bf16 v[68:71], v[202:205], v[192:195], v[68:71]
	v_mfma_f32_16x16x32_bf16 v[64:67], v[210:213], v[192:195], v[64:67]
	v_mfma_f32_16x16x32_bf16 v[112:115], v[206:209], v[172:175], v[112:115]
	v_mfma_f32_16x16x32_bf16 v[108:111], v[214:217], v[172:175], v[108:111]
	v_mfma_f32_16x16x32_bf16 v[100:103], v[206:209], v[180:183], v[100:103]
	v_mfma_f32_16x16x32_bf16 v[92:95], v[214:217], v[180:183], v[92:95]
	v_mfma_f32_16x16x32_bf16 v[84:87], v[206:209], v[188:191], v[84:87]
	v_mfma_f32_16x16x32_bf16 v[76:79], v[214:217], v[188:191], v[76:79]
	v_mfma_f32_16x16x32_bf16 v[68:71], v[206:209], v[196:199], v[68:71]
	v_mfma_f32_16x16x32_bf16 v[64:67], v[214:217], v[196:199], v[64:67]
	s_mov_b32 m0, s42
	s_barrier
	s_setprio 0
	ds_read_b128 v[168:171], v166 offset:16384
	ds_read_b128 v[172:175], v166 offset:17408
	ds_read_b128 v[176:179], v166 offset:18432
	ds_read_b128 v[180:183], v166 offset:19456
	ds_read_b128 v[184:187], v166 offset:20480
	ds_read_b128 v[188:191], v166 offset:21504
	ds_read_b128 v[192:195], v166 offset:22528
	ds_read_b128 v[196:199], v166 offset:23552
	global_load_lds_dwordx4 v134, s[36:37]
	s_mov_b32 m0, s43
	s_nop 0
	global_load_lds_dwordx4 v130, s[36:37]
	s_waitcnt lgkmcnt(0)
	s_setprio 1
	s_barrier
	v_mfma_f32_16x16x32_bf16 v[60:63], v[144:147], v[168:171], v[60:63]
	v_mfma_f32_16x16x32_bf16 v[56:59], v[152:155], v[168:171], v[56:59]
	v_mfma_f32_16x16x32_bf16 v[48:51], v[144:147], v[176:179], v[48:51]
	v_mfma_f32_16x16x32_bf16 v[40:43], v[152:155], v[176:179], v[40:43]
	v_mfma_f32_16x16x32_bf16 v[32:35], v[144:147], v[184:187], v[32:35]
	v_mfma_f32_16x16x32_bf16 v[24:27], v[152:155], v[184:187], v[24:27]
	v_mfma_f32_16x16x32_bf16 v[16:19], v[144:147], v[192:195], v[16:19]
	v_mfma_f32_16x16x32_bf16 v[8:11], v[152:155], v[192:195], v[8:11]
	v_mfma_f32_16x16x32_bf16 v[60:63], v[148:151], v[172:175], v[60:63]
	v_mfma_f32_16x16x32_bf16 v[56:59], v[156:159], v[172:175], v[56:59]
	v_mfma_f32_16x16x32_bf16 v[48:51], v[148:151], v[180:183], v[48:51]
	v_mfma_f32_16x16x32_bf16 v[40:43], v[156:159], v[180:183], v[40:43]
	v_mfma_f32_16x16x32_bf16 v[32:35], v[148:151], v[188:191], v[32:35]
	v_mfma_f32_16x16x32_bf16 v[24:27], v[156:159], v[188:191], v[24:27]
	v_mfma_f32_16x16x32_bf16 v[16:19], v[148:151], v[196:199], v[16:19]
	v_mfma_f32_16x16x32_bf16 v[8:11], v[156:159], v[196:199], v[8:11]
	s_barrier
	s_setprio 0
	s_add_u32 s16, s34, 0xb0000
	s_addc_u32 s17, s35, 0
	s_add_i32 s20, s59, s40
	s_mov_b32 m0, s20
	s_nop 0
	global_load_lds_dwordx4 v132, s[16:17]
	s_add_i32 m0, s20, 0x2000
	s_nop 0
	global_load_lds_dwordx4 v128, s[16:17]
	s_add_u32 s16, s36, 0xb0000
	s_addc_u32 s17, s37, 0
	s_mov_b32 m0, s44
	s_nop 0
	global_load_lds_dwordx4 v134, s[16:17]
	s_mov_b32 m0, s45
	s_nop 0
	global_load_lds_dwordx4 v130, s[16:17]
	s_waitcnt vmcnt(10)
	s_setprio 1
	s_barrier
	v_mfma_f32_16x16x32_bf16 v[52:55], v[202:205], v[168:171], v[52:55]
	v_mfma_f32_16x16x32_bf16 v[44:47], v[210:213], v[168:171], v[44:47]
	v_mfma_f32_16x16x32_bf16 v[36:39], v[202:205], v[176:179], v[36:39]
	v_mfma_f32_16x16x32_bf16 v[28:31], v[210:213], v[176:179], v[28:31]
	v_mfma_f32_16x16x32_bf16 v[20:23], v[202:205], v[184:187], v[20:23]
	v_mfma_f32_16x16x32_bf16 v[12:15], v[210:213], v[184:187], v[12:15]
	v_mfma_f32_16x16x32_bf16 v[4:7], v[202:205], v[192:195], v[4:7]
	v_mfma_f32_16x16x32_bf16 v[0:3], v[210:213], v[192:195], v[0:3]
	v_mfma_f32_16x16x32_bf16 v[52:55], v[206:209], v[172:175], v[52:55]
	v_mfma_f32_16x16x32_bf16 v[44:47], v[214:217], v[172:175], v[44:47]
	v_mfma_f32_16x16x32_bf16 v[36:39], v[206:209], v[180:183], v[36:39]
	v_mfma_f32_16x16x32_bf16 v[28:31], v[214:217], v[180:183], v[28:31]
	v_mfma_f32_16x16x32_bf16 v[20:23], v[206:209], v[188:191], v[20:23]
	v_mfma_f32_16x16x32_bf16 v[12:15], v[214:217], v[188:191], v[12:15]
	v_mfma_f32_16x16x32_bf16 v[4:7], v[206:209], v[196:199], v[4:7]
	v_mfma_f32_16x16x32_bf16 v[0:3], v[214:217], v[196:199], v[0:3]
	s_add_i32 s20, 0, 0x18000
	v_add_u32_e32 v156, s20, v164
	s_barrier
	s_setprio 0
	ds_read_b128 v[144:147], v156
	ds_read_b128 v[148:151], v156 offset:1024
	ds_read_b128 v[152:155], v156 offset:2048
	ds_read_b128 v[156:159], v156 offset:3072
	ds_read_b128 v[168:171], v166 offset:32768
	ds_read_b128 v[172:175], v166 offset:33792
	ds_read_b128 v[176:179], v166 offset:34816
	ds_read_b128 v[180:183], v166 offset:35840
	ds_read_b128 v[184:187], v166 offset:36864
	ds_read_b128 v[188:191], v166 offset:37888
	ds_read_b128 v[192:195], v166 offset:38912
	ds_read_b128 v[196:199], v166 offset:39936
	s_waitcnt lgkmcnt(8)
	s_waitcnt vmcnt(8)
	s_waitcnt lgkmcnt(0)
	s_setprio 1
	s_barrier
	v_mfma_f32_16x16x32_bf16 v[124:127], v[144:147], v[168:171], v[124:127]
	v_mfma_f32_16x16x32_bf16 v[120:123], v[152:155], v[168:171], v[120:123]
	v_mfma_f32_16x16x32_bf16 v[116:119], v[144:147], v[176:179], v[116:119]
	v_mfma_f32_16x16x32_bf16 v[104:107], v[152:155], v[176:179], v[104:107]
	v_mfma_f32_16x16x32_bf16 v[96:99], v[144:147], v[184:187], v[96:99]
	v_mfma_f32_16x16x32_bf16 v[88:91], v[152:155], v[184:187], v[88:91]
	v_mfma_f32_16x16x32_bf16 v[80:83], v[144:147], v[192:195], v[80:83]
	v_mfma_f32_16x16x32_bf16 v[72:75], v[152:155], v[192:195], v[72:75]
	v_mfma_f32_16x16x32_bf16 v[124:127], v[148:151], v[172:175], v[124:127]
	v_mfma_f32_16x16x32_bf16 v[120:123], v[156:159], v[172:175], v[120:123]
	v_mfma_f32_16x16x32_bf16 v[116:119], v[148:151], v[180:183], v[116:119]
	v_mfma_f32_16x16x32_bf16 v[104:107], v[156:159], v[180:183], v[104:107]
	v_mfma_f32_16x16x32_bf16 v[96:99], v[148:151], v[188:191], v[96:99]
	v_mfma_f32_16x16x32_bf16 v[88:91], v[156:159], v[188:191], v[88:91]
	v_mfma_f32_16x16x32_bf16 v[80:83], v[148:151], v[196:199], v[80:83]
	v_mfma_f32_16x16x32_bf16 v[72:75], v[156:159], v[196:199], v[72:75]
	s_barrier
; #define PG8_STAGE(bufoff, gbase, voff) do { _Pragma("unroll") for (int _i = 0; _i < 2; ++_i) \
;         __builtin_amdgcn_global_load_lds((const unsigned*)((const char*)(gbase) + (voff)[_i]), (LAS unsigned*)(lds + (bufoff) + ldsw + _i * 8192), 16, 0, 0); } while (0)
; #define PG8_LDA(dst, b, h) do { _Pragma("unroll") for (int m = 0; m < 4; ++m) _Pragma("unroll") for (int k = 0; k < 2; ++k) dst[m][k] = *(const LAS bf16x8*)(lds + PG8_SA(b, h) + aoff + m * 2048 + k * 1024); } while (0)
; #define PG8_LDB(dst, b, h) do { _Pragma("unroll") for (int n = 0; n < 2; ++n) _Pragma("unroll") for (int k = 0; k < 2; ++k) dst[n][k] = *(const LAS bf16x8*)(lds + PG8_SB(b, h) + boff + n * 2048 + k * 1024); } while (0)
; #define PG8_MMA(ai, bj, At, Bt) do { __builtin_amdgcn_s_setprio(1); _Pragma("unroll") for (int m = 0; m < 4; ++m) _Pragma("unroll") for (int n = 0; n < 2; ++n) _Pragma("unroll") for (int k = 0; k < 2; ++k) \
;         acc[ai][bj][m][n] = __builtin_amdgcn_mfma_f32_16x16x32_bf16(Bt[n][k], At[m][k], acc[ai][bj][m][n], 0, 0, 0); __builtin_amdgcn_s_setprio(0); } while (0)
; #define PG8_WAIT_V(n) asm volatile("s_waitcnt vmcnt(" #n ")" ::: "memory")
; #define PG8_WAIT_L(n) asm volatile("s_waitcnt lgkmcnt(" #n ")" ::: "memory")
; #define PG8_BAR __builtin_amdgcn_s_barrier()
; template <class Epi, class Sched>
; __device__ __forceinline__ void gemm_phase(LAS unsigned char* lds, const Gemm g, const Sched& S, const Epi& E) {
;     ...
;             PG8_WAIT_L(8); PG8_BAR; PG8_WAIT_L(0); PG8_MMA(0, 0, At, B0); PG8_BAR; PG8_SCHED;
;             PG8_LDB(B1, 1, 1); PG8_STAGE(PG8_SB(1, 0), b3, voffB);
;             PG8_BAR; PG8_WAIT_L(0); PG8_MMA(0, 1, At, B1); PG8_BAR;
;             PG8_LDA(At, 1, 1); PG8_STAGE(PG8_SA(1, 0), a3, voffA);
;             PG8_BAR; PG8_WAIT_L(0); PG8_MMA(1, 0, At, B0); PG8_BAR; PG8_SCHED;
;             PG8_STAGE(PG8_SB(1, 1), b3 + hstep, voffB);
;             PG8_WAIT_V(6); PG8_BAR; PG8_MMA(1, 1, At, B1); PG8_BAR;
;     __device__ __forceinline__ void operator()(const AccT& acc, const Unit& u, int wr, int wc, int fr, int fq) const {
;     ...
;         const int rowt = u.pm * 256; const bool isc = rowt >= MX;
;         const int b = isc ? 32 : (rowt >> 11);
;         const float* res = isc ? res_c + (size_t)(rowt - MX) * DM : res_x + (size_t)rowt * DM;
;         float* out = isc ? out_c + (size_t)(rowt - MX) * DM : out_x + (size_t)rowt * DM;
	s_setprio 0
	s_add_i32 s21, 0, 0x1c000
	s_add_i32 s16, s20, s40
	v_add_u32_e32 v214, s21, v164
	s_add_u32 s8, s34, 0x80
	s_addc_u32 s9, s35, 0
	s_mov_b32 m0, s16
	ds_read_b128 v[202:205], v214
	ds_read_b128 v[206:209], v214 offset:1024
	ds_read_b128 v[210:213], v214 offset:2048
	ds_read_b128 v[214:217], v214 offset:3072
	global_load_lds_dwordx4 v132, s[8:9]
	s_add_i32 m0, s16, 0x2000
	s_nop 0
	global_load_lds_dwordx4 v128, s[8:9]
	s_waitcnt vmcnt(8)
	s_waitcnt lgkmcnt(0)
	s_setprio 1
	s_barrier
	v_mfma_f32_16x16x32_bf16 v[112:115], v[202:205], v[168:171], v[112:115]
	v_mfma_f32_16x16x32_bf16 v[108:111], v[210:213], v[168:171], v[108:111]
	v_mfma_f32_16x16x32_bf16 v[100:103], v[202:205], v[176:179], v[100:103]
	v_mfma_f32_16x16x32_bf16 v[92:95], v[210:213], v[176:179], v[92:95]
	v_mfma_f32_16x16x32_bf16 v[84:87], v[202:205], v[184:187], v[84:87]
	v_mfma_f32_16x16x32_bf16 v[76:79], v[210:213], v[184:187], v[76:79]
	v_mfma_f32_16x16x32_bf16 v[68:71], v[202:205], v[192:195], v[68:71]
	v_mfma_f32_16x16x32_bf16 v[64:67], v[210:213], v[192:195], v[64:67]
	v_mfma_f32_16x16x32_bf16 v[112:115], v[206:209], v[172:175], v[112:115]
	v_mfma_f32_16x16x32_bf16 v[108:111], v[214:217], v[172:175], v[108:111]
	v_mfma_f32_16x16x32_bf16 v[100:103], v[206:209], v[180:183], v[100:103]
	v_mfma_f32_16x16x32_bf16 v[92:95], v[214:217], v[180:183], v[92:95]
	v_mfma_f32_16x16x32_bf16 v[84:87], v[206:209], v[188:191], v[84:87]
	v_mfma_f32_16x16x32_bf16 v[76:79], v[214:217], v[188:191], v[76:79]
	v_mfma_f32_16x16x32_bf16 v[68:71], v[206:209], v[196:199], v[68:71]
	v_mfma_f32_16x16x32_bf16 v[64:67], v[214:217], v[196:199], v[64:67]
	s_mov_b32 m0, s52
	s_add_u32 s8, s36, 0x80
	s_addc_u32 s9, s37, 0
	s_barrier
	s_setprio 0
	ds_read_b128 v[168:171], v166 offset:49152
	ds_read_b128 v[172:175], v166 offset:50176
	ds_read_b128 v[176:179], v166 offset:51200
	ds_read_b128 v[180:183], v166 offset:52224
	ds_read_b128 v[184:187], v166 offset:53248
	ds_read_b128 v[188:191], v166 offset:54272
	ds_read_b128 v[192:195], v166 offset:55296
	ds_read_b128 v[196:199], v166 offset:56320
	global_load_lds_dwordx4 v134, s[8:9]
	s_mov_b32 m0, s53
	s_nop 0
	global_load_lds_dwordx4 v130, s[8:9]
	s_waitcnt lgkmcnt(0)
	s_setprio 1
	s_barrier
	v_mfma_f32_16x16x32_bf16 v[60:63], v[144:147], v[168:171], v[60:63]
	v_mfma_f32_16x16x32_bf16 v[56:59], v[152:155], v[168:171], v[56:59]
	v_mfma_f32_16x16x32_bf16 v[48:51], v[144:147], v[176:179], v[48:51]
	v_mfma_f32_16x16x32_bf16 v[40:43], v[152:155], v[176:179], v[40:43]
	v_mfma_f32_16x16x32_bf16 v[32:35], v[144:147], v[184:187], v[32:35]
	v_mfma_f32_16x16x32_bf16 v[24:27], v[152:155], v[184:187], v[24:27]
	v_mfma_f32_16x16x32_bf16 v[16:19], v[144:147], v[192:195], v[16:19]
	v_mfma_f32_16x16x32_bf16 v[8:11], v[152:155], v[192:195], v[8:11]
	v_mfma_f32_16x16x32_bf16 v[60:63], v[148:151], v[172:175], v[60:63]
	v_mfma_f32_16x16x32_bf16 v[56:59], v[156:159], v[172:175], v[56:59]
	v_mfma_f32_16x16x32_bf16 v[48:51], v[148:151], v[180:183], v[48:51]
	v_mfma_f32_16x16x32_bf16 v[40:43], v[156:159], v[180:183], v[40:43]
	v_mfma_f32_16x16x32_bf16 v[32:35], v[148:151], v[188:191], v[32:35]
	v_mfma_f32_16x16x32_bf16 v[24:27], v[156:159], v[188:191], v[24:27]
	v_mfma_f32_16x16x32_bf16 v[16:19], v[148:151], v[196:199], v[16:19]
	v_mfma_f32_16x16x32_bf16 v[8:11], v[156:159], v[196:199], v[8:11]
	s_barrier
	s_setprio 0
	s_add_u32 s16, s34, 0xb0080
	s_addc_u32 s17, s35, 0
	s_add_i32 s20, s21, s40
	s_mov_b32 m0, s20
	s_nop 0
	global_load_lds_dwordx4 v132, s[16:17]
	s_add_i32 m0, s20, 0x2000
	s_nop 0
	global_load_lds_dwordx4 v128, s[16:17]
	s_waitcnt vmcnt(8)
	s_setprio 1
	s_barrier
	v_mfma_f32_16x16x32_bf16 v[52:55], v[202:205], v[168:171], v[52:55]
	v_mfma_f32_16x16x32_bf16 v[44:47], v[210:213], v[168:171], v[44:47]
	v_mfma_f32_16x16x32_bf16 v[36:39], v[202:205], v[176:179], v[36:39]
	v_mfma_f32_16x16x32_bf16 v[28:31], v[210:213], v[176:179], v[28:31]
	v_mfma_f32_16x16x32_bf16 v[20:23], v[202:205], v[184:187], v[20:23]
	v_mfma_f32_16x16x32_bf16 v[12:15], v[210:213], v[184:187], v[12:15]
	v_mfma_f32_16x16x32_bf16 v[4:7], v[202:205], v[192:195], v[4:7]
	v_mfma_f32_16x16x32_bf16 v[0:3], v[210:213], v[192:195], v[0:3]
	v_mfma_f32_16x16x32_bf16 v[52:55], v[206:209], v[172:175], v[52:55]
	v_mfma_f32_16x16x32_bf16 v[44:47], v[214:217], v[172:175], v[44:47]
	v_mfma_f32_16x16x32_bf16 v[36:39], v[206:209], v[180:183], v[36:39]
	v_mfma_f32_16x16x32_bf16 v[28:31], v[214:217], v[180:183], v[28:31]
	v_mfma_f32_16x16x32_bf16 v[20:23], v[206:209], v[188:191], v[20:23]
	v_mfma_f32_16x16x32_bf16 v[12:15], v[214:217], v[188:191], v[12:15]
	v_mfma_f32_16x16x32_bf16 v[4:7], v[206:209], v[196:199], v[4:7]
	v_mfma_f32_16x16x32_bf16 v[0:3], v[214:217], v[196:199], v[0:3]
	s_add_i32 s68, s68, 2
	s_add_u32 s0, s0, 0x100
	s_addc_u32 s67, s67, 0
	s_cmp_gt_u32 s68, 41
	s_mov_b64 s[26:27], s[28:29]
	s_barrier
	s_setprio 0
	s_cbranch_scc0 .LBB0_305
	s_lshl_b32 s0, s66, 8
	v_mov_b32_e32 v145, v163
	v_mov_b32_e32 v144, v162
	s_cmpk_lt_i32 s66, 0x100
	s_cbranch_scc0 .LBB0_308
	s_ashr_i32 s29, s0, 31
	s_mov_b32 s28, s0
	s_lshl_b64 s[16:17], s[28:29], 12
	v_readlane_b32 s80, v254, 23
	v_readlane_b32 s81, v254, 24
	s_add_u32 s26, s80, s16
	v_readlane_b32 s82, v254, 25
	v_readlane_b32 s83, v254, 26
	v_readlane_b32 s84, v254, 27
	v_readlane_b32 s85, v254, 28
	v_readlane_b32 s86, v254, 29
	v_readlane_b32 s87, v254, 30
	v_readlane_b32 s88, v254, 31
	v_readlane_b32 s89, v254, 32
	v_readlane_b32 s90, v254, 33
	v_readlane_b32 s91, v254, 34
	v_readlane_b32 s92, v254, 35
	v_readlane_b32 s93, v254, 36
	v_readlane_b32 s94, v254, 37
	v_readlane_b32 s95, v254, 38
	s_addc_u32 s27, s81, s17
	s_cbranch_execnz .LBB0_297
	s_branch .LBB0_296

; #define PG8_STAGE(bufoff, gbase, voff) do { _Pragma("unroll") for (int _i = 0; _i < 2; ++_i) \
;         __builtin_amdgcn_global_load_lds((const unsigned*)((const char*)(gbase) + (voff)[_i]), (LAS unsigned*)(lds + (bufoff) + ldsw + _i * 8192), 16, 0, 0); } while (0)
; #define PG8_LDA(dst, b, h) do { _Pragma("unroll") for (int m = 0; m < 4; ++m) _Pragma("unroll") for (int k = 0; k < 2; ++k) dst[m][k] = *(const LAS bf16x8*)(lds + PG8_SA(b, h) + aoff + m * 2048 + k * 1024); } while (0)
; #define PG8_LDB(dst, b, h) do { _Pragma("unroll") for (int n = 0; n < 2; ++n) _Pragma("unroll") for (int k = 0; k < 2; ++k) dst[n][k] = *(const LAS bf16x8*)(lds + PG8_SB(b, h) + boff + n * 2048 + k * 1024); } while (0)
; #define PG8_MMA(ai, bj, At, Bt) do { __builtin_amdgcn_s_setprio(1); _Pragma("unroll") for (int m = 0; m < 4; ++m) _Pragma("unroll") for (int n = 0; n < 2; ++n) _Pragma("unroll") for (int k = 0; k < 2; ++k) \
;         acc[ai][bj][m][n] = __builtin_amdgcn_mfma_f32_16x16x32_bf16(Bt[n][k], At[m][k], acc[ai][bj][m][n], 0, 0, 0); __builtin_amdgcn_s_setprio(0); } while (0)
; #define PG8_WAIT_L(n) asm volatile("s_waitcnt lgkmcnt(" #n ")" ::: "memory")
; template <class Epi, class Sched>
; __device__ __forceinline__ void gemm_phase(LAS unsigned char* lds, const Gemm g, const Sched& S, const Epi& E) {
;     ...
;         const bool has_next = S.next(ui + 1, nxt);
;         const char* nA = has_next ? (const char*)g.A + (size_t)nxt.pm * tstep : cA; const char* nB = has_next ? (const char*)g.Bt + (size_t)nxt.pn * tstep : cB;
;         for (int t = 0; t < nt; t += 2) {
;             const bool last = (t == nt - 2);
;             const char* a1 = cA + (size_t)(t + 1) * kstep;
;             const char* a2 = last ? nA : cA + (size_t)(t + 2) * kstep; const char* b2 = last ? nB : cB + (size_t)(t + 2) * kstep;
;             const char* a3 = a2 + kstep; const char* b3 = b2 + kstep;
;             PG8_LDB(B0, 0, 0); PG8_SCHED; PG8_LDA(At, 0, 0); PG8_STAGE(PG8_SA(1, 1), a1 + hstep, voffA);
;             PG8_WAIT_L(8); PG8_BAR; PG8_WAIT_L(0); PG8_MMA(0, 0, At, B0); PG8_BAR; PG8_SCHED;
;             PG8_LDB(B1, 0, 1); PG8_STAGE(PG8_SB(0, 0), b2, voffB);
;             PG8_BAR; PG8_WAIT_L(0); PG8_MMA(0, 1, At, B1); PG8_BAR;
;             PG8_LDA(At, 0, 1); PG8_STAGE(PG8_SA(0, 0), a2, voffA);
;             PG8_BAR; PG8_WAIT_L(0); PG8_MMA(1, 0, At, B0); PG8_BAR; PG8_SCHED;
.LBB0_577:
	s_ashr_i32 s21, s20, 31
	v_cmp_lt_i64_e32 vcc, s[22:23], v[156:157]
	s_lshl_b64 s[22:23], s[20:21], 19
	s_add_u32 s22, s96, s22
	s_addc_u32 s23, s97, s23
	s_and_b64 s[24:25], vcc, exec
	s_cselect_b32 s5, s23, s7
	s_cselect_b32 s21, s22, s6
	s_ashr_i32 s19, s18, 31
	s_lshl_b64 s[24:25], s[18:19], 19
	s_add_u32 s24, s31, s24
	s_addc_u32 s25, s33, s25
	s_and_b64 s[28:29], vcc, exec
	s_cselect_b32 s19, s25, s27
	s_cselect_b32 s53, s24, s26
	s_add_u32 s6, s6, 0x40080
	s_addc_u32 s7, s7, 0
	s_add_u32 s54, s26, 0x100
	s_addc_u32 s55, s27, 0
	s_mov_b32 s56, -2
	s_waitcnt lgkmcnt(0)
	ds_read_b128 v[128:131], v167
	ds_read_b128 v[132:135], v167 offset:1024
	ds_read_b128 v[136:139], v167 offset:2048
	ds_read_b128 v[160:163], v167 offset:3072
	s_add_u32 s26, s6, 0xfffc0080
	s_addc_u32 s27, s7, -1
	s_cmp_eq_u32 s56, 12
	s_cselect_b32 s29, s5, s27
	s_cselect_b32 s28, s21, s26
	s_cselect_b32 s27, s19, s55
	s_cselect_b32 s26, s53, s54
	s_add_i32 m0, s37, 0xc000
	ds_read_b128 v[170:173], v168
	ds_read_b128 v[174:177], v168 offset:1024
	ds_read_b128 v[178:181], v168 offset:2048
	ds_read_b128 v[182:185], v168 offset:3072
	ds_read_b128 v[186:189], v168 offset:4096
	ds_read_b128 v[190:193], v168 offset:5120
	ds_read_b128 v[194:197], v168 offset:6144
	ds_read_b128 v[202:205], v168 offset:7168
	global_load_lds_dwordx4 v152, s[6:7]
	s_add_i32 m0, s37, 0xe000
	s_nop 0
	global_load_lds_dwordx4 v154, s[6:7]
	s_waitcnt lgkmcnt(8)
	s_waitcnt vmcnt(8)
	s_waitcnt lgkmcnt(0)
	s_setprio 1
	s_barrier
	v_mfma_f32_16x16x32_bf16 v[124:127], v[128:131], v[170:173], 0
	v_mfma_f32_16x16x32_bf16 v[120:123], v[136:139], v[170:173], 0
	v_mfma_f32_16x16x32_bf16 v[108:111], v[128:131], v[178:181], 0
	v_mfma_f32_16x16x32_bf16 v[104:107], v[136:139], v[178:181], 0
	v_mfma_f32_16x16x32_bf16 v[92:95], v[128:131], v[186:189], 0
	v_mfma_f32_16x16x32_bf16 v[88:91], v[136:139], v[186:189], 0
	v_mfma_f32_16x16x32_bf16 v[76:79], v[128:131], v[194:197], 0
	v_mfma_f32_16x16x32_bf16 v[72:75], v[136:139], v[194:197], 0
	v_mfma_f32_16x16x32_bf16 v[124:127], v[132:135], v[174:177], v[124:127]
	v_mfma_f32_16x16x32_bf16 v[120:123], v[160:163], v[174:177], v[120:123]
	v_mfma_f32_16x16x32_bf16 v[108:111], v[132:135], v[182:185], v[108:111]
	v_mfma_f32_16x16x32_bf16 v[104:107], v[160:163], v[182:185], v[104:107]
	v_mfma_f32_16x16x32_bf16 v[92:95], v[132:135], v[190:193], v[92:95]
	v_mfma_f32_16x16x32_bf16 v[88:91], v[160:163], v[190:193], v[88:91]
	v_mfma_f32_16x16x32_bf16 v[76:79], v[132:135], v[202:205], v[76:79]
	v_mfma_f32_16x16x32_bf16 v[72:75], v[160:163], v[202:205], v[72:75]
	s_barrier
	s_setprio 0
	s_add_i32 s57, s48, s34
	s_mov_b32 m0, s57
	ds_read_b128 v[206:209], v169
	ds_read_b128 v[210:213], v169 offset:1024
	ds_read_b128 v[214:217], v169 offset:2048
	ds_read_b128 v[218:221], v169 offset:3072
	global_load_lds_dwordx4 v146, s[26:27]
	s_add_i32 m0, s57, 0x2000
	s_nop 0
	global_load_lds_dwordx4 v142, s[26:27]
	s_waitcnt vmcnt(8)
	s_waitcnt lgkmcnt(0)
	s_setprio 1
	s_barrier
	v_mfma_f32_16x16x32_bf16 v[116:119], v[206:209], v[170:173], 0
	v_mfma_f32_16x16x32_bf16 v[112:115], v[214:217], v[170:173], 0
	v_mfma_f32_16x16x32_bf16 v[100:103], v[206:209], v[178:181], 0
	v_mfma_f32_16x16x32_bf16 v[96:99], v[214:217], v[178:181], 0
	v_mfma_f32_16x16x32_bf16 v[84:87], v[206:209], v[186:189], 0
	v_mfma_f32_16x16x32_bf16 v[80:83], v[214:217], v[186:189], 0
	v_mfma_f32_16x16x32_bf16 v[68:71], v[206:209], v[194:197], 0
	v_mfma_f32_16x16x32_bf16 v[64:67], v[214:217], v[194:197], 0
	v_mfma_f32_16x16x32_bf16 v[116:119], v[210:213], v[174:177], v[116:119]
	v_mfma_f32_16x16x32_bf16 v[112:115], v[218:221], v[174:177], v[112:115]
	v_mfma_f32_16x16x32_bf16 v[100:103], v[210:213], v[182:185], v[100:103]
	v_mfma_f32_16x16x32_bf16 v[96:99], v[218:221], v[182:185], v[96:99]
	v_mfma_f32_16x16x32_bf16 v[84:87], v[210:213], v[190:193], v[84:87]
	v_mfma_f32_16x16x32_bf16 v[80:83], v[218:221], v[190:193], v[80:83]
	v_mfma_f32_16x16x32_bf16 v[68:71], v[210:213], v[202:205], v[68:71]
	v_mfma_f32_16x16x32_bf16 v[64:67], v[218:221], v[202:205], v[64:67]
	s_mov_b32 m0, s37
	v_lshl_add_u64 v[222:223], s[28:29], 0, v[148:149]
	s_barrier
	s_setprio 0
	ds_read_b128 v[170:173], v168 offset:16384
	ds_read_b128 v[174:177], v168 offset:17408
	ds_read_b128 v[178:181], v168 offset:18432
	ds_read_b128 v[182:185], v168 offset:19456
	ds_read_b128 v[186:189], v168 offset:20480
	ds_read_b128 v[190:193], v168 offset:21504
	ds_read_b128 v[194:197], v168 offset:22528
	ds_read_b128 v[202:205], v168 offset:23552
	global_load_lds_dwordx4 v148, s[28:29]
	v_lshl_add_u64 v[224:225], s[28:29], 0, v[144:145]
	s_mov_b32 m0, s38
	s_nop 0
	global_load_lds_dwordx4 v144, s[28:29]
	s_waitcnt lgkmcnt(0)
	s_setprio 1
	s_barrier
	v_mfma_f32_16x16x32_bf16 v[60:63], v[128:131], v[170:173], 0
	v_mfma_f32_16x16x32_bf16 v[56:59], v[136:139], v[170:173], 0
	v_mfma_f32_16x16x32_bf16 v[44:47], v[128:131], v[178:181], 0
	v_mfma_f32_16x16x32_bf16 v[40:43], v[136:139], v[178:181], 0
	v_mfma_f32_16x16x32_bf16 v[28:31], v[128:131], v[186:189], 0
	v_mfma_f32_16x16x32_bf16 v[24:27], v[136:139], v[186:189], 0
	v_mfma_f32_16x16x32_bf16 v[12:15], v[128:131], v[194:197], 0
	v_mfma_f32_16x16x32_bf16 v[8:11], v[136:139], v[194:197], 0
	v_mfma_f32_16x16x32_bf16 v[60:63], v[132:135], v[174:177], v[60:63]
	v_mfma_f32_16x16x32_bf16 v[56:59], v[160:163], v[174:177], v[56:59]
	v_mfma_f32_16x16x32_bf16 v[44:47], v[132:135], v[182:185], v[44:47]
	v_mfma_f32_16x16x32_bf16 v[40:43], v[160:163], v[182:185], v[40:43]
	v_mfma_f32_16x16x32_bf16 v[28:31], v[132:135], v[190:193], v[28:31]
	v_mfma_f32_16x16x32_bf16 v[24:27], v[160:163], v[190:193], v[24:27]
	v_mfma_f32_16x16x32_bf16 v[12:15], v[132:135], v[202:205], v[12:15]
	v_mfma_f32_16x16x32_bf16 v[8:11], v[160:163], v[202:205], v[8:11]
	s_barrier
; #define PG8_STAGE(bufoff, gbase, voff) do { _Pragma("unroll") for (int _i = 0; _i < 2; ++_i) \
;         __builtin_amdgcn_global_load_lds((const unsigned*)((const char*)(gbase) + (voff)[_i]), (LAS unsigned*)(lds + (bufoff) + ldsw + _i * 8192), 16, 0, 0); } while (0)
; #define PG8_LDA(dst, b, h) do { _Pragma("unroll") for (int m = 0; m < 4; ++m) _Pragma("unroll") for (int k = 0; k < 2; ++k) dst[m][k] = *(const LAS bf16x8*)(lds + PG8_SA(b, h) + aoff + m * 2048 + k * 1024); } while (0)
; #define PG8_LDB(dst, b, h) do { _Pragma("unroll") for (int n = 0; n < 2; ++n) _Pragma("unroll") for (int k = 0; k < 2; ++k) dst[n][k] = *(const LAS bf16x8*)(lds + PG8_SB(b, h) + boff + n * 2048 + k * 1024); } while (0)
; #define PG8_MMA(ai, bj, At, Bt) do { __builtin_amdgcn_s_setprio(1); _Pragma("unroll") for (int m = 0; m < 4; ++m) _Pragma("unroll") for (int n = 0; n < 2; ++n) _Pragma("unroll") for (int k = 0; k < 2; ++k) \
;         acc[ai][bj][m][n] = __builtin_amdgcn_mfma_f32_16x16x32_bf16(Bt[n][k], At[m][k], acc[ai][bj][m][n], 0, 0, 0); __builtin_amdgcn_s_setprio(0); } while (0)
; #define PG8_WAIT_V(n) asm volatile("s_waitcnt vmcnt(" #n ")" ::: "memory")
; #define PG8_WAIT_L(n) asm volatile("s_waitcnt lgkmcnt(" #n ")" ::: "memory")
; #define PG8_BAR __builtin_amdgcn_s_barrier()
; #define PG8_SCHED __builtin_amdgcn_sched_barrier(0)
; template <class Epi, class Sched>
; __device__ __forceinline__ void gemm_phase(LAS unsigned char* lds, const Gemm g, const Sched& S, const Epi& E) {
;     ...
;             PG8_STAGE(PG8_SB(0, 1), b2 + hstep, voffB);
;             PG8_WAIT_V(6); PG8_BAR; PG8_MMA(1, 1, At, B1); PG8_BAR;
;             PG8_LDB(B0, 1, 0); PG8_SCHED; PG8_LDA(At, 1, 0); PG8_STAGE(PG8_SA(0, 1), a2 + hstep, voffA);
;             PG8_WAIT_L(8); PG8_BAR; PG8_WAIT_L(0); PG8_MMA(0, 0, At, B0); PG8_BAR; PG8_SCHED;
;             PG8_LDB(B1, 1, 1); PG8_STAGE(PG8_SB(1, 0), b3, voffB);
;             PG8_BAR; PG8_WAIT_L(0); PG8_MMA(0, 1, At, B1); PG8_BAR;
;             PG8_LDA(At, 1, 1); PG8_STAGE(PG8_SA(1, 0), a3, voffA);
;             PG8_BAR; PG8_WAIT_L(0); PG8_MMA(1, 0, At, B0); PG8_BAR; PG8_SCHED;
	s_setprio 0
	s_add_u32 s58, s26, 0x40000
	s_addc_u32 s59, s27, 0
	s_add_i32 s57, s49, s34
	s_mov_b32 m0, s57
	s_nop 0
	global_load_lds_dwordx4 v146, s[58:59]
	s_add_i32 m0, s57, 0x2000
	s_nop 0
	global_load_lds_dwordx4 v142, s[58:59]
	s_add_u32 s28, s28, 0x40000
	s_addc_u32 s29, s29, 0
	s_mov_b32 m0, s39
	s_nop 0
	global_load_lds_dwordx4 v148, s[28:29]
	s_mov_b32 m0, s40
	s_nop 0
	global_load_lds_dwordx4 v144, s[28:29]
	s_waitcnt vmcnt(10)
	s_setprio 1
	s_barrier
	v_mfma_f32_16x16x32_bf16 v[52:55], v[206:209], v[170:173], 0
	v_mfma_f32_16x16x32_bf16 v[48:51], v[214:217], v[170:173], 0
	v_mfma_f32_16x16x32_bf16 v[36:39], v[206:209], v[178:181], 0
	v_mfma_f32_16x16x32_bf16 v[32:35], v[214:217], v[178:181], 0
	v_mfma_f32_16x16x32_bf16 v[20:23], v[206:209], v[186:189], 0
	v_mfma_f32_16x16x32_bf16 v[16:19], v[214:217], v[186:189], 0
	v_mfma_f32_16x16x32_bf16 v[4:7], v[206:209], v[194:197], 0
	v_mfma_f32_16x16x32_bf16 v[0:3], v[214:217], v[194:197], 0
	v_mfma_f32_16x16x32_bf16 v[52:55], v[210:213], v[174:177], v[52:55]
	v_mfma_f32_16x16x32_bf16 v[48:51], v[218:221], v[174:177], v[48:51]
	v_mfma_f32_16x16x32_bf16 v[36:39], v[210:213], v[182:185], v[36:39]
	v_mfma_f32_16x16x32_bf16 v[32:35], v[218:221], v[182:185], v[32:35]
	v_mfma_f32_16x16x32_bf16 v[20:23], v[210:213], v[190:193], v[20:23]
	v_mfma_f32_16x16x32_bf16 v[16:19], v[218:221], v[190:193], v[16:19]
	v_mfma_f32_16x16x32_bf16 v[4:7], v[210:213], v[202:205], v[4:7]
	v_mfma_f32_16x16x32_bf16 v[0:3], v[218:221], v[202:205], v[0:3]
	s_add_i32 s57, 0, 0x18000
	v_add_u32_e32 v150, s57, v166
	s_barrier
	s_setprio 0
	ds_read_b128 v[128:131], v150
	ds_read_b128 v[132:135], v150 offset:1024
	ds_read_b128 v[136:139], v150 offset:2048
	ds_read_b128 v[160:163], v150 offset:3072
	ds_read_b128 v[170:173], v168 offset:32768
	ds_read_b128 v[174:177], v168 offset:33792
	ds_read_b128 v[178:181], v168 offset:34816
	ds_read_b128 v[182:185], v168 offset:35840
	ds_read_b128 v[186:189], v168 offset:36864
	ds_read_b128 v[190:193], v168 offset:37888
	ds_read_b128 v[194:197], v168 offset:38912
	ds_read_b128 v[202:205], v168 offset:39936
	s_waitcnt lgkmcnt(8)
	s_waitcnt vmcnt(8)
	s_waitcnt lgkmcnt(0)
	s_setprio 1
	s_barrier
	v_mfma_f32_16x16x32_bf16 v[124:127], v[128:131], v[170:173], v[124:127]
	v_mfma_f32_16x16x32_bf16 v[120:123], v[136:139], v[170:173], v[120:123]
	v_mfma_f32_16x16x32_bf16 v[108:111], v[128:131], v[178:181], v[108:111]
	v_mfma_f32_16x16x32_bf16 v[104:107], v[136:139], v[178:181], v[104:107]
	v_mfma_f32_16x16x32_bf16 v[92:95], v[128:131], v[186:189], v[92:95]
	v_mfma_f32_16x16x32_bf16 v[88:91], v[136:139], v[186:189], v[88:91]
	v_mfma_f32_16x16x32_bf16 v[76:79], v[128:131], v[194:197], v[76:79]
	v_mfma_f32_16x16x32_bf16 v[72:75], v[136:139], v[194:197], v[72:75]
	v_mfma_f32_16x16x32_bf16 v[124:127], v[132:135], v[174:177], v[124:127]
	v_mfma_f32_16x16x32_bf16 v[120:123], v[160:163], v[174:177], v[120:123]
	v_mfma_f32_16x16x32_bf16 v[108:111], v[132:135], v[182:185], v[108:111]
	v_mfma_f32_16x16x32_bf16 v[104:107], v[160:163], v[182:185], v[104:107]
	v_mfma_f32_16x16x32_bf16 v[92:95], v[132:135], v[190:193], v[92:95]
	v_mfma_f32_16x16x32_bf16 v[88:91], v[160:163], v[190:193], v[88:91]
	v_mfma_f32_16x16x32_bf16 v[76:79], v[132:135], v[202:205], v[76:79]
	v_mfma_f32_16x16x32_bf16 v[72:75], v[160:163], v[202:205], v[72:75]
	s_barrier
	s_setprio 0
	s_add_i32 s28, 0, 0x1c000
	s_add_i32 s29, s57, s34
	v_add_u32_e32 v150, s28, v166
	s_add_u32 s0, s26, 0x80
	s_addc_u32 s1, s27, 0
	s_mov_b32 m0, s29
	ds_read_b128 v[206:209], v150
	ds_read_b128 v[210:213], v150 offset:1024
	ds_read_b128 v[214:217], v150 offset:2048
	ds_read_b128 v[218:221], v150 offset:3072
	global_load_lds_dwordx4 v146, s[0:1]
	s_add_i32 m0, s29, 0x2000
	s_nop 0
	global_load_lds_dwordx4 v142, s[0:1]
	s_waitcnt vmcnt(8)
	s_waitcnt lgkmcnt(0)
	s_setprio 1
	s_barrier
	v_mfma_f32_16x16x32_bf16 v[116:119], v[206:209], v[170:173], v[116:119]
	v_mfma_f32_16x16x32_bf16 v[112:115], v[214:217], v[170:173], v[112:115]
	v_mfma_f32_16x16x32_bf16 v[100:103], v[206:209], v[178:181], v[100:103]
	v_mfma_f32_16x16x32_bf16 v[96:99], v[214:217], v[178:181], v[96:99]
	v_mfma_f32_16x16x32_bf16 v[84:87], v[206:209], v[186:189], v[84:87]
	v_mfma_f32_16x16x32_bf16 v[80:83], v[214:217], v[186:189], v[80:83]
	v_mfma_f32_16x16x32_bf16 v[68:71], v[206:209], v[194:197], v[68:71]
	v_mfma_f32_16x16x32_bf16 v[64:67], v[214:217], v[194:197], v[64:67]
	v_mfma_f32_16x16x32_bf16 v[116:119], v[210:213], v[174:177], v[116:119]
	v_mfma_f32_16x16x32_bf16 v[112:115], v[218:221], v[174:177], v[112:115]
	v_mfma_f32_16x16x32_bf16 v[100:103], v[210:213], v[182:185], v[100:103]
	v_mfma_f32_16x16x32_bf16 v[96:99], v[218:221], v[182:185], v[96:99]
	v_mfma_f32_16x16x32_bf16 v[84:87], v[210:213], v[190:193], v[84:87]
	v_mfma_f32_16x16x32_bf16 v[80:83], v[218:221], v[190:193], v[80:83]
	v_mfma_f32_16x16x32_bf16 v[68:71], v[210:213], v[202:205], v[68:71]
	v_mfma_f32_16x16x32_bf16 v[64:67], v[218:221], v[202:205], v[64:67]
	s_mov_b32 m0, s44
	s_mov_b64 s[0:1], 0x80
	v_lshl_add_u64 v[140:141], v[222:223], 0, s[0:1]
	s_barrier
	s_setprio 0
	ds_read_b128 v[170:173], v168 offset:49152
	ds_read_b128 v[174:177], v168 offset:50176
	ds_read_b128 v[178:181], v168 offset:51200
	ds_read_b128 v[182:185], v168 offset:52224
	ds_read_b128 v[186:189], v168 offset:53248
	ds_read_b128 v[190:193], v168 offset:54272
	ds_read_b128 v[194:197], v168 offset:55296
	ds_read_b128 v[202:205], v168 offset:56320
	global_load_lds_dwordx4 v[140:141], off
	v_lshl_add_u64 v[140:141], v[224:225], 0, s[0:1]
	s_mov_b32 m0, s45
	s_nop 0
	global_load_lds_dwordx4 v[140:141], off
	s_waitcnt lgkmcnt(0)
	s_setprio 1
	s_barrier
; #define PG8_STAGE(bufoff, gbase, voff) do { _Pragma("unroll") for (int _i = 0; _i < 2; ++_i) \
;         __builtin_amdgcn_global_load_lds((const unsigned*)((const char*)(gbase) + (voff)[_i]), (LAS unsigned*)(lds + (bufoff) + ldsw + _i * 8192), 16, 0, 0); } while (0)
; #define PG8_LDA(dst, b, h) do { _Pragma("unroll") for (int m = 0; m < 4; ++m) _Pragma("unroll") for (int k = 0; k < 2; ++k) dst[m][k] = *(const LAS bf16x8*)(lds + PG8_SA(b, h) + aoff + m * 2048 + k * 1024); } while (0)
; #define PG8_WAIT_V(n) asm volatile("s_waitcnt vmcnt(" #n ")" ::: "memory")
; #define PG8_WAIT_L(n) asm volatile("s_waitcnt lgkmcnt(" #n ")" ::: "memory")
; template <class Epi, class Sched>
; __device__ __forceinline__ void gemm_phase(LAS unsigned char* lds, const Gemm g, const Sched& S, const Epi& E) {
;     ...
;         for (int t = 0; t < nt; t += 2) {
;             const bool last = (t == nt - 2);
;             const char* a1 = cA + (size_t)(t + 1) * kstep;
;             const char* a2 = last ? nA : cA + (size_t)(t + 2) * kstep; const char* b2 = last ? nB : cB + (size_t)(t + 2) * kstep;
;             const char* a3 = a2 + kstep; const char* b3 = b2 + kstep;
;             PG8_LDB(B0, 0, 0); PG8_SCHED; PG8_LDA(At, 0, 0); PG8_STAGE(PG8_SA(1, 1), a1 + hstep, voffA);
;             PG8_WAIT_L(8); PG8_BAR; PG8_WAIT_L(0); PG8_MMA(0, 0, At, B0); PG8_BAR; PG8_SCHED;
;             PG8_LDB(B1, 0, 1); PG8_STAGE(PG8_SB(0, 0), b2, voffB);
;             PG8_BAR; PG8_WAIT_L(0); PG8_MMA(0, 1, At, B1); PG8_BAR;
;             PG8_LDA(At, 0, 1); PG8_STAGE(PG8_SA(0, 0), a2, voffA);
;             PG8_BAR; PG8_WAIT_L(0); PG8_MMA(1, 0, At, B0); PG8_BAR; PG8_SCHED;
;             PG8_STAGE(PG8_SB(0, 1), b2 + hstep, voffB);
;             PG8_WAIT_V(6); PG8_BAR; PG8_MMA(1, 1, At, B1); PG8_BAR;
;             PG8_LDB(B0, 1, 0); PG8_SCHED; PG8_LDA(At, 1, 0); PG8_STAGE(PG8_SA(0, 1), a2 + hstep, voffA);
;             PG8_WAIT_L(8); PG8_BAR; PG8_WAIT_L(0); PG8_MMA(0, 0, At, B0); PG8_BAR; PG8_SCHED;
;             PG8_LDB(B1, 1, 1); PG8_STAGE(PG8_SB(1, 0), b3, voffB);
;             PG8_BAR; PG8_WAIT_L(0); PG8_MMA(0, 1, At, B1); PG8_BAR;
;             PG8_LDA(At, 1, 1); PG8_STAGE(PG8_SA(1, 0), a3, voffA);
;             PG8_BAR; PG8_WAIT_L(0); PG8_MMA(1, 0, At, B0); PG8_BAR; PG8_SCHED;
;             PG8_STAGE(PG8_SB(1, 1), b3 + hstep, voffB);
;             PG8_WAIT_V(6); PG8_BAR; PG8_MMA(1, 1, At, B1); PG8_BAR;
	v_mfma_f32_16x16x32_bf16 v[60:63], v[128:131], v[170:173], v[60:63]
	v_mfma_f32_16x16x32_bf16 v[56:59], v[136:139], v[170:173], v[56:59]
	v_mfma_f32_16x16x32_bf16 v[44:47], v[128:131], v[178:181], v[44:47]
	v_mfma_f32_16x16x32_bf16 v[40:43], v[136:139], v[178:181], v[40:43]
	v_mfma_f32_16x16x32_bf16 v[28:31], v[128:131], v[186:189], v[28:31]
	v_mfma_f32_16x16x32_bf16 v[24:27], v[136:139], v[186:189], v[24:27]
	v_mfma_f32_16x16x32_bf16 v[12:15], v[128:131], v[194:197], v[12:15]
	v_mfma_f32_16x16x32_bf16 v[8:11], v[136:139], v[194:197], v[8:11]
	v_mfma_f32_16x16x32_bf16 v[60:63], v[132:135], v[174:177], v[60:63]
	v_mfma_f32_16x16x32_bf16 v[56:59], v[160:163], v[174:177], v[56:59]
	v_mfma_f32_16x16x32_bf16 v[44:47], v[132:135], v[182:185], v[44:47]
	v_mfma_f32_16x16x32_bf16 v[40:43], v[160:163], v[182:185], v[40:43]
	v_mfma_f32_16x16x32_bf16 v[28:31], v[132:135], v[190:193], v[28:31]
	v_mfma_f32_16x16x32_bf16 v[24:27], v[160:163], v[190:193], v[24:27]
	v_mfma_f32_16x16x32_bf16 v[12:15], v[132:135], v[202:205], v[12:15]
	v_mfma_f32_16x16x32_bf16 v[8:11], v[160:163], v[202:205], v[8:11]
	s_barrier
	s_setprio 0
	s_add_u32 s26, s26, 0x40080
	s_addc_u32 s27, s27, 0
	s_add_i32 s28, s28, s34
	s_mov_b32 m0, s28
	s_nop 0
	global_load_lds_dwordx4 v146, s[26:27]
	s_add_i32 m0, s28, 0x2000
	s_nop 0
	global_load_lds_dwordx4 v142, s[26:27]
	s_waitcnt vmcnt(8)
	s_setprio 1
	s_barrier
	v_mfma_f32_16x16x32_bf16 v[52:55], v[206:209], v[170:173], v[52:55]
	v_mfma_f32_16x16x32_bf16 v[48:51], v[214:217], v[170:173], v[48:51]
	v_mfma_f32_16x16x32_bf16 v[36:39], v[206:209], v[178:181], v[36:39]
	v_mfma_f32_16x16x32_bf16 v[32:35], v[214:217], v[178:181], v[32:35]
	v_mfma_f32_16x16x32_bf16 v[20:23], v[206:209], v[186:189], v[20:23]
	v_mfma_f32_16x16x32_bf16 v[16:19], v[214:217], v[186:189], v[16:19]
	v_mfma_f32_16x16x32_bf16 v[4:7], v[206:209], v[194:197], v[4:7]
	v_mfma_f32_16x16x32_bf16 v[0:3], v[214:217], v[194:197], v[0:3]
	v_mfma_f32_16x16x32_bf16 v[52:55], v[210:213], v[174:177], v[52:55]
	v_mfma_f32_16x16x32_bf16 v[48:51], v[218:221], v[174:177], v[48:51]
	v_mfma_f32_16x16x32_bf16 v[36:39], v[210:213], v[182:185], v[36:39]
	v_mfma_f32_16x16x32_bf16 v[32:35], v[218:221], v[182:185], v[32:35]
	v_mfma_f32_16x16x32_bf16 v[20:23], v[210:213], v[190:193], v[20:23]
	v_mfma_f32_16x16x32_bf16 v[16:19], v[218:221], v[190:193], v[16:19]
	v_mfma_f32_16x16x32_bf16 v[4:7], v[210:213], v[202:205], v[4:7]
	v_mfma_f32_16x16x32_bf16 v[0:3], v[218:221], v[202:205], v[0:3]
	s_add_i32 s56, s56, 2
	s_add_u32 s6, s6, 0x100
	s_addc_u32 s7, s7, 0
	s_add_u32 s54, s54, 0x100
	s_addc_u32 s55, s55, 0
	s_cmp_gt_u32 s56, 13
	s_barrier
	s_setprio 0
.LBB0_578:
	ds_read_b128 v[128:131], v167
	ds_read_b128 v[132:135], v167 offset:1024
	ds_read_b128 v[136:139], v167 offset:2048
	ds_read_b128 v[160:163], v167 offset:3072
	s_add_u32 s26, s6, 0xfffc0080
	s_addc_u32 s27, s7, -1
	s_cmp_eq_u32 s56, 12
	s_cselect_b32 s29, s5, s27
	s_cselect_b32 s28, s21, s26
	s_cselect_b32 s27, s19, s55
	s_cselect_b32 s26, s53, s54
	s_add_i32 m0, s37, 0xc000
	ds_read_b128 v[170:173], v168
	ds_read_b128 v[174:177], v168 offset:1024
	ds_read_b128 v[178:181], v168 offset:2048
	ds_read_b128 v[182:185], v168 offset:3072
	ds_read_b128 v[186:189], v168 offset:4096
	ds_read_b128 v[190:193], v168 offset:5120
	ds_read_b128 v[194:197], v168 offset:6144
	ds_read_b128 v[202:205], v168 offset:7168
	global_load_lds_dwordx4 v152, s[6:7]
	s_add_i32 m0, s37, 0xe000
	s_nop 0
	global_load_lds_dwordx4 v154, s[6:7]
	s_waitcnt lgkmcnt(8)
	s_waitcnt vmcnt(8)
	s_waitcnt lgkmcnt(0)
	s_setprio 1
	s_barrier
	v_mfma_f32_16x16x32_bf16 v[124:127], v[128:131], v[170:173], v[124:127]
	v_mfma_f32_16x16x32_bf16 v[120:123], v[136:139], v[170:173], v[120:123]
	v_mfma_f32_16x16x32_bf16 v[108:111], v[128:131], v[178:181], v[108:111]
	v_mfma_f32_16x16x32_bf16 v[104:107], v[136:139], v[178:181], v[104:107]
	v_mfma_f32_16x16x32_bf16 v[92:95], v[128:131], v[186:189], v[92:95]
	v_mfma_f32_16x16x32_bf16 v[88:91], v[136:139], v[186:189], v[88:91]
	v_mfma_f32_16x16x32_bf16 v[76:79], v[128:131], v[194:197], v[76:79]
	v_mfma_f32_16x16x32_bf16 v[72:75], v[136:139], v[194:197], v[72:75]
	v_mfma_f32_16x16x32_bf16 v[124:127], v[132:135], v[174:177], v[124:127]
	v_mfma_f32_16x16x32_bf16 v[120:123], v[160:163], v[174:177], v[120:123]
	v_mfma_f32_16x16x32_bf16 v[108:111], v[132:135], v[182:185], v[108:111]
	v_mfma_f32_16x16x32_bf16 v[104:107], v[160:163], v[182:185], v[104:107]
	v_mfma_f32_16x16x32_bf16 v[92:95], v[132:135], v[190:193], v[92:95]
	v_mfma_f32_16x16x32_bf16 v[88:91], v[160:163], v[190:193], v[88:91]
	v_mfma_f32_16x16x32_bf16 v[76:79], v[132:135], v[202:205], v[76:79]
	v_mfma_f32_16x16x32_bf16 v[72:75], v[160:163], v[202:205], v[72:75]
	s_barrier
	s_setprio 0
	s_add_i32 s57, s48, s34
	s_mov_b32 m0, s57
	ds_read_b128 v[206:209], v169
	ds_read_b128 v[210:213], v169 offset:1024
	ds_read_b128 v[214:217], v169 offset:2048
	ds_read_b128 v[218:221], v169 offset:3072
	global_load_lds_dwordx4 v146, s[26:27]
	s_add_i32 m0, s57, 0x2000
	s_nop 0
	global_load_lds_dwordx4 v142, s[26:27]
	s_waitcnt vmcnt(8)
	s_waitcnt lgkmcnt(0)
	s_setprio 1
	s_barrier
; #define PG8_STAGE(bufoff, gbase, voff) do { _Pragma("unroll") for (int _i = 0; _i < 2; ++_i) \
;         __builtin_amdgcn_global_load_lds((const unsigned*)((const char*)(gbase) + (voff)[_i]), (LAS unsigned*)(lds + (bufoff) + ldsw + _i * 8192), 16, 0, 0); } while (0)
; #define PG8_LDA(dst, b, h) do { _Pragma("unroll") for (int m = 0; m < 4; ++m) _Pragma("unroll") for (int k = 0; k < 2; ++k) dst[m][k] = *(const LAS bf16x8*)(lds + PG8_SA(b, h) + aoff + m * 2048 + k * 1024); } while (0)
; #define PG8_LDB(dst, b, h) do { _Pragma("unroll") for (int n = 0; n < 2; ++n) _Pragma("unroll") for (int k = 0; k < 2; ++k) dst[n][k] = *(const LAS bf16x8*)(lds + PG8_SB(b, h) + boff + n * 2048 + k * 1024); } while (0)
; #define PG8_MMA(ai, bj, At, Bt) do { __builtin_amdgcn_s_setprio(1); _Pragma("unroll") for (int m = 0; m < 4; ++m) _Pragma("unroll") for (int n = 0; n < 2; ++n) _Pragma("unroll") for (int k = 0; k < 2; ++k) \
;         acc[ai][bj][m][n] = __builtin_amdgcn_mfma_f32_16x16x32_bf16(Bt[n][k], At[m][k], acc[ai][bj][m][n], 0, 0, 0); __builtin_amdgcn_s_setprio(0); } while (0)
; #define PG8_WAIT_V(n) asm volatile("s_waitcnt vmcnt(" #n ")" ::: "memory")
; #define PG8_WAIT_L(n) asm volatile("s_waitcnt lgkmcnt(" #n ")" ::: "memory")
; #define PG8_BAR __builtin_amdgcn_s_barrier()
; #define PG8_SCHED __builtin_amdgcn_sched_barrier(0)
; template <class Epi, class Sched>
; __device__ __forceinline__ void gemm_phase(LAS unsigned char* lds, const Gemm g, const Sched& S, const Epi& E) {
;     ...
;             PG8_LDA(At, 0, 1); PG8_STAGE(PG8_SA(0, 0), a2, voffA);
;             PG8_BAR; PG8_WAIT_L(0); PG8_MMA(1, 0, At, B0); PG8_BAR; PG8_SCHED;
;             PG8_STAGE(PG8_SB(0, 1), b2 + hstep, voffB);
;             PG8_WAIT_V(6); PG8_BAR; PG8_MMA(1, 1, At, B1); PG8_BAR;
;             PG8_LDB(B0, 1, 0); PG8_SCHED; PG8_LDA(At, 1, 0); PG8_STAGE(PG8_SA(0, 1), a2 + hstep, voffA);
;             PG8_WAIT_L(8); PG8_BAR; PG8_WAIT_L(0); PG8_MMA(0, 0, At, B0); PG8_BAR; PG8_SCHED;
	v_mfma_f32_16x16x32_bf16 v[116:119], v[206:209], v[170:173], v[116:119]
	v_mfma_f32_16x16x32_bf16 v[112:115], v[214:217], v[170:173], v[112:115]
	v_mfma_f32_16x16x32_bf16 v[100:103], v[206:209], v[178:181], v[100:103]
	v_mfma_f32_16x16x32_bf16 v[96:99], v[214:217], v[178:181], v[96:99]
	v_mfma_f32_16x16x32_bf16 v[84:87], v[206:209], v[186:189], v[84:87]
	v_mfma_f32_16x16x32_bf16 v[80:83], v[214:217], v[186:189], v[80:83]
	v_mfma_f32_16x16x32_bf16 v[68:71], v[206:209], v[194:197], v[68:71]
	v_mfma_f32_16x16x32_bf16 v[64:67], v[214:217], v[194:197], v[64:67]
	v_mfma_f32_16x16x32_bf16 v[116:119], v[210:213], v[174:177], v[116:119]
	v_mfma_f32_16x16x32_bf16 v[112:115], v[218:221], v[174:177], v[112:115]
	v_mfma_f32_16x16x32_bf16 v[100:103], v[210:213], v[182:185], v[100:103]
	v_mfma_f32_16x16x32_bf16 v[96:99], v[218:221], v[182:185], v[96:99]
	v_mfma_f32_16x16x32_bf16 v[84:87], v[210:213], v[190:193], v[84:87]
	v_mfma_f32_16x16x32_bf16 v[80:83], v[218:221], v[190:193], v[80:83]
	v_mfma_f32_16x16x32_bf16 v[68:71], v[210:213], v[202:205], v[68:71]
	v_mfma_f32_16x16x32_bf16 v[64:67], v[218:221], v[202:205], v[64:67]
	s_mov_b32 m0, s37
	v_lshl_add_u64 v[222:223], s[28:29], 0, v[148:149]
	s_barrier
	s_setprio 0
	ds_read_b128 v[170:173], v168 offset:16384
	ds_read_b128 v[174:177], v168 offset:17408
	ds_read_b128 v[178:181], v168 offset:18432
	ds_read_b128 v[182:185], v168 offset:19456
	ds_read_b128 v[186:189], v168 offset:20480
	ds_read_b128 v[190:193], v168 offset:21504
	ds_read_b128 v[194:197], v168 offset:22528
	ds_read_b128 v[202:205], v168 offset:23552
	global_load_lds_dwordx4 v148, s[28:29]
	v_lshl_add_u64 v[224:225], s[28:29], 0, v[144:145]
	s_mov_b32 m0, s38
	s_nop 0
	global_load_lds_dwordx4 v144, s[28:29]
	s_waitcnt lgkmcnt(0)
	s_setprio 1
	s_barrier
	v_mfma_f32_16x16x32_bf16 v[60:63], v[128:131], v[170:173], v[60:63]
	v_mfma_f32_16x16x32_bf16 v[56:59], v[136:139], v[170:173], v[56:59]
	v_mfma_f32_16x16x32_bf16 v[44:47], v[128:131], v[178:181], v[44:47]
	v_mfma_f32_16x16x32_bf16 v[40:43], v[136:139], v[178:181], v[40:43]
	v_mfma_f32_16x16x32_bf16 v[28:31], v[128:131], v[186:189], v[28:31]
	v_mfma_f32_16x16x32_bf16 v[24:27], v[136:139], v[186:189], v[24:27]
	v_mfma_f32_16x16x32_bf16 v[12:15], v[128:131], v[194:197], v[12:15]
	v_mfma_f32_16x16x32_bf16 v[8:11], v[136:139], v[194:197], v[8:11]
	v_mfma_f32_16x16x32_bf16 v[60:63], v[132:135], v[174:177], v[60:63]
	v_mfma_f32_16x16x32_bf16 v[56:59], v[160:163], v[174:177], v[56:59]
	v_mfma_f32_16x16x32_bf16 v[44:47], v[132:135], v[182:185], v[44:47]
	v_mfma_f32_16x16x32_bf16 v[40:43], v[160:163], v[182:185], v[40:43]
	v_mfma_f32_16x16x32_bf16 v[28:31], v[132:135], v[190:193], v[28:31]
	v_mfma_f32_16x16x32_bf16 v[24:27], v[160:163], v[190:193], v[24:27]
	v_mfma_f32_16x16x32_bf16 v[12:15], v[132:135], v[202:205], v[12:15]
	v_mfma_f32_16x16x32_bf16 v[8:11], v[160:163], v[202:205], v[8:11]
	s_barrier
	s_setprio 0
	s_add_u32 s58, s26, 0x40000
	s_addc_u32 s59, s27, 0
	s_add_i32 s57, s49, s34
	s_mov_b32 m0, s57
	s_nop 0
	global_load_lds_dwordx4 v146, s[58:59]
	s_add_i32 m0, s57, 0x2000
	s_nop 0
	global_load_lds_dwordx4 v142, s[58:59]
	s_add_u32 s28, s28, 0x40000
	s_addc_u32 s29, s29, 0
	s_mov_b32 m0, s39
	s_nop 0
	global_load_lds_dwordx4 v148, s[28:29]
	s_mov_b32 m0, s40
	s_nop 0
	global_load_lds_dwordx4 v144, s[28:29]
	s_waitcnt vmcnt(10)
	s_setprio 1
	s_barrier
	v_mfma_f32_16x16x32_bf16 v[52:55], v[206:209], v[170:173], v[52:55]
	v_mfma_f32_16x16x32_bf16 v[48:51], v[214:217], v[170:173], v[48:51]
	v_mfma_f32_16x16x32_bf16 v[36:39], v[206:209], v[178:181], v[36:39]
	v_mfma_f32_16x16x32_bf16 v[32:35], v[214:217], v[178:181], v[32:35]
	v_mfma_f32_16x16x32_bf16 v[20:23], v[206:209], v[186:189], v[20:23]
	v_mfma_f32_16x16x32_bf16 v[16:19], v[214:217], v[186:189], v[16:19]
	v_mfma_f32_16x16x32_bf16 v[4:7], v[206:209], v[194:197], v[4:7]
	v_mfma_f32_16x16x32_bf16 v[0:3], v[214:217], v[194:197], v[0:3]
	v_mfma_f32_16x16x32_bf16 v[52:55], v[210:213], v[174:177], v[52:55]
	v_mfma_f32_16x16x32_bf16 v[48:51], v[218:221], v[174:177], v[48:51]
	v_mfma_f32_16x16x32_bf16 v[36:39], v[210:213], v[182:185], v[36:39]
	v_mfma_f32_16x16x32_bf16 v[32:35], v[218:221], v[182:185], v[32:35]
	v_mfma_f32_16x16x32_bf16 v[20:23], v[210:213], v[190:193], v[20:23]
	v_mfma_f32_16x16x32_bf16 v[16:19], v[218:221], v[190:193], v[16:19]
	v_mfma_f32_16x16x32_bf16 v[4:7], v[210:213], v[202:205], v[4:7]
	v_mfma_f32_16x16x32_bf16 v[0:3], v[218:221], v[202:205], v[0:3]
	s_add_i32 s57, 0, 0x18000
	v_add_u32_e32 v150, s57, v166
	s_barrier
	s_setprio 0
	ds_read_b128 v[128:131], v150
	ds_read_b128 v[132:135], v150 offset:1024
	ds_read_b128 v[136:139], v150 offset:2048
	ds_read_b128 v[160:163], v150 offset:3072
	ds_read_b128 v[170:173], v168 offset:32768
	ds_read_b128 v[174:177], v168 offset:33792
	ds_read_b128 v[178:181], v168 offset:34816
	ds_read_b128 v[182:185], v168 offset:35840
	ds_read_b128 v[186:189], v168 offset:36864
	ds_read_b128 v[190:193], v168 offset:37888
	ds_read_b128 v[194:197], v168 offset:38912
	ds_read_b128 v[202:205], v168 offset:39936
	s_waitcnt lgkmcnt(8)
	s_waitcnt vmcnt(8)
	s_waitcnt lgkmcnt(0)
	s_setprio 1
	s_barrier
; #define PG8_STAGE(bufoff, gbase, voff) do { _Pragma("unroll") for (int _i = 0; _i < 2; ++_i) \
;         __builtin_amdgcn_global_load_lds((const unsigned*)((const char*)(gbase) + (voff)[_i]), (LAS unsigned*)(lds + (bufoff) + ldsw + _i * 8192), 16, 0, 0); } while (0)
; #define PG8_LDA(dst, b, h) do { _Pragma("unroll") for (int m = 0; m < 4; ++m) _Pragma("unroll") for (int k = 0; k < 2; ++k) dst[m][k] = *(const LAS bf16x8*)(lds + PG8_SA(b, h) + aoff + m * 2048 + k * 1024); } while (0)
; #define PG8_LDB(dst, b, h) do { _Pragma("unroll") for (int n = 0; n < 2; ++n) _Pragma("unroll") for (int k = 0; k < 2; ++k) dst[n][k] = *(const LAS bf16x8*)(lds + PG8_SB(b, h) + boff + n * 2048 + k * 1024); } while (0)
; #define PG8_MMA(ai, bj, At, Bt) do { __builtin_amdgcn_s_setprio(1); _Pragma("unroll") for (int m = 0; m < 4; ++m) _Pragma("unroll") for (int n = 0; n < 2; ++n) _Pragma("unroll") for (int k = 0; k < 2; ++k) \
;         acc[ai][bj][m][n] = __builtin_amdgcn_mfma_f32_16x16x32_bf16(Bt[n][k], At[m][k], acc[ai][bj][m][n], 0, 0, 0); __builtin_amdgcn_s_setprio(0); } while (0)
; #define PG8_WAIT_L(n) asm volatile("s_waitcnt lgkmcnt(" #n ")" ::: "memory")
; #define PG8_BAR __builtin_amdgcn_s_barrier()
; #define PG8_SCHED __builtin_amdgcn_sched_barrier(0)
; template <class Epi, class Sched>
; __device__ __forceinline__ void gemm_phase(LAS unsigned char* lds, const Gemm g, const Sched& S, const Epi& E) {
;     ...
;             PG8_WAIT_L(8); PG8_BAR; PG8_WAIT_L(0); PG8_MMA(0, 0, At, B0); PG8_BAR; PG8_SCHED;
;             PG8_LDB(B1, 1, 1); PG8_STAGE(PG8_SB(1, 0), b3, voffB);
;             PG8_BAR; PG8_WAIT_L(0); PG8_MMA(0, 1, At, B1); PG8_BAR;
;             PG8_LDA(At, 1, 1); PG8_STAGE(PG8_SA(1, 0), a3, voffA);
;             PG8_BAR; PG8_WAIT_L(0); PG8_MMA(1, 0, At, B0); PG8_BAR; PG8_SCHED;
	v_mfma_f32_16x16x32_bf16 v[124:127], v[128:131], v[170:173], v[124:127]
	v_mfma_f32_16x16x32_bf16 v[120:123], v[136:139], v[170:173], v[120:123]
	v_mfma_f32_16x16x32_bf16 v[108:111], v[128:131], v[178:181], v[108:111]
	v_mfma_f32_16x16x32_bf16 v[104:107], v[136:139], v[178:181], v[104:107]
	v_mfma_f32_16x16x32_bf16 v[92:95], v[128:131], v[186:189], v[92:95]
	v_mfma_f32_16x16x32_bf16 v[88:91], v[136:139], v[186:189], v[88:91]
	v_mfma_f32_16x16x32_bf16 v[76:79], v[128:131], v[194:197], v[76:79]
	v_mfma_f32_16x16x32_bf16 v[72:75], v[136:139], v[194:197], v[72:75]
	v_mfma_f32_16x16x32_bf16 v[124:127], v[132:135], v[174:177], v[124:127]
	v_mfma_f32_16x16x32_bf16 v[120:123], v[160:163], v[174:177], v[120:123]
	v_mfma_f32_16x16x32_bf16 v[108:111], v[132:135], v[182:185], v[108:111]
	v_mfma_f32_16x16x32_bf16 v[104:107], v[160:163], v[182:185], v[104:107]
	v_mfma_f32_16x16x32_bf16 v[92:95], v[132:135], v[190:193], v[92:95]
	v_mfma_f32_16x16x32_bf16 v[88:91], v[160:163], v[190:193], v[88:91]
	v_mfma_f32_16x16x32_bf16 v[76:79], v[132:135], v[202:205], v[76:79]
	v_mfma_f32_16x16x32_bf16 v[72:75], v[160:163], v[202:205], v[72:75]
	s_barrier
	s_setprio 0
	s_add_i32 s28, 0, 0x1c000
	s_add_i32 s29, s57, s34
	v_add_u32_e32 v150, s28, v166
	s_add_u32 s0, s26, 0x80
	s_addc_u32 s1, s27, 0
	s_mov_b32 m0, s29
	ds_read_b128 v[206:209], v150
	ds_read_b128 v[210:213], v150 offset:1024
	ds_read_b128 v[214:217], v150 offset:2048
	ds_read_b128 v[218:221], v150 offset:3072
	global_load_lds_dwordx4 v146, s[0:1]
	s_add_i32 m0, s29, 0x2000
	s_nop 0
	global_load_lds_dwordx4 v142, s[0:1]
	s_waitcnt vmcnt(8)
	s_waitcnt lgkmcnt(0)
	s_setprio 1
	s_barrier
	v_mfma_f32_16x16x32_bf16 v[116:119], v[206:209], v[170:173], v[116:119]
	v_mfma_f32_16x16x32_bf16 v[112:115], v[214:217], v[170:173], v[112:115]
	v_mfma_f32_16x16x32_bf16 v[100:103], v[206:209], v[178:181], v[100:103]
	v_mfma_f32_16x16x32_bf16 v[96:99], v[214:217], v[178:181], v[96:99]
	v_mfma_f32_16x16x32_bf16 v[84:87], v[206:209], v[186:189], v[84:87]
	v_mfma_f32_16x16x32_bf16 v[80:83], v[214:217], v[186:189], v[80:83]
	v_mfma_f32_16x16x32_bf16 v[68:71], v[206:209], v[194:197], v[68:71]
	v_mfma_f32_16x16x32_bf16 v[64:67], v[214:217], v[194:197], v[64:67]
	v_mfma_f32_16x16x32_bf16 v[116:119], v[210:213], v[174:177], v[116:119]
	v_mfma_f32_16x16x32_bf16 v[112:115], v[218:221], v[174:177], v[112:115]
	v_mfma_f32_16x16x32_bf16 v[100:103], v[210:213], v[182:185], v[100:103]
	v_mfma_f32_16x16x32_bf16 v[96:99], v[218:221], v[182:185], v[96:99]
	v_mfma_f32_16x16x32_bf16 v[84:87], v[210:213], v[190:193], v[84:87]
	v_mfma_f32_16x16x32_bf16 v[80:83], v[218:221], v[190:193], v[80:83]
	v_mfma_f32_16x16x32_bf16 v[68:71], v[210:213], v[202:205], v[68:71]
	v_mfma_f32_16x16x32_bf16 v[64:67], v[218:221], v[202:205], v[64:67]
	s_mov_b32 m0, s44
	s_mov_b64 s[0:1], 0x80
	v_lshl_add_u64 v[140:141], v[222:223], 0, s[0:1]
	s_barrier
	s_setprio 0
	ds_read_b128 v[170:173], v168 offset:49152
	ds_read_b128 v[174:177], v168 offset:50176
	ds_read_b128 v[178:181], v168 offset:51200
	ds_read_b128 v[182:185], v168 offset:52224
	ds_read_b128 v[186:189], v168 offset:53248
	ds_read_b128 v[190:193], v168 offset:54272
	ds_read_b128 v[194:197], v168 offset:55296
	ds_read_b128 v[202:205], v168 offset:56320
	global_load_lds_dwordx4 v[140:141], off
	v_lshl_add_u64 v[140:141], v[224:225], 0, s[0:1]
	s_mov_b32 m0, s45
	s_nop 0
	global_load_lds_dwordx4 v[140:141], off
	s_waitcnt lgkmcnt(0)
	s_setprio 1
	s_barrier
; #define PG8_STAGE(bufoff, gbase, voff) do { _Pragma("unroll") for (int _i = 0; _i < 2; ++_i) \
;         __builtin_amdgcn_global_load_lds((const unsigned*)((const char*)(gbase) + (voff)[_i]), (LAS unsigned*)(lds + (bufoff) + ldsw + _i * 8192), 16, 0, 0); } while (0)
; #define PG8_MMA(ai, bj, At, Bt) do { __builtin_amdgcn_s_setprio(1); _Pragma("unroll") for (int m = 0; m < 4; ++m) _Pragma("unroll") for (int n = 0; n < 2; ++n) _Pragma("unroll") for (int k = 0; k < 2; ++k) \
;         acc[ai][bj][m][n] = __builtin_amdgcn_mfma_f32_16x16x32_bf16(Bt[n][k], At[m][k], acc[ai][bj][m][n], 0, 0, 0); __builtin_amdgcn_s_setprio(0); } while (0)
; #define PG8_WAIT_V(n) asm volatile("s_waitcnt vmcnt(" #n ")" ::: "memory")
; #define PG8_WAIT_L(n) asm volatile("s_waitcnt lgkmcnt(" #n ")" ::: "memory")
; #define PG8_BAR __builtin_amdgcn_s_barrier()
; #define PG8_SCHED __builtin_amdgcn_sched_barrier(0)
; template <class Epi, class Sched>
; __device__ __forceinline__ void gemm_phase(LAS unsigned char* lds, const Gemm g, const Sched& S, const Epi& E) {
;     ...
;             PG8_BAR; PG8_WAIT_L(0); PG8_MMA(1, 0, At, B0); PG8_BAR; PG8_SCHED;
;             PG8_STAGE(PG8_SB(1, 1), b3 + hstep, voffB);
;             PG8_WAIT_V(6); PG8_BAR; PG8_MMA(1, 1, At, B1); PG8_BAR;
;     __device__ __forceinline__ void operator()(const AccT& acc, const Unit& u, int wr, int wc, int fr, int fq) const {
;         asm volatile("" : "+v"(fr), "+v"(fq));
;         const int row0 = u.pm * 256 + wr * 64 + fr, col0 = u.pn * 256 + wc * 32 + 8 * fq;
;         const bool rope = u.pn < 2;
;         const int i = 4 * (wc & 1) + fq;
; #pragma unroll
;         for (int ai = 0; ai < 2; ++ai)
; #pragma unroll
;             for (int m = 0; m < 4; ++m) {
;                 const int row = row0 + ai * 128 + m * 16;
;                 f32x4 cs = {1.f, 1.f, 1.f, 1.f}, sn = {0.f, 0.f, 0.f, 0.f};
;                 if (rope) { const int t = row & 2047; const int pos = (i < 4) ? (t >> 6) : (t & 63);
;                     cs = *(const f32x4*)(ropeA + pos * 16 + ((4 * i) & 15)); sn = *(const f32x4*)(ropeA + 1024 + pos * 16 + ((4 * i) & 15)); }
	v_mfma_f32_16x16x32_bf16 v[60:63], v[128:131], v[170:173], v[60:63]
	v_mfma_f32_16x16x32_bf16 v[56:59], v[136:139], v[170:173], v[56:59]
	v_mfma_f32_16x16x32_bf16 v[44:47], v[128:131], v[178:181], v[44:47]
	v_mfma_f32_16x16x32_bf16 v[40:43], v[136:139], v[178:181], v[40:43]
	v_mfma_f32_16x16x32_bf16 v[28:31], v[128:131], v[186:189], v[28:31]
	v_mfma_f32_16x16x32_bf16 v[24:27], v[136:139], v[186:189], v[24:27]
	v_mfma_f32_16x16x32_bf16 v[12:15], v[128:131], v[194:197], v[12:15]
	v_mfma_f32_16x16x32_bf16 v[8:11], v[136:139], v[194:197], v[8:11]
	v_mfma_f32_16x16x32_bf16 v[60:63], v[132:135], v[174:177], v[60:63]
	v_mfma_f32_16x16x32_bf16 v[56:59], v[160:163], v[174:177], v[56:59]
	v_mfma_f32_16x16x32_bf16 v[44:47], v[132:135], v[182:185], v[44:47]
	v_mfma_f32_16x16x32_bf16 v[40:43], v[160:163], v[182:185], v[40:43]
	v_mfma_f32_16x16x32_bf16 v[28:31], v[132:135], v[190:193], v[28:31]
	v_mfma_f32_16x16x32_bf16 v[24:27], v[160:163], v[190:193], v[24:27]
	v_mfma_f32_16x16x32_bf16 v[12:15], v[132:135], v[202:205], v[12:15]
	v_mfma_f32_16x16x32_bf16 v[8:11], v[160:163], v[202:205], v[8:11]
	s_barrier
	s_setprio 0
	s_add_u32 s26, s26, 0x40080
	s_addc_u32 s27, s27, 0
	s_add_i32 s28, s28, s34
	s_mov_b32 m0, s28
	s_nop 0
	global_load_lds_dwordx4 v146, s[26:27]
	s_add_i32 m0, s28, 0x2000
	s_nop 0
	global_load_lds_dwordx4 v142, s[26:27]
	s_waitcnt vmcnt(8)
	s_setprio 1
	s_barrier
	v_mfma_f32_16x16x32_bf16 v[52:55], v[206:209], v[170:173], v[52:55]
	v_mfma_f32_16x16x32_bf16 v[48:51], v[214:217], v[170:173], v[48:51]
	v_mfma_f32_16x16x32_bf16 v[36:39], v[206:209], v[178:181], v[36:39]
	v_mfma_f32_16x16x32_bf16 v[32:35], v[214:217], v[178:181], v[32:35]
	v_mfma_f32_16x16x32_bf16 v[20:23], v[206:209], v[186:189], v[20:23]
	v_mfma_f32_16x16x32_bf16 v[16:19], v[214:217], v[186:189], v[16:19]
	v_mfma_f32_16x16x32_bf16 v[4:7], v[206:209], v[194:197], v[4:7]
	v_mfma_f32_16x16x32_bf16 v[0:3], v[214:217], v[194:197], v[0:3]
	v_mfma_f32_16x16x32_bf16 v[52:55], v[210:213], v[174:177], v[52:55]
	v_mfma_f32_16x16x32_bf16 v[48:51], v[218:221], v[174:177], v[48:51]
	v_mfma_f32_16x16x32_bf16 v[36:39], v[210:213], v[182:185], v[36:39]
	v_mfma_f32_16x16x32_bf16 v[32:35], v[218:221], v[182:185], v[32:35]
	v_mfma_f32_16x16x32_bf16 v[20:23], v[210:213], v[190:193], v[20:23]
	v_mfma_f32_16x16x32_bf16 v[16:19], v[218:221], v[190:193], v[16:19]
	v_mfma_f32_16x16x32_bf16 v[4:7], v[210:213], v[202:205], v[4:7]
	v_mfma_f32_16x16x32_bf16 v[0:3], v[218:221], v[202:205], v[0:3]
	s_add_i32 s56, s56, 2
	s_add_u32 s6, s6, 0x100
	s_addc_u32 s7, s7, 0
	s_add_u32 s54, s54, 0x100
	s_addc_u32 s55, s55, 0
	s_cmp_gt_u32 s56, 13
	s_barrier
	s_setprio 0
	s_cbranch_scc0 .LBB0_578
	v_mov_b32_e32 v129, v165
	v_mov_b32_e32 v173, v164
	s_lshl_b32 s4, s4, 8
	s_add_i32 s4, s4, s42
	v_add_u32_e32 v128, s46, v129
	v_add_u32_e32 v170, s4, v173
	v_cmp_gt_i32_e64 s[4:5], 4, v128
	v_lshlrev_b32_e32 v128, 2, v128
	s_cmp_lt_i32 s52, 2
	v_and_b32_e32 v130, 12, v128
	s_cselect_b64 s[26:27], -1, 0
	s_cmp_gt_i32 s52, 1
	v_and_b32_e32 v172, 63, v173
	v_mov_b32_e32 v128, 1.0
	v_mov_b32_e32 v132, 0
	v_lshlrev_b32_e32 v162, 2, v130
	v_mov_b32_e32 v134, 0
	v_mov_b32_e32 v135, 0
	v_mov_b32_e32 v136, 0
	v_mov_b32_e32 v137, 0
	v_mov_b32_e32 v138, 1.0
	v_mov_b32_e32 v139, 1.0
	v_mov_b32_e32 v140, 1.0
	v_mov_b32_e32 v141, 1.0
	s_cbranch_scc1 .LBB0_581
	v_bfe_u32 v130, v170, 6, 5
	v_cndmask_b32_e64 v130, v172, v130, s[4:5]
	v_lshlrev_b32_e32 v150, 6, v130
	v_lshl_add_u64 v[130:131], s[16:17], 0, v[150:151]
	v_mov_b32_e32 v163, v151
	v_lshl_add_u64 v[134:135], s[8:9], 0, v[150:151]
	v_lshl_add_u64 v[130:131], v[130:131], 0, v[162:163]
	v_lshl_add_u64 v[134:135], v[134:135], 0, v[162:163]
	global_load_dwordx4 v[138:141], v[130:131], off
	s_nop 0
	global_load_dwordx4 v[134:137], v[134:135], off
	s_waitcnt vmcnt(0)

; #define PG8_STAGE(bufoff, gbase, voff) do { _Pragma("unroll") for (int _i = 0; _i < 2; ++_i) \
;         __builtin_amdgcn_global_load_lds((const unsigned*)((const char*)(gbase) + (voff)[_i]), (LAS unsigned*)(lds + (bufoff) + ldsw + _i * 8192), 16, 0, 0); } while (0)
; #define PG8_LDA(dst, b, h) do { _Pragma("unroll") for (int m = 0; m < 4; ++m) _Pragma("unroll") for (int k = 0; k < 2; ++k) dst[m][k] = *(const LAS bf16x8*)(lds + PG8_SA(b, h) + aoff + m * 2048 + k * 1024); } while (0)
; #define PG8_LDB(dst, b, h) do { _Pragma("unroll") for (int n = 0; n < 2; ++n) _Pragma("unroll") for (int k = 0; k < 2; ++k) dst[n][k] = *(const LAS bf16x8*)(lds + PG8_SB(b, h) + boff + n * 2048 + k * 1024); } while (0)
; #define PG8_MMA(ai, bj, At, Bt) do { __builtin_amdgcn_s_setprio(1); _Pragma("unroll") for (int m = 0; m < 4; ++m) _Pragma("unroll") for (int n = 0; n < 2; ++n) _Pragma("unroll") for (int k = 0; k < 2; ++k) \
;         acc[ai][bj][m][n] = __builtin_amdgcn_mfma_f32_16x16x32_bf16(Bt[n][k], At[m][k], acc[ai][bj][m][n], 0, 0, 0); __builtin_amdgcn_s_setprio(0); } while (0)
; #define PG8_WAIT_L(n) asm volatile("s_waitcnt lgkmcnt(" #n ")" ::: "memory")
; template <class Epi, class Sched>
; __device__ __forceinline__ void gemm_phase(LAS unsigned char* lds, const Gemm g, const Sched& S, const Epi& E) {
;     ...
;         const bool has_next = S.next(ui + 1, nxt);
;         const char* nA = has_next ? (const char*)g.A + (size_t)nxt.pm * tstep : cA; const char* nB = has_next ? (const char*)g.Bt + (size_t)nxt.pn * tstep : cB;
;         for (int t = 0; t < nt; t += 2) {
;             const bool last = (t == nt - 2);
;             const char* a1 = cA + (size_t)(t + 1) * kstep;
;             const char* a2 = last ? nA : cA + (size_t)(t + 2) * kstep; const char* b2 = last ? nB : cB + (size_t)(t + 2) * kstep;
;             const char* a3 = a2 + kstep; const char* b3 = b2 + kstep;
;             PG8_LDB(B0, 0, 0); PG8_SCHED; PG8_LDA(At, 0, 0); PG8_STAGE(PG8_SA(1, 1), a1 + hstep, voffA);
;             PG8_WAIT_L(8); PG8_BAR; PG8_WAIT_L(0); PG8_MMA(0, 0, At, B0); PG8_BAR; PG8_SCHED;
;             PG8_LDB(B1, 0, 1); PG8_STAGE(PG8_SB(0, 0), b2, voffB);
;             PG8_BAR; PG8_WAIT_L(0); PG8_MMA(0, 1, At, B1); PG8_BAR;
;             PG8_LDA(At, 0, 1); PG8_STAGE(PG8_SA(0, 0), a2, voffA);
;             PG8_BAR; PG8_WAIT_L(0); PG8_MMA(1, 0, At, B0); PG8_BAR; PG8_SCHED;
.LBB0_612:
	s_ashr_i32 s35, s34, 31
	v_cmp_lt_i64_e32 vcc, s[6:7], v[142:143]
	s_lshl_b64 s[6:7], s[34:35], 19
	s_add_u32 s36, s40, s6
	s_addc_u32 s37, s41, s7
	s_and_b64 s[6:7], vcc, exec
	s_cselect_b32 s8, s37, s1
	s_cselect_b32 s9, s36, s0
	s_ashr_i32 s31, s30, 31
	s_lshl_b64 s[6:7], s[30:31], 19
	s_add_u32 s38, s96, s6
	s_addc_u32 s39, s97, s7
	s_and_b64 s[6:7], vcc, exec
	s_cselect_b32 s31, s39, s5
	s_cselect_b32 s35, s38, s4
	s_add_u32 s0, s0, 0x40080
	s_addc_u32 s1, s1, 0
	s_add_u32 s65, s4, 0x100
	s_addc_u32 s66, s5, 0
	s_mov_b32 s67, -2
	s_waitcnt lgkmcnt(0)
	ds_read_b128 v[146:149], v171
	ds_read_b128 v[150:153], v171 offset:1024
	ds_read_b128 v[154:157], v171 offset:2048
	ds_read_b128 v[158:161], v171 offset:3072
	s_add_u32 s4, s0, 0xfffc0080
	s_addc_u32 s5, s1, -1
	s_cmp_eq_u32 s67, 12
	s_cselect_b32 s7, s8, s5
	s_cselect_b32 s6, s9, s4
	s_cselect_b32 s5, s31, s66
	s_cselect_b32 s4, s35, s65
	s_add_i32 m0, s45, 0xc000
	ds_read_b128 v[162:165], v172
	ds_read_b128 v[178:181], v172 offset:1024
	ds_read_b128 v[182:185], v172 offset:2048
	ds_read_b128 v[186:189], v172 offset:3072
	ds_read_b128 v[190:193], v172 offset:4096
	ds_read_b128 v[194:197], v172 offset:5120
	ds_read_b128 v[202:205], v172 offset:6144
	ds_read_b128 v[206:209], v172 offset:7168
	global_load_lds_dwordx4 v138, s[0:1]
	s_add_i32 m0, s45, 0xe000
	s_nop 0
	global_load_lds_dwordx4 v140, s[0:1]
	s_waitcnt lgkmcnt(8)
	s_waitcnt vmcnt(8)
	s_waitcnt lgkmcnt(0)
	s_setprio 1
	s_barrier
	v_mfma_f32_16x16x32_bf16 v[124:127], v[146:149], v[162:165], 0
	v_mfma_f32_16x16x32_bf16 v[120:123], v[154:157], v[162:165], 0
	v_mfma_f32_16x16x32_bf16 v[108:111], v[146:149], v[182:185], 0
	v_mfma_f32_16x16x32_bf16 v[104:107], v[154:157], v[182:185], 0
	v_mfma_f32_16x16x32_bf16 v[92:95], v[146:149], v[190:193], 0
	v_mfma_f32_16x16x32_bf16 v[88:91], v[154:157], v[190:193], 0
	v_mfma_f32_16x16x32_bf16 v[76:79], v[146:149], v[202:205], 0
	v_mfma_f32_16x16x32_bf16 v[72:75], v[154:157], v[202:205], 0
	v_mfma_f32_16x16x32_bf16 v[124:127], v[150:153], v[178:181], v[124:127]
	v_mfma_f32_16x16x32_bf16 v[120:123], v[158:161], v[178:181], v[120:123]
	v_mfma_f32_16x16x32_bf16 v[108:111], v[150:153], v[186:189], v[108:111]
	v_mfma_f32_16x16x32_bf16 v[104:107], v[158:161], v[186:189], v[104:107]
	v_mfma_f32_16x16x32_bf16 v[92:95], v[150:153], v[194:197], v[92:95]
	v_mfma_f32_16x16x32_bf16 v[88:91], v[158:161], v[194:197], v[88:91]
	v_mfma_f32_16x16x32_bf16 v[76:79], v[150:153], v[206:209], v[76:79]
	v_mfma_f32_16x16x32_bf16 v[72:75], v[158:161], v[206:209], v[72:75]
	s_barrier
	s_setprio 0
	s_add_i32 s68, s57, s44
	s_mov_b32 m0, s68
	ds_read_b128 v[210:213], v173
	ds_read_b128 v[214:217], v173 offset:1024
	ds_read_b128 v[218:221], v173 offset:2048
	ds_read_b128 v[222:225], v173 offset:3072
	global_load_lds_dwordx4 v130, s[4:5]
	s_add_i32 m0, s68, 0x2000
	s_nop 0
	global_load_lds_dwordx4 v134, s[4:5]
	s_waitcnt vmcnt(8)
	s_waitcnt lgkmcnt(0)
	s_setprio 1
	s_barrier
	v_mfma_f32_16x16x32_bf16 v[116:119], v[210:213], v[162:165], 0
	v_mfma_f32_16x16x32_bf16 v[112:115], v[218:221], v[162:165], 0
	v_mfma_f32_16x16x32_bf16 v[100:103], v[210:213], v[182:185], 0
	v_mfma_f32_16x16x32_bf16 v[96:99], v[218:221], v[182:185], 0
	v_mfma_f32_16x16x32_bf16 v[84:87], v[210:213], v[190:193], 0
	v_mfma_f32_16x16x32_bf16 v[80:83], v[218:221], v[190:193], 0
	v_mfma_f32_16x16x32_bf16 v[68:71], v[210:213], v[202:205], 0
	v_mfma_f32_16x16x32_bf16 v[64:67], v[218:221], v[202:205], 0
	v_mfma_f32_16x16x32_bf16 v[116:119], v[214:217], v[178:181], v[116:119]
	v_mfma_f32_16x16x32_bf16 v[112:115], v[222:225], v[178:181], v[112:115]
	v_mfma_f32_16x16x32_bf16 v[100:103], v[214:217], v[186:189], v[100:103]
	v_mfma_f32_16x16x32_bf16 v[96:99], v[222:225], v[186:189], v[96:99]
	v_mfma_f32_16x16x32_bf16 v[84:87], v[214:217], v[194:197], v[84:87]
	v_mfma_f32_16x16x32_bf16 v[80:83], v[222:225], v[194:197], v[80:83]
	v_mfma_f32_16x16x32_bf16 v[68:71], v[214:217], v[206:209], v[68:71]
	v_mfma_f32_16x16x32_bf16 v[64:67], v[222:225], v[206:209], v[64:67]
	s_mov_b32 m0, s45
	v_lshl_add_u64 v[226:227], s[6:7], 0, v[128:129]
	s_barrier
	s_setprio 0
	ds_read_b128 v[162:165], v172 offset:16384
	ds_read_b128 v[178:181], v172 offset:17408
	ds_read_b128 v[182:185], v172 offset:18432
	ds_read_b128 v[186:189], v172 offset:19456
	ds_read_b128 v[190:193], v172 offset:20480
	ds_read_b128 v[194:197], v172 offset:21504
	ds_read_b128 v[202:205], v172 offset:22528
	ds_read_b128 v[206:209], v172 offset:23552
	global_load_lds_dwordx4 v128, s[6:7]
	v_lshl_add_u64 v[228:229], s[6:7], 0, v[132:133]
	s_mov_b32 m0, s46
	s_nop 0
	global_load_lds_dwordx4 v132, s[6:7]
	s_waitcnt lgkmcnt(0)
	s_setprio 1
	s_barrier
	v_mfma_f32_16x16x32_bf16 v[60:63], v[146:149], v[162:165], 0
	v_mfma_f32_16x16x32_bf16 v[56:59], v[154:157], v[162:165], 0
	v_mfma_f32_16x16x32_bf16 v[44:47], v[146:149], v[182:185], 0
	v_mfma_f32_16x16x32_bf16 v[40:43], v[154:157], v[182:185], 0
	v_mfma_f32_16x16x32_bf16 v[28:31], v[146:149], v[190:193], 0
	v_mfma_f32_16x16x32_bf16 v[24:27], v[154:157], v[190:193], 0
	v_mfma_f32_16x16x32_bf16 v[12:15], v[146:149], v[202:205], 0
	v_mfma_f32_16x16x32_bf16 v[8:11], v[154:157], v[202:205], 0
	v_mfma_f32_16x16x32_bf16 v[60:63], v[150:153], v[178:181], v[60:63]
	v_mfma_f32_16x16x32_bf16 v[56:59], v[158:161], v[178:181], v[56:59]
	v_mfma_f32_16x16x32_bf16 v[44:47], v[150:153], v[186:189], v[44:47]
	v_mfma_f32_16x16x32_bf16 v[40:43], v[158:161], v[186:189], v[40:43]
	v_mfma_f32_16x16x32_bf16 v[28:31], v[150:153], v[194:197], v[28:31]
	v_mfma_f32_16x16x32_bf16 v[24:27], v[158:161], v[194:197], v[24:27]
	v_mfma_f32_16x16x32_bf16 v[12:15], v[150:153], v[206:209], v[12:15]
	v_mfma_f32_16x16x32_bf16 v[8:11], v[158:161], v[206:209], v[8:11]
	s_barrier
; #define PG8_STAGE(bufoff, gbase, voff) do { _Pragma("unroll") for (int _i = 0; _i < 2; ++_i) \
;         __builtin_amdgcn_global_load_lds((const unsigned*)((const char*)(gbase) + (voff)[_i]), (LAS unsigned*)(lds + (bufoff) + ldsw + _i * 8192), 16, 0, 0); } while (0)
; #define PG8_LDA(dst, b, h) do { _Pragma("unroll") for (int m = 0; m < 4; ++m) _Pragma("unroll") for (int k = 0; k < 2; ++k) dst[m][k] = *(const LAS bf16x8*)(lds + PG8_SA(b, h) + aoff + m * 2048 + k * 1024); } while (0)
; #define PG8_LDB(dst, b, h) do { _Pragma("unroll") for (int n = 0; n < 2; ++n) _Pragma("unroll") for (int k = 0; k < 2; ++k) dst[n][k] = *(const LAS bf16x8*)(lds + PG8_SB(b, h) + boff + n * 2048 + k * 1024); } while (0)
; #define PG8_MMA(ai, bj, At, Bt) do { __builtin_amdgcn_s_setprio(1); _Pragma("unroll") for (int m = 0; m < 4; ++m) _Pragma("unroll") for (int n = 0; n < 2; ++n) _Pragma("unroll") for (int k = 0; k < 2; ++k) \
;         acc[ai][bj][m][n] = __builtin_amdgcn_mfma_f32_16x16x32_bf16(Bt[n][k], At[m][k], acc[ai][bj][m][n], 0, 0, 0); __builtin_amdgcn_s_setprio(0); } while (0)
; #define PG8_WAIT_V(n) asm volatile("s_waitcnt vmcnt(" #n ")" ::: "memory")
; #define PG8_WAIT_L(n) asm volatile("s_waitcnt lgkmcnt(" #n ")" ::: "memory")
; #define PG8_BAR __builtin_amdgcn_s_barrier()
; #define PG8_SCHED __builtin_amdgcn_sched_barrier(0)
; template <class Epi, class Sched>
; __device__ __forceinline__ void gemm_phase(LAS unsigned char* lds, const Gemm g, const Sched& S, const Epi& E) {
;     ...
;             PG8_STAGE(PG8_SB(0, 1), b2 + hstep, voffB);
;             PG8_WAIT_V(6); PG8_BAR; PG8_MMA(1, 1, At, B1); PG8_BAR;
;             PG8_LDB(B0, 1, 0); PG8_SCHED; PG8_LDA(At, 1, 0); PG8_STAGE(PG8_SA(0, 1), a2 + hstep, voffA);
;             PG8_WAIT_L(8); PG8_BAR; PG8_WAIT_L(0); PG8_MMA(0, 0, At, B0); PG8_BAR; PG8_SCHED;
;             PG8_LDB(B1, 1, 1); PG8_STAGE(PG8_SB(1, 0), b3, voffB);
;             PG8_BAR; PG8_WAIT_L(0); PG8_MMA(0, 1, At, B1); PG8_BAR;
;             PG8_LDA(At, 1, 1); PG8_STAGE(PG8_SA(1, 0), a3, voffA);
;             PG8_BAR; PG8_WAIT_L(0); PG8_MMA(1, 0, At, B0); PG8_BAR; PG8_SCHED;
	s_setprio 0
	s_add_u32 s68, s4, 0x40000
	s_addc_u32 s69, s5, 0
	s_add_i32 s70, s58, s44
	s_mov_b32 m0, s70
	s_nop 0
	global_load_lds_dwordx4 v130, s[68:69]
	s_add_i32 m0, s70, 0x2000
	s_nop 0
	global_load_lds_dwordx4 v134, s[68:69]
	s_add_u32 s6, s6, 0x40000
	s_addc_u32 s7, s7, 0
	s_mov_b32 m0, s47
	s_nop 0
	global_load_lds_dwordx4 v128, s[6:7]
	s_mov_b32 m0, s48
	s_nop 0
	global_load_lds_dwordx4 v132, s[6:7]
	s_waitcnt vmcnt(10)
	s_setprio 1
	s_barrier
	v_mfma_f32_16x16x32_bf16 v[52:55], v[210:213], v[162:165], 0
	v_mfma_f32_16x16x32_bf16 v[48:51], v[218:221], v[162:165], 0
	v_mfma_f32_16x16x32_bf16 v[36:39], v[210:213], v[182:185], 0
	v_mfma_f32_16x16x32_bf16 v[32:35], v[218:221], v[182:185], 0
	v_mfma_f32_16x16x32_bf16 v[20:23], v[210:213], v[190:193], 0
	v_mfma_f32_16x16x32_bf16 v[16:19], v[218:221], v[190:193], 0
	v_mfma_f32_16x16x32_bf16 v[4:7], v[210:213], v[202:205], 0
	v_mfma_f32_16x16x32_bf16 v[0:3], v[218:221], v[202:205], 0
	v_mfma_f32_16x16x32_bf16 v[52:55], v[214:217], v[178:181], v[52:55]
	v_mfma_f32_16x16x32_bf16 v[48:51], v[222:225], v[178:181], v[48:51]
	v_mfma_f32_16x16x32_bf16 v[36:39], v[214:217], v[186:189], v[36:39]
	v_mfma_f32_16x16x32_bf16 v[32:35], v[222:225], v[186:189], v[32:35]
	v_mfma_f32_16x16x32_bf16 v[20:23], v[214:217], v[194:197], v[20:23]
	v_mfma_f32_16x16x32_bf16 v[16:19], v[222:225], v[194:197], v[16:19]
	v_mfma_f32_16x16x32_bf16 v[4:7], v[214:217], v[206:209], v[4:7]
	v_mfma_f32_16x16x32_bf16 v[0:3], v[222:225], v[206:209], v[0:3]
	s_add_i32 s68, 0, 0x18000
	v_add_u32_e32 v136, s68, v170
	s_barrier
	s_setprio 0
	ds_read_b128 v[146:149], v136
	ds_read_b128 v[150:153], v136 offset:1024
	ds_read_b128 v[154:157], v136 offset:2048
	ds_read_b128 v[158:161], v136 offset:3072
	ds_read_b128 v[162:165], v172 offset:32768
	ds_read_b128 v[178:181], v172 offset:33792
	ds_read_b128 v[182:185], v172 offset:34816
	ds_read_b128 v[186:189], v172 offset:35840
	ds_read_b128 v[190:193], v172 offset:36864
	ds_read_b128 v[194:197], v172 offset:37888
	ds_read_b128 v[202:205], v172 offset:38912
	ds_read_b128 v[206:209], v172 offset:39936
	s_waitcnt lgkmcnt(8)
	s_waitcnt vmcnt(8)
	s_waitcnt lgkmcnt(0)
	s_setprio 1
	s_barrier
	v_mfma_f32_16x16x32_bf16 v[124:127], v[146:149], v[162:165], v[124:127]
	v_mfma_f32_16x16x32_bf16 v[120:123], v[154:157], v[162:165], v[120:123]
	v_mfma_f32_16x16x32_bf16 v[108:111], v[146:149], v[182:185], v[108:111]
	v_mfma_f32_16x16x32_bf16 v[104:107], v[154:157], v[182:185], v[104:107]
	v_mfma_f32_16x16x32_bf16 v[92:95], v[146:149], v[190:193], v[92:95]
	v_mfma_f32_16x16x32_bf16 v[88:91], v[154:157], v[190:193], v[88:91]
	v_mfma_f32_16x16x32_bf16 v[76:79], v[146:149], v[202:205], v[76:79]
	v_mfma_f32_16x16x32_bf16 v[72:75], v[154:157], v[202:205], v[72:75]
	v_mfma_f32_16x16x32_bf16 v[124:127], v[150:153], v[178:181], v[124:127]
	v_mfma_f32_16x16x32_bf16 v[120:123], v[158:161], v[178:181], v[120:123]
	v_mfma_f32_16x16x32_bf16 v[108:111], v[150:153], v[186:189], v[108:111]
	v_mfma_f32_16x16x32_bf16 v[104:107], v[158:161], v[186:189], v[104:107]
	v_mfma_f32_16x16x32_bf16 v[92:95], v[150:153], v[194:197], v[92:95]
	v_mfma_f32_16x16x32_bf16 v[88:91], v[158:161], v[194:197], v[88:91]
	v_mfma_f32_16x16x32_bf16 v[76:79], v[150:153], v[206:209], v[76:79]
	v_mfma_f32_16x16x32_bf16 v[72:75], v[158:161], v[206:209], v[72:75]
	s_barrier
	s_setprio 0
	s_add_i32 s6, 0, 0x1c000
	s_add_i32 s7, s68, s44
	v_add_u32_e32 v136, s6, v170
	s_add_u32 s20, s4, 0x80
	s_addc_u32 s21, s5, 0
	s_mov_b32 m0, s7
	ds_read_b128 v[210:213], v136
	ds_read_b128 v[214:217], v136 offset:1024
	ds_read_b128 v[218:221], v136 offset:2048
	ds_read_b128 v[222:225], v136 offset:3072
	global_load_lds_dwordx4 v130, s[20:21]
	s_add_i32 m0, s7, 0x2000
	s_nop 0
	global_load_lds_dwordx4 v134, s[20:21]
	s_waitcnt vmcnt(8)
	s_waitcnt lgkmcnt(0)
	s_setprio 1
	s_barrier
	v_mfma_f32_16x16x32_bf16 v[116:119], v[210:213], v[162:165], v[116:119]
	v_mfma_f32_16x16x32_bf16 v[112:115], v[218:221], v[162:165], v[112:115]
	v_mfma_f32_16x16x32_bf16 v[100:103], v[210:213], v[182:185], v[100:103]
	v_mfma_f32_16x16x32_bf16 v[96:99], v[218:221], v[182:185], v[96:99]
	v_mfma_f32_16x16x32_bf16 v[84:87], v[210:213], v[190:193], v[84:87]
	v_mfma_f32_16x16x32_bf16 v[80:83], v[218:221], v[190:193], v[80:83]
	v_mfma_f32_16x16x32_bf16 v[68:71], v[210:213], v[202:205], v[68:71]
	v_mfma_f32_16x16x32_bf16 v[64:67], v[218:221], v[202:205], v[64:67]
	v_mfma_f32_16x16x32_bf16 v[116:119], v[214:217], v[178:181], v[116:119]
	v_mfma_f32_16x16x32_bf16 v[112:115], v[222:225], v[178:181], v[112:115]
	v_mfma_f32_16x16x32_bf16 v[100:103], v[214:217], v[186:189], v[100:103]
	v_mfma_f32_16x16x32_bf16 v[96:99], v[222:225], v[186:189], v[96:99]
	v_mfma_f32_16x16x32_bf16 v[84:87], v[214:217], v[194:197], v[84:87]
	v_mfma_f32_16x16x32_bf16 v[80:83], v[222:225], v[194:197], v[80:83]
	v_mfma_f32_16x16x32_bf16 v[68:71], v[214:217], v[206:209], v[68:71]
	v_mfma_f32_16x16x32_bf16 v[64:67], v[222:225], v[206:209], v[64:67]
	s_mov_b32 m0, s54
	s_mov_b64 s[20:21], 0x80
	v_lshl_add_u64 v[166:167], v[226:227], 0, s[20:21]
	s_barrier
	s_setprio 0
	ds_read_b128 v[162:165], v172 offset:49152
	ds_read_b128 v[178:181], v172 offset:50176
	ds_read_b128 v[182:185], v172 offset:51200
	ds_read_b128 v[186:189], v172 offset:52224
	ds_read_b128 v[190:193], v172 offset:53248
	ds_read_b128 v[194:197], v172 offset:54272
	ds_read_b128 v[202:205], v172 offset:55296
	ds_read_b128 v[206:209], v172 offset:56320
	global_load_lds_dwordx4 v[166:167], off
	v_lshl_add_u64 v[166:167], v[228:229], 0, s[20:21]
	s_mov_b32 m0, s55
	s_nop 0
	global_load_lds_dwordx4 v[166:167], off
	s_waitcnt lgkmcnt(0)
	s_setprio 1
	s_barrier
; #define PG8_STAGE(bufoff, gbase, voff) do { _Pragma("unroll") for (int _i = 0; _i < 2; ++_i) \
;         __builtin_amdgcn_global_load_lds((const unsigned*)((const char*)(gbase) + (voff)[_i]), (LAS unsigned*)(lds + (bufoff) + ldsw + _i * 8192), 16, 0, 0); } while (0)
; #define PG8_LDA(dst, b, h) do { _Pragma("unroll") for (int m = 0; m < 4; ++m) _Pragma("unroll") for (int k = 0; k < 2; ++k) dst[m][k] = *(const LAS bf16x8*)(lds + PG8_SA(b, h) + aoff + m * 2048 + k * 1024); } while (0)
; #define PG8_WAIT_V(n) asm volatile("s_waitcnt vmcnt(" #n ")" ::: "memory")
; #define PG8_WAIT_L(n) asm volatile("s_waitcnt lgkmcnt(" #n ")" ::: "memory")
; template <class Epi, class Sched>
; __device__ __forceinline__ void gemm_phase(LAS unsigned char* lds, const Gemm g, const Sched& S, const Epi& E) {
;     ...
;         for (int t = 0; t < nt; t += 2) {
;             const bool last = (t == nt - 2);
;             const char* a1 = cA + (size_t)(t + 1) * kstep;
;             const char* a2 = last ? nA : cA + (size_t)(t + 2) * kstep; const char* b2 = last ? nB : cB + (size_t)(t + 2) * kstep;
;             const char* a3 = a2 + kstep; const char* b3 = b2 + kstep;
;             PG8_LDB(B0, 0, 0); PG8_SCHED; PG8_LDA(At, 0, 0); PG8_STAGE(PG8_SA(1, 1), a1 + hstep, voffA);
;             PG8_WAIT_L(8); PG8_BAR; PG8_WAIT_L(0); PG8_MMA(0, 0, At, B0); PG8_BAR; PG8_SCHED;
;             PG8_LDB(B1, 0, 1); PG8_STAGE(PG8_SB(0, 0), b2, voffB);
;             PG8_BAR; PG8_WAIT_L(0); PG8_MMA(0, 1, At, B1); PG8_BAR;
;             PG8_LDA(At, 0, 1); PG8_STAGE(PG8_SA(0, 0), a2, voffA);
;             PG8_BAR; PG8_WAIT_L(0); PG8_MMA(1, 0, At, B0); PG8_BAR; PG8_SCHED;
;             PG8_STAGE(PG8_SB(0, 1), b2 + hstep, voffB);
;             PG8_WAIT_V(6); PG8_BAR; PG8_MMA(1, 1, At, B1); PG8_BAR;
;             PG8_LDB(B0, 1, 0); PG8_SCHED; PG8_LDA(At, 1, 0); PG8_STAGE(PG8_SA(0, 1), a2 + hstep, voffA);
;             PG8_WAIT_L(8); PG8_BAR; PG8_WAIT_L(0); PG8_MMA(0, 0, At, B0); PG8_BAR; PG8_SCHED;
;             PG8_LDB(B1, 1, 1); PG8_STAGE(PG8_SB(1, 0), b3, voffB);
;             PG8_BAR; PG8_WAIT_L(0); PG8_MMA(0, 1, At, B1); PG8_BAR;
;             PG8_LDA(At, 1, 1); PG8_STAGE(PG8_SA(1, 0), a3, voffA);
;             PG8_BAR; PG8_WAIT_L(0); PG8_MMA(1, 0, At, B0); PG8_BAR; PG8_SCHED;
;             PG8_STAGE(PG8_SB(1, 1), b3 + hstep, voffB);
;             PG8_WAIT_V(6); PG8_BAR; PG8_MMA(1, 1, At, B1); PG8_BAR;
	v_mfma_f32_16x16x32_bf16 v[60:63], v[146:149], v[162:165], v[60:63]
	v_mfma_f32_16x16x32_bf16 v[56:59], v[154:157], v[162:165], v[56:59]
	v_mfma_f32_16x16x32_bf16 v[44:47], v[146:149], v[182:185], v[44:47]
	v_mfma_f32_16x16x32_bf16 v[40:43], v[154:157], v[182:185], v[40:43]
	v_mfma_f32_16x16x32_bf16 v[28:31], v[146:149], v[190:193], v[28:31]
	v_mfma_f32_16x16x32_bf16 v[24:27], v[154:157], v[190:193], v[24:27]
	v_mfma_f32_16x16x32_bf16 v[12:15], v[146:149], v[202:205], v[12:15]
	v_mfma_f32_16x16x32_bf16 v[8:11], v[154:157], v[202:205], v[8:11]
	v_mfma_f32_16x16x32_bf16 v[60:63], v[150:153], v[178:181], v[60:63]
	v_mfma_f32_16x16x32_bf16 v[56:59], v[158:161], v[178:181], v[56:59]
	v_mfma_f32_16x16x32_bf16 v[44:47], v[150:153], v[186:189], v[44:47]
	v_mfma_f32_16x16x32_bf16 v[40:43], v[158:161], v[186:189], v[40:43]
	v_mfma_f32_16x16x32_bf16 v[28:31], v[150:153], v[194:197], v[28:31]
	v_mfma_f32_16x16x32_bf16 v[24:27], v[158:161], v[194:197], v[24:27]
	v_mfma_f32_16x16x32_bf16 v[12:15], v[150:153], v[206:209], v[12:15]
	v_mfma_f32_16x16x32_bf16 v[8:11], v[158:161], v[206:209], v[8:11]
	s_barrier
	s_setprio 0
	s_add_u32 s4, s4, 0x40080
	s_addc_u32 s5, s5, 0
	s_add_i32 s6, s6, s44
	s_mov_b32 m0, s6
	s_nop 0
	global_load_lds_dwordx4 v130, s[4:5]
	s_add_i32 m0, s6, 0x2000
	s_nop 0
	global_load_lds_dwordx4 v134, s[4:5]
	s_waitcnt vmcnt(8)
	s_setprio 1
	s_barrier
	v_mfma_f32_16x16x32_bf16 v[52:55], v[210:213], v[162:165], v[52:55]
	v_mfma_f32_16x16x32_bf16 v[48:51], v[218:221], v[162:165], v[48:51]
	v_mfma_f32_16x16x32_bf16 v[36:39], v[210:213], v[182:185], v[36:39]
	v_mfma_f32_16x16x32_bf16 v[32:35], v[218:221], v[182:185], v[32:35]
	v_mfma_f32_16x16x32_bf16 v[20:23], v[210:213], v[190:193], v[20:23]
	v_mfma_f32_16x16x32_bf16 v[16:19], v[218:221], v[190:193], v[16:19]
	v_mfma_f32_16x16x32_bf16 v[4:7], v[210:213], v[202:205], v[4:7]
	v_mfma_f32_16x16x32_bf16 v[0:3], v[218:221], v[202:205], v[0:3]
	v_mfma_f32_16x16x32_bf16 v[52:55], v[214:217], v[178:181], v[52:55]
	v_mfma_f32_16x16x32_bf16 v[48:51], v[222:225], v[178:181], v[48:51]
	v_mfma_f32_16x16x32_bf16 v[36:39], v[214:217], v[186:189], v[36:39]
	v_mfma_f32_16x16x32_bf16 v[32:35], v[222:225], v[186:189], v[32:35]
	v_mfma_f32_16x16x32_bf16 v[20:23], v[214:217], v[194:197], v[20:23]
	v_mfma_f32_16x16x32_bf16 v[16:19], v[222:225], v[194:197], v[16:19]
	v_mfma_f32_16x16x32_bf16 v[4:7], v[214:217], v[206:209], v[4:7]
	v_mfma_f32_16x16x32_bf16 v[0:3], v[222:225], v[206:209], v[0:3]
	s_add_i32 s67, s67, 2
	s_add_u32 s0, s0, 0x100
	s_addc_u32 s1, s1, 0
	s_add_u32 s65, s65, 0x100
	s_addc_u32 s66, s66, 0
	s_cmp_gt_u32 s67, 13
	s_barrier
	s_setprio 0
.LBB0_613:
	ds_read_b128 v[146:149], v171
	ds_read_b128 v[150:153], v171 offset:1024
	ds_read_b128 v[154:157], v171 offset:2048
	ds_read_b128 v[158:161], v171 offset:3072
	s_add_u32 s4, s0, 0xfffc0080
	s_addc_u32 s5, s1, -1
	s_cmp_eq_u32 s67, 12
	s_cselect_b32 s7, s8, s5
	s_cselect_b32 s6, s9, s4
	s_cselect_b32 s5, s31, s66
	s_cselect_b32 s4, s35, s65
	s_add_i32 m0, s45, 0xc000
	ds_read_b128 v[162:165], v172
	ds_read_b128 v[178:181], v172 offset:1024
	ds_read_b128 v[182:185], v172 offset:2048
	ds_read_b128 v[186:189], v172 offset:3072
	ds_read_b128 v[190:193], v172 offset:4096
	ds_read_b128 v[194:197], v172 offset:5120
	ds_read_b128 v[202:205], v172 offset:6144
	ds_read_b128 v[206:209], v172 offset:7168
	global_load_lds_dwordx4 v138, s[0:1]
	s_add_i32 m0, s45, 0xe000
	s_nop 0
	global_load_lds_dwordx4 v140, s[0:1]
	s_waitcnt lgkmcnt(8)
	s_waitcnt vmcnt(8)
	s_waitcnt lgkmcnt(0)
	s_setprio 1
	s_barrier
	v_mfma_f32_16x16x32_bf16 v[124:127], v[146:149], v[162:165], v[124:127]
	v_mfma_f32_16x16x32_bf16 v[120:123], v[154:157], v[162:165], v[120:123]
	v_mfma_f32_16x16x32_bf16 v[108:111], v[146:149], v[182:185], v[108:111]
	v_mfma_f32_16x16x32_bf16 v[104:107], v[154:157], v[182:185], v[104:107]
	v_mfma_f32_16x16x32_bf16 v[92:95], v[146:149], v[190:193], v[92:95]
	v_mfma_f32_16x16x32_bf16 v[88:91], v[154:157], v[190:193], v[88:91]
	v_mfma_f32_16x16x32_bf16 v[76:79], v[146:149], v[202:205], v[76:79]
	v_mfma_f32_16x16x32_bf16 v[72:75], v[154:157], v[202:205], v[72:75]
	v_mfma_f32_16x16x32_bf16 v[124:127], v[150:153], v[178:181], v[124:127]
	v_mfma_f32_16x16x32_bf16 v[120:123], v[158:161], v[178:181], v[120:123]
	v_mfma_f32_16x16x32_bf16 v[108:111], v[150:153], v[186:189], v[108:111]
	v_mfma_f32_16x16x32_bf16 v[104:107], v[158:161], v[186:189], v[104:107]
	v_mfma_f32_16x16x32_bf16 v[92:95], v[150:153], v[194:197], v[92:95]
	v_mfma_f32_16x16x32_bf16 v[88:91], v[158:161], v[194:197], v[88:91]
	v_mfma_f32_16x16x32_bf16 v[76:79], v[150:153], v[206:209], v[76:79]
	v_mfma_f32_16x16x32_bf16 v[72:75], v[158:161], v[206:209], v[72:75]
	s_barrier
	s_setprio 0
	s_add_i32 s68, s57, s44
	s_mov_b32 m0, s68
	ds_read_b128 v[210:213], v173
	ds_read_b128 v[214:217], v173 offset:1024
	ds_read_b128 v[218:221], v173 offset:2048
	ds_read_b128 v[222:225], v173 offset:3072
	global_load_lds_dwordx4 v130, s[4:5]
	s_add_i32 m0, s68, 0x2000
	s_nop 0
	global_load_lds_dwordx4 v134, s[4:5]
	s_waitcnt vmcnt(8)
	s_waitcnt lgkmcnt(0)
	s_setprio 1
	s_barrier
; #define PG8_STAGE(bufoff, gbase, voff) do { _Pragma("unroll") for (int _i = 0; _i < 2; ++_i) \
;         __builtin_amdgcn_global_load_lds((const unsigned*)((const char*)(gbase) + (voff)[_i]), (LAS unsigned*)(lds + (bufoff) + ldsw + _i * 8192), 16, 0, 0); } while (0)
; #define PG8_LDA(dst, b, h) do { _Pragma("unroll") for (int m = 0; m < 4; ++m) _Pragma("unroll") for (int k = 0; k < 2; ++k) dst[m][k] = *(const LAS bf16x8*)(lds + PG8_SA(b, h) + aoff + m * 2048 + k * 1024); } while (0)
; #define PG8_LDB(dst, b, h) do { _Pragma("unroll") for (int n = 0; n < 2; ++n) _Pragma("unroll") for (int k = 0; k < 2; ++k) dst[n][k] = *(const LAS bf16x8*)(lds + PG8_SB(b, h) + boff + n * 2048 + k * 1024); } while (0)
; #define PG8_MMA(ai, bj, At, Bt) do { __builtin_amdgcn_s_setprio(1); _Pragma("unroll") for (int m = 0; m < 4; ++m) _Pragma("unroll") for (int n = 0; n < 2; ++n) _Pragma("unroll") for (int k = 0; k < 2; ++k) \
;         acc[ai][bj][m][n] = __builtin_amdgcn_mfma_f32_16x16x32_bf16(Bt[n][k], At[m][k], acc[ai][bj][m][n], 0, 0, 0); __builtin_amdgcn_s_setprio(0); } while (0)
; #define PG8_WAIT_V(n) asm volatile("s_waitcnt vmcnt(" #n ")" ::: "memory")
; #define PG8_WAIT_L(n) asm volatile("s_waitcnt lgkmcnt(" #n ")" ::: "memory")
; #define PG8_BAR __builtin_amdgcn_s_barrier()
; #define PG8_SCHED __builtin_amdgcn_sched_barrier(0)
; template <class Epi, class Sched>
; __device__ __forceinline__ void gemm_phase(LAS unsigned char* lds, const Gemm g, const Sched& S, const Epi& E) {
;     ...
;             PG8_LDA(At, 0, 1); PG8_STAGE(PG8_SA(0, 0), a2, voffA);
;             PG8_BAR; PG8_WAIT_L(0); PG8_MMA(1, 0, At, B0); PG8_BAR; PG8_SCHED;
;             PG8_STAGE(PG8_SB(0, 1), b2 + hstep, voffB);
;             PG8_WAIT_V(6); PG8_BAR; PG8_MMA(1, 1, At, B1); PG8_BAR;
;             PG8_LDB(B0, 1, 0); PG8_SCHED; PG8_LDA(At, 1, 0); PG8_STAGE(PG8_SA(0, 1), a2 + hstep, voffA);
;             PG8_WAIT_L(8); PG8_BAR; PG8_WAIT_L(0); PG8_MMA(0, 0, At, B0); PG8_BAR; PG8_SCHED;
	v_mfma_f32_16x16x32_bf16 v[116:119], v[210:213], v[162:165], v[116:119]
	v_mfma_f32_16x16x32_bf16 v[112:115], v[218:221], v[162:165], v[112:115]
	v_mfma_f32_16x16x32_bf16 v[100:103], v[210:213], v[182:185], v[100:103]
	v_mfma_f32_16x16x32_bf16 v[96:99], v[218:221], v[182:185], v[96:99]
	v_mfma_f32_16x16x32_bf16 v[84:87], v[210:213], v[190:193], v[84:87]
	v_mfma_f32_16x16x32_bf16 v[80:83], v[218:221], v[190:193], v[80:83]
	v_mfma_f32_16x16x32_bf16 v[68:71], v[210:213], v[202:205], v[68:71]
	v_mfma_f32_16x16x32_bf16 v[64:67], v[218:221], v[202:205], v[64:67]
	v_mfma_f32_16x16x32_bf16 v[116:119], v[214:217], v[178:181], v[116:119]
	v_mfma_f32_16x16x32_bf16 v[112:115], v[222:225], v[178:181], v[112:115]
	v_mfma_f32_16x16x32_bf16 v[100:103], v[214:217], v[186:189], v[100:103]
	v_mfma_f32_16x16x32_bf16 v[96:99], v[222:225], v[186:189], v[96:99]
	v_mfma_f32_16x16x32_bf16 v[84:87], v[214:217], v[194:197], v[84:87]
	v_mfma_f32_16x16x32_bf16 v[80:83], v[222:225], v[194:197], v[80:83]
	v_mfma_f32_16x16x32_bf16 v[68:71], v[214:217], v[206:209], v[68:71]
	v_mfma_f32_16x16x32_bf16 v[64:67], v[222:225], v[206:209], v[64:67]
	s_mov_b32 m0, s45
	v_lshl_add_u64 v[226:227], s[6:7], 0, v[128:129]
	s_barrier
	s_setprio 0
	ds_read_b128 v[162:165], v172 offset:16384
	ds_read_b128 v[178:181], v172 offset:17408
	ds_read_b128 v[182:185], v172 offset:18432
	ds_read_b128 v[186:189], v172 offset:19456
	ds_read_b128 v[190:193], v172 offset:20480
	ds_read_b128 v[194:197], v172 offset:21504
	ds_read_b128 v[202:205], v172 offset:22528
	ds_read_b128 v[206:209], v172 offset:23552
	global_load_lds_dwordx4 v128, s[6:7]
	v_lshl_add_u64 v[228:229], s[6:7], 0, v[132:133]
	s_mov_b32 m0, s46
	s_nop 0
	global_load_lds_dwordx4 v132, s[6:7]
	s_waitcnt lgkmcnt(0)
	s_setprio 1
	s_barrier
	v_mfma_f32_16x16x32_bf16 v[60:63], v[146:149], v[162:165], v[60:63]
	v_mfma_f32_16x16x32_bf16 v[56:59], v[154:157], v[162:165], v[56:59]
	v_mfma_f32_16x16x32_bf16 v[44:47], v[146:149], v[182:185], v[44:47]
	v_mfma_f32_16x16x32_bf16 v[40:43], v[154:157], v[182:185], v[40:43]
	v_mfma_f32_16x16x32_bf16 v[28:31], v[146:149], v[190:193], v[28:31]
	v_mfma_f32_16x16x32_bf16 v[24:27], v[154:157], v[190:193], v[24:27]
	v_mfma_f32_16x16x32_bf16 v[12:15], v[146:149], v[202:205], v[12:15]
	v_mfma_f32_16x16x32_bf16 v[8:11], v[154:157], v[202:205], v[8:11]
	v_mfma_f32_16x16x32_bf16 v[60:63], v[150:153], v[178:181], v[60:63]
	v_mfma_f32_16x16x32_bf16 v[56:59], v[158:161], v[178:181], v[56:59]
	v_mfma_f32_16x16x32_bf16 v[44:47], v[150:153], v[186:189], v[44:47]
	v_mfma_f32_16x16x32_bf16 v[40:43], v[158:161], v[186:189], v[40:43]
	v_mfma_f32_16x16x32_bf16 v[28:31], v[150:153], v[194:197], v[28:31]
	v_mfma_f32_16x16x32_bf16 v[24:27], v[158:161], v[194:197], v[24:27]
	v_mfma_f32_16x16x32_bf16 v[12:15], v[150:153], v[206:209], v[12:15]
	v_mfma_f32_16x16x32_bf16 v[8:11], v[158:161], v[206:209], v[8:11]
	s_barrier
	s_setprio 0
	s_add_u32 s68, s4, 0x40000
	s_addc_u32 s69, s5, 0
	s_add_i32 s70, s58, s44
	s_mov_b32 m0, s70
	s_nop 0
	global_load_lds_dwordx4 v130, s[68:69]
	s_add_i32 m0, s70, 0x2000
	s_nop 0
	global_load_lds_dwordx4 v134, s[68:69]
	s_add_u32 s6, s6, 0x40000
	s_addc_u32 s7, s7, 0
	s_mov_b32 m0, s47
	s_nop 0
	global_load_lds_dwordx4 v128, s[6:7]
	s_mov_b32 m0, s48
	s_nop 0
	global_load_lds_dwordx4 v132, s[6:7]
	s_waitcnt vmcnt(10)
	s_setprio 1
	s_barrier
	v_mfma_f32_16x16x32_bf16 v[52:55], v[210:213], v[162:165], v[52:55]
	v_mfma_f32_16x16x32_bf16 v[48:51], v[218:221], v[162:165], v[48:51]
	v_mfma_f32_16x16x32_bf16 v[36:39], v[210:213], v[182:185], v[36:39]
	v_mfma_f32_16x16x32_bf16 v[32:35], v[218:221], v[182:185], v[32:35]
	v_mfma_f32_16x16x32_bf16 v[20:23], v[210:213], v[190:193], v[20:23]
	v_mfma_f32_16x16x32_bf16 v[16:19], v[218:221], v[190:193], v[16:19]
	v_mfma_f32_16x16x32_bf16 v[4:7], v[210:213], v[202:205], v[4:7]
	v_mfma_f32_16x16x32_bf16 v[0:3], v[218:221], v[202:205], v[0:3]
	v_mfma_f32_16x16x32_bf16 v[52:55], v[214:217], v[178:181], v[52:55]
	v_mfma_f32_16x16x32_bf16 v[48:51], v[222:225], v[178:181], v[48:51]
	v_mfma_f32_16x16x32_bf16 v[36:39], v[214:217], v[186:189], v[36:39]
	v_mfma_f32_16x16x32_bf16 v[32:35], v[222:225], v[186:189], v[32:35]
	v_mfma_f32_16x16x32_bf16 v[20:23], v[214:217], v[194:197], v[20:23]
	v_mfma_f32_16x16x32_bf16 v[16:19], v[222:225], v[194:197], v[16:19]
	v_mfma_f32_16x16x32_bf16 v[4:7], v[214:217], v[206:209], v[4:7]
	v_mfma_f32_16x16x32_bf16 v[0:3], v[222:225], v[206:209], v[0:3]
	s_add_i32 s68, 0, 0x18000
	v_add_u32_e32 v136, s68, v170
	s_barrier
	s_setprio 0
	ds_read_b128 v[146:149], v136
	ds_read_b128 v[150:153], v136 offset:1024
	ds_read_b128 v[154:157], v136 offset:2048
	ds_read_b128 v[158:161], v136 offset:3072
	ds_read_b128 v[162:165], v172 offset:32768
	ds_read_b128 v[178:181], v172 offset:33792
	ds_read_b128 v[182:185], v172 offset:34816
	ds_read_b128 v[186:189], v172 offset:35840
	ds_read_b128 v[190:193], v172 offset:36864
	ds_read_b128 v[194:197], v172 offset:37888
	ds_read_b128 v[202:205], v172 offset:38912
	ds_read_b128 v[206:209], v172 offset:39936
	s_waitcnt lgkmcnt(8)
	s_waitcnt vmcnt(8)
	s_waitcnt lgkmcnt(0)
	s_setprio 1
	s_barrier
; #define PG8_STAGE(bufoff, gbase, voff) do { _Pragma("unroll") for (int _i = 0; _i < 2; ++_i) \
;         __builtin_amdgcn_global_load_lds((const unsigned*)((const char*)(gbase) + (voff)[_i]), (LAS unsigned*)(lds + (bufoff) + ldsw + _i * 8192), 16, 0, 0); } while (0)
; #define PG8_LDA(dst, b, h) do { _Pragma("unroll") for (int m = 0; m < 4; ++m) _Pragma("unroll") for (int k = 0; k < 2; ++k) dst[m][k] = *(const LAS bf16x8*)(lds + PG8_SA(b, h) + aoff + m * 2048 + k * 1024); } while (0)
; #define PG8_LDB(dst, b, h) do { _Pragma("unroll") for (int n = 0; n < 2; ++n) _Pragma("unroll") for (int k = 0; k < 2; ++k) dst[n][k] = *(const LAS bf16x8*)(lds + PG8_SB(b, h) + boff + n * 2048 + k * 1024); } while (0)
; #define PG8_MMA(ai, bj, At, Bt) do { __builtin_amdgcn_s_setprio(1); _Pragma("unroll") for (int m = 0; m < 4; ++m) _Pragma("unroll") for (int n = 0; n < 2; ++n) _Pragma("unroll") for (int k = 0; k < 2; ++k) \
;         acc[ai][bj][m][n] = __builtin_amdgcn_mfma_f32_16x16x32_bf16(Bt[n][k], At[m][k], acc[ai][bj][m][n], 0, 0, 0); __builtin_amdgcn_s_setprio(0); } while (0)
; #define PG8_WAIT_V(n) asm volatile("s_waitcnt vmcnt(" #n ")" ::: "memory")
; #define PG8_WAIT_L(n) asm volatile("s_waitcnt lgkmcnt(" #n ")" ::: "memory")
; #define PG8_BAR __builtin_amdgcn_s_barrier()
; #define PG8_SCHED __builtin_amdgcn_sched_barrier(0)
; template <class Epi, class Sched>
; __device__ __forceinline__ void gemm_phase(LAS unsigned char* lds, const Gemm g, const Sched& S, const Epi& E) {
;     ...
;             PG8_WAIT_L(8); PG8_BAR; PG8_WAIT_L(0); PG8_MMA(0, 0, At, B0); PG8_BAR; PG8_SCHED;
;             PG8_LDB(B1, 1, 1); PG8_STAGE(PG8_SB(1, 0), b3, voffB);
;             PG8_BAR; PG8_WAIT_L(0); PG8_MMA(0, 1, At, B1); PG8_BAR;
;             PG8_LDA(At, 1, 1); PG8_STAGE(PG8_SA(1, 0), a3, voffA);
;             PG8_BAR; PG8_WAIT_L(0); PG8_MMA(1, 0, At, B0); PG8_BAR; PG8_SCHED;
;             PG8_STAGE(PG8_SB(1, 1), b3 + hstep, voffB);
;             PG8_WAIT_V(6); PG8_BAR; PG8_MMA(1, 1, At, B1); PG8_BAR;
	v_mfma_f32_16x16x32_bf16 v[124:127], v[146:149], v[162:165], v[124:127]
	v_mfma_f32_16x16x32_bf16 v[120:123], v[154:157], v[162:165], v[120:123]
	v_mfma_f32_16x16x32_bf16 v[108:111], v[146:149], v[182:185], v[108:111]
	v_mfma_f32_16x16x32_bf16 v[104:107], v[154:157], v[182:185], v[104:107]
	v_mfma_f32_16x16x32_bf16 v[92:95], v[146:149], v[190:193], v[92:95]
	v_mfma_f32_16x16x32_bf16 v[88:91], v[154:157], v[190:193], v[88:91]
	v_mfma_f32_16x16x32_bf16 v[76:79], v[146:149], v[202:205], v[76:79]
	v_mfma_f32_16x16x32_bf16 v[72:75], v[154:157], v[202:205], v[72:75]
	v_mfma_f32_16x16x32_bf16 v[124:127], v[150:153], v[178:181], v[124:127]
	v_mfma_f32_16x16x32_bf16 v[120:123], v[158:161], v[178:181], v[120:123]
	v_mfma_f32_16x16x32_bf16 v[108:111], v[150:153], v[186:189], v[108:111]
	v_mfma_f32_16x16x32_bf16 v[104:107], v[158:161], v[186:189], v[104:107]
	v_mfma_f32_16x16x32_bf16 v[92:95], v[150:153], v[194:197], v[92:95]
	v_mfma_f32_16x16x32_bf16 v[88:91], v[158:161], v[194:197], v[88:91]
	v_mfma_f32_16x16x32_bf16 v[76:79], v[150:153], v[206:209], v[76:79]
	v_mfma_f32_16x16x32_bf16 v[72:75], v[158:161], v[206:209], v[72:75]
	s_barrier
	s_setprio 0
	s_add_i32 s6, 0, 0x1c000
	s_add_i32 s7, s68, s44
	v_add_u32_e32 v136, s6, v170
	s_add_u32 s20, s4, 0x80
	s_addc_u32 s21, s5, 0
	s_mov_b32 m0, s7
	ds_read_b128 v[210:213], v136
	ds_read_b128 v[214:217], v136 offset:1024
	ds_read_b128 v[218:221], v136 offset:2048
	ds_read_b128 v[222:225], v136 offset:3072
	global_load_lds_dwordx4 v130, s[20:21]
	s_add_i32 m0, s7, 0x2000
	s_nop 0
	global_load_lds_dwordx4 v134, s[20:21]
	s_waitcnt vmcnt(8)
	s_waitcnt lgkmcnt(0)
	s_setprio 1
	s_barrier
	v_mfma_f32_16x16x32_bf16 v[116:119], v[210:213], v[162:165], v[116:119]
	v_mfma_f32_16x16x32_bf16 v[112:115], v[218:221], v[162:165], v[112:115]
	v_mfma_f32_16x16x32_bf16 v[100:103], v[210:213], v[182:185], v[100:103]
	v_mfma_f32_16x16x32_bf16 v[96:99], v[218:221], v[182:185], v[96:99]
	v_mfma_f32_16x16x32_bf16 v[84:87], v[210:213], v[190:193], v[84:87]
	v_mfma_f32_16x16x32_bf16 v[80:83], v[218:221], v[190:193], v[80:83]
	v_mfma_f32_16x16x32_bf16 v[68:71], v[210:213], v[202:205], v[68:71]
	v_mfma_f32_16x16x32_bf16 v[64:67], v[218:221], v[202:205], v[64:67]
	v_mfma_f32_16x16x32_bf16 v[116:119], v[214:217], v[178:181], v[116:119]
	v_mfma_f32_16x16x32_bf16 v[112:115], v[222:225], v[178:181], v[112:115]
	v_mfma_f32_16x16x32_bf16 v[100:103], v[214:217], v[186:189], v[100:103]
	v_mfma_f32_16x16x32_bf16 v[96:99], v[222:225], v[186:189], v[96:99]
	v_mfma_f32_16x16x32_bf16 v[84:87], v[214:217], v[194:197], v[84:87]
	v_mfma_f32_16x16x32_bf16 v[80:83], v[222:225], v[194:197], v[80:83]
	v_mfma_f32_16x16x32_bf16 v[68:71], v[214:217], v[206:209], v[68:71]
	v_mfma_f32_16x16x32_bf16 v[64:67], v[222:225], v[206:209], v[64:67]
	s_mov_b32 m0, s54
	s_mov_b64 s[20:21], 0x80
	v_lshl_add_u64 v[166:167], v[226:227], 0, s[20:21]
	s_barrier
	s_setprio 0
	ds_read_b128 v[162:165], v172 offset:49152
	ds_read_b128 v[178:181], v172 offset:50176
	ds_read_b128 v[182:185], v172 offset:51200
	ds_read_b128 v[186:189], v172 offset:52224
	ds_read_b128 v[190:193], v172 offset:53248
	ds_read_b128 v[194:197], v172 offset:54272
	ds_read_b128 v[202:205], v172 offset:55296
	ds_read_b128 v[206:209], v172 offset:56320
	global_load_lds_dwordx4 v[166:167], off
	v_lshl_add_u64 v[166:167], v[228:229], 0, s[20:21]
	s_mov_b32 m0, s55
	s_nop 0
	global_load_lds_dwordx4 v[166:167], off
	s_waitcnt lgkmcnt(0)
	s_setprio 1
	s_barrier
	v_mfma_f32_16x16x32_bf16 v[60:63], v[146:149], v[162:165], v[60:63]
	v_mfma_f32_16x16x32_bf16 v[56:59], v[154:157], v[162:165], v[56:59]
	v_mfma_f32_16x16x32_bf16 v[44:47], v[146:149], v[182:185], v[44:47]
	v_mfma_f32_16x16x32_bf16 v[40:43], v[154:157], v[182:185], v[40:43]
	v_mfma_f32_16x16x32_bf16 v[28:31], v[146:149], v[190:193], v[28:31]
	v_mfma_f32_16x16x32_bf16 v[24:27], v[154:157], v[190:193], v[24:27]
	v_mfma_f32_16x16x32_bf16 v[12:15], v[146:149], v[202:205], v[12:15]
	v_mfma_f32_16x16x32_bf16 v[8:11], v[154:157], v[202:205], v[8:11]
	v_mfma_f32_16x16x32_bf16 v[60:63], v[150:153], v[178:181], v[60:63]
	v_mfma_f32_16x16x32_bf16 v[56:59], v[158:161], v[178:181], v[56:59]
	v_mfma_f32_16x16x32_bf16 v[44:47], v[150:153], v[186:189], v[44:47]
	v_mfma_f32_16x16x32_bf16 v[40:43], v[158:161], v[186:189], v[40:43]
	v_mfma_f32_16x16x32_bf16 v[28:31], v[150:153], v[194:197], v[28:31]
	v_mfma_f32_16x16x32_bf16 v[24:27], v[158:161], v[194:197], v[24:27]
	v_mfma_f32_16x16x32_bf16 v[12:15], v[150:153], v[206:209], v[12:15]
	v_mfma_f32_16x16x32_bf16 v[8:11], v[158:161], v[206:209], v[8:11]
	s_barrier
	s_setprio 0
	s_add_u32 s4, s4, 0x40080
	s_addc_u32 s5, s5, 0
	s_add_i32 s6, s6, s44
	s_mov_b32 m0, s6
	s_nop 0
	global_load_lds_dwordx4 v130, s[4:5]
	s_add_i32 m0, s6, 0x2000
	s_nop 0
	global_load_lds_dwordx4 v134, s[4:5]
	s_waitcnt vmcnt(8)
	s_setprio 1
	s_barrier
	v_mfma_f32_16x16x32_bf16 v[52:55], v[210:213], v[162:165], v[52:55]
	v_mfma_f32_16x16x32_bf16 v[48:51], v[218:221], v[162:165], v[48:51]
	v_mfma_f32_16x16x32_bf16 v[36:39], v[210:213], v[182:185], v[36:39]
	v_mfma_f32_16x16x32_bf16 v[32:35], v[218:221], v[182:185], v[32:35]
	v_mfma_f32_16x16x32_bf16 v[20:23], v[210:213], v[190:193], v[20:23]
	v_mfma_f32_16x16x32_bf16 v[16:19], v[218:221], v[190:193], v[16:19]
	v_mfma_f32_16x16x32_bf16 v[4:7], v[210:213], v[202:205], v[4:7]
	v_mfma_f32_16x16x32_bf16 v[0:3], v[218:221], v[202:205], v[0:3]
	v_mfma_f32_16x16x32_bf16 v[52:55], v[214:217], v[178:181], v[52:55]
	v_mfma_f32_16x16x32_bf16 v[48:51], v[222:225], v[178:181], v[48:51]
	v_mfma_f32_16x16x32_bf16 v[36:39], v[214:217], v[186:189], v[36:39]
	v_mfma_f32_16x16x32_bf16 v[32:35], v[222:225], v[186:189], v[32:35]
	v_mfma_f32_16x16x32_bf16 v[20:23], v[214:217], v[194:197], v[20:23]
	v_mfma_f32_16x16x32_bf16 v[16:19], v[222:225], v[194:197], v[16:19]
	v_mfma_f32_16x16x32_bf16 v[4:7], v[214:217], v[206:209], v[4:7]
	v_mfma_f32_16x16x32_bf16 v[0:3], v[222:225], v[206:209], v[0:3]
	s_add_i32 s67, s67, 2
	s_add_u32 s0, s0, 0x100
	s_addc_u32 s1, s1, 0
	s_add_u32 s65, s65, 0x100
	s_addc_u32 s66, s66, 0
	s_cmp_gt_u32 s67, 13
	s_barrier
;     __device__ __forceinline__ void operator()(const AccT& acc, const Unit& u, int wr, int wc, int fr, int fq) const {
;     ...
;         const int rbase = wr * 64 + fr;
;         const int tb = u.pn * 256 + wc * 32 + 8 * fq;
;         const int o0 = wc * 32 + 8 * fq;
;         const int j = fr & 3; const float sgn = ((fr >> 2) & 1) ? 1.0f : -1.0f;
; #pragma unroll
;         for (int ai = 0; ai < 2; ++ai) {
;             const int hh = 2 * ai + wr;
;             const float l2f = lgd[hh] * 1.4426950408889634f, l2b = lgd[4 + hh] * 1.4426950408889634f;
;             const float zf0 = exp2f((float)(127 - o0) * l2f), zfs = exp2f(-l2f), zb0 = exp2f((float)o0 * l2b), zbs = exp2f(l2b);
; #pragma unroll
;             for (int m = 0; m < 4; ++m) {
;                 const int r = rbase + ai * 128 + m * 16;
;                 const int d = 4 * (2 * m + (fr >> 3)) + j;
; #pragma unroll
;                 for (int bj = 0; bj < 2; ++bj) {
;                     const int t0 = tb + bj * 128;
;                     float v[8];
; #pragma unroll
;                     for (int jj = 0; jj < 4; ++jj) { v[jj] = acc[ai][bj][m][0][jj]; v[4 + jj] = acc[ai][bj][m][1][jj]; }
;                     if constexpr (ROPE) {
;                         const int t = t0 & 2047;
; #pragma unroll
;                         for (int hf = 0; hf < 2; ++hf) {
;                             f32x4 cs, sn;
;                             if (m < 2) { const float c1 = ropeA[(t >> 6) * 16 + d], s1 = ropeA[1024 + (t >> 6) * 16 + d]; cs = (f32x4){c1, c1, c1, c1}; sn = (f32x4){s1, s1, s1, s1}; }
;                             else { const float* cb = ropeA + 2048 + (d - 16) * 64 + (t & 63) + 4 * hf; cs = *(const f32x4*)(cb); sn = *(const f32x4*)(cb + 1024); }
; #pragma unroll
;                             for (int jj = 0; jj < 4; ++jj) { const float pr = __shfl_xor(v[4 * hf + jj], 4); v[4 * hf + jj] = v[4 * hf + jj] * cs[jj] + sgn * pr * sn[jj]; }
;                             __builtin_amdgcn_sched_barrier(0);
;                         }
;                     }
;                     float zf[8], zb[8]; zf[0] = zf0; zb[0] = zb0;
; #pragma unroll
;                     for (int jj = 1; jj < 8; ++jj) { zf[jj] = zf[jj - 1] * zfs; zb[jj] = zb[jj - 1] * zbs; }
;                     u32x4 wf, wb;
	s_setprio 0
	s_cbranch_scc0 .LBB0_613
	v_mov_b32_e32 v136, v169
	v_mov_b32_e32 v150, v168
	s_lshl_b32 s0, s33, 8
	global_load_dword v154, v137, s[22:23]
	global_load_dword v155, v137, s[22:23] offset:16
	s_or_b32 s0, s0, s53
	v_lshlrev_b32_e32 v151, 3, v136
	v_ashrrev_i32_e32 v136, 1, v150
	v_add_u32_e32 v162, s0, v151
	v_bfi_b32 v136, -4, v136, v150
	v_lshrrev_b32_e32 v146, 2, v162
	v_add_u32_e32 v192, 0x400, v136
	v_and_b32_e32 v187, 0x1f0, v146
	v_add_u32_e32 v146, v192, v187
	v_add_u32_e32 v148, v187, v136
	v_ashrrev_i32_e32 v147, 31, v146
	v_ashrrev_i32_e32 v149, 31, v148
	v_lshl_add_u64 v[146:147], v[146:147], 2, s[16:17]
	v_lshl_add_u64 v[148:149], v[148:149], 2, s[16:17]
	global_load_dword v153, v[146:147], off
	global_load_dword v166, v[148:149], off
	v_and_b32_e32 v157, 64, v174
	v_xor_b32_e32 v156, 4, v174
	v_add_u32_e32 v157, 64, v157
	v_cmp_lt_i32_e32 vcc, v156, v157
	v_mov_b32_e32 v152, v124
	v_add_u32_e32 v151, s53, v151
	v_cndmask_b32_e32 v156, v174, v156, vcc
	v_lshlrev_b32_e32 v177, 2, v156
	ds_bpermute_b32 v124, v177, v124
	v_sub_u32_e32 v156, 0x7f, v151
	v_add_u32_e32 v164, s52, v150
	v_and_b32_e32 v150, 4, v150
	v_cvt_f32_i32_e32 v179, v156
	v_cvt_f32_i32_e32 v178, v151
	v_cmp_eq_u32_e32 vcc, 0, v150
	ds_bpermute_b32 v157, v177, v125
	ds_bpermute_b32 v158, v177, v127
	s_waitcnt lgkmcnt(0)
	v_cndmask_b32_e64 v167, v124, -v124, vcc
	ds_bpermute_b32 v151, v177, v126
	v_ashrrev_i32_e32 v165, 31, v164
	v_and_b32_e32 v186, 56, v162
	s_waitcnt lgkmcnt(0)
	v_cndmask_b32_e64 v151, v151, -v151, vcc
	s_waitcnt vmcnt(0)
	v_mul_f32_e32 v124, 0x3fb8aa3b, v154
	v_mul_f32_e32 v150, 0x3fb8aa3b, v155
	v_cmp_lt_f32_e64 s[4:5], s60, v124
	v_mul_f32_e32 v156, v124, v179
	v_cmp_gt_f32_e64 s[6:7], s59, v150
	v_cndmask_b32_e64 v159, 0, v176, s[4:5]
	v_mul_f32_e32 v160, v150, v178
	v_cndmask_b32_e64 v161, 0, v176, s[6:7]
	v_cmp_gt_f32_e64 s[8:9], s59, v156
	v_fmac_f32_e32 v159, 0xbfb8aa3b, v154
	s_and_b64 s[0:1], s[4:5], exec
	v_cmp_gt_f32_e64 s[4:5], s59, v160
	v_fmac_f32_e32 v161, 0x3fb8aa3b, v155
	v_cndmask_b32_e64 v154, 0, v176, s[8:9]
	v_exp_f32_e32 v155, v159
	v_cndmask_b32_e64 v159, 0, v176, s[4:5]
	v_fmac_f32_e32 v154, v124, v179
	v_fmac_f32_e32 v159, v150, v178
	v_exp_f32_e32 v150, v154
	v_cndmask_b32_e64 v156, 0, v175, s[8:9]
	s_cselect_b32 s8, 0xffffffc0, 0
	v_exp_f32_e32 v161, v161
	v_exp_f32_e32 v159, v159
	v_ldexp_f32 v163, v155, s8
	v_pk_mul_f32 v[154:155], v[152:153], v[166:167]
	v_cndmask_b32_e64 v167, v157, -v157, vcc
	v_mov_b32_e32 v152, v125
	s_and_b64 s[0:1], s[6:7], exec
	v_add_f32_e32 v190, v154, v155
	v_pk_mul_f32 v[154:155], v[152:153], v[166:167]
	v_cndmask_b32_e64 v167, v158, -v158, vcc
	v_mov_b32_e32 v152, v127
	v_cndmask_b32_e64 v160, 0, v175, s[4:5]
	s_cselect_b32 s0, 0xffffffc0, 0
	v_ldexp_f32 v180, v150, v156
	v_add_f32_e32 v191, v154, v155
	v_pk_mul_f32 v[154:155], v[152:153], v[166:167]
	v_ldexp_f32 v124, v161, s0
	v_mul_f32_e32 v161, v126, v166
	v_ldexp_f32 v150, v159, v160
	v_mul_f32_e32 v181, v163, v180
	v_add_f32_e32 v193, v154, v155
	global_load_dword v188, v[148:149], off
	global_load_dword v157, v[146:147], off
	ds_bpermute_b32 v127, v177, v121
	v_mov_b32_e32 v156, v121
	ds_bpermute_b32 v121, v177, v123
	ds_bpermute_b32 v125, v177, v120
	ds_bpermute_b32 v152, v177, v122
	s_waitcnt lgkmcnt(3)
	v_cndmask_b32_e64 v189, v127, -v127, vcc
	s_waitcnt lgkmcnt(1)
	v_cndmask_b32_e64 v158, v125, -v125, vcc
	s_waitcnt lgkmcnt(0)
	v_cndmask_b32_e64 v127, v152, -v152, vcc
	s_waitcnt vmcnt(1)
	v_mul_f32_e32 v159, v120, v188
	s_waitcnt vmcnt(0)
	v_pk_mul_f32 v[154:155], v[156:157], v[188:189]
	v_cndmask_b32_e64 v189, v121, -v121, vcc
	v_mov_b32_e32 v156, v123
	v_add_f32_e32 v121, v154, v155
	v_pk_mul_f32 v[154:155], v[156:157], v[188:189]
	s_nop 0
	v_add_f32_e32 v123, v154, v155
	v_mov_b32_e32 v125, v153
	v_pk_mul_f32 v[152:153], v[124:125], v[150:151]
	v_mov_b32_e32 v125, v161
	v_pk_mul_f32 v[154:155], v[124:125], v[152:153]
	v_mov_b32_e32 v125, v157
	v_mov_b32_e32 v155, v158
	v_pk_mul_f32 v[156:157], v[124:125], v[154:155]
	v_mov_b32_e32 v158, v124
	v_pk_mul_f32 v[158:159], v[158:159], v[156:157]
	v_mul_f32_e32 v167, v163, v181
	v_mov_b32_e32 v159, v127
	v_mul_f32_e32 v183, v163, v167
	v_pk_mul_f32 v[160:161], v[124:125], v[158:159]
	v_mul_f32_e32 v182, v163, v183
	v_mul_f32_e32 v151, v124, v160
	v_mul_f32_e32 v185, v163, v182
	v_mul_f32_e32 v155, v124, v151
	v_mul_f32_e32 v124, v180, v190
	v_mul_f32_e32 v125, v181, v191
	v_fma_f32 v153, v126, v166, v153
	v_mul_f32_e32 v184, v163, v185
	v_cvt_pk_bf16_f32 v124, v124, v125
	v_mul_f32_e32 v125, v167, v153
	v_mul_f32_e32 v126, v183, v193
	v_fma_f32 v120, v120, v188, v157
	v_mul_f32_e32 v159, v163, v184
	v_cvt_pk_bf16_f32 v125, v125, v126
	v_mul_f32_e32 v126, v182, v120
	v_mul_f32_e32 v127, v185, v121
	v_fma_f32 v122, v122, v188, v161
	v_cvt_pk_bf16_f32 v126, v126, v127
	v_mul_f32_e32 v127, v184, v122
	v_mul_f32_e32 v157, v159, v123
	v_cvt_pk_bf16_f32 v127, v127, v157
	v_mul_f32_e32 v157, v150, v190
	v_mul_f32_e32 v120, v158, v120
	v_mul_f32_e32 v121, v160, v121
	v_mul_f32_e32 v161, v152, v191
	v_cvt_pk_bf16_f32 v188, v157, v161
	v_mul_f32_e32 v153, v154, v153
	v_mul_f32_e32 v157, v156, v193
	v_cvt_pk_bf16_f32 v189, v153, v157
	v_cvt_pk_bf16_f32 v190, v120, v121
	v_mul_f32_e32 v120, v151, v122
	v_mul_f32_e32 v121, v155, v123
	v_cvt_pk_bf16_f32 v191, v120, v121
	v_lshlrev_b64 v[120:121], 17, v[164:165]
	v_lshl_add_u64 v[120:121], s[80:81], 0, v[120:121]
	v_ashrrev_i32_e32 v163, 31, v162
	v_lshl_add_u64 v[120:121], v[162:163], 1, v[120:121]
	s_mov_b64 s[0:1], 0x2000000
	global_store_dwordx4 v[120:121], v[124:127], off
	s_nop 1
	v_lshl_add_u64 v[126:127], v[120:121], 0, s[0:1]
	s_brev_b32 s0, 64
	v_add_co_u32_e64 v122, s[4:5], s0, v120
	s_nop 1
	v_addc_co_u32_e64 v123, s[4:5], 0, v121, s[4:5]
	global_store_dwordx4 v[122:123], v[188:191], off
	v_add_u32_e32 v122, 0x80, v162
	v_lshrrev_b32_e32 v122, 2, v122
	v_and_b32_e32 v153, 0x1f0, v122
	v_add_u32_e32 v122, v153, v192
	v_add_u32_e32 v124, v153, v136
	v_ashrrev_i32_e32 v123, 31, v122
	v_ashrrev_i32_e32 v125, 31, v124
	v_lshl_add_u64 v[122:123], v[122:123], 2, s[16:17]
	v_lshl_add_u64 v[124:125], v[124:125], 2, s[16:17]
	global_load_dword v163, v[122:123], off
	global_load_dword v164, v[124:125], off
	ds_bpermute_b32 v157, v177, v116
	v_mov_b32_e32 v162, v116
	ds_bpermute_b32 v116, v177, v117
	ds_bpermute_b32 v161, v177, v118
	ds_bpermute_b32 v166, v177, v119
	s_waitcnt lgkmcnt(3)
;     __device__ __forceinline__ void operator()(const AccT& acc, const Unit& u, int wr, int wc, int fr, int fq) const {
;     ...
;                 const int r = rbase + ai * 128 + m * 16;
;                 const int d = 4 * (2 * m + (fr >> 3)) + j;
; #pragma unroll
;                 for (int bj = 0; bj < 2; ++bj) {
;                     const int t0 = tb + bj * 128;
;                     float v[8];
; #pragma unroll
;                     for (int jj = 0; jj < 4; ++jj) { v[jj] = acc[ai][bj][m][0][jj]; v[4 + jj] = acc[ai][bj][m][1][jj]; }
;                     if constexpr (ROPE) {
;                         const int t = t0 & 2047;
; #pragma unroll
;                         for (int hf = 0; hf < 2; ++hf) {
;                             f32x4 cs, sn;
;                             if (m < 2) { const float c1 = ropeA[(t >> 6) * 16 + d], s1 = ropeA[1024 + (t >> 6) * 16 + d]; cs = (f32x4){c1, c1, c1, c1}; sn = (f32x4){s1, s1, s1, s1}; }
;                             else { const float* cb = ropeA + 2048 + (d - 16) * 64 + (t & 63) + 4 * hf; cs = *(const f32x4*)(cb); sn = *(const f32x4*)(cb + 1024); }
; #pragma unroll
;                             for (int jj = 0; jj < 4; ++jj) { const float pr = __shfl_xor(v[4 * hf + jj], 4); v[4 * hf + jj] = v[4 * hf + jj] * cs[jj] + sgn * pr * sn[jj]; }
;                             __builtin_amdgcn_sched_barrier(0);
;                         }
;                     }
;                     float zf[8], zb[8]; zf[0] = zf0; zb[0] = zb0;
; #pragma unroll
;                     for (int jj = 1; jj < 8; ++jj) { zf[jj] = zf[jj - 1] * zfs; zb[jj] = zb[jj - 1] * zbs; }
;                     u32x4 wf, wb;
;                     wf.x = cvt_pk_bf16(v[0] * zf[0], v[1] * zf[1]); wf.y = cvt_pk_bf16(v[2] * zf[2], v[3] * zf[3]); wf.z = cvt_pk_bf16(v[4] * zf[4], v[5] * zf[5]); wf.w = cvt_pk_bf16(v[6] * zf[6], v[7] * zf[7]);
;                     wb.x = cvt_pk_bf16(v[0] * zb[0], v[1] * zb[1]); wb.y = cvt_pk_bf16(v[2] * zb[2], v[3] * zb[3]); wb.z = cvt_pk_bf16(v[4] * zb[4], v[5] * zb[5]); wb.w = cvt_pk_bf16(v[6] * zb[6], v[7] * zb[7]);
;                     *(u32x4*)(KTZ + (size_t)r * NT + t0) = wf;
;                     *(u32x4*)(KTZ + (size_t)(256 + r) * NT + t0) = wb;
;                     __builtin_amdgcn_sched_barrier(0);
	v_cndmask_b32_e64 v165, v157, -v157, vcc
	s_waitcnt vmcnt(0)
	v_pk_mul_f32 v[188:189], v[162:163], v[164:165]
	s_waitcnt lgkmcnt(2)
	v_cndmask_b32_e64 v165, v116, -v116, vcc
	v_mov_b32_e32 v162, v117
	v_pk_mul_f32 v[116:117], v[162:163], v[164:165]
	s_waitcnt lgkmcnt(1)
	v_cndmask_b32_e64 v165, v161, -v161, vcc
	v_mov_b32_e32 v162, v118
	v_add_f32_e32 v161, v116, v117
	v_pk_mul_f32 v[116:117], v[162:163], v[164:165]
	s_waitcnt lgkmcnt(0)
	v_cndmask_b32_e64 v165, v166, -v166, vcc
	v_mov_b32_e32 v162, v119
	v_add_f32_e32 v166, v116, v117
	v_pk_mul_f32 v[116:117], v[162:163], v[164:165]
	v_add_f32_e32 v157, v188, v189
	v_add_f32_e32 v164, v116, v117
	global_load_dword v117, v[122:123], off
	global_load_dword v118, v[124:125], off
	ds_bpermute_b32 v119, v177, v112
	v_mov_b32_e32 v116, v112
	ds_bpermute_b32 v112, v177, v113
	ds_bpermute_b32 v165, v177, v114
	ds_bpermute_b32 v188, v177, v115
	s_waitcnt lgkmcnt(3)
	v_cndmask_b32_e64 v119, v119, -v119, vcc
	s_waitcnt vmcnt(0)
	v_pk_mul_f32 v[162:163], v[116:117], v[118:119]
	s_waitcnt lgkmcnt(2)
	v_cndmask_b32_e64 v119, v112, -v112, vcc
	v_mov_b32_e32 v116, v113
	v_pk_mul_f32 v[112:113], v[116:117], v[118:119]
	s_waitcnt lgkmcnt(1)
	v_cndmask_b32_e64 v119, v165, -v165, vcc
	v_mov_b32_e32 v116, v114
	v_add_f32_e32 v162, v162, v163
	v_add_f32_e32 v163, v112, v113
	v_pk_mul_f32 v[112:113], v[116:117], v[118:119]
	s_waitcnt lgkmcnt(0)
	v_cndmask_b32_e64 v119, v188, -v188, vcc
	v_mov_b32_e32 v116, v115
	v_add_f32_e32 v165, v112, v113
	v_pk_mul_f32 v[112:113], v[116:117], v[118:119]
	s_nop 0
	v_add_f32_e32 v119, v112, v113
	v_mul_f32_e32 v112, v180, v157
	v_mul_f32_e32 v113, v181, v161
	v_cvt_pk_bf16_f32 v112, v112, v113
	v_mul_f32_e32 v113, v167, v166
	v_mul_f32_e32 v114, v183, v164
	v_cvt_pk_bf16_f32 v113, v113, v114
	v_mul_f32_e32 v114, v182, v162
	v_mul_f32_e32 v115, v185, v163
	v_cvt_pk_bf16_f32 v114, v114, v115
	v_mul_f32_e32 v115, v184, v165
	v_mul_f32_e32 v116, v159, v119
	v_cvt_pk_bf16_f32 v115, v115, v116
	v_mul_f32_e32 v116, v150, v157
	v_mul_f32_e32 v117, v152, v161
	v_cvt_pk_bf16_f32 v116, v116, v117
	v_mul_f32_e32 v117, v154, v166
	v_mul_f32_e32 v118, v156, v164
	v_cvt_pk_bf16_f32 v117, v117, v118
	v_mul_f32_e32 v118, v158, v162
	v_mul_f32_e32 v157, v160, v163
	v_mul_f32_e32 v119, v155, v119
	v_cvt_pk_bf16_f32 v118, v118, v157
	v_mul_f32_e32 v157, v151, v165
	v_cvt_pk_bf16_f32 v119, v157, v119
	global_store_dwordx4 v[120:121], v[112:115], off offset:256
	global_store_dwordx4 v[126:127], v[116:119], off offset:256
	v_add_u32_e32 v161, 0x408, v136
	v_add_u32_e32 v157, 8, v136
	v_add_u32_e32 v112, v161, v187
	v_add_u32_e32 v114, v187, v157
	v_ashrrev_i32_e32 v113, 31, v112
	v_ashrrev_i32_e32 v115, 31, v114
	v_lshl_add_u64 v[112:113], v[112:113], 2, s[16:17]
	v_lshl_add_u64 v[114:115], v[114:115], 2, s[16:17]
	global_load_dword v117, v[112:113], off
	global_load_dword v118, v[114:115], off
	ds_bpermute_b32 v119, v177, v108
	v_mov_b32_e32 v116, v108
	ds_bpermute_b32 v108, v177, v109
	ds_bpermute_b32 v162, v177, v110
	ds_bpermute_b32 v163, v177, v111
	s_waitcnt lgkmcnt(3)
	v_cndmask_b32_e64 v119, v119, -v119, vcc
	s_waitcnt vmcnt(0)
	v_pk_mul_f32 v[126:127], v[116:117], v[118:119]
	s_waitcnt lgkmcnt(2)
	v_cndmask_b32_e64 v119, v108, -v108, vcc
	v_mov_b32_e32 v116, v109
	v_pk_mul_f32 v[108:109], v[116:117], v[118:119]
	s_waitcnt lgkmcnt(1)
	v_cndmask_b32_e64 v119, v162, -v162, vcc
	v_mov_b32_e32 v116, v110
	v_add_f32_e32 v126, v126, v127
	v_add_f32_e32 v127, v108, v109
	v_pk_mul_f32 v[108:109], v[116:117], v[118:119]
	s_waitcnt lgkmcnt(0)
	v_cndmask_b32_e64 v119, v163, -v163, vcc
	v_mov_b32_e32 v116, v111
	v_add_f32_e32 v162, v108, v109
	v_pk_mul_f32 v[108:109], v[116:117], v[118:119]
	s_nop 0
	v_add_f32_e32 v118, v108, v109
	global_load_dword v109, v[112:113], off
	global_load_dword v110, v[114:115], off
	ds_bpermute_b32 v111, v177, v104
	v_mov_b32_e32 v108, v104
	ds_bpermute_b32 v104, v177, v105
	ds_bpermute_b32 v119, v177, v106
	ds_bpermute_b32 v163, v177, v107
	s_waitcnt lgkmcnt(3)
	v_cndmask_b32_e64 v111, v111, -v111, vcc
	s_waitcnt vmcnt(0)
	v_pk_mul_f32 v[116:117], v[108:109], v[110:111]
	s_waitcnt lgkmcnt(2)
	v_cndmask_b32_e64 v111, v104, -v104, vcc
	v_mov_b32_e32 v108, v105
	v_pk_mul_f32 v[104:105], v[108:109], v[110:111]
	s_waitcnt lgkmcnt(1)
	v_cndmask_b32_e64 v111, v119, -v119, vcc
	v_mov_b32_e32 v108, v106
	v_add_f32_e32 v119, v104, v105
	v_pk_mul_f32 v[104:105], v[108:109], v[110:111]
	s_waitcnt lgkmcnt(0)
	v_cndmask_b32_e64 v111, v163, -v163, vcc
	v_mov_b32_e32 v108, v107
	v_add_f32_e32 v163, v104, v105
	v_pk_mul_f32 v[104:105], v[108:109], v[110:111]
	v_add_f32_e32 v164, v116, v117
	v_add_f32_e32 v108, v104, v105
	v_mul_f32_e32 v104, v180, v126
	v_mul_f32_e32 v105, v181, v127
	v_cvt_pk_bf16_f32 v104, v104, v105
	v_mul_f32_e32 v105, v167, v162
	v_mul_f32_e32 v106, v183, v118
	v_cvt_pk_bf16_f32 v105, v105, v106
	v_mul_f32_e32 v106, v182, v164
	v_mul_f32_e32 v107, v185, v119
	v_cvt_pk_bf16_f32 v106, v106, v107
	v_mul_f32_e32 v107, v184, v163
	v_mul_f32_e32 v109, v159, v108
	v_cvt_pk_bf16_f32 v107, v107, v109
	v_mul_f32_e32 v109, v150, v126
	v_mul_f32_e32 v110, v152, v127
	v_cvt_pk_bf16_f32 v116, v109, v110
	v_mul_f32_e32 v109, v154, v162
	v_mul_f32_e32 v110, v156, v118
	v_cvt_pk_bf16_f32 v117, v109, v110
	v_mul_f32_e32 v109, v158, v164
	v_mul_f32_e32 v110, v160, v119
	v_cvt_pk_bf16_f32 v118, v109, v110
	v_mul_f32_e32 v109, v151, v163
	v_mul_f32_e32 v108, v155, v108
	s_mov_b64 s[0:1], 0x200000
	v_cvt_pk_bf16_f32 v119, v109, v108
	v_lshl_add_u64 v[108:109], v[120:121], 0, s[0:1]
	s_mov_b32 s0, 0x200000
	v_add_co_u32_e64 v110, s[4:5], s0, v120
	s_mov_b64 s[0:1], 0x2200000
	s_nop 0
	v_addc_co_u32_e64 v111, s[4:5], 0, v121, s[4:5]
	global_store_dwordx4 v[110:111], v[104:107], off
	v_lshl_add_u64 v[110:111], v[120:121], 0, s[0:1]
	s_mov_b32 s0, 0x2200000
	v_add_co_u32_e64 v104, s[4:5], s0, v120
	s_nop 1
	v_addc_co_u32_e64 v105, s[4:5], 0, v121, s[4:5]
	global_store_dwordx4 v[104:105], v[116:119], off
	v_add_u32_e32 v104, v153, v161
	v_add_u32_e32 v106, v153, v157
	v_ashrrev_i32_e32 v105, 31, v104
	v_ashrrev_i32_e32 v107, 31, v106
	v_lshl_add_u64 v[104:105], v[104:105], 2, s[16:17]
	v_lshl_add_u64 v[106:107], v[106:107], 2, s[16:17]
	global_load_dword v117, v[104:105], off
	global_load_dword v118, v[106:107], off
	ds_bpermute_b32 v119, v177, v100
	v_mov_b32_e32 v116, v100
	ds_bpermute_b32 v100, v177, v101
	ds_bpermute_b32 v153, v177, v102
	ds_bpermute_b32 v157, v177, v103
	s_waitcnt lgkmcnt(3)
; __device__ __forceinline__ unsigned cvt_pk_bf16(float lo, float hi) { unsigned r; asm volatile("v_cvt_pk_bf16_f32 %0, %1, %2" : "=v"(r) : "v"(lo), "v"(hi)); return r; }
;     __device__ __forceinline__ void operator()(const AccT& acc, const Unit& u, int wr, int wc, int fr, int fq) const {
;     ...
;                     const int t0 = tb + bj * 128;
;                     float v[8];
; #pragma unroll
;                     for (int jj = 0; jj < 4; ++jj) { v[jj] = acc[ai][bj][m][0][jj]; v[4 + jj] = acc[ai][bj][m][1][jj]; }
;                     if constexpr (ROPE) {
;                         const int t = t0 & 2047;
; #pragma unroll
;                         for (int hf = 0; hf < 2; ++hf) {
;                             f32x4 cs, sn;
;                             if (m < 2) { const float c1 = ropeA[(t >> 6) * 16 + d], s1 = ropeA[1024 + (t >> 6) * 16 + d]; cs = (f32x4){c1, c1, c1, c1}; sn = (f32x4){s1, s1, s1, s1}; }
;                             else { const float* cb = ropeA + 2048 + (d - 16) * 64 + (t & 63) + 4 * hf; cs = *(const f32x4*)(cb); sn = *(const f32x4*)(cb + 1024); }
; #pragma unroll
;                             for (int jj = 0; jj < 4; ++jj) { const float pr = __shfl_xor(v[4 * hf + jj], 4); v[4 * hf + jj] = v[4 * hf + jj] * cs[jj] + sgn * pr * sn[jj]; }
;                             __builtin_amdgcn_sched_barrier(0);
;                         }
;                     }
;                     float zf[8], zb[8]; zf[0] = zf0; zb[0] = zb0;
; #pragma unroll
;                     for (int jj = 1; jj < 8; ++jj) { zf[jj] = zf[jj - 1] * zfs; zb[jj] = zb[jj - 1] * zbs; }
;                     u32x4 wf, wb;
;                     wf.x = cvt_pk_bf16(v[0] * zf[0], v[1] * zf[1]); wf.y = cvt_pk_bf16(v[2] * zf[2], v[3] * zf[3]); wf.z = cvt_pk_bf16(v[4] * zf[4], v[5] * zf[5]); wf.w = cvt_pk_bf16(v[6] * zf[6], v[7] * zf[7]);
;                     wb.x = cvt_pk_bf16(v[0] * zb[0], v[1] * zb[1]); wb.y = cvt_pk_bf16(v[2] * zb[2], v[3] * zb[3]); wb.z = cvt_pk_bf16(v[4] * zb[4], v[5] * zb[5]); wb.w = cvt_pk_bf16(v[6] * zb[6], v[7] * zb[7]);
;                     *(u32x4*)(KTZ + (size_t)r * NT + t0) = wf;
;                     *(u32x4*)(KTZ + (size_t)(256 + r) * NT + t0) = wb;
;                     __builtin_amdgcn_sched_barrier(0);
	v_cndmask_b32_e64 v119, v119, -v119, vcc
	s_waitcnt vmcnt(0)
	v_pk_mul_f32 v[126:127], v[116:117], v[118:119]
	s_waitcnt lgkmcnt(2)
	v_cndmask_b32_e64 v119, v100, -v100, vcc
	v_mov_b32_e32 v116, v101
	v_pk_mul_f32 v[100:101], v[116:117], v[118:119]
	s_waitcnt lgkmcnt(1)
	v_cndmask_b32_e64 v119, v153, -v153, vcc
	v_mov_b32_e32 v116, v102
	v_add_f32_e32 v126, v126, v127
	v_add_f32_e32 v127, v100, v101
	v_pk_mul_f32 v[100:101], v[116:117], v[118:119]
	s_waitcnt lgkmcnt(0)
	v_cndmask_b32_e64 v119, v157, -v157, vcc
	v_mov_b32_e32 v116, v103
	v_add_f32_e32 v153, v100, v101
	v_pk_mul_f32 v[100:101], v[116:117], v[118:119]
	s_nop 0
	v_add_f32_e32 v118, v100, v101
	global_load_dword v101, v[104:105], off
	global_load_dword v102, v[106:107], off
	ds_bpermute_b32 v103, v177, v96
	v_mov_b32_e32 v100, v96
	ds_bpermute_b32 v96, v177, v97
	ds_bpermute_b32 v119, v177, v98
	ds_bpermute_b32 v157, v177, v99
	s_waitcnt lgkmcnt(3)
	v_cndmask_b32_e64 v103, v103, -v103, vcc
	s_waitcnt vmcnt(0)
	v_pk_mul_f32 v[116:117], v[100:101], v[102:103]
	s_waitcnt lgkmcnt(2)
	v_cndmask_b32_e64 v103, v96, -v96, vcc
	v_mov_b32_e32 v100, v97
	v_pk_mul_f32 v[96:97], v[100:101], v[102:103]
	s_waitcnt lgkmcnt(1)
	v_cndmask_b32_e64 v103, v119, -v119, vcc
	v_mov_b32_e32 v100, v98
	v_add_f32_e32 v116, v116, v117
	v_add_f32_e32 v117, v96, v97
	v_pk_mul_f32 v[96:97], v[100:101], v[102:103]
	s_waitcnt lgkmcnt(0)
	v_cndmask_b32_e64 v103, v157, -v157, vcc
	v_mov_b32_e32 v100, v99
	v_add_f32_e32 v119, v96, v97
	v_pk_mul_f32 v[96:97], v[100:101], v[102:103]
	s_nop 0
	v_add_f32_e32 v103, v96, v97
	v_mul_f32_e32 v96, v180, v126
	v_mul_f32_e32 v97, v181, v127
	v_cvt_pk_bf16_f32 v96, v96, v97
	v_mul_f32_e32 v97, v167, v153
	v_mul_f32_e32 v98, v183, v118
	v_cvt_pk_bf16_f32 v97, v97, v98
	v_mul_f32_e32 v98, v182, v116
	v_mul_f32_e32 v99, v185, v117
	v_cvt_pk_bf16_f32 v98, v98, v99
	v_mul_f32_e32 v99, v184, v119
	v_mul_f32_e32 v100, v159, v103
	v_cvt_pk_bf16_f32 v99, v99, v100
	v_mul_f32_e32 v100, v150, v126
	v_mul_f32_e32 v101, v152, v127
	v_cvt_pk_bf16_f32 v100, v100, v101
	v_mul_f32_e32 v101, v154, v153
	v_mul_f32_e32 v102, v156, v118
	v_cvt_pk_bf16_f32 v101, v101, v102
	v_mul_f32_e32 v102, v158, v116
	v_mul_f32_e32 v116, v160, v117
	v_mul_f32_e32 v103, v155, v103
	v_cvt_pk_bf16_f32 v102, v102, v116
	v_mul_f32_e32 v116, v151, v119
	v_cvt_pk_bf16_f32 v103, v116, v103
	global_store_dwordx4 v[108:109], v[96:99], off offset:256
	global_store_dwordx4 v[110:111], v[100:103], off offset:256
	s_nop 1
	v_lshlrev_b32_e32 v100, 6, v136
	v_ashrrev_i32_e32 v101, 31, v100
	v_lshlrev_b64 v[102:103], 2, v[100:101]
	v_lshl_add_u64 v[96:97], s[24:25], 0, v[102:103]
	v_lshlrev_b32_e32 v136, 2, v186
	v_lshl_add_u64 v[96:97], v[96:97], 0, v[136:137]
	v_add_co_u32_e64 v98, s[4:5], s61, v96
	ds_bpermute_b32 v101, v177, v92
	s_nop 0
	v_addc_co_u32_e64 v99, s[4:5], 0, v97, s[4:5]
	global_load_dwordx4 v[108:111], v[98:99], off
	global_load_dwordx4 v[116:119], v[96:97], off
	ds_bpermute_b32 v127, v177, v93
	ds_bpermute_b32 v153, v177, v94
	ds_bpermute_b32 v157, v177, v95
	v_mov_b32_e32 v126, v92
	v_mov_b32_e32 v92, v94
	s_waitcnt lgkmcnt(3)
	v_cndmask_b32_e64 v163, v101, -v101, vcc
	s_waitcnt lgkmcnt(2)
	v_cndmask_b32_e64 v165, v127, -v127, vcc
	s_waitcnt lgkmcnt(1)
	v_cndmask_b32_e64 v187, v153, -v153, vcc
	s_waitcnt lgkmcnt(0)
	v_cndmask_b32_e64 v189, v157, -v157, vcc
	s_waitcnt vmcnt(1)
	v_mov_b32_e32 v127, v108
	s_waitcnt vmcnt(0)
	v_mov_b32_e32 v162, v116
	v_mov_b32_e32 v108, v93
	v_mov_b32_e32 v164, v117
	v_mov_b32_e32 v93, v110
	v_mov_b32_e32 v186, v118
	v_mov_b32_e32 v110, v95
	v_mov_b32_e32 v188, v119
	v_pk_mul_f32 v[94:95], v[126:127], v[162:163]
	v_pk_mul_f32 v[108:109], v[108:109], v[164:165]
	v_pk_mul_f32 v[92:93], v[92:93], v[186:187]
	v_pk_mul_f32 v[110:111], v[110:111], v[188:189]
	v_add_f32_e32 v101, v94, v95
	v_add_f32_e32 v153, v108, v109
	v_add_f32_e32 v157, v92, v93
	v_add_f32_e32 v161, v110, v111
	v_lshl_add_u64 v[92:93], s[16:17], 0, v[102:103]
	v_lshl_add_u64 v[94:95], v[92:93], 0, v[136:137]
	v_add_co_u32_e64 v92, s[4:5], s62, v94
	ds_bpermute_b32 v103, v177, v88
	s_nop 0
	v_addc_co_u32_e64 v93, s[4:5], 0, v95, s[4:5]
	v_add_co_u32_e64 v94, s[4:5], s49, v94
	ds_bpermute_b32 v126, v177, v89
	s_nop 0
	v_addc_co_u32_e64 v95, s[4:5], 0, v95, s[4:5]
	global_load_dwordx4 v[108:111], v[92:93], off offset:16
	global_load_dwordx4 v[116:119], v[94:95], off offset:16
	ds_bpermute_b32 v162, v177, v90
	ds_bpermute_b32 v164, v177, v91
	v_mov_b32_e32 v102, v88
	v_mov_b32_e32 v88, v90
	s_waitcnt lgkmcnt(3)
	v_cndmask_b32_e64 v127, v103, -v103, vcc
	s_waitcnt lgkmcnt(2)
	v_cndmask_b32_e64 v163, v126, -v126, vcc
	s_waitcnt lgkmcnt(1)
	v_cndmask_b32_e64 v165, v162, -v162, vcc
	s_waitcnt lgkmcnt(0)
	v_cndmask_b32_e64 v187, v164, -v164, vcc
	s_waitcnt vmcnt(1)
	v_mov_b32_e32 v103, v108
	s_waitcnt vmcnt(0)
; __device__ __forceinline__ unsigned cvt_pk_bf16(float lo, float hi) { unsigned r; asm volatile("v_cvt_pk_bf16_f32 %0, %1, %2" : "=v"(r) : "v"(lo), "v"(hi)); return r; }
;     __device__ __forceinline__ void operator()(const AccT& acc, const Unit& u, int wr, int wc, int fr, int fq) const {
;     ...
;                     const int t0 = tb + bj * 128;
;                     float v[8];
; #pragma unroll
;                     for (int jj = 0; jj < 4; ++jj) { v[jj] = acc[ai][bj][m][0][jj]; v[4 + jj] = acc[ai][bj][m][1][jj]; }
;                     if constexpr (ROPE) {
;                         const int t = t0 & 2047;
; #pragma unroll
;                         for (int hf = 0; hf < 2; ++hf) {
;                             f32x4 cs, sn;
;                             if (m < 2) { const float c1 = ropeA[(t >> 6) * 16 + d], s1 = ropeA[1024 + (t >> 6) * 16 + d]; cs = (f32x4){c1, c1, c1, c1}; sn = (f32x4){s1, s1, s1, s1}; }
;                             else { const float* cb = ropeA + 2048 + (d - 16) * 64 + (t & 63) + 4 * hf; cs = *(const f32x4*)(cb); sn = *(const f32x4*)(cb + 1024); }
; #pragma unroll
;                             for (int jj = 0; jj < 4; ++jj) { const float pr = __shfl_xor(v[4 * hf + jj], 4); v[4 * hf + jj] = v[4 * hf + jj] * cs[jj] + sgn * pr * sn[jj]; }
;                             __builtin_amdgcn_sched_barrier(0);
;                         }
;                     }
;                     float zf[8], zb[8]; zf[0] = zf0; zb[0] = zb0;
; #pragma unroll
;                     for (int jj = 1; jj < 8; ++jj) { zf[jj] = zf[jj - 1] * zfs; zb[jj] = zb[jj - 1] * zbs; }
;                     u32x4 wf, wb;
;                     wf.x = cvt_pk_bf16(v[0] * zf[0], v[1] * zf[1]); wf.y = cvt_pk_bf16(v[2] * zf[2], v[3] * zf[3]); wf.z = cvt_pk_bf16(v[4] * zf[4], v[5] * zf[5]); wf.w = cvt_pk_bf16(v[6] * zf[6], v[7] * zf[7]);
;                     wb.x = cvt_pk_bf16(v[0] * zb[0], v[1] * zb[1]); wb.y = cvt_pk_bf16(v[2] * zb[2], v[3] * zb[3]); wb.z = cvt_pk_bf16(v[4] * zb[4], v[5] * zb[5]); wb.w = cvt_pk_bf16(v[6] * zb[6], v[7] * zb[7]);
;                     *(u32x4*)(KTZ + (size_t)r * NT + t0) = wf;
;                     *(u32x4*)(KTZ + (size_t)(256 + r) * NT + t0) = wb;
;                     __builtin_amdgcn_sched_barrier(0);
	v_mov_b32_e32 v126, v116
	v_mov_b32_e32 v108, v89
	v_mov_b32_e32 v162, v117
	v_mov_b32_e32 v89, v110
	v_mov_b32_e32 v164, v118
	v_mov_b32_e32 v110, v91
	v_mov_b32_e32 v186, v119
	v_pk_mul_f32 v[90:91], v[102:103], v[126:127]
	v_pk_mul_f32 v[102:103], v[108:109], v[162:163]
	v_pk_mul_f32 v[88:89], v[88:89], v[164:165]
	v_pk_mul_f32 v[108:109], v[110:111], v[186:187]
	v_add_f32_e32 v90, v90, v91
	v_add_f32_e32 v91, v102, v103
	v_add_f32_e32 v88, v88, v89
	v_add_f32_e32 v89, v108, v109
	v_mul_f32_e32 v102, v180, v101
	v_mul_f32_e32 v103, v181, v153
	v_cvt_pk_bf16_f32 v108, v102, v103
	v_mul_f32_e32 v102, v167, v157
	v_mul_f32_e32 v103, v183, v161
	v_cvt_pk_bf16_f32 v109, v102, v103
	v_mul_f32_e32 v102, v182, v90
	v_mul_f32_e32 v103, v185, v91
	v_cvt_pk_bf16_f32 v110, v102, v103
	v_mul_f32_e32 v102, v184, v88
	v_mul_f32_e32 v103, v159, v89
	v_cvt_pk_bf16_f32 v111, v102, v103
	v_mul_f32_e32 v101, v150, v101
	v_mul_f32_e32 v102, v152, v153
	v_mul_f32_e32 v88, v151, v88
	v_mul_f32_e32 v89, v155, v89
	s_mov_b64 s[0:1], 0x400000
	v_cvt_pk_bf16_f32 v116, v101, v102
	v_mul_f32_e32 v101, v154, v157
	v_mul_f32_e32 v102, v156, v161
	v_cvt_pk_bf16_f32 v117, v101, v102
	v_mul_f32_e32 v90, v158, v90
	v_mul_f32_e32 v91, v160, v91
	v_cvt_pk_bf16_f32 v118, v90, v91
	v_cvt_pk_bf16_f32 v119, v88, v89
	v_lshl_add_u64 v[88:89], v[120:121], 0, s[0:1]
	s_mov_b32 s0, 0x400000
	v_add_co_u32_e64 v90, s[4:5], s0, v120
	s_mov_b64 s[0:1], 0x2400000
	s_nop 0
	v_addc_co_u32_e64 v91, s[4:5], 0, v121, s[4:5]
	global_store_dwordx4 v[90:91], v[108:111], off
	v_lshl_add_u64 v[90:91], v[120:121], 0, s[0:1]
	s_mov_b32 s0, 0x2400000
	v_add_co_u32_e64 v102, s[4:5], s0, v120
	s_nop 1
	v_addc_co_u32_e64 v103, s[4:5], 0, v121, s[4:5]
	global_store_dwordx4 v[102:103], v[116:119], off
	global_load_dwordx4 v[108:111], v[98:99], off
	s_nop 0
	global_load_dwordx4 v[116:119], v[96:97], off
	ds_bpermute_b32 v101, v177, v84
	ds_bpermute_b32 v103, v177, v85
	ds_bpermute_b32 v126, v177, v86
	ds_bpermute_b32 v153, v177, v87
	v_mov_b32_e32 v102, v84
	v_mov_b32_e32 v84, v86
	s_waitcnt lgkmcnt(3)
	v_cndmask_b32_e64 v127, v101, -v101, vcc
	s_waitcnt lgkmcnt(2)
	v_cndmask_b32_e64 v163, v103, -v103, vcc
	s_waitcnt lgkmcnt(1)
	v_cndmask_b32_e64 v165, v126, -v126, vcc
	s_waitcnt lgkmcnt(0)
	v_cndmask_b32_e64 v187, v153, -v153, vcc
	s_waitcnt vmcnt(1)
	v_mov_b32_e32 v103, v108
	s_waitcnt vmcnt(0)
	v_mov_b32_e32 v126, v116
	v_mov_b32_e32 v108, v85
	v_mov_b32_e32 v162, v117
	v_mov_b32_e32 v85, v110
	v_mov_b32_e32 v164, v118
	v_mov_b32_e32 v110, v87
	v_mov_b32_e32 v186, v119
	v_pk_mul_f32 v[86:87], v[102:103], v[126:127]
	v_pk_mul_f32 v[102:103], v[108:109], v[162:163]
	v_pk_mul_f32 v[84:85], v[84:85], v[164:165]
	v_pk_mul_f32 v[108:109], v[110:111], v[186:187]
	v_add_f32_e32 v101, v86, v87
	v_add_f32_e32 v153, v102, v103
	v_add_f32_e32 v157, v84, v85
	v_add_f32_e32 v161, v108, v109
	global_load_dwordx4 v[84:87], v[92:93], off offset:16
	global_load_dwordx4 v[108:111], v[94:95], off offset:16
	ds_bpermute_b32 v103, v177, v80
	ds_bpermute_b32 v116, v177, v81
	ds_bpermute_b32 v118, v177, v82
	ds_bpermute_b32 v126, v177, v83
	v_mov_b32_e32 v102, v80
	v_mov_b32_e32 v80, v82
	s_waitcnt lgkmcnt(3)
	v_cndmask_b32_e64 v117, v103, -v103, vcc
	s_waitcnt lgkmcnt(2)
	v_cndmask_b32_e64 v119, v116, -v116, vcc
	s_waitcnt lgkmcnt(1)
	v_cndmask_b32_e64 v127, v118, -v118, vcc
	s_waitcnt lgkmcnt(0)
	v_cndmask_b32_e64 v163, v126, -v126, vcc
	s_waitcnt vmcnt(1)
	v_mov_b32_e32 v103, v84
	s_waitcnt vmcnt(0)
	v_mov_b32_e32 v116, v108
	v_mov_b32_e32 v84, v81
	v_mov_b32_e32 v118, v109
	v_mov_b32_e32 v81, v86
	v_mov_b32_e32 v126, v110
	v_mov_b32_e32 v86, v83
	v_mov_b32_e32 v162, v111
	v_pk_mul_f32 v[82:83], v[102:103], v[116:117]
	v_pk_mul_f32 v[84:85], v[84:85], v[118:119]
	v_pk_mul_f32 v[80:81], v[80:81], v[126:127]
	v_pk_mul_f32 v[86:87], v[86:87], v[162:163]
	v_add_f32_e32 v102, v82, v83
	v_add_f32_e32 v103, v84, v85
	v_add_f32_e32 v108, v80, v81
	v_add_f32_e32 v87, v86, v87
	v_mul_f32_e32 v80, v180, v101
	v_mul_f32_e32 v81, v181, v153
	v_cvt_pk_bf16_f32 v80, v80, v81
	v_mul_f32_e32 v81, v167, v157
	v_mul_f32_e32 v82, v183, v161
	v_cvt_pk_bf16_f32 v81, v81, v82
	v_mul_f32_e32 v82, v182, v102
	v_mul_f32_e32 v83, v185, v103
	v_cvt_pk_bf16_f32 v82, v82, v83
	v_mul_f32_e32 v83, v184, v108
	v_mul_f32_e32 v84, v159, v87
	v_cvt_pk_bf16_f32 v83, v83, v84
	v_mul_f32_e32 v84, v150, v101
	v_mul_f32_e32 v85, v152, v153
	v_cvt_pk_bf16_f32 v84, v84, v85
	v_mul_f32_e32 v85, v154, v157
	v_mul_f32_e32 v86, v156, v161
	v_cvt_pk_bf16_f32 v85, v85, v86
	v_mul_f32_e32 v86, v158, v102
	v_mul_f32_e32 v101, v160, v103
	v_mul_f32_e32 v87, v155, v87
	v_cvt_pk_bf16_f32 v86, v86, v101
	v_mul_f32_e32 v101, v151, v108
	v_cvt_pk_bf16_f32 v87, v101, v87
	global_store_dwordx4 v[88:89], v[80:83], off offset:256
	global_store_dwordx4 v[90:91], v[84:87], off offset:256
	s_nop 0
	v_add_u32_e32 v80, 0x200, v100
	v_ashrrev_i32_e32 v81, 31, v80
	v_lshl_add_u64 v[82:83], s[24:25], 0, v[136:137]
	v_lshlrev_b64 v[100:101], 2, v[80:81]
	v_lshl_add_u64 v[80:81], v[82:83], 0, v[100:101]
	v_add_co_u32_e64 v82, s[4:5], s61, v80
	ds_bpermute_b32 v103, v177, v76
	s_nop 0
	v_addc_co_u32_e64 v83, s[4:5], 0, v81, s[4:5]
	global_load_dwordx4 v[84:87], v[82:83], off
	global_load_dwordx4 v[88:91], v[80:81], off
	ds_bpermute_b32 v108, v177, v77
	ds_bpermute_b32 v110, v177, v78
	ds_bpermute_b32 v116, v177, v79
	v_mov_b32_e32 v102, v76
	v_mov_b32_e32 v76, v78
	s_waitcnt lgkmcnt(3)
	v_cndmask_b32_e64 v109, v103, -v103, vcc
	s_waitcnt lgkmcnt(2)
	v_cndmask_b32_e64 v111, v108, -v108, vcc
	s_waitcnt lgkmcnt(1)
	v_cndmask_b32_e64 v117, v110, -v110, vcc
	s_waitcnt lgkmcnt(0)
; __device__ __forceinline__ unsigned cvt_pk_bf16(float lo, float hi) { unsigned r; asm volatile("v_cvt_pk_bf16_f32 %0, %1, %2" : "=v"(r) : "v"(lo), "v"(hi)); return r; }
;     __device__ __forceinline__ void operator()(const AccT& acc, const Unit& u, int wr, int wc, int fr, int fq) const {
;     ...
;                     const int t0 = tb + bj * 128;
;                     float v[8];
; #pragma unroll
;                     for (int jj = 0; jj < 4; ++jj) { v[jj] = acc[ai][bj][m][0][jj]; v[4 + jj] = acc[ai][bj][m][1][jj]; }
;                     if constexpr (ROPE) {
;                         const int t = t0 & 2047;
; #pragma unroll
;                         for (int hf = 0; hf < 2; ++hf) {
;                             f32x4 cs, sn;
;                             if (m < 2) { const float c1 = ropeA[(t >> 6) * 16 + d], s1 = ropeA[1024 + (t >> 6) * 16 + d]; cs = (f32x4){c1, c1, c1, c1}; sn = (f32x4){s1, s1, s1, s1}; }
;                             else { const float* cb = ropeA + 2048 + (d - 16) * 64 + (t & 63) + 4 * hf; cs = *(const f32x4*)(cb); sn = *(const f32x4*)(cb + 1024); }
; #pragma unroll
;                             for (int jj = 0; jj < 4; ++jj) { const float pr = __shfl_xor(v[4 * hf + jj], 4); v[4 * hf + jj] = v[4 * hf + jj] * cs[jj] + sgn * pr * sn[jj]; }
;                             __builtin_amdgcn_sched_barrier(0);
;                         }
;                     }
;                     float zf[8], zb[8]; zf[0] = zf0; zb[0] = zb0;
; #pragma unroll
;                     for (int jj = 1; jj < 8; ++jj) { zf[jj] = zf[jj - 1] * zfs; zb[jj] = zb[jj - 1] * zbs; }
;                     u32x4 wf, wb;
;                     wf.x = cvt_pk_bf16(v[0] * zf[0], v[1] * zf[1]); wf.y = cvt_pk_bf16(v[2] * zf[2], v[3] * zf[3]); wf.z = cvt_pk_bf16(v[4] * zf[4], v[5] * zf[5]); wf.w = cvt_pk_bf16(v[6] * zf[6], v[7] * zf[7]);
;                     wb.x = cvt_pk_bf16(v[0] * zb[0], v[1] * zb[1]); wb.y = cvt_pk_bf16(v[2] * zb[2], v[3] * zb[3]); wb.z = cvt_pk_bf16(v[4] * zb[4], v[5] * zb[5]); wb.w = cvt_pk_bf16(v[6] * zb[6], v[7] * zb[7]);
;                     *(u32x4*)(KTZ + (size_t)r * NT + t0) = wf;
;                     *(u32x4*)(KTZ + (size_t)(256 + r) * NT + t0) = wb;
;                     __builtin_amdgcn_sched_barrier(0);
	v_cndmask_b32_e64 v119, v116, -v116, vcc
	s_waitcnt vmcnt(1)
	v_mov_b32_e32 v103, v84
	s_waitcnt vmcnt(0)
	v_mov_b32_e32 v108, v88
	v_mov_b32_e32 v84, v77
	v_mov_b32_e32 v110, v89
	v_mov_b32_e32 v77, v86
	v_mov_b32_e32 v116, v90
	v_mov_b32_e32 v86, v79
	v_mov_b32_e32 v118, v91
	v_pk_mul_f32 v[78:79], v[102:103], v[108:109]
	v_pk_mul_f32 v[84:85], v[84:85], v[110:111]
	v_pk_mul_f32 v[76:77], v[76:77], v[116:117]
	v_pk_mul_f32 v[86:87], v[86:87], v[118:119]
	v_add_f32_e32 v118, v78, v79
	v_add_f32_e32 v119, v84, v85
	v_add_f32_e32 v126, v76, v77
	v_add_f32_e32 v127, v86, v87
	v_lshl_add_u64 v[76:77], s[16:17], 0, v[100:101]
	v_lshl_add_u64 v[78:79], v[76:77], 0, v[136:137]
	v_add_co_u32_e64 v76, s[4:5], s62, v78
	ds_bpermute_b32 v101, v177, v72
	s_nop 0
	v_addc_co_u32_e64 v77, s[4:5], 0, v79, s[4:5]
	v_add_co_u32_e64 v78, s[4:5], s49, v78
	ds_bpermute_b32 v102, v177, v73
	s_nop 0
	v_addc_co_u32_e64 v79, s[4:5], 0, v79, s[4:5]
	global_load_dwordx4 v[84:87], v[76:77], off offset:16
	global_load_dwordx4 v[88:91], v[78:79], off offset:16
	ds_bpermute_b32 v108, v177, v74
	ds_bpermute_b32 v110, v177, v75
	v_mov_b32_e32 v100, v72
	v_mov_b32_e32 v72, v74
	s_waitcnt lgkmcnt(3)
	v_cndmask_b32_e64 v103, v101, -v101, vcc
	s_waitcnt lgkmcnt(2)
	v_cndmask_b32_e64 v109, v102, -v102, vcc
	s_waitcnt lgkmcnt(1)
	v_cndmask_b32_e64 v111, v108, -v108, vcc
	s_waitcnt lgkmcnt(0)
	v_cndmask_b32_e64 v117, v110, -v110, vcc
	s_waitcnt vmcnt(1)
	v_mov_b32_e32 v101, v84
	s_waitcnt vmcnt(0)
	v_mov_b32_e32 v102, v88
	v_mov_b32_e32 v84, v73
	v_mov_b32_e32 v108, v89
	v_mov_b32_e32 v73, v86
	v_mov_b32_e32 v110, v90
	v_mov_b32_e32 v86, v75
	v_mov_b32_e32 v116, v91
	v_pk_mul_f32 v[74:75], v[100:101], v[102:103]
	v_pk_mul_f32 v[84:85], v[84:85], v[108:109]
	v_pk_mul_f32 v[72:73], v[72:73], v[110:111]
	v_pk_mul_f32 v[86:87], v[86:87], v[116:117]
	v_add_f32_e32 v74, v74, v75
	v_add_f32_e32 v75, v84, v85
	v_add_f32_e32 v72, v72, v73
	v_add_f32_e32 v73, v86, v87
	v_mul_f32_e32 v84, v180, v118
	v_mul_f32_e32 v85, v181, v119
	v_cvt_pk_bf16_f32 v84, v84, v85
	v_mul_f32_e32 v85, v167, v126
	v_mul_f32_e32 v86, v183, v127
	v_cvt_pk_bf16_f32 v85, v85, v86
	v_mul_f32_e32 v86, v182, v74
	v_mul_f32_e32 v87, v185, v75
	v_cvt_pk_bf16_f32 v86, v86, v87
	v_mul_f32_e32 v87, v184, v72
	v_mul_f32_e32 v88, v159, v73
	v_cvt_pk_bf16_f32 v87, v87, v88
	v_mul_f32_e32 v88, v150, v118
	v_mul_f32_e32 v89, v152, v119
	v_cvt_pk_bf16_f32 v88, v88, v89
	v_mul_f32_e32 v89, v154, v126
	v_mul_f32_e32 v90, v156, v127
	v_mul_f32_e32 v72, v151, v72
	v_mul_f32_e32 v73, v155, v73
	s_mov_b64 s[0:1], 0x600000
	v_cvt_pk_bf16_f32 v89, v89, v90
	v_mul_f32_e32 v74, v158, v74
	v_mul_f32_e32 v75, v160, v75
	v_cvt_pk_bf16_f32 v90, v74, v75
	v_cvt_pk_bf16_f32 v91, v72, v73
	v_lshl_add_u64 v[72:73], v[120:121], 0, s[0:1]
	s_mov_b32 s0, 0x600000
	v_add_co_u32_e64 v74, s[4:5], s0, v120
	s_mov_b64 s[0:1], 0x2600000
	s_nop 0
	v_addc_co_u32_e64 v75, s[4:5], 0, v121, s[4:5]
	global_store_dwordx4 v[74:75], v[84:87], off
	v_lshl_add_u64 v[74:75], v[120:121], 0, s[0:1]
	s_mov_b32 s0, 0x2600000
	v_add_co_u32_e64 v84, s[4:5], s0, v120
	s_nop 1
	v_addc_co_u32_e64 v85, s[4:5], 0, v121, s[4:5]
	global_store_dwordx4 v[84:85], v[88:91], off
	global_load_dwordx4 v[84:87], v[82:83], off
	s_nop 0
	global_load_dwordx4 v[88:91], v[80:81], off
	ds_bpermute_b32 v101, v177, v68
	ds_bpermute_b32 v102, v177, v69
	ds_bpermute_b32 v108, v177, v70
	ds_bpermute_b32 v110, v177, v71
	v_mov_b32_e32 v100, v68
	v_mov_b32_e32 v68, v70
	s_waitcnt lgkmcnt(3)
	v_cndmask_b32_e64 v103, v101, -v101, vcc
	s_waitcnt lgkmcnt(2)
	v_cndmask_b32_e64 v109, v102, -v102, vcc
	s_waitcnt lgkmcnt(1)
	v_cndmask_b32_e64 v111, v108, -v108, vcc
	s_waitcnt lgkmcnt(0)
	v_cndmask_b32_e64 v117, v110, -v110, vcc
	s_waitcnt vmcnt(1)
	v_mov_b32_e32 v101, v84
	s_waitcnt vmcnt(0)
	v_mov_b32_e32 v102, v88
	v_mov_b32_e32 v84, v69
	v_mov_b32_e32 v108, v89
	v_mov_b32_e32 v69, v86
	v_mov_b32_e32 v110, v90
	v_mov_b32_e32 v86, v71
	v_mov_b32_e32 v116, v91
	v_pk_mul_f32 v[70:71], v[100:101], v[102:103]
	v_pk_mul_f32 v[84:85], v[84:85], v[108:109]
	v_pk_mul_f32 v[68:69], v[68:69], v[110:111]
	v_pk_mul_f32 v[86:87], v[86:87], v[116:117]
	v_add_f32_e32 v110, v70, v71
	v_add_f32_e32 v111, v84, v85
	v_add_f32_e32 v116, v68, v69
	v_add_f32_e32 v117, v86, v87
	global_load_dwordx4 v[68:71], v[76:77], off offset:16
	global_load_dwordx4 v[84:87], v[78:79], off offset:16
	ds_bpermute_b32 v89, v177, v64
	ds_bpermute_b32 v90, v177, v65
	ds_bpermute_b32 v100, v177, v66
	ds_bpermute_b32 v102, v177, v67
	v_mov_b32_e32 v88, v64
	v_mov_b32_e32 v64, v66
	s_waitcnt lgkmcnt(3)
	v_cndmask_b32_e64 v91, v89, -v89, vcc
	s_waitcnt lgkmcnt(2)
	v_cndmask_b32_e64 v101, v90, -v90, vcc
	s_waitcnt lgkmcnt(1)
	v_cndmask_b32_e64 v103, v100, -v100, vcc
	s_waitcnt lgkmcnt(0)
	v_cndmask_b32_e64 v109, v102, -v102, vcc
	s_waitcnt vmcnt(1)
	v_mov_b32_e32 v89, v68
	s_waitcnt vmcnt(0)
;     __device__ __forceinline__ void operator()(const AccT& acc, const Unit& u, int wr, int wc, int fr, int fq) const {
;     ...
;         for (int ai = 0; ai < 2; ++ai) {
;             const int hh = 2 * ai + wr;
;             const float l2f = lgd[hh] * 1.4426950408889634f, l2b = lgd[4 + hh] * 1.4426950408889634f;
;             const float zf0 = exp2f((float)(127 - o0) * l2f), zfs = exp2f(-l2f), zb0 = exp2f((float)o0 * l2b), zbs = exp2f(l2b);
; #pragma unroll
;             for (int m = 0; m < 4; ++m) {
;                 const int r = rbase + ai * 128 + m * 16;
;                 const int d = 4 * (2 * m + (fr >> 3)) + j;
; #pragma unroll
;                 for (int bj = 0; bj < 2; ++bj) {
;                     const int t0 = tb + bj * 128;
;                     float v[8];
; #pragma unroll
;                     for (int jj = 0; jj < 4; ++jj) { v[jj] = acc[ai][bj][m][0][jj]; v[4 + jj] = acc[ai][bj][m][1][jj]; }
;                     if constexpr (ROPE) {
;                         const int t = t0 & 2047;
; #pragma unroll
;                         for (int hf = 0; hf < 2; ++hf) {
;                             f32x4 cs, sn;
;                             if (m < 2) { const float c1 = ropeA[(t >> 6) * 16 + d], s1 = ropeA[1024 + (t >> 6) * 16 + d]; cs = (f32x4){c1, c1, c1, c1}; sn = (f32x4){s1, s1, s1, s1}; }
;                             else { const float* cb = ropeA + 2048 + (d - 16) * 64 + (t & 63) + 4 * hf; cs = *(const f32x4*)(cb); sn = *(const f32x4*)(cb + 1024); }
; #pragma unroll
;                             for (int jj = 0; jj < 4; ++jj) { const float pr = __shfl_xor(v[4 * hf + jj], 4); v[4 * hf + jj] = v[4 * hf + jj] * cs[jj] + sgn * pr * sn[jj]; }
;                             __builtin_amdgcn_sched_barrier(0);
;                         }
;                     }
;                     float zf[8], zb[8]; zf[0] = zf0; zb[0] = zb0;
; #pragma unroll
;                     for (int jj = 1; jj < 8; ++jj) { zf[jj] = zf[jj - 1] * zfs; zb[jj] = zb[jj - 1] * zbs; }
;                     u32x4 wf, wb;
;                     wf.x = cvt_pk_bf16(v[0] * zf[0], v[1] * zf[1]); wf.y = cvt_pk_bf16(v[2] * zf[2], v[3] * zf[3]); wf.z = cvt_pk_bf16(v[4] * zf[4], v[5] * zf[5]); wf.w = cvt_pk_bf16(v[6] * zf[6], v[7] * zf[7]);
	v_mov_b32_e32 v90, v84
	v_mov_b32_e32 v68, v65
	v_mov_b32_e32 v100, v85
	v_mov_b32_e32 v65, v70
	v_mov_b32_e32 v102, v86
	v_mov_b32_e32 v70, v67
	v_mov_b32_e32 v108, v87
	v_pk_mul_f32 v[66:67], v[88:89], v[90:91]
	v_pk_mul_f32 v[68:69], v[68:69], v[100:101]
	v_pk_mul_f32 v[64:65], v[64:65], v[102:103]
	v_pk_mul_f32 v[70:71], v[70:71], v[108:109]
	v_add_f32_e32 v84, v66, v67
	v_add_f32_e32 v85, v68, v69
	v_add_f32_e32 v86, v64, v65
	v_add_f32_e32 v71, v70, v71
	v_mul_f32_e32 v64, v180, v110
	v_mul_f32_e32 v65, v181, v111
	v_cvt_pk_bf16_f32 v64, v64, v65
	v_mul_f32_e32 v65, v167, v116
	v_mul_f32_e32 v66, v183, v117
	v_cvt_pk_bf16_f32 v65, v65, v66
	v_mul_f32_e32 v66, v182, v84
	v_mul_f32_e32 v67, v185, v85
	v_cvt_pk_bf16_f32 v66, v66, v67
	v_mul_f32_e32 v67, v184, v86
	v_mul_f32_e32 v68, v159, v71
	v_cvt_pk_bf16_f32 v67, v67, v68
	v_mul_f32_e32 v68, v150, v110
	v_mul_f32_e32 v69, v152, v111
	v_cvt_pk_bf16_f32 v68, v68, v69
	v_mul_f32_e32 v69, v154, v116
	v_mul_f32_e32 v70, v156, v117
	v_cvt_pk_bf16_f32 v69, v69, v70
	v_mul_f32_e32 v70, v158, v84
	v_mul_f32_e32 v84, v160, v85
	v_mul_f32_e32 v71, v155, v71
	v_cvt_pk_bf16_f32 v70, v70, v84
	v_mul_f32_e32 v84, v151, v86
	v_cvt_pk_bf16_f32 v71, v84, v71
	global_store_dwordx4 v[72:73], v[64:67], off offset:256
	global_store_dwordx4 v[74:75], v[68:71], off offset:256
	global_load_dword v64, v137, s[22:23] offset:8
	s_nop 0
	global_load_dword v70, v137, s[22:23] offset:24
	global_load_dword v67, v[146:147], off
	global_load_dword v74, v[148:149], off
	ds_bpermute_b32 v65, v177, v60
	ds_bpermute_b32 v68, v177, v62
	v_mov_b32_e32 v66, v60
	ds_bpermute_b32 v60, v177, v61
	ds_bpermute_b32 v71, v177, v63
	s_waitcnt lgkmcnt(3)
	v_cndmask_b32_e64 v75, v65, -v65, vcc
	s_waitcnt lgkmcnt(2)
	v_cndmask_b32_e64 v65, v68, -v68, vcc
	s_waitcnt vmcnt(3)
	v_mul_f32_e32 v72, 0x3fb8aa3b, v64
	s_waitcnt vmcnt(2)
	v_mul_f32_e32 v73, 0x3fb8aa3b, v70
	v_mul_f32_e32 v84, v72, v179
	s_waitcnt vmcnt(0)
	v_pk_mul_f32 v[68:69], v[66:67], v[74:75]
	s_waitcnt lgkmcnt(1)
	v_cndmask_b32_e64 v75, v60, -v60, vcc
	v_mov_b32_e32 v66, v61
	v_cmp_lt_f32_e64 s[4:5], s60, v72
	v_mul_f32_e32 v87, v73, v178
	v_pk_mul_f32 v[60:61], v[66:67], v[74:75]
	s_waitcnt lgkmcnt(0)
	v_cndmask_b32_e64 v75, v71, -v71, vcc
	v_mov_b32_e32 v66, v63
	v_cmp_gt_f32_e64 s[8:9], s59, v84
	v_cndmask_b32_e64 v86, 0, v176, s[4:5]
	v_cmp_gt_f32_e64 s[6:7], s59, v73
	s_and_b64 s[0:1], s[4:5], exec
	v_cmp_gt_f32_e64 s[4:5], s59, v87
	v_add_f32_e32 v110, v60, v61
	v_pk_mul_f32 v[60:61], v[66:67], v[74:75]
	v_cndmask_b32_e64 v66, 0, v176, s[8:9]
	v_cndmask_b32_e64 v88, 0, v176, s[6:7]
	v_add_f32_e32 v89, v68, v69
	v_fmac_f32_e32 v86, 0xbfb8aa3b, v64
	v_cndmask_b32_e64 v69, 0, v176, s[4:5]
	v_fmac_f32_e32 v66, v72, v179
	v_fmac_f32_e32 v88, 0x3fb8aa3b, v70
	v_exp_f32_e32 v68, v86
	v_fmac_f32_e32 v69, v73, v178
	v_exp_f32_e32 v66, v66
	v_exp_f32_e32 v70, v88
	v_exp_f32_e32 v69, v69
	v_cndmask_b32_e64 v63, 0, v175, s[8:9]
	s_cselect_b32 s8, 0xffffffc0, 0
	s_and_b64 s[0:1], s[6:7], exec
	v_cndmask_b32_e64 v64, 0, v175, s[4:5]
	s_cselect_b32 s0, 0xffffffc0, 0
	v_ldexp_f32 v100, v68, s8
	v_ldexp_f32 v63, v66, v63
	v_mul_f32_e32 v85, v62, v74
	v_ldexp_f32 v90, v70, s0
	v_ldexp_f32 v64, v69, v64
	v_mul_f32_e32 v75, v100, v63
	v_add_f32_e32 v111, v60, v61
	global_load_dword v108, v[148:149], off
	global_load_dword v69, v[146:147], off
	ds_bpermute_b32 v61, v177, v57
	ds_bpermute_b32 v60, v177, v56
	v_mov_b32_e32 v68, v57
	ds_bpermute_b32 v57, v177, v59
	ds_bpermute_b32 v66, v177, v58
	s_waitcnt lgkmcnt(3)
	v_cndmask_b32_e64 v109, v61, -v61, vcc
	s_waitcnt lgkmcnt(2)
	v_cndmask_b32_e64 v70, v60, -v60, vcc
	s_waitcnt lgkmcnt(0)
	v_cndmask_b32_e64 v72, v66, -v66, vcc
	s_waitcnt vmcnt(1)
	v_mul_f32_e32 v71, v56, v108
	s_waitcnt vmcnt(0)
	v_pk_mul_f32 v[60:61], v[68:69], v[108:109]
	v_cndmask_b32_e64 v109, v57, -v57, vcc
	v_mov_b32_e32 v68, v59
	v_add_f32_e32 v57, v60, v61
	v_pk_mul_f32 v[60:61], v[68:69], v[108:109]
	s_nop 0
	v_add_f32_e32 v59, v60, v61
	v_mov_b32_e32 v91, v67
	v_pk_mul_f32 v[60:61], v[90:91], v[64:65]
	v_mov_b32_e32 v91, v85
	v_pk_mul_f32 v[66:67], v[90:91], v[60:61]
	v_mov_b32_e32 v91, v69
	v_mov_b32_e32 v67, v70
	v_mul_f32_e32 v84, v100, v75
	v_pk_mul_f32 v[68:69], v[90:91], v[66:67]
	v_mov_b32_e32 v70, v90
	v_mul_f32_e32 v86, v100, v84
	v_pk_mul_f32 v[70:71], v[70:71], v[68:69]
	v_mul_f32_e32 v85, v100, v86
	v_mov_b32_e32 v71, v72
	v_mul_f32_e32 v88, v100, v85
	v_pk_mul_f32 v[72:73], v[90:91], v[70:71]
	v_fma_f32 v61, v62, v74, v61
	v_mul_f32_e32 v87, v100, v88
	v_mul_f32_e32 v65, v90, v72
	v_mul_f32_e32 v62, v84, v61
	v_fma_f32 v56, v56, v108, v69
	v_mul_f32_e32 v71, v100, v87
	v_mul_f32_e32 v67, v90, v65
	v_mul_f32_e32 v90, v63, v89
	v_mul_f32_e32 v91, v75, v110
	v_cvt_pk_bf16_f32 v100, v90, v91
	v_mul_f32_e32 v74, v86, v111
	v_cvt_pk_bf16_f32 v101, v62, v74
	v_mul_f32_e32 v62, v85, v56
	v_fma_f32 v58, v58, v108, v73
	v_mul_f32_e32 v69, v88, v57
	v_cvt_pk_bf16_f32 v102, v62, v69
	v_mul_f32_e32 v62, v87, v58
	v_mul_f32_e32 v69, v71, v59
	v_cvt_pk_bf16_f32 v103, v62, v69
	v_mul_f32_e32 v62, v64, v89
	v_mul_f32_e32 v56, v70, v56
	v_mul_f32_e32 v57, v72, v57
	v_mul_f32_e32 v69, v60, v110
	v_cvt_pk_bf16_f32 v108, v62, v69
	v_mul_f32_e32 v61, v66, v61
	v_mul_f32_e32 v62, v68, v111
	v_cvt_pk_bf16_f32 v109, v61, v62
	v_cvt_pk_bf16_f32 v110, v56, v57
	v_mul_f32_e32 v56, v65, v58
	v_mul_f32_e32 v57, v67, v59
	s_mov_b64 s[0:1], 0x1000000
	v_cvt_pk_bf16_f32 v111, v56, v57
	v_lshl_add_u64 v[56:57], v[120:121], 0, s[0:1]
	s_mov_b32 s0, 0x1000000
	v_add_co_u32_e64 v58, s[4:5], s0, v120
	s_mov_b64 s[0:1], 0x3000000
	s_nop 0
	v_addc_co_u32_e64 v59, s[4:5], 0, v121, s[4:5]
	global_store_dwordx4 v[58:59], v[100:103], off
	v_lshl_add_u64 v[58:59], v[120:121], 0, s[0:1]
	s_mov_b32 s0, 0x3000000
	v_add_co_u32_e64 v90, s[4:5], s0, v120
	s_nop 1
	v_addc_co_u32_e64 v91, s[4:5], 0, v121, s[4:5]
	global_store_dwordx4 v[90:91], v[108:111], off
	global_load_dword v91, v[122:123], off
	s_nop 0
	global_load_dword v100, v[124:125], off
	ds_bpermute_b32 v61, v177, v52
	v_mov_b32_e32 v90, v52
	ds_bpermute_b32 v52, v177, v53
	ds_bpermute_b32 v62, v177, v54
	ds_bpermute_b32 v69, v177, v55
	s_waitcnt lgkmcnt(3)
; __device__ __forceinline__ unsigned cvt_pk_bf16(float lo, float hi) { unsigned r; asm volatile("v_cvt_pk_bf16_f32 %0, %1, %2" : "=v"(r) : "v"(lo), "v"(hi)); return r; }
;     __device__ __forceinline__ void operator()(const AccT& acc, const Unit& u, int wr, int wc, int fr, int fq) const {
;     ...
;                         const int t = t0 & 2047;
; #pragma unroll
;                         for (int hf = 0; hf < 2; ++hf) {
;                             f32x4 cs, sn;
;                             if (m < 2) { const float c1 = ropeA[(t >> 6) * 16 + d], s1 = ropeA[1024 + (t >> 6) * 16 + d]; cs = (f32x4){c1, c1, c1, c1}; sn = (f32x4){s1, s1, s1, s1}; }
;                             else { const float* cb = ropeA + 2048 + (d - 16) * 64 + (t & 63) + 4 * hf; cs = *(const f32x4*)(cb); sn = *(const f32x4*)(cb + 1024); }
; #pragma unroll
;                             for (int jj = 0; jj < 4; ++jj) { const float pr = __shfl_xor(v[4 * hf + jj], 4); v[4 * hf + jj] = v[4 * hf + jj] * cs[jj] + sgn * pr * sn[jj]; }
;                             __builtin_amdgcn_sched_barrier(0);
;                         }
;                     }
;                     float zf[8], zb[8]; zf[0] = zf0; zb[0] = zb0;
; #pragma unroll
;                     for (int jj = 1; jj < 8; ++jj) { zf[jj] = zf[jj - 1] * zfs; zb[jj] = zb[jj - 1] * zbs; }
;                     u32x4 wf, wb;
;                     wf.x = cvt_pk_bf16(v[0] * zf[0], v[1] * zf[1]); wf.y = cvt_pk_bf16(v[2] * zf[2], v[3] * zf[3]); wf.z = cvt_pk_bf16(v[4] * zf[4], v[5] * zf[5]); wf.w = cvt_pk_bf16(v[6] * zf[6], v[7] * zf[7]);
;                     wb.x = cvt_pk_bf16(v[0] * zb[0], v[1] * zb[1]); wb.y = cvt_pk_bf16(v[2] * zb[2], v[3] * zb[3]); wb.z = cvt_pk_bf16(v[4] * zb[4], v[5] * zb[5]); wb.w = cvt_pk_bf16(v[6] * zb[6], v[7] * zb[7]);
;                     *(u32x4*)(KTZ + (size_t)r * NT + t0) = wf;
;                     *(u32x4*)(KTZ + (size_t)(256 + r) * NT + t0) = wb;
	v_cndmask_b32_e64 v101, v61, -v61, vcc
	s_waitcnt vmcnt(0)
	v_pk_mul_f32 v[102:103], v[90:91], v[100:101]
	s_waitcnt lgkmcnt(2)
	v_cndmask_b32_e64 v101, v52, -v52, vcc
	v_mov_b32_e32 v90, v53
	v_pk_mul_f32 v[52:53], v[90:91], v[100:101]
	s_waitcnt lgkmcnt(1)
	v_cndmask_b32_e64 v101, v62, -v62, vcc
	v_mov_b32_e32 v90, v54
	v_add_f32_e32 v62, v52, v53
	v_pk_mul_f32 v[52:53], v[90:91], v[100:101]
	s_waitcnt lgkmcnt(0)
	v_cndmask_b32_e64 v101, v69, -v69, vcc
	v_mov_b32_e32 v90, v55
	v_add_f32_e32 v69, v52, v53
	v_pk_mul_f32 v[52:53], v[90:91], v[100:101]
	v_add_f32_e32 v61, v102, v103
	v_add_f32_e32 v73, v52, v53
	global_load_dword v53, v[122:123], off
	global_load_dword v54, v[124:125], off
	ds_bpermute_b32 v55, v177, v48
	v_mov_b32_e32 v52, v48
	ds_bpermute_b32 v48, v177, v49
	ds_bpermute_b32 v74, v177, v50
	ds_bpermute_b32 v89, v177, v51
	s_waitcnt lgkmcnt(3)
	v_cndmask_b32_e64 v55, v55, -v55, vcc
	s_waitcnt vmcnt(0)
	v_pk_mul_f32 v[90:91], v[52:53], v[54:55]
	s_waitcnt lgkmcnt(2)
	v_cndmask_b32_e64 v55, v48, -v48, vcc
	v_mov_b32_e32 v52, v49
	v_pk_mul_f32 v[48:49], v[52:53], v[54:55]
	s_waitcnt lgkmcnt(1)
	v_cndmask_b32_e64 v55, v74, -v74, vcc
	v_mov_b32_e32 v52, v50
	v_add_f32_e32 v74, v48, v49
	v_pk_mul_f32 v[48:49], v[52:53], v[54:55]
	s_waitcnt lgkmcnt(0)
	v_cndmask_b32_e64 v55, v89, -v89, vcc
	v_mov_b32_e32 v52, v51
	v_add_f32_e32 v89, v48, v49
	v_pk_mul_f32 v[48:49], v[52:53], v[54:55]
	v_add_f32_e32 v90, v90, v91
	v_add_f32_e32 v55, v48, v49
	v_mul_f32_e32 v48, v63, v61
	v_mul_f32_e32 v49, v75, v62
	v_cvt_pk_bf16_f32 v48, v48, v49
	v_mul_f32_e32 v49, v84, v69
	v_mul_f32_e32 v50, v86, v73
	v_cvt_pk_bf16_f32 v49, v49, v50
	v_mul_f32_e32 v50, v85, v90
	v_mul_f32_e32 v51, v88, v74
	v_cvt_pk_bf16_f32 v50, v50, v51
	v_mul_f32_e32 v51, v87, v89
	v_mul_f32_e32 v52, v71, v55
	v_cvt_pk_bf16_f32 v51, v51, v52
	v_mul_f32_e32 v52, v64, v61
	v_mul_f32_e32 v53, v60, v62
	v_cvt_pk_bf16_f32 v52, v52, v53
	v_mul_f32_e32 v53, v66, v69
	v_mul_f32_e32 v54, v68, v73
	v_cvt_pk_bf16_f32 v53, v53, v54
	v_mul_f32_e32 v54, v70, v90
	v_mul_f32_e32 v61, v72, v74
	v_mul_f32_e32 v55, v67, v55
	v_cvt_pk_bf16_f32 v54, v54, v61
	v_mul_f32_e32 v61, v65, v89
	v_cvt_pk_bf16_f32 v55, v61, v55
	global_store_dwordx4 v[56:57], v[48:51], off offset:256
	global_store_dwordx4 v[58:59], v[52:55], off offset:256
	global_load_dword v49, v[112:113], off
	s_nop 0
	global_load_dword v50, v[114:115], off
	ds_bpermute_b32 v51, v177, v44
	v_mov_b32_e32 v48, v44
	ds_bpermute_b32 v44, v177, v45
	ds_bpermute_b32 v54, v177, v46
	ds_bpermute_b32 v55, v177, v47
	s_waitcnt lgkmcnt(3)
	v_cndmask_b32_e64 v51, v51, -v51, vcc
	s_waitcnt vmcnt(0)
	v_pk_mul_f32 v[52:53], v[48:49], v[50:51]
	s_waitcnt lgkmcnt(2)
	v_cndmask_b32_e64 v51, v44, -v44, vcc
	v_mov_b32_e32 v48, v45
	v_pk_mul_f32 v[44:45], v[48:49], v[50:51]
	s_waitcnt lgkmcnt(1)
	v_cndmask_b32_e64 v51, v54, -v54, vcc
	v_mov_b32_e32 v48, v46
	v_add_f32_e32 v52, v52, v53
	v_add_f32_e32 v53, v44, v45
	v_pk_mul_f32 v[44:45], v[48:49], v[50:51]
	s_waitcnt lgkmcnt(0)
	v_cndmask_b32_e64 v51, v55, -v55, vcc
	v_mov_b32_e32 v48, v47
	v_add_f32_e32 v54, v44, v45
	v_pk_mul_f32 v[44:45], v[48:49], v[50:51]
	s_nop 0
	v_add_f32_e32 v50, v44, v45
	global_load_dword v45, v[112:113], off
	global_load_dword v46, v[114:115], off
	ds_bpermute_b32 v47, v177, v40
	v_mov_b32_e32 v44, v40
	ds_bpermute_b32 v40, v177, v41
	ds_bpermute_b32 v51, v177, v42
	ds_bpermute_b32 v55, v177, v43
	s_waitcnt lgkmcnt(3)
	v_cndmask_b32_e64 v47, v47, -v47, vcc
	s_waitcnt vmcnt(0)
	v_pk_mul_f32 v[48:49], v[44:45], v[46:47]
	s_waitcnt lgkmcnt(2)
	v_cndmask_b32_e64 v47, v40, -v40, vcc
	v_mov_b32_e32 v44, v41
	v_pk_mul_f32 v[40:41], v[44:45], v[46:47]
	s_waitcnt lgkmcnt(1)
	v_cndmask_b32_e64 v47, v51, -v51, vcc
	v_mov_b32_e32 v44, v42
	v_add_f32_e32 v48, v48, v49
	v_add_f32_e32 v49, v40, v41
	v_pk_mul_f32 v[40:41], v[44:45], v[46:47]
	s_waitcnt lgkmcnt(0)
	v_cndmask_b32_e64 v47, v55, -v55, vcc
	v_mov_b32_e32 v44, v43
	v_add_f32_e32 v51, v40, v41
	v_pk_mul_f32 v[40:41], v[44:45], v[46:47]
	s_nop 0
	v_add_f32_e32 v40, v40, v41
	v_mul_f32_e32 v41, v63, v52
	v_mul_f32_e32 v42, v75, v53
	v_cvt_pk_bf16_f32 v42, v41, v42
	v_mul_f32_e32 v41, v84, v54
	v_mul_f32_e32 v43, v86, v50
	v_cvt_pk_bf16_f32 v43, v41, v43
	v_mul_f32_e32 v41, v85, v48
	v_mul_f32_e32 v44, v88, v49
	v_cvt_pk_bf16_f32 v44, v41, v44
	v_mul_f32_e32 v41, v87, v51
	v_mul_f32_e32 v45, v71, v40
	v_cvt_pk_bf16_f32 v45, v41, v45
	v_mul_f32_e32 v41, v64, v52
	v_mul_f32_e32 v46, v60, v53
	v_cvt_pk_bf16_f32 v46, v41, v46
	v_mul_f32_e32 v41, v66, v54
	v_mul_f32_e32 v47, v68, v50
	v_cvt_pk_bf16_f32 v47, v41, v47
	v_mul_f32_e32 v41, v70, v48
	v_mul_f32_e32 v48, v72, v49
	v_cvt_pk_bf16_f32 v48, v41, v48
	v_mul_f32_e32 v41, v65, v51
	v_mul_f32_e32 v40, v67, v40
	s_mov_b64 s[0:1], 0x1200000
	v_cvt_pk_bf16_f32 v49, v41, v40
	v_lshl_add_u64 v[40:41], v[120:121], 0, s[0:1]
	s_mov_b32 s0, 0x1200000
	v_add_co_u32_e64 v50, s[4:5], s0, v120
	s_mov_b64 s[0:1], 0x3200000
	s_nop 0
	v_addc_co_u32_e64 v51, s[4:5], 0, v121, s[4:5]
	global_store_dwordx4 v[50:51], v[42:45], off
	s_nop 1
	v_lshl_add_u64 v[42:43], v[120:121], 0, s[0:1]
	s_mov_b32 s0, 0x3200000
	v_add_co_u32_e64 v44, s[4:5], s0, v120
	s_nop 1
	v_addc_co_u32_e64 v45, s[4:5], 0, v121, s[4:5]
	global_store_dwordx4 v[44:45], v[46:49], off
	global_load_dword v45, v[104:105], off
	s_nop 0
	global_load_dword v46, v[106:107], off
	ds_bpermute_b32 v47, v177, v36
	v_mov_b32_e32 v44, v36
	ds_bpermute_b32 v36, v177, v37
	ds_bpermute_b32 v50, v177, v38
	ds_bpermute_b32 v51, v177, v39
	s_waitcnt lgkmcnt(3)
	v_cndmask_b32_e64 v47, v47, -v47, vcc
	s_waitcnt vmcnt(0)
	v_pk_mul_f32 v[48:49], v[44:45], v[46:47]
	s_waitcnt lgkmcnt(2)
; __device__ __forceinline__ unsigned cvt_pk_bf16(float lo, float hi) { unsigned r; asm volatile("v_cvt_pk_bf16_f32 %0, %1, %2" : "=v"(r) : "v"(lo), "v"(hi)); return r; }
;     __device__ __forceinline__ void operator()(const AccT& acc, const Unit& u, int wr, int wc, int fr, int fq) const {
;     ...
;                         const int t = t0 & 2047;
; #pragma unroll
;                         for (int hf = 0; hf < 2; ++hf) {
;                             f32x4 cs, sn;
;                             if (m < 2) { const float c1 = ropeA[(t >> 6) * 16 + d], s1 = ropeA[1024 + (t >> 6) * 16 + d]; cs = (f32x4){c1, c1, c1, c1}; sn = (f32x4){s1, s1, s1, s1}; }
;                             else { const float* cb = ropeA + 2048 + (d - 16) * 64 + (t & 63) + 4 * hf; cs = *(const f32x4*)(cb); sn = *(const f32x4*)(cb + 1024); }
; #pragma unroll
;                             for (int jj = 0; jj < 4; ++jj) { const float pr = __shfl_xor(v[4 * hf + jj], 4); v[4 * hf + jj] = v[4 * hf + jj] * cs[jj] + sgn * pr * sn[jj]; }
;                             __builtin_amdgcn_sched_barrier(0);
;                         }
;                     }
;                     float zf[8], zb[8]; zf[0] = zf0; zb[0] = zb0;
; #pragma unroll
;                     for (int jj = 1; jj < 8; ++jj) { zf[jj] = zf[jj - 1] * zfs; zb[jj] = zb[jj - 1] * zbs; }
;                     u32x4 wf, wb;
;                     wf.x = cvt_pk_bf16(v[0] * zf[0], v[1] * zf[1]); wf.y = cvt_pk_bf16(v[2] * zf[2], v[3] * zf[3]); wf.z = cvt_pk_bf16(v[4] * zf[4], v[5] * zf[5]); wf.w = cvt_pk_bf16(v[6] * zf[6], v[7] * zf[7]);
;                     wb.x = cvt_pk_bf16(v[0] * zb[0], v[1] * zb[1]); wb.y = cvt_pk_bf16(v[2] * zb[2], v[3] * zb[3]); wb.z = cvt_pk_bf16(v[4] * zb[4], v[5] * zb[5]); wb.w = cvt_pk_bf16(v[6] * zb[6], v[7] * zb[7]);
;                     *(u32x4*)(KTZ + (size_t)r * NT + t0) = wf;
;                     *(u32x4*)(KTZ + (size_t)(256 + r) * NT + t0) = wb;
	v_cndmask_b32_e64 v47, v36, -v36, vcc
	v_mov_b32_e32 v44, v37
	v_pk_mul_f32 v[36:37], v[44:45], v[46:47]
	s_waitcnt lgkmcnt(1)
	v_cndmask_b32_e64 v47, v50, -v50, vcc
	v_mov_b32_e32 v44, v38
	v_add_f32_e32 v48, v48, v49
	v_add_f32_e32 v49, v36, v37
	v_pk_mul_f32 v[36:37], v[44:45], v[46:47]
	s_waitcnt lgkmcnt(0)
	v_cndmask_b32_e64 v47, v51, -v51, vcc
	v_mov_b32_e32 v44, v39
	v_add_f32_e32 v50, v36, v37
	v_pk_mul_f32 v[36:37], v[44:45], v[46:47]
	s_nop 0
	v_add_f32_e32 v46, v36, v37
	global_load_dword v37, v[104:105], off
	global_load_dword v38, v[106:107], off
	ds_bpermute_b32 v39, v177, v32
	v_mov_b32_e32 v36, v32
	ds_bpermute_b32 v32, v177, v33
	ds_bpermute_b32 v47, v177, v34
	ds_bpermute_b32 v51, v177, v35
	s_waitcnt lgkmcnt(3)
	v_cndmask_b32_e64 v39, v39, -v39, vcc
	s_waitcnt vmcnt(0)
	v_pk_mul_f32 v[44:45], v[36:37], v[38:39]
	s_waitcnt lgkmcnt(2)
	v_cndmask_b32_e64 v39, v32, -v32, vcc
	v_mov_b32_e32 v36, v33
	v_pk_mul_f32 v[32:33], v[36:37], v[38:39]
	s_waitcnt lgkmcnt(1)
	v_cndmask_b32_e64 v39, v47, -v47, vcc
	v_mov_b32_e32 v36, v34
	v_add_f32_e32 v44, v44, v45
	v_add_f32_e32 v45, v32, v33
	v_pk_mul_f32 v[32:33], v[36:37], v[38:39]
	s_waitcnt lgkmcnt(0)
	v_cndmask_b32_e64 v39, v51, -v51, vcc
	v_mov_b32_e32 v36, v35
	v_add_f32_e32 v47, v32, v33
	v_pk_mul_f32 v[32:33], v[36:37], v[38:39]
	s_nop 0
	v_add_f32_e32 v39, v32, v33
	v_mul_f32_e32 v32, v63, v48
	v_mul_f32_e32 v33, v75, v49
	v_cvt_pk_bf16_f32 v32, v32, v33
	v_mul_f32_e32 v33, v84, v50
	v_mul_f32_e32 v34, v86, v46
	v_cvt_pk_bf16_f32 v33, v33, v34
	v_mul_f32_e32 v34, v85, v44
	v_mul_f32_e32 v35, v88, v45
	v_cvt_pk_bf16_f32 v34, v34, v35
	v_mul_f32_e32 v35, v87, v47
	v_mul_f32_e32 v36, v71, v39
	v_cvt_pk_bf16_f32 v35, v35, v36
	v_mul_f32_e32 v36, v64, v48
	v_mul_f32_e32 v37, v60, v49
	v_cvt_pk_bf16_f32 v36, v36, v37
	v_mul_f32_e32 v37, v66, v50
	v_mul_f32_e32 v38, v68, v46
	v_cvt_pk_bf16_f32 v37, v37, v38
	v_mul_f32_e32 v38, v70, v44
	v_mul_f32_e32 v44, v72, v45
	v_mul_f32_e32 v39, v67, v39
	v_cvt_pk_bf16_f32 v38, v38, v44
	v_mul_f32_e32 v44, v65, v47
	v_cvt_pk_bf16_f32 v39, v44, v39
	global_store_dwordx4 v[40:41], v[32:35], off offset:256
	global_store_dwordx4 v[42:43], v[36:39], off offset:256
	global_load_dwordx4 v[32:35], v[98:99], off
	s_nop 0
	global_load_dwordx4 v[36:39], v[96:97], off
	ds_bpermute_b32 v41, v177, v28
	ds_bpermute_b32 v42, v177, v29
	ds_bpermute_b32 v44, v177, v30
	ds_bpermute_b32 v46, v177, v31
	v_mov_b32_e32 v40, v28
	v_mov_b32_e32 v28, v30
	s_waitcnt lgkmcnt(3)
	v_cndmask_b32_e64 v43, v41, -v41, vcc
	s_waitcnt lgkmcnt(2)
	v_cndmask_b32_e64 v45, v42, -v42, vcc
	s_waitcnt lgkmcnt(1)
	v_cndmask_b32_e64 v47, v44, -v44, vcc
	s_waitcnt lgkmcnt(0)
	v_cndmask_b32_e64 v49, v46, -v46, vcc
	s_waitcnt vmcnt(1)
	v_mov_b32_e32 v41, v32
	s_waitcnt vmcnt(0)
	v_mov_b32_e32 v42, v36
	v_mov_b32_e32 v32, v29
	v_mov_b32_e32 v44, v37
	v_mov_b32_e32 v29, v34
	v_mov_b32_e32 v46, v38
	v_mov_b32_e32 v34, v31
	v_mov_b32_e32 v48, v39
	v_pk_mul_f32 v[30:31], v[40:41], v[42:43]
	v_pk_mul_f32 v[32:33], v[32:33], v[44:45]
	v_pk_mul_f32 v[28:29], v[28:29], v[46:47]
	v_pk_mul_f32 v[34:35], v[34:35], v[48:49]
	v_add_f32_e32 v46, v30, v31
	v_add_f32_e32 v47, v32, v33
	v_add_f32_e32 v48, v28, v29
	v_add_f32_e32 v49, v34, v35
	global_load_dwordx4 v[28:31], v[92:93], off offset:16
	global_load_dwordx4 v[32:35], v[94:95], off offset:16
	ds_bpermute_b32 v37, v177, v24
	ds_bpermute_b32 v38, v177, v25
	ds_bpermute_b32 v40, v177, v26
	ds_bpermute_b32 v42, v177, v27
	v_mov_b32_e32 v36, v24
	v_mov_b32_e32 v24, v26
	s_waitcnt lgkmcnt(3)
	v_cndmask_b32_e64 v39, v37, -v37, vcc
	s_waitcnt lgkmcnt(2)
	v_cndmask_b32_e64 v41, v38, -v38, vcc
	s_waitcnt lgkmcnt(1)
	v_cndmask_b32_e64 v43, v40, -v40, vcc
	s_waitcnt lgkmcnt(0)
	v_cndmask_b32_e64 v45, v42, -v42, vcc
	s_waitcnt vmcnt(1)
	v_mov_b32_e32 v37, v28
	s_waitcnt vmcnt(0)
	v_mov_b32_e32 v38, v32
	v_mov_b32_e32 v28, v25
	v_mov_b32_e32 v40, v33
	v_mov_b32_e32 v25, v30
	v_mov_b32_e32 v42, v34
	v_mov_b32_e32 v30, v27
	v_mov_b32_e32 v44, v35
	v_pk_mul_f32 v[26:27], v[36:37], v[38:39]
	v_pk_mul_f32 v[28:29], v[28:29], v[40:41]
	v_pk_mul_f32 v[24:25], v[24:25], v[42:43]
	v_pk_mul_f32 v[30:31], v[30:31], v[44:45]
	v_add_f32_e32 v32, v26, v27
	v_add_f32_e32 v33, v28, v29
	v_add_f32_e32 v24, v24, v25
	v_add_f32_e32 v25, v30, v31
	v_mul_f32_e32 v26, v63, v46
	v_mul_f32_e32 v27, v75, v47
	v_cvt_pk_bf16_f32 v26, v26, v27
	v_mul_f32_e32 v27, v84, v48
	v_mul_f32_e32 v28, v86, v49
	v_cvt_pk_bf16_f32 v27, v27, v28
	v_mul_f32_e32 v28, v85, v32
	v_mul_f32_e32 v29, v88, v33
	v_cvt_pk_bf16_f32 v28, v28, v29
	v_mul_f32_e32 v29, v87, v24
	v_mul_f32_e32 v30, v71, v25
	v_cvt_pk_bf16_f32 v29, v29, v30
	v_mul_f32_e32 v30, v64, v46
	v_mul_f32_e32 v31, v60, v47
	v_cvt_pk_bf16_f32 v30, v30, v31
	v_mul_f32_e32 v31, v66, v48
	v_mul_f32_e32 v32, v70, v32
	v_mul_f32_e32 v33, v72, v33
	v_mul_f32_e32 v24, v65, v24
	v_mul_f32_e32 v25, v67, v25
	s_mov_b64 s[0:1], 0x1400000
	v_mul_f32_e32 v34, v68, v49
	v_cvt_pk_bf16_f32 v31, v31, v34
	v_cvt_pk_bf16_f32 v32, v32, v33
	v_cvt_pk_bf16_f32 v33, v24, v25
	v_lshl_add_u64 v[24:25], v[120:121], 0, s[0:1]
	s_mov_b32 s0, 0x1400000
	v_add_co_u32_e64 v34, s[4:5], s0, v120
	s_mov_b64 s[0:1], 0x3400000
	s_nop 0
	v_addc_co_u32_e64 v35, s[4:5], 0, v121, s[4:5]
	global_store_dwordx4 v[34:35], v[26:29], off
	s_nop 1
	v_lshl_add_u64 v[26:27], v[120:121], 0, s[0:1]
	s_mov_b32 s0, 0x3400000
	v_add_co_u32_e64 v28, s[4:5], s0, v120
	s_nop 1
	v_addc_co_u32_e64 v29, s[4:5], 0, v121, s[4:5]
	global_store_dwordx4 v[28:29], v[30:33], off
	global_load_dwordx4 v[28:31], v[98:99], off
	s_nop 0
	global_load_dwordx4 v[32:35], v[96:97], off
	ds_bpermute_b32 v37, v177, v20
	ds_bpermute_b32 v38, v177, v21
	ds_bpermute_b32 v40, v177, v22
	ds_bpermute_b32 v42, v177, v23
	v_mov_b32_e32 v36, v20
	v_mov_b32_e32 v20, v22
	s_waitcnt lgkmcnt(3)
; __device__ __forceinline__ unsigned cvt_pk_bf16(float lo, float hi) { unsigned r; asm volatile("v_cvt_pk_bf16_f32 %0, %1, %2" : "=v"(r) : "v"(lo), "v"(hi)); return r; }
;     __device__ __forceinline__ void operator()(const AccT& acc, const Unit& u, int wr, int wc, int fr, int fq) const {
;     ...
;                         const int t = t0 & 2047;
; #pragma unroll
;                         for (int hf = 0; hf < 2; ++hf) {
;                             f32x4 cs, sn;
;                             if (m < 2) { const float c1 = ropeA[(t >> 6) * 16 + d], s1 = ropeA[1024 + (t >> 6) * 16 + d]; cs = (f32x4){c1, c1, c1, c1}; sn = (f32x4){s1, s1, s1, s1}; }
;                             else { const float* cb = ropeA + 2048 + (d - 16) * 64 + (t & 63) + 4 * hf; cs = *(const f32x4*)(cb); sn = *(const f32x4*)(cb + 1024); }
; #pragma unroll
;                             for (int jj = 0; jj < 4; ++jj) { const float pr = __shfl_xor(v[4 * hf + jj], 4); v[4 * hf + jj] = v[4 * hf + jj] * cs[jj] + sgn * pr * sn[jj]; }
;                             __builtin_amdgcn_sched_barrier(0);
;                         }
;                     }
;                     float zf[8], zb[8]; zf[0] = zf0; zb[0] = zb0;
; #pragma unroll
;                     for (int jj = 1; jj < 8; ++jj) { zf[jj] = zf[jj - 1] * zfs; zb[jj] = zb[jj - 1] * zbs; }
;                     u32x4 wf, wb;
;                     wf.x = cvt_pk_bf16(v[0] * zf[0], v[1] * zf[1]); wf.y = cvt_pk_bf16(v[2] * zf[2], v[3] * zf[3]); wf.z = cvt_pk_bf16(v[4] * zf[4], v[5] * zf[5]); wf.w = cvt_pk_bf16(v[6] * zf[6], v[7] * zf[7]);
;                     wb.x = cvt_pk_bf16(v[0] * zb[0], v[1] * zb[1]); wb.y = cvt_pk_bf16(v[2] * zb[2], v[3] * zb[3]); wb.z = cvt_pk_bf16(v[4] * zb[4], v[5] * zb[5]); wb.w = cvt_pk_bf16(v[6] * zb[6], v[7] * zb[7]);
;                     *(u32x4*)(KTZ + (size_t)r * NT + t0) = wf;
;                     *(u32x4*)(KTZ + (size_t)(256 + r) * NT + t0) = wb;
	v_cndmask_b32_e64 v39, v37, -v37, vcc
	s_waitcnt lgkmcnt(2)
	v_cndmask_b32_e64 v41, v38, -v38, vcc
	s_waitcnt lgkmcnt(1)
	v_cndmask_b32_e64 v43, v40, -v40, vcc
	s_waitcnt lgkmcnt(0)
	v_cndmask_b32_e64 v45, v42, -v42, vcc
	s_waitcnt vmcnt(1)
	v_mov_b32_e32 v37, v28
	s_waitcnt vmcnt(0)
	v_mov_b32_e32 v38, v32
	v_mov_b32_e32 v28, v21
	v_mov_b32_e32 v40, v33
	v_mov_b32_e32 v21, v30
	v_mov_b32_e32 v42, v34
	v_mov_b32_e32 v30, v23
	v_mov_b32_e32 v44, v35
	v_pk_mul_f32 v[22:23], v[36:37], v[38:39]
	v_pk_mul_f32 v[28:29], v[28:29], v[40:41]
	v_pk_mul_f32 v[20:21], v[20:21], v[42:43]
	v_pk_mul_f32 v[30:31], v[30:31], v[44:45]
	v_add_f32_e32 v42, v22, v23
	v_add_f32_e32 v43, v28, v29
	v_add_f32_e32 v44, v20, v21
	v_add_f32_e32 v45, v30, v31
	global_load_dwordx4 v[20:23], v[92:93], off offset:16
	global_load_dwordx4 v[28:31], v[94:95], off offset:16
	ds_bpermute_b32 v33, v177, v16
	ds_bpermute_b32 v34, v177, v17
	ds_bpermute_b32 v36, v177, v18
	ds_bpermute_b32 v38, v177, v19
	v_mov_b32_e32 v32, v16
	v_mov_b32_e32 v16, v18
	s_waitcnt lgkmcnt(3)
	v_cndmask_b32_e64 v35, v33, -v33, vcc
	s_waitcnt lgkmcnt(2)
	v_cndmask_b32_e64 v37, v34, -v34, vcc
	s_waitcnt lgkmcnt(1)
	v_cndmask_b32_e64 v39, v36, -v36, vcc
	s_waitcnt lgkmcnt(0)
	v_cndmask_b32_e64 v41, v38, -v38, vcc
	s_waitcnt vmcnt(1)
	v_mov_b32_e32 v33, v20
	s_waitcnt vmcnt(0)
	v_mov_b32_e32 v34, v28
	v_mov_b32_e32 v20, v17
	v_mov_b32_e32 v36, v29
	v_mov_b32_e32 v17, v22
	v_mov_b32_e32 v38, v30
	v_mov_b32_e32 v22, v19
	v_mov_b32_e32 v40, v31
	v_pk_mul_f32 v[18:19], v[32:33], v[34:35]
	v_pk_mul_f32 v[20:21], v[20:21], v[36:37]
	v_pk_mul_f32 v[16:17], v[16:17], v[38:39]
	v_pk_mul_f32 v[22:23], v[22:23], v[40:41]
	v_add_f32_e32 v28, v18, v19
	v_add_f32_e32 v29, v20, v21
	v_add_f32_e32 v30, v16, v17
	v_add_f32_e32 v23, v22, v23
	v_mul_f32_e32 v16, v63, v42
	v_mul_f32_e32 v17, v75, v43
	v_cvt_pk_bf16_f32 v16, v16, v17
	v_mul_f32_e32 v17, v84, v44
	v_mul_f32_e32 v18, v86, v45
	v_cvt_pk_bf16_f32 v17, v17, v18
	v_mul_f32_e32 v18, v85, v28
	v_mul_f32_e32 v19, v88, v29
	v_cvt_pk_bf16_f32 v18, v18, v19
	v_mul_f32_e32 v19, v87, v30
	v_mul_f32_e32 v20, v71, v23
	v_cvt_pk_bf16_f32 v19, v19, v20
	v_mul_f32_e32 v20, v64, v42
	v_mul_f32_e32 v21, v60, v43
	v_cvt_pk_bf16_f32 v20, v20, v21
	v_mul_f32_e32 v21, v66, v44
	v_mul_f32_e32 v22, v68, v45
	v_cvt_pk_bf16_f32 v21, v21, v22
	v_mul_f32_e32 v22, v70, v28
	v_mul_f32_e32 v28, v72, v29
	v_mul_f32_e32 v23, v67, v23
	v_cvt_pk_bf16_f32 v22, v22, v28
	v_mul_f32_e32 v28, v65, v30
	v_cvt_pk_bf16_f32 v23, v28, v23
	global_store_dwordx4 v[24:25], v[16:19], off offset:256
	global_store_dwordx4 v[26:27], v[20:23], off offset:256
	global_load_dwordx4 v[16:19], v[82:83], off
	s_nop 0
	global_load_dwordx4 v[20:23], v[80:81], off
	ds_bpermute_b32 v25, v177, v12
	ds_bpermute_b32 v26, v177, v13
	ds_bpermute_b32 v28, v177, v14
	ds_bpermute_b32 v30, v177, v15
	v_mov_b32_e32 v24, v12
	v_mov_b32_e32 v12, v14
	s_waitcnt lgkmcnt(3)
	v_cndmask_b32_e64 v27, v25, -v25, vcc
	s_waitcnt lgkmcnt(2)
	v_cndmask_b32_e64 v29, v26, -v26, vcc
	s_waitcnt lgkmcnt(1)
	v_cndmask_b32_e64 v31, v28, -v28, vcc
	s_waitcnt lgkmcnt(0)
	v_cndmask_b32_e64 v33, v30, -v30, vcc
	s_waitcnt vmcnt(1)
	v_mov_b32_e32 v25, v16
	s_waitcnt vmcnt(0)
	v_mov_b32_e32 v26, v20
	v_mov_b32_e32 v16, v13
	v_mov_b32_e32 v28, v21
	v_mov_b32_e32 v13, v18
	v_mov_b32_e32 v30, v22
	v_mov_b32_e32 v18, v15
	v_mov_b32_e32 v32, v23
	v_pk_mul_f32 v[14:15], v[24:25], v[26:27]
	v_pk_mul_f32 v[16:17], v[16:17], v[28:29]
	v_pk_mul_f32 v[12:13], v[12:13], v[30:31]
	v_pk_mul_f32 v[18:19], v[18:19], v[32:33]
	v_add_f32_e32 v30, v14, v15
	v_add_f32_e32 v31, v16, v17
	v_add_f32_e32 v32, v12, v13
	v_add_f32_e32 v33, v18, v19
	global_load_dwordx4 v[12:15], v[76:77], off offset:16
	global_load_dwordx4 v[16:19], v[78:79], off offset:16
	ds_bpermute_b32 v21, v177, v8
	ds_bpermute_b32 v22, v177, v9
	ds_bpermute_b32 v24, v177, v10
	ds_bpermute_b32 v26, v177, v11
	v_mov_b32_e32 v20, v8
	v_mov_b32_e32 v8, v10
	s_waitcnt lgkmcnt(3)
	v_cndmask_b32_e64 v23, v21, -v21, vcc
	s_waitcnt lgkmcnt(2)
	v_cndmask_b32_e64 v25, v22, -v22, vcc
	s_waitcnt lgkmcnt(1)
	v_cndmask_b32_e64 v27, v24, -v24, vcc
	s_waitcnt lgkmcnt(0)
	v_cndmask_b32_e64 v29, v26, -v26, vcc
	s_waitcnt vmcnt(1)
	v_mov_b32_e32 v21, v12
	s_waitcnt vmcnt(0)
; #define PG8_WAIT_V(n) asm volatile("s_waitcnt vmcnt(" #n ")" ::: "memory")
; #define PG8_BAR __builtin_amdgcn_s_barrier()
; template <class Epi, class Sched>
; __device__ __forceinline__ void gemm_phase(LAS unsigned char* lds, const Gemm g, const Sched& S, const Epi& E) {
;     ...
;         E(acc, cur, wr, wc, fr, fq);
;         if (!has_next) break;
; #pragma unroll
;         for (int a = 0; a < 2; ++a)
; #pragma unroll
;             for (int b = 0; b < 2; ++b)
; #pragma unroll
;                 for (int m = 0; m < 4; ++m)
; #pragma unroll
;                     for (int n = 0; n < 2; ++n) acc[a][b][m][n] = (f32x4){0.f, 0.f, 0.f, 0.f};
;         cur = nxt; cA = nA; cB = nB; ++ui;
;     }
;     PG8_WAIT_V(0);
;     if (wr == 0) PG8_BAR;
;     PG8_BAR;
;     __device__ __forceinline__ void operator()(const AccT& acc, const Unit& u, int wr, int wc, int fr, int fq) const {
;     ...
;                             if (m < 2) { const float c1 = ropeA[(t >> 6) * 16 + d], s1 = ropeA[1024 + (t >> 6) * 16 + d]; cs = (f32x4){c1, c1, c1, c1}; sn = (f32x4){s1, s1, s1, s1}; }
;                             else { const float* cb = ropeA + 2048 + (d - 16) * 64 + (t & 63) + 4 * hf; cs = *(const f32x4*)(cb); sn = *(const f32x4*)(cb + 1024); }
; #pragma unroll
;                             for (int jj = 0; jj < 4; ++jj) { const float pr = __shfl_xor(v[4 * hf + jj], 4); v[4 * hf + jj] = v[4 * hf + jj] * cs[jj] + sgn * pr * sn[jj]; }
;                             __builtin_amdgcn_sched_barrier(0);
;                         }
;                     }
;                     float zf[8], zb[8]; zf[0] = zf0; zb[0] = zb0;
; #pragma unroll
;                     for (int jj = 1; jj < 8; ++jj) { zf[jj] = zf[jj - 1] * zfs; zb[jj] = zb[jj - 1] * zbs; }
;                     u32x4 wf, wb;
;                     wf.x = cvt_pk_bf16(v[0] * zf[0], v[1] * zf[1]); wf.y = cvt_pk_bf16(v[2] * zf[2], v[3] * zf[3]); wf.z = cvt_pk_bf16(v[4] * zf[4], v[5] * zf[5]); wf.w = cvt_pk_bf16(v[6] * zf[6], v[7] * zf[7]);
;                     wb.x = cvt_pk_bf16(v[0] * zb[0], v[1] * zb[1]); wb.y = cvt_pk_bf16(v[2] * zb[2], v[3] * zb[3]); wb.z = cvt_pk_bf16(v[4] * zb[4], v[5] * zb[5]); wb.w = cvt_pk_bf16(v[6] * zb[6], v[7] * zb[7]);
;                     *(u32x4*)(KTZ + (size_t)r * NT + t0) = wf;
;                     *(u32x4*)(KTZ + (size_t)(256 + r) * NT + t0) = wb;
;                     __builtin_amdgcn_sched_barrier(0);
	v_mov_b32_e32 v22, v16
	v_mov_b32_e32 v12, v9
	v_mov_b32_e32 v24, v17
	v_mov_b32_e32 v9, v14
	v_mov_b32_e32 v26, v18
	v_mov_b32_e32 v14, v11
	v_mov_b32_e32 v28, v19
	v_pk_mul_f32 v[10:11], v[20:21], v[22:23]
	v_pk_mul_f32 v[12:13], v[12:13], v[24:25]
	v_pk_mul_f32 v[8:9], v[8:9], v[26:27]
	v_pk_mul_f32 v[14:15], v[14:15], v[28:29]
	v_add_f32_e32 v16, v10, v11
	v_add_f32_e32 v17, v12, v13
	v_add_f32_e32 v8, v8, v9
	v_add_f32_e32 v9, v14, v15
	v_mul_f32_e32 v10, v63, v30
	v_mul_f32_e32 v11, v75, v31
	v_cvt_pk_bf16_f32 v10, v10, v11
	v_mul_f32_e32 v11, v84, v32
	v_mul_f32_e32 v12, v86, v33
	v_cvt_pk_bf16_f32 v11, v11, v12
	v_mul_f32_e32 v12, v85, v16
	v_mul_f32_e32 v13, v88, v17
	v_cvt_pk_bf16_f32 v12, v12, v13
	v_mul_f32_e32 v13, v87, v8
	v_mul_f32_e32 v14, v71, v9
	v_cvt_pk_bf16_f32 v13, v13, v14
	v_mul_f32_e32 v14, v64, v30
	v_mul_f32_e32 v15, v60, v31
	v_cvt_pk_bf16_f32 v14, v14, v15
	v_mul_f32_e32 v15, v66, v32
	v_mul_f32_e32 v18, v68, v33
	v_cvt_pk_bf16_f32 v15, v15, v18
	v_add_co_u32_e64 v18, s[4:5], s63, v120
	v_mul_f32_e32 v16, v70, v16
	v_mul_f32_e32 v17, v72, v17
	v_addc_co_u32_e64 v19, s[4:5], 0, v121, s[4:5]
	v_cvt_pk_bf16_f32 v16, v16, v17
	v_mul_f32_e32 v8, v65, v8
	v_mul_f32_e32 v9, v67, v9
	v_cvt_pk_bf16_f32 v17, v8, v9
	global_store_dwordx4 v[18:19], v[10:13], off
	v_lshl_add_u64 v[8:9], v[120:121], 0, s[26:27]
	s_nop 0
	v_add_co_u32_e64 v12, s[4:5], s64, v120
	v_lshl_add_u64 v[10:11], v[120:121], 0, s[28:29]
	s_nop 0
	v_addc_co_u32_e64 v13, s[4:5], 0, v121, s[4:5]
	global_store_dwordx4 v[12:13], v[14:17], off
	global_load_dwordx4 v[12:15], v[82:83], off
	s_nop 0
	global_load_dwordx4 v[16:19], v[80:81], off
	ds_bpermute_b32 v34, v177, v4
	ds_bpermute_b32 v32, v177, v5
	ds_bpermute_b32 v33, v177, v6
	ds_bpermute_b32 v28, v177, v7
	global_load_dwordx4 v[20:23], v[76:77], off offset:16
	global_load_dwordx4 v[24:27], v[78:79], off offset:16
	s_waitcnt lgkmcnt(0)
	v_cndmask_b32_e64 v29, v28, -v28, vcc
	v_mov_b32_e32 v30, v7
	s_waitcnt vmcnt(3)
	v_mov_b32_e32 v31, v15
	s_waitcnt vmcnt(2)
	v_mov_b32_e32 v28, v19
	v_cndmask_b32_e64 v19, v33, -v33, vcc
	v_mov_b32_e32 v7, v14
	v_cndmask_b32_e64 v15, v32, -v32, vcc
	v_mov_b32_e32 v32, v5
	v_mov_b32_e32 v33, v13
	v_mov_b32_e32 v14, v17
	v_cndmask_b32_e64 v17, v34, -v34, vcc
	v_mov_b32_e32 v5, v12
	ds_bpermute_b32 v13, v177, v0
	v_mov_b32_e32 v12, v0
	ds_bpermute_b32 v34, v177, v1
	ds_bpermute_b32 v35, v177, v2
	v_mov_b32_e32 v0, v2
	ds_bpermute_b32 v2, v177, v3
	v_pk_mul_f32 v[28:29], v[30:31], v[28:29]
	v_pk_mul_f32 v[6:7], v[6:7], v[18:19]
	v_pk_mul_f32 v[14:15], v[32:33], v[14:15]
	v_pk_mul_f32 v[4:5], v[4:5], v[16:17]
	v_add_f32_e32 v18, v28, v29
	v_add_f32_e32 v19, v6, v7
	v_add_f32_e32 v28, v14, v15
	v_add_f32_e32 v29, v4, v5
	s_waitcnt lgkmcnt(3)
	v_cndmask_b32_e64 v5, v13, -v13, vcc
	s_waitcnt lgkmcnt(2)
	v_cndmask_b32_e64 v7, v34, -v34, vcc
	s_waitcnt lgkmcnt(1)
	v_cndmask_b32_e64 v15, v35, -v35, vcc
	s_waitcnt lgkmcnt(0)
	v_cndmask_b32_e64 v17, v2, -v2, vcc
	s_waitcnt vmcnt(1)
	v_mov_b32_e32 v13, v20
	s_waitcnt vmcnt(0)
	v_mov_b32_e32 v4, v24
	v_mov_b32_e32 v20, v1
	v_mov_b32_e32 v6, v25
	v_mov_b32_e32 v1, v22
	v_mov_b32_e32 v14, v26
	v_mov_b32_e32 v22, v3
	v_mov_b32_e32 v16, v27
	v_pk_mul_f32 v[2:3], v[12:13], v[4:5]
	v_pk_mul_f32 v[4:5], v[20:21], v[6:7]
	v_pk_mul_f32 v[0:1], v[0:1], v[14:15]
	v_pk_mul_f32 v[6:7], v[22:23], v[16:17]
	v_add_f32_e32 v12, v2, v3
	v_add_f32_e32 v13, v4, v5
	v_add_f32_e32 v14, v0, v1
	v_add_f32_e32 v7, v6, v7
	v_mul_f32_e32 v0, v63, v29
	v_mul_f32_e32 v1, v75, v28
	v_cvt_pk_bf16_f32 v0, v0, v1
	v_mul_f32_e32 v1, v84, v19
	v_mul_f32_e32 v2, v86, v18
	v_cvt_pk_bf16_f32 v1, v1, v2
	v_mul_f32_e32 v2, v85, v12
	v_mul_f32_e32 v3, v88, v13
	v_cvt_pk_bf16_f32 v2, v2, v3
	v_mul_f32_e32 v3, v87, v14
	v_mul_f32_e32 v4, v71, v7
	v_cvt_pk_bf16_f32 v3, v3, v4
	v_mul_f32_e32 v4, v64, v29
	v_mul_f32_e32 v5, v60, v28
	v_cvt_pk_bf16_f32 v4, v4, v5
	v_mul_f32_e32 v5, v66, v19
	v_mul_f32_e32 v6, v68, v18
	v_cvt_pk_bf16_f32 v5, v5, v6
	v_mul_f32_e32 v6, v70, v12
	v_mul_f32_e32 v12, v72, v13
	v_mul_f32_e32 v7, v67, v7
	v_cvt_pk_bf16_f32 v6, v6, v12
	v_mul_f32_e32 v12, v65, v14
	v_cvt_pk_bf16_f32 v7, v12, v7
	global_store_dwordx4 v[8:9], v[0:3], off offset:256
	global_store_dwordx4 v[10:11], v[4:7], off offset:256
	s_and_b64 vcc, exec, s[2:3]
	s_mov_b32 s33, s30
	s_mov_b64 s[4:5], s[38:39]
	s_mov_b64 s[0:1], s[36:37]
	s_cbranch_vccz .LBB0_606
	s_waitcnt vmcnt(0)
	s_cmpk_gt_u32 s42, 0xff
	s_cbranch_scc1 .LBB0_617
	s_barrier

; #define PG8_STAGE(bufoff, gbase, voff) do { _Pragma("unroll") for (int _i = 0; _i < 2; ++_i) \
;         __builtin_amdgcn_global_load_lds((const unsigned*)((const char*)(gbase) + (voff)[_i]), (LAS unsigned*)(lds + (bufoff) + ldsw + _i * 8192), 16, 0, 0); } while (0)
; #define PG8_LDA(dst, b, h) do { _Pragma("unroll") for (int m = 0; m < 4; ++m) _Pragma("unroll") for (int k = 0; k < 2; ++k) dst[m][k] = *(const LAS bf16x8*)(lds + PG8_SA(b, h) + aoff + m * 2048 + k * 1024); } while (0)
; #define PG8_LDB(dst, b, h) do { _Pragma("unroll") for (int n = 0; n < 2; ++n) _Pragma("unroll") for (int k = 0; k < 2; ++k) dst[n][k] = *(const LAS bf16x8*)(lds + PG8_SB(b, h) + boff + n * 2048 + k * 1024); } while (0)
; #define PG8_WAIT_V(n) asm volatile("s_waitcnt vmcnt(" #n ")" ::: "memory")
; #define PG8_BAR __builtin_amdgcn_s_barrier()
; template <class Epi, class Sched>
; __device__ __forceinline__ void gemm_phase(LAS unsigned char* lds, const Gemm g, const Sched& S, const Epi& E) {
;     ...
;         const bool has_next = S.next(ui + 1, nxt);
;         const char* nA = has_next ? (const char*)g.A + (size_t)nxt.pm * tstep : cA; const char* nB = has_next ? (const char*)g.Bt + (size_t)nxt.pn * tstep : cB;
;         for (int t = 0; t < nt; t += 2) {
;             const bool last = (t == nt - 2);
;             const char* a1 = cA + (size_t)(t + 1) * kstep;
;             const char* a2 = last ? nA : cA + (size_t)(t + 2) * kstep; const char* b2 = last ? nB : cB + (size_t)(t + 2) * kstep;
;             const char* a3 = a2 + kstep; const char* b3 = b2 + kstep;
;             PG8_LDB(B0, 0, 0); PG8_SCHED; PG8_LDA(At, 0, 0); PG8_STAGE(PG8_SA(1, 1), a1 + hstep, voffA);
;             PG8_WAIT_L(8); PG8_BAR; PG8_WAIT_L(0); PG8_MMA(0, 0, At, B0); PG8_BAR; PG8_SCHED;
;             PG8_LDB(B1, 0, 1); PG8_STAGE(PG8_SB(0, 0), b2, voffB);
;             PG8_BAR; PG8_WAIT_L(0); PG8_MMA(0, 1, At, B1); PG8_BAR;
;             PG8_LDA(At, 0, 1); PG8_STAGE(PG8_SA(0, 0), a2, voffA);
;             PG8_BAR; PG8_WAIT_L(0); PG8_MMA(1, 0, At, B0); PG8_BAR; PG8_SCHED;
;             PG8_STAGE(PG8_SB(0, 1), b2 + hstep, voffB);
;             PG8_WAIT_V(6); PG8_BAR; PG8_MMA(1, 1, At, B1); PG8_BAR;
;             PG8_LDB(B0, 1, 0); PG8_SCHED; PG8_LDA(At, 1, 0); PG8_STAGE(PG8_SA(0, 1), a2 + hstep, voffA);
;             PG8_WAIT_L(8); PG8_BAR; PG8_WAIT_L(0); PG8_MMA(0, 0, At, B0); PG8_BAR; PG8_SCHED;
.LBB0_632:
	s_ashr_i32 s23, s22, 31
	v_cmp_lt_i64_e32 vcc, s[24:25], v[140:141]
	s_lshl_b64 s[24:25], s[22:23], 19
	s_add_u32 s24, s38, s24
	s_addc_u32 s25, s39, s25
	s_and_b64 s[26:27], vcc, exec
	s_cselect_b32 s23, s25, s31
	s_cselect_b32 s61, s24, s30
	s_ashr_i32 s21, s20, 31
	s_lshl_b64 s[26:27], s[20:21], 19
	s_add_u32 s26, s96, s26
	s_addc_u32 s27, s97, s27
	s_and_b64 s[36:37], vcc, exec
	s_cselect_b32 s21, s27, s35
	s_cselect_b32 s62, s26, s34
	s_add_u32 s30, s30, 0x40080
	s_addc_u32 s31, s31, 0
	s_add_u32 s63, s34, 0x100
	s_addc_u32 s64, s35, 0
	s_mov_b32 s65, -2
	s_waitcnt lgkmcnt(0)
	ds_read_b128 v[150:153], v147
	ds_read_b128 v[154:157], v147 offset:1024
	ds_read_b128 v[158:161], v147 offset:2048
	ds_read_b128 v[162:165], v147 offset:3072
	s_add_u32 s34, s30, 0xfffc0080
	s_addc_u32 s35, s31, -1
	s_cmp_eq_u32 s65, 12
	s_cselect_b32 s37, s23, s35
	s_cselect_b32 s36, s61, s34
	s_cselect_b32 s35, s21, s64
	s_cselect_b32 s34, s62, s63
	s_add_i32 m0, s29, 0xc000
	ds_read_b128 v[166:169], v148
	ds_read_b128 v[170:173], v148 offset:1024
	ds_read_b128 v[174:177], v148 offset:2048
	ds_read_b128 v[178:181], v148 offset:3072
	ds_read_b128 v[182:185], v148 offset:4096
	ds_read_b128 v[186:189], v148 offset:5120
	ds_read_b128 v[190:193], v148 offset:6144
	ds_read_b128 v[194:197], v148 offset:7168
	global_load_lds_dwordx4 v136, s[30:31]
	s_add_i32 m0, s29, 0xe000
	s_nop 0
	global_load_lds_dwordx4 v138, s[30:31]
	s_waitcnt lgkmcnt(8)
	s_waitcnt vmcnt(8)
	s_waitcnt lgkmcnt(0)
	s_setprio 1
	s_barrier
	v_mfma_f32_16x16x32_bf16 v[124:127], v[150:153], v[166:169], 0
	v_mfma_f32_16x16x32_bf16 v[120:123], v[158:161], v[166:169], 0
	v_mfma_f32_16x16x32_bf16 v[116:119], v[150:153], v[174:177], 0
	v_mfma_f32_16x16x32_bf16 v[108:111], v[158:161], v[174:177], 0
	v_mfma_f32_16x16x32_bf16 v[100:103], v[150:153], v[182:185], 0
	v_mfma_f32_16x16x32_bf16 v[92:95], v[158:161], v[182:185], 0
	v_mfma_f32_16x16x32_bf16 v[84:87], v[150:153], v[190:193], 0
	v_mfma_f32_16x16x32_bf16 v[76:79], v[158:161], v[190:193], 0
	v_mfma_f32_16x16x32_bf16 v[124:127], v[154:157], v[170:173], v[124:127]
	v_mfma_f32_16x16x32_bf16 v[120:123], v[162:165], v[170:173], v[120:123]
	v_mfma_f32_16x16x32_bf16 v[116:119], v[154:157], v[178:181], v[116:119]
	v_mfma_f32_16x16x32_bf16 v[108:111], v[162:165], v[178:181], v[108:111]
	v_mfma_f32_16x16x32_bf16 v[100:103], v[154:157], v[186:189], v[100:103]
	v_mfma_f32_16x16x32_bf16 v[92:95], v[162:165], v[186:189], v[92:95]
	v_mfma_f32_16x16x32_bf16 v[84:87], v[154:157], v[194:197], v[84:87]
	v_mfma_f32_16x16x32_bf16 v[76:79], v[162:165], v[194:197], v[76:79]
	s_barrier
	s_setprio 0
	s_add_i32 s66, s54, s43
	s_mov_b32 m0, s66
	ds_read_b128 v[202:205], v149
	ds_read_b128 v[206:209], v149 offset:1024
	ds_read_b128 v[210:213], v149 offset:2048
	ds_read_b128 v[214:217], v149 offset:3072
	global_load_lds_dwordx4 v130, s[34:35]
	s_add_i32 m0, s66, 0x2000
	s_nop 0
	global_load_lds_dwordx4 v134, s[34:35]
	s_waitcnt vmcnt(8)
	s_waitcnt lgkmcnt(0)
	s_setprio 1
	s_barrier
	v_mfma_f32_16x16x32_bf16 v[112:115], v[202:205], v[166:169], 0
	v_mfma_f32_16x16x32_bf16 v[104:107], v[210:213], v[166:169], 0
	v_mfma_f32_16x16x32_bf16 v[96:99], v[202:205], v[174:177], 0
	v_mfma_f32_16x16x32_bf16 v[88:91], v[210:213], v[174:177], 0
	v_mfma_f32_16x16x32_bf16 v[80:83], v[202:205], v[182:185], 0
	v_mfma_f32_16x16x32_bf16 v[72:75], v[210:213], v[182:185], 0
	v_mfma_f32_16x16x32_bf16 v[68:71], v[202:205], v[190:193], 0
	v_mfma_f32_16x16x32_bf16 v[64:67], v[210:213], v[190:193], 0
	v_mfma_f32_16x16x32_bf16 v[112:115], v[206:209], v[170:173], v[112:115]
	v_mfma_f32_16x16x32_bf16 v[104:107], v[214:217], v[170:173], v[104:107]
	v_mfma_f32_16x16x32_bf16 v[96:99], v[206:209], v[178:181], v[96:99]
	v_mfma_f32_16x16x32_bf16 v[88:91], v[214:217], v[178:181], v[88:91]
	v_mfma_f32_16x16x32_bf16 v[80:83], v[206:209], v[186:189], v[80:83]
	v_mfma_f32_16x16x32_bf16 v[72:75], v[214:217], v[186:189], v[72:75]
	v_mfma_f32_16x16x32_bf16 v[68:71], v[206:209], v[194:197], v[68:71]
	v_mfma_f32_16x16x32_bf16 v[64:67], v[214:217], v[194:197], v[64:67]
	s_mov_b32 m0, s29
	v_lshl_add_u64 v[220:221], s[36:37], 0, v[128:129]
	s_barrier
	s_setprio 0
	ds_read_b128 v[166:169], v148 offset:16384
	ds_read_b128 v[170:173], v148 offset:17408
	ds_read_b128 v[174:177], v148 offset:18432
	ds_read_b128 v[178:181], v148 offset:19456
	ds_read_b128 v[182:185], v148 offset:20480
	ds_read_b128 v[186:189], v148 offset:21504
	ds_read_b128 v[190:193], v148 offset:22528
	ds_read_b128 v[194:197], v148 offset:23552
	global_load_lds_dwordx4 v128, s[36:37]
	v_lshl_add_u64 v[222:223], s[36:37], 0, v[132:133]
	s_mov_b32 m0, s44
	s_nop 0
	global_load_lds_dwordx4 v132, s[36:37]
	s_waitcnt lgkmcnt(0)
	s_setprio 1
	s_barrier
	v_mfma_f32_16x16x32_bf16 v[60:63], v[150:153], v[166:169], 0
	v_mfma_f32_16x16x32_bf16 v[56:59], v[158:161], v[166:169], 0
	v_mfma_f32_16x16x32_bf16 v[52:55], v[150:153], v[174:177], 0
	v_mfma_f32_16x16x32_bf16 v[44:47], v[158:161], v[174:177], 0
	v_mfma_f32_16x16x32_bf16 v[36:39], v[150:153], v[182:185], 0
	v_mfma_f32_16x16x32_bf16 v[28:31], v[158:161], v[182:185], 0
	v_mfma_f32_16x16x32_bf16 v[20:23], v[150:153], v[190:193], 0
	v_mfma_f32_16x16x32_bf16 v[12:15], v[158:161], v[190:193], 0
	v_mfma_f32_16x16x32_bf16 v[60:63], v[154:157], v[170:173], v[60:63]
	v_mfma_f32_16x16x32_bf16 v[56:59], v[162:165], v[170:173], v[56:59]
	v_mfma_f32_16x16x32_bf16 v[52:55], v[154:157], v[178:181], v[52:55]
	v_mfma_f32_16x16x32_bf16 v[44:47], v[162:165], v[178:181], v[44:47]
	v_mfma_f32_16x16x32_bf16 v[36:39], v[154:157], v[186:189], v[36:39]
	v_mfma_f32_16x16x32_bf16 v[28:31], v[162:165], v[186:189], v[28:31]
	v_mfma_f32_16x16x32_bf16 v[20:23], v[154:157], v[194:197], v[20:23]
	v_mfma_f32_16x16x32_bf16 v[12:15], v[162:165], v[194:197], v[12:15]
	s_barrier
; #define PG8_STAGE(bufoff, gbase, voff) do { _Pragma("unroll") for (int _i = 0; _i < 2; ++_i) \
;         __builtin_amdgcn_global_load_lds((const unsigned*)((const char*)(gbase) + (voff)[_i]), (LAS unsigned*)(lds + (bufoff) + ldsw + _i * 8192), 16, 0, 0); } while (0)
; #define PG8_LDA(dst, b, h) do { _Pragma("unroll") for (int m = 0; m < 4; ++m) _Pragma("unroll") for (int k = 0; k < 2; ++k) dst[m][k] = *(const LAS bf16x8*)(lds + PG8_SA(b, h) + aoff + m * 2048 + k * 1024); } while (0)
; #define PG8_LDB(dst, b, h) do { _Pragma("unroll") for (int n = 0; n < 2; ++n) _Pragma("unroll") for (int k = 0; k < 2; ++k) dst[n][k] = *(const LAS bf16x8*)(lds + PG8_SB(b, h) + boff + n * 2048 + k * 1024); } while (0)
; #define PG8_MMA(ai, bj, At, Bt) do { __builtin_amdgcn_s_setprio(1); _Pragma("unroll") for (int m = 0; m < 4; ++m) _Pragma("unroll") for (int n = 0; n < 2; ++n) _Pragma("unroll") for (int k = 0; k < 2; ++k) \
;         acc[ai][bj][m][n] = __builtin_amdgcn_mfma_f32_16x16x32_bf16(Bt[n][k], At[m][k], acc[ai][bj][m][n], 0, 0, 0); __builtin_amdgcn_s_setprio(0); } while (0)
; #define PG8_WAIT_V(n) asm volatile("s_waitcnt vmcnt(" #n ")" ::: "memory")
; #define PG8_WAIT_L(n) asm volatile("s_waitcnt lgkmcnt(" #n ")" ::: "memory")
; #define PG8_BAR __builtin_amdgcn_s_barrier()
; #define PG8_SCHED __builtin_amdgcn_sched_barrier(0)
; template <class Epi, class Sched>
; __device__ __forceinline__ void gemm_phase(LAS unsigned char* lds, const Gemm g, const Sched& S, const Epi& E) {
;     ...
;             PG8_WAIT_V(6); PG8_BAR; PG8_MMA(1, 1, At, B1); PG8_BAR;
;             PG8_LDB(B0, 1, 0); PG8_SCHED; PG8_LDA(At, 1, 0); PG8_STAGE(PG8_SA(0, 1), a2 + hstep, voffA);
;             PG8_WAIT_L(8); PG8_BAR; PG8_WAIT_L(0); PG8_MMA(0, 0, At, B0); PG8_BAR; PG8_SCHED;
;             PG8_LDB(B1, 1, 1); PG8_STAGE(PG8_SB(1, 0), b3, voffB);
;             PG8_BAR; PG8_WAIT_L(0); PG8_MMA(0, 1, At, B1); PG8_BAR;
;             PG8_LDA(At, 1, 1); PG8_STAGE(PG8_SA(1, 0), a3, voffA);
;             PG8_BAR; PG8_WAIT_L(0); PG8_MMA(1, 0, At, B0); PG8_BAR; PG8_SCHED;
	s_setprio 0
	s_add_u32 s66, s34, 0x40000
	s_addc_u32 s67, s35, 0
	s_add_i32 s68, s55, s43
	s_mov_b32 m0, s68
	s_nop 0
	global_load_lds_dwordx4 v130, s[66:67]
	s_add_i32 m0, s68, 0x2000
	s_nop 0
	global_load_lds_dwordx4 v134, s[66:67]
	s_add_u32 s36, s36, 0x40000
	s_addc_u32 s37, s37, 0
	s_mov_b32 m0, s45
	s_nop 0
	global_load_lds_dwordx4 v128, s[36:37]
	s_mov_b32 m0, s46
	s_nop 0
	global_load_lds_dwordx4 v132, s[36:37]
	s_waitcnt vmcnt(10)
	s_setprio 1
	s_barrier
	v_mfma_f32_16x16x32_bf16 v[48:51], v[202:205], v[166:169], 0
	v_mfma_f32_16x16x32_bf16 v[40:43], v[210:213], v[166:169], 0
	v_mfma_f32_16x16x32_bf16 v[32:35], v[202:205], v[174:177], 0
	v_mfma_f32_16x16x32_bf16 v[24:27], v[210:213], v[174:177], 0
	v_mfma_f32_16x16x32_bf16 v[16:19], v[202:205], v[182:185], 0
	v_mfma_f32_16x16x32_bf16 v[8:11], v[210:213], v[182:185], 0
	v_mfma_f32_16x16x32_bf16 v[4:7], v[202:205], v[190:193], 0
	v_mfma_f32_16x16x32_bf16 v[0:3], v[210:213], v[190:193], 0
	v_mfma_f32_16x16x32_bf16 v[48:51], v[206:209], v[170:173], v[48:51]
	v_mfma_f32_16x16x32_bf16 v[40:43], v[214:217], v[170:173], v[40:43]
	v_mfma_f32_16x16x32_bf16 v[32:35], v[206:209], v[178:181], v[32:35]
	v_mfma_f32_16x16x32_bf16 v[24:27], v[214:217], v[178:181], v[24:27]
	v_mfma_f32_16x16x32_bf16 v[16:19], v[206:209], v[186:189], v[16:19]
	v_mfma_f32_16x16x32_bf16 v[8:11], v[214:217], v[186:189], v[8:11]
	v_mfma_f32_16x16x32_bf16 v[4:7], v[206:209], v[194:197], v[4:7]
	v_mfma_f32_16x16x32_bf16 v[0:3], v[214:217], v[194:197], v[0:3]
	s_add_i32 s66, 0, 0x18000
	v_add_u32_e32 v162, s66, v146
	s_barrier
	s_setprio 0
	ds_read_b128 v[150:153], v162
	ds_read_b128 v[154:157], v162 offset:1024
	ds_read_b128 v[158:161], v162 offset:2048
	ds_read_b128 v[162:165], v162 offset:3072
	ds_read_b128 v[166:169], v148 offset:32768
	ds_read_b128 v[170:173], v148 offset:33792
	ds_read_b128 v[174:177], v148 offset:34816
	ds_read_b128 v[178:181], v148 offset:35840
	ds_read_b128 v[182:185], v148 offset:36864
	ds_read_b128 v[186:189], v148 offset:37888
	ds_read_b128 v[190:193], v148 offset:38912
	ds_read_b128 v[194:197], v148 offset:39936
	s_waitcnt lgkmcnt(8)
	s_waitcnt vmcnt(8)
	s_waitcnt lgkmcnt(0)
	s_setprio 1
	s_barrier
	v_mfma_f32_16x16x32_bf16 v[124:127], v[150:153], v[166:169], v[124:127]
	v_mfma_f32_16x16x32_bf16 v[120:123], v[158:161], v[166:169], v[120:123]
	v_mfma_f32_16x16x32_bf16 v[116:119], v[150:153], v[174:177], v[116:119]
	v_mfma_f32_16x16x32_bf16 v[108:111], v[158:161], v[174:177], v[108:111]
	v_mfma_f32_16x16x32_bf16 v[100:103], v[150:153], v[182:185], v[100:103]
	v_mfma_f32_16x16x32_bf16 v[92:95], v[158:161], v[182:185], v[92:95]
	v_mfma_f32_16x16x32_bf16 v[84:87], v[150:153], v[190:193], v[84:87]
	v_mfma_f32_16x16x32_bf16 v[76:79], v[158:161], v[190:193], v[76:79]
	v_mfma_f32_16x16x32_bf16 v[124:127], v[154:157], v[170:173], v[124:127]
	v_mfma_f32_16x16x32_bf16 v[120:123], v[162:165], v[170:173], v[120:123]
	v_mfma_f32_16x16x32_bf16 v[116:119], v[154:157], v[178:181], v[116:119]
	v_mfma_f32_16x16x32_bf16 v[108:111], v[162:165], v[178:181], v[108:111]
	v_mfma_f32_16x16x32_bf16 v[100:103], v[154:157], v[186:189], v[100:103]
	v_mfma_f32_16x16x32_bf16 v[92:95], v[162:165], v[186:189], v[92:95]
	v_mfma_f32_16x16x32_bf16 v[84:87], v[154:157], v[194:197], v[84:87]
	v_mfma_f32_16x16x32_bf16 v[76:79], v[162:165], v[194:197], v[76:79]
	s_barrier
	s_setprio 0
	s_add_i32 s36, 0, 0x1c000
	s_add_i32 s37, s66, s43
	v_add_u32_e32 v214, s36, v146
	s_add_u32 s4, s34, 0x80
	s_addc_u32 s5, s35, 0
	s_mov_b32 m0, s37
	ds_read_b128 v[202:205], v214
	ds_read_b128 v[206:209], v214 offset:1024
	ds_read_b128 v[210:213], v214 offset:2048
	ds_read_b128 v[214:217], v214 offset:3072
	global_load_lds_dwordx4 v130, s[4:5]
	s_add_i32 m0, s37, 0x2000
	s_nop 0
	global_load_lds_dwordx4 v134, s[4:5]
	s_waitcnt vmcnt(8)
	s_waitcnt lgkmcnt(0)
	s_setprio 1
	s_barrier
	v_mfma_f32_16x16x32_bf16 v[112:115], v[202:205], v[166:169], v[112:115]
	v_mfma_f32_16x16x32_bf16 v[104:107], v[210:213], v[166:169], v[104:107]
	v_mfma_f32_16x16x32_bf16 v[96:99], v[202:205], v[174:177], v[96:99]
	v_mfma_f32_16x16x32_bf16 v[88:91], v[210:213], v[174:177], v[88:91]
	v_mfma_f32_16x16x32_bf16 v[80:83], v[202:205], v[182:185], v[80:83]
	v_mfma_f32_16x16x32_bf16 v[72:75], v[210:213], v[182:185], v[72:75]
	v_mfma_f32_16x16x32_bf16 v[68:71], v[202:205], v[190:193], v[68:71]
	v_mfma_f32_16x16x32_bf16 v[64:67], v[210:213], v[190:193], v[64:67]
	v_mfma_f32_16x16x32_bf16 v[112:115], v[206:209], v[170:173], v[112:115]
	v_mfma_f32_16x16x32_bf16 v[104:107], v[214:217], v[170:173], v[104:107]
	v_mfma_f32_16x16x32_bf16 v[96:99], v[206:209], v[178:181], v[96:99]
	v_mfma_f32_16x16x32_bf16 v[88:91], v[214:217], v[178:181], v[88:91]
	v_mfma_f32_16x16x32_bf16 v[80:83], v[206:209], v[186:189], v[80:83]
	v_mfma_f32_16x16x32_bf16 v[72:75], v[214:217], v[186:189], v[72:75]
	v_mfma_f32_16x16x32_bf16 v[68:71], v[206:209], v[194:197], v[68:71]
	v_mfma_f32_16x16x32_bf16 v[64:67], v[214:217], v[194:197], v[64:67]
	s_mov_b32 m0, s51
	s_mov_b64 s[4:5], 0x80
	v_lshl_add_u64 v[198:199], v[220:221], 0, s[4:5]
	s_barrier
	s_setprio 0
	ds_read_b128 v[166:169], v148 offset:49152
	ds_read_b128 v[170:173], v148 offset:50176
	ds_read_b128 v[174:177], v148 offset:51200
	ds_read_b128 v[178:181], v148 offset:52224
	ds_read_b128 v[182:185], v148 offset:53248
	ds_read_b128 v[186:189], v148 offset:54272
	ds_read_b128 v[190:193], v148 offset:55296
	ds_read_b128 v[194:197], v148 offset:56320
	global_load_lds_dwordx4 v[198:199], off
	v_lshl_add_u64 v[198:199], v[222:223], 0, s[4:5]
	s_mov_b32 m0, s52
	s_nop 0
	global_load_lds_dwordx4 v[198:199], off
	s_waitcnt lgkmcnt(0)
	s_setprio 1
	s_barrier
; #define PG8_STAGE(bufoff, gbase, voff) do { _Pragma("unroll") for (int _i = 0; _i < 2; ++_i) \
;         __builtin_amdgcn_global_load_lds((const unsigned*)((const char*)(gbase) + (voff)[_i]), (LAS unsigned*)(lds + (bufoff) + ldsw + _i * 8192), 16, 0, 0); } while (0)
; #define PG8_LDA(dst, b, h) do { _Pragma("unroll") for (int m = 0; m < 4; ++m) _Pragma("unroll") for (int k = 0; k < 2; ++k) dst[m][k] = *(const LAS bf16x8*)(lds + PG8_SA(b, h) + aoff + m * 2048 + k * 1024); } while (0)
; #define PG8_LDB(dst, b, h) do { _Pragma("unroll") for (int n = 0; n < 2; ++n) _Pragma("unroll") for (int k = 0; k < 2; ++k) dst[n][k] = *(const LAS bf16x8*)(lds + PG8_SB(b, h) + boff + n * 2048 + k * 1024); } while (0)
; #define PG8_MMA(ai, bj, At, Bt) do { __builtin_amdgcn_s_setprio(1); _Pragma("unroll") for (int m = 0; m < 4; ++m) _Pragma("unroll") for (int n = 0; n < 2; ++n) _Pragma("unroll") for (int k = 0; k < 2; ++k) \
;         acc[ai][bj][m][n] = __builtin_amdgcn_mfma_f32_16x16x32_bf16(Bt[n][k], At[m][k], acc[ai][bj][m][n], 0, 0, 0); __builtin_amdgcn_s_setprio(0); } while (0)
; #define PG8_WAIT_V(n) asm volatile("s_waitcnt vmcnt(" #n ")" ::: "memory")
; #define PG8_WAIT_L(n) asm volatile("s_waitcnt lgkmcnt(" #n ")" ::: "memory")
; template <class Epi, class Sched>
; __device__ __forceinline__ void gemm_phase(LAS unsigned char* lds, const Gemm g, const Sched& S, const Epi& E) {
;     ...
;             PG8_LDB(B0, 0, 0); PG8_SCHED; PG8_LDA(At, 0, 0); PG8_STAGE(PG8_SA(1, 1), a1 + hstep, voffA);
;             PG8_WAIT_L(8); PG8_BAR; PG8_WAIT_L(0); PG8_MMA(0, 0, At, B0); PG8_BAR; PG8_SCHED;
;             PG8_LDB(B1, 0, 1); PG8_STAGE(PG8_SB(0, 0), b2, voffB);
;             PG8_BAR; PG8_WAIT_L(0); PG8_MMA(0, 1, At, B1); PG8_BAR;
;             PG8_LDA(At, 0, 1); PG8_STAGE(PG8_SA(0, 0), a2, voffA);
;             PG8_BAR; PG8_WAIT_L(0); PG8_MMA(1, 0, At, B0); PG8_BAR; PG8_SCHED;
;     ...
;             PG8_WAIT_L(8); PG8_BAR; PG8_WAIT_L(0); PG8_MMA(0, 0, At, B0); PG8_BAR; PG8_SCHED;
;             PG8_LDB(B1, 1, 1); PG8_STAGE(PG8_SB(1, 0), b3, voffB);
;             PG8_BAR; PG8_WAIT_L(0); PG8_MMA(0, 1, At, B1); PG8_BAR;
;             PG8_LDA(At, 1, 1); PG8_STAGE(PG8_SA(1, 0), a3, voffA);
;             PG8_BAR; PG8_WAIT_L(0); PG8_MMA(1, 0, At, B0); PG8_BAR; PG8_SCHED;
;             PG8_STAGE(PG8_SB(1, 1), b3 + hstep, voffB);
;             PG8_WAIT_V(6); PG8_BAR; PG8_MMA(1, 1, At, B1); PG8_BAR;
	v_mfma_f32_16x16x32_bf16 v[60:63], v[150:153], v[166:169], v[60:63]
	v_mfma_f32_16x16x32_bf16 v[56:59], v[158:161], v[166:169], v[56:59]
	v_mfma_f32_16x16x32_bf16 v[52:55], v[150:153], v[174:177], v[52:55]
	v_mfma_f32_16x16x32_bf16 v[44:47], v[158:161], v[174:177], v[44:47]
	v_mfma_f32_16x16x32_bf16 v[36:39], v[150:153], v[182:185], v[36:39]
	v_mfma_f32_16x16x32_bf16 v[28:31], v[158:161], v[182:185], v[28:31]
	v_mfma_f32_16x16x32_bf16 v[20:23], v[150:153], v[190:193], v[20:23]
	v_mfma_f32_16x16x32_bf16 v[12:15], v[158:161], v[190:193], v[12:15]
	v_mfma_f32_16x16x32_bf16 v[60:63], v[154:157], v[170:173], v[60:63]
	v_mfma_f32_16x16x32_bf16 v[56:59], v[162:165], v[170:173], v[56:59]
	v_mfma_f32_16x16x32_bf16 v[52:55], v[154:157], v[178:181], v[52:55]
	v_mfma_f32_16x16x32_bf16 v[44:47], v[162:165], v[178:181], v[44:47]
	v_mfma_f32_16x16x32_bf16 v[36:39], v[154:157], v[186:189], v[36:39]
	v_mfma_f32_16x16x32_bf16 v[28:31], v[162:165], v[186:189], v[28:31]
	v_mfma_f32_16x16x32_bf16 v[20:23], v[154:157], v[194:197], v[20:23]
	v_mfma_f32_16x16x32_bf16 v[12:15], v[162:165], v[194:197], v[12:15]
	s_barrier
	s_setprio 0
	s_add_u32 s34, s34, 0x40080
	s_addc_u32 s35, s35, 0
	s_add_i32 s36, s36, s43
	s_mov_b32 m0, s36
	s_nop 0
	global_load_lds_dwordx4 v130, s[34:35]
	s_add_i32 m0, s36, 0x2000
	s_nop 0
	global_load_lds_dwordx4 v134, s[34:35]
	s_waitcnt vmcnt(8)
	s_setprio 1
	s_barrier
	v_mfma_f32_16x16x32_bf16 v[48:51], v[202:205], v[166:169], v[48:51]
	v_mfma_f32_16x16x32_bf16 v[40:43], v[210:213], v[166:169], v[40:43]
	v_mfma_f32_16x16x32_bf16 v[32:35], v[202:205], v[174:177], v[32:35]
	v_mfma_f32_16x16x32_bf16 v[24:27], v[210:213], v[174:177], v[24:27]
	v_mfma_f32_16x16x32_bf16 v[16:19], v[202:205], v[182:185], v[16:19]
	v_mfma_f32_16x16x32_bf16 v[8:11], v[210:213], v[182:185], v[8:11]
	v_mfma_f32_16x16x32_bf16 v[4:7], v[202:205], v[190:193], v[4:7]
	v_mfma_f32_16x16x32_bf16 v[0:3], v[210:213], v[190:193], v[0:3]
	v_mfma_f32_16x16x32_bf16 v[48:51], v[206:209], v[170:173], v[48:51]
	v_mfma_f32_16x16x32_bf16 v[40:43], v[214:217], v[170:173], v[40:43]
	v_mfma_f32_16x16x32_bf16 v[32:35], v[206:209], v[178:181], v[32:35]
	v_mfma_f32_16x16x32_bf16 v[24:27], v[214:217], v[178:181], v[24:27]
	v_mfma_f32_16x16x32_bf16 v[16:19], v[206:209], v[186:189], v[16:19]
	v_mfma_f32_16x16x32_bf16 v[8:11], v[214:217], v[186:189], v[8:11]
	v_mfma_f32_16x16x32_bf16 v[4:7], v[206:209], v[194:197], v[4:7]
	v_mfma_f32_16x16x32_bf16 v[0:3], v[214:217], v[194:197], v[0:3]
	s_add_i32 s65, s65, 2
	s_add_u32 s30, s30, 0x100
	s_addc_u32 s31, s31, 0
	s_add_u32 s63, s63, 0x100
	s_addc_u32 s64, s64, 0
	s_cmp_gt_u32 s65, 13
	s_barrier
	s_setprio 0
.LBB0_633:
	ds_read_b128 v[150:153], v147
	ds_read_b128 v[154:157], v147 offset:1024
	ds_read_b128 v[158:161], v147 offset:2048
	ds_read_b128 v[162:165], v147 offset:3072
	s_add_u32 s34, s30, 0xfffc0080
	s_addc_u32 s35, s31, -1
	s_cmp_eq_u32 s65, 12
	s_cselect_b32 s37, s23, s35
	s_cselect_b32 s36, s61, s34
	s_cselect_b32 s35, s21, s64
	s_cselect_b32 s34, s62, s63
	s_add_i32 m0, s29, 0xc000
	ds_read_b128 v[166:169], v148
	ds_read_b128 v[170:173], v148 offset:1024
	ds_read_b128 v[174:177], v148 offset:2048
	ds_read_b128 v[178:181], v148 offset:3072
	ds_read_b128 v[182:185], v148 offset:4096
	ds_read_b128 v[186:189], v148 offset:5120
	ds_read_b128 v[190:193], v148 offset:6144
	ds_read_b128 v[194:197], v148 offset:7168
	global_load_lds_dwordx4 v136, s[30:31]
	s_add_i32 m0, s29, 0xe000
	s_nop 0
	global_load_lds_dwordx4 v138, s[30:31]
	s_waitcnt lgkmcnt(8)
	s_waitcnt vmcnt(8)
	s_waitcnt lgkmcnt(0)
	s_setprio 1
	s_barrier
	v_mfma_f32_16x16x32_bf16 v[124:127], v[150:153], v[166:169], v[124:127]
	v_mfma_f32_16x16x32_bf16 v[120:123], v[158:161], v[166:169], v[120:123]
	v_mfma_f32_16x16x32_bf16 v[116:119], v[150:153], v[174:177], v[116:119]
	v_mfma_f32_16x16x32_bf16 v[108:111], v[158:161], v[174:177], v[108:111]
	v_mfma_f32_16x16x32_bf16 v[100:103], v[150:153], v[182:185], v[100:103]
	v_mfma_f32_16x16x32_bf16 v[92:95], v[158:161], v[182:185], v[92:95]
	v_mfma_f32_16x16x32_bf16 v[84:87], v[150:153], v[190:193], v[84:87]
	v_mfma_f32_16x16x32_bf16 v[76:79], v[158:161], v[190:193], v[76:79]
	v_mfma_f32_16x16x32_bf16 v[124:127], v[154:157], v[170:173], v[124:127]
	v_mfma_f32_16x16x32_bf16 v[120:123], v[162:165], v[170:173], v[120:123]
	v_mfma_f32_16x16x32_bf16 v[116:119], v[154:157], v[178:181], v[116:119]
	v_mfma_f32_16x16x32_bf16 v[108:111], v[162:165], v[178:181], v[108:111]
	v_mfma_f32_16x16x32_bf16 v[100:103], v[154:157], v[186:189], v[100:103]
	v_mfma_f32_16x16x32_bf16 v[92:95], v[162:165], v[186:189], v[92:95]
	v_mfma_f32_16x16x32_bf16 v[84:87], v[154:157], v[194:197], v[84:87]
	v_mfma_f32_16x16x32_bf16 v[76:79], v[162:165], v[194:197], v[76:79]
	s_barrier
	s_setprio 0
	s_add_i32 s66, s54, s43
	s_mov_b32 m0, s66
	ds_read_b128 v[202:205], v149
	ds_read_b128 v[206:209], v149 offset:1024
	ds_read_b128 v[210:213], v149 offset:2048
	ds_read_b128 v[214:217], v149 offset:3072
	global_load_lds_dwordx4 v130, s[34:35]
	s_add_i32 m0, s66, 0x2000
	s_nop 0
	global_load_lds_dwordx4 v134, s[34:35]
	s_waitcnt vmcnt(8)
	s_waitcnt lgkmcnt(0)
	s_setprio 1
	s_barrier
; #define PG8_STAGE(bufoff, gbase, voff) do { _Pragma("unroll") for (int _i = 0; _i < 2; ++_i) \
;         __builtin_amdgcn_global_load_lds((const unsigned*)((const char*)(gbase) + (voff)[_i]), (LAS unsigned*)(lds + (bufoff) + ldsw + _i * 8192), 16, 0, 0); } while (0)
; #define PG8_LDA(dst, b, h) do { _Pragma("unroll") for (int m = 0; m < 4; ++m) _Pragma("unroll") for (int k = 0; k < 2; ++k) dst[m][k] = *(const LAS bf16x8*)(lds + PG8_SA(b, h) + aoff + m * 2048 + k * 1024); } while (0)
; #define PG8_LDB(dst, b, h) do { _Pragma("unroll") for (int n = 0; n < 2; ++n) _Pragma("unroll") for (int k = 0; k < 2; ++k) dst[n][k] = *(const LAS bf16x8*)(lds + PG8_SB(b, h) + boff + n * 2048 + k * 1024); } while (0)
; #define PG8_MMA(ai, bj, At, Bt) do { __builtin_amdgcn_s_setprio(1); _Pragma("unroll") for (int m = 0; m < 4; ++m) _Pragma("unroll") for (int n = 0; n < 2; ++n) _Pragma("unroll") for (int k = 0; k < 2; ++k) \
;         acc[ai][bj][m][n] = __builtin_amdgcn_mfma_f32_16x16x32_bf16(Bt[n][k], At[m][k], acc[ai][bj][m][n], 0, 0, 0); __builtin_amdgcn_s_setprio(0); } while (0)
; #define PG8_WAIT_V(n) asm volatile("s_waitcnt vmcnt(" #n ")" ::: "memory")
; #define PG8_WAIT_L(n) asm volatile("s_waitcnt lgkmcnt(" #n ")" ::: "memory")
; #define PG8_BAR __builtin_amdgcn_s_barrier()
; #define PG8_SCHED __builtin_amdgcn_sched_barrier(0)
; template <class Epi, class Sched>
; __device__ __forceinline__ void gemm_phase(LAS unsigned char* lds, const Gemm g, const Sched& S, const Epi& E) {
;     ...
;             PG8_WAIT_L(8); PG8_BAR; PG8_WAIT_L(0); PG8_MMA(0, 0, At, B0); PG8_BAR; PG8_SCHED;
;             PG8_LDB(B1, 0, 1); PG8_STAGE(PG8_SB(0, 0), b2, voffB);
;             PG8_BAR; PG8_WAIT_L(0); PG8_MMA(0, 1, At, B1); PG8_BAR;
;             PG8_LDA(At, 0, 1); PG8_STAGE(PG8_SA(0, 0), a2, voffA);
;             PG8_BAR; PG8_WAIT_L(0); PG8_MMA(1, 0, At, B0); PG8_BAR; PG8_SCHED;
;             PG8_STAGE(PG8_SB(0, 1), b2 + hstep, voffB);
;             PG8_WAIT_V(6); PG8_BAR; PG8_MMA(1, 1, At, B1); PG8_BAR;
;             PG8_LDB(B0, 1, 0); PG8_SCHED; PG8_LDA(At, 1, 0); PG8_STAGE(PG8_SA(0, 1), a2 + hstep, voffA);
;             PG8_WAIT_L(8); PG8_BAR; PG8_WAIT_L(0); PG8_MMA(0, 0, At, B0); PG8_BAR; PG8_SCHED;
	v_mfma_f32_16x16x32_bf16 v[112:115], v[202:205], v[166:169], v[112:115]
	v_mfma_f32_16x16x32_bf16 v[104:107], v[210:213], v[166:169], v[104:107]
	v_mfma_f32_16x16x32_bf16 v[96:99], v[202:205], v[174:177], v[96:99]
	v_mfma_f32_16x16x32_bf16 v[88:91], v[210:213], v[174:177], v[88:91]
	v_mfma_f32_16x16x32_bf16 v[80:83], v[202:205], v[182:185], v[80:83]
	v_mfma_f32_16x16x32_bf16 v[72:75], v[210:213], v[182:185], v[72:75]
	v_mfma_f32_16x16x32_bf16 v[68:71], v[202:205], v[190:193], v[68:71]
	v_mfma_f32_16x16x32_bf16 v[64:67], v[210:213], v[190:193], v[64:67]
	v_mfma_f32_16x16x32_bf16 v[112:115], v[206:209], v[170:173], v[112:115]
	v_mfma_f32_16x16x32_bf16 v[104:107], v[214:217], v[170:173], v[104:107]
	v_mfma_f32_16x16x32_bf16 v[96:99], v[206:209], v[178:181], v[96:99]
	v_mfma_f32_16x16x32_bf16 v[88:91], v[214:217], v[178:181], v[88:91]
	v_mfma_f32_16x16x32_bf16 v[80:83], v[206:209], v[186:189], v[80:83]
	v_mfma_f32_16x16x32_bf16 v[72:75], v[214:217], v[186:189], v[72:75]
	v_mfma_f32_16x16x32_bf16 v[68:71], v[206:209], v[194:197], v[68:71]
	v_mfma_f32_16x16x32_bf16 v[64:67], v[214:217], v[194:197], v[64:67]
	s_mov_b32 m0, s29
	v_lshl_add_u64 v[220:221], s[36:37], 0, v[128:129]
	s_barrier
	s_setprio 0
	ds_read_b128 v[166:169], v148 offset:16384
	ds_read_b128 v[170:173], v148 offset:17408
	ds_read_b128 v[174:177], v148 offset:18432
	ds_read_b128 v[178:181], v148 offset:19456
	ds_read_b128 v[182:185], v148 offset:20480
	ds_read_b128 v[186:189], v148 offset:21504
	ds_read_b128 v[190:193], v148 offset:22528
	ds_read_b128 v[194:197], v148 offset:23552
	global_load_lds_dwordx4 v128, s[36:37]
	v_lshl_add_u64 v[222:223], s[36:37], 0, v[132:133]
	s_mov_b32 m0, s44
	s_nop 0
	global_load_lds_dwordx4 v132, s[36:37]
	s_waitcnt lgkmcnt(0)
	s_setprio 1
	s_barrier
	v_mfma_f32_16x16x32_bf16 v[60:63], v[150:153], v[166:169], v[60:63]
	v_mfma_f32_16x16x32_bf16 v[56:59], v[158:161], v[166:169], v[56:59]
	v_mfma_f32_16x16x32_bf16 v[52:55], v[150:153], v[174:177], v[52:55]
	v_mfma_f32_16x16x32_bf16 v[44:47], v[158:161], v[174:177], v[44:47]
	v_mfma_f32_16x16x32_bf16 v[36:39], v[150:153], v[182:185], v[36:39]
	v_mfma_f32_16x16x32_bf16 v[28:31], v[158:161], v[182:185], v[28:31]
	v_mfma_f32_16x16x32_bf16 v[20:23], v[150:153], v[190:193], v[20:23]
	v_mfma_f32_16x16x32_bf16 v[12:15], v[158:161], v[190:193], v[12:15]
	v_mfma_f32_16x16x32_bf16 v[60:63], v[154:157], v[170:173], v[60:63]
	v_mfma_f32_16x16x32_bf16 v[56:59], v[162:165], v[170:173], v[56:59]
	v_mfma_f32_16x16x32_bf16 v[52:55], v[154:157], v[178:181], v[52:55]
	v_mfma_f32_16x16x32_bf16 v[44:47], v[162:165], v[178:181], v[44:47]
	v_mfma_f32_16x16x32_bf16 v[36:39], v[154:157], v[186:189], v[36:39]
	v_mfma_f32_16x16x32_bf16 v[28:31], v[162:165], v[186:189], v[28:31]
	v_mfma_f32_16x16x32_bf16 v[20:23], v[154:157], v[194:197], v[20:23]
	v_mfma_f32_16x16x32_bf16 v[12:15], v[162:165], v[194:197], v[12:15]
	s_barrier
	s_setprio 0
	s_add_u32 s66, s34, 0x40000
	s_addc_u32 s67, s35, 0
	s_add_i32 s68, s55, s43
	s_mov_b32 m0, s68
	s_nop 0
	global_load_lds_dwordx4 v130, s[66:67]
	s_add_i32 m0, s68, 0x2000
	s_nop 0
	global_load_lds_dwordx4 v134, s[66:67]
	s_add_u32 s36, s36, 0x40000
	s_addc_u32 s37, s37, 0
	s_mov_b32 m0, s45
	s_nop 0
	global_load_lds_dwordx4 v128, s[36:37]
	s_mov_b32 m0, s46
	s_nop 0
	global_load_lds_dwordx4 v132, s[36:37]
	s_waitcnt vmcnt(10)
	s_setprio 1
	s_barrier
	v_mfma_f32_16x16x32_bf16 v[48:51], v[202:205], v[166:169], v[48:51]
	v_mfma_f32_16x16x32_bf16 v[40:43], v[210:213], v[166:169], v[40:43]
	v_mfma_f32_16x16x32_bf16 v[32:35], v[202:205], v[174:177], v[32:35]
	v_mfma_f32_16x16x32_bf16 v[24:27], v[210:213], v[174:177], v[24:27]
	v_mfma_f32_16x16x32_bf16 v[16:19], v[202:205], v[182:185], v[16:19]
	v_mfma_f32_16x16x32_bf16 v[8:11], v[210:213], v[182:185], v[8:11]
	v_mfma_f32_16x16x32_bf16 v[4:7], v[202:205], v[190:193], v[4:7]
	v_mfma_f32_16x16x32_bf16 v[0:3], v[210:213], v[190:193], v[0:3]
	v_mfma_f32_16x16x32_bf16 v[48:51], v[206:209], v[170:173], v[48:51]
	v_mfma_f32_16x16x32_bf16 v[40:43], v[214:217], v[170:173], v[40:43]
	v_mfma_f32_16x16x32_bf16 v[32:35], v[206:209], v[178:181], v[32:35]
	v_mfma_f32_16x16x32_bf16 v[24:27], v[214:217], v[178:181], v[24:27]
	v_mfma_f32_16x16x32_bf16 v[16:19], v[206:209], v[186:189], v[16:19]
	v_mfma_f32_16x16x32_bf16 v[8:11], v[214:217], v[186:189], v[8:11]
	v_mfma_f32_16x16x32_bf16 v[4:7], v[206:209], v[194:197], v[4:7]
	v_mfma_f32_16x16x32_bf16 v[0:3], v[214:217], v[194:197], v[0:3]
	s_add_i32 s66, 0, 0x18000
	v_add_u32_e32 v162, s66, v146
	s_barrier
	s_setprio 0
	ds_read_b128 v[150:153], v162
	ds_read_b128 v[154:157], v162 offset:1024
	ds_read_b128 v[158:161], v162 offset:2048
	ds_read_b128 v[162:165], v162 offset:3072
	ds_read_b128 v[166:169], v148 offset:32768
	ds_read_b128 v[170:173], v148 offset:33792
	ds_read_b128 v[174:177], v148 offset:34816
	ds_read_b128 v[178:181], v148 offset:35840
	ds_read_b128 v[182:185], v148 offset:36864
	ds_read_b128 v[186:189], v148 offset:37888
	ds_read_b128 v[190:193], v148 offset:38912
	ds_read_b128 v[194:197], v148 offset:39936
	s_waitcnt lgkmcnt(8)
	s_waitcnt vmcnt(8)
	s_waitcnt lgkmcnt(0)
	s_setprio 1
	s_barrier
; #define PG8_STAGE(bufoff, gbase, voff) do { _Pragma("unroll") for (int _i = 0; _i < 2; ++_i) \
;         __builtin_amdgcn_global_load_lds((const unsigned*)((const char*)(gbase) + (voff)[_i]), (LAS unsigned*)(lds + (bufoff) + ldsw + _i * 8192), 16, 0, 0); } while (0)
; #define PG8_LDA(dst, b, h) do { _Pragma("unroll") for (int m = 0; m < 4; ++m) _Pragma("unroll") for (int k = 0; k < 2; ++k) dst[m][k] = *(const LAS bf16x8*)(lds + PG8_SA(b, h) + aoff + m * 2048 + k * 1024); } while (0)
; #define PG8_LDB(dst, b, h) do { _Pragma("unroll") for (int n = 0; n < 2; ++n) _Pragma("unroll") for (int k = 0; k < 2; ++k) dst[n][k] = *(const LAS bf16x8*)(lds + PG8_SB(b, h) + boff + n * 2048 + k * 1024); } while (0)
; #define PG8_MMA(ai, bj, At, Bt) do { __builtin_amdgcn_s_setprio(1); _Pragma("unroll") for (int m = 0; m < 4; ++m) _Pragma("unroll") for (int n = 0; n < 2; ++n) _Pragma("unroll") for (int k = 0; k < 2; ++k) \
;         acc[ai][bj][m][n] = __builtin_amdgcn_mfma_f32_16x16x32_bf16(Bt[n][k], At[m][k], acc[ai][bj][m][n], 0, 0, 0); __builtin_amdgcn_s_setprio(0); } while (0)
; #define PG8_WAIT_V(n) asm volatile("s_waitcnt vmcnt(" #n ")" ::: "memory")
; #define PG8_WAIT_L(n) asm volatile("s_waitcnt lgkmcnt(" #n ")" ::: "memory")
; #define PG8_BAR __builtin_amdgcn_s_barrier()
; #define PG8_SCHED __builtin_amdgcn_sched_barrier(0)
; template <class Epi, class Sched>
; __device__ __forceinline__ void gemm_phase(LAS unsigned char* lds, const Gemm g, const Sched& S, const Epi& E) {
;     ...
;             PG8_WAIT_L(8); PG8_BAR; PG8_WAIT_L(0); PG8_MMA(0, 0, At, B0); PG8_BAR; PG8_SCHED;
;             PG8_LDB(B1, 1, 1); PG8_STAGE(PG8_SB(1, 0), b3, voffB);
;             PG8_BAR; PG8_WAIT_L(0); PG8_MMA(0, 1, At, B1); PG8_BAR;
;             PG8_LDA(At, 1, 1); PG8_STAGE(PG8_SA(1, 0), a3, voffA);
;             PG8_BAR; PG8_WAIT_L(0); PG8_MMA(1, 0, At, B0); PG8_BAR; PG8_SCHED;
;             PG8_STAGE(PG8_SB(1, 1), b3 + hstep, voffB);
;             PG8_WAIT_V(6); PG8_BAR; PG8_MMA(1, 1, At, B1); PG8_BAR;
	v_mfma_f32_16x16x32_bf16 v[124:127], v[150:153], v[166:169], v[124:127]
	v_mfma_f32_16x16x32_bf16 v[120:123], v[158:161], v[166:169], v[120:123]
	v_mfma_f32_16x16x32_bf16 v[116:119], v[150:153], v[174:177], v[116:119]
	v_mfma_f32_16x16x32_bf16 v[108:111], v[158:161], v[174:177], v[108:111]
	v_mfma_f32_16x16x32_bf16 v[100:103], v[150:153], v[182:185], v[100:103]
	v_mfma_f32_16x16x32_bf16 v[92:95], v[158:161], v[182:185], v[92:95]
	v_mfma_f32_16x16x32_bf16 v[84:87], v[150:153], v[190:193], v[84:87]
	v_mfma_f32_16x16x32_bf16 v[76:79], v[158:161], v[190:193], v[76:79]
	v_mfma_f32_16x16x32_bf16 v[124:127], v[154:157], v[170:173], v[124:127]
	v_mfma_f32_16x16x32_bf16 v[120:123], v[162:165], v[170:173], v[120:123]
	v_mfma_f32_16x16x32_bf16 v[116:119], v[154:157], v[178:181], v[116:119]
	v_mfma_f32_16x16x32_bf16 v[108:111], v[162:165], v[178:181], v[108:111]
	v_mfma_f32_16x16x32_bf16 v[100:103], v[154:157], v[186:189], v[100:103]
	v_mfma_f32_16x16x32_bf16 v[92:95], v[162:165], v[186:189], v[92:95]
	v_mfma_f32_16x16x32_bf16 v[84:87], v[154:157], v[194:197], v[84:87]
	v_mfma_f32_16x16x32_bf16 v[76:79], v[162:165], v[194:197], v[76:79]
	s_barrier
	s_setprio 0
	s_add_i32 s36, 0, 0x1c000
	s_add_i32 s37, s66, s43
	v_add_u32_e32 v214, s36, v146
	s_add_u32 s4, s34, 0x80
	s_addc_u32 s5, s35, 0
	s_mov_b32 m0, s37
	ds_read_b128 v[202:205], v214
	ds_read_b128 v[206:209], v214 offset:1024
	ds_read_b128 v[210:213], v214 offset:2048
	ds_read_b128 v[214:217], v214 offset:3072
	global_load_lds_dwordx4 v130, s[4:5]
	s_add_i32 m0, s37, 0x2000
	s_nop 0
	global_load_lds_dwordx4 v134, s[4:5]
	s_waitcnt vmcnt(8)
	s_waitcnt lgkmcnt(0)
	s_setprio 1
	s_barrier
	v_mfma_f32_16x16x32_bf16 v[112:115], v[202:205], v[166:169], v[112:115]
	v_mfma_f32_16x16x32_bf16 v[104:107], v[210:213], v[166:169], v[104:107]
	v_mfma_f32_16x16x32_bf16 v[96:99], v[202:205], v[174:177], v[96:99]
	v_mfma_f32_16x16x32_bf16 v[88:91], v[210:213], v[174:177], v[88:91]
	v_mfma_f32_16x16x32_bf16 v[80:83], v[202:205], v[182:185], v[80:83]
	v_mfma_f32_16x16x32_bf16 v[72:75], v[210:213], v[182:185], v[72:75]
	v_mfma_f32_16x16x32_bf16 v[68:71], v[202:205], v[190:193], v[68:71]
	v_mfma_f32_16x16x32_bf16 v[64:67], v[210:213], v[190:193], v[64:67]
	v_mfma_f32_16x16x32_bf16 v[112:115], v[206:209], v[170:173], v[112:115]
	v_mfma_f32_16x16x32_bf16 v[104:107], v[214:217], v[170:173], v[104:107]
	v_mfma_f32_16x16x32_bf16 v[96:99], v[206:209], v[178:181], v[96:99]
	v_mfma_f32_16x16x32_bf16 v[88:91], v[214:217], v[178:181], v[88:91]
	v_mfma_f32_16x16x32_bf16 v[80:83], v[206:209], v[186:189], v[80:83]
	v_mfma_f32_16x16x32_bf16 v[72:75], v[214:217], v[186:189], v[72:75]
	v_mfma_f32_16x16x32_bf16 v[68:71], v[206:209], v[194:197], v[68:71]
	v_mfma_f32_16x16x32_bf16 v[64:67], v[214:217], v[194:197], v[64:67]
	s_mov_b32 m0, s51
	s_mov_b64 s[4:5], 0x80
	v_lshl_add_u64 v[198:199], v[220:221], 0, s[4:5]
	s_barrier
	s_setprio 0
	ds_read_b128 v[166:169], v148 offset:49152
	ds_read_b128 v[170:173], v148 offset:50176
	ds_read_b128 v[174:177], v148 offset:51200
	ds_read_b128 v[178:181], v148 offset:52224
	ds_read_b128 v[182:185], v148 offset:53248
	ds_read_b128 v[186:189], v148 offset:54272
	ds_read_b128 v[190:193], v148 offset:55296
	ds_read_b128 v[194:197], v148 offset:56320
	global_load_lds_dwordx4 v[198:199], off
	v_lshl_add_u64 v[198:199], v[222:223], 0, s[4:5]
	s_mov_b32 m0, s52
	s_nop 0
	global_load_lds_dwordx4 v[198:199], off
	s_waitcnt lgkmcnt(0)
	s_setprio 1
	s_barrier
	v_mfma_f32_16x16x32_bf16 v[60:63], v[150:153], v[166:169], v[60:63]
	v_mfma_f32_16x16x32_bf16 v[56:59], v[158:161], v[166:169], v[56:59]
	v_mfma_f32_16x16x32_bf16 v[52:55], v[150:153], v[174:177], v[52:55]
	v_mfma_f32_16x16x32_bf16 v[44:47], v[158:161], v[174:177], v[44:47]
	v_mfma_f32_16x16x32_bf16 v[36:39], v[150:153], v[182:185], v[36:39]
	v_mfma_f32_16x16x32_bf16 v[28:31], v[158:161], v[182:185], v[28:31]
	v_mfma_f32_16x16x32_bf16 v[20:23], v[150:153], v[190:193], v[20:23]
	v_mfma_f32_16x16x32_bf16 v[12:15], v[158:161], v[190:193], v[12:15]
	v_mfma_f32_16x16x32_bf16 v[60:63], v[154:157], v[170:173], v[60:63]
	v_mfma_f32_16x16x32_bf16 v[56:59], v[162:165], v[170:173], v[56:59]
	v_mfma_f32_16x16x32_bf16 v[52:55], v[154:157], v[178:181], v[52:55]
	v_mfma_f32_16x16x32_bf16 v[44:47], v[162:165], v[178:181], v[44:47]
	v_mfma_f32_16x16x32_bf16 v[36:39], v[154:157], v[186:189], v[36:39]
	v_mfma_f32_16x16x32_bf16 v[28:31], v[162:165], v[186:189], v[28:31]
	v_mfma_f32_16x16x32_bf16 v[20:23], v[154:157], v[194:197], v[20:23]
	v_mfma_f32_16x16x32_bf16 v[12:15], v[162:165], v[194:197], v[12:15]
	s_barrier
	s_setprio 0
	s_add_u32 s34, s34, 0x40080
	s_addc_u32 s35, s35, 0
	s_add_i32 s36, s36, s43
	s_mov_b32 m0, s36
	s_nop 0
	global_load_lds_dwordx4 v130, s[34:35]
	s_add_i32 m0, s36, 0x2000
	s_nop 0
	global_load_lds_dwordx4 v134, s[34:35]
	s_waitcnt vmcnt(8)
	s_setprio 1
	s_barrier
; __device__ __forceinline__ unsigned cvt_pk_bf16(float lo, float hi) { unsigned r; asm volatile("v_cvt_pk_bf16_f32 %0, %1, %2" : "=v"(r) : "v"(lo), "v"(hi)); return r; }
; #define PG8_MMA(ai, bj, At, Bt) do { __builtin_amdgcn_s_setprio(1); _Pragma("unroll") for (int m = 0; m < 4; ++m) _Pragma("unroll") for (int n = 0; n < 2; ++n) _Pragma("unroll") for (int k = 0; k < 2; ++k) \
;         acc[ai][bj][m][n] = __builtin_amdgcn_mfma_f32_16x16x32_bf16(Bt[n][k], At[m][k], acc[ai][bj][m][n], 0, 0, 0); __builtin_amdgcn_s_setprio(0); } while (0)
; #define PG8_WAIT_V(n) asm volatile("s_waitcnt vmcnt(" #n ")" ::: "memory")
; #define PG8_BAR __builtin_amdgcn_s_barrier()
; template <class Epi, class Sched>
; __device__ __forceinline__ void gemm_phase(LAS unsigned char* lds, const Gemm g, const Sched& S, const Epi& E) {
;     ...
;             PG8_WAIT_V(6); PG8_BAR; PG8_MMA(1, 1, At, B1); PG8_BAR;
;         }
;         E(acc, cur, wr, wc, fr, fq);
;     __device__ __forceinline__ void operator()(const AccT& acc, const Unit& u, int wr, int wc, int fr, int fq) const {
;     ...
;         const int rbase = u.pm * 256 + wr * 64 + fr;
;         const int tb = u.pn * 256 + wc * 32 + 8 * fq;
; #pragma unroll
;         for (int ai = 0; ai < 2; ++ai)
; #pragma unroll
;             for (int m = 0; m < 4; ++m) {
;                 const int r = rbase + ai * 128 + m * 16;
; #pragma unroll
;                 for (int bj = 0; bj < 2; ++bj) {
;                     const int t0 = tb + bj * 128;
;                     const f32x4 v0 = acc[ai][bj][m][0], v1 = acc[ai][bj][m][1];
;                     u32x4 w; w.x = cvt_pk_bf16(v0[0], v0[1]); w.y = cvt_pk_bf16(v0[2], v0[3]); w.z = cvt_pk_bf16(v1[0], v1[1]); w.w = cvt_pk_bf16(v1[2], v1[3]);
;                     *(u32x4*)(VT + (size_t)r * NT + t0) = w;
;                 }
;             }
;     }
	v_mfma_f32_16x16x32_bf16 v[48:51], v[202:205], v[166:169], v[48:51]
	v_mfma_f32_16x16x32_bf16 v[40:43], v[210:213], v[166:169], v[40:43]
	v_mfma_f32_16x16x32_bf16 v[32:35], v[202:205], v[174:177], v[32:35]
	v_mfma_f32_16x16x32_bf16 v[24:27], v[210:213], v[174:177], v[24:27]
	v_mfma_f32_16x16x32_bf16 v[16:19], v[202:205], v[182:185], v[16:19]
	v_mfma_f32_16x16x32_bf16 v[8:11], v[210:213], v[182:185], v[8:11]
	v_mfma_f32_16x16x32_bf16 v[4:7], v[202:205], v[190:193], v[4:7]
	v_mfma_f32_16x16x32_bf16 v[0:3], v[210:213], v[190:193], v[0:3]
	v_mfma_f32_16x16x32_bf16 v[48:51], v[206:209], v[170:173], v[48:51]
	v_mfma_f32_16x16x32_bf16 v[40:43], v[214:217], v[170:173], v[40:43]
	v_mfma_f32_16x16x32_bf16 v[32:35], v[206:209], v[178:181], v[32:35]
	v_mfma_f32_16x16x32_bf16 v[24:27], v[214:217], v[178:181], v[24:27]
	v_mfma_f32_16x16x32_bf16 v[16:19], v[206:209], v[186:189], v[16:19]
	v_mfma_f32_16x16x32_bf16 v[8:11], v[214:217], v[186:189], v[8:11]
	v_mfma_f32_16x16x32_bf16 v[4:7], v[206:209], v[194:197], v[4:7]
	v_mfma_f32_16x16x32_bf16 v[0:3], v[214:217], v[194:197], v[0:3]
	s_add_i32 s65, s65, 2
	s_add_u32 s30, s30, 0x100
	s_addc_u32 s31, s31, 0
	s_add_u32 s63, s63, 0x100
	s_addc_u32 s64, s64, 0
	s_cmp_gt_u32 s65, 13
	s_barrier
	s_setprio 0
	s_cbranch_scc0 .LBB0_633
	v_mov_b32_e32 v150, v144
	v_mov_b32_e32 v151, v145
	s_lshl_b32 s21, s28, 8
	s_add_i32 s21, s21, s48
	v_add_u32_e32 v150, s21, v150
	s_lshl_b32 s21, s60, 8
	s_or_b32 s21, s21, s49
	v_lshl_add_u32 v152, v151, 3, s21
	v_ashrrev_i32_e32 v151, 31, v150
	v_cvt_pk_bf16_f32 v124, v124, v125
	v_cvt_pk_bf16_f32 v125, v126, v127
	v_cvt_pk_bf16_f32 v126, v120, v121
	v_lshlrev_b64 v[120:121], 17, v[150:151]
	v_lshl_add_u64 v[120:121], s[0:1], 0, v[120:121]
	v_ashrrev_i32_e32 v153, 31, v152
	v_lshl_add_u64 v[120:121], v[152:153], 1, v[120:121]
	s_mov_b32 s21, 0x200000
	v_cvt_pk_bf16_f32 v127, v122, v123
	global_store_dwordx4 v[120:121], v[124:127], off
	v_cvt_pk_bf16_f32 v112, v112, v113
	v_cvt_pk_bf16_f32 v113, v114, v115
	v_cvt_pk_bf16_f32 v114, v104, v105
	v_cvt_pk_bf16_f32 v115, v106, v107
	global_store_dwordx4 v[120:121], v[112:115], off offset:256
	v_cvt_pk_bf16_f32 v104, v116, v117
	v_cvt_pk_bf16_f32 v105, v118, v119
	v_cvt_pk_bf16_f32 v106, v108, v109
	v_cvt_pk_bf16_f32 v107, v110, v111
	s_mov_b64 s[30:31], 0x200000
	v_add_co_u32_e32 v110, vcc, s21, v120
	v_lshl_add_u64 v[108:109], v[120:121], 0, s[30:31]
	s_nop 0
	v_addc_co_u32_e32 v111, vcc, 0, v121, vcc
	s_mov_b32 s21, 0x400000
	global_store_dwordx4 v[110:111], v[104:107], off
	v_cvt_pk_bf16_f32 v96, v96, v97
	v_cvt_pk_bf16_f32 v97, v98, v99
	v_cvt_pk_bf16_f32 v98, v88, v89
	v_cvt_pk_bf16_f32 v99, v90, v91
	global_store_dwordx4 v[108:109], v[96:99], off offset:256
	v_cvt_pk_bf16_f32 v88, v100, v101
	v_cvt_pk_bf16_f32 v89, v102, v103
	v_cvt_pk_bf16_f32 v90, v92, v93
	v_cvt_pk_bf16_f32 v91, v94, v95
	s_mov_b64 s[30:31], 0x400000
	v_add_co_u32_e32 v94, vcc, s21, v120
	v_lshl_add_u64 v[92:93], v[120:121], 0, s[30:31]
	s_nop 0
	v_addc_co_u32_e32 v95, vcc, 0, v121, vcc
	s_mov_b32 s21, 0x600000
	global_store_dwordx4 v[94:95], v[88:91], off
	v_cvt_pk_bf16_f32 v80, v80, v81
	v_cvt_pk_bf16_f32 v81, v82, v83
	v_cvt_pk_bf16_f32 v82, v72, v73
	v_cvt_pk_bf16_f32 v83, v74, v75
	global_store_dwordx4 v[92:93], v[80:83], off offset:256
	v_cvt_pk_bf16_f32 v72, v84, v85
	v_cvt_pk_bf16_f32 v73, v86, v87
	v_cvt_pk_bf16_f32 v74, v76, v77
	v_cvt_pk_bf16_f32 v75, v78, v79
	s_mov_b64 s[30:31], 0x600000
	v_add_co_u32_e32 v78, vcc, s21, v120
	v_lshl_add_u64 v[76:77], v[120:121], 0, s[30:31]
	s_nop 0
	v_addc_co_u32_e32 v79, vcc, 0, v121, vcc
	global_store_dwordx4 v[78:79], v[72:75], off
	v_cvt_pk_bf16_f32 v68, v68, v69
	v_cvt_pk_bf16_f32 v69, v70, v71
	v_cvt_pk_bf16_f32 v70, v64, v65
	v_cvt_pk_bf16_f32 v71, v66, v67
	global_store_dwordx4 v[76:77], v[68:71], off offset:256
	v_cvt_pk_bf16_f32 v60, v60, v61
	v_cvt_pk_bf16_f32 v61, v62, v63
	v_cvt_pk_bf16_f32 v62, v56, v57
	v_cvt_pk_bf16_f32 v63, v58, v59
	s_mov_b64 s[30:31], 0x1000000
	v_add_co_u32_e32 v58, vcc, s56, v120
	v_lshl_add_u64 v[56:57], v[120:121], 0, s[30:31]
	s_nop 0
	v_addc_co_u32_e32 v59, vcc, 0, v121, vcc
	global_store_dwordx4 v[58:59], v[60:63], off
	v_cvt_pk_bf16_f32 v48, v48, v49
	v_cvt_pk_bf16_f32 v49, v50, v51
	v_cvt_pk_bf16_f32 v50, v40, v41
	v_cvt_pk_bf16_f32 v51, v42, v43
	global_store_dwordx4 v[56:57], v[48:51], off offset:256
	v_cvt_pk_bf16_f32 v40, v52, v53
	v_cvt_pk_bf16_f32 v41, v54, v55
	v_cvt_pk_bf16_f32 v42, v44, v45
	v_cvt_pk_bf16_f32 v43, v46, v47
	v_add_co_u32_e32 v46, vcc, s57, v120
	v_lshl_add_u64 v[44:45], v[120:121], 0, s[6:7]
	s_nop 0
	v_addc_co_u32_e32 v47, vcc, 0, v121, vcc
	global_store_dwordx4 v[46:47], v[40:43], off
	v_cvt_pk_bf16_f32 v32, v32, v33
	v_cvt_pk_bf16_f32 v33, v34, v35
	v_cvt_pk_bf16_f32 v34, v24, v25
	v_cvt_pk_bf16_f32 v35, v26, v27
	global_store_dwordx4 v[44:45], v[32:35], off offset:256
	v_cvt_pk_bf16_f32 v24, v36, v37
	v_cvt_pk_bf16_f32 v25, v38, v39
	v_cvt_pk_bf16_f32 v26, v28, v29
	v_cvt_pk_bf16_f32 v27, v30, v31
	v_add_co_u32_e32 v30, vcc, s58, v120
	v_lshl_add_u64 v[28:29], v[120:121], 0, s[8:9]
	s_nop 0
	v_addc_co_u32_e32 v31, vcc, 0, v121, vcc
	global_store_dwordx4 v[30:31], v[24:27], off
	v_cvt_pk_bf16_f32 v16, v16, v17
	v_cvt_pk_bf16_f32 v17, v18, v19
	v_cvt_pk_bf16_f32 v18, v8, v9
	v_cvt_pk_bf16_f32 v19, v10, v11
	global_store_dwordx4 v[28:29], v[16:19], off offset:256
	v_cvt_pk_bf16_f32 v8, v20, v21
	v_cvt_pk_bf16_f32 v9, v22, v23
	v_cvt_pk_bf16_f32 v10, v12, v13
	v_cvt_pk_bf16_f32 v11, v14, v15
	v_add_co_u32_e32 v14, vcc, s59, v120
	v_lshl_add_u64 v[12:13], v[120:121], 0, s[16:17]
	s_nop 0
	v_addc_co_u32_e32 v15, vcc, 0, v121, vcc
	s_and_b64 vcc, exec, s[2:3]
	s_mov_b32 s60, s20
	s_mov_b32 s28, s22
	s_mov_b64 s[34:35], s[26:27]
	s_mov_b64 s[30:31], s[24:25]
	global_store_dwordx4 v[14:15], v[8:11], off
	v_cvt_pk_bf16_f32 v4, v4, v5
	v_cvt_pk_bf16_f32 v5, v6, v7
	v_cvt_pk_bf16_f32 v6, v0, v1
	v_cvt_pk_bf16_f32 v7, v2, v3
	global_store_dwordx4 v[12:13], v[4:7], off offset:256
	s_cbranch_vccz .LBB0_626
	s_waitcnt vmcnt(0)
	s_cmpk_gt_u32 s33, 0xff
	s_cbranch_scc1 .LBB0_637
	s_barrier

; #define PG8_STAGE(bufoff, gbase, voff) do { _Pragma("unroll") for (int _i = 0; _i < 2; ++_i) \
;         __builtin_amdgcn_global_load_lds((const unsigned*)((const char*)(gbase) + (voff)[_i]), (LAS unsigned*)(lds + (bufoff) + ldsw + _i * 8192), 16, 0, 0); } while (0)
; #define PG8_LDA(dst, b, h) do { _Pragma("unroll") for (int m = 0; m < 4; ++m) _Pragma("unroll") for (int k = 0; k < 2; ++k) dst[m][k] = *(const LAS bf16x8*)(lds + PG8_SA(b, h) + aoff + m * 2048 + k * 1024); } while (0)
; #define PG8_LDB(dst, b, h) do { _Pragma("unroll") for (int n = 0; n < 2; ++n) _Pragma("unroll") for (int k = 0; k < 2; ++k) dst[n][k] = *(const LAS bf16x8*)(lds + PG8_SB(b, h) + boff + n * 2048 + k * 1024); } while (0)
; #define PG8_WAIT_V(n) asm volatile("s_waitcnt vmcnt(" #n ")" ::: "memory")
; #define PG8_BAR __builtin_amdgcn_s_barrier()
; template <class Epi, class Sched>
; __device__ __forceinline__ void gemm_phase(LAS unsigned char* lds, const Gemm g, const Sched& S, const Epi& E) {
;     ...
;         const bool has_next = S.next(ui + 1, nxt);
;         const char* nA = has_next ? (const char*)g.A + (size_t)nxt.pm * tstep : cA; const char* nB = has_next ? (const char*)g.Bt + (size_t)nxt.pn * tstep : cB;
;         for (int t = 0; t < nt; t += 2) {
;             const bool last = (t == nt - 2);
;             const char* a1 = cA + (size_t)(t + 1) * kstep;
;             const char* a2 = last ? nA : cA + (size_t)(t + 2) * kstep; const char* b2 = last ? nB : cB + (size_t)(t + 2) * kstep;
;             const char* a3 = a2 + kstep; const char* b3 = b2 + kstep;
;             PG8_LDB(B0, 0, 0); PG8_SCHED; PG8_LDA(At, 0, 0); PG8_STAGE(PG8_SA(1, 1), a1 + hstep, voffA);
;             PG8_WAIT_L(8); PG8_BAR; PG8_WAIT_L(0); PG8_MMA(0, 0, At, B0); PG8_BAR; PG8_SCHED;
;             PG8_LDB(B1, 0, 1); PG8_STAGE(PG8_SB(0, 0), b2, voffB);
;             PG8_BAR; PG8_WAIT_L(0); PG8_MMA(0, 1, At, B1); PG8_BAR;
;             PG8_LDA(At, 0, 1); PG8_STAGE(PG8_SA(0, 0), a2, voffA);
;             PG8_BAR; PG8_WAIT_L(0); PG8_MMA(1, 0, At, B0); PG8_BAR; PG8_SCHED;
;             PG8_STAGE(PG8_SB(0, 1), b2 + hstep, voffB);
;             PG8_WAIT_V(6); PG8_BAR; PG8_MMA(1, 1, At, B1); PG8_BAR;
;             PG8_LDB(B0, 1, 0); PG8_SCHED; PG8_LDA(At, 1, 0); PG8_STAGE(PG8_SA(0, 1), a2 + hstep, voffA);
;             PG8_WAIT_L(8); PG8_BAR; PG8_WAIT_L(0); PG8_MMA(0, 0, At, B0); PG8_BAR; PG8_SCHED;
.LBB0_652:
	s_ashr_i32 s9, s8, 31
	v_cmp_lt_i64_e32 vcc, s[16:17], v[142:143]
	s_lshl_b64 s[16:17], s[8:9], 19
	s_add_u32 s16, s14, s16
	s_addc_u32 s17, s15, s17
	s_and_b64 s[18:19], vcc, exec
	s_cselect_b32 s9, s17, s23
	s_cselect_b32 s48, s16, s22
	s_ashr_i32 s7, s6, 31
	s_lshl_b64 s[18:19], s[6:7], 19
	s_add_u32 s18, s12, s18
	s_addc_u32 s19, s13, s19
	s_and_b64 s[26:27], vcc, exec
	s_cselect_b32 s7, s19, s25
	s_cselect_b32 s49, s18, s24
	s_add_u32 s22, s22, 0x40080
	s_addc_u32 s23, s23, 0
	s_add_u32 s51, s24, 0x100
	s_addc_u32 s52, s25, 0
	s_mov_b32 s53, -2
	s_waitcnt lgkmcnt(0)
	ds_read_b128 v[152:155], v149
	ds_read_b128 v[156:159], v149 offset:1024
	ds_read_b128 v[160:163], v149 offset:2048
	ds_read_b128 v[164:167], v149 offset:3072
	s_add_u32 s24, s22, 0xfffc0080
	s_addc_u32 s25, s23, -1
	s_cmp_eq_u32 s53, 12
	s_cselect_b32 s27, s9, s25
	s_cselect_b32 s26, s48, s24
	s_cselect_b32 s25, s7, s52
	s_cselect_b32 s24, s49, s51
	s_add_i32 m0, s21, 0xc000
	ds_read_b128 v[168:171], v150
	ds_read_b128 v[172:175], v150 offset:1024
	ds_read_b128 v[176:179], v150 offset:2048
	ds_read_b128 v[180:183], v150 offset:3072
	ds_read_b128 v[184:187], v150 offset:4096
	ds_read_b128 v[188:191], v150 offset:5120
	ds_read_b128 v[192:195], v150 offset:6144
	ds_read_b128 v[196:199], v150 offset:7168
	global_load_lds_dwordx4 v138, s[22:23]
	s_add_i32 m0, s21, 0xe000
	s_nop 0
	global_load_lds_dwordx4 v140, s[22:23]
	s_waitcnt lgkmcnt(8)
	s_waitcnt vmcnt(8)
	s_waitcnt lgkmcnt(0)
	s_setprio 1
	s_barrier
	v_mfma_f32_16x16x32_bf16 v[124:127], v[152:155], v[168:171], 0
	v_mfma_f32_16x16x32_bf16 v[120:123], v[160:163], v[168:171], 0
	v_mfma_f32_16x16x32_bf16 v[112:115], v[152:155], v[176:179], 0
	v_mfma_f32_16x16x32_bf16 v[104:107], v[160:163], v[176:179], 0
	v_mfma_f32_16x16x32_bf16 v[96:99], v[152:155], v[184:187], 0
	v_mfma_f32_16x16x32_bf16 v[88:91], v[160:163], v[184:187], 0
	v_mfma_f32_16x16x32_bf16 v[80:83], v[152:155], v[192:195], 0
	v_mfma_f32_16x16x32_bf16 v[72:75], v[160:163], v[192:195], 0
	v_mfma_f32_16x16x32_bf16 v[124:127], v[156:159], v[172:175], v[124:127]
	v_mfma_f32_16x16x32_bf16 v[120:123], v[164:167], v[172:175], v[120:123]
	v_mfma_f32_16x16x32_bf16 v[112:115], v[156:159], v[180:183], v[112:115]
	v_mfma_f32_16x16x32_bf16 v[104:107], v[164:167], v[180:183], v[104:107]
	v_mfma_f32_16x16x32_bf16 v[96:99], v[156:159], v[188:191], v[96:99]
	v_mfma_f32_16x16x32_bf16 v[88:91], v[164:167], v[188:191], v[88:91]
	v_mfma_f32_16x16x32_bf16 v[80:83], v[156:159], v[196:199], v[80:83]
	v_mfma_f32_16x16x32_bf16 v[72:75], v[164:167], v[196:199], v[72:75]
	s_barrier
	s_setprio 0
	s_add_i32 s54, s45, s30
	s_mov_b32 m0, s54
	ds_read_b128 v[202:205], v151
	ds_read_b128 v[206:209], v151 offset:1024
	ds_read_b128 v[210:213], v151 offset:2048
	ds_read_b128 v[214:217], v151 offset:3072
	global_load_lds_dwordx4 v130, s[24:25]
	s_add_i32 m0, s54, 0x2000
	s_nop 0
	global_load_lds_dwordx4 v134, s[24:25]
	s_waitcnt vmcnt(8)
	s_waitcnt lgkmcnt(0)
	s_setprio 1
	s_barrier
	v_mfma_f32_16x16x32_bf16 v[116:119], v[202:205], v[168:171], 0
	v_mfma_f32_16x16x32_bf16 v[108:111], v[210:213], v[168:171], 0
	v_mfma_f32_16x16x32_bf16 v[100:103], v[202:205], v[176:179], 0
	v_mfma_f32_16x16x32_bf16 v[92:95], v[210:213], v[176:179], 0
	v_mfma_f32_16x16x32_bf16 v[84:87], v[202:205], v[184:187], 0
	v_mfma_f32_16x16x32_bf16 v[76:79], v[210:213], v[184:187], 0
	v_mfma_f32_16x16x32_bf16 v[68:71], v[202:205], v[192:195], 0
	v_mfma_f32_16x16x32_bf16 v[64:67], v[210:213], v[192:195], 0
	v_mfma_f32_16x16x32_bf16 v[116:119], v[206:209], v[172:175], v[116:119]
	v_mfma_f32_16x16x32_bf16 v[108:111], v[214:217], v[172:175], v[108:111]
	v_mfma_f32_16x16x32_bf16 v[100:103], v[206:209], v[180:183], v[100:103]
	v_mfma_f32_16x16x32_bf16 v[92:95], v[214:217], v[180:183], v[92:95]
	v_mfma_f32_16x16x32_bf16 v[84:87], v[206:209], v[188:191], v[84:87]
	v_mfma_f32_16x16x32_bf16 v[76:79], v[214:217], v[188:191], v[76:79]
	v_mfma_f32_16x16x32_bf16 v[68:71], v[206:209], v[196:199], v[68:71]
	v_mfma_f32_16x16x32_bf16 v[64:67], v[214:217], v[196:199], v[64:67]
	s_mov_b32 m0, s21
	v_lshl_add_u64 v[222:223], s[26:27], 0, v[128:129]
	s_barrier
	s_setprio 0
	ds_read_b128 v[168:171], v150 offset:16384
	ds_read_b128 v[172:175], v150 offset:17408
	ds_read_b128 v[176:179], v150 offset:18432
	ds_read_b128 v[180:183], v150 offset:19456
	ds_read_b128 v[184:187], v150 offset:20480
	ds_read_b128 v[188:191], v150 offset:21504
	ds_read_b128 v[192:195], v150 offset:22528
	ds_read_b128 v[196:199], v150 offset:23552
	global_load_lds_dwordx4 v128, s[26:27]
	v_lshl_add_u64 v[224:225], s[26:27], 0, v[132:133]
	s_mov_b32 m0, s31
	s_nop 0
	global_load_lds_dwordx4 v132, s[26:27]
	s_waitcnt lgkmcnt(0)
	s_setprio 1
	s_barrier
	v_mfma_f32_16x16x32_bf16 v[60:63], v[152:155], v[168:171], 0
	v_mfma_f32_16x16x32_bf16 v[56:59], v[160:163], v[168:171], 0
	v_mfma_f32_16x16x32_bf16 v[48:51], v[152:155], v[176:179], 0
	v_mfma_f32_16x16x32_bf16 v[40:43], v[160:163], v[176:179], 0
	v_mfma_f32_16x16x32_bf16 v[32:35], v[152:155], v[184:187], 0
	v_mfma_f32_16x16x32_bf16 v[24:27], v[160:163], v[184:187], 0
	v_mfma_f32_16x16x32_bf16 v[16:19], v[152:155], v[192:195], 0
	v_mfma_f32_16x16x32_bf16 v[8:11], v[160:163], v[192:195], 0
	v_mfma_f32_16x16x32_bf16 v[60:63], v[156:159], v[172:175], v[60:63]
	v_mfma_f32_16x16x32_bf16 v[56:59], v[164:167], v[172:175], v[56:59]
	v_mfma_f32_16x16x32_bf16 v[48:51], v[156:159], v[180:183], v[48:51]
	v_mfma_f32_16x16x32_bf16 v[40:43], v[164:167], v[180:183], v[40:43]
	v_mfma_f32_16x16x32_bf16 v[32:35], v[156:159], v[188:191], v[32:35]
	v_mfma_f32_16x16x32_bf16 v[24:27], v[164:167], v[188:191], v[24:27]
	v_mfma_f32_16x16x32_bf16 v[16:19], v[156:159], v[196:199], v[16:19]
	v_mfma_f32_16x16x32_bf16 v[8:11], v[164:167], v[196:199], v[8:11]
	s_barrier
; #define PG8_STAGE(bufoff, gbase, voff) do { _Pragma("unroll") for (int _i = 0; _i < 2; ++_i) \
;         __builtin_amdgcn_global_load_lds((const unsigned*)((const char*)(gbase) + (voff)[_i]), (LAS unsigned*)(lds + (bufoff) + ldsw + _i * 8192), 16, 0, 0); } while (0)
; #define PG8_LDA(dst, b, h) do { _Pragma("unroll") for (int m = 0; m < 4; ++m) _Pragma("unroll") for (int k = 0; k < 2; ++k) dst[m][k] = *(const LAS bf16x8*)(lds + PG8_SA(b, h) + aoff + m * 2048 + k * 1024); } while (0)
; #define PG8_LDB(dst, b, h) do { _Pragma("unroll") for (int n = 0; n < 2; ++n) _Pragma("unroll") for (int k = 0; k < 2; ++k) dst[n][k] = *(const LAS bf16x8*)(lds + PG8_SB(b, h) + boff + n * 2048 + k * 1024); } while (0)
; #define PG8_MMA(ai, bj, At, Bt) do { __builtin_amdgcn_s_setprio(1); _Pragma("unroll") for (int m = 0; m < 4; ++m) _Pragma("unroll") for (int n = 0; n < 2; ++n) _Pragma("unroll") for (int k = 0; k < 2; ++k) \
;         acc[ai][bj][m][n] = __builtin_amdgcn_mfma_f32_16x16x32_bf16(Bt[n][k], At[m][k], acc[ai][bj][m][n], 0, 0, 0); __builtin_amdgcn_s_setprio(0); } while (0)
; #define PG8_WAIT_V(n) asm volatile("s_waitcnt vmcnt(" #n ")" ::: "memory")
; #define PG8_WAIT_L(n) asm volatile("s_waitcnt lgkmcnt(" #n ")" ::: "memory")
; #define PG8_BAR __builtin_amdgcn_s_barrier()
; #define PG8_SCHED __builtin_amdgcn_sched_barrier(0)
; template <class Epi, class Sched>
; __device__ __forceinline__ void gemm_phase(LAS unsigned char* lds, const Gemm g, const Sched& S, const Epi& E) {
;     ...
;             PG8_WAIT_V(6); PG8_BAR; PG8_MMA(1, 1, At, B1); PG8_BAR;
;             PG8_LDB(B0, 1, 0); PG8_SCHED; PG8_LDA(At, 1, 0); PG8_STAGE(PG8_SA(0, 1), a2 + hstep, voffA);
;             PG8_WAIT_L(8); PG8_BAR; PG8_WAIT_L(0); PG8_MMA(0, 0, At, B0); PG8_BAR; PG8_SCHED;
;             PG8_LDB(B1, 1, 1); PG8_STAGE(PG8_SB(1, 0), b3, voffB);
;             PG8_BAR; PG8_WAIT_L(0); PG8_MMA(0, 1, At, B1); PG8_BAR;
;             PG8_LDA(At, 1, 1); PG8_STAGE(PG8_SA(1, 0), a3, voffA);
;             PG8_BAR; PG8_WAIT_L(0); PG8_MMA(1, 0, At, B0); PG8_BAR; PG8_SCHED;
	s_setprio 0
	s_add_u32 s54, s24, 0x40000
	s_addc_u32 s55, s25, 0
	s_add_i32 s56, s46, s30
	s_mov_b32 m0, s56
	s_nop 0
	global_load_lds_dwordx4 v130, s[54:55]
	s_add_i32 m0, s56, 0x2000
	s_nop 0
	global_load_lds_dwordx4 v134, s[54:55]
	s_add_u32 s26, s26, 0x40000
	s_addc_u32 s27, s27, 0
	s_mov_b32 m0, s33
	s_nop 0
	global_load_lds_dwordx4 v128, s[26:27]
	s_mov_b32 m0, s34
	s_nop 0
	global_load_lds_dwordx4 v132, s[26:27]
	s_waitcnt vmcnt(10)
	s_setprio 1
	s_barrier
	v_mfma_f32_16x16x32_bf16 v[52:55], v[202:205], v[168:171], 0
	v_mfma_f32_16x16x32_bf16 v[44:47], v[210:213], v[168:171], 0
	v_mfma_f32_16x16x32_bf16 v[36:39], v[202:205], v[176:179], 0
	v_mfma_f32_16x16x32_bf16 v[28:31], v[210:213], v[176:179], 0
	v_mfma_f32_16x16x32_bf16 v[20:23], v[202:205], v[184:187], 0
	v_mfma_f32_16x16x32_bf16 v[12:15], v[210:213], v[184:187], 0
	v_mfma_f32_16x16x32_bf16 v[4:7], v[202:205], v[192:195], 0
	v_mfma_f32_16x16x32_bf16 v[0:3], v[210:213], v[192:195], 0
	v_mfma_f32_16x16x32_bf16 v[52:55], v[206:209], v[172:175], v[52:55]
	v_mfma_f32_16x16x32_bf16 v[44:47], v[214:217], v[172:175], v[44:47]
	v_mfma_f32_16x16x32_bf16 v[36:39], v[206:209], v[180:183], v[36:39]
	v_mfma_f32_16x16x32_bf16 v[28:31], v[214:217], v[180:183], v[28:31]
	v_mfma_f32_16x16x32_bf16 v[20:23], v[206:209], v[188:191], v[20:23]
	v_mfma_f32_16x16x32_bf16 v[12:15], v[214:217], v[188:191], v[12:15]
	v_mfma_f32_16x16x32_bf16 v[4:7], v[206:209], v[196:199], v[4:7]
	v_mfma_f32_16x16x32_bf16 v[0:3], v[214:217], v[196:199], v[0:3]
	s_add_i32 s54, 0, 0x18000
	v_add_u32_e32 v136, s54, v148
	s_barrier
	s_setprio 0
	ds_read_b128 v[152:155], v136
	ds_read_b128 v[156:159], v136 offset:1024
	ds_read_b128 v[160:163], v136 offset:2048
	ds_read_b128 v[164:167], v136 offset:3072
	ds_read_b128 v[168:171], v150 offset:32768
	ds_read_b128 v[172:175], v150 offset:33792
	ds_read_b128 v[176:179], v150 offset:34816
	ds_read_b128 v[180:183], v150 offset:35840
	ds_read_b128 v[184:187], v150 offset:36864
	ds_read_b128 v[188:191], v150 offset:37888
	ds_read_b128 v[192:195], v150 offset:38912
	ds_read_b128 v[196:199], v150 offset:39936
	s_waitcnt lgkmcnt(8)
	s_waitcnt vmcnt(8)
	s_waitcnt lgkmcnt(0)
	s_setprio 1
	s_barrier
	v_mfma_f32_16x16x32_bf16 v[124:127], v[152:155], v[168:171], v[124:127]
	v_mfma_f32_16x16x32_bf16 v[120:123], v[160:163], v[168:171], v[120:123]
	v_mfma_f32_16x16x32_bf16 v[112:115], v[152:155], v[176:179], v[112:115]
	v_mfma_f32_16x16x32_bf16 v[104:107], v[160:163], v[176:179], v[104:107]
	v_mfma_f32_16x16x32_bf16 v[96:99], v[152:155], v[184:187], v[96:99]
	v_mfma_f32_16x16x32_bf16 v[88:91], v[160:163], v[184:187], v[88:91]
	v_mfma_f32_16x16x32_bf16 v[80:83], v[152:155], v[192:195], v[80:83]
	v_mfma_f32_16x16x32_bf16 v[72:75], v[160:163], v[192:195], v[72:75]
	v_mfma_f32_16x16x32_bf16 v[124:127], v[156:159], v[172:175], v[124:127]
	v_mfma_f32_16x16x32_bf16 v[120:123], v[164:167], v[172:175], v[120:123]
	v_mfma_f32_16x16x32_bf16 v[112:115], v[156:159], v[180:183], v[112:115]
	v_mfma_f32_16x16x32_bf16 v[104:107], v[164:167], v[180:183], v[104:107]
	v_mfma_f32_16x16x32_bf16 v[96:99], v[156:159], v[188:191], v[96:99]
	v_mfma_f32_16x16x32_bf16 v[88:91], v[164:167], v[188:191], v[88:91]
	v_mfma_f32_16x16x32_bf16 v[80:83], v[156:159], v[196:199], v[80:83]
	v_mfma_f32_16x16x32_bf16 v[72:75], v[164:167], v[196:199], v[72:75]
	s_barrier
	s_setprio 0
	s_add_i32 s26, 0, 0x1c000
	s_add_i32 s27, s54, s30
	v_add_u32_e32 v136, s26, v148
	s_add_u32 s0, s24, 0x80
	s_addc_u32 s1, s25, 0
	s_mov_b32 m0, s27
	ds_read_b128 v[202:205], v136
	ds_read_b128 v[206:209], v136 offset:1024
	ds_read_b128 v[210:213], v136 offset:2048
	ds_read_b128 v[214:217], v136 offset:3072
	global_load_lds_dwordx4 v130, s[0:1]
	s_add_i32 m0, s27, 0x2000
	s_nop 0
	global_load_lds_dwordx4 v134, s[0:1]
	s_waitcnt vmcnt(8)
	s_waitcnt lgkmcnt(0)
	s_setprio 1
	s_barrier
	v_mfma_f32_16x16x32_bf16 v[116:119], v[202:205], v[168:171], v[116:119]
	v_mfma_f32_16x16x32_bf16 v[108:111], v[210:213], v[168:171], v[108:111]
	v_mfma_f32_16x16x32_bf16 v[100:103], v[202:205], v[176:179], v[100:103]
	v_mfma_f32_16x16x32_bf16 v[92:95], v[210:213], v[176:179], v[92:95]
	v_mfma_f32_16x16x32_bf16 v[84:87], v[202:205], v[184:187], v[84:87]
	v_mfma_f32_16x16x32_bf16 v[76:79], v[210:213], v[184:187], v[76:79]
	v_mfma_f32_16x16x32_bf16 v[68:71], v[202:205], v[192:195], v[68:71]
	v_mfma_f32_16x16x32_bf16 v[64:67], v[210:213], v[192:195], v[64:67]
	v_mfma_f32_16x16x32_bf16 v[116:119], v[206:209], v[172:175], v[116:119]
	v_mfma_f32_16x16x32_bf16 v[108:111], v[214:217], v[172:175], v[108:111]
	v_mfma_f32_16x16x32_bf16 v[100:103], v[206:209], v[180:183], v[100:103]
	v_mfma_f32_16x16x32_bf16 v[92:95], v[214:217], v[180:183], v[92:95]
	v_mfma_f32_16x16x32_bf16 v[84:87], v[206:209], v[188:191], v[84:87]
	v_mfma_f32_16x16x32_bf16 v[76:79], v[214:217], v[188:191], v[76:79]
	v_mfma_f32_16x16x32_bf16 v[68:71], v[206:209], v[196:199], v[68:71]
	v_mfma_f32_16x16x32_bf16 v[64:67], v[214:217], v[196:199], v[64:67]
	s_mov_b32 m0, s42
	s_mov_b64 s[0:1], 0x80
	v_lshl_add_u64 v[218:219], v[222:223], 0, s[0:1]
	s_barrier
	s_setprio 0
	ds_read_b128 v[168:171], v150 offset:49152
	ds_read_b128 v[172:175], v150 offset:50176
	ds_read_b128 v[176:179], v150 offset:51200
	ds_read_b128 v[180:183], v150 offset:52224
	ds_read_b128 v[184:187], v150 offset:53248
	ds_read_b128 v[188:191], v150 offset:54272
	ds_read_b128 v[192:195], v150 offset:55296
	ds_read_b128 v[196:199], v150 offset:56320
	global_load_lds_dwordx4 v[218:219], off
	v_lshl_add_u64 v[218:219], v[224:225], 0, s[0:1]
	s_mov_b32 m0, s43
	s_nop 0
	global_load_lds_dwordx4 v[218:219], off
	s_waitcnt lgkmcnt(0)
	s_setprio 1
	s_barrier
; #define PG8_STAGE(bufoff, gbase, voff) do { _Pragma("unroll") for (int _i = 0; _i < 2; ++_i) \
;         __builtin_amdgcn_global_load_lds((const unsigned*)((const char*)(gbase) + (voff)[_i]), (LAS unsigned*)(lds + (bufoff) + ldsw + _i * 8192), 16, 0, 0); } while (0)
; #define PG8_LDA(dst, b, h) do { _Pragma("unroll") for (int m = 0; m < 4; ++m) _Pragma("unroll") for (int k = 0; k < 2; ++k) dst[m][k] = *(const LAS bf16x8*)(lds + PG8_SA(b, h) + aoff + m * 2048 + k * 1024); } while (0)
; #define PG8_LDB(dst, b, h) do { _Pragma("unroll") for (int n = 0; n < 2; ++n) _Pragma("unroll") for (int k = 0; k < 2; ++k) dst[n][k] = *(const LAS bf16x8*)(lds + PG8_SB(b, h) + boff + n * 2048 + k * 1024); } while (0)
; #define PG8_MMA(ai, bj, At, Bt) do { __builtin_amdgcn_s_setprio(1); _Pragma("unroll") for (int m = 0; m < 4; ++m) _Pragma("unroll") for (int n = 0; n < 2; ++n) _Pragma("unroll") for (int k = 0; k < 2; ++k) \
;         acc[ai][bj][m][n] = __builtin_amdgcn_mfma_f32_16x16x32_bf16(Bt[n][k], At[m][k], acc[ai][bj][m][n], 0, 0, 0); __builtin_amdgcn_s_setprio(0); } while (0)
; #define PG8_WAIT_V(n) asm volatile("s_waitcnt vmcnt(" #n ")" ::: "memory")
; #define PG8_WAIT_L(n) asm volatile("s_waitcnt lgkmcnt(" #n ")" ::: "memory")
; #define PG8_BAR __builtin_amdgcn_s_barrier()
; #define PG8_SCHED __builtin_amdgcn_sched_barrier(0)
; template <class Epi, class Sched>
; __device__ __forceinline__ void gemm_phase(LAS unsigned char* lds, const Gemm g, const Sched& S, const Epi& E) {
;     ...
;             PG8_LDB(B0, 0, 0); PG8_SCHED; PG8_LDA(At, 0, 0); PG8_STAGE(PG8_SA(1, 1), a1 + hstep, voffA);
;             PG8_WAIT_L(8); PG8_BAR; PG8_WAIT_L(0); PG8_MMA(0, 0, At, B0); PG8_BAR; PG8_SCHED;
;             PG8_LDB(B1, 0, 1); PG8_STAGE(PG8_SB(0, 0), b2, voffB);
;             PG8_BAR; PG8_WAIT_L(0); PG8_MMA(0, 1, At, B1); PG8_BAR;
;             PG8_LDA(At, 0, 1); PG8_STAGE(PG8_SA(0, 0), a2, voffA);
;             PG8_BAR; PG8_WAIT_L(0); PG8_MMA(1, 0, At, B0); PG8_BAR; PG8_SCHED;
;     ...
;             PG8_BAR; PG8_WAIT_L(0); PG8_MMA(1, 0, At, B0); PG8_BAR; PG8_SCHED;
;             PG8_STAGE(PG8_SB(1, 1), b3 + hstep, voffB);
;             PG8_WAIT_V(6); PG8_BAR; PG8_MMA(1, 1, At, B1); PG8_BAR;
	v_mfma_f32_16x16x32_bf16 v[60:63], v[152:155], v[168:171], v[60:63]
	v_mfma_f32_16x16x32_bf16 v[56:59], v[160:163], v[168:171], v[56:59]
	v_mfma_f32_16x16x32_bf16 v[48:51], v[152:155], v[176:179], v[48:51]
	v_mfma_f32_16x16x32_bf16 v[40:43], v[160:163], v[176:179], v[40:43]
	v_mfma_f32_16x16x32_bf16 v[32:35], v[152:155], v[184:187], v[32:35]
	v_mfma_f32_16x16x32_bf16 v[24:27], v[160:163], v[184:187], v[24:27]
	v_mfma_f32_16x16x32_bf16 v[16:19], v[152:155], v[192:195], v[16:19]
	v_mfma_f32_16x16x32_bf16 v[8:11], v[160:163], v[192:195], v[8:11]
	v_mfma_f32_16x16x32_bf16 v[60:63], v[156:159], v[172:175], v[60:63]
	v_mfma_f32_16x16x32_bf16 v[56:59], v[164:167], v[172:175], v[56:59]
	v_mfma_f32_16x16x32_bf16 v[48:51], v[156:159], v[180:183], v[48:51]
	v_mfma_f32_16x16x32_bf16 v[40:43], v[164:167], v[180:183], v[40:43]
	v_mfma_f32_16x16x32_bf16 v[32:35], v[156:159], v[188:191], v[32:35]
	v_mfma_f32_16x16x32_bf16 v[24:27], v[164:167], v[188:191], v[24:27]
	v_mfma_f32_16x16x32_bf16 v[16:19], v[156:159], v[196:199], v[16:19]
	v_mfma_f32_16x16x32_bf16 v[8:11], v[164:167], v[196:199], v[8:11]
	s_barrier
	s_setprio 0
	s_add_u32 s24, s24, 0x40080
	s_addc_u32 s25, s25, 0
	s_add_i32 s26, s26, s30
	s_mov_b32 m0, s26
	s_nop 0
	global_load_lds_dwordx4 v130, s[24:25]
	s_add_i32 m0, s26, 0x2000
	s_nop 0
	global_load_lds_dwordx4 v134, s[24:25]
	s_waitcnt vmcnt(8)
	s_setprio 1
	s_barrier
	v_mfma_f32_16x16x32_bf16 v[52:55], v[202:205], v[168:171], v[52:55]
	v_mfma_f32_16x16x32_bf16 v[44:47], v[210:213], v[168:171], v[44:47]
	v_mfma_f32_16x16x32_bf16 v[36:39], v[202:205], v[176:179], v[36:39]
	v_mfma_f32_16x16x32_bf16 v[28:31], v[210:213], v[176:179], v[28:31]
	v_mfma_f32_16x16x32_bf16 v[20:23], v[202:205], v[184:187], v[20:23]
	v_mfma_f32_16x16x32_bf16 v[12:15], v[210:213], v[184:187], v[12:15]
	v_mfma_f32_16x16x32_bf16 v[4:7], v[202:205], v[192:195], v[4:7]
	v_mfma_f32_16x16x32_bf16 v[0:3], v[210:213], v[192:195], v[0:3]
	v_mfma_f32_16x16x32_bf16 v[52:55], v[206:209], v[172:175], v[52:55]
	v_mfma_f32_16x16x32_bf16 v[44:47], v[214:217], v[172:175], v[44:47]
	v_mfma_f32_16x16x32_bf16 v[36:39], v[206:209], v[180:183], v[36:39]
	v_mfma_f32_16x16x32_bf16 v[28:31], v[214:217], v[180:183], v[28:31]
	v_mfma_f32_16x16x32_bf16 v[20:23], v[206:209], v[188:191], v[20:23]
	v_mfma_f32_16x16x32_bf16 v[12:15], v[214:217], v[188:191], v[12:15]
	v_mfma_f32_16x16x32_bf16 v[4:7], v[206:209], v[196:199], v[4:7]
	v_mfma_f32_16x16x32_bf16 v[0:3], v[214:217], v[196:199], v[0:3]
	s_add_i32 s53, s53, 2
	s_add_u32 s22, s22, 0x100
	s_addc_u32 s23, s23, 0
	s_add_u32 s51, s51, 0x100
	s_addc_u32 s52, s52, 0
	s_cmp_gt_u32 s53, 13
	s_barrier
	s_setprio 0
.LBB0_653:
	ds_read_b128 v[152:155], v149
	ds_read_b128 v[156:159], v149 offset:1024
	ds_read_b128 v[160:163], v149 offset:2048
	ds_read_b128 v[164:167], v149 offset:3072
	s_add_u32 s24, s22, 0xfffc0080
	s_addc_u32 s25, s23, -1
	s_cmp_eq_u32 s53, 12
	s_cselect_b32 s27, s9, s25
	s_cselect_b32 s26, s48, s24
	s_cselect_b32 s25, s7, s52
	s_cselect_b32 s24, s49, s51
	s_add_i32 m0, s21, 0xc000
	ds_read_b128 v[168:171], v150
	ds_read_b128 v[172:175], v150 offset:1024
	ds_read_b128 v[176:179], v150 offset:2048
	ds_read_b128 v[180:183], v150 offset:3072
	ds_read_b128 v[184:187], v150 offset:4096
	ds_read_b128 v[188:191], v150 offset:5120
	ds_read_b128 v[192:195], v150 offset:6144
	ds_read_b128 v[196:199], v150 offset:7168
	global_load_lds_dwordx4 v138, s[22:23]
	s_add_i32 m0, s21, 0xe000
	s_nop 0
	global_load_lds_dwordx4 v140, s[22:23]
	s_waitcnt lgkmcnt(8)
	s_waitcnt vmcnt(8)
	s_waitcnt lgkmcnt(0)
	s_setprio 1
	s_barrier
	v_mfma_f32_16x16x32_bf16 v[124:127], v[152:155], v[168:171], v[124:127]
	v_mfma_f32_16x16x32_bf16 v[120:123], v[160:163], v[168:171], v[120:123]
	v_mfma_f32_16x16x32_bf16 v[112:115], v[152:155], v[176:179], v[112:115]
	v_mfma_f32_16x16x32_bf16 v[104:107], v[160:163], v[176:179], v[104:107]
	v_mfma_f32_16x16x32_bf16 v[96:99], v[152:155], v[184:187], v[96:99]
	v_mfma_f32_16x16x32_bf16 v[88:91], v[160:163], v[184:187], v[88:91]
	v_mfma_f32_16x16x32_bf16 v[80:83], v[152:155], v[192:195], v[80:83]
	v_mfma_f32_16x16x32_bf16 v[72:75], v[160:163], v[192:195], v[72:75]
	v_mfma_f32_16x16x32_bf16 v[124:127], v[156:159], v[172:175], v[124:127]
	v_mfma_f32_16x16x32_bf16 v[120:123], v[164:167], v[172:175], v[120:123]
	v_mfma_f32_16x16x32_bf16 v[112:115], v[156:159], v[180:183], v[112:115]
	v_mfma_f32_16x16x32_bf16 v[104:107], v[164:167], v[180:183], v[104:107]
	v_mfma_f32_16x16x32_bf16 v[96:99], v[156:159], v[188:191], v[96:99]
	v_mfma_f32_16x16x32_bf16 v[88:91], v[164:167], v[188:191], v[88:91]
	v_mfma_f32_16x16x32_bf16 v[80:83], v[156:159], v[196:199], v[80:83]
	v_mfma_f32_16x16x32_bf16 v[72:75], v[164:167], v[196:199], v[72:75]
	s_barrier
	s_setprio 0
	s_add_i32 s54, s45, s30
	s_mov_b32 m0, s54
	ds_read_b128 v[202:205], v151
	ds_read_b128 v[206:209], v151 offset:1024
	ds_read_b128 v[210:213], v151 offset:2048
	ds_read_b128 v[214:217], v151 offset:3072
	global_load_lds_dwordx4 v130, s[24:25]
	s_add_i32 m0, s54, 0x2000
	s_nop 0
	global_load_lds_dwordx4 v134, s[24:25]
	s_waitcnt vmcnt(8)
	s_waitcnt lgkmcnt(0)
	s_setprio 1
	s_barrier
; #define PG8_STAGE(bufoff, gbase, voff) do { _Pragma("unroll") for (int _i = 0; _i < 2; ++_i) \
;         __builtin_amdgcn_global_load_lds((const unsigned*)((const char*)(gbase) + (voff)[_i]), (LAS unsigned*)(lds + (bufoff) + ldsw + _i * 8192), 16, 0, 0); } while (0)
; #define PG8_LDA(dst, b, h) do { _Pragma("unroll") for (int m = 0; m < 4; ++m) _Pragma("unroll") for (int k = 0; k < 2; ++k) dst[m][k] = *(const LAS bf16x8*)(lds + PG8_SA(b, h) + aoff + m * 2048 + k * 1024); } while (0)
; #define PG8_LDB(dst, b, h) do { _Pragma("unroll") for (int n = 0; n < 2; ++n) _Pragma("unroll") for (int k = 0; k < 2; ++k) dst[n][k] = *(const LAS bf16x8*)(lds + PG8_SB(b, h) + boff + n * 2048 + k * 1024); } while (0)
; #define PG8_MMA(ai, bj, At, Bt) do { __builtin_amdgcn_s_setprio(1); _Pragma("unroll") for (int m = 0; m < 4; ++m) _Pragma("unroll") for (int n = 0; n < 2; ++n) _Pragma("unroll") for (int k = 0; k < 2; ++k) \
;         acc[ai][bj][m][n] = __builtin_amdgcn_mfma_f32_16x16x32_bf16(Bt[n][k], At[m][k], acc[ai][bj][m][n], 0, 0, 0); __builtin_amdgcn_s_setprio(0); } while (0)
; #define PG8_WAIT_V(n) asm volatile("s_waitcnt vmcnt(" #n ")" ::: "memory")
; #define PG8_WAIT_L(n) asm volatile("s_waitcnt lgkmcnt(" #n ")" ::: "memory")
; #define PG8_BAR __builtin_amdgcn_s_barrier()
; #define PG8_SCHED __builtin_amdgcn_sched_barrier(0)
; template <class Epi, class Sched>
; __device__ __forceinline__ void gemm_phase(LAS unsigned char* lds, const Gemm g, const Sched& S, const Epi& E) {
;     ...
;             PG8_WAIT_L(8); PG8_BAR; PG8_WAIT_L(0); PG8_MMA(0, 0, At, B0); PG8_BAR; PG8_SCHED;
;             PG8_LDB(B1, 0, 1); PG8_STAGE(PG8_SB(0, 0), b2, voffB);
;             PG8_BAR; PG8_WAIT_L(0); PG8_MMA(0, 1, At, B1); PG8_BAR;
;             PG8_LDA(At, 0, 1); PG8_STAGE(PG8_SA(0, 0), a2, voffA);
;             PG8_BAR; PG8_WAIT_L(0); PG8_MMA(1, 0, At, B0); PG8_BAR; PG8_SCHED;
;             PG8_STAGE(PG8_SB(0, 1), b2 + hstep, voffB);
;             PG8_WAIT_V(6); PG8_BAR; PG8_MMA(1, 1, At, B1); PG8_BAR;
;             PG8_LDB(B0, 1, 0); PG8_SCHED; PG8_LDA(At, 1, 0); PG8_STAGE(PG8_SA(0, 1), a2 + hstep, voffA);
;             PG8_WAIT_L(8); PG8_BAR; PG8_WAIT_L(0); PG8_MMA(0, 0, At, B0); PG8_BAR; PG8_SCHED;
	v_mfma_f32_16x16x32_bf16 v[116:119], v[202:205], v[168:171], v[116:119]
	v_mfma_f32_16x16x32_bf16 v[108:111], v[210:213], v[168:171], v[108:111]
	v_mfma_f32_16x16x32_bf16 v[100:103], v[202:205], v[176:179], v[100:103]
	v_mfma_f32_16x16x32_bf16 v[92:95], v[210:213], v[176:179], v[92:95]
	v_mfma_f32_16x16x32_bf16 v[84:87], v[202:205], v[184:187], v[84:87]
	v_mfma_f32_16x16x32_bf16 v[76:79], v[210:213], v[184:187], v[76:79]
	v_mfma_f32_16x16x32_bf16 v[68:71], v[202:205], v[192:195], v[68:71]
	v_mfma_f32_16x16x32_bf16 v[64:67], v[210:213], v[192:195], v[64:67]
	v_mfma_f32_16x16x32_bf16 v[116:119], v[206:209], v[172:175], v[116:119]
	v_mfma_f32_16x16x32_bf16 v[108:111], v[214:217], v[172:175], v[108:111]
	v_mfma_f32_16x16x32_bf16 v[100:103], v[206:209], v[180:183], v[100:103]
	v_mfma_f32_16x16x32_bf16 v[92:95], v[214:217], v[180:183], v[92:95]
	v_mfma_f32_16x16x32_bf16 v[84:87], v[206:209], v[188:191], v[84:87]
	v_mfma_f32_16x16x32_bf16 v[76:79], v[214:217], v[188:191], v[76:79]
	v_mfma_f32_16x16x32_bf16 v[68:71], v[206:209], v[196:199], v[68:71]
	v_mfma_f32_16x16x32_bf16 v[64:67], v[214:217], v[196:199], v[64:67]
	s_mov_b32 m0, s21
	v_lshl_add_u64 v[222:223], s[26:27], 0, v[128:129]
	s_barrier
	s_setprio 0
	ds_read_b128 v[168:171], v150 offset:16384
	ds_read_b128 v[172:175], v150 offset:17408
	ds_read_b128 v[176:179], v150 offset:18432
	ds_read_b128 v[180:183], v150 offset:19456
	ds_read_b128 v[184:187], v150 offset:20480
	ds_read_b128 v[188:191], v150 offset:21504
	ds_read_b128 v[192:195], v150 offset:22528
	ds_read_b128 v[196:199], v150 offset:23552
	global_load_lds_dwordx4 v128, s[26:27]
	v_lshl_add_u64 v[224:225], s[26:27], 0, v[132:133]
	s_mov_b32 m0, s31
	s_nop 0
	global_load_lds_dwordx4 v132, s[26:27]
	s_waitcnt lgkmcnt(0)
	s_setprio 1
	s_barrier
	v_mfma_f32_16x16x32_bf16 v[60:63], v[152:155], v[168:171], v[60:63]
	v_mfma_f32_16x16x32_bf16 v[56:59], v[160:163], v[168:171], v[56:59]
	v_mfma_f32_16x16x32_bf16 v[48:51], v[152:155], v[176:179], v[48:51]
	v_mfma_f32_16x16x32_bf16 v[40:43], v[160:163], v[176:179], v[40:43]
	v_mfma_f32_16x16x32_bf16 v[32:35], v[152:155], v[184:187], v[32:35]
	v_mfma_f32_16x16x32_bf16 v[24:27], v[160:163], v[184:187], v[24:27]
	v_mfma_f32_16x16x32_bf16 v[16:19], v[152:155], v[192:195], v[16:19]
	v_mfma_f32_16x16x32_bf16 v[8:11], v[160:163], v[192:195], v[8:11]
	v_mfma_f32_16x16x32_bf16 v[60:63], v[156:159], v[172:175], v[60:63]
	v_mfma_f32_16x16x32_bf16 v[56:59], v[164:167], v[172:175], v[56:59]
	v_mfma_f32_16x16x32_bf16 v[48:51], v[156:159], v[180:183], v[48:51]
	v_mfma_f32_16x16x32_bf16 v[40:43], v[164:167], v[180:183], v[40:43]
	v_mfma_f32_16x16x32_bf16 v[32:35], v[156:159], v[188:191], v[32:35]
	v_mfma_f32_16x16x32_bf16 v[24:27], v[164:167], v[188:191], v[24:27]
	v_mfma_f32_16x16x32_bf16 v[16:19], v[156:159], v[196:199], v[16:19]
	v_mfma_f32_16x16x32_bf16 v[8:11], v[164:167], v[196:199], v[8:11]
	s_barrier
	s_setprio 0
	s_add_u32 s54, s24, 0x40000
	s_addc_u32 s55, s25, 0
	s_add_i32 s56, s46, s30
	s_mov_b32 m0, s56
	s_nop 0
	global_load_lds_dwordx4 v130, s[54:55]
	s_add_i32 m0, s56, 0x2000
	s_nop 0
	global_load_lds_dwordx4 v134, s[54:55]
	s_add_u32 s26, s26, 0x40000
	s_addc_u32 s27, s27, 0
	s_mov_b32 m0, s33
	s_nop 0
	global_load_lds_dwordx4 v128, s[26:27]
	s_mov_b32 m0, s34
	s_nop 0
	global_load_lds_dwordx4 v132, s[26:27]
	s_waitcnt vmcnt(10)
	s_setprio 1
	s_barrier
	v_mfma_f32_16x16x32_bf16 v[52:55], v[202:205], v[168:171], v[52:55]
	v_mfma_f32_16x16x32_bf16 v[44:47], v[210:213], v[168:171], v[44:47]
	v_mfma_f32_16x16x32_bf16 v[36:39], v[202:205], v[176:179], v[36:39]
	v_mfma_f32_16x16x32_bf16 v[28:31], v[210:213], v[176:179], v[28:31]
	v_mfma_f32_16x16x32_bf16 v[20:23], v[202:205], v[184:187], v[20:23]
	v_mfma_f32_16x16x32_bf16 v[12:15], v[210:213], v[184:187], v[12:15]
	v_mfma_f32_16x16x32_bf16 v[4:7], v[202:205], v[192:195], v[4:7]
	v_mfma_f32_16x16x32_bf16 v[0:3], v[210:213], v[192:195], v[0:3]
	v_mfma_f32_16x16x32_bf16 v[52:55], v[206:209], v[172:175], v[52:55]
	v_mfma_f32_16x16x32_bf16 v[44:47], v[214:217], v[172:175], v[44:47]
	v_mfma_f32_16x16x32_bf16 v[36:39], v[206:209], v[180:183], v[36:39]
	v_mfma_f32_16x16x32_bf16 v[28:31], v[214:217], v[180:183], v[28:31]
	v_mfma_f32_16x16x32_bf16 v[20:23], v[206:209], v[188:191], v[20:23]
	v_mfma_f32_16x16x32_bf16 v[12:15], v[214:217], v[188:191], v[12:15]
	v_mfma_f32_16x16x32_bf16 v[4:7], v[206:209], v[196:199], v[4:7]
	v_mfma_f32_16x16x32_bf16 v[0:3], v[214:217], v[196:199], v[0:3]
	s_add_i32 s54, 0, 0x18000
	v_add_u32_e32 v136, s54, v148
	s_barrier
	s_setprio 0
	ds_read_b128 v[152:155], v136
	ds_read_b128 v[156:159], v136 offset:1024
	ds_read_b128 v[160:163], v136 offset:2048
	ds_read_b128 v[164:167], v136 offset:3072
	ds_read_b128 v[168:171], v150 offset:32768
	ds_read_b128 v[172:175], v150 offset:33792
	ds_read_b128 v[176:179], v150 offset:34816
	ds_read_b128 v[180:183], v150 offset:35840
	ds_read_b128 v[184:187], v150 offset:36864
	ds_read_b128 v[188:191], v150 offset:37888
	ds_read_b128 v[192:195], v150 offset:38912
	ds_read_b128 v[196:199], v150 offset:39936
	s_waitcnt lgkmcnt(8)
	s_waitcnt vmcnt(8)
	s_waitcnt lgkmcnt(0)
	s_setprio 1
	s_barrier
; #define PG8_STAGE(bufoff, gbase, voff) do { _Pragma("unroll") for (int _i = 0; _i < 2; ++_i) \
;         __builtin_amdgcn_global_load_lds((const unsigned*)((const char*)(gbase) + (voff)[_i]), (LAS unsigned*)(lds + (bufoff) + ldsw + _i * 8192), 16, 0, 0); } while (0)
; #define PG8_LDA(dst, b, h) do { _Pragma("unroll") for (int m = 0; m < 4; ++m) _Pragma("unroll") for (int k = 0; k < 2; ++k) dst[m][k] = *(const LAS bf16x8*)(lds + PG8_SA(b, h) + aoff + m * 2048 + k * 1024); } while (0)
; #define PG8_LDB(dst, b, h) do { _Pragma("unroll") for (int n = 0; n < 2; ++n) _Pragma("unroll") for (int k = 0; k < 2; ++k) dst[n][k] = *(const LAS bf16x8*)(lds + PG8_SB(b, h) + boff + n * 2048 + k * 1024); } while (0)
; #define PG8_MMA(ai, bj, At, Bt) do { __builtin_amdgcn_s_setprio(1); _Pragma("unroll") for (int m = 0; m < 4; ++m) _Pragma("unroll") for (int n = 0; n < 2; ++n) _Pragma("unroll") for (int k = 0; k < 2; ++k) \
;         acc[ai][bj][m][n] = __builtin_amdgcn_mfma_f32_16x16x32_bf16(Bt[n][k], At[m][k], acc[ai][bj][m][n], 0, 0, 0); __builtin_amdgcn_s_setprio(0); } while (0)
; #define PG8_WAIT_V(n) asm volatile("s_waitcnt vmcnt(" #n ")" ::: "memory")
; #define PG8_WAIT_L(n) asm volatile("s_waitcnt lgkmcnt(" #n ")" ::: "memory")
; #define PG8_BAR __builtin_amdgcn_s_barrier()
; #define PG8_SCHED __builtin_amdgcn_sched_barrier(0)
; template <class Epi, class Sched>
; __device__ __forceinline__ void gemm_phase(LAS unsigned char* lds, const Gemm g, const Sched& S, const Epi& E) {
;     ...
;             PG8_WAIT_L(8); PG8_BAR; PG8_WAIT_L(0); PG8_MMA(0, 0, At, B0); PG8_BAR; PG8_SCHED;
;             PG8_LDB(B1, 1, 1); PG8_STAGE(PG8_SB(1, 0), b3, voffB);
;             PG8_BAR; PG8_WAIT_L(0); PG8_MMA(0, 1, At, B1); PG8_BAR;
;             PG8_LDA(At, 1, 1); PG8_STAGE(PG8_SA(1, 0), a3, voffA);
;             PG8_BAR; PG8_WAIT_L(0); PG8_MMA(1, 0, At, B0); PG8_BAR; PG8_SCHED;
;             PG8_STAGE(PG8_SB(1, 1), b3 + hstep, voffB);
;             PG8_WAIT_V(6); PG8_BAR; PG8_MMA(1, 1, At, B1); PG8_BAR;
	v_mfma_f32_16x16x32_bf16 v[124:127], v[152:155], v[168:171], v[124:127]
	v_mfma_f32_16x16x32_bf16 v[120:123], v[160:163], v[168:171], v[120:123]
	v_mfma_f32_16x16x32_bf16 v[112:115], v[152:155], v[176:179], v[112:115]
	v_mfma_f32_16x16x32_bf16 v[104:107], v[160:163], v[176:179], v[104:107]
	v_mfma_f32_16x16x32_bf16 v[96:99], v[152:155], v[184:187], v[96:99]
	v_mfma_f32_16x16x32_bf16 v[88:91], v[160:163], v[184:187], v[88:91]
	v_mfma_f32_16x16x32_bf16 v[80:83], v[152:155], v[192:195], v[80:83]
	v_mfma_f32_16x16x32_bf16 v[72:75], v[160:163], v[192:195], v[72:75]
	v_mfma_f32_16x16x32_bf16 v[124:127], v[156:159], v[172:175], v[124:127]
	v_mfma_f32_16x16x32_bf16 v[120:123], v[164:167], v[172:175], v[120:123]
	v_mfma_f32_16x16x32_bf16 v[112:115], v[156:159], v[180:183], v[112:115]
	v_mfma_f32_16x16x32_bf16 v[104:107], v[164:167], v[180:183], v[104:107]
	v_mfma_f32_16x16x32_bf16 v[96:99], v[156:159], v[188:191], v[96:99]
	v_mfma_f32_16x16x32_bf16 v[88:91], v[164:167], v[188:191], v[88:91]
	v_mfma_f32_16x16x32_bf16 v[80:83], v[156:159], v[196:199], v[80:83]
	v_mfma_f32_16x16x32_bf16 v[72:75], v[164:167], v[196:199], v[72:75]
	s_barrier
	s_setprio 0
	s_add_i32 s26, 0, 0x1c000
	s_add_i32 s27, s54, s30
	v_add_u32_e32 v136, s26, v148
	s_add_u32 s0, s24, 0x80
	s_addc_u32 s1, s25, 0
	s_mov_b32 m0, s27
	ds_read_b128 v[202:205], v136
	ds_read_b128 v[206:209], v136 offset:1024
	ds_read_b128 v[210:213], v136 offset:2048
	ds_read_b128 v[214:217], v136 offset:3072
	global_load_lds_dwordx4 v130, s[0:1]
	s_add_i32 m0, s27, 0x2000
	s_nop 0
	global_load_lds_dwordx4 v134, s[0:1]
	s_waitcnt vmcnt(8)
	s_waitcnt lgkmcnt(0)
	s_setprio 1
	s_barrier
	v_mfma_f32_16x16x32_bf16 v[116:119], v[202:205], v[168:171], v[116:119]
	v_mfma_f32_16x16x32_bf16 v[108:111], v[210:213], v[168:171], v[108:111]
	v_mfma_f32_16x16x32_bf16 v[100:103], v[202:205], v[176:179], v[100:103]
	v_mfma_f32_16x16x32_bf16 v[92:95], v[210:213], v[176:179], v[92:95]
	v_mfma_f32_16x16x32_bf16 v[84:87], v[202:205], v[184:187], v[84:87]
	v_mfma_f32_16x16x32_bf16 v[76:79], v[210:213], v[184:187], v[76:79]
	v_mfma_f32_16x16x32_bf16 v[68:71], v[202:205], v[192:195], v[68:71]
	v_mfma_f32_16x16x32_bf16 v[64:67], v[210:213], v[192:195], v[64:67]
	v_mfma_f32_16x16x32_bf16 v[116:119], v[206:209], v[172:175], v[116:119]
	v_mfma_f32_16x16x32_bf16 v[108:111], v[214:217], v[172:175], v[108:111]
	v_mfma_f32_16x16x32_bf16 v[100:103], v[206:209], v[180:183], v[100:103]
	v_mfma_f32_16x16x32_bf16 v[92:95], v[214:217], v[180:183], v[92:95]
	v_mfma_f32_16x16x32_bf16 v[84:87], v[206:209], v[188:191], v[84:87]
	v_mfma_f32_16x16x32_bf16 v[76:79], v[214:217], v[188:191], v[76:79]
	v_mfma_f32_16x16x32_bf16 v[68:71], v[206:209], v[196:199], v[68:71]
	v_mfma_f32_16x16x32_bf16 v[64:67], v[214:217], v[196:199], v[64:67]
	s_mov_b32 m0, s42
	s_mov_b64 s[0:1], 0x80
	v_lshl_add_u64 v[218:219], v[222:223], 0, s[0:1]
	s_barrier
	s_setprio 0
	ds_read_b128 v[168:171], v150 offset:49152
	ds_read_b128 v[172:175], v150 offset:50176
	ds_read_b128 v[176:179], v150 offset:51200
	ds_read_b128 v[180:183], v150 offset:52224
	ds_read_b128 v[184:187], v150 offset:53248
	ds_read_b128 v[188:191], v150 offset:54272
	ds_read_b128 v[192:195], v150 offset:55296
	ds_read_b128 v[196:199], v150 offset:56320
	global_load_lds_dwordx4 v[218:219], off
	v_lshl_add_u64 v[218:219], v[224:225], 0, s[0:1]
	s_mov_b32 m0, s43
	s_nop 0
	global_load_lds_dwordx4 v[218:219], off
	s_waitcnt lgkmcnt(0)
	s_setprio 1
	s_barrier
	v_mfma_f32_16x16x32_bf16 v[60:63], v[152:155], v[168:171], v[60:63]
	v_mfma_f32_16x16x32_bf16 v[56:59], v[160:163], v[168:171], v[56:59]
	v_mfma_f32_16x16x32_bf16 v[48:51], v[152:155], v[176:179], v[48:51]
	v_mfma_f32_16x16x32_bf16 v[40:43], v[160:163], v[176:179], v[40:43]
	v_mfma_f32_16x16x32_bf16 v[32:35], v[152:155], v[184:187], v[32:35]
	v_mfma_f32_16x16x32_bf16 v[24:27], v[160:163], v[184:187], v[24:27]
	v_mfma_f32_16x16x32_bf16 v[16:19], v[152:155], v[192:195], v[16:19]
	v_mfma_f32_16x16x32_bf16 v[8:11], v[160:163], v[192:195], v[8:11]
	v_mfma_f32_16x16x32_bf16 v[60:63], v[156:159], v[172:175], v[60:63]
	v_mfma_f32_16x16x32_bf16 v[56:59], v[164:167], v[172:175], v[56:59]
	v_mfma_f32_16x16x32_bf16 v[48:51], v[156:159], v[180:183], v[48:51]
	v_mfma_f32_16x16x32_bf16 v[40:43], v[164:167], v[180:183], v[40:43]
	v_mfma_f32_16x16x32_bf16 v[32:35], v[156:159], v[188:191], v[32:35]
	v_mfma_f32_16x16x32_bf16 v[24:27], v[164:167], v[188:191], v[24:27]
	v_mfma_f32_16x16x32_bf16 v[16:19], v[156:159], v[196:199], v[16:19]
	v_mfma_f32_16x16x32_bf16 v[8:11], v[164:167], v[196:199], v[8:11]
	s_barrier
	s_setprio 0
	s_add_u32 s24, s24, 0x40080
	s_addc_u32 s25, s25, 0
	s_add_i32 s26, s26, s30
	s_mov_b32 m0, s26
	s_nop 0
	global_load_lds_dwordx4 v130, s[24:25]
	s_add_i32 m0, s26, 0x2000
	s_nop 0
	global_load_lds_dwordx4 v134, s[24:25]
	s_waitcnt vmcnt(8)
	s_setprio 1
	s_barrier
	v_mfma_f32_16x16x32_bf16 v[52:55], v[202:205], v[168:171], v[52:55]
	v_mfma_f32_16x16x32_bf16 v[44:47], v[210:213], v[168:171], v[44:47]
	v_mfma_f32_16x16x32_bf16 v[36:39], v[202:205], v[176:179], v[36:39]
	v_mfma_f32_16x16x32_bf16 v[28:31], v[210:213], v[176:179], v[28:31]
	v_mfma_f32_16x16x32_bf16 v[20:23], v[202:205], v[184:187], v[20:23]
	v_mfma_f32_16x16x32_bf16 v[12:15], v[210:213], v[184:187], v[12:15]
	v_mfma_f32_16x16x32_bf16 v[4:7], v[202:205], v[192:195], v[4:7]
	v_mfma_f32_16x16x32_bf16 v[0:3], v[210:213], v[192:195], v[0:3]
	v_mfma_f32_16x16x32_bf16 v[52:55], v[206:209], v[172:175], v[52:55]
	v_mfma_f32_16x16x32_bf16 v[44:47], v[214:217], v[172:175], v[44:47]
	v_mfma_f32_16x16x32_bf16 v[36:39], v[206:209], v[180:183], v[36:39]
	v_mfma_f32_16x16x32_bf16 v[28:31], v[214:217], v[180:183], v[28:31]
	v_mfma_f32_16x16x32_bf16 v[20:23], v[206:209], v[188:191], v[20:23]
	v_mfma_f32_16x16x32_bf16 v[12:15], v[214:217], v[188:191], v[12:15]
	v_mfma_f32_16x16x32_bf16 v[4:7], v[206:209], v[196:199], v[4:7]
	v_mfma_f32_16x16x32_bf16 v[0:3], v[214:217], v[196:199], v[0:3]
	s_add_i32 s53, s53, 2
	s_add_u32 s22, s22, 0x100
	s_addc_u32 s23, s23, 0
	s_add_u32 s51, s51, 0x100
	s_addc_u32 s52, s52, 0
	s_cmp_gt_u32 s53, 13
	s_barrier
; __device__ __forceinline__ unsigned cvt_pk_bf16(float lo, float hi) { unsigned r; asm volatile("v_cvt_pk_bf16_f32 %0, %1, %2" : "=v"(r) : "v"(lo), "v"(hi)); return r; }
; template <class Epi, class Sched>
; __device__ __forceinline__ void gemm_phase(LAS unsigned char* lds, const Gemm g, const Sched& S, const Epi& E) {
;     ...
;         E(acc, cur, wr, wc, fr, fq);
;     __device__ __forceinline__ void operator()(const AccT& acc, const Unit& u, int wr, int wc, int fr, int fq) const {
;         asm volatile("" : "+v"(fr), "+v"(fq));
;         const int rbase = u.pm * 256 + wr * 64 + fr;
;         const int tb = u.pn * 256 + wc * 32 + 8 * fq;
; #pragma unroll
;         for (int ai = 0; ai < 2; ++ai)
; #pragma unroll
;             for (int m = 0; m < 4; ++m) {
;                 const int gm = rbase + ai * 128 + m * 16;
; #pragma unroll
;                 for (int bj = 0; bj < 2; ++bj) {
;                     const int t0 = tb + bj * 128;
;                     const f32x4 v0 = acc[ai][bj][m][0], v1 = acc[ai][bj][m][1];
;                     u32x4 w; w.x = cvt_pk_bf16(v0[0], v0[1]); w.y = cvt_pk_bf16(v0[2], v0[3]); w.z = cvt_pk_bf16(v1[0], v1[1]); w.w = cvt_pk_bf16(v1[2], v1[3]);
;                     *(u32x4*)(YT + ((size_t)((t0 >> 10) * 512 + gm)) * 2048 + part * 1024 + (t0 & 1023)) = w;
;                 }
	s_setprio 0
	s_cbranch_scc0 .LBB0_653
	v_mov_b32_e32 v136, v147
	v_mov_b32_e32 v152, v146
	s_lshl_b32 s7, s20, 8
	s_add_i32 s7, s7, s36
	v_add_u32_e32 v152, s7, v152
	s_lshl_b32 s7, s47, 8
	s_or_b32 s7, s7, s37
	v_lshl_add_u32 v153, v136, 3, s7
	v_cvt_pk_bf16_f32 v124, v124, v125
	v_cvt_pk_bf16_f32 v125, v126, v127
	v_cvt_pk_bf16_f32 v126, v120, v121
	v_ashrrev_i32_e32 v120, 1, v153
	v_cvt_pk_bf16_f32 v127, v122, v123
	v_and_b32_e32 v122, 0xfffffe00, v120
	v_add_u32_e32 v120, v122, v152
	v_ashrrev_i32_e32 v121, 31, v120
	v_lshlrev_b64 v[120:121], 12, v[120:121]
	v_and_b32_e32 v123, 0x3f8, v153
	v_lshl_add_u64 v[120:121], s[68:69], 0, v[120:121]
	v_lshlrev_b32_e32 v136, 1, v123
	v_lshl_add_u64 v[120:121], v[120:121], 0, v[136:137]
	global_store_dwordx4 v[120:121], v[124:127], off
	v_add_u32_e32 v120, 0x80, v153
	v_cvt_pk_bf16_f32 v116, v116, v117
	v_cvt_pk_bf16_f32 v117, v118, v119
	v_cvt_pk_bf16_f32 v118, v108, v109
	v_ashrrev_i32_e32 v108, 1, v120
	v_and_b32_e32 v121, 0xfffffe00, v108
	v_add_u32_e32 v108, v121, v152
	v_ashrrev_i32_e32 v109, 31, v108
	v_lshlrev_b64 v[108:109], 12, v[108:109]
	v_cvt_pk_bf16_f32 v119, v110, v111
	v_lshl_add_u64 v[110:111], s[68:69], 0, v[108:109]
	v_and_b32_e32 v108, 0x3f8, v120
	v_lshlrev_b32_e32 v108, 1, v108
	v_mov_b32_e32 v109, v137
	v_lshl_add_u64 v[110:111], v[110:111], 0, v[108:109]
	global_store_dwordx4 v[110:111], v[116:119], off
	v_cvt_pk_bf16_f32 v110, v112, v113
	v_cvt_pk_bf16_f32 v111, v114, v115
	v_cvt_pk_bf16_f32 v112, v104, v105
	v_cvt_pk_bf16_f32 v113, v106, v107
	s_and_b64 vcc, exec, s[4:5]
	s_nop 0
	v_add_u32_e32 v116, 16, v152
	v_add_u32_e32 v104, v122, v116
	v_ashrrev_i32_e32 v105, 31, v104
	v_lshlrev_b64 v[104:105], 12, v[104:105]
	v_lshl_add_u64 v[104:105], s[68:69], 0, v[104:105]
	v_lshl_add_u64 v[104:105], v[104:105], 0, v[136:137]
	global_store_dwordx4 v[104:105], v[110:113], off
	v_cvt_pk_bf16_f32 v100, v100, v101
	v_cvt_pk_bf16_f32 v101, v102, v103
	v_cvt_pk_bf16_f32 v102, v92, v93
	v_add_u32_e32 v92, v121, v116
	v_ashrrev_i32_e32 v93, 31, v92
	v_lshlrev_b64 v[92:93], 12, v[92:93]
	v_lshl_add_u64 v[92:93], s[68:69], 0, v[92:93]
	v_lshl_add_u64 v[92:93], v[92:93], 0, v[108:109]
	v_cvt_pk_bf16_f32 v103, v94, v95
	global_store_dwordx4 v[92:93], v[100:103], off
	v_cvt_pk_bf16_f32 v92, v96, v97
	v_cvt_pk_bf16_f32 v93, v98, v99
	v_cvt_pk_bf16_f32 v94, v88, v89
	v_cvt_pk_bf16_f32 v95, v90, v91
	s_mov_b32 s47, s6
	s_nop 0
	v_add_u32_e32 v100, 32, v152
	v_add_u32_e32 v88, v122, v100
	v_ashrrev_i32_e32 v89, 31, v88
	v_lshlrev_b64 v[88:89], 12, v[88:89]
	v_lshl_add_u64 v[88:89], s[68:69], 0, v[88:89]
	v_lshl_add_u64 v[88:89], v[88:89], 0, v[136:137]
	global_store_dwordx4 v[88:89], v[92:95], off
	v_cvt_pk_bf16_f32 v84, v84, v85
	v_cvt_pk_bf16_f32 v85, v86, v87
	v_cvt_pk_bf16_f32 v86, v76, v77
	v_add_u32_e32 v76, v121, v100
	v_ashrrev_i32_e32 v77, 31, v76
	v_lshlrev_b64 v[76:77], 12, v[76:77]
	v_lshl_add_u64 v[76:77], s[68:69], 0, v[76:77]
	v_lshl_add_u64 v[76:77], v[76:77], 0, v[108:109]
	v_cvt_pk_bf16_f32 v87, v78, v79
	global_store_dwordx4 v[76:77], v[84:87], off
	v_cvt_pk_bf16_f32 v76, v80, v81
	v_cvt_pk_bf16_f32 v77, v82, v83
	v_cvt_pk_bf16_f32 v78, v72, v73
	v_cvt_pk_bf16_f32 v79, v74, v75
	s_mov_b32 s20, s8
	s_nop 0
	v_add_u32_e32 v84, 48, v152
	v_add_u32_e32 v72, v122, v84
	v_ashrrev_i32_e32 v73, 31, v72
	v_lshlrev_b64 v[72:73], 12, v[72:73]
	v_lshl_add_u64 v[72:73], s[68:69], 0, v[72:73]
	v_lshl_add_u64 v[72:73], v[72:73], 0, v[136:137]
	global_store_dwordx4 v[72:73], v[76:79], off
	v_cvt_pk_bf16_f32 v68, v68, v69
	v_cvt_pk_bf16_f32 v69, v70, v71
; __device__ __forceinline__ unsigned cvt_pk_bf16(float lo, float hi) { unsigned r; asm volatile("v_cvt_pk_bf16_f32 %0, %1, %2" : "=v"(r) : "v"(lo), "v"(hi)); return r; }
; #define PG8_WAIT_V(n) asm volatile("s_waitcnt vmcnt(" #n ")" ::: "memory")
; #define PG8_BAR __builtin_amdgcn_s_barrier()
; template <class Epi, class Sched>
; __device__ __forceinline__ void gemm_phase(LAS unsigned char* lds, const Gemm g, const Sched& S, const Epi& E) {
;     ...
;         if (!has_next) break;
; #pragma unroll
;         for (int a = 0; a < 2; ++a)
; #pragma unroll
;             for (int b = 0; b < 2; ++b)
; #pragma unroll
;                 for (int m = 0; m < 4; ++m)
; #pragma unroll
;                     for (int n = 0; n < 2; ++n) acc[a][b][m][n] = (f32x4){0.f, 0.f, 0.f, 0.f};
;         cur = nxt; cA = nA; cB = nB; ++ui;
;     }
;     PG8_WAIT_V(0);
;     if (wr == 0) PG8_BAR;
;     PG8_BAR;
;     __device__ __forceinline__ void operator()(const AccT& acc, const Unit& u, int wr, int wc, int fr, int fq) const {
;     ...
;         for (int ai = 0; ai < 2; ++ai)
; #pragma unroll
;             for (int m = 0; m < 4; ++m) {
;                 const int gm = rbase + ai * 128 + m * 16;
; #pragma unroll
;                 for (int bj = 0; bj < 2; ++bj) {
;                     const int t0 = tb + bj * 128;
;                     const f32x4 v0 = acc[ai][bj][m][0], v1 = acc[ai][bj][m][1];
;                     u32x4 w; w.x = cvt_pk_bf16(v0[0], v0[1]); w.y = cvt_pk_bf16(v0[2], v0[3]); w.z = cvt_pk_bf16(v1[0], v1[1]); w.w = cvt_pk_bf16(v1[2], v1[3]);
;                     *(u32x4*)(YT + ((size_t)((t0 >> 10) * 512 + gm)) * 2048 + part * 1024 + (t0 & 1023)) = w;
;                 }
;             }
;     }
	v_cvt_pk_bf16_f32 v70, v64, v65
	v_add_u32_e32 v64, v121, v84
	v_ashrrev_i32_e32 v65, 31, v64
	v_lshlrev_b64 v[64:65], 12, v[64:65]
	v_lshl_add_u64 v[64:65], s[68:69], 0, v[64:65]
	v_lshl_add_u64 v[64:65], v[64:65], 0, v[108:109]
	v_cvt_pk_bf16_f32 v71, v66, v67
	global_store_dwordx4 v[64:65], v[68:71], off
	v_add_u32_e32 v64, 0x80, v152
	v_cvt_pk_bf16_f32 v60, v60, v61
	v_cvt_pk_bf16_f32 v61, v62, v63
	v_cvt_pk_bf16_f32 v62, v56, v57
	v_add_u32_e32 v56, v122, v64
	v_ashrrev_i32_e32 v57, 31, v56
	v_lshlrev_b64 v[56:57], 12, v[56:57]
	v_lshl_add_u64 v[56:57], s[68:69], 0, v[56:57]
	v_lshl_add_u64 v[56:57], v[56:57], 0, v[136:137]
	v_cvt_pk_bf16_f32 v63, v58, v59
	global_store_dwordx4 v[56:57], v[60:63], off
	v_cvt_pk_bf16_f32 v52, v52, v53
	v_cvt_pk_bf16_f32 v53, v54, v55
	v_cvt_pk_bf16_f32 v54, v44, v45
	v_add_u32_e32 v44, v121, v64
	v_ashrrev_i32_e32 v45, 31, v44
	v_lshlrev_b64 v[44:45], 12, v[44:45]
	v_lshl_add_u64 v[44:45], s[68:69], 0, v[44:45]
	v_lshl_add_u64 v[44:45], v[44:45], 0, v[108:109]
	v_cvt_pk_bf16_f32 v55, v46, v47
	global_store_dwordx4 v[44:45], v[52:55], off
	v_cvt_pk_bf16_f32 v44, v48, v49
	v_cvt_pk_bf16_f32 v45, v50, v51
	v_cvt_pk_bf16_f32 v46, v40, v41
	v_cvt_pk_bf16_f32 v47, v42, v43
	s_mov_b64 s[24:25], s[18:19]
	s_nop 0
	v_add_u32_e32 v52, 0x90, v152
	v_add_u32_e32 v40, v122, v52
	v_ashrrev_i32_e32 v41, 31, v40
	v_lshlrev_b64 v[40:41], 12, v[40:41]
	v_lshl_add_u64 v[40:41], s[68:69], 0, v[40:41]
	v_lshl_add_u64 v[40:41], v[40:41], 0, v[136:137]
	global_store_dwordx4 v[40:41], v[44:47], off
	v_cvt_pk_bf16_f32 v36, v36, v37
	v_cvt_pk_bf16_f32 v37, v38, v39
	v_cvt_pk_bf16_f32 v38, v28, v29
	v_add_u32_e32 v28, v121, v52
	v_ashrrev_i32_e32 v29, 31, v28
	v_lshlrev_b64 v[28:29], 12, v[28:29]
	v_lshl_add_u64 v[28:29], s[68:69], 0, v[28:29]
	v_lshl_add_u64 v[28:29], v[28:29], 0, v[108:109]
	v_cvt_pk_bf16_f32 v39, v30, v31
	global_store_dwordx4 v[28:29], v[36:39], off
	v_cvt_pk_bf16_f32 v28, v32, v33
	v_cvt_pk_bf16_f32 v29, v34, v35
	v_cvt_pk_bf16_f32 v30, v24, v25
	v_cvt_pk_bf16_f32 v31, v26, v27
	s_mov_b64 s[22:23], s[16:17]
	s_nop 0
	v_add_u32_e32 v36, 0xa0, v152
	v_add_u32_e32 v24, v122, v36
	v_ashrrev_i32_e32 v25, 31, v24
	v_lshlrev_b64 v[24:25], 12, v[24:25]
	v_lshl_add_u64 v[24:25], s[68:69], 0, v[24:25]
	v_lshl_add_u64 v[24:25], v[24:25], 0, v[136:137]
	global_store_dwordx4 v[24:25], v[28:31], off
	v_cvt_pk_bf16_f32 v20, v20, v21
	v_cvt_pk_bf16_f32 v21, v22, v23
	v_cvt_pk_bf16_f32 v22, v12, v13
	v_add_u32_e32 v12, v121, v36
	v_ashrrev_i32_e32 v13, 31, v12
	v_lshlrev_b64 v[12:13], 12, v[12:13]
	v_lshl_add_u64 v[12:13], s[68:69], 0, v[12:13]
	v_lshl_add_u64 v[12:13], v[12:13], 0, v[108:109]
	v_cvt_pk_bf16_f32 v23, v14, v15
	global_store_dwordx4 v[12:13], v[20:23], off
	v_cvt_pk_bf16_f32 v12, v16, v17
	v_cvt_pk_bf16_f32 v13, v18, v19
	v_cvt_pk_bf16_f32 v14, v8, v9
	v_cvt_pk_bf16_f32 v15, v10, v11
	s_nop 1
	v_add_u32_e32 v20, 0xb0, v152
	v_add_u32_e32 v8, v122, v20
	v_ashrrev_i32_e32 v9, 31, v8
	v_lshlrev_b64 v[8:9], 12, v[8:9]
	v_lshl_add_u64 v[8:9], s[68:69], 0, v[8:9]
	v_lshl_add_u64 v[8:9], v[8:9], 0, v[136:137]
	global_store_dwordx4 v[8:9], v[12:15], off
	v_cvt_pk_bf16_f32 v4, v4, v5
	v_cvt_pk_bf16_f32 v5, v6, v7
	v_cvt_pk_bf16_f32 v6, v0, v1
	v_add_u32_e32 v0, v121, v20
	v_ashrrev_i32_e32 v1, 31, v0
	v_lshlrev_b64 v[0:1], 12, v[0:1]
	v_lshl_add_u64 v[0:1], s[68:69], 0, v[0:1]
	v_lshl_add_u64 v[0:1], v[0:1], 0, v[108:109]
	v_cvt_pk_bf16_f32 v7, v2, v3
	global_store_dwordx4 v[0:1], v[4:7], off
	s_cbranch_vccz .LBB0_646
	s_waitcnt vmcnt(0)
	s_cmpk_gt_u32 s28, 0xff
	s_cbranch_scc1 .LBB0_657
	s_barrier

; #define PG8_STAGE(bufoff, gbase, voff) do { _Pragma("unroll") for (int _i = 0; _i < 2; ++_i) \
;         __builtin_amdgcn_global_load_lds((const unsigned*)((const char*)(gbase) + (voff)[_i]), (LAS unsigned*)(lds + (bufoff) + ldsw + _i * 8192), 16, 0, 0); } while (0)
; #define PG8_LDA(dst, b, h) do { _Pragma("unroll") for (int m = 0; m < 4; ++m) _Pragma("unroll") for (int k = 0; k < 2; ++k) dst[m][k] = *(const LAS bf16x8*)(lds + PG8_SA(b, h) + aoff + m * 2048 + k * 1024); } while (0)
; #define PG8_LDB(dst, b, h) do { _Pragma("unroll") for (int n = 0; n < 2; ++n) _Pragma("unroll") for (int k = 0; k < 2; ++k) dst[n][k] = *(const LAS bf16x8*)(lds + PG8_SB(b, h) + boff + n * 2048 + k * 1024); } while (0)
; #define PG8_WAIT_V(n) asm volatile("s_waitcnt vmcnt(" #n ")" ::: "memory")
; #define PG8_BAR __builtin_amdgcn_s_barrier()
; template <class Epi, class Sched>
; __device__ __forceinline__ void gemm_phase(LAS unsigned char* lds, const Gemm g, const Sched& S, const Epi& E) {
;     ...
;         const bool has_next = S.next(ui + 1, nxt);
;         const char* nA = has_next ? (const char*)g.A + (size_t)nxt.pm * tstep : cA; const char* nB = has_next ? (const char*)g.Bt + (size_t)nxt.pn * tstep : cB;
;         for (int t = 0; t < nt; t += 2) {
;             const bool last = (t == nt - 2);
;             const char* a1 = cA + (size_t)(t + 1) * kstep;
;             const char* a2 = last ? nA : cA + (size_t)(t + 2) * kstep; const char* b2 = last ? nB : cB + (size_t)(t + 2) * kstep;
;             const char* a3 = a2 + kstep; const char* b3 = b2 + kstep;
;             PG8_LDB(B0, 0, 0); PG8_SCHED; PG8_LDA(At, 0, 0); PG8_STAGE(PG8_SA(1, 1), a1 + hstep, voffA);
;             PG8_WAIT_L(8); PG8_BAR; PG8_WAIT_L(0); PG8_MMA(0, 0, At, B0); PG8_BAR; PG8_SCHED;
;             PG8_LDB(B1, 0, 1); PG8_STAGE(PG8_SB(0, 0), b2, voffB);
;             PG8_BAR; PG8_WAIT_L(0); PG8_MMA(0, 1, At, B1); PG8_BAR;
;             PG8_LDA(At, 0, 1); PG8_STAGE(PG8_SA(0, 0), a2, voffA);
;             PG8_BAR; PG8_WAIT_L(0); PG8_MMA(1, 0, At, B0); PG8_BAR; PG8_SCHED;
;             PG8_STAGE(PG8_SB(0, 1), b2 + hstep, voffB);
;             PG8_WAIT_V(6); PG8_BAR; PG8_MMA(1, 1, At, B1); PG8_BAR;
;             PG8_LDB(B0, 1, 0); PG8_SCHED; PG8_LDA(At, 1, 0); PG8_STAGE(PG8_SA(0, 1), a2 + hstep, voffA);
;             PG8_WAIT_L(8); PG8_BAR; PG8_WAIT_L(0); PG8_MMA(0, 0, At, B0); PG8_BAR; PG8_SCHED;
.LBB0_672:
	s_ashr_i32 s9, s8, 31
	v_cmp_lt_i64_e32 vcc, s[12:13], v[142:143]
	s_lshl_b64 s[12:13], s[8:9], 19
	s_add_u32 s12, s26, s12
	s_addc_u32 s13, s27, s13
	s_and_b64 s[14:15], vcc, exec
	s_cselect_b32 s9, s13, s19
	s_cselect_b32 s46, s12, s18
	s_ashr_i32 s7, s6, 31
	s_lshl_b64 s[14:15], s[6:7], 19
	s_add_u32 s14, s10, s14
	s_addc_u32 s15, s11, s15
	s_and_b64 s[22:23], vcc, exec
	s_cselect_b32 s7, s15, s21
	s_cselect_b32 s47, s14, s20
	s_add_u32 s18, s18, 0x40080
	s_addc_u32 s19, s19, 0
	s_add_u32 s48, s20, 0x100
	s_addc_u32 s49, s21, 0
	s_mov_b32 s51, -2
	s_waitcnt lgkmcnt(0)
	ds_read_b128 v[152:155], v149
	ds_read_b128 v[156:159], v149 offset:1024
	ds_read_b128 v[160:163], v149 offset:2048
	ds_read_b128 v[164:167], v149 offset:3072
	s_add_u32 s20, s18, 0xfffc0080
	s_addc_u32 s21, s19, -1
	s_cmp_eq_u32 s51, 12
	s_cselect_b32 s23, s9, s21
	s_cselect_b32 s22, s46, s20
	s_cselect_b32 s21, s7, s49
	s_cselect_b32 s20, s47, s48
	s_add_i32 m0, s17, 0xc000
	ds_read_b128 v[168:171], v150
	ds_read_b128 v[172:175], v150 offset:1024
	ds_read_b128 v[176:179], v150 offset:2048
	ds_read_b128 v[180:183], v150 offset:3072
	ds_read_b128 v[184:187], v150 offset:4096
	ds_read_b128 v[188:191], v150 offset:5120
	ds_read_b128 v[192:195], v150 offset:6144
	ds_read_b128 v[196:199], v150 offset:7168
	global_load_lds_dwordx4 v138, s[18:19]
	s_add_i32 m0, s17, 0xe000
	s_nop 0
	global_load_lds_dwordx4 v140, s[18:19]
	s_waitcnt lgkmcnt(8)
	s_waitcnt vmcnt(8)
	s_waitcnt lgkmcnt(0)
	s_setprio 1
	s_barrier
	v_mfma_f32_16x16x32_bf16 v[124:127], v[152:155], v[168:171], 0
	v_mfma_f32_16x16x32_bf16 v[120:123], v[160:163], v[168:171], 0
	v_mfma_f32_16x16x32_bf16 v[112:115], v[152:155], v[176:179], 0
	v_mfma_f32_16x16x32_bf16 v[104:107], v[160:163], v[176:179], 0
	v_mfma_f32_16x16x32_bf16 v[96:99], v[152:155], v[184:187], 0
	v_mfma_f32_16x16x32_bf16 v[88:91], v[160:163], v[184:187], 0
	v_mfma_f32_16x16x32_bf16 v[80:83], v[152:155], v[192:195], 0
	v_mfma_f32_16x16x32_bf16 v[72:75], v[160:163], v[192:195], 0
	v_mfma_f32_16x16x32_bf16 v[124:127], v[156:159], v[172:175], v[124:127]
	v_mfma_f32_16x16x32_bf16 v[120:123], v[164:167], v[172:175], v[120:123]
	v_mfma_f32_16x16x32_bf16 v[112:115], v[156:159], v[180:183], v[112:115]
	v_mfma_f32_16x16x32_bf16 v[104:107], v[164:167], v[180:183], v[104:107]
	v_mfma_f32_16x16x32_bf16 v[96:99], v[156:159], v[188:191], v[96:99]
	v_mfma_f32_16x16x32_bf16 v[88:91], v[164:167], v[188:191], v[88:91]
	v_mfma_f32_16x16x32_bf16 v[80:83], v[156:159], v[196:199], v[80:83]
	v_mfma_f32_16x16x32_bf16 v[72:75], v[164:167], v[196:199], v[72:75]
	s_barrier
	s_setprio 0
	s_add_i32 s52, s43, s28
	s_mov_b32 m0, s52
	ds_read_b128 v[202:205], v151
	ds_read_b128 v[206:209], v151 offset:1024
	ds_read_b128 v[210:213], v151 offset:2048
	ds_read_b128 v[214:217], v151 offset:3072
	global_load_lds_dwordx4 v130, s[20:21]
	s_add_i32 m0, s52, 0x2000
	s_nop 0
	global_load_lds_dwordx4 v134, s[20:21]
	s_waitcnt vmcnt(8)
	s_waitcnt lgkmcnt(0)
	s_setprio 1
	s_barrier
	v_mfma_f32_16x16x32_bf16 v[116:119], v[202:205], v[168:171], 0
	v_mfma_f32_16x16x32_bf16 v[108:111], v[210:213], v[168:171], 0
	v_mfma_f32_16x16x32_bf16 v[100:103], v[202:205], v[176:179], 0
	v_mfma_f32_16x16x32_bf16 v[92:95], v[210:213], v[176:179], 0
	v_mfma_f32_16x16x32_bf16 v[84:87], v[202:205], v[184:187], 0
	v_mfma_f32_16x16x32_bf16 v[76:79], v[210:213], v[184:187], 0
	v_mfma_f32_16x16x32_bf16 v[68:71], v[202:205], v[192:195], 0
	v_mfma_f32_16x16x32_bf16 v[64:67], v[210:213], v[192:195], 0
	v_mfma_f32_16x16x32_bf16 v[116:119], v[206:209], v[172:175], v[116:119]
	v_mfma_f32_16x16x32_bf16 v[108:111], v[214:217], v[172:175], v[108:111]
	v_mfma_f32_16x16x32_bf16 v[100:103], v[206:209], v[180:183], v[100:103]
	v_mfma_f32_16x16x32_bf16 v[92:95], v[214:217], v[180:183], v[92:95]
	v_mfma_f32_16x16x32_bf16 v[84:87], v[206:209], v[188:191], v[84:87]
	v_mfma_f32_16x16x32_bf16 v[76:79], v[214:217], v[188:191], v[76:79]
	v_mfma_f32_16x16x32_bf16 v[68:71], v[206:209], v[196:199], v[68:71]
	v_mfma_f32_16x16x32_bf16 v[64:67], v[214:217], v[196:199], v[64:67]
	s_mov_b32 m0, s17
	v_lshl_add_u64 v[222:223], s[22:23], 0, v[128:129]
	s_barrier
	s_setprio 0
	ds_read_b128 v[168:171], v150 offset:16384
	ds_read_b128 v[172:175], v150 offset:17408
	ds_read_b128 v[176:179], v150 offset:18432
	ds_read_b128 v[180:183], v150 offset:19456
	ds_read_b128 v[184:187], v150 offset:20480
	ds_read_b128 v[188:191], v150 offset:21504
	ds_read_b128 v[192:195], v150 offset:22528
	ds_read_b128 v[196:199], v150 offset:23552
	global_load_lds_dwordx4 v128, s[22:23]
	v_lshl_add_u64 v[224:225], s[22:23], 0, v[132:133]
	s_mov_b32 m0, s29
	s_nop 0
	global_load_lds_dwordx4 v132, s[22:23]
	s_waitcnt lgkmcnt(0)
	s_setprio 1
	s_barrier
	v_mfma_f32_16x16x32_bf16 v[60:63], v[152:155], v[168:171], 0
	v_mfma_f32_16x16x32_bf16 v[56:59], v[160:163], v[168:171], 0
	v_mfma_f32_16x16x32_bf16 v[48:51], v[152:155], v[176:179], 0
	v_mfma_f32_16x16x32_bf16 v[40:43], v[160:163], v[176:179], 0
	v_mfma_f32_16x16x32_bf16 v[32:35], v[152:155], v[184:187], 0
	v_mfma_f32_16x16x32_bf16 v[24:27], v[160:163], v[184:187], 0
	v_mfma_f32_16x16x32_bf16 v[16:19], v[152:155], v[192:195], 0
	v_mfma_f32_16x16x32_bf16 v[8:11], v[160:163], v[192:195], 0
	v_mfma_f32_16x16x32_bf16 v[60:63], v[156:159], v[172:175], v[60:63]
	v_mfma_f32_16x16x32_bf16 v[56:59], v[164:167], v[172:175], v[56:59]
	v_mfma_f32_16x16x32_bf16 v[48:51], v[156:159], v[180:183], v[48:51]
	v_mfma_f32_16x16x32_bf16 v[40:43], v[164:167], v[180:183], v[40:43]
	v_mfma_f32_16x16x32_bf16 v[32:35], v[156:159], v[188:191], v[32:35]
	v_mfma_f32_16x16x32_bf16 v[24:27], v[164:167], v[188:191], v[24:27]
	v_mfma_f32_16x16x32_bf16 v[16:19], v[156:159], v[196:199], v[16:19]
	v_mfma_f32_16x16x32_bf16 v[8:11], v[164:167], v[196:199], v[8:11]
	s_barrier
; #define PG8_STAGE(bufoff, gbase, voff) do { _Pragma("unroll") for (int _i = 0; _i < 2; ++_i) \
;         __builtin_amdgcn_global_load_lds((const unsigned*)((const char*)(gbase) + (voff)[_i]), (LAS unsigned*)(lds + (bufoff) + ldsw + _i * 8192), 16, 0, 0); } while (0)
; #define PG8_LDA(dst, b, h) do { _Pragma("unroll") for (int m = 0; m < 4; ++m) _Pragma("unroll") for (int k = 0; k < 2; ++k) dst[m][k] = *(const LAS bf16x8*)(lds + PG8_SA(b, h) + aoff + m * 2048 + k * 1024); } while (0)
; #define PG8_LDB(dst, b, h) do { _Pragma("unroll") for (int n = 0; n < 2; ++n) _Pragma("unroll") for (int k = 0; k < 2; ++k) dst[n][k] = *(const LAS bf16x8*)(lds + PG8_SB(b, h) + boff + n * 2048 + k * 1024); } while (0)
; #define PG8_MMA(ai, bj, At, Bt) do { __builtin_amdgcn_s_setprio(1); _Pragma("unroll") for (int m = 0; m < 4; ++m) _Pragma("unroll") for (int n = 0; n < 2; ++n) _Pragma("unroll") for (int k = 0; k < 2; ++k) \
;         acc[ai][bj][m][n] = __builtin_amdgcn_mfma_f32_16x16x32_bf16(Bt[n][k], At[m][k], acc[ai][bj][m][n], 0, 0, 0); __builtin_amdgcn_s_setprio(0); } while (0)
; #define PG8_WAIT_V(n) asm volatile("s_waitcnt vmcnt(" #n ")" ::: "memory")
; #define PG8_WAIT_L(n) asm volatile("s_waitcnt lgkmcnt(" #n ")" ::: "memory")
; #define PG8_BAR __builtin_amdgcn_s_barrier()
; #define PG8_SCHED __builtin_amdgcn_sched_barrier(0)
; template <class Epi, class Sched>
; __device__ __forceinline__ void gemm_phase(LAS unsigned char* lds, const Gemm g, const Sched& S, const Epi& E) {
;     ...
;             PG8_WAIT_V(6); PG8_BAR; PG8_MMA(1, 1, At, B1); PG8_BAR;
;             PG8_LDB(B0, 1, 0); PG8_SCHED; PG8_LDA(At, 1, 0); PG8_STAGE(PG8_SA(0, 1), a2 + hstep, voffA);
;             PG8_WAIT_L(8); PG8_BAR; PG8_WAIT_L(0); PG8_MMA(0, 0, At, B0); PG8_BAR; PG8_SCHED;
;             PG8_LDB(B1, 1, 1); PG8_STAGE(PG8_SB(1, 0), b3, voffB);
;             PG8_BAR; PG8_WAIT_L(0); PG8_MMA(0, 1, At, B1); PG8_BAR;
;             PG8_LDA(At, 1, 1); PG8_STAGE(PG8_SA(1, 0), a3, voffA);
;             PG8_BAR; PG8_WAIT_L(0); PG8_MMA(1, 0, At, B0); PG8_BAR; PG8_SCHED;
	s_setprio 0
	s_add_u32 s52, s20, 0x40000
	s_addc_u32 s53, s21, 0
	s_add_i32 s54, s44, s28
	s_mov_b32 m0, s54
	s_nop 0
	global_load_lds_dwordx4 v130, s[52:53]
	s_add_i32 m0, s54, 0x2000
	s_nop 0
	global_load_lds_dwordx4 v134, s[52:53]
	s_add_u32 s22, s22, 0x40000
	s_addc_u32 s23, s23, 0
	s_mov_b32 m0, s30
	s_nop 0
	global_load_lds_dwordx4 v128, s[22:23]
	s_mov_b32 m0, s31
	s_nop 0
	global_load_lds_dwordx4 v132, s[22:23]
	s_waitcnt vmcnt(10)
	s_setprio 1
	s_barrier
	v_mfma_f32_16x16x32_bf16 v[52:55], v[202:205], v[168:171], 0
	v_mfma_f32_16x16x32_bf16 v[44:47], v[210:213], v[168:171], 0
	v_mfma_f32_16x16x32_bf16 v[36:39], v[202:205], v[176:179], 0
	v_mfma_f32_16x16x32_bf16 v[28:31], v[210:213], v[176:179], 0
	v_mfma_f32_16x16x32_bf16 v[20:23], v[202:205], v[184:187], 0
	v_mfma_f32_16x16x32_bf16 v[12:15], v[210:213], v[184:187], 0
	v_mfma_f32_16x16x32_bf16 v[4:7], v[202:205], v[192:195], 0
	v_mfma_f32_16x16x32_bf16 v[0:3], v[210:213], v[192:195], 0
	v_mfma_f32_16x16x32_bf16 v[52:55], v[206:209], v[172:175], v[52:55]
	v_mfma_f32_16x16x32_bf16 v[44:47], v[214:217], v[172:175], v[44:47]
	v_mfma_f32_16x16x32_bf16 v[36:39], v[206:209], v[180:183], v[36:39]
	v_mfma_f32_16x16x32_bf16 v[28:31], v[214:217], v[180:183], v[28:31]
	v_mfma_f32_16x16x32_bf16 v[20:23], v[206:209], v[188:191], v[20:23]
	v_mfma_f32_16x16x32_bf16 v[12:15], v[214:217], v[188:191], v[12:15]
	v_mfma_f32_16x16x32_bf16 v[4:7], v[206:209], v[196:199], v[4:7]
	v_mfma_f32_16x16x32_bf16 v[0:3], v[214:217], v[196:199], v[0:3]
	s_add_i32 s52, 0, 0x18000
	v_add_u32_e32 v136, s52, v148
	s_barrier
	s_setprio 0
	ds_read_b128 v[152:155], v136
	ds_read_b128 v[156:159], v136 offset:1024
	ds_read_b128 v[160:163], v136 offset:2048
	ds_read_b128 v[164:167], v136 offset:3072
	ds_read_b128 v[168:171], v150 offset:32768
	ds_read_b128 v[172:175], v150 offset:33792
	ds_read_b128 v[176:179], v150 offset:34816
	ds_read_b128 v[180:183], v150 offset:35840
	ds_read_b128 v[184:187], v150 offset:36864
	ds_read_b128 v[188:191], v150 offset:37888
	ds_read_b128 v[192:195], v150 offset:38912
	ds_read_b128 v[196:199], v150 offset:39936
	s_waitcnt lgkmcnt(8)
	s_waitcnt vmcnt(8)
	s_waitcnt lgkmcnt(0)
	s_setprio 1
	s_barrier
	v_mfma_f32_16x16x32_bf16 v[124:127], v[152:155], v[168:171], v[124:127]
	v_mfma_f32_16x16x32_bf16 v[120:123], v[160:163], v[168:171], v[120:123]
	v_mfma_f32_16x16x32_bf16 v[112:115], v[152:155], v[176:179], v[112:115]
	v_mfma_f32_16x16x32_bf16 v[104:107], v[160:163], v[176:179], v[104:107]
	v_mfma_f32_16x16x32_bf16 v[96:99], v[152:155], v[184:187], v[96:99]
	v_mfma_f32_16x16x32_bf16 v[88:91], v[160:163], v[184:187], v[88:91]
	v_mfma_f32_16x16x32_bf16 v[80:83], v[152:155], v[192:195], v[80:83]
	v_mfma_f32_16x16x32_bf16 v[72:75], v[160:163], v[192:195], v[72:75]
	v_mfma_f32_16x16x32_bf16 v[124:127], v[156:159], v[172:175], v[124:127]
	v_mfma_f32_16x16x32_bf16 v[120:123], v[164:167], v[172:175], v[120:123]
	v_mfma_f32_16x16x32_bf16 v[112:115], v[156:159], v[180:183], v[112:115]
	v_mfma_f32_16x16x32_bf16 v[104:107], v[164:167], v[180:183], v[104:107]
	v_mfma_f32_16x16x32_bf16 v[96:99], v[156:159], v[188:191], v[96:99]
	v_mfma_f32_16x16x32_bf16 v[88:91], v[164:167], v[188:191], v[88:91]
	v_mfma_f32_16x16x32_bf16 v[80:83], v[156:159], v[196:199], v[80:83]
	v_mfma_f32_16x16x32_bf16 v[72:75], v[164:167], v[196:199], v[72:75]
	s_barrier
	s_setprio 0
	s_add_i32 s22, 0, 0x1c000
	s_add_i32 s23, s52, s28
	v_add_u32_e32 v136, s22, v148
	s_add_u32 s0, s20, 0x80
	s_addc_u32 s1, s21, 0
	s_mov_b32 m0, s23
	ds_read_b128 v[202:205], v136
	ds_read_b128 v[206:209], v136 offset:1024
	ds_read_b128 v[210:213], v136 offset:2048
	ds_read_b128 v[214:217], v136 offset:3072
	global_load_lds_dwordx4 v130, s[0:1]
	s_add_i32 m0, s23, 0x2000
	s_nop 0
	global_load_lds_dwordx4 v134, s[0:1]
	s_waitcnt vmcnt(8)
	s_waitcnt lgkmcnt(0)
	s_setprio 1
	s_barrier
	v_mfma_f32_16x16x32_bf16 v[116:119], v[202:205], v[168:171], v[116:119]
	v_mfma_f32_16x16x32_bf16 v[108:111], v[210:213], v[168:171], v[108:111]
	v_mfma_f32_16x16x32_bf16 v[100:103], v[202:205], v[176:179], v[100:103]
	v_mfma_f32_16x16x32_bf16 v[92:95], v[210:213], v[176:179], v[92:95]
	v_mfma_f32_16x16x32_bf16 v[84:87], v[202:205], v[184:187], v[84:87]
	v_mfma_f32_16x16x32_bf16 v[76:79], v[210:213], v[184:187], v[76:79]
	v_mfma_f32_16x16x32_bf16 v[68:71], v[202:205], v[192:195], v[68:71]
	v_mfma_f32_16x16x32_bf16 v[64:67], v[210:213], v[192:195], v[64:67]
	v_mfma_f32_16x16x32_bf16 v[116:119], v[206:209], v[172:175], v[116:119]
	v_mfma_f32_16x16x32_bf16 v[108:111], v[214:217], v[172:175], v[108:111]
	v_mfma_f32_16x16x32_bf16 v[100:103], v[206:209], v[180:183], v[100:103]
	v_mfma_f32_16x16x32_bf16 v[92:95], v[214:217], v[180:183], v[92:95]
	v_mfma_f32_16x16x32_bf16 v[84:87], v[206:209], v[188:191], v[84:87]
	v_mfma_f32_16x16x32_bf16 v[76:79], v[214:217], v[188:191], v[76:79]
	v_mfma_f32_16x16x32_bf16 v[68:71], v[206:209], v[196:199], v[68:71]
	v_mfma_f32_16x16x32_bf16 v[64:67], v[214:217], v[196:199], v[64:67]
	s_mov_b32 m0, s36
	s_mov_b64 s[0:1], 0x80
	v_lshl_add_u64 v[218:219], v[222:223], 0, s[0:1]
	s_barrier
	s_setprio 0
	ds_read_b128 v[168:171], v150 offset:49152
	ds_read_b128 v[172:175], v150 offset:50176
	ds_read_b128 v[176:179], v150 offset:51200
	ds_read_b128 v[180:183], v150 offset:52224
	ds_read_b128 v[184:187], v150 offset:53248
	ds_read_b128 v[188:191], v150 offset:54272
	ds_read_b128 v[192:195], v150 offset:55296
	ds_read_b128 v[196:199], v150 offset:56320
	global_load_lds_dwordx4 v[218:219], off
	v_lshl_add_u64 v[218:219], v[224:225], 0, s[0:1]
	s_mov_b32 m0, s37
	s_nop 0
	global_load_lds_dwordx4 v[218:219], off
	s_waitcnt lgkmcnt(0)
	s_setprio 1
	s_barrier
; #define PG8_STAGE(bufoff, gbase, voff) do { _Pragma("unroll") for (int _i = 0; _i < 2; ++_i) \
;         __builtin_amdgcn_global_load_lds((const unsigned*)((const char*)(gbase) + (voff)[_i]), (LAS unsigned*)(lds + (bufoff) + ldsw + _i * 8192), 16, 0, 0); } while (0)
; #define PG8_LDA(dst, b, h) do { _Pragma("unroll") for (int m = 0; m < 4; ++m) _Pragma("unroll") for (int k = 0; k < 2; ++k) dst[m][k] = *(const LAS bf16x8*)(lds + PG8_SA(b, h) + aoff + m * 2048 + k * 1024); } while (0)
; #define PG8_LDB(dst, b, h) do { _Pragma("unroll") for (int n = 0; n < 2; ++n) _Pragma("unroll") for (int k = 0; k < 2; ++k) dst[n][k] = *(const LAS bf16x8*)(lds + PG8_SB(b, h) + boff + n * 2048 + k * 1024); } while (0)
; #define PG8_MMA(ai, bj, At, Bt) do { __builtin_amdgcn_s_setprio(1); _Pragma("unroll") for (int m = 0; m < 4; ++m) _Pragma("unroll") for (int n = 0; n < 2; ++n) _Pragma("unroll") for (int k = 0; k < 2; ++k) \
;         acc[ai][bj][m][n] = __builtin_amdgcn_mfma_f32_16x16x32_bf16(Bt[n][k], At[m][k], acc[ai][bj][m][n], 0, 0, 0); __builtin_amdgcn_s_setprio(0); } while (0)
; #define PG8_WAIT_V(n) asm volatile("s_waitcnt vmcnt(" #n ")" ::: "memory")
; #define PG8_WAIT_L(n) asm volatile("s_waitcnt lgkmcnt(" #n ")" ::: "memory")
; #define PG8_BAR __builtin_amdgcn_s_barrier()
; #define PG8_SCHED __builtin_amdgcn_sched_barrier(0)
; template <class Epi, class Sched>
; __device__ __forceinline__ void gemm_phase(LAS unsigned char* lds, const Gemm g, const Sched& S, const Epi& E) {
;     ...
;             PG8_LDB(B0, 0, 0); PG8_SCHED; PG8_LDA(At, 0, 0); PG8_STAGE(PG8_SA(1, 1), a1 + hstep, voffA);
;             PG8_WAIT_L(8); PG8_BAR; PG8_WAIT_L(0); PG8_MMA(0, 0, At, B0); PG8_BAR; PG8_SCHED;
;             PG8_LDB(B1, 0, 1); PG8_STAGE(PG8_SB(0, 0), b2, voffB);
;             PG8_BAR; PG8_WAIT_L(0); PG8_MMA(0, 1, At, B1); PG8_BAR;
;             PG8_LDA(At, 0, 1); PG8_STAGE(PG8_SA(0, 0), a2, voffA);
;             PG8_BAR; PG8_WAIT_L(0); PG8_MMA(1, 0, At, B0); PG8_BAR; PG8_SCHED;
;     ...
;             PG8_BAR; PG8_WAIT_L(0); PG8_MMA(1, 0, At, B0); PG8_BAR; PG8_SCHED;
;             PG8_STAGE(PG8_SB(1, 1), b3 + hstep, voffB);
;             PG8_WAIT_V(6); PG8_BAR; PG8_MMA(1, 1, At, B1); PG8_BAR;
	v_mfma_f32_16x16x32_bf16 v[60:63], v[152:155], v[168:171], v[60:63]
	v_mfma_f32_16x16x32_bf16 v[56:59], v[160:163], v[168:171], v[56:59]
	v_mfma_f32_16x16x32_bf16 v[48:51], v[152:155], v[176:179], v[48:51]
	v_mfma_f32_16x16x32_bf16 v[40:43], v[160:163], v[176:179], v[40:43]
	v_mfma_f32_16x16x32_bf16 v[32:35], v[152:155], v[184:187], v[32:35]
	v_mfma_f32_16x16x32_bf16 v[24:27], v[160:163], v[184:187], v[24:27]
	v_mfma_f32_16x16x32_bf16 v[16:19], v[152:155], v[192:195], v[16:19]
	v_mfma_f32_16x16x32_bf16 v[8:11], v[160:163], v[192:195], v[8:11]
	v_mfma_f32_16x16x32_bf16 v[60:63], v[156:159], v[172:175], v[60:63]
	v_mfma_f32_16x16x32_bf16 v[56:59], v[164:167], v[172:175], v[56:59]
	v_mfma_f32_16x16x32_bf16 v[48:51], v[156:159], v[180:183], v[48:51]
	v_mfma_f32_16x16x32_bf16 v[40:43], v[164:167], v[180:183], v[40:43]
	v_mfma_f32_16x16x32_bf16 v[32:35], v[156:159], v[188:191], v[32:35]
	v_mfma_f32_16x16x32_bf16 v[24:27], v[164:167], v[188:191], v[24:27]
	v_mfma_f32_16x16x32_bf16 v[16:19], v[156:159], v[196:199], v[16:19]
	v_mfma_f32_16x16x32_bf16 v[8:11], v[164:167], v[196:199], v[8:11]
	s_barrier
	s_setprio 0
	s_add_u32 s20, s20, 0x40080
	s_addc_u32 s21, s21, 0
	s_add_i32 s22, s22, s28
	s_mov_b32 m0, s22
	s_nop 0
	global_load_lds_dwordx4 v130, s[20:21]
	s_add_i32 m0, s22, 0x2000
	s_nop 0
	global_load_lds_dwordx4 v134, s[20:21]
	s_waitcnt vmcnt(8)
	s_setprio 1
	s_barrier
	v_mfma_f32_16x16x32_bf16 v[52:55], v[202:205], v[168:171], v[52:55]
	v_mfma_f32_16x16x32_bf16 v[44:47], v[210:213], v[168:171], v[44:47]
	v_mfma_f32_16x16x32_bf16 v[36:39], v[202:205], v[176:179], v[36:39]
	v_mfma_f32_16x16x32_bf16 v[28:31], v[210:213], v[176:179], v[28:31]
	v_mfma_f32_16x16x32_bf16 v[20:23], v[202:205], v[184:187], v[20:23]
	v_mfma_f32_16x16x32_bf16 v[12:15], v[210:213], v[184:187], v[12:15]
	v_mfma_f32_16x16x32_bf16 v[4:7], v[202:205], v[192:195], v[4:7]
	v_mfma_f32_16x16x32_bf16 v[0:3], v[210:213], v[192:195], v[0:3]
	v_mfma_f32_16x16x32_bf16 v[52:55], v[206:209], v[172:175], v[52:55]
	v_mfma_f32_16x16x32_bf16 v[44:47], v[214:217], v[172:175], v[44:47]
	v_mfma_f32_16x16x32_bf16 v[36:39], v[206:209], v[180:183], v[36:39]
	v_mfma_f32_16x16x32_bf16 v[28:31], v[214:217], v[180:183], v[28:31]
	v_mfma_f32_16x16x32_bf16 v[20:23], v[206:209], v[188:191], v[20:23]
	v_mfma_f32_16x16x32_bf16 v[12:15], v[214:217], v[188:191], v[12:15]
	v_mfma_f32_16x16x32_bf16 v[4:7], v[206:209], v[196:199], v[4:7]
	v_mfma_f32_16x16x32_bf16 v[0:3], v[214:217], v[196:199], v[0:3]
	s_add_i32 s51, s51, 2
	s_add_u32 s18, s18, 0x100
	s_addc_u32 s19, s19, 0
	s_add_u32 s48, s48, 0x100
	s_addc_u32 s49, s49, 0
	s_cmp_gt_u32 s51, 13
	s_barrier
	s_setprio 0
.LBB0_673:
	ds_read_b128 v[152:155], v149
	ds_read_b128 v[156:159], v149 offset:1024
	ds_read_b128 v[160:163], v149 offset:2048
	ds_read_b128 v[164:167], v149 offset:3072
	s_add_u32 s20, s18, 0xfffc0080
	s_addc_u32 s21, s19, -1
	s_cmp_eq_u32 s51, 12
	s_cselect_b32 s23, s9, s21
	s_cselect_b32 s22, s46, s20
	s_cselect_b32 s21, s7, s49
	s_cselect_b32 s20, s47, s48
	s_add_i32 m0, s17, 0xc000
	ds_read_b128 v[168:171], v150
	ds_read_b128 v[172:175], v150 offset:1024
	ds_read_b128 v[176:179], v150 offset:2048
	ds_read_b128 v[180:183], v150 offset:3072
	ds_read_b128 v[184:187], v150 offset:4096
	ds_read_b128 v[188:191], v150 offset:5120
	ds_read_b128 v[192:195], v150 offset:6144
	ds_read_b128 v[196:199], v150 offset:7168
	global_load_lds_dwordx4 v138, s[18:19]
	s_add_i32 m0, s17, 0xe000
	s_nop 0
	global_load_lds_dwordx4 v140, s[18:19]
	s_waitcnt lgkmcnt(8)
	s_waitcnt vmcnt(8)
	s_waitcnt lgkmcnt(0)
	s_setprio 1
	s_barrier
	v_mfma_f32_16x16x32_bf16 v[124:127], v[152:155], v[168:171], v[124:127]
	v_mfma_f32_16x16x32_bf16 v[120:123], v[160:163], v[168:171], v[120:123]
	v_mfma_f32_16x16x32_bf16 v[112:115], v[152:155], v[176:179], v[112:115]
	v_mfma_f32_16x16x32_bf16 v[104:107], v[160:163], v[176:179], v[104:107]
	v_mfma_f32_16x16x32_bf16 v[96:99], v[152:155], v[184:187], v[96:99]
	v_mfma_f32_16x16x32_bf16 v[88:91], v[160:163], v[184:187], v[88:91]
	v_mfma_f32_16x16x32_bf16 v[80:83], v[152:155], v[192:195], v[80:83]
	v_mfma_f32_16x16x32_bf16 v[72:75], v[160:163], v[192:195], v[72:75]
	v_mfma_f32_16x16x32_bf16 v[124:127], v[156:159], v[172:175], v[124:127]
	v_mfma_f32_16x16x32_bf16 v[120:123], v[164:167], v[172:175], v[120:123]
	v_mfma_f32_16x16x32_bf16 v[112:115], v[156:159], v[180:183], v[112:115]
	v_mfma_f32_16x16x32_bf16 v[104:107], v[164:167], v[180:183], v[104:107]
	v_mfma_f32_16x16x32_bf16 v[96:99], v[156:159], v[188:191], v[96:99]
	v_mfma_f32_16x16x32_bf16 v[88:91], v[164:167], v[188:191], v[88:91]
	v_mfma_f32_16x16x32_bf16 v[80:83], v[156:159], v[196:199], v[80:83]
	v_mfma_f32_16x16x32_bf16 v[72:75], v[164:167], v[196:199], v[72:75]
	s_barrier
	s_setprio 0
	s_add_i32 s52, s43, s28
	s_mov_b32 m0, s52
	ds_read_b128 v[202:205], v151
	ds_read_b128 v[206:209], v151 offset:1024
	ds_read_b128 v[210:213], v151 offset:2048
	ds_read_b128 v[214:217], v151 offset:3072
	global_load_lds_dwordx4 v130, s[20:21]
	s_add_i32 m0, s52, 0x2000
	s_nop 0
	global_load_lds_dwordx4 v134, s[20:21]
	s_waitcnt vmcnt(8)
	s_waitcnt lgkmcnt(0)
	s_setprio 1
	s_barrier
; #define PG8_STAGE(bufoff, gbase, voff) do { _Pragma("unroll") for (int _i = 0; _i < 2; ++_i) \
;         __builtin_amdgcn_global_load_lds((const unsigned*)((const char*)(gbase) + (voff)[_i]), (LAS unsigned*)(lds + (bufoff) + ldsw + _i * 8192), 16, 0, 0); } while (0)
; #define PG8_LDA(dst, b, h) do { _Pragma("unroll") for (int m = 0; m < 4; ++m) _Pragma("unroll") for (int k = 0; k < 2; ++k) dst[m][k] = *(const LAS bf16x8*)(lds + PG8_SA(b, h) + aoff + m * 2048 + k * 1024); } while (0)
; #define PG8_LDB(dst, b, h) do { _Pragma("unroll") for (int n = 0; n < 2; ++n) _Pragma("unroll") for (int k = 0; k < 2; ++k) dst[n][k] = *(const LAS bf16x8*)(lds + PG8_SB(b, h) + boff + n * 2048 + k * 1024); } while (0)
; #define PG8_MMA(ai, bj, At, Bt) do { __builtin_amdgcn_s_setprio(1); _Pragma("unroll") for (int m = 0; m < 4; ++m) _Pragma("unroll") for (int n = 0; n < 2; ++n) _Pragma("unroll") for (int k = 0; k < 2; ++k) \
;         acc[ai][bj][m][n] = __builtin_amdgcn_mfma_f32_16x16x32_bf16(Bt[n][k], At[m][k], acc[ai][bj][m][n], 0, 0, 0); __builtin_amdgcn_s_setprio(0); } while (0)
; #define PG8_WAIT_V(n) asm volatile("s_waitcnt vmcnt(" #n ")" ::: "memory")
; #define PG8_WAIT_L(n) asm volatile("s_waitcnt lgkmcnt(" #n ")" ::: "memory")
; #define PG8_BAR __builtin_amdgcn_s_barrier()
; #define PG8_SCHED __builtin_amdgcn_sched_barrier(0)
; template <class Epi, class Sched>
; __device__ __forceinline__ void gemm_phase(LAS unsigned char* lds, const Gemm g, const Sched& S, const Epi& E) {
;     ...
;             PG8_WAIT_L(8); PG8_BAR; PG8_WAIT_L(0); PG8_MMA(0, 0, At, B0); PG8_BAR; PG8_SCHED;
;             PG8_LDB(B1, 0, 1); PG8_STAGE(PG8_SB(0, 0), b2, voffB);
;             PG8_BAR; PG8_WAIT_L(0); PG8_MMA(0, 1, At, B1); PG8_BAR;
;             PG8_LDA(At, 0, 1); PG8_STAGE(PG8_SA(0, 0), a2, voffA);
;             PG8_BAR; PG8_WAIT_L(0); PG8_MMA(1, 0, At, B0); PG8_BAR; PG8_SCHED;
;             PG8_STAGE(PG8_SB(0, 1), b2 + hstep, voffB);
;             PG8_WAIT_V(6); PG8_BAR; PG8_MMA(1, 1, At, B1); PG8_BAR;
;             PG8_LDB(B0, 1, 0); PG8_SCHED; PG8_LDA(At, 1, 0); PG8_STAGE(PG8_SA(0, 1), a2 + hstep, voffA);
;             PG8_WAIT_L(8); PG8_BAR; PG8_WAIT_L(0); PG8_MMA(0, 0, At, B0); PG8_BAR; PG8_SCHED;
	v_mfma_f32_16x16x32_bf16 v[116:119], v[202:205], v[168:171], v[116:119]
	v_mfma_f32_16x16x32_bf16 v[108:111], v[210:213], v[168:171], v[108:111]
	v_mfma_f32_16x16x32_bf16 v[100:103], v[202:205], v[176:179], v[100:103]
	v_mfma_f32_16x16x32_bf16 v[92:95], v[210:213], v[176:179], v[92:95]
	v_mfma_f32_16x16x32_bf16 v[84:87], v[202:205], v[184:187], v[84:87]
	v_mfma_f32_16x16x32_bf16 v[76:79], v[210:213], v[184:187], v[76:79]
	v_mfma_f32_16x16x32_bf16 v[68:71], v[202:205], v[192:195], v[68:71]
	v_mfma_f32_16x16x32_bf16 v[64:67], v[210:213], v[192:195], v[64:67]
	v_mfma_f32_16x16x32_bf16 v[116:119], v[206:209], v[172:175], v[116:119]
	v_mfma_f32_16x16x32_bf16 v[108:111], v[214:217], v[172:175], v[108:111]
	v_mfma_f32_16x16x32_bf16 v[100:103], v[206:209], v[180:183], v[100:103]
	v_mfma_f32_16x16x32_bf16 v[92:95], v[214:217], v[180:183], v[92:95]
	v_mfma_f32_16x16x32_bf16 v[84:87], v[206:209], v[188:191], v[84:87]
	v_mfma_f32_16x16x32_bf16 v[76:79], v[214:217], v[188:191], v[76:79]
	v_mfma_f32_16x16x32_bf16 v[68:71], v[206:209], v[196:199], v[68:71]
	v_mfma_f32_16x16x32_bf16 v[64:67], v[214:217], v[196:199], v[64:67]
	s_mov_b32 m0, s17
	v_lshl_add_u64 v[222:223], s[22:23], 0, v[128:129]
	s_barrier
	s_setprio 0
	ds_read_b128 v[168:171], v150 offset:16384
	ds_read_b128 v[172:175], v150 offset:17408
	ds_read_b128 v[176:179], v150 offset:18432
	ds_read_b128 v[180:183], v150 offset:19456
	ds_read_b128 v[184:187], v150 offset:20480
	ds_read_b128 v[188:191], v150 offset:21504
	ds_read_b128 v[192:195], v150 offset:22528
	ds_read_b128 v[196:199], v150 offset:23552
	global_load_lds_dwordx4 v128, s[22:23]
	v_lshl_add_u64 v[224:225], s[22:23], 0, v[132:133]
	s_mov_b32 m0, s29
	s_nop 0
	global_load_lds_dwordx4 v132, s[22:23]
	s_waitcnt lgkmcnt(0)
	s_setprio 1
	s_barrier
	v_mfma_f32_16x16x32_bf16 v[60:63], v[152:155], v[168:171], v[60:63]
	v_mfma_f32_16x16x32_bf16 v[56:59], v[160:163], v[168:171], v[56:59]
	v_mfma_f32_16x16x32_bf16 v[48:51], v[152:155], v[176:179], v[48:51]
	v_mfma_f32_16x16x32_bf16 v[40:43], v[160:163], v[176:179], v[40:43]
	v_mfma_f32_16x16x32_bf16 v[32:35], v[152:155], v[184:187], v[32:35]
	v_mfma_f32_16x16x32_bf16 v[24:27], v[160:163], v[184:187], v[24:27]
	v_mfma_f32_16x16x32_bf16 v[16:19], v[152:155], v[192:195], v[16:19]
	v_mfma_f32_16x16x32_bf16 v[8:11], v[160:163], v[192:195], v[8:11]
	v_mfma_f32_16x16x32_bf16 v[60:63], v[156:159], v[172:175], v[60:63]
	v_mfma_f32_16x16x32_bf16 v[56:59], v[164:167], v[172:175], v[56:59]
	v_mfma_f32_16x16x32_bf16 v[48:51], v[156:159], v[180:183], v[48:51]
	v_mfma_f32_16x16x32_bf16 v[40:43], v[164:167], v[180:183], v[40:43]
	v_mfma_f32_16x16x32_bf16 v[32:35], v[156:159], v[188:191], v[32:35]
	v_mfma_f32_16x16x32_bf16 v[24:27], v[164:167], v[188:191], v[24:27]
	v_mfma_f32_16x16x32_bf16 v[16:19], v[156:159], v[196:199], v[16:19]
	v_mfma_f32_16x16x32_bf16 v[8:11], v[164:167], v[196:199], v[8:11]
	s_barrier
	s_setprio 0
	s_add_u32 s52, s20, 0x40000
	s_addc_u32 s53, s21, 0
	s_add_i32 s54, s44, s28
	s_mov_b32 m0, s54
	s_nop 0
	global_load_lds_dwordx4 v130, s[52:53]
	s_add_i32 m0, s54, 0x2000
	s_nop 0
	global_load_lds_dwordx4 v134, s[52:53]
	s_add_u32 s22, s22, 0x40000
	s_addc_u32 s23, s23, 0
	s_mov_b32 m0, s30
	s_nop 0
	global_load_lds_dwordx4 v128, s[22:23]
	s_mov_b32 m0, s31
	s_nop 0
	global_load_lds_dwordx4 v132, s[22:23]
	s_waitcnt vmcnt(10)
	s_setprio 1
	s_barrier
	v_mfma_f32_16x16x32_bf16 v[52:55], v[202:205], v[168:171], v[52:55]
	v_mfma_f32_16x16x32_bf16 v[44:47], v[210:213], v[168:171], v[44:47]
	v_mfma_f32_16x16x32_bf16 v[36:39], v[202:205], v[176:179], v[36:39]
	v_mfma_f32_16x16x32_bf16 v[28:31], v[210:213], v[176:179], v[28:31]
	v_mfma_f32_16x16x32_bf16 v[20:23], v[202:205], v[184:187], v[20:23]
	v_mfma_f32_16x16x32_bf16 v[12:15], v[210:213], v[184:187], v[12:15]
	v_mfma_f32_16x16x32_bf16 v[4:7], v[202:205], v[192:195], v[4:7]
	v_mfma_f32_16x16x32_bf16 v[0:3], v[210:213], v[192:195], v[0:3]
	v_mfma_f32_16x16x32_bf16 v[52:55], v[206:209], v[172:175], v[52:55]
	v_mfma_f32_16x16x32_bf16 v[44:47], v[214:217], v[172:175], v[44:47]
	v_mfma_f32_16x16x32_bf16 v[36:39], v[206:209], v[180:183], v[36:39]
	v_mfma_f32_16x16x32_bf16 v[28:31], v[214:217], v[180:183], v[28:31]
	v_mfma_f32_16x16x32_bf16 v[20:23], v[206:209], v[188:191], v[20:23]
	v_mfma_f32_16x16x32_bf16 v[12:15], v[214:217], v[188:191], v[12:15]
	v_mfma_f32_16x16x32_bf16 v[4:7], v[206:209], v[196:199], v[4:7]
	v_mfma_f32_16x16x32_bf16 v[0:3], v[214:217], v[196:199], v[0:3]
	s_add_i32 s52, 0, 0x18000
	v_add_u32_e32 v136, s52, v148
	s_barrier
	s_setprio 0
	ds_read_b128 v[152:155], v136
	ds_read_b128 v[156:159], v136 offset:1024
	ds_read_b128 v[160:163], v136 offset:2048
	ds_read_b128 v[164:167], v136 offset:3072
	ds_read_b128 v[168:171], v150 offset:32768
	ds_read_b128 v[172:175], v150 offset:33792
	ds_read_b128 v[176:179], v150 offset:34816
	ds_read_b128 v[180:183], v150 offset:35840
	ds_read_b128 v[184:187], v150 offset:36864
	ds_read_b128 v[188:191], v150 offset:37888
	ds_read_b128 v[192:195], v150 offset:38912
	ds_read_b128 v[196:199], v150 offset:39936
	s_waitcnt lgkmcnt(8)
	s_waitcnt vmcnt(8)
	s_waitcnt lgkmcnt(0)
	s_setprio 1
	s_barrier
; #define PG8_STAGE(bufoff, gbase, voff) do { _Pragma("unroll") for (int _i = 0; _i < 2; ++_i) \
;         __builtin_amdgcn_global_load_lds((const unsigned*)((const char*)(gbase) + (voff)[_i]), (LAS unsigned*)(lds + (bufoff) + ldsw + _i * 8192), 16, 0, 0); } while (0)
; #define PG8_LDA(dst, b, h) do { _Pragma("unroll") for (int m = 0; m < 4; ++m) _Pragma("unroll") for (int k = 0; k < 2; ++k) dst[m][k] = *(const LAS bf16x8*)(lds + PG8_SA(b, h) + aoff + m * 2048 + k * 1024); } while (0)
; #define PG8_LDB(dst, b, h) do { _Pragma("unroll") for (int n = 0; n < 2; ++n) _Pragma("unroll") for (int k = 0; k < 2; ++k) dst[n][k] = *(const LAS bf16x8*)(lds + PG8_SB(b, h) + boff + n * 2048 + k * 1024); } while (0)
; #define PG8_MMA(ai, bj, At, Bt) do { __builtin_amdgcn_s_setprio(1); _Pragma("unroll") for (int m = 0; m < 4; ++m) _Pragma("unroll") for (int n = 0; n < 2; ++n) _Pragma("unroll") for (int k = 0; k < 2; ++k) \
;         acc[ai][bj][m][n] = __builtin_amdgcn_mfma_f32_16x16x32_bf16(Bt[n][k], At[m][k], acc[ai][bj][m][n], 0, 0, 0); __builtin_amdgcn_s_setprio(0); } while (0)
; #define PG8_WAIT_V(n) asm volatile("s_waitcnt vmcnt(" #n ")" ::: "memory")
; #define PG8_WAIT_L(n) asm volatile("s_waitcnt lgkmcnt(" #n ")" ::: "memory")
; #define PG8_BAR __builtin_amdgcn_s_barrier()
; #define PG8_SCHED __builtin_amdgcn_sched_barrier(0)
; template <class Epi, class Sched>
; __device__ __forceinline__ void gemm_phase(LAS unsigned char* lds, const Gemm g, const Sched& S, const Epi& E) {
;     ...
;             PG8_WAIT_L(8); PG8_BAR; PG8_WAIT_L(0); PG8_MMA(0, 0, At, B0); PG8_BAR; PG8_SCHED;
;             PG8_LDB(B1, 1, 1); PG8_STAGE(PG8_SB(1, 0), b3, voffB);
;             PG8_BAR; PG8_WAIT_L(0); PG8_MMA(0, 1, At, B1); PG8_BAR;
;             PG8_LDA(At, 1, 1); PG8_STAGE(PG8_SA(1, 0), a3, voffA);
;             PG8_BAR; PG8_WAIT_L(0); PG8_MMA(1, 0, At, B0); PG8_BAR; PG8_SCHED;
;             PG8_STAGE(PG8_SB(1, 1), b3 + hstep, voffB);
;             PG8_WAIT_V(6); PG8_BAR; PG8_MMA(1, 1, At, B1); PG8_BAR;
	v_mfma_f32_16x16x32_bf16 v[124:127], v[152:155], v[168:171], v[124:127]
	v_mfma_f32_16x16x32_bf16 v[120:123], v[160:163], v[168:171], v[120:123]
	v_mfma_f32_16x16x32_bf16 v[112:115], v[152:155], v[176:179], v[112:115]
	v_mfma_f32_16x16x32_bf16 v[104:107], v[160:163], v[176:179], v[104:107]
	v_mfma_f32_16x16x32_bf16 v[96:99], v[152:155], v[184:187], v[96:99]
	v_mfma_f32_16x16x32_bf16 v[88:91], v[160:163], v[184:187], v[88:91]
	v_mfma_f32_16x16x32_bf16 v[80:83], v[152:155], v[192:195], v[80:83]
	v_mfma_f32_16x16x32_bf16 v[72:75], v[160:163], v[192:195], v[72:75]
	v_mfma_f32_16x16x32_bf16 v[124:127], v[156:159], v[172:175], v[124:127]
	v_mfma_f32_16x16x32_bf16 v[120:123], v[164:167], v[172:175], v[120:123]
	v_mfma_f32_16x16x32_bf16 v[112:115], v[156:159], v[180:183], v[112:115]
	v_mfma_f32_16x16x32_bf16 v[104:107], v[164:167], v[180:183], v[104:107]
	v_mfma_f32_16x16x32_bf16 v[96:99], v[156:159], v[188:191], v[96:99]
	v_mfma_f32_16x16x32_bf16 v[88:91], v[164:167], v[188:191], v[88:91]
	v_mfma_f32_16x16x32_bf16 v[80:83], v[156:159], v[196:199], v[80:83]
	v_mfma_f32_16x16x32_bf16 v[72:75], v[164:167], v[196:199], v[72:75]
	s_barrier
	s_setprio 0
	s_add_i32 s22, 0, 0x1c000
	s_add_i32 s23, s52, s28
	v_add_u32_e32 v136, s22, v148
	s_add_u32 s0, s20, 0x80
	s_addc_u32 s1, s21, 0
	s_mov_b32 m0, s23
	ds_read_b128 v[202:205], v136
	ds_read_b128 v[206:209], v136 offset:1024
	ds_read_b128 v[210:213], v136 offset:2048
	ds_read_b128 v[214:217], v136 offset:3072
	global_load_lds_dwordx4 v130, s[0:1]
	s_add_i32 m0, s23, 0x2000
	s_nop 0
	global_load_lds_dwordx4 v134, s[0:1]
	s_waitcnt vmcnt(8)
	s_waitcnt lgkmcnt(0)
	s_setprio 1
	s_barrier
	v_mfma_f32_16x16x32_bf16 v[116:119], v[202:205], v[168:171], v[116:119]
	v_mfma_f32_16x16x32_bf16 v[108:111], v[210:213], v[168:171], v[108:111]
	v_mfma_f32_16x16x32_bf16 v[100:103], v[202:205], v[176:179], v[100:103]
	v_mfma_f32_16x16x32_bf16 v[92:95], v[210:213], v[176:179], v[92:95]
	v_mfma_f32_16x16x32_bf16 v[84:87], v[202:205], v[184:187], v[84:87]
	v_mfma_f32_16x16x32_bf16 v[76:79], v[210:213], v[184:187], v[76:79]
	v_mfma_f32_16x16x32_bf16 v[68:71], v[202:205], v[192:195], v[68:71]
	v_mfma_f32_16x16x32_bf16 v[64:67], v[210:213], v[192:195], v[64:67]
	v_mfma_f32_16x16x32_bf16 v[116:119], v[206:209], v[172:175], v[116:119]
	v_mfma_f32_16x16x32_bf16 v[108:111], v[214:217], v[172:175], v[108:111]
	v_mfma_f32_16x16x32_bf16 v[100:103], v[206:209], v[180:183], v[100:103]
	v_mfma_f32_16x16x32_bf16 v[92:95], v[214:217], v[180:183], v[92:95]
	v_mfma_f32_16x16x32_bf16 v[84:87], v[206:209], v[188:191], v[84:87]
	v_mfma_f32_16x16x32_bf16 v[76:79], v[214:217], v[188:191], v[76:79]
	v_mfma_f32_16x16x32_bf16 v[68:71], v[206:209], v[196:199], v[68:71]
	v_mfma_f32_16x16x32_bf16 v[64:67], v[214:217], v[196:199], v[64:67]
	s_mov_b32 m0, s36
	s_mov_b64 s[0:1], 0x80
	v_lshl_add_u64 v[218:219], v[222:223], 0, s[0:1]
	s_barrier
	s_setprio 0
	ds_read_b128 v[168:171], v150 offset:49152
	ds_read_b128 v[172:175], v150 offset:50176
	ds_read_b128 v[176:179], v150 offset:51200
	ds_read_b128 v[180:183], v150 offset:52224
	ds_read_b128 v[184:187], v150 offset:53248
	ds_read_b128 v[188:191], v150 offset:54272
	ds_read_b128 v[192:195], v150 offset:55296
	ds_read_b128 v[196:199], v150 offset:56320
	global_load_lds_dwordx4 v[218:219], off
	v_lshl_add_u64 v[218:219], v[224:225], 0, s[0:1]
	s_mov_b32 m0, s37
	s_nop 0
	global_load_lds_dwordx4 v[218:219], off
	s_waitcnt lgkmcnt(0)
	s_setprio 1
	s_barrier
	v_mfma_f32_16x16x32_bf16 v[60:63], v[152:155], v[168:171], v[60:63]
	v_mfma_f32_16x16x32_bf16 v[56:59], v[160:163], v[168:171], v[56:59]
	v_mfma_f32_16x16x32_bf16 v[48:51], v[152:155], v[176:179], v[48:51]
	v_mfma_f32_16x16x32_bf16 v[40:43], v[160:163], v[176:179], v[40:43]
	v_mfma_f32_16x16x32_bf16 v[32:35], v[152:155], v[184:187], v[32:35]
	v_mfma_f32_16x16x32_bf16 v[24:27], v[160:163], v[184:187], v[24:27]
	v_mfma_f32_16x16x32_bf16 v[16:19], v[152:155], v[192:195], v[16:19]
	v_mfma_f32_16x16x32_bf16 v[8:11], v[160:163], v[192:195], v[8:11]
	v_mfma_f32_16x16x32_bf16 v[60:63], v[156:159], v[172:175], v[60:63]
	v_mfma_f32_16x16x32_bf16 v[56:59], v[164:167], v[172:175], v[56:59]
	v_mfma_f32_16x16x32_bf16 v[48:51], v[156:159], v[180:183], v[48:51]
	v_mfma_f32_16x16x32_bf16 v[40:43], v[164:167], v[180:183], v[40:43]
	v_mfma_f32_16x16x32_bf16 v[32:35], v[156:159], v[188:191], v[32:35]
	v_mfma_f32_16x16x32_bf16 v[24:27], v[164:167], v[188:191], v[24:27]
	v_mfma_f32_16x16x32_bf16 v[16:19], v[156:159], v[196:199], v[16:19]
	v_mfma_f32_16x16x32_bf16 v[8:11], v[164:167], v[196:199], v[8:11]
	s_barrier
	s_setprio 0
	s_add_u32 s20, s20, 0x40080
	s_addc_u32 s21, s21, 0
	s_add_i32 s22, s22, s28
	s_mov_b32 m0, s22
	s_nop 0
	global_load_lds_dwordx4 v130, s[20:21]
	s_add_i32 m0, s22, 0x2000
	s_nop 0
	global_load_lds_dwordx4 v134, s[20:21]
	s_waitcnt vmcnt(8)
	s_setprio 1
	s_barrier
	v_mfma_f32_16x16x32_bf16 v[52:55], v[202:205], v[168:171], v[52:55]
	v_mfma_f32_16x16x32_bf16 v[44:47], v[210:213], v[168:171], v[44:47]
	v_mfma_f32_16x16x32_bf16 v[36:39], v[202:205], v[176:179], v[36:39]
	v_mfma_f32_16x16x32_bf16 v[28:31], v[210:213], v[176:179], v[28:31]
	v_mfma_f32_16x16x32_bf16 v[20:23], v[202:205], v[184:187], v[20:23]
	v_mfma_f32_16x16x32_bf16 v[12:15], v[210:213], v[184:187], v[12:15]
	v_mfma_f32_16x16x32_bf16 v[4:7], v[202:205], v[192:195], v[4:7]
	v_mfma_f32_16x16x32_bf16 v[0:3], v[210:213], v[192:195], v[0:3]
	v_mfma_f32_16x16x32_bf16 v[52:55], v[206:209], v[172:175], v[52:55]
	v_mfma_f32_16x16x32_bf16 v[44:47], v[214:217], v[172:175], v[44:47]
	v_mfma_f32_16x16x32_bf16 v[36:39], v[206:209], v[180:183], v[36:39]
	v_mfma_f32_16x16x32_bf16 v[28:31], v[214:217], v[180:183], v[28:31]
	v_mfma_f32_16x16x32_bf16 v[20:23], v[206:209], v[188:191], v[20:23]
	v_mfma_f32_16x16x32_bf16 v[12:15], v[214:217], v[188:191], v[12:15]
	v_mfma_f32_16x16x32_bf16 v[4:7], v[206:209], v[196:199], v[4:7]
	v_mfma_f32_16x16x32_bf16 v[0:3], v[214:217], v[196:199], v[0:3]
	s_add_i32 s51, s51, 2
	s_add_u32 s18, s18, 0x100
	s_addc_u32 s19, s19, 0
	s_add_u32 s48, s48, 0x100
	s_addc_u32 s49, s49, 0
	s_cmp_gt_u32 s51, 13
	s_barrier
; __device__ __forceinline__ unsigned cvt_pk_bf16(float lo, float hi) { unsigned r; asm volatile("v_cvt_pk_bf16_f32 %0, %1, %2" : "=v"(r) : "v"(lo), "v"(hi)); return r; }
; template <class Epi, class Sched>
; __device__ __forceinline__ void gemm_phase(LAS unsigned char* lds, const Gemm g, const Sched& S, const Epi& E) {
;     ...
;         E(acc, cur, wr, wc, fr, fq);
;     __device__ __forceinline__ void operator()(const AccT& acc, const Unit& u, int wr, int wc, int fr, int fq) const {
;         asm volatile("" : "+v"(fr), "+v"(fq));
;         const int rbase = u.pm * 256 + wr * 64 + fr;
;         const int tb = u.pn * 256 + wc * 32 + 8 * fq;
; #pragma unroll
;         for (int ai = 0; ai < 2; ++ai)
; #pragma unroll
;             for (int m = 0; m < 4; ++m) {
;                 const int gm = rbase + ai * 128 + m * 16;
; #pragma unroll
;                 for (int bj = 0; bj < 2; ++bj) {
;                     const int t0 = tb + bj * 128;
;                     const f32x4 v0 = acc[ai][bj][m][0], v1 = acc[ai][bj][m][1];
;                     u32x4 w; w.x = cvt_pk_bf16(v0[0], v0[1]); w.y = cvt_pk_bf16(v0[2], v0[3]); w.z = cvt_pk_bf16(v1[0], v1[1]); w.w = cvt_pk_bf16(v1[2], v1[3]);
;                     *(u32x4*)(YT + ((size_t)((t0 >> 10) * 512 + gm)) * 2048 + part * 1024 + (t0 & 1023)) = w;
;                 }
	s_setprio 0
	s_cbranch_scc0 .LBB0_673
	v_mov_b32_e32 v136, v147
	v_mov_b32_e32 v152, v146
	s_lshl_b32 s7, s16, 8
	s_add_i32 s7, s7, s34
	v_add_u32_e32 v152, s7, v152
	s_lshl_b32 s7, s45, 8
	s_or_b32 s7, s7, s35
	v_lshl_add_u32 v153, v136, 3, s7
	v_cvt_pk_bf16_f32 v124, v124, v125
	v_cvt_pk_bf16_f32 v125, v126, v127
	v_cvt_pk_bf16_f32 v126, v120, v121
	v_ashrrev_i32_e32 v120, 1, v153
	v_cvt_pk_bf16_f32 v127, v122, v123
	v_and_b32_e32 v122, 0xfffffe00, v120
	v_add_u32_e32 v120, v122, v152
	v_ashrrev_i32_e32 v121, 31, v120
	v_lshlrev_b64 v[120:121], 12, v[120:121]
	v_and_b32_e32 v123, 0x3f8, v153
	v_lshl_add_u64 v[120:121], s[4:5], 0, v[120:121]
	v_lshlrev_b32_e32 v136, 1, v123
	v_lshl_add_u64 v[120:121], v[120:121], 0, v[136:137]
	global_store_dwordx4 v[120:121], v[124:127], off
	v_add_u32_e32 v120, 0x80, v153
	v_cvt_pk_bf16_f32 v116, v116, v117
	v_cvt_pk_bf16_f32 v117, v118, v119
	v_cvt_pk_bf16_f32 v118, v108, v109
	v_ashrrev_i32_e32 v108, 1, v120
	v_and_b32_e32 v121, 0xfffffe00, v108
	v_add_u32_e32 v108, v121, v152
	v_ashrrev_i32_e32 v109, 31, v108
	v_lshlrev_b64 v[108:109], 12, v[108:109]
	v_cvt_pk_bf16_f32 v119, v110, v111
	v_lshl_add_u64 v[110:111], s[4:5], 0, v[108:109]
	v_and_b32_e32 v108, 0x3f8, v120
	v_lshlrev_b32_e32 v108, 1, v108
	v_mov_b32_e32 v109, v137
	v_lshl_add_u64 v[110:111], v[110:111], 0, v[108:109]
	global_store_dwordx4 v[110:111], v[116:119], off
	v_cvt_pk_bf16_f32 v110, v112, v113
	v_cvt_pk_bf16_f32 v111, v114, v115
	v_cvt_pk_bf16_f32 v112, v104, v105
	v_cvt_pk_bf16_f32 v113, v106, v107
	s_and_b64 vcc, exec, s[2:3]
	s_nop 0
	v_add_u32_e32 v116, 16, v152
	v_add_u32_e32 v104, v122, v116
	v_ashrrev_i32_e32 v105, 31, v104
	v_lshlrev_b64 v[104:105], 12, v[104:105]
	v_lshl_add_u64 v[104:105], s[4:5], 0, v[104:105]
	v_lshl_add_u64 v[104:105], v[104:105], 0, v[136:137]
	global_store_dwordx4 v[104:105], v[110:113], off
	v_cvt_pk_bf16_f32 v100, v100, v101
	v_cvt_pk_bf16_f32 v101, v102, v103
	v_cvt_pk_bf16_f32 v102, v92, v93
	v_add_u32_e32 v92, v121, v116
	v_ashrrev_i32_e32 v93, 31, v92
	v_lshlrev_b64 v[92:93], 12, v[92:93]
	v_lshl_add_u64 v[92:93], s[4:5], 0, v[92:93]
	v_lshl_add_u64 v[92:93], v[92:93], 0, v[108:109]
	v_cvt_pk_bf16_f32 v103, v94, v95
	global_store_dwordx4 v[92:93], v[100:103], off
	v_cvt_pk_bf16_f32 v92, v96, v97
	v_cvt_pk_bf16_f32 v93, v98, v99
	v_cvt_pk_bf16_f32 v94, v88, v89
	v_cvt_pk_bf16_f32 v95, v90, v91
	s_mov_b32 s45, s6
	s_nop 0
	v_add_u32_e32 v100, 32, v152
	v_add_u32_e32 v88, v122, v100
	v_ashrrev_i32_e32 v89, 31, v88
	v_lshlrev_b64 v[88:89], 12, v[88:89]
	v_lshl_add_u64 v[88:89], s[4:5], 0, v[88:89]
	v_lshl_add_u64 v[88:89], v[88:89], 0, v[136:137]
	global_store_dwordx4 v[88:89], v[92:95], off
	v_cvt_pk_bf16_f32 v84, v84, v85
	v_cvt_pk_bf16_f32 v85, v86, v87
	v_cvt_pk_bf16_f32 v86, v76, v77
	v_add_u32_e32 v76, v121, v100
	v_ashrrev_i32_e32 v77, 31, v76
	v_lshlrev_b64 v[76:77], 12, v[76:77]
	v_lshl_add_u64 v[76:77], s[4:5], 0, v[76:77]
	v_lshl_add_u64 v[76:77], v[76:77], 0, v[108:109]
	v_cvt_pk_bf16_f32 v87, v78, v79
	global_store_dwordx4 v[76:77], v[84:87], off
	v_cvt_pk_bf16_f32 v76, v80, v81
	v_cvt_pk_bf16_f32 v77, v82, v83
	v_cvt_pk_bf16_f32 v78, v72, v73
	v_cvt_pk_bf16_f32 v79, v74, v75
	s_mov_b32 s16, s8
	s_nop 0
	v_add_u32_e32 v84, 48, v152
	v_add_u32_e32 v72, v122, v84
	v_ashrrev_i32_e32 v73, 31, v72
	v_lshlrev_b64 v[72:73], 12, v[72:73]
	v_lshl_add_u64 v[72:73], s[4:5], 0, v[72:73]
	v_lshl_add_u64 v[72:73], v[72:73], 0, v[136:137]
	global_store_dwordx4 v[72:73], v[76:79], off
	v_cvt_pk_bf16_f32 v68, v68, v69
	v_cvt_pk_bf16_f32 v69, v70, v71
	v_cvt_pk_bf16_f32 v70, v64, v65
	v_add_u32_e32 v64, v121, v84
	v_ashrrev_i32_e32 v65, 31, v64
	v_lshlrev_b64 v[64:65], 12, v[64:65]
	v_lshl_add_u64 v[64:65], s[4:5], 0, v[64:65]
	v_lshl_add_u64 v[64:65], v[64:65], 0, v[108:109]
	v_cvt_pk_bf16_f32 v71, v66, v67
	global_store_dwordx4 v[64:65], v[68:71], off
	v_add_u32_e32 v64, 0x80, v152
	v_cvt_pk_bf16_f32 v60, v60, v61
	v_cvt_pk_bf16_f32 v61, v62, v63
	v_cvt_pk_bf16_f32 v62, v56, v57
	v_add_u32_e32 v56, v122, v64
	v_ashrrev_i32_e32 v57, 31, v56
	v_lshlrev_b64 v[56:57], 12, v[56:57]
	v_lshl_add_u64 v[56:57], s[4:5], 0, v[56:57]
	v_lshl_add_u64 v[56:57], v[56:57], 0, v[136:137]
	v_cvt_pk_bf16_f32 v63, v58, v59
	global_store_dwordx4 v[56:57], v[60:63], off
	v_cvt_pk_bf16_f32 v52, v52, v53
	v_cvt_pk_bf16_f32 v53, v54, v55
	v_cvt_pk_bf16_f32 v54, v44, v45
	v_add_u32_e32 v44, v121, v64
	v_ashrrev_i32_e32 v45, 31, v44
	v_lshlrev_b64 v[44:45], 12, v[44:45]
	v_lshl_add_u64 v[44:45], s[4:5], 0, v[44:45]
	v_lshl_add_u64 v[44:45], v[44:45], 0, v[108:109]
	v_cvt_pk_bf16_f32 v55, v46, v47
	global_store_dwordx4 v[44:45], v[52:55], off
	v_cvt_pk_bf16_f32 v44, v48, v49
	v_cvt_pk_bf16_f32 v45, v50, v51
	v_cvt_pk_bf16_f32 v46, v40, v41
	v_cvt_pk_bf16_f32 v47, v42, v43
	s_mov_b64 s[20:21], s[14:15]
	s_nop 0
	v_add_u32_e32 v52, 0x90, v152
	v_add_u32_e32 v40, v122, v52
	v_ashrrev_i32_e32 v41, 31, v40
	v_lshlrev_b64 v[40:41], 12, v[40:41]
	v_lshl_add_u64 v[40:41], s[4:5], 0, v[40:41]
	v_lshl_add_u64 v[40:41], v[40:41], 0, v[136:137]
	global_store_dwordx4 v[40:41], v[44:47], off
	v_cvt_pk_bf16_f32 v36, v36, v37
	v_cvt_pk_bf16_f32 v37, v38, v39
	v_cvt_pk_bf16_f32 v38, v28, v29
	v_add_u32_e32 v28, v121, v52
	v_ashrrev_i32_e32 v29, 31, v28
	v_lshlrev_b64 v[28:29], 12, v[28:29]
	v_lshl_add_u64 v[28:29], s[4:5], 0, v[28:29]
	v_lshl_add_u64 v[28:29], v[28:29], 0, v[108:109]
	v_cvt_pk_bf16_f32 v39, v30, v31
	global_store_dwordx4 v[28:29], v[36:39], off
	v_cvt_pk_bf16_f32 v28, v32, v33
	v_cvt_pk_bf16_f32 v29, v34, v35
	v_cvt_pk_bf16_f32 v30, v24, v25
	v_cvt_pk_bf16_f32 v31, v26, v27
	s_mov_b64 s[18:19], s[12:13]
	s_nop 0
	v_add_u32_e32 v36, 0xa0, v152
	v_add_u32_e32 v24, v122, v36
	v_ashrrev_i32_e32 v25, 31, v24
	v_lshlrev_b64 v[24:25], 12, v[24:25]
	v_lshl_add_u64 v[24:25], s[4:5], 0, v[24:25]
	v_lshl_add_u64 v[24:25], v[24:25], 0, v[136:137]
	global_store_dwordx4 v[24:25], v[28:31], off
	v_cvt_pk_bf16_f32 v20, v20, v21
	v_cvt_pk_bf16_f32 v21, v22, v23
	v_cvt_pk_bf16_f32 v22, v12, v13
	v_add_u32_e32 v12, v121, v36
	v_ashrrev_i32_e32 v13, 31, v12
	v_lshlrev_b64 v[12:13], 12, v[12:13]
	v_lshl_add_u64 v[12:13], s[4:5], 0, v[12:13]
	v_lshl_add_u64 v[12:13], v[12:13], 0, v[108:109]
	v_cvt_pk_bf16_f32 v23, v14, v15
	global_store_dwordx4 v[12:13], v[20:23], off
	v_cvt_pk_bf16_f32 v12, v16, v17
	v_cvt_pk_bf16_f32 v13, v18, v19
	v_cvt_pk_bf16_f32 v14, v8, v9
	v_cvt_pk_bf16_f32 v15, v10, v11
	s_nop 1
	v_add_u32_e32 v20, 0xb0, v152
	v_add_u32_e32 v8, v122, v20
	v_ashrrev_i32_e32 v9, 31, v8
	v_lshlrev_b64 v[8:9], 12, v[8:9]
	v_lshl_add_u64 v[8:9], s[4:5], 0, v[8:9]
	v_lshl_add_u64 v[8:9], v[8:9], 0, v[136:137]
	global_store_dwordx4 v[8:9], v[12:15], off
	v_cvt_pk_bf16_f32 v4, v4, v5
	v_cvt_pk_bf16_f32 v5, v6, v7
	v_cvt_pk_bf16_f32 v6, v0, v1
	v_add_u32_e32 v0, v121, v20
	v_ashrrev_i32_e32 v1, 31, v0
	v_lshlrev_b64 v[0:1], 12, v[0:1]
	v_lshl_add_u64 v[0:1], s[4:5], 0, v[0:1]
	v_lshl_add_u64 v[0:1], v[0:1], 0, v[108:109]
	v_cvt_pk_bf16_f32 v7, v2, v3
	global_store_dwordx4 v[0:1], v[4:7], off
	s_cbranch_vccz .LBB0_666
; #define PG8_WAIT_V(n) asm volatile("s_waitcnt vmcnt(" #n ")" ::: "memory")
; #define PG8_BAR __builtin_amdgcn_s_barrier()
; template <class Epi, class Sched>
; __device__ __forceinline__ void gemm_phase(LAS unsigned char* lds, const Gemm g, const Sched& S, const Epi& E) {
;     ...
;     PG8_WAIT_V(0);
;     if (wr == 0) PG8_BAR;
;     PG8_BAR;
	s_waitcnt vmcnt(0)
	s_cmpk_gt_u32 s24, 0xff
	s_cbranch_scc1 .LBB0_677
	s_barrier

; #define PG8_STAGE(bufoff, gbase, voff) do { _Pragma("unroll") for (int _i = 0; _i < 2; ++_i) \
;         __builtin_amdgcn_global_load_lds((const unsigned*)((const char*)(gbase) + (voff)[_i]), (LAS unsigned*)(lds + (bufoff) + ldsw + _i * 8192), 16, 0, 0); } while (0)
; #define PG8_LDA(dst, b, h) do { _Pragma("unroll") for (int m = 0; m < 4; ++m) _Pragma("unroll") for (int k = 0; k < 2; ++k) dst[m][k] = *(const LAS bf16x8*)(lds + PG8_SA(b, h) + aoff + m * 2048 + k * 1024); } while (0)
; #define PG8_LDB(dst, b, h) do { _Pragma("unroll") for (int n = 0; n < 2; ++n) _Pragma("unroll") for (int k = 0; k < 2; ++k) dst[n][k] = *(const LAS bf16x8*)(lds + PG8_SB(b, h) + boff + n * 2048 + k * 1024); } while (0)
; #define PG8_MMA(ai, bj, At, Bt) do { __builtin_amdgcn_s_setprio(1); _Pragma("unroll") for (int m = 0; m < 4; ++m) _Pragma("unroll") for (int n = 0; n < 2; ++n) _Pragma("unroll") for (int k = 0; k < 2; ++k) \
;         acc[ai][bj][m][n] = __builtin_amdgcn_mfma_f32_16x16x32_bf16(Bt[n][k], At[m][k], acc[ai][bj][m][n], 0, 0, 0); __builtin_amdgcn_s_setprio(0); } while (0)
; #define PG8_WAIT_L(n) asm volatile("s_waitcnt lgkmcnt(" #n ")" ::: "memory")
; template <class Epi, class Sched>
; __device__ __forceinline__ void gemm_phase(LAS unsigned char* lds, const Gemm g, const Sched& S, const Epi& E) {
;     ...
;         const bool has_next = S.next(ui + 1, nxt);
;         const char* nA = has_next ? (const char*)g.A + (size_t)nxt.pm * tstep : cA; const char* nB = has_next ? (const char*)g.Bt + (size_t)nxt.pn * tstep : cB;
;         for (int t = 0; t < nt; t += 2) {
;             const bool last = (t == nt - 2);
;             const char* a1 = cA + (size_t)(t + 1) * kstep;
;             const char* a2 = last ? nA : cA + (size_t)(t + 2) * kstep; const char* b2 = last ? nB : cB + (size_t)(t + 2) * kstep;
;             const char* a3 = a2 + kstep; const char* b3 = b2 + kstep;
;             PG8_LDB(B0, 0, 0); PG8_SCHED; PG8_LDA(At, 0, 0); PG8_STAGE(PG8_SA(1, 1), a1 + hstep, voffA);
;             PG8_WAIT_L(8); PG8_BAR; PG8_WAIT_L(0); PG8_MMA(0, 0, At, B0); PG8_BAR; PG8_SCHED;
;             PG8_LDB(B1, 0, 1); PG8_STAGE(PG8_SB(0, 0), b2, voffB);
;             PG8_BAR; PG8_WAIT_L(0); PG8_MMA(0, 1, At, B1); PG8_BAR;
;             PG8_LDA(At, 0, 1); PG8_STAGE(PG8_SA(0, 0), a2, voffA);
;             PG8_BAR; PG8_WAIT_L(0); PG8_MMA(1, 0, At, B0); PG8_BAR; PG8_SCHED;
.LBB0_692:
	s_ashr_i32 s19, s18, 31
	v_cmp_lt_i64_e64 s[24:25], s[20:21], 32
	s_lshl_b64 s[20:21], s[18:19], 19
	s_add_u32 s20, s40, s20
	s_addc_u32 s21, s41, s21
	s_and_b64 s[22:23], s[24:25], exec
	s_cselect_b32 s19, s21, s3
	s_cselect_b32 s57, s20, s2
	s_ashr_i32 s17, s16, 31
	s_lshl_b64 s[22:23], s[16:17], 19
	s_add_u32 s22, s28, s22
	s_addc_u32 s23, s29, s23
	s_and_b64 s[24:25], s[24:25], exec
	s_cselect_b32 s17, s23, s5
	s_cselect_b32 s58, s22, s4
	s_add_u32 s2, s2, 0x40080
	s_addc_u32 s3, s3, 0
	s_add_u32 s59, s4, 0x100
	s_addc_u32 s60, s5, 0
	s_mov_b32 s61, -2
	s_waitcnt lgkmcnt(0)
	ds_read_b128 v[140:143], v149
	ds_read_b128 v[154:157], v149 offset:1024
	ds_read_b128 v[158:161], v149 offset:2048
	ds_read_b128 v[162:165], v149 offset:3072
	s_add_u32 s4, s2, 0xfffc0080
	s_addc_u32 s5, s3, -1
	s_cmp_eq_u32 s61, 12
	s_cselect_b32 s25, s19, s5
	s_cselect_b32 s24, s57, s4
	s_cselect_b32 s5, s17, s60
	s_cselect_b32 s4, s58, s59
	s_add_i32 m0, s33, 0xc000
	ds_read_b128 v[166:169], v150
	ds_read_b128 v[170:173], v150 offset:1024
	ds_read_b128 v[174:177], v150 offset:2048
	ds_read_b128 v[178:181], v150 offset:3072
	ds_read_b128 v[182:185], v150 offset:4096
	ds_read_b128 v[186:189], v150 offset:5120
	ds_read_b128 v[190:193], v150 offset:6144
	ds_read_b128 v[194:197], v150 offset:7168
	global_load_lds_dwordx4 v136, s[2:3]
	s_add_i32 m0, s33, 0xe000
	s_nop 0
	global_load_lds_dwordx4 v138, s[2:3]
	s_waitcnt lgkmcnt(8)
	s_waitcnt vmcnt(8)
	s_waitcnt lgkmcnt(0)
	s_setprio 1
	s_barrier
	v_mfma_f32_16x16x32_bf16 v[124:127], v[140:143], v[166:169], 0
	v_mfma_f32_16x16x32_bf16 v[120:123], v[158:161], v[166:169], 0
	v_mfma_f32_16x16x32_bf16 v[108:111], v[140:143], v[174:177], 0
	v_mfma_f32_16x16x32_bf16 v[104:107], v[158:161], v[174:177], 0
	v_mfma_f32_16x16x32_bf16 v[92:95], v[140:143], v[182:185], 0
	v_mfma_f32_16x16x32_bf16 v[88:91], v[158:161], v[182:185], 0
	v_mfma_f32_16x16x32_bf16 v[76:79], v[140:143], v[190:193], 0
	v_mfma_f32_16x16x32_bf16 v[72:75], v[158:161], v[190:193], 0
	v_mfma_f32_16x16x32_bf16 v[124:127], v[154:157], v[170:173], v[124:127]
	v_mfma_f32_16x16x32_bf16 v[120:123], v[162:165], v[170:173], v[120:123]
	v_mfma_f32_16x16x32_bf16 v[108:111], v[154:157], v[178:181], v[108:111]
	v_mfma_f32_16x16x32_bf16 v[104:107], v[162:165], v[178:181], v[104:107]
	v_mfma_f32_16x16x32_bf16 v[92:95], v[154:157], v[186:189], v[92:95]
	v_mfma_f32_16x16x32_bf16 v[88:91], v[162:165], v[186:189], v[88:91]
	v_mfma_f32_16x16x32_bf16 v[76:79], v[154:157], v[194:197], v[76:79]
	v_mfma_f32_16x16x32_bf16 v[72:75], v[162:165], v[194:197], v[72:75]
	s_barrier
	s_setprio 0
	s_add_i32 s62, s47, s31
	s_mov_b32 m0, s62
	ds_read_b128 v[202:205], v151
	ds_read_b128 v[206:209], v151 offset:1024
	ds_read_b128 v[210:213], v151 offset:2048
	ds_read_b128 v[214:217], v151 offset:3072
	global_load_lds_dwordx4 v130, s[4:5]
	s_add_i32 m0, s62, 0x2000
	s_nop 0
	global_load_lds_dwordx4 v134, s[4:5]
	s_waitcnt vmcnt(8)
	s_waitcnt lgkmcnt(0)
	s_setprio 1
	s_barrier
	v_mfma_f32_16x16x32_bf16 v[116:119], v[202:205], v[166:169], 0
	v_mfma_f32_16x16x32_bf16 v[112:115], v[210:213], v[166:169], 0
	v_mfma_f32_16x16x32_bf16 v[100:103], v[202:205], v[174:177], 0
	v_mfma_f32_16x16x32_bf16 v[96:99], v[210:213], v[174:177], 0
	v_mfma_f32_16x16x32_bf16 v[84:87], v[202:205], v[182:185], 0
	v_mfma_f32_16x16x32_bf16 v[80:83], v[210:213], v[182:185], 0
	v_mfma_f32_16x16x32_bf16 v[68:71], v[202:205], v[190:193], 0
	v_mfma_f32_16x16x32_bf16 v[64:67], v[210:213], v[190:193], 0
	v_mfma_f32_16x16x32_bf16 v[116:119], v[206:209], v[170:173], v[116:119]
	v_mfma_f32_16x16x32_bf16 v[112:115], v[214:217], v[170:173], v[112:115]
	v_mfma_f32_16x16x32_bf16 v[100:103], v[206:209], v[178:181], v[100:103]
	v_mfma_f32_16x16x32_bf16 v[96:99], v[214:217], v[178:181], v[96:99]
	v_mfma_f32_16x16x32_bf16 v[84:87], v[206:209], v[186:189], v[84:87]
	v_mfma_f32_16x16x32_bf16 v[80:83], v[214:217], v[186:189], v[80:83]
	v_mfma_f32_16x16x32_bf16 v[68:71], v[206:209], v[194:197], v[68:71]
	v_mfma_f32_16x16x32_bf16 v[64:67], v[214:217], v[194:197], v[64:67]
	s_mov_b32 m0, s33
	v_lshl_add_u64 v[218:219], s[24:25], 0, v[128:129]
	s_barrier
	s_setprio 0
	ds_read_b128 v[166:169], v150 offset:16384
	ds_read_b128 v[170:173], v150 offset:17408
	ds_read_b128 v[174:177], v150 offset:18432
	ds_read_b128 v[178:181], v150 offset:19456
	ds_read_b128 v[182:185], v150 offset:20480
	ds_read_b128 v[186:189], v150 offset:21504
	ds_read_b128 v[190:193], v150 offset:22528
	ds_read_b128 v[194:197], v150 offset:23552
	global_load_lds_dwordx4 v128, s[24:25]
	v_lshl_add_u64 v[220:221], s[24:25], 0, v[132:133]
	s_mov_b32 m0, s34
	s_nop 0
	global_load_lds_dwordx4 v132, s[24:25]
	s_waitcnt lgkmcnt(0)
	s_setprio 1
	s_barrier
	v_mfma_f32_16x16x32_bf16 v[60:63], v[140:143], v[166:169], 0
	v_mfma_f32_16x16x32_bf16 v[56:59], v[158:161], v[166:169], 0
	v_mfma_f32_16x16x32_bf16 v[44:47], v[140:143], v[174:177], 0
	v_mfma_f32_16x16x32_bf16 v[40:43], v[158:161], v[174:177], 0
	v_mfma_f32_16x16x32_bf16 v[28:31], v[140:143], v[182:185], 0
	v_mfma_f32_16x16x32_bf16 v[24:27], v[158:161], v[182:185], 0
	v_mfma_f32_16x16x32_bf16 v[12:15], v[140:143], v[190:193], 0
	v_mfma_f32_16x16x32_bf16 v[8:11], v[158:161], v[190:193], 0
	v_mfma_f32_16x16x32_bf16 v[60:63], v[154:157], v[170:173], v[60:63]
	v_mfma_f32_16x16x32_bf16 v[56:59], v[162:165], v[170:173], v[56:59]
	v_mfma_f32_16x16x32_bf16 v[44:47], v[154:157], v[178:181], v[44:47]
	v_mfma_f32_16x16x32_bf16 v[40:43], v[162:165], v[178:181], v[40:43]
	v_mfma_f32_16x16x32_bf16 v[28:31], v[154:157], v[186:189], v[28:31]
	v_mfma_f32_16x16x32_bf16 v[24:27], v[162:165], v[186:189], v[24:27]
	v_mfma_f32_16x16x32_bf16 v[12:15], v[154:157], v[194:197], v[12:15]
	v_mfma_f32_16x16x32_bf16 v[8:11], v[162:165], v[194:197], v[8:11]
	s_barrier
; #define PG8_STAGE(bufoff, gbase, voff) do { _Pragma("unroll") for (int _i = 0; _i < 2; ++_i) \
;         __builtin_amdgcn_global_load_lds((const unsigned*)((const char*)(gbase) + (voff)[_i]), (LAS unsigned*)(lds + (bufoff) + ldsw + _i * 8192), 16, 0, 0); } while (0)
; #define PG8_LDA(dst, b, h) do { _Pragma("unroll") for (int m = 0; m < 4; ++m) _Pragma("unroll") for (int k = 0; k < 2; ++k) dst[m][k] = *(const LAS bf16x8*)(lds + PG8_SA(b, h) + aoff + m * 2048 + k * 1024); } while (0)
; #define PG8_LDB(dst, b, h) do { _Pragma("unroll") for (int n = 0; n < 2; ++n) _Pragma("unroll") for (int k = 0; k < 2; ++k) dst[n][k] = *(const LAS bf16x8*)(lds + PG8_SB(b, h) + boff + n * 2048 + k * 1024); } while (0)
; #define PG8_MMA(ai, bj, At, Bt) do { __builtin_amdgcn_s_setprio(1); _Pragma("unroll") for (int m = 0; m < 4; ++m) _Pragma("unroll") for (int n = 0; n < 2; ++n) _Pragma("unroll") for (int k = 0; k < 2; ++k) \
;         acc[ai][bj][m][n] = __builtin_amdgcn_mfma_f32_16x16x32_bf16(Bt[n][k], At[m][k], acc[ai][bj][m][n], 0, 0, 0); __builtin_amdgcn_s_setprio(0); } while (0)
; #define PG8_WAIT_V(n) asm volatile("s_waitcnt vmcnt(" #n ")" ::: "memory")
; #define PG8_WAIT_L(n) asm volatile("s_waitcnt lgkmcnt(" #n ")" ::: "memory")
; #define PG8_BAR __builtin_amdgcn_s_barrier()
; #define PG8_SCHED __builtin_amdgcn_sched_barrier(0)
; template <class Epi, class Sched>
; __device__ __forceinline__ void gemm_phase(LAS unsigned char* lds, const Gemm g, const Sched& S, const Epi& E) {
;     ...
;             PG8_STAGE(PG8_SB(0, 1), b2 + hstep, voffB);
;             PG8_WAIT_V(6); PG8_BAR; PG8_MMA(1, 1, At, B1); PG8_BAR;
;             PG8_LDB(B0, 1, 0); PG8_SCHED; PG8_LDA(At, 1, 0); PG8_STAGE(PG8_SA(0, 1), a2 + hstep, voffA);
;             PG8_WAIT_L(8); PG8_BAR; PG8_WAIT_L(0); PG8_MMA(0, 0, At, B0); PG8_BAR; PG8_SCHED;
;             PG8_LDB(B1, 1, 1); PG8_STAGE(PG8_SB(1, 0), b3, voffB);
;             PG8_BAR; PG8_WAIT_L(0); PG8_MMA(0, 1, At, B1); PG8_BAR;
;             PG8_LDA(At, 1, 1); PG8_STAGE(PG8_SA(1, 0), a3, voffA);
	s_setprio 0
	s_add_u32 s62, s4, 0x40000
	s_addc_u32 s63, s5, 0
	s_add_i32 s64, s48, s31
	s_mov_b32 m0, s64
	s_nop 0
	global_load_lds_dwordx4 v130, s[62:63]
	s_add_i32 m0, s64, 0x2000
	s_nop 0
	global_load_lds_dwordx4 v134, s[62:63]
	s_add_u32 s24, s24, 0x40000
	s_addc_u32 s25, s25, 0
	s_mov_b32 m0, s35
	s_nop 0
	global_load_lds_dwordx4 v128, s[24:25]
	s_mov_b32 m0, s36
	s_nop 0
	global_load_lds_dwordx4 v132, s[24:25]
	s_waitcnt vmcnt(10)
	s_setprio 1
	s_barrier
	v_mfma_f32_16x16x32_bf16 v[52:55], v[202:205], v[166:169], 0
	v_mfma_f32_16x16x32_bf16 v[48:51], v[210:213], v[166:169], 0
	v_mfma_f32_16x16x32_bf16 v[36:39], v[202:205], v[174:177], 0
	v_mfma_f32_16x16x32_bf16 v[32:35], v[210:213], v[174:177], 0
	v_mfma_f32_16x16x32_bf16 v[20:23], v[202:205], v[182:185], 0
	v_mfma_f32_16x16x32_bf16 v[16:19], v[210:213], v[182:185], 0
	v_mfma_f32_16x16x32_bf16 v[4:7], v[202:205], v[190:193], 0
	v_mfma_f32_16x16x32_bf16 v[0:3], v[210:213], v[190:193], 0
	v_mfma_f32_16x16x32_bf16 v[52:55], v[206:209], v[170:173], v[52:55]
	v_mfma_f32_16x16x32_bf16 v[48:51], v[214:217], v[170:173], v[48:51]
	v_mfma_f32_16x16x32_bf16 v[36:39], v[206:209], v[178:181], v[36:39]
	v_mfma_f32_16x16x32_bf16 v[32:35], v[214:217], v[178:181], v[32:35]
	v_mfma_f32_16x16x32_bf16 v[20:23], v[206:209], v[186:189], v[20:23]
	v_mfma_f32_16x16x32_bf16 v[16:19], v[214:217], v[186:189], v[16:19]
	v_mfma_f32_16x16x32_bf16 v[4:7], v[206:209], v[194:197], v[4:7]
	v_mfma_f32_16x16x32_bf16 v[0:3], v[214:217], v[194:197], v[0:3]
	s_add_i32 s62, 0, 0x18000
	v_add_u32_e32 v162, s62, v148
	s_barrier
	s_setprio 0
	ds_read_b128 v[140:143], v162
	ds_read_b128 v[154:157], v162 offset:1024
	ds_read_b128 v[158:161], v162 offset:2048
	ds_read_b128 v[162:165], v162 offset:3072
	ds_read_b128 v[166:169], v150 offset:32768
	ds_read_b128 v[170:173], v150 offset:33792
	ds_read_b128 v[174:177], v150 offset:34816
	ds_read_b128 v[178:181], v150 offset:35840
	ds_read_b128 v[182:185], v150 offset:36864
	ds_read_b128 v[186:189], v150 offset:37888
	ds_read_b128 v[190:193], v150 offset:38912
	ds_read_b128 v[194:197], v150 offset:39936
	s_waitcnt lgkmcnt(8)
	s_waitcnt vmcnt(8)
	s_waitcnt lgkmcnt(0)
	s_setprio 1
	s_barrier
	v_mfma_f32_16x16x32_bf16 v[124:127], v[140:143], v[166:169], v[124:127]
	v_mfma_f32_16x16x32_bf16 v[120:123], v[158:161], v[166:169], v[120:123]
	v_mfma_f32_16x16x32_bf16 v[108:111], v[140:143], v[174:177], v[108:111]
	v_mfma_f32_16x16x32_bf16 v[104:107], v[158:161], v[174:177], v[104:107]
	v_mfma_f32_16x16x32_bf16 v[92:95], v[140:143], v[182:185], v[92:95]
	v_mfma_f32_16x16x32_bf16 v[88:91], v[158:161], v[182:185], v[88:91]
	v_mfma_f32_16x16x32_bf16 v[76:79], v[140:143], v[190:193], v[76:79]
	v_mfma_f32_16x16x32_bf16 v[72:75], v[158:161], v[190:193], v[72:75]
	v_mfma_f32_16x16x32_bf16 v[124:127], v[154:157], v[170:173], v[124:127]
	v_mfma_f32_16x16x32_bf16 v[120:123], v[162:165], v[170:173], v[120:123]
	v_mfma_f32_16x16x32_bf16 v[108:111], v[154:157], v[178:181], v[108:111]
	v_mfma_f32_16x16x32_bf16 v[104:107], v[162:165], v[178:181], v[104:107]
	v_mfma_f32_16x16x32_bf16 v[92:95], v[154:157], v[186:189], v[92:95]
	v_mfma_f32_16x16x32_bf16 v[88:91], v[162:165], v[186:189], v[88:91]
	v_mfma_f32_16x16x32_bf16 v[76:79], v[154:157], v[194:197], v[76:79]
	v_mfma_f32_16x16x32_bf16 v[72:75], v[162:165], v[194:197], v[72:75]
	s_barrier
	s_setprio 0
	s_add_i32 s24, 0, 0x1c000
	s_add_i32 s25, s62, s31
	v_add_u32_e32 v214, s24, v148
	s_add_u32 s0, s4, 0x80
	s_addc_u32 s1, s5, 0
	s_mov_b32 m0, s25
	ds_read_b128 v[202:205], v214
	ds_read_b128 v[206:209], v214 offset:1024
	ds_read_b128 v[210:213], v214 offset:2048
	ds_read_b128 v[214:217], v214 offset:3072
	global_load_lds_dwordx4 v130, s[0:1]
	s_add_i32 m0, s25, 0x2000
	s_nop 0
	global_load_lds_dwordx4 v134, s[0:1]
	s_waitcnt vmcnt(8)
	s_waitcnt lgkmcnt(0)
	s_setprio 1
	s_barrier
	v_mfma_f32_16x16x32_bf16 v[116:119], v[202:205], v[166:169], v[116:119]
	v_mfma_f32_16x16x32_bf16 v[112:115], v[210:213], v[166:169], v[112:115]
	v_mfma_f32_16x16x32_bf16 v[100:103], v[202:205], v[174:177], v[100:103]
	v_mfma_f32_16x16x32_bf16 v[96:99], v[210:213], v[174:177], v[96:99]
	v_mfma_f32_16x16x32_bf16 v[84:87], v[202:205], v[182:185], v[84:87]
	v_mfma_f32_16x16x32_bf16 v[80:83], v[210:213], v[182:185], v[80:83]
	v_mfma_f32_16x16x32_bf16 v[68:71], v[202:205], v[190:193], v[68:71]
	v_mfma_f32_16x16x32_bf16 v[64:67], v[210:213], v[190:193], v[64:67]
	v_mfma_f32_16x16x32_bf16 v[116:119], v[206:209], v[170:173], v[116:119]
	v_mfma_f32_16x16x32_bf16 v[112:115], v[214:217], v[170:173], v[112:115]
	v_mfma_f32_16x16x32_bf16 v[100:103], v[206:209], v[178:181], v[100:103]
	v_mfma_f32_16x16x32_bf16 v[96:99], v[214:217], v[178:181], v[96:99]
	v_mfma_f32_16x16x32_bf16 v[84:87], v[206:209], v[186:189], v[84:87]
	v_mfma_f32_16x16x32_bf16 v[80:83], v[214:217], v[186:189], v[80:83]
	v_mfma_f32_16x16x32_bf16 v[68:71], v[206:209], v[194:197], v[68:71]
	v_mfma_f32_16x16x32_bf16 v[64:67], v[214:217], v[194:197], v[64:67]
	s_mov_b32 m0, s44
	s_mov_b64 s[0:1], 0x80
	v_lshl_add_u64 v[144:145], v[218:219], 0, s[0:1]
	s_barrier
	s_setprio 0
	ds_read_b128 v[166:169], v150 offset:49152
	ds_read_b128 v[170:173], v150 offset:50176
	ds_read_b128 v[174:177], v150 offset:51200
	ds_read_b128 v[178:181], v150 offset:52224
	ds_read_b128 v[182:185], v150 offset:53248
	ds_read_b128 v[186:189], v150 offset:54272
	ds_read_b128 v[190:193], v150 offset:55296
	ds_read_b128 v[194:197], v150 offset:56320
	global_load_lds_dwordx4 v[144:145], off
	v_lshl_add_u64 v[144:145], v[220:221], 0, s[0:1]
	s_mov_b32 m0, s45
	s_nop 0
	global_load_lds_dwordx4 v[144:145], off
	s_waitcnt lgkmcnt(0)
	s_setprio 1
	s_barrier
; #define PG8_STAGE(bufoff, gbase, voff) do { _Pragma("unroll") for (int _i = 0; _i < 2; ++_i) \
;         __builtin_amdgcn_global_load_lds((const unsigned*)((const char*)(gbase) + (voff)[_i]), (LAS unsigned*)(lds + (bufoff) + ldsw + _i * 8192), 16, 0, 0); } while (0)
; #define PG8_LDA(dst, b, h) do { _Pragma("unroll") for (int m = 0; m < 4; ++m) _Pragma("unroll") for (int k = 0; k < 2; ++k) dst[m][k] = *(const LAS bf16x8*)(lds + PG8_SA(b, h) + aoff + m * 2048 + k * 1024); } while (0)
; #define PG8_LDB(dst, b, h) do { _Pragma("unroll") for (int n = 0; n < 2; ++n) _Pragma("unroll") for (int k = 0; k < 2; ++k) dst[n][k] = *(const LAS bf16x8*)(lds + PG8_SB(b, h) + boff + n * 2048 + k * 1024); } while (0)
; #define PG8_WAIT_V(n) asm volatile("s_waitcnt vmcnt(" #n ")" ::: "memory")
; #define PG8_WAIT_L(n) asm volatile("s_waitcnt lgkmcnt(" #n ")" ::: "memory")
; #define PG8_BAR __builtin_amdgcn_s_barrier()
; #define PG8_SCHED __builtin_amdgcn_sched_barrier(0)
; template <class Epi, class Sched>
; __device__ __forceinline__ void gemm_phase(LAS unsigned char* lds, const Gemm g, const Sched& S, const Epi& E) {
;     ...
;             PG8_LDB(B0, 0, 0); PG8_SCHED; PG8_LDA(At, 0, 0); PG8_STAGE(PG8_SA(1, 1), a1 + hstep, voffA);
;             PG8_WAIT_L(8); PG8_BAR; PG8_WAIT_L(0); PG8_MMA(0, 0, At, B0); PG8_BAR; PG8_SCHED;
;             PG8_LDB(B1, 0, 1); PG8_STAGE(PG8_SB(0, 0), b2, voffB);
;             PG8_BAR; PG8_WAIT_L(0); PG8_MMA(0, 1, At, B1); PG8_BAR;
;             PG8_LDA(At, 0, 1); PG8_STAGE(PG8_SA(0, 0), a2, voffA);
;             PG8_BAR; PG8_WAIT_L(0); PG8_MMA(1, 0, At, B0); PG8_BAR; PG8_SCHED;
;             PG8_STAGE(PG8_SB(0, 1), b2 + hstep, voffB);
;             PG8_WAIT_V(6); PG8_BAR; PG8_MMA(1, 1, At, B1); PG8_BAR;
;             PG8_LDB(B0, 1, 0); PG8_SCHED; PG8_LDA(At, 1, 0); PG8_STAGE(PG8_SA(0, 1), a2 + hstep, voffA);
;             PG8_WAIT_L(8); PG8_BAR; PG8_WAIT_L(0); PG8_MMA(0, 0, At, B0); PG8_BAR; PG8_SCHED;
;             PG8_LDB(B1, 1, 1); PG8_STAGE(PG8_SB(1, 0), b3, voffB);
;             PG8_BAR; PG8_WAIT_L(0); PG8_MMA(0, 1, At, B1); PG8_BAR;
;             PG8_LDA(At, 1, 1); PG8_STAGE(PG8_SA(1, 0), a3, voffA);
;             PG8_BAR; PG8_WAIT_L(0); PG8_MMA(1, 0, At, B0); PG8_BAR; PG8_SCHED;
;             PG8_STAGE(PG8_SB(1, 1), b3 + hstep, voffB);
;             PG8_WAIT_V(6); PG8_BAR; PG8_MMA(1, 1, At, B1); PG8_BAR;
	v_mfma_f32_16x16x32_bf16 v[60:63], v[140:143], v[166:169], v[60:63]
	v_mfma_f32_16x16x32_bf16 v[56:59], v[158:161], v[166:169], v[56:59]
	v_mfma_f32_16x16x32_bf16 v[44:47], v[140:143], v[174:177], v[44:47]
	v_mfma_f32_16x16x32_bf16 v[40:43], v[158:161], v[174:177], v[40:43]
	v_mfma_f32_16x16x32_bf16 v[28:31], v[140:143], v[182:185], v[28:31]
	v_mfma_f32_16x16x32_bf16 v[24:27], v[158:161], v[182:185], v[24:27]
	v_mfma_f32_16x16x32_bf16 v[12:15], v[140:143], v[190:193], v[12:15]
	v_mfma_f32_16x16x32_bf16 v[8:11], v[158:161], v[190:193], v[8:11]
	v_mfma_f32_16x16x32_bf16 v[60:63], v[154:157], v[170:173], v[60:63]
	v_mfma_f32_16x16x32_bf16 v[56:59], v[162:165], v[170:173], v[56:59]
	v_mfma_f32_16x16x32_bf16 v[44:47], v[154:157], v[178:181], v[44:47]
	v_mfma_f32_16x16x32_bf16 v[40:43], v[162:165], v[178:181], v[40:43]
	v_mfma_f32_16x16x32_bf16 v[28:31], v[154:157], v[186:189], v[28:31]
	v_mfma_f32_16x16x32_bf16 v[24:27], v[162:165], v[186:189], v[24:27]
	v_mfma_f32_16x16x32_bf16 v[12:15], v[154:157], v[194:197], v[12:15]
	v_mfma_f32_16x16x32_bf16 v[8:11], v[162:165], v[194:197], v[8:11]
	s_barrier
	s_setprio 0
	s_add_u32 s4, s4, 0x40080
	s_addc_u32 s5, s5, 0
	s_add_i32 s24, s24, s31
	s_mov_b32 m0, s24
	s_nop 0
	global_load_lds_dwordx4 v130, s[4:5]
	s_add_i32 m0, s24, 0x2000
	s_nop 0
	global_load_lds_dwordx4 v134, s[4:5]
	s_waitcnt vmcnt(8)
	s_setprio 1
	s_barrier
	v_mfma_f32_16x16x32_bf16 v[52:55], v[202:205], v[166:169], v[52:55]
	v_mfma_f32_16x16x32_bf16 v[48:51], v[210:213], v[166:169], v[48:51]
	v_mfma_f32_16x16x32_bf16 v[36:39], v[202:205], v[174:177], v[36:39]
	v_mfma_f32_16x16x32_bf16 v[32:35], v[210:213], v[174:177], v[32:35]
	v_mfma_f32_16x16x32_bf16 v[20:23], v[202:205], v[182:185], v[20:23]
	v_mfma_f32_16x16x32_bf16 v[16:19], v[210:213], v[182:185], v[16:19]
	v_mfma_f32_16x16x32_bf16 v[4:7], v[202:205], v[190:193], v[4:7]
	v_mfma_f32_16x16x32_bf16 v[0:3], v[210:213], v[190:193], v[0:3]
	v_mfma_f32_16x16x32_bf16 v[52:55], v[206:209], v[170:173], v[52:55]
	v_mfma_f32_16x16x32_bf16 v[48:51], v[214:217], v[170:173], v[48:51]
	v_mfma_f32_16x16x32_bf16 v[36:39], v[206:209], v[178:181], v[36:39]
	v_mfma_f32_16x16x32_bf16 v[32:35], v[214:217], v[178:181], v[32:35]
	v_mfma_f32_16x16x32_bf16 v[20:23], v[206:209], v[186:189], v[20:23]
	v_mfma_f32_16x16x32_bf16 v[16:19], v[214:217], v[186:189], v[16:19]
	v_mfma_f32_16x16x32_bf16 v[4:7], v[206:209], v[194:197], v[4:7]
	v_mfma_f32_16x16x32_bf16 v[0:3], v[214:217], v[194:197], v[0:3]
	s_add_i32 s61, s61, 2
	s_add_u32 s2, s2, 0x100
	s_addc_u32 s3, s3, 0
	s_add_u32 s59, s59, 0x100
	s_addc_u32 s60, s60, 0
	s_cmp_gt_u32 s61, 13
	s_barrier
	s_setprio 0
.LBB0_693:
	ds_read_b128 v[140:143], v149
	ds_read_b128 v[154:157], v149 offset:1024
	ds_read_b128 v[158:161], v149 offset:2048
	ds_read_b128 v[162:165], v149 offset:3072
	s_add_u32 s4, s2, 0xfffc0080
	s_addc_u32 s5, s3, -1
	s_cmp_eq_u32 s61, 12
	s_cselect_b32 s25, s19, s5
	s_cselect_b32 s24, s57, s4
	s_cselect_b32 s5, s17, s60
	s_cselect_b32 s4, s58, s59
	s_add_i32 m0, s33, 0xc000
	ds_read_b128 v[166:169], v150
	ds_read_b128 v[170:173], v150 offset:1024
	ds_read_b128 v[174:177], v150 offset:2048
	ds_read_b128 v[178:181], v150 offset:3072
	ds_read_b128 v[182:185], v150 offset:4096
	ds_read_b128 v[186:189], v150 offset:5120
	ds_read_b128 v[190:193], v150 offset:6144
	ds_read_b128 v[194:197], v150 offset:7168
	global_load_lds_dwordx4 v136, s[2:3]
	s_add_i32 m0, s33, 0xe000
	s_nop 0
	global_load_lds_dwordx4 v138, s[2:3]
	s_waitcnt lgkmcnt(8)
	s_waitcnt vmcnt(8)
	s_waitcnt lgkmcnt(0)
	s_setprio 1
	s_barrier
	v_mfma_f32_16x16x32_bf16 v[124:127], v[140:143], v[166:169], v[124:127]
	v_mfma_f32_16x16x32_bf16 v[120:123], v[158:161], v[166:169], v[120:123]
	v_mfma_f32_16x16x32_bf16 v[108:111], v[140:143], v[174:177], v[108:111]
	v_mfma_f32_16x16x32_bf16 v[104:107], v[158:161], v[174:177], v[104:107]
	v_mfma_f32_16x16x32_bf16 v[92:95], v[140:143], v[182:185], v[92:95]
	v_mfma_f32_16x16x32_bf16 v[88:91], v[158:161], v[182:185], v[88:91]
	v_mfma_f32_16x16x32_bf16 v[76:79], v[140:143], v[190:193], v[76:79]
	v_mfma_f32_16x16x32_bf16 v[72:75], v[158:161], v[190:193], v[72:75]
	v_mfma_f32_16x16x32_bf16 v[124:127], v[154:157], v[170:173], v[124:127]
	v_mfma_f32_16x16x32_bf16 v[120:123], v[162:165], v[170:173], v[120:123]
	v_mfma_f32_16x16x32_bf16 v[108:111], v[154:157], v[178:181], v[108:111]
	v_mfma_f32_16x16x32_bf16 v[104:107], v[162:165], v[178:181], v[104:107]
	v_mfma_f32_16x16x32_bf16 v[92:95], v[154:157], v[186:189], v[92:95]
	v_mfma_f32_16x16x32_bf16 v[88:91], v[162:165], v[186:189], v[88:91]
	v_mfma_f32_16x16x32_bf16 v[76:79], v[154:157], v[194:197], v[76:79]
	v_mfma_f32_16x16x32_bf16 v[72:75], v[162:165], v[194:197], v[72:75]
	s_barrier
	s_setprio 0
	s_add_i32 s62, s47, s31
	s_mov_b32 m0, s62
	ds_read_b128 v[202:205], v151
	ds_read_b128 v[206:209], v151 offset:1024
	ds_read_b128 v[210:213], v151 offset:2048
	ds_read_b128 v[214:217], v151 offset:3072
	global_load_lds_dwordx4 v130, s[4:5]
	s_add_i32 m0, s62, 0x2000
	s_nop 0
	global_load_lds_dwordx4 v134, s[4:5]
	s_waitcnt vmcnt(8)
	s_waitcnt lgkmcnt(0)
	s_setprio 1
	s_barrier
; #define PG8_STAGE(bufoff, gbase, voff) do { _Pragma("unroll") for (int _i = 0; _i < 2; ++_i) \
;         __builtin_amdgcn_global_load_lds((const unsigned*)((const char*)(gbase) + (voff)[_i]), (LAS unsigned*)(lds + (bufoff) + ldsw + _i * 8192), 16, 0, 0); } while (0)
; #define PG8_LDA(dst, b, h) do { _Pragma("unroll") for (int m = 0; m < 4; ++m) _Pragma("unroll") for (int k = 0; k < 2; ++k) dst[m][k] = *(const LAS bf16x8*)(lds + PG8_SA(b, h) + aoff + m * 2048 + k * 1024); } while (0)
; #define PG8_LDB(dst, b, h) do { _Pragma("unroll") for (int n = 0; n < 2; ++n) _Pragma("unroll") for (int k = 0; k < 2; ++k) dst[n][k] = *(const LAS bf16x8*)(lds + PG8_SB(b, h) + boff + n * 2048 + k * 1024); } while (0)
; #define PG8_MMA(ai, bj, At, Bt) do { __builtin_amdgcn_s_setprio(1); _Pragma("unroll") for (int m = 0; m < 4; ++m) _Pragma("unroll") for (int n = 0; n < 2; ++n) _Pragma("unroll") for (int k = 0; k < 2; ++k) \
;         acc[ai][bj][m][n] = __builtin_amdgcn_mfma_f32_16x16x32_bf16(Bt[n][k], At[m][k], acc[ai][bj][m][n], 0, 0, 0); __builtin_amdgcn_s_setprio(0); } while (0)
; #define PG8_WAIT_V(n) asm volatile("s_waitcnt vmcnt(" #n ")" ::: "memory")
; #define PG8_WAIT_L(n) asm volatile("s_waitcnt lgkmcnt(" #n ")" ::: "memory")
; #define PG8_BAR __builtin_amdgcn_s_barrier()
; #define PG8_SCHED __builtin_amdgcn_sched_barrier(0)
; template <class Epi, class Sched>
; __device__ __forceinline__ void gemm_phase(LAS unsigned char* lds, const Gemm g, const Sched& S, const Epi& E) {
;     ...
;             PG8_BAR; PG8_WAIT_L(0); PG8_MMA(0, 1, At, B1); PG8_BAR;
;             PG8_LDA(At, 0, 1); PG8_STAGE(PG8_SA(0, 0), a2, voffA);
;             PG8_BAR; PG8_WAIT_L(0); PG8_MMA(1, 0, At, B0); PG8_BAR; PG8_SCHED;
;             PG8_STAGE(PG8_SB(0, 1), b2 + hstep, voffB);
;             PG8_WAIT_V(6); PG8_BAR; PG8_MMA(1, 1, At, B1); PG8_BAR;
;             PG8_LDB(B0, 1, 0); PG8_SCHED; PG8_LDA(At, 1, 0); PG8_STAGE(PG8_SA(0, 1), a2 + hstep, voffA);
;             PG8_WAIT_L(8); PG8_BAR; PG8_WAIT_L(0); PG8_MMA(0, 0, At, B0); PG8_BAR; PG8_SCHED;
	v_mfma_f32_16x16x32_bf16 v[116:119], v[202:205], v[166:169], v[116:119]
	v_mfma_f32_16x16x32_bf16 v[112:115], v[210:213], v[166:169], v[112:115]
	v_mfma_f32_16x16x32_bf16 v[100:103], v[202:205], v[174:177], v[100:103]
	v_mfma_f32_16x16x32_bf16 v[96:99], v[210:213], v[174:177], v[96:99]
	v_mfma_f32_16x16x32_bf16 v[84:87], v[202:205], v[182:185], v[84:87]
	v_mfma_f32_16x16x32_bf16 v[80:83], v[210:213], v[182:185], v[80:83]
	v_mfma_f32_16x16x32_bf16 v[68:71], v[202:205], v[190:193], v[68:71]
	v_mfma_f32_16x16x32_bf16 v[64:67], v[210:213], v[190:193], v[64:67]
	v_mfma_f32_16x16x32_bf16 v[116:119], v[206:209], v[170:173], v[116:119]
	v_mfma_f32_16x16x32_bf16 v[112:115], v[214:217], v[170:173], v[112:115]
	v_mfma_f32_16x16x32_bf16 v[100:103], v[206:209], v[178:181], v[100:103]
	v_mfma_f32_16x16x32_bf16 v[96:99], v[214:217], v[178:181], v[96:99]
	v_mfma_f32_16x16x32_bf16 v[84:87], v[206:209], v[186:189], v[84:87]
	v_mfma_f32_16x16x32_bf16 v[80:83], v[214:217], v[186:189], v[80:83]
	v_mfma_f32_16x16x32_bf16 v[68:71], v[206:209], v[194:197], v[68:71]
	v_mfma_f32_16x16x32_bf16 v[64:67], v[214:217], v[194:197], v[64:67]
	s_mov_b32 m0, s33
	v_lshl_add_u64 v[218:219], s[24:25], 0, v[128:129]
	s_barrier
	s_setprio 0
	ds_read_b128 v[166:169], v150 offset:16384
	ds_read_b128 v[170:173], v150 offset:17408
	ds_read_b128 v[174:177], v150 offset:18432
	ds_read_b128 v[178:181], v150 offset:19456
	ds_read_b128 v[182:185], v150 offset:20480
	ds_read_b128 v[186:189], v150 offset:21504
	ds_read_b128 v[190:193], v150 offset:22528
	ds_read_b128 v[194:197], v150 offset:23552
	global_load_lds_dwordx4 v128, s[24:25]
	v_lshl_add_u64 v[220:221], s[24:25], 0, v[132:133]
	s_mov_b32 m0, s34
	s_nop 0
	global_load_lds_dwordx4 v132, s[24:25]
	s_waitcnt lgkmcnt(0)
	s_setprio 1
	s_barrier
	v_mfma_f32_16x16x32_bf16 v[60:63], v[140:143], v[166:169], v[60:63]
	v_mfma_f32_16x16x32_bf16 v[56:59], v[158:161], v[166:169], v[56:59]
	v_mfma_f32_16x16x32_bf16 v[44:47], v[140:143], v[174:177], v[44:47]
	v_mfma_f32_16x16x32_bf16 v[40:43], v[158:161], v[174:177], v[40:43]
	v_mfma_f32_16x16x32_bf16 v[28:31], v[140:143], v[182:185], v[28:31]
	v_mfma_f32_16x16x32_bf16 v[24:27], v[158:161], v[182:185], v[24:27]
	v_mfma_f32_16x16x32_bf16 v[12:15], v[140:143], v[190:193], v[12:15]
	v_mfma_f32_16x16x32_bf16 v[8:11], v[158:161], v[190:193], v[8:11]
	v_mfma_f32_16x16x32_bf16 v[60:63], v[154:157], v[170:173], v[60:63]
	v_mfma_f32_16x16x32_bf16 v[56:59], v[162:165], v[170:173], v[56:59]
	v_mfma_f32_16x16x32_bf16 v[44:47], v[154:157], v[178:181], v[44:47]
	v_mfma_f32_16x16x32_bf16 v[40:43], v[162:165], v[178:181], v[40:43]
	v_mfma_f32_16x16x32_bf16 v[28:31], v[154:157], v[186:189], v[28:31]
	v_mfma_f32_16x16x32_bf16 v[24:27], v[162:165], v[186:189], v[24:27]
	v_mfma_f32_16x16x32_bf16 v[12:15], v[154:157], v[194:197], v[12:15]
	v_mfma_f32_16x16x32_bf16 v[8:11], v[162:165], v[194:197], v[8:11]
	s_barrier
	s_setprio 0
	s_add_u32 s62, s4, 0x40000
	s_addc_u32 s63, s5, 0
	s_add_i32 s64, s48, s31
	s_mov_b32 m0, s64
	s_nop 0
	global_load_lds_dwordx4 v130, s[62:63]
	s_add_i32 m0, s64, 0x2000
	s_nop 0
	global_load_lds_dwordx4 v134, s[62:63]
	s_add_u32 s24, s24, 0x40000
	s_addc_u32 s25, s25, 0
	s_mov_b32 m0, s35
	s_nop 0
	global_load_lds_dwordx4 v128, s[24:25]
	s_mov_b32 m0, s36
	s_nop 0
	global_load_lds_dwordx4 v132, s[24:25]
	s_waitcnt vmcnt(10)
	s_setprio 1
	s_barrier
	v_mfma_f32_16x16x32_bf16 v[52:55], v[202:205], v[166:169], v[52:55]
	v_mfma_f32_16x16x32_bf16 v[48:51], v[210:213], v[166:169], v[48:51]
	v_mfma_f32_16x16x32_bf16 v[36:39], v[202:205], v[174:177], v[36:39]
	v_mfma_f32_16x16x32_bf16 v[32:35], v[210:213], v[174:177], v[32:35]
	v_mfma_f32_16x16x32_bf16 v[20:23], v[202:205], v[182:185], v[20:23]
	v_mfma_f32_16x16x32_bf16 v[16:19], v[210:213], v[182:185], v[16:19]
	v_mfma_f32_16x16x32_bf16 v[4:7], v[202:205], v[190:193], v[4:7]
	v_mfma_f32_16x16x32_bf16 v[0:3], v[210:213], v[190:193], v[0:3]
	v_mfma_f32_16x16x32_bf16 v[52:55], v[206:209], v[170:173], v[52:55]
	v_mfma_f32_16x16x32_bf16 v[48:51], v[214:217], v[170:173], v[48:51]
	v_mfma_f32_16x16x32_bf16 v[36:39], v[206:209], v[178:181], v[36:39]
	v_mfma_f32_16x16x32_bf16 v[32:35], v[214:217], v[178:181], v[32:35]
	v_mfma_f32_16x16x32_bf16 v[20:23], v[206:209], v[186:189], v[20:23]
	v_mfma_f32_16x16x32_bf16 v[16:19], v[214:217], v[186:189], v[16:19]
	v_mfma_f32_16x16x32_bf16 v[4:7], v[206:209], v[194:197], v[4:7]
	v_mfma_f32_16x16x32_bf16 v[0:3], v[214:217], v[194:197], v[0:3]
	s_add_i32 s62, 0, 0x18000
	v_add_u32_e32 v162, s62, v148
	s_barrier
	s_setprio 0
	ds_read_b128 v[140:143], v162
	ds_read_b128 v[154:157], v162 offset:1024
	ds_read_b128 v[158:161], v162 offset:2048
	ds_read_b128 v[162:165], v162 offset:3072
	ds_read_b128 v[166:169], v150 offset:32768
	ds_read_b128 v[170:173], v150 offset:33792
	ds_read_b128 v[174:177], v150 offset:34816
	ds_read_b128 v[178:181], v150 offset:35840
	ds_read_b128 v[182:185], v150 offset:36864
	ds_read_b128 v[186:189], v150 offset:37888
	ds_read_b128 v[190:193], v150 offset:38912
	ds_read_b128 v[194:197], v150 offset:39936
	s_waitcnt lgkmcnt(8)
	s_waitcnt vmcnt(8)
	s_waitcnt lgkmcnt(0)
	s_setprio 1
	s_barrier
; #define PG8_STAGE(bufoff, gbase, voff) do { _Pragma("unroll") for (int _i = 0; _i < 2; ++_i) \
;         __builtin_amdgcn_global_load_lds((const unsigned*)((const char*)(gbase) + (voff)[_i]), (LAS unsigned*)(lds + (bufoff) + ldsw + _i * 8192), 16, 0, 0); } while (0)
; #define PG8_LDA(dst, b, h) do { _Pragma("unroll") for (int m = 0; m < 4; ++m) _Pragma("unroll") for (int k = 0; k < 2; ++k) dst[m][k] = *(const LAS bf16x8*)(lds + PG8_SA(b, h) + aoff + m * 2048 + k * 1024); } while (0)
; #define PG8_LDB(dst, b, h) do { _Pragma("unroll") for (int n = 0; n < 2; ++n) _Pragma("unroll") for (int k = 0; k < 2; ++k) dst[n][k] = *(const LAS bf16x8*)(lds + PG8_SB(b, h) + boff + n * 2048 + k * 1024); } while (0)
; #define PG8_MMA(ai, bj, At, Bt) do { __builtin_amdgcn_s_setprio(1); _Pragma("unroll") for (int m = 0; m < 4; ++m) _Pragma("unroll") for (int n = 0; n < 2; ++n) _Pragma("unroll") for (int k = 0; k < 2; ++k) \
;         acc[ai][bj][m][n] = __builtin_amdgcn_mfma_f32_16x16x32_bf16(Bt[n][k], At[m][k], acc[ai][bj][m][n], 0, 0, 0); __builtin_amdgcn_s_setprio(0); } while (0)
; #define PG8_WAIT_V(n) asm volatile("s_waitcnt vmcnt(" #n ")" ::: "memory")
; #define PG8_WAIT_L(n) asm volatile("s_waitcnt lgkmcnt(" #n ")" ::: "memory")
; #define PG8_BAR __builtin_amdgcn_s_barrier()
; #define PG8_SCHED __builtin_amdgcn_sched_barrier(0)
; template <class Epi, class Sched>
; __device__ __forceinline__ void gemm_phase(LAS unsigned char* lds, const Gemm g, const Sched& S, const Epi& E) {
;     ...
;             PG8_WAIT_L(8); PG8_BAR; PG8_WAIT_L(0); PG8_MMA(0, 0, At, B0); PG8_BAR; PG8_SCHED;
;             PG8_LDB(B1, 1, 1); PG8_STAGE(PG8_SB(1, 0), b3, voffB);
;             PG8_BAR; PG8_WAIT_L(0); PG8_MMA(0, 1, At, B1); PG8_BAR;
;             PG8_LDA(At, 1, 1); PG8_STAGE(PG8_SA(1, 0), a3, voffA);
;             PG8_BAR; PG8_WAIT_L(0); PG8_MMA(1, 0, At, B0); PG8_BAR; PG8_SCHED;
;             PG8_STAGE(PG8_SB(1, 1), b3 + hstep, voffB);
;             PG8_WAIT_V(6); PG8_BAR; PG8_MMA(1, 1, At, B1); PG8_BAR;
	v_mfma_f32_16x16x32_bf16 v[124:127], v[140:143], v[166:169], v[124:127]
	v_mfma_f32_16x16x32_bf16 v[120:123], v[158:161], v[166:169], v[120:123]
	v_mfma_f32_16x16x32_bf16 v[108:111], v[140:143], v[174:177], v[108:111]
	v_mfma_f32_16x16x32_bf16 v[104:107], v[158:161], v[174:177], v[104:107]
	v_mfma_f32_16x16x32_bf16 v[92:95], v[140:143], v[182:185], v[92:95]
	v_mfma_f32_16x16x32_bf16 v[88:91], v[158:161], v[182:185], v[88:91]
	v_mfma_f32_16x16x32_bf16 v[76:79], v[140:143], v[190:193], v[76:79]
	v_mfma_f32_16x16x32_bf16 v[72:75], v[158:161], v[190:193], v[72:75]
	v_mfma_f32_16x16x32_bf16 v[124:127], v[154:157], v[170:173], v[124:127]
	v_mfma_f32_16x16x32_bf16 v[120:123], v[162:165], v[170:173], v[120:123]
	v_mfma_f32_16x16x32_bf16 v[108:111], v[154:157], v[178:181], v[108:111]
	v_mfma_f32_16x16x32_bf16 v[104:107], v[162:165], v[178:181], v[104:107]
	v_mfma_f32_16x16x32_bf16 v[92:95], v[154:157], v[186:189], v[92:95]
	v_mfma_f32_16x16x32_bf16 v[88:91], v[162:165], v[186:189], v[88:91]
	v_mfma_f32_16x16x32_bf16 v[76:79], v[154:157], v[194:197], v[76:79]
	v_mfma_f32_16x16x32_bf16 v[72:75], v[162:165], v[194:197], v[72:75]
	s_barrier
	s_setprio 0
	s_add_i32 s24, 0, 0x1c000
	s_add_i32 s25, s62, s31
	v_add_u32_e32 v214, s24, v148
	s_add_u32 s0, s4, 0x80
	s_addc_u32 s1, s5, 0
	s_mov_b32 m0, s25
	ds_read_b128 v[202:205], v214
	ds_read_b128 v[206:209], v214 offset:1024
	ds_read_b128 v[210:213], v214 offset:2048
	ds_read_b128 v[214:217], v214 offset:3072
	global_load_lds_dwordx4 v130, s[0:1]
	s_add_i32 m0, s25, 0x2000
	s_nop 0
	global_load_lds_dwordx4 v134, s[0:1]
	s_waitcnt vmcnt(8)
	s_waitcnt lgkmcnt(0)
	s_setprio 1
	s_barrier
	v_mfma_f32_16x16x32_bf16 v[116:119], v[202:205], v[166:169], v[116:119]
	v_mfma_f32_16x16x32_bf16 v[112:115], v[210:213], v[166:169], v[112:115]
	v_mfma_f32_16x16x32_bf16 v[100:103], v[202:205], v[174:177], v[100:103]
	v_mfma_f32_16x16x32_bf16 v[96:99], v[210:213], v[174:177], v[96:99]
	v_mfma_f32_16x16x32_bf16 v[84:87], v[202:205], v[182:185], v[84:87]
	v_mfma_f32_16x16x32_bf16 v[80:83], v[210:213], v[182:185], v[80:83]
	v_mfma_f32_16x16x32_bf16 v[68:71], v[202:205], v[190:193], v[68:71]
	v_mfma_f32_16x16x32_bf16 v[64:67], v[210:213], v[190:193], v[64:67]
	v_mfma_f32_16x16x32_bf16 v[116:119], v[206:209], v[170:173], v[116:119]
	v_mfma_f32_16x16x32_bf16 v[112:115], v[214:217], v[170:173], v[112:115]
	v_mfma_f32_16x16x32_bf16 v[100:103], v[206:209], v[178:181], v[100:103]
	v_mfma_f32_16x16x32_bf16 v[96:99], v[214:217], v[178:181], v[96:99]
	v_mfma_f32_16x16x32_bf16 v[84:87], v[206:209], v[186:189], v[84:87]
	v_mfma_f32_16x16x32_bf16 v[80:83], v[214:217], v[186:189], v[80:83]
	v_mfma_f32_16x16x32_bf16 v[68:71], v[206:209], v[194:197], v[68:71]
	v_mfma_f32_16x16x32_bf16 v[64:67], v[214:217], v[194:197], v[64:67]
	s_mov_b32 m0, s44
	s_mov_b64 s[0:1], 0x80
	v_lshl_add_u64 v[144:145], v[218:219], 0, s[0:1]
	s_barrier
	s_setprio 0
	ds_read_b128 v[166:169], v150 offset:49152
	ds_read_b128 v[170:173], v150 offset:50176
	ds_read_b128 v[174:177], v150 offset:51200
	ds_read_b128 v[178:181], v150 offset:52224
	ds_read_b128 v[182:185], v150 offset:53248
	ds_read_b128 v[186:189], v150 offset:54272
	ds_read_b128 v[190:193], v150 offset:55296
	ds_read_b128 v[194:197], v150 offset:56320
	global_load_lds_dwordx4 v[144:145], off
	v_lshl_add_u64 v[144:145], v[220:221], 0, s[0:1]
	s_mov_b32 m0, s45
	s_nop 0
	global_load_lds_dwordx4 v[144:145], off
	s_waitcnt lgkmcnt(0)
	s_setprio 1
	s_barrier
	v_mfma_f32_16x16x32_bf16 v[60:63], v[140:143], v[166:169], v[60:63]
	v_mfma_f32_16x16x32_bf16 v[56:59], v[158:161], v[166:169], v[56:59]
	v_mfma_f32_16x16x32_bf16 v[44:47], v[140:143], v[174:177], v[44:47]
	v_mfma_f32_16x16x32_bf16 v[40:43], v[158:161], v[174:177], v[40:43]
	v_mfma_f32_16x16x32_bf16 v[28:31], v[140:143], v[182:185], v[28:31]
	v_mfma_f32_16x16x32_bf16 v[24:27], v[158:161], v[182:185], v[24:27]
	v_mfma_f32_16x16x32_bf16 v[12:15], v[140:143], v[190:193], v[12:15]
	v_mfma_f32_16x16x32_bf16 v[8:11], v[158:161], v[190:193], v[8:11]
	v_mfma_f32_16x16x32_bf16 v[60:63], v[154:157], v[170:173], v[60:63]
	v_mfma_f32_16x16x32_bf16 v[56:59], v[162:165], v[170:173], v[56:59]
	v_mfma_f32_16x16x32_bf16 v[44:47], v[154:157], v[178:181], v[44:47]
	v_mfma_f32_16x16x32_bf16 v[40:43], v[162:165], v[178:181], v[40:43]
	v_mfma_f32_16x16x32_bf16 v[28:31], v[154:157], v[186:189], v[28:31]
	v_mfma_f32_16x16x32_bf16 v[24:27], v[162:165], v[186:189], v[24:27]
	v_mfma_f32_16x16x32_bf16 v[12:15], v[154:157], v[194:197], v[12:15]
	v_mfma_f32_16x16x32_bf16 v[8:11], v[162:165], v[194:197], v[8:11]
	s_barrier
	s_setprio 0
	s_add_u32 s4, s4, 0x40080
	s_addc_u32 s5, s5, 0
	s_add_i32 s24, s24, s31
	s_mov_b32 m0, s24
	s_nop 0
	global_load_lds_dwordx4 v130, s[4:5]
	s_add_i32 m0, s24, 0x2000
	s_nop 0
	global_load_lds_dwordx4 v134, s[4:5]
	s_waitcnt vmcnt(8)
	s_setprio 1
	s_barrier
	v_mfma_f32_16x16x32_bf16 v[52:55], v[202:205], v[166:169], v[52:55]
	v_mfma_f32_16x16x32_bf16 v[48:51], v[210:213], v[166:169], v[48:51]
	v_mfma_f32_16x16x32_bf16 v[36:39], v[202:205], v[174:177], v[36:39]
	v_mfma_f32_16x16x32_bf16 v[32:35], v[210:213], v[174:177], v[32:35]
	v_mfma_f32_16x16x32_bf16 v[20:23], v[202:205], v[182:185], v[20:23]
	v_mfma_f32_16x16x32_bf16 v[16:19], v[210:213], v[182:185], v[16:19]
	v_mfma_f32_16x16x32_bf16 v[4:7], v[202:205], v[190:193], v[4:7]
	v_mfma_f32_16x16x32_bf16 v[0:3], v[210:213], v[190:193], v[0:3]
	v_mfma_f32_16x16x32_bf16 v[52:55], v[206:209], v[170:173], v[52:55]
	v_mfma_f32_16x16x32_bf16 v[48:51], v[214:217], v[170:173], v[48:51]
	v_mfma_f32_16x16x32_bf16 v[36:39], v[206:209], v[178:181], v[36:39]
	v_mfma_f32_16x16x32_bf16 v[32:35], v[214:217], v[178:181], v[32:35]
	v_mfma_f32_16x16x32_bf16 v[20:23], v[206:209], v[186:189], v[20:23]
	v_mfma_f32_16x16x32_bf16 v[16:19], v[214:217], v[186:189], v[16:19]
	v_mfma_f32_16x16x32_bf16 v[4:7], v[206:209], v[194:197], v[4:7]
	v_mfma_f32_16x16x32_bf16 v[0:3], v[214:217], v[194:197], v[0:3]
	s_add_i32 s61, s61, 2
	s_add_u32 s2, s2, 0x100
	s_addc_u32 s3, s3, 0
	s_add_u32 s59, s59, 0x100
	s_addc_u32 s60, s60, 0
	s_cmp_gt_u32 s61, 13
	s_barrier
;     __device__ __forceinline__ void operator()(const AccT& acc, const Unit& u, int wr, int wc, int fr, int fq) const {
;     ...
;         const int rbase = wr * 64 + fr;
;         const int tb = u.pn * 256 + wc * 32 + 8 * fq;
;         const int o0 = wc * 32 + 8 * fq;
;         const int j = fr & 3; const float sgn = ((fr >> 2) & 1) ? 1.0f : -1.0f;
; #pragma unroll
;         for (int ai = 0; ai < 2; ++ai) {
;             const int hh = 2 * ai + wr;
;             const float l2f = lgd[hh] * 1.4426950408889634f, l2b = lgd[4 + hh] * 1.4426950408889634f;
;             const float zf0 = exp2f((float)(127 - o0) * l2f), zfs = exp2f(-l2f), zb0 = exp2f((float)o0 * l2b), zbs = exp2f(l2b);
; #pragma unroll
;             for (int m = 0; m < 4; ++m) {
;                 const int r = rbase + ai * 128 + m * 16;
;                 const int d = 4 * (2 * m + (fr >> 3)) + j;
; #pragma unroll
;                 for (int bj = 0; bj < 2; ++bj) {
;                     const int t0 = tb + bj * 128;
;                     float v[8];
; #pragma unroll
;                     for (int jj = 0; jj < 4; ++jj) { v[jj] = acc[ai][bj][m][0][jj]; v[4 + jj] = acc[ai][bj][m][1][jj]; }
;                     if constexpr (ROPE) {
;                         const int t = t0 & 2047;
; #pragma unroll
;                         for (int hf = 0; hf < 2; ++hf) {
;                             f32x4 cs, sn;
;                             if (m < 2) { const float c1 = ropeA[(t >> 6) * 16 + d], s1 = ropeA[1024 + (t >> 6) * 16 + d]; cs = (f32x4){c1, c1, c1, c1}; sn = (f32x4){s1, s1, s1, s1}; }
;                             else { const float* cb = ropeA + 2048 + (d - 16) * 64 + (t & 63) + 4 * hf; cs = *(const f32x4*)(cb); sn = *(const f32x4*)(cb + 1024); }
; #pragma unroll
;                             for (int jj = 0; jj < 4; ++jj) { const float pr = __shfl_xor(v[4 * hf + jj], 4); v[4 * hf + jj] = v[4 * hf + jj] * cs[jj] + sgn * pr * sn[jj]; }
;                             __builtin_amdgcn_sched_barrier(0);
;                         }
;                     }
;                     float zf[8], zb[8]; zf[0] = zf0; zb[0] = zb0;
; #pragma unroll
;                     for (int jj = 1; jj < 8; ++jj) { zf[jj] = zf[jj - 1] * zfs; zb[jj] = zb[jj - 1] * zbs; }
;                     u32x4 wf, wb;
	s_setprio 0
	s_cbranch_scc0 .LBB0_693
	v_mov_b32_e32 v141, v147
	v_mov_b32_e32 v140, v146
	global_load_dword v156, v131, s[6:7]
	global_load_dword v157, v131, s[6:7] offset:16
	s_lshl_b32 s2, s56, 8
	s_or_b32 s2, s2, s43
	v_add_u32_e32 v140, s42, v140
	v_lshlrev_b32_e32 v141, 3, v141
	v_add_u32_e32 v142, s2, v141
	v_add_u32_e32 v143, s43, v141
	v_ashrrev_i32_e32 v141, 31, v140
	v_sub_u32_e32 v144, 0x7f, v143
	v_lshlrev_b64 v[140:141], 14, v[140:141]
	v_cvt_f32_i32_e32 v154, v143
	v_ashrrev_i32_e32 v143, 31, v142
	v_cvt_f32_i32_e32 v155, v144
	v_lshl_add_u64 v[140:141], s[70:71], 0, v[140:141]
	s_mov_b32 s3, 0x400000
	v_lshl_add_u64 v[140:141], v[142:143], 1, v[140:141]
	v_add_co_u32_e32 v144, vcc, s3, v140
	s_mov_b64 s[4:5], 0x400000
	s_nop 0
	v_addc_co_u32_e32 v145, vcc, 0, v141, vcc
	v_lshl_add_u64 v[142:143], v[140:141], 0, s[4:5]
	s_waitcnt vmcnt(0)
	v_mul_f32_e32 v158, 0x3fb8aa3b, v156
	v_mul_f32_e32 v159, 0x3fb8aa3b, v157
	v_mul_f32_e32 v160, v158, v155
	v_cmp_lt_f32_e32 vcc, s51, v158
	v_mul_f32_e32 v162, v159, v154
	v_cmp_gt_f32_e64 s[2:3], s49, v159
	v_cndmask_b32_e32 v161, 0, v153, vcc
	v_cmp_gt_f32_e64 s[4:5], s49, v160
	v_cndmask_b32_e64 v163, 0, v153, s[2:3]
	s_and_b64 s[24:25], vcc, exec
	v_cmp_gt_f32_e32 vcc, s49, v162
	v_fmac_f32_e32 v163, 0x3fb8aa3b, v157
	v_cndmask_b32_e64 v157, 0, v153, s[4:5]
	v_cndmask_b32_e32 v162, 0, v153, vcc
	v_fmac_f32_e32 v161, 0xbfb8aa3b, v156
	v_fmac_f32_e32 v157, v158, v155
	v_fmac_f32_e32 v162, v159, v154
	v_exp_f32_e32 v161, v161
	v_exp_f32_e32 v163, v163
	v_exp_f32_e32 v157, v157
	v_exp_f32_e32 v158, v162
	v_cndmask_b32_e64 v160, 0, v152, s[4:5]
	s_cselect_b32 s4, 0xffffffc0, 0
	s_and_b64 s[2:3], s[2:3], exec
	v_cndmask_b32_e32 v156, 0, v152, vcc
	s_cselect_b32 s2, 0xffffffc0, 0
	v_ldexp_f32 v161, v161, s4
	v_ldexp_f32 v162, v163, s2
	v_ldexp_f32 v163, v157, v160
	v_ldexp_f32 v156, v158, v156
	v_mul_f32_e32 v164, v161, v163
	v_mul_f32_e32 v157, v162, v156
	v_mul_f32_e32 v158, v124, v163
	v_mul_f32_e32 v165, v124, v156
	v_mul_f32_e32 v166, v161, v164
	v_mul_f32_e32 v124, v162, v157
	v_mul_f32_e32 v159, v125, v164
	v_mul_f32_e32 v167, v125, v157
	v_mul_f32_e32 v168, v161, v166
	v_mul_f32_e32 v125, v162, v124
	v_cvt_pk_bf16_f32 v158, v158, v159
	v_mul_f32_e32 v159, v126, v166
	v_mul_f32_e32 v169, v126, v124
	v_mul_f32_e32 v170, v161, v168
	v_mul_f32_e32 v126, v162, v125
	v_mul_f32_e32 v171, v161, v170
	v_mul_f32_e32 v172, v162, v126
	v_mul_f32_e32 v160, v127, v168
	v_mul_f32_e32 v174, v161, v171
	v_mul_f32_e32 v175, v162, v172
	v_cvt_pk_bf16_f32 v159, v159, v160
	v_mul_f32_e32 v160, v120, v170
	v_mul_f32_e32 v173, v120, v126
	v_mul_f32_e32 v120, v121, v171
	v_mul_f32_e32 v177, v161, v174
	v_mul_f32_e32 v162, v162, v175
	v_mul_f32_e32 v176, v121, v172
	v_cvt_pk_bf16_f32 v160, v160, v120
	v_mul_f32_e32 v120, v122, v174
	v_mul_f32_e32 v121, v123, v177
	v_mul_f32_e32 v123, v123, v162
	v_cvt_pk_bf16_f32 v161, v120, v121
	v_mul_f32_e32 v127, v127, v125
	v_mul_f32_e32 v178, v122, v175
	v_cvt_pk_bf16_f32 v120, v165, v167
	v_cvt_pk_bf16_f32 v121, v169, v127
	v_cvt_pk_bf16_f32 v122, v173, v176
	v_cvt_pk_bf16_f32 v123, v178, v123
	global_store_dwordx4 v[140:141], v[158:161], off
	global_store_dwordx4 v[144:145], v[120:123], off
	s_nop 1
	v_mul_f32_e32 v120, v116, v163
	v_mul_f32_e32 v121, v117, v164
	v_cvt_pk_bf16_f32 v120, v120, v121
	v_mul_f32_e32 v121, v118, v166
	v_mul_f32_e32 v122, v119, v168
	v_cvt_pk_bf16_f32 v121, v121, v122
	v_mul_f32_e32 v122, v112, v170
	v_mul_f32_e32 v123, v113, v171
	v_cvt_pk_bf16_f32 v122, v122, v123
	v_mul_f32_e32 v123, v114, v174
	v_mul_f32_e32 v116, v116, v156
	v_mul_f32_e32 v117, v117, v157
	v_mul_f32_e32 v127, v115, v177
	v_cvt_pk_bf16_f32 v123, v123, v127
	v_cvt_pk_bf16_f32 v116, v116, v117
	v_mul_f32_e32 v117, v118, v124
	v_mul_f32_e32 v118, v119, v125
	v_mul_f32_e32 v112, v112, v126
	v_mul_f32_e32 v113, v113, v172
	v_cvt_pk_bf16_f32 v117, v117, v118
	v_cvt_pk_bf16_f32 v118, v112, v113
	v_mul_f32_e32 v112, v114, v175
	v_mul_f32_e32 v113, v115, v162
	v_cvt_pk_bf16_f32 v119, v112, v113
	global_store_dwordx4 v[140:141], v[120:123], off offset:256
	global_store_dwordx4 v[142:143], v[116:119], off offset:256
	v_mul_f32_e32 v112, v108, v163
	v_mul_f32_e32 v113, v109, v164
	v_cvt_pk_bf16_f32 v112, v112, v113
	v_mul_f32_e32 v113, v110, v166
	v_mul_f32_e32 v114, v111, v168
	v_cvt_pk_bf16_f32 v113, v113, v114
	v_mul_f32_e32 v114, v104, v170
	v_mul_f32_e32 v115, v105, v171
	v_cvt_pk_bf16_f32 v114, v114, v115
	v_mul_f32_e32 v115, v106, v174
	v_mul_f32_e32 v108, v108, v156
	v_mul_f32_e32 v109, v109, v157
	v_mul_f32_e32 v116, v107, v177
	v_cvt_pk_bf16_f32 v115, v115, v116
	v_cvt_pk_bf16_f32 v108, v108, v109
	v_mul_f32_e32 v109, v110, v124
	v_mul_f32_e32 v110, v111, v125
	v_mul_f32_e32 v104, v104, v126
	s_mov_b64 s[2:3], 0x40000
	v_cvt_pk_bf16_f32 v109, v109, v110
	v_mul_f32_e32 v105, v105, v172
	v_cvt_pk_bf16_f32 v110, v104, v105
	v_mul_f32_e32 v104, v106, v175
	v_lshl_add_u64 v[116:117], v[140:141], 0, s[2:3]
	s_mov_b32 s2, 0x40000
	v_mul_f32_e32 v105, v107, v162
	v_cvt_pk_bf16_f32 v111, v104, v105
	v_add_co_u32_e32 v104, vcc, s2, v140
	s_mov_b64 s[2:3], 0x440000
	s_nop 0
	v_addc_co_u32_e32 v105, vcc, 0, v141, vcc
	global_store_dwordx4 v[104:105], v[112:115], off
	s_nop 1
	v_lshl_add_u64 v[112:113], v[140:141], 0, s[2:3]
	s_mov_b32 s2, 0x440000
	v_add_co_u32_e32 v104, vcc, s2, v140
	s_nop 1
	v_addc_co_u32_e32 v105, vcc, 0, v141, vcc
	global_store_dwordx4 v[104:105], v[108:111], off
	v_mul_f32_e32 v104, v100, v163
	v_mul_f32_e32 v105, v101, v164
	v_cvt_pk_bf16_f32 v104, v104, v105
	v_mul_f32_e32 v105, v102, v166
	v_mul_f32_e32 v106, v103, v168
	v_cvt_pk_bf16_f32 v105, v105, v106
;     __device__ __forceinline__ void operator()(const AccT& acc, const Unit& u, int wr, int wc, int fr, int fq) const {
;     ...
;         for (int ai = 0; ai < 2; ++ai) {
;             const int hh = 2 * ai + wr;
;             const float l2f = lgd[hh] * 1.4426950408889634f, l2b = lgd[4 + hh] * 1.4426950408889634f;
;             const float zf0 = exp2f((float)(127 - o0) * l2f), zfs = exp2f(-l2f), zb0 = exp2f((float)o0 * l2b), zbs = exp2f(l2b);
; #pragma unroll
;             for (int m = 0; m < 4; ++m) {
;                 const int r = rbase + ai * 128 + m * 16;
;                 const int d = 4 * (2 * m + (fr >> 3)) + j;
; #pragma unroll
;                 for (int bj = 0; bj < 2; ++bj) {
;                     const int t0 = tb + bj * 128;
;                     float v[8];
; #pragma unroll
;                     for (int jj = 0; jj < 4; ++jj) { v[jj] = acc[ai][bj][m][0][jj]; v[4 + jj] = acc[ai][bj][m][1][jj]; }
;                     if constexpr (ROPE) {
;                         const int t = t0 & 2047;
; #pragma unroll
;                         for (int hf = 0; hf < 2; ++hf) {
;                             f32x4 cs, sn;
;                             if (m < 2) { const float c1 = ropeA[(t >> 6) * 16 + d], s1 = ropeA[1024 + (t >> 6) * 16 + d]; cs = (f32x4){c1, c1, c1, c1}; sn = (f32x4){s1, s1, s1, s1}; }
;                             else { const float* cb = ropeA + 2048 + (d - 16) * 64 + (t & 63) + 4 * hf; cs = *(const f32x4*)(cb); sn = *(const f32x4*)(cb + 1024); }
; #pragma unroll
;                             for (int jj = 0; jj < 4; ++jj) { const float pr = __shfl_xor(v[4 * hf + jj], 4); v[4 * hf + jj] = v[4 * hf + jj] * cs[jj] + sgn * pr * sn[jj]; }
;                             __builtin_amdgcn_sched_barrier(0);
;                         }
;                     }
;                     float zf[8], zb[8]; zf[0] = zf0; zb[0] = zb0;
; #pragma unroll
;                     for (int jj = 1; jj < 8; ++jj) { zf[jj] = zf[jj - 1] * zfs; zb[jj] = zb[jj - 1] * zbs; }
;                     u32x4 wf, wb;
;                     wf.x = cvt_pk_bf16(v[0] * zf[0], v[1] * zf[1]); wf.y = cvt_pk_bf16(v[2] * zf[2], v[3] * zf[3]); wf.z = cvt_pk_bf16(v[4] * zf[4], v[5] * zf[5]); wf.w = cvt_pk_bf16(v[6] * zf[6], v[7] * zf[7]);
	v_mul_f32_e32 v106, v96, v170
	v_mul_f32_e32 v107, v97, v171
	v_cvt_pk_bf16_f32 v106, v106, v107
	v_mul_f32_e32 v107, v98, v174
	v_mul_f32_e32 v100, v100, v156
	v_mul_f32_e32 v101, v101, v157
	v_mul_f32_e32 v108, v99, v177
	v_cvt_pk_bf16_f32 v107, v107, v108
	v_cvt_pk_bf16_f32 v100, v100, v101
	v_mul_f32_e32 v101, v102, v124
	v_mul_f32_e32 v102, v103, v125
	v_mul_f32_e32 v96, v96, v126
	v_mul_f32_e32 v97, v97, v172
	v_cvt_pk_bf16_f32 v101, v101, v102
	v_cvt_pk_bf16_f32 v102, v96, v97
	v_mul_f32_e32 v96, v98, v175
	v_mul_f32_e32 v97, v99, v162
	v_cvt_pk_bf16_f32 v103, v96, v97
	global_store_dwordx4 v[116:117], v[104:107], off offset:256
	global_store_dwordx4 v[112:113], v[100:103], off offset:256
	v_mul_f32_e32 v96, v92, v163
	v_mul_f32_e32 v97, v93, v164
	v_cvt_pk_bf16_f32 v96, v96, v97
	v_mul_f32_e32 v97, v94, v166
	v_mul_f32_e32 v98, v95, v168
	v_cvt_pk_bf16_f32 v97, v97, v98
	v_mul_f32_e32 v98, v88, v170
	v_mul_f32_e32 v99, v89, v171
	v_cvt_pk_bf16_f32 v98, v98, v99
	v_mul_f32_e32 v99, v90, v174
	v_mul_f32_e32 v92, v92, v156
	v_mul_f32_e32 v93, v93, v157
	v_mul_f32_e32 v100, v91, v177
	v_cvt_pk_bf16_f32 v99, v99, v100
	v_cvt_pk_bf16_f32 v92, v92, v93
	v_mul_f32_e32 v93, v94, v124
	v_mul_f32_e32 v94, v95, v125
	v_mul_f32_e32 v88, v88, v126
	s_mov_b64 s[2:3], 0x80000
	v_cvt_pk_bf16_f32 v93, v93, v94
	v_mul_f32_e32 v89, v89, v172
	v_cvt_pk_bf16_f32 v94, v88, v89
	v_mul_f32_e32 v88, v90, v175
	v_lshl_add_u64 v[100:101], v[140:141], 0, s[2:3]
	s_mov_b32 s2, 0x80000
	v_mul_f32_e32 v89, v91, v162
	v_cvt_pk_bf16_f32 v95, v88, v89
	v_add_co_u32_e32 v88, vcc, s2, v140
	s_mov_b64 s[2:3], 0x480000
	s_nop 0
	v_addc_co_u32_e32 v89, vcc, 0, v141, vcc
	global_store_dwordx4 v[88:89], v[96:99], off
	s_nop 1
	v_lshl_add_u64 v[96:97], v[140:141], 0, s[2:3]
	s_mov_b32 s2, 0x480000
	v_add_co_u32_e32 v88, vcc, s2, v140
	s_nop 1
	v_addc_co_u32_e32 v89, vcc, 0, v141, vcc
	global_store_dwordx4 v[88:89], v[92:95], off
	v_mul_f32_e32 v88, v84, v163
	v_mul_f32_e32 v89, v85, v164
	v_cvt_pk_bf16_f32 v88, v88, v89
	v_mul_f32_e32 v89, v86, v166
	v_mul_f32_e32 v90, v87, v168
	v_cvt_pk_bf16_f32 v89, v89, v90
	v_mul_f32_e32 v90, v80, v170
	v_mul_f32_e32 v91, v81, v171
	v_cvt_pk_bf16_f32 v90, v90, v91
	v_mul_f32_e32 v91, v82, v174
	v_mul_f32_e32 v84, v84, v156
	v_mul_f32_e32 v85, v85, v157
	v_mul_f32_e32 v92, v83, v177
	v_cvt_pk_bf16_f32 v91, v91, v92
	v_cvt_pk_bf16_f32 v84, v84, v85
	v_mul_f32_e32 v85, v86, v124
	v_mul_f32_e32 v86, v87, v125
	v_mul_f32_e32 v80, v80, v126
	v_mul_f32_e32 v81, v81, v172
	v_cvt_pk_bf16_f32 v85, v85, v86
	v_cvt_pk_bf16_f32 v86, v80, v81
	v_mul_f32_e32 v80, v82, v175
	v_mul_f32_e32 v81, v83, v162
	v_cvt_pk_bf16_f32 v87, v80, v81
	global_store_dwordx4 v[100:101], v[88:91], off offset:256
	global_store_dwordx4 v[96:97], v[84:87], off offset:256
	v_mul_f32_e32 v80, v76, v163
	v_mul_f32_e32 v81, v77, v164
	v_cvt_pk_bf16_f32 v80, v80, v81
	v_mul_f32_e32 v81, v78, v166
	v_mul_f32_e32 v82, v79, v168
	v_cvt_pk_bf16_f32 v81, v81, v82
	v_mul_f32_e32 v82, v72, v170
	v_mul_f32_e32 v83, v73, v171
	v_cvt_pk_bf16_f32 v82, v82, v83
	v_mul_f32_e32 v83, v74, v174
	v_mul_f32_e32 v76, v76, v156
	v_mul_f32_e32 v77, v77, v157
	v_mul_f32_e32 v84, v75, v177
	v_cvt_pk_bf16_f32 v83, v83, v84
	v_cvt_pk_bf16_f32 v76, v76, v77
	v_mul_f32_e32 v77, v78, v124
	v_mul_f32_e32 v78, v79, v125
	v_mul_f32_e32 v72, v72, v126
	s_mov_b64 s[2:3], 0xc0000
	v_cvt_pk_bf16_f32 v77, v77, v78
	v_mul_f32_e32 v73, v73, v172
	v_cvt_pk_bf16_f32 v78, v72, v73
	v_mul_f32_e32 v72, v74, v175
	v_lshl_add_u64 v[84:85], v[140:141], 0, s[2:3]
	s_mov_b32 s2, 0xc0000
	v_mul_f32_e32 v73, v75, v162
	v_cvt_pk_bf16_f32 v79, v72, v73
	v_add_co_u32_e32 v72, vcc, s2, v140
	s_mov_b64 s[2:3], 0x4c0000
	s_nop 0
	v_addc_co_u32_e32 v73, vcc, 0, v141, vcc
	global_store_dwordx4 v[72:73], v[80:83], off
	s_nop 1
	v_lshl_add_u64 v[80:81], v[140:141], 0, s[2:3]
	s_mov_b32 s2, 0x4c0000
	v_add_co_u32_e32 v72, vcc, s2, v140
	s_nop 1
	v_addc_co_u32_e32 v73, vcc, 0, v141, vcc
	global_store_dwordx4 v[72:73], v[76:79], off
	v_mul_f32_e32 v72, v68, v163
	v_mul_f32_e32 v73, v69, v164
	v_cvt_pk_bf16_f32 v72, v72, v73
	v_mul_f32_e32 v73, v70, v166
	v_mul_f32_e32 v74, v71, v168
	v_cvt_pk_bf16_f32 v73, v73, v74
	v_mul_f32_e32 v74, v64, v170
	v_mul_f32_e32 v75, v65, v171
	v_cvt_pk_bf16_f32 v74, v74, v75
	v_mul_f32_e32 v75, v66, v174
	v_mul_f32_e32 v68, v68, v156
	v_mul_f32_e32 v69, v69, v157
	v_mul_f32_e32 v76, v67, v177
	v_cvt_pk_bf16_f32 v75, v75, v76
	v_cvt_pk_bf16_f32 v68, v68, v69
	v_mul_f32_e32 v69, v70, v124
	v_mul_f32_e32 v70, v71, v125
	v_mul_f32_e32 v64, v64, v126
	v_mul_f32_e32 v65, v65, v172
	v_cvt_pk_bf16_f32 v69, v69, v70
	v_cvt_pk_bf16_f32 v70, v64, v65
	v_mul_f32_e32 v64, v66, v175
	v_mul_f32_e32 v65, v67, v162
	v_cvt_pk_bf16_f32 v71, v64, v65
	global_store_dwordx4 v[84:85], v[72:75], off offset:256
	global_store_dwordx4 v[80:81], v[68:71], off offset:256
	global_load_dword v70, v131, s[6:7] offset:8
	s_nop 0
	global_load_dword v71, v131, s[6:7] offset:24
	s_mov_b32 s17, 0x200000
	v_add_co_u32_e32 v76, vcc, s17, v140
	s_mov_b32 s19, 0x600000
	s_nop 0
	v_addc_co_u32_e32 v77, vcc, 0, v141, vcc
	v_add_co_u32_e32 v68, vcc, s19, v140
	s_mov_b64 s[2:3], 0x200000
	s_nop 0
	v_addc_co_u32_e32 v69, vcc, 0, v141, vcc
	s_mov_b64 s[4:5], 0x600000
	v_lshl_add_u64 v[64:65], v[140:141], 0, s[2:3]
	v_lshl_add_u64 v[66:67], v[140:141], 0, s[4:5]
	s_waitcnt vmcnt(0)
;     __device__ __forceinline__ void operator()(const AccT& acc, const Unit& u, int wr, int wc, int fr, int fq) const {
;     ...
;             const float l2f = lgd[hh] * 1.4426950408889634f, l2b = lgd[4 + hh] * 1.4426950408889634f;
;             const float zf0 = exp2f((float)(127 - o0) * l2f), zfs = exp2f(-l2f), zb0 = exp2f((float)o0 * l2b), zbs = exp2f(l2b);
; #pragma unroll
;             for (int m = 0; m < 4; ++m) {
;                 const int r = rbase + ai * 128 + m * 16;
;                 const int d = 4 * (2 * m + (fr >> 3)) + j;
; #pragma unroll
;                 for (int bj = 0; bj < 2; ++bj) {
;                     const int t0 = tb + bj * 128;
;                     float v[8];
; #pragma unroll
;                     for (int jj = 0; jj < 4; ++jj) { v[jj] = acc[ai][bj][m][0][jj]; v[4 + jj] = acc[ai][bj][m][1][jj]; }
;                     if constexpr (ROPE) {
;                         const int t = t0 & 2047;
; #pragma unroll
;                         for (int hf = 0; hf < 2; ++hf) {
;                             f32x4 cs, sn;
;                             if (m < 2) { const float c1 = ropeA[(t >> 6) * 16 + d], s1 = ropeA[1024 + (t >> 6) * 16 + d]; cs = (f32x4){c1, c1, c1, c1}; sn = (f32x4){s1, s1, s1, s1}; }
;                             else { const float* cb = ropeA + 2048 + (d - 16) * 64 + (t & 63) + 4 * hf; cs = *(const f32x4*)(cb); sn = *(const f32x4*)(cb + 1024); }
; #pragma unroll
;                             for (int jj = 0; jj < 4; ++jj) { const float pr = __shfl_xor(v[4 * hf + jj], 4); v[4 * hf + jj] = v[4 * hf + jj] * cs[jj] + sgn * pr * sn[jj]; }
;                             __builtin_amdgcn_sched_barrier(0);
;                         }
;                     }
;                     float zf[8], zb[8]; zf[0] = zf0; zb[0] = zb0;
; #pragma unroll
;                     for (int jj = 1; jj < 8; ++jj) { zf[jj] = zf[jj - 1] * zfs; zb[jj] = zb[jj - 1] * zbs; }
;                     u32x4 wf, wb;
;                     wf.x = cvt_pk_bf16(v[0] * zf[0], v[1] * zf[1]); wf.y = cvt_pk_bf16(v[2] * zf[2], v[3] * zf[3]); wf.z = cvt_pk_bf16(v[4] * zf[4], v[5] * zf[5]); wf.w = cvt_pk_bf16(v[6] * zf[6], v[7] * zf[7]);
;                     wb.x = cvt_pk_bf16(v[0] * zb[0], v[1] * zb[1]); wb.y = cvt_pk_bf16(v[2] * zb[2], v[3] * zb[3]); wb.z = cvt_pk_bf16(v[4] * zb[4], v[5] * zb[5]); wb.w = cvt_pk_bf16(v[6] * zb[6], v[7] * zb[7]);
	v_mul_f32_e32 v72, 0x3fb8aa3b, v70
	v_mul_f32_e32 v73, 0x3fb8aa3b, v71
	v_mul_f32_e32 v74, v72, v155
	v_cmp_lt_f32_e32 vcc, s51, v72
	v_mul_f32_e32 v78, v73, v154
	v_cmp_gt_f32_e64 s[2:3], s49, v73
	v_cndmask_b32_e32 v75, 0, v153, vcc
	v_cmp_gt_f32_e64 s[4:5], s49, v74
	v_cndmask_b32_e64 v79, 0, v153, s[2:3]
	s_and_b64 s[24:25], vcc, exec
	v_cmp_gt_f32_e32 vcc, s49, v78
	v_fmac_f32_e32 v79, 0x3fb8aa3b, v71
	v_cndmask_b32_e64 v71, 0, v153, s[4:5]
	v_cndmask_b32_e32 v78, 0, v153, vcc
	v_fmac_f32_e32 v75, 0xbfb8aa3b, v70
	v_fmac_f32_e32 v71, v72, v155
	v_fmac_f32_e32 v78, v73, v154
	v_exp_f32_e32 v75, v75
	v_exp_f32_e32 v79, v79
	v_exp_f32_e32 v71, v71
	v_exp_f32_e32 v72, v78
	v_cndmask_b32_e64 v74, 0, v152, s[4:5]
	s_cselect_b32 s4, 0xffffffc0, 0
	s_and_b64 s[2:3], s[2:3], exec
	v_cndmask_b32_e32 v70, 0, v152, vcc
	s_cselect_b32 s2, 0xffffffc0, 0
	v_ldexp_f32 v75, v75, s4
	v_ldexp_f32 v78, v79, s2
	v_ldexp_f32 v79, v71, v74
	v_ldexp_f32 v70, v72, v70
	v_mul_f32_e32 v80, v75, v79
	v_mul_f32_e32 v71, v78, v70
	v_mul_f32_e32 v72, v60, v79
	v_mul_f32_e32 v81, v60, v70
	v_mul_f32_e32 v82, v75, v80
	v_mul_f32_e32 v60, v78, v71
	v_mul_f32_e32 v83, v75, v82
	v_mul_f32_e32 v84, v78, v60
	v_mul_f32_e32 v85, v75, v83
	v_mul_f32_e32 v86, v78, v84
	v_mul_f32_e32 v73, v61, v80
	v_mul_f32_e32 v87, v75, v85
	v_mul_f32_e32 v88, v78, v86
	v_cvt_pk_bf16_f32 v72, v72, v73
	v_mul_f32_e32 v73, v62, v82
	v_mul_f32_e32 v74, v63, v83
	v_mul_f32_e32 v90, v75, v87
	v_mul_f32_e32 v91, v78, v88
	v_cvt_pk_bf16_f32 v73, v73, v74
	v_mul_f32_e32 v74, v56, v85
	v_mul_f32_e32 v89, v56, v86
	v_mul_f32_e32 v56, v57, v87
	v_mul_f32_e32 v93, v75, v90
	v_mul_f32_e32 v78, v78, v91
	v_mul_f32_e32 v92, v57, v88
	v_cvt_pk_bf16_f32 v74, v74, v56
	v_mul_f32_e32 v56, v58, v90
	v_mul_f32_e32 v57, v59, v93
	v_mul_f32_e32 v59, v59, v78
	v_cvt_pk_bf16_f32 v75, v56, v57
	v_mul_f32_e32 v61, v61, v71
	v_mul_f32_e32 v62, v62, v60
	v_mul_f32_e32 v63, v63, v84
	v_mul_f32_e32 v94, v58, v91
	v_cvt_pk_bf16_f32 v56, v81, v61
	v_cvt_pk_bf16_f32 v57, v62, v63
	v_cvt_pk_bf16_f32 v58, v89, v92
	v_cvt_pk_bf16_f32 v59, v94, v59
	global_store_dwordx4 v[76:77], v[72:75], off
	global_store_dwordx4 v[68:69], v[56:59], off
	s_nop 1
	v_mul_f32_e32 v56, v52, v79
	v_mul_f32_e32 v57, v53, v80
	v_cvt_pk_bf16_f32 v56, v56, v57
	v_mul_f32_e32 v57, v54, v82
	v_mul_f32_e32 v58, v55, v83
	v_cvt_pk_bf16_f32 v57, v57, v58
	v_mul_f32_e32 v58, v48, v85
	v_mul_f32_e32 v59, v49, v87
	v_cvt_pk_bf16_f32 v58, v58, v59
	v_mul_f32_e32 v59, v50, v90
	v_mul_f32_e32 v52, v52, v70
	v_mul_f32_e32 v53, v53, v71
	v_mul_f32_e32 v61, v51, v93
	v_cvt_pk_bf16_f32 v59, v59, v61
	v_cvt_pk_bf16_f32 v52, v52, v53
	v_mul_f32_e32 v53, v54, v60
	v_mul_f32_e32 v54, v55, v84
	v_mul_f32_e32 v48, v48, v86
	v_mul_f32_e32 v49, v49, v88
	v_cvt_pk_bf16_f32 v53, v53, v54
	v_cvt_pk_bf16_f32 v54, v48, v49
	v_mul_f32_e32 v48, v50, v91
	v_mul_f32_e32 v49, v51, v78
	v_cvt_pk_bf16_f32 v55, v48, v49
	global_store_dwordx4 v[64:65], v[56:59], off offset:256
	global_store_dwordx4 v[66:67], v[52:55], off offset:256
	v_mul_f32_e32 v48, v44, v79
	v_mul_f32_e32 v49, v45, v80
	v_cvt_pk_bf16_f32 v48, v48, v49
	v_mul_f32_e32 v49, v46, v82
	v_mul_f32_e32 v50, v47, v83
	v_cvt_pk_bf16_f32 v49, v49, v50
	v_mul_f32_e32 v50, v40, v85
	v_mul_f32_e32 v51, v41, v87
	v_cvt_pk_bf16_f32 v50, v50, v51
	v_mul_f32_e32 v51, v42, v90
	v_mul_f32_e32 v44, v44, v70
	v_mul_f32_e32 v45, v45, v71
	v_mul_f32_e32 v52, v43, v93
	v_cvt_pk_bf16_f32 v51, v51, v52
	v_cvt_pk_bf16_f32 v44, v44, v45
	v_mul_f32_e32 v45, v46, v60
	v_mul_f32_e32 v46, v47, v84
	v_mul_f32_e32 v40, v40, v86
	s_mov_b64 s[2:3], 0x240000
	v_cvt_pk_bf16_f32 v45, v45, v46
	v_mul_f32_e32 v41, v41, v88
	v_cvt_pk_bf16_f32 v46, v40, v41
	v_mul_f32_e32 v40, v42, v91
	v_lshl_add_u64 v[52:53], v[140:141], 0, s[2:3]
	s_mov_b32 s2, 0x240000
	v_mul_f32_e32 v41, v43, v78
	v_cvt_pk_bf16_f32 v47, v40, v41
	v_add_co_u32_e32 v40, vcc, s2, v140
	s_mov_b64 s[2:3], 0x640000
	s_nop 0
	v_addc_co_u32_e32 v41, vcc, 0, v141, vcc
	global_store_dwordx4 v[40:41], v[48:51], off
	s_nop 1
	v_lshl_add_u64 v[48:49], v[140:141], 0, s[2:3]
	s_mov_b32 s2, 0x640000
	v_add_co_u32_e32 v40, vcc, s2, v140
	s_nop 1
	v_addc_co_u32_e32 v41, vcc, 0, v141, vcc
	global_store_dwordx4 v[40:41], v[44:47], off
	v_mul_f32_e32 v40, v36, v79
	v_mul_f32_e32 v41, v37, v80
	v_cvt_pk_bf16_f32 v40, v40, v41
	v_mul_f32_e32 v41, v38, v82
	v_mul_f32_e32 v42, v39, v83
	v_cvt_pk_bf16_f32 v41, v41, v42
	v_mul_f32_e32 v42, v32, v85
	v_mul_f32_e32 v43, v33, v87
	v_cvt_pk_bf16_f32 v42, v42, v43
	v_mul_f32_e32 v43, v34, v90
	v_mul_f32_e32 v36, v36, v70
; __device__ __forceinline__ unsigned cvt_pk_bf16(float lo, float hi) { unsigned r; asm volatile("v_cvt_pk_bf16_f32 %0, %1, %2" : "=v"(r) : "v"(lo), "v"(hi)); return r; }
; #define PG8_WAIT_V(n) asm volatile("s_waitcnt vmcnt(" #n ")" ::: "memory")
; #define PG8_BAR __builtin_amdgcn_s_barrier()
; template <class Epi, class Sched>
; __device__ __forceinline__ void gemm_phase(LAS unsigned char* lds, const Gemm g, const Sched& S, const Epi& E) {
;     ...
;         E(acc, cur, wr, wc, fr, fq);
;         if (!has_next) break;
; #pragma unroll
;         for (int a = 0; a < 2; ++a)
; #pragma unroll
;             for (int b = 0; b < 2; ++b)
; #pragma unroll
;                 for (int m = 0; m < 4; ++m)
; #pragma unroll
;                     for (int n = 0; n < 2; ++n) acc[a][b][m][n] = (f32x4){0.f, 0.f, 0.f, 0.f};
;         cur = nxt; cA = nA; cB = nB; ++ui;
;     }
;     PG8_WAIT_V(0);
;     if (wr == 0) PG8_BAR;
;     PG8_BAR;
;     __device__ __forceinline__ void operator()(const AccT& acc, const Unit& u, int wr, int wc, int fr, int fq) const {
;     ...
;                     float zf[8], zb[8]; zf[0] = zf0; zb[0] = zb0;
; #pragma unroll
;                     for (int jj = 1; jj < 8; ++jj) { zf[jj] = zf[jj - 1] * zfs; zb[jj] = zb[jj - 1] * zbs; }
;                     u32x4 wf, wb;
;                     wf.x = cvt_pk_bf16(v[0] * zf[0], v[1] * zf[1]); wf.y = cvt_pk_bf16(v[2] * zf[2], v[3] * zf[3]); wf.z = cvt_pk_bf16(v[4] * zf[4], v[5] * zf[5]); wf.w = cvt_pk_bf16(v[6] * zf[6], v[7] * zf[7]);
;                     wb.x = cvt_pk_bf16(v[0] * zb[0], v[1] * zb[1]); wb.y = cvt_pk_bf16(v[2] * zb[2], v[3] * zb[3]); wb.z = cvt_pk_bf16(v[4] * zb[4], v[5] * zb[5]); wb.w = cvt_pk_bf16(v[6] * zb[6], v[7] * zb[7]);
;                     *(u32x4*)(KTZ + (size_t)r * NT + t0) = wf;
;                     *(u32x4*)(KTZ + (size_t)(256 + r) * NT + t0) = wb;
	v_mul_f32_e32 v37, v37, v71
	v_mul_f32_e32 v44, v35, v93
	v_cvt_pk_bf16_f32 v43, v43, v44
	v_cvt_pk_bf16_f32 v36, v36, v37
	v_mul_f32_e32 v37, v38, v60
	v_mul_f32_e32 v38, v39, v84
	v_mul_f32_e32 v32, v32, v86
	v_mul_f32_e32 v33, v33, v88
	v_cvt_pk_bf16_f32 v37, v37, v38
	v_cvt_pk_bf16_f32 v38, v32, v33
	v_mul_f32_e32 v32, v34, v91
	v_mul_f32_e32 v33, v35, v78
	v_cvt_pk_bf16_f32 v39, v32, v33
	global_store_dwordx4 v[52:53], v[40:43], off offset:256
	global_store_dwordx4 v[48:49], v[36:39], off offset:256
	v_mul_f32_e32 v32, v28, v79
	v_mul_f32_e32 v33, v29, v80
	v_cvt_pk_bf16_f32 v32, v32, v33
	v_mul_f32_e32 v33, v30, v82
	v_mul_f32_e32 v34, v31, v83
	v_cvt_pk_bf16_f32 v33, v33, v34
	v_mul_f32_e32 v34, v24, v85
	v_mul_f32_e32 v35, v25, v87
	v_cvt_pk_bf16_f32 v34, v34, v35
	v_mul_f32_e32 v35, v26, v90
	v_mul_f32_e32 v28, v28, v70
	v_mul_f32_e32 v29, v29, v71
	v_mul_f32_e32 v36, v27, v93
	v_cvt_pk_bf16_f32 v35, v35, v36
	v_cvt_pk_bf16_f32 v28, v28, v29
	v_mul_f32_e32 v29, v30, v60
	v_mul_f32_e32 v30, v31, v84
	v_mul_f32_e32 v24, v24, v86
	v_cvt_pk_bf16_f32 v29, v29, v30
	v_mul_f32_e32 v25, v25, v88
	v_cvt_pk_bf16_f32 v30, v24, v25
	v_mul_f32_e32 v24, v26, v91
	v_mul_f32_e32 v25, v27, v78
	v_cvt_pk_bf16_f32 v31, v24, v25
	v_add_co_u32_e32 v24, vcc, s52, v140
	s_mov_b64 s[2:3], 0x280000
	s_nop 0
	v_addc_co_u32_e32 v25, vcc, 0, v141, vcc
	global_store_dwordx4 v[24:25], v[32:35], off
	v_add_co_u32_e32 v24, vcc, s53, v140
	v_lshl_add_u64 v[36:37], v[140:141], 0, s[2:3]
	s_nop 0
	v_addc_co_u32_e32 v25, vcc, 0, v141, vcc
	v_lshl_add_u64 v[32:33], v[140:141], 0, s[8:9]
	global_store_dwordx4 v[24:25], v[28:31], off
	v_mul_f32_e32 v24, v20, v79
	v_mul_f32_e32 v25, v21, v80
	v_cvt_pk_bf16_f32 v24, v24, v25
	v_mul_f32_e32 v25, v22, v82
	v_mul_f32_e32 v26, v23, v83
	v_cvt_pk_bf16_f32 v25, v25, v26
	v_mul_f32_e32 v26, v16, v85
	v_mul_f32_e32 v27, v17, v87
	v_cvt_pk_bf16_f32 v26, v26, v27
	v_mul_f32_e32 v27, v18, v90
	v_mul_f32_e32 v20, v20, v70
	v_mul_f32_e32 v21, v21, v71
	v_mul_f32_e32 v28, v19, v93
	v_cvt_pk_bf16_f32 v27, v27, v28
	v_cvt_pk_bf16_f32 v20, v20, v21
	v_mul_f32_e32 v21, v22, v60
	v_mul_f32_e32 v22, v23, v84
	v_mul_f32_e32 v16, v16, v86
	v_mul_f32_e32 v17, v17, v88
	v_cvt_pk_bf16_f32 v21, v21, v22
	v_cvt_pk_bf16_f32 v22, v16, v17
	v_mul_f32_e32 v16, v18, v91
	v_mul_f32_e32 v17, v19, v78
	v_cvt_pk_bf16_f32 v23, v16, v17
	global_store_dwordx4 v[36:37], v[24:27], off offset:256
	global_store_dwordx4 v[32:33], v[20:23], off offset:256
	v_mul_f32_e32 v16, v12, v79
	v_mul_f32_e32 v17, v13, v80
	v_cvt_pk_bf16_f32 v16, v16, v17
	v_mul_f32_e32 v17, v14, v82
	v_mul_f32_e32 v18, v15, v83
	v_cvt_pk_bf16_f32 v17, v17, v18
	v_mul_f32_e32 v18, v8, v85
	v_mul_f32_e32 v19, v9, v87
	v_cvt_pk_bf16_f32 v18, v18, v19
	v_mul_f32_e32 v19, v10, v90
	v_mul_f32_e32 v12, v12, v70
	v_mul_f32_e32 v13, v13, v71
	v_mul_f32_e32 v20, v11, v93
	v_cvt_pk_bf16_f32 v19, v19, v20
	v_cvt_pk_bf16_f32 v12, v12, v13
	v_mul_f32_e32 v13, v14, v60
	v_mul_f32_e32 v14, v15, v84
	v_mul_f32_e32 v8, v8, v86
	v_cvt_pk_bf16_f32 v13, v13, v14
	v_mul_f32_e32 v9, v9, v88
	v_cvt_pk_bf16_f32 v14, v8, v9
	v_mul_f32_e32 v8, v10, v91
	v_mul_f32_e32 v9, v11, v78
	v_cvt_pk_bf16_f32 v15, v8, v9
	v_add_co_u32_e32 v8, vcc, s54, v140
	v_lshl_add_u64 v[20:21], v[140:141], 0, s[10:11]
	s_nop 0
	v_addc_co_u32_e32 v9, vcc, 0, v141, vcc
	global_store_dwordx4 v[8:9], v[16:19], off
	v_add_co_u32_e32 v8, vcc, s55, v140
	s_nop 0
	v_lshl_add_u64 v[16:17], v[140:141], 0, s[12:13]
	v_addc_co_u32_e32 v9, vcc, 0, v141, vcc
	global_store_dwordx4 v[8:9], v[12:15], off
	v_mul_f32_e32 v8, v4, v79
	v_mul_f32_e32 v9, v5, v80
	v_cvt_pk_bf16_f32 v8, v8, v9
	v_mul_f32_e32 v9, v6, v82
	v_mul_f32_e32 v10, v7, v83
	v_cvt_pk_bf16_f32 v9, v9, v10
	v_mul_f32_e32 v10, v0, v85
	v_mul_f32_e32 v11, v1, v87
	v_cvt_pk_bf16_f32 v10, v10, v11
	v_mul_f32_e32 v11, v2, v90
	v_mul_f32_e32 v4, v4, v70
	v_mul_f32_e32 v5, v5, v71
	v_mul_f32_e32 v12, v3, v93
	v_cvt_pk_bf16_f32 v11, v11, v12
	v_cvt_pk_bf16_f32 v4, v4, v5
	v_mul_f32_e32 v5, v6, v60
	v_mul_f32_e32 v6, v7, v84
	v_mul_f32_e32 v0, v0, v86
	v_mul_f32_e32 v1, v1, v88
	v_cvt_pk_bf16_f32 v5, v5, v6
	v_cvt_pk_bf16_f32 v6, v0, v1
	v_mul_f32_e32 v0, v2, v91
	v_mul_f32_e32 v1, v3, v78
	v_cvt_pk_bf16_f32 v7, v0, v1
	global_store_dwordx4 v[20:21], v[8:11], off offset:256
	global_store_dwordx4 v[16:17], v[4:7], off offset:256
	s_and_b64 vcc, exec, s[14:15]
	s_mov_b32 s56, s16
	s_mov_b64 s[4:5], s[22:23]
	s_mov_b64 s[2:3], s[20:21]
	s_cbranch_vccz .LBB0_686
	s_waitcnt vmcnt(0)
	s_cmpk_gt_u32 s27, 0xff
	s_cbranch_scc1 .LBB0_697
	s_barrier

; #define PG8_STAGE(bufoff, gbase, voff) do { _Pragma("unroll") for (int _i = 0; _i < 2; ++_i) \
;         __builtin_amdgcn_global_load_lds((const unsigned*)((const char*)(gbase) + (voff)[_i]), (LAS unsigned*)(lds + (bufoff) + ldsw + _i * 8192), 16, 0, 0); } while (0)
; #define PG8_LDA(dst, b, h) do { _Pragma("unroll") for (int m = 0; m < 4; ++m) _Pragma("unroll") for (int k = 0; k < 2; ++k) dst[m][k] = *(const LAS bf16x8*)(lds + PG8_SA(b, h) + aoff + m * 2048 + k * 1024); } while (0)
; #define PG8_LDB(dst, b, h) do { _Pragma("unroll") for (int n = 0; n < 2; ++n) _Pragma("unroll") for (int k = 0; k < 2; ++k) dst[n][k] = *(const LAS bf16x8*)(lds + PG8_SB(b, h) + boff + n * 2048 + k * 1024); } while (0)
; #define PG8_MMA(ai, bj, At, Bt) do { __builtin_amdgcn_s_setprio(1); _Pragma("unroll") for (int m = 0; m < 4; ++m) _Pragma("unroll") for (int n = 0; n < 2; ++n) _Pragma("unroll") for (int k = 0; k < 2; ++k) \
;         acc[ai][bj][m][n] = __builtin_amdgcn_mfma_f32_16x16x32_bf16(Bt[n][k], At[m][k], acc[ai][bj][m][n], 0, 0, 0); __builtin_amdgcn_s_setprio(0); } while (0)
; #define PG8_WAIT_L(n) asm volatile("s_waitcnt lgkmcnt(" #n ")" ::: "memory")
; template <class Epi, class Sched>
; __device__ __forceinline__ void gemm_phase(LAS unsigned char* lds, const Gemm g, const Sched& S, const Epi& E) {
;     ...
;         const bool has_next = S.next(ui + 1, nxt);
;         const char* nA = has_next ? (const char*)g.A + (size_t)nxt.pm * tstep : cA; const char* nB = has_next ? (const char*)g.Bt + (size_t)nxt.pn * tstep : cB;
;         for (int t = 0; t < nt; t += 2) {
;             const bool last = (t == nt - 2);
;             const char* a1 = cA + (size_t)(t + 1) * kstep;
;             const char* a2 = last ? nA : cA + (size_t)(t + 2) * kstep; const char* b2 = last ? nB : cB + (size_t)(t + 2) * kstep;
;             const char* a3 = a2 + kstep; const char* b3 = b2 + kstep;
;             PG8_LDB(B0, 0, 0); PG8_SCHED; PG8_LDA(At, 0, 0); PG8_STAGE(PG8_SA(1, 1), a1 + hstep, voffA);
;             PG8_WAIT_L(8); PG8_BAR; PG8_WAIT_L(0); PG8_MMA(0, 0, At, B0); PG8_BAR; PG8_SCHED;
;             PG8_LDB(B1, 0, 1); PG8_STAGE(PG8_SB(0, 0), b2, voffB);
;             PG8_BAR; PG8_WAIT_L(0); PG8_MMA(0, 1, At, B1); PG8_BAR;
;             PG8_LDA(At, 0, 1); PG8_STAGE(PG8_SA(0, 0), a2, voffA);
;             PG8_BAR; PG8_WAIT_L(0); PG8_MMA(1, 0, At, B0); PG8_BAR; PG8_SCHED;
.LBB0_712:
	s_ashr_i32 s15, s14, 31
	v_cmp_lt_i64_e64 s[26:27], s[16:17], 64
	s_lshl_b64 s[16:17], s[14:15], 19
	s_add_u32 s16, s38, s16
	s_addc_u32 s17, s39, s17
	s_and_b64 s[18:19], s[26:27], exec
	s_cselect_b32 s15, s17, s23
	s_cselect_b32 s54, s16, s22
	s_ashr_i32 s13, s12, 31
	s_lshl_b64 s[18:19], s[12:13], 19
	s_add_u32 s18, s28, s18
	s_addc_u32 s19, s29, s19
	s_and_b64 s[26:27], s[26:27], exec
	s_cselect_b32 s13, s19, s25
	s_cselect_b32 s55, s18, s24
	s_add_u32 s22, s22, 0x40080
	s_addc_u32 s23, s23, 0
	s_add_u32 s56, s24, 0x100
	s_addc_u32 s57, s25, 0
	s_mov_b32 s58, -2
	s_waitcnt lgkmcnt(0)
	ds_read_b128 v[146:149], v143
	ds_read_b128 v[150:153], v143 offset:1024
	ds_read_b128 v[154:157], v143 offset:2048
	ds_read_b128 v[158:161], v143 offset:3072
	s_add_u32 s24, s22, 0xfffc0080
	s_addc_u32 s25, s23, -1
	s_cmp_eq_u32 s58, 12
	s_cselect_b32 s27, s15, s25
	s_cselect_b32 s26, s54, s24
	s_cselect_b32 s25, s13, s57
	s_cselect_b32 s24, s55, s56
	s_add_i32 m0, s21, 0xc000
	ds_read_b128 v[162:165], v144
	ds_read_b128 v[166:169], v144 offset:1024
	ds_read_b128 v[170:173], v144 offset:2048
	ds_read_b128 v[174:177], v144 offset:3072
	ds_read_b128 v[178:181], v144 offset:4096
	ds_read_b128 v[182:185], v144 offset:5120
	ds_read_b128 v[186:189], v144 offset:6144
	ds_read_b128 v[190:193], v144 offset:7168
	global_load_lds_dwordx4 v136, s[22:23]
	s_add_i32 m0, s21, 0xe000
	s_nop 0
	global_load_lds_dwordx4 v138, s[22:23]
	s_waitcnt lgkmcnt(8)
	s_waitcnt vmcnt(8)
	s_waitcnt lgkmcnt(0)
	s_setprio 1
	s_barrier
	v_mfma_f32_16x16x32_bf16 v[124:127], v[146:149], v[162:165], 0
	v_mfma_f32_16x16x32_bf16 v[120:123], v[154:157], v[162:165], 0
	v_mfma_f32_16x16x32_bf16 v[116:119], v[146:149], v[170:173], 0
	v_mfma_f32_16x16x32_bf16 v[108:111], v[154:157], v[170:173], 0
	v_mfma_f32_16x16x32_bf16 v[100:103], v[146:149], v[178:181], 0
	v_mfma_f32_16x16x32_bf16 v[92:95], v[154:157], v[178:181], 0
	v_mfma_f32_16x16x32_bf16 v[84:87], v[146:149], v[186:189], 0
	v_mfma_f32_16x16x32_bf16 v[76:79], v[154:157], v[186:189], 0
	v_mfma_f32_16x16x32_bf16 v[124:127], v[150:153], v[166:169], v[124:127]
	v_mfma_f32_16x16x32_bf16 v[120:123], v[158:161], v[166:169], v[120:123]
	v_mfma_f32_16x16x32_bf16 v[116:119], v[150:153], v[174:177], v[116:119]
	v_mfma_f32_16x16x32_bf16 v[108:111], v[158:161], v[174:177], v[108:111]
	v_mfma_f32_16x16x32_bf16 v[100:103], v[150:153], v[182:185], v[100:103]
	v_mfma_f32_16x16x32_bf16 v[92:95], v[158:161], v[182:185], v[92:95]
	v_mfma_f32_16x16x32_bf16 v[84:87], v[150:153], v[190:193], v[84:87]
	v_mfma_f32_16x16x32_bf16 v[76:79], v[158:161], v[190:193], v[76:79]
	s_barrier
	s_setprio 0
	s_add_i32 s59, s46, s34
	s_mov_b32 m0, s59
	ds_read_b128 v[194:197], v145
	ds_read_b128 v[202:205], v145 offset:1024
	ds_read_b128 v[206:209], v145 offset:2048
	ds_read_b128 v[210:213], v145 offset:3072
	global_load_lds_dwordx4 v130, s[24:25]
	s_add_i32 m0, s59, 0x2000
	s_nop 0
	global_load_lds_dwordx4 v134, s[24:25]
	s_waitcnt vmcnt(8)
	s_waitcnt lgkmcnt(0)
	s_setprio 1
	s_barrier
	v_mfma_f32_16x16x32_bf16 v[112:115], v[194:197], v[162:165], 0
	v_mfma_f32_16x16x32_bf16 v[104:107], v[206:209], v[162:165], 0
	v_mfma_f32_16x16x32_bf16 v[96:99], v[194:197], v[170:173], 0
	v_mfma_f32_16x16x32_bf16 v[88:91], v[206:209], v[170:173], 0
	v_mfma_f32_16x16x32_bf16 v[80:83], v[194:197], v[178:181], 0
	v_mfma_f32_16x16x32_bf16 v[72:75], v[206:209], v[178:181], 0
	v_mfma_f32_16x16x32_bf16 v[68:71], v[194:197], v[186:189], 0
	v_mfma_f32_16x16x32_bf16 v[64:67], v[206:209], v[186:189], 0
	v_mfma_f32_16x16x32_bf16 v[112:115], v[202:205], v[166:169], v[112:115]
	v_mfma_f32_16x16x32_bf16 v[104:107], v[210:213], v[166:169], v[104:107]
	v_mfma_f32_16x16x32_bf16 v[96:99], v[202:205], v[174:177], v[96:99]
	v_mfma_f32_16x16x32_bf16 v[88:91], v[210:213], v[174:177], v[88:91]
	v_mfma_f32_16x16x32_bf16 v[80:83], v[202:205], v[182:185], v[80:83]
	v_mfma_f32_16x16x32_bf16 v[72:75], v[210:213], v[182:185], v[72:75]
	v_mfma_f32_16x16x32_bf16 v[68:71], v[202:205], v[190:193], v[68:71]
	v_mfma_f32_16x16x32_bf16 v[64:67], v[210:213], v[190:193], v[64:67]
	s_mov_b32 m0, s21
	v_lshl_add_u64 v[216:217], s[26:27], 0, v[128:129]
	s_barrier
	s_setprio 0
	ds_read_b128 v[162:165], v144 offset:16384
	ds_read_b128 v[166:169], v144 offset:17408
	ds_read_b128 v[170:173], v144 offset:18432
	ds_read_b128 v[174:177], v144 offset:19456
	ds_read_b128 v[178:181], v144 offset:20480
	ds_read_b128 v[182:185], v144 offset:21504
	ds_read_b128 v[186:189], v144 offset:22528
	ds_read_b128 v[190:193], v144 offset:23552
	global_load_lds_dwordx4 v128, s[26:27]
	v_lshl_add_u64 v[218:219], s[26:27], 0, v[132:133]
	s_mov_b32 m0, s35
	s_nop 0
	global_load_lds_dwordx4 v132, s[26:27]
	s_waitcnt lgkmcnt(0)
	s_setprio 1
	s_barrier
	v_mfma_f32_16x16x32_bf16 v[60:63], v[146:149], v[162:165], 0
	v_mfma_f32_16x16x32_bf16 v[56:59], v[154:157], v[162:165], 0
	v_mfma_f32_16x16x32_bf16 v[52:55], v[146:149], v[170:173], 0
	v_mfma_f32_16x16x32_bf16 v[44:47], v[154:157], v[170:173], 0
	v_mfma_f32_16x16x32_bf16 v[36:39], v[146:149], v[178:181], 0
	v_mfma_f32_16x16x32_bf16 v[28:31], v[154:157], v[178:181], 0
	v_mfma_f32_16x16x32_bf16 v[20:23], v[146:149], v[186:189], 0
	v_mfma_f32_16x16x32_bf16 v[12:15], v[154:157], v[186:189], 0
	v_mfma_f32_16x16x32_bf16 v[60:63], v[150:153], v[166:169], v[60:63]
	v_mfma_f32_16x16x32_bf16 v[56:59], v[158:161], v[166:169], v[56:59]
	v_mfma_f32_16x16x32_bf16 v[52:55], v[150:153], v[174:177], v[52:55]
	v_mfma_f32_16x16x32_bf16 v[44:47], v[158:161], v[174:177], v[44:47]
	v_mfma_f32_16x16x32_bf16 v[36:39], v[150:153], v[182:185], v[36:39]
	v_mfma_f32_16x16x32_bf16 v[28:31], v[158:161], v[182:185], v[28:31]
	v_mfma_f32_16x16x32_bf16 v[20:23], v[150:153], v[190:193], v[20:23]
	v_mfma_f32_16x16x32_bf16 v[12:15], v[158:161], v[190:193], v[12:15]
	s_barrier
; #define PG8_STAGE(bufoff, gbase, voff) do { _Pragma("unroll") for (int _i = 0; _i < 2; ++_i) \
;         __builtin_amdgcn_global_load_lds((const unsigned*)((const char*)(gbase) + (voff)[_i]), (LAS unsigned*)(lds + (bufoff) + ldsw + _i * 8192), 16, 0, 0); } while (0)
; #define PG8_LDA(dst, b, h) do { _Pragma("unroll") for (int m = 0; m < 4; ++m) _Pragma("unroll") for (int k = 0; k < 2; ++k) dst[m][k] = *(const LAS bf16x8*)(lds + PG8_SA(b, h) + aoff + m * 2048 + k * 1024); } while (0)
; #define PG8_LDB(dst, b, h) do { _Pragma("unroll") for (int n = 0; n < 2; ++n) _Pragma("unroll") for (int k = 0; k < 2; ++k) dst[n][k] = *(const LAS bf16x8*)(lds + PG8_SB(b, h) + boff + n * 2048 + k * 1024); } while (0)
; #define PG8_MMA(ai, bj, At, Bt) do { __builtin_amdgcn_s_setprio(1); _Pragma("unroll") for (int m = 0; m < 4; ++m) _Pragma("unroll") for (int n = 0; n < 2; ++n) _Pragma("unroll") for (int k = 0; k < 2; ++k) \
;         acc[ai][bj][m][n] = __builtin_amdgcn_mfma_f32_16x16x32_bf16(Bt[n][k], At[m][k], acc[ai][bj][m][n], 0, 0, 0); __builtin_amdgcn_s_setprio(0); } while (0)
; #define PG8_WAIT_V(n) asm volatile("s_waitcnt vmcnt(" #n ")" ::: "memory")
; #define PG8_WAIT_L(n) asm volatile("s_waitcnt lgkmcnt(" #n ")" ::: "memory")
; #define PG8_BAR __builtin_amdgcn_s_barrier()
; #define PG8_SCHED __builtin_amdgcn_sched_barrier(0)
; template <class Epi, class Sched>
; __device__ __forceinline__ void gemm_phase(LAS unsigned char* lds, const Gemm g, const Sched& S, const Epi& E) {
;     ...
;             PG8_STAGE(PG8_SB(0, 1), b2 + hstep, voffB);
;             PG8_WAIT_V(6); PG8_BAR; PG8_MMA(1, 1, At, B1); PG8_BAR;
;             PG8_LDB(B0, 1, 0); PG8_SCHED; PG8_LDA(At, 1, 0); PG8_STAGE(PG8_SA(0, 1), a2 + hstep, voffA);
;             PG8_WAIT_L(8); PG8_BAR; PG8_WAIT_L(0); PG8_MMA(0, 0, At, B0); PG8_BAR; PG8_SCHED;
;             PG8_LDB(B1, 1, 1); PG8_STAGE(PG8_SB(1, 0), b3, voffB);
;             PG8_BAR; PG8_WAIT_L(0); PG8_MMA(0, 1, At, B1); PG8_BAR;
;             PG8_LDA(At, 1, 1); PG8_STAGE(PG8_SA(1, 0), a3, voffA);
	s_setprio 0
	s_add_u32 s60, s24, 0x40000
	s_addc_u32 s61, s25, 0
	s_add_i32 s59, s47, s34
	s_mov_b32 m0, s59
	s_nop 0
	global_load_lds_dwordx4 v130, s[60:61]
	s_add_i32 m0, s59, 0x2000
	s_nop 0
	global_load_lds_dwordx4 v134, s[60:61]
	s_add_u32 s26, s26, 0x40000
	s_addc_u32 s27, s27, 0
	s_mov_b32 m0, s36
	s_nop 0
	global_load_lds_dwordx4 v128, s[26:27]
	s_mov_b32 m0, s37
	s_nop 0
	global_load_lds_dwordx4 v132, s[26:27]
	s_waitcnt vmcnt(10)
	s_setprio 1
	s_barrier
	v_mfma_f32_16x16x32_bf16 v[48:51], v[194:197], v[162:165], 0
	v_mfma_f32_16x16x32_bf16 v[40:43], v[206:209], v[162:165], 0
	v_mfma_f32_16x16x32_bf16 v[32:35], v[194:197], v[170:173], 0
	v_mfma_f32_16x16x32_bf16 v[24:27], v[206:209], v[170:173], 0
	v_mfma_f32_16x16x32_bf16 v[16:19], v[194:197], v[178:181], 0
	v_mfma_f32_16x16x32_bf16 v[8:11], v[206:209], v[178:181], 0
	v_mfma_f32_16x16x32_bf16 v[4:7], v[194:197], v[186:189], 0
	v_mfma_f32_16x16x32_bf16 v[0:3], v[206:209], v[186:189], 0
	v_mfma_f32_16x16x32_bf16 v[48:51], v[202:205], v[166:169], v[48:51]
	v_mfma_f32_16x16x32_bf16 v[40:43], v[210:213], v[166:169], v[40:43]
	v_mfma_f32_16x16x32_bf16 v[32:35], v[202:205], v[174:177], v[32:35]
	v_mfma_f32_16x16x32_bf16 v[24:27], v[210:213], v[174:177], v[24:27]
	v_mfma_f32_16x16x32_bf16 v[16:19], v[202:205], v[182:185], v[16:19]
	v_mfma_f32_16x16x32_bf16 v[8:11], v[210:213], v[182:185], v[8:11]
	v_mfma_f32_16x16x32_bf16 v[4:7], v[202:205], v[190:193], v[4:7]
	v_mfma_f32_16x16x32_bf16 v[0:3], v[210:213], v[190:193], v[0:3]
	s_add_i32 s59, 0, 0x18000
	v_add_u32_e32 v158, s59, v142
	s_barrier
	s_setprio 0
	ds_read_b128 v[146:149], v158
	ds_read_b128 v[150:153], v158 offset:1024
	ds_read_b128 v[154:157], v158 offset:2048
	ds_read_b128 v[158:161], v158 offset:3072
	ds_read_b128 v[162:165], v144 offset:32768
	ds_read_b128 v[166:169], v144 offset:33792
	ds_read_b128 v[170:173], v144 offset:34816
	ds_read_b128 v[174:177], v144 offset:35840
	ds_read_b128 v[178:181], v144 offset:36864
	ds_read_b128 v[182:185], v144 offset:37888
	ds_read_b128 v[186:189], v144 offset:38912
	ds_read_b128 v[190:193], v144 offset:39936
	s_waitcnt lgkmcnt(8)
	s_waitcnt vmcnt(8)
	s_waitcnt lgkmcnt(0)
	s_setprio 1
	s_barrier
	v_mfma_f32_16x16x32_bf16 v[124:127], v[146:149], v[162:165], v[124:127]
	v_mfma_f32_16x16x32_bf16 v[120:123], v[154:157], v[162:165], v[120:123]
	v_mfma_f32_16x16x32_bf16 v[116:119], v[146:149], v[170:173], v[116:119]
	v_mfma_f32_16x16x32_bf16 v[108:111], v[154:157], v[170:173], v[108:111]
	v_mfma_f32_16x16x32_bf16 v[100:103], v[146:149], v[178:181], v[100:103]
	v_mfma_f32_16x16x32_bf16 v[92:95], v[154:157], v[178:181], v[92:95]
	v_mfma_f32_16x16x32_bf16 v[84:87], v[146:149], v[186:189], v[84:87]
	v_mfma_f32_16x16x32_bf16 v[76:79], v[154:157], v[186:189], v[76:79]
	v_mfma_f32_16x16x32_bf16 v[124:127], v[150:153], v[166:169], v[124:127]
	v_mfma_f32_16x16x32_bf16 v[120:123], v[158:161], v[166:169], v[120:123]
	v_mfma_f32_16x16x32_bf16 v[116:119], v[150:153], v[174:177], v[116:119]
	v_mfma_f32_16x16x32_bf16 v[108:111], v[158:161], v[174:177], v[108:111]
	v_mfma_f32_16x16x32_bf16 v[100:103], v[150:153], v[182:185], v[100:103]
	v_mfma_f32_16x16x32_bf16 v[92:95], v[158:161], v[182:185], v[92:95]
	v_mfma_f32_16x16x32_bf16 v[84:87], v[150:153], v[190:193], v[84:87]
	v_mfma_f32_16x16x32_bf16 v[76:79], v[158:161], v[190:193], v[76:79]
	s_barrier
	s_setprio 0
	s_add_i32 s26, 0, 0x1c000
	s_add_i32 s27, s59, s34
	v_add_u32_e32 v210, s26, v142
	s_add_u32 s0, s24, 0x80
	s_addc_u32 s1, s25, 0
	s_mov_b32 m0, s27
	ds_read_b128 v[194:197], v210
	ds_read_b128 v[202:205], v210 offset:1024
	ds_read_b128 v[206:209], v210 offset:2048
	ds_read_b128 v[210:213], v210 offset:3072
	global_load_lds_dwordx4 v130, s[0:1]
	s_add_i32 m0, s27, 0x2000
	s_nop 0
	global_load_lds_dwordx4 v134, s[0:1]
	s_waitcnt vmcnt(8)
	s_waitcnt lgkmcnt(0)
	s_setprio 1
	s_barrier
	v_mfma_f32_16x16x32_bf16 v[112:115], v[194:197], v[162:165], v[112:115]
	v_mfma_f32_16x16x32_bf16 v[104:107], v[206:209], v[162:165], v[104:107]
	v_mfma_f32_16x16x32_bf16 v[96:99], v[194:197], v[170:173], v[96:99]
	v_mfma_f32_16x16x32_bf16 v[88:91], v[206:209], v[170:173], v[88:91]
	v_mfma_f32_16x16x32_bf16 v[80:83], v[194:197], v[178:181], v[80:83]
	v_mfma_f32_16x16x32_bf16 v[72:75], v[206:209], v[178:181], v[72:75]
	v_mfma_f32_16x16x32_bf16 v[68:71], v[194:197], v[186:189], v[68:71]
	v_mfma_f32_16x16x32_bf16 v[64:67], v[206:209], v[186:189], v[64:67]
	v_mfma_f32_16x16x32_bf16 v[112:115], v[202:205], v[166:169], v[112:115]
	v_mfma_f32_16x16x32_bf16 v[104:107], v[210:213], v[166:169], v[104:107]
	v_mfma_f32_16x16x32_bf16 v[96:99], v[202:205], v[174:177], v[96:99]
	v_mfma_f32_16x16x32_bf16 v[88:91], v[210:213], v[174:177], v[88:91]
	v_mfma_f32_16x16x32_bf16 v[80:83], v[202:205], v[182:185], v[80:83]
	v_mfma_f32_16x16x32_bf16 v[72:75], v[210:213], v[182:185], v[72:75]
	v_mfma_f32_16x16x32_bf16 v[68:71], v[202:205], v[190:193], v[68:71]
	v_mfma_f32_16x16x32_bf16 v[64:67], v[210:213], v[190:193], v[64:67]
	s_mov_b32 m0, s43
	s_mov_b64 s[0:1], 0x80
	v_lshl_add_u64 v[198:199], v[216:217], 0, s[0:1]
	s_barrier
	s_setprio 0
	ds_read_b128 v[162:165], v144 offset:49152
	ds_read_b128 v[166:169], v144 offset:50176
	ds_read_b128 v[170:173], v144 offset:51200
	ds_read_b128 v[174:177], v144 offset:52224
	ds_read_b128 v[178:181], v144 offset:53248
	ds_read_b128 v[182:185], v144 offset:54272
	ds_read_b128 v[186:189], v144 offset:55296
	ds_read_b128 v[190:193], v144 offset:56320
	global_load_lds_dwordx4 v[198:199], off
	v_lshl_add_u64 v[198:199], v[218:219], 0, s[0:1]
	s_mov_b32 m0, s44
	s_nop 0
	global_load_lds_dwordx4 v[198:199], off
	s_waitcnt lgkmcnt(0)
	s_setprio 1
	s_barrier
; #define PG8_STAGE(bufoff, gbase, voff) do { _Pragma("unroll") for (int _i = 0; _i < 2; ++_i) \
;         __builtin_amdgcn_global_load_lds((const unsigned*)((const char*)(gbase) + (voff)[_i]), (LAS unsigned*)(lds + (bufoff) + ldsw + _i * 8192), 16, 0, 0); } while (0)
; #define PG8_LDA(dst, b, h) do { _Pragma("unroll") for (int m = 0; m < 4; ++m) _Pragma("unroll") for (int k = 0; k < 2; ++k) dst[m][k] = *(const LAS bf16x8*)(lds + PG8_SA(b, h) + aoff + m * 2048 + k * 1024); } while (0)
; #define PG8_LDB(dst, b, h) do { _Pragma("unroll") for (int n = 0; n < 2; ++n) _Pragma("unroll") for (int k = 0; k < 2; ++k) dst[n][k] = *(const LAS bf16x8*)(lds + PG8_SB(b, h) + boff + n * 2048 + k * 1024); } while (0)
; #define PG8_WAIT_V(n) asm volatile("s_waitcnt vmcnt(" #n ")" ::: "memory")
; #define PG8_WAIT_L(n) asm volatile("s_waitcnt lgkmcnt(" #n ")" ::: "memory")
; #define PG8_BAR __builtin_amdgcn_s_barrier()
; #define PG8_SCHED __builtin_amdgcn_sched_barrier(0)
; template <class Epi, class Sched>
; __device__ __forceinline__ void gemm_phase(LAS unsigned char* lds, const Gemm g, const Sched& S, const Epi& E) {
;     ...
;             PG8_LDB(B0, 0, 0); PG8_SCHED; PG8_LDA(At, 0, 0); PG8_STAGE(PG8_SA(1, 1), a1 + hstep, voffA);
;             PG8_WAIT_L(8); PG8_BAR; PG8_WAIT_L(0); PG8_MMA(0, 0, At, B0); PG8_BAR; PG8_SCHED;
;             PG8_LDB(B1, 0, 1); PG8_STAGE(PG8_SB(0, 0), b2, voffB);
;             PG8_BAR; PG8_WAIT_L(0); PG8_MMA(0, 1, At, B1); PG8_BAR;
;             PG8_LDA(At, 0, 1); PG8_STAGE(PG8_SA(0, 0), a2, voffA);
;             PG8_BAR; PG8_WAIT_L(0); PG8_MMA(1, 0, At, B0); PG8_BAR; PG8_SCHED;
;             PG8_STAGE(PG8_SB(0, 1), b2 + hstep, voffB);
;             PG8_WAIT_V(6); PG8_BAR; PG8_MMA(1, 1, At, B1); PG8_BAR;
;             PG8_LDB(B0, 1, 0); PG8_SCHED; PG8_LDA(At, 1, 0); PG8_STAGE(PG8_SA(0, 1), a2 + hstep, voffA);
;             PG8_WAIT_L(8); PG8_BAR; PG8_WAIT_L(0); PG8_MMA(0, 0, At, B0); PG8_BAR; PG8_SCHED;
;             PG8_LDB(B1, 1, 1); PG8_STAGE(PG8_SB(1, 0), b3, voffB);
;             PG8_BAR; PG8_WAIT_L(0); PG8_MMA(0, 1, At, B1); PG8_BAR;
;             PG8_LDA(At, 1, 1); PG8_STAGE(PG8_SA(1, 0), a3, voffA);
;             PG8_BAR; PG8_WAIT_L(0); PG8_MMA(1, 0, At, B0); PG8_BAR; PG8_SCHED;
;             PG8_STAGE(PG8_SB(1, 1), b3 + hstep, voffB);
;             PG8_WAIT_V(6); PG8_BAR; PG8_MMA(1, 1, At, B1); PG8_BAR;
	v_mfma_f32_16x16x32_bf16 v[60:63], v[146:149], v[162:165], v[60:63]
	v_mfma_f32_16x16x32_bf16 v[56:59], v[154:157], v[162:165], v[56:59]
	v_mfma_f32_16x16x32_bf16 v[52:55], v[146:149], v[170:173], v[52:55]
	v_mfma_f32_16x16x32_bf16 v[44:47], v[154:157], v[170:173], v[44:47]
	v_mfma_f32_16x16x32_bf16 v[36:39], v[146:149], v[178:181], v[36:39]
	v_mfma_f32_16x16x32_bf16 v[28:31], v[154:157], v[178:181], v[28:31]
	v_mfma_f32_16x16x32_bf16 v[20:23], v[146:149], v[186:189], v[20:23]
	v_mfma_f32_16x16x32_bf16 v[12:15], v[154:157], v[186:189], v[12:15]
	v_mfma_f32_16x16x32_bf16 v[60:63], v[150:153], v[166:169], v[60:63]
	v_mfma_f32_16x16x32_bf16 v[56:59], v[158:161], v[166:169], v[56:59]
	v_mfma_f32_16x16x32_bf16 v[52:55], v[150:153], v[174:177], v[52:55]
	v_mfma_f32_16x16x32_bf16 v[44:47], v[158:161], v[174:177], v[44:47]
	v_mfma_f32_16x16x32_bf16 v[36:39], v[150:153], v[182:185], v[36:39]
	v_mfma_f32_16x16x32_bf16 v[28:31], v[158:161], v[182:185], v[28:31]
	v_mfma_f32_16x16x32_bf16 v[20:23], v[150:153], v[190:193], v[20:23]
	v_mfma_f32_16x16x32_bf16 v[12:15], v[158:161], v[190:193], v[12:15]
	s_barrier
	s_setprio 0
	s_add_u32 s24, s24, 0x40080
	s_addc_u32 s25, s25, 0
	s_add_i32 s26, s26, s34
	s_mov_b32 m0, s26
	s_nop 0
	global_load_lds_dwordx4 v130, s[24:25]
	s_add_i32 m0, s26, 0x2000
	s_nop 0
	global_load_lds_dwordx4 v134, s[24:25]
	s_waitcnt vmcnt(8)
	s_setprio 1
	s_barrier
	v_mfma_f32_16x16x32_bf16 v[48:51], v[194:197], v[162:165], v[48:51]
	v_mfma_f32_16x16x32_bf16 v[40:43], v[206:209], v[162:165], v[40:43]
	v_mfma_f32_16x16x32_bf16 v[32:35], v[194:197], v[170:173], v[32:35]
	v_mfma_f32_16x16x32_bf16 v[24:27], v[206:209], v[170:173], v[24:27]
	v_mfma_f32_16x16x32_bf16 v[16:19], v[194:197], v[178:181], v[16:19]
	v_mfma_f32_16x16x32_bf16 v[8:11], v[206:209], v[178:181], v[8:11]
	v_mfma_f32_16x16x32_bf16 v[4:7], v[194:197], v[186:189], v[4:7]
	v_mfma_f32_16x16x32_bf16 v[0:3], v[206:209], v[186:189], v[0:3]
	v_mfma_f32_16x16x32_bf16 v[48:51], v[202:205], v[166:169], v[48:51]
	v_mfma_f32_16x16x32_bf16 v[40:43], v[210:213], v[166:169], v[40:43]
	v_mfma_f32_16x16x32_bf16 v[32:35], v[202:205], v[174:177], v[32:35]
	v_mfma_f32_16x16x32_bf16 v[24:27], v[210:213], v[174:177], v[24:27]
	v_mfma_f32_16x16x32_bf16 v[16:19], v[202:205], v[182:185], v[16:19]
	v_mfma_f32_16x16x32_bf16 v[8:11], v[210:213], v[182:185], v[8:11]
	v_mfma_f32_16x16x32_bf16 v[4:7], v[202:205], v[190:193], v[4:7]
	v_mfma_f32_16x16x32_bf16 v[0:3], v[210:213], v[190:193], v[0:3]
	s_add_i32 s58, s58, 2
	s_add_u32 s22, s22, 0x100
	s_addc_u32 s23, s23, 0
	s_add_u32 s56, s56, 0x100
	s_addc_u32 s57, s57, 0
	s_cmp_gt_u32 s58, 13
	s_barrier
	s_setprio 0
.LBB0_713:
	ds_read_b128 v[146:149], v143
	ds_read_b128 v[150:153], v143 offset:1024
	ds_read_b128 v[154:157], v143 offset:2048
	ds_read_b128 v[158:161], v143 offset:3072
	s_add_u32 s24, s22, 0xfffc0080
	s_addc_u32 s25, s23, -1
	s_cmp_eq_u32 s58, 12
	s_cselect_b32 s27, s15, s25
	s_cselect_b32 s26, s54, s24
	s_cselect_b32 s25, s13, s57
	s_cselect_b32 s24, s55, s56
	s_add_i32 m0, s21, 0xc000
	ds_read_b128 v[162:165], v144
	ds_read_b128 v[166:169], v144 offset:1024
	ds_read_b128 v[170:173], v144 offset:2048
	ds_read_b128 v[174:177], v144 offset:3072
	ds_read_b128 v[178:181], v144 offset:4096
	ds_read_b128 v[182:185], v144 offset:5120
	ds_read_b128 v[186:189], v144 offset:6144
	ds_read_b128 v[190:193], v144 offset:7168
	global_load_lds_dwordx4 v136, s[22:23]
	s_add_i32 m0, s21, 0xe000
	s_nop 0
	global_load_lds_dwordx4 v138, s[22:23]
	s_waitcnt lgkmcnt(8)
	s_waitcnt vmcnt(8)
	s_waitcnt lgkmcnt(0)
	s_setprio 1
	s_barrier
	v_mfma_f32_16x16x32_bf16 v[124:127], v[146:149], v[162:165], v[124:127]
	v_mfma_f32_16x16x32_bf16 v[120:123], v[154:157], v[162:165], v[120:123]
	v_mfma_f32_16x16x32_bf16 v[116:119], v[146:149], v[170:173], v[116:119]
	v_mfma_f32_16x16x32_bf16 v[108:111], v[154:157], v[170:173], v[108:111]
	v_mfma_f32_16x16x32_bf16 v[100:103], v[146:149], v[178:181], v[100:103]
	v_mfma_f32_16x16x32_bf16 v[92:95], v[154:157], v[178:181], v[92:95]
	v_mfma_f32_16x16x32_bf16 v[84:87], v[146:149], v[186:189], v[84:87]
	v_mfma_f32_16x16x32_bf16 v[76:79], v[154:157], v[186:189], v[76:79]
	v_mfma_f32_16x16x32_bf16 v[124:127], v[150:153], v[166:169], v[124:127]
	v_mfma_f32_16x16x32_bf16 v[120:123], v[158:161], v[166:169], v[120:123]
	v_mfma_f32_16x16x32_bf16 v[116:119], v[150:153], v[174:177], v[116:119]
	v_mfma_f32_16x16x32_bf16 v[108:111], v[158:161], v[174:177], v[108:111]
	v_mfma_f32_16x16x32_bf16 v[100:103], v[150:153], v[182:185], v[100:103]
	v_mfma_f32_16x16x32_bf16 v[92:95], v[158:161], v[182:185], v[92:95]
	v_mfma_f32_16x16x32_bf16 v[84:87], v[150:153], v[190:193], v[84:87]
	v_mfma_f32_16x16x32_bf16 v[76:79], v[158:161], v[190:193], v[76:79]
	s_barrier
	s_setprio 0
	s_add_i32 s59, s46, s34
	s_mov_b32 m0, s59
	ds_read_b128 v[194:197], v145
	ds_read_b128 v[202:205], v145 offset:1024
	ds_read_b128 v[206:209], v145 offset:2048
	ds_read_b128 v[210:213], v145 offset:3072
	global_load_lds_dwordx4 v130, s[24:25]
	s_add_i32 m0, s59, 0x2000
	s_nop 0
	global_load_lds_dwordx4 v134, s[24:25]
	s_waitcnt vmcnt(8)
	s_waitcnt lgkmcnt(0)
	s_setprio 1
	s_barrier
; #define PG8_STAGE(bufoff, gbase, voff) do { _Pragma("unroll") for (int _i = 0; _i < 2; ++_i) \
;         __builtin_amdgcn_global_load_lds((const unsigned*)((const char*)(gbase) + (voff)[_i]), (LAS unsigned*)(lds + (bufoff) + ldsw + _i * 8192), 16, 0, 0); } while (0)
; #define PG8_LDA(dst, b, h) do { _Pragma("unroll") for (int m = 0; m < 4; ++m) _Pragma("unroll") for (int k = 0; k < 2; ++k) dst[m][k] = *(const LAS bf16x8*)(lds + PG8_SA(b, h) + aoff + m * 2048 + k * 1024); } while (0)
; #define PG8_LDB(dst, b, h) do { _Pragma("unroll") for (int n = 0; n < 2; ++n) _Pragma("unroll") for (int k = 0; k < 2; ++k) dst[n][k] = *(const LAS bf16x8*)(lds + PG8_SB(b, h) + boff + n * 2048 + k * 1024); } while (0)
; #define PG8_MMA(ai, bj, At, Bt) do { __builtin_amdgcn_s_setprio(1); _Pragma("unroll") for (int m = 0; m < 4; ++m) _Pragma("unroll") for (int n = 0; n < 2; ++n) _Pragma("unroll") for (int k = 0; k < 2; ++k) \
;         acc[ai][bj][m][n] = __builtin_amdgcn_mfma_f32_16x16x32_bf16(Bt[n][k], At[m][k], acc[ai][bj][m][n], 0, 0, 0); __builtin_amdgcn_s_setprio(0); } while (0)
; #define PG8_WAIT_V(n) asm volatile("s_waitcnt vmcnt(" #n ")" ::: "memory")
; #define PG8_WAIT_L(n) asm volatile("s_waitcnt lgkmcnt(" #n ")" ::: "memory")
; #define PG8_BAR __builtin_amdgcn_s_barrier()
; #define PG8_SCHED __builtin_amdgcn_sched_barrier(0)
; template <class Epi, class Sched>
; __device__ __forceinline__ void gemm_phase(LAS unsigned char* lds, const Gemm g, const Sched& S, const Epi& E) {
;     ...
;             PG8_BAR; PG8_WAIT_L(0); PG8_MMA(0, 1, At, B1); PG8_BAR;
;             PG8_LDA(At, 0, 1); PG8_STAGE(PG8_SA(0, 0), a2, voffA);
;             PG8_BAR; PG8_WAIT_L(0); PG8_MMA(1, 0, At, B0); PG8_BAR; PG8_SCHED;
;             PG8_STAGE(PG8_SB(0, 1), b2 + hstep, voffB);
;             PG8_WAIT_V(6); PG8_BAR; PG8_MMA(1, 1, At, B1); PG8_BAR;
;             PG8_LDB(B0, 1, 0); PG8_SCHED; PG8_LDA(At, 1, 0); PG8_STAGE(PG8_SA(0, 1), a2 + hstep, voffA);
;             PG8_WAIT_L(8); PG8_BAR; PG8_WAIT_L(0); PG8_MMA(0, 0, At, B0); PG8_BAR; PG8_SCHED;
	v_mfma_f32_16x16x32_bf16 v[112:115], v[194:197], v[162:165], v[112:115]
	v_mfma_f32_16x16x32_bf16 v[104:107], v[206:209], v[162:165], v[104:107]
	v_mfma_f32_16x16x32_bf16 v[96:99], v[194:197], v[170:173], v[96:99]
	v_mfma_f32_16x16x32_bf16 v[88:91], v[206:209], v[170:173], v[88:91]
	v_mfma_f32_16x16x32_bf16 v[80:83], v[194:197], v[178:181], v[80:83]
	v_mfma_f32_16x16x32_bf16 v[72:75], v[206:209], v[178:181], v[72:75]
	v_mfma_f32_16x16x32_bf16 v[68:71], v[194:197], v[186:189], v[68:71]
	v_mfma_f32_16x16x32_bf16 v[64:67], v[206:209], v[186:189], v[64:67]
	v_mfma_f32_16x16x32_bf16 v[112:115], v[202:205], v[166:169], v[112:115]
	v_mfma_f32_16x16x32_bf16 v[104:107], v[210:213], v[166:169], v[104:107]
	v_mfma_f32_16x16x32_bf16 v[96:99], v[202:205], v[174:177], v[96:99]
	v_mfma_f32_16x16x32_bf16 v[88:91], v[210:213], v[174:177], v[88:91]
	v_mfma_f32_16x16x32_bf16 v[80:83], v[202:205], v[182:185], v[80:83]
	v_mfma_f32_16x16x32_bf16 v[72:75], v[210:213], v[182:185], v[72:75]
	v_mfma_f32_16x16x32_bf16 v[68:71], v[202:205], v[190:193], v[68:71]
	v_mfma_f32_16x16x32_bf16 v[64:67], v[210:213], v[190:193], v[64:67]
	s_mov_b32 m0, s21
	v_lshl_add_u64 v[216:217], s[26:27], 0, v[128:129]
	s_barrier
	s_setprio 0
	ds_read_b128 v[162:165], v144 offset:16384
	ds_read_b128 v[166:169], v144 offset:17408
	ds_read_b128 v[170:173], v144 offset:18432
	ds_read_b128 v[174:177], v144 offset:19456
	ds_read_b128 v[178:181], v144 offset:20480
	ds_read_b128 v[182:185], v144 offset:21504
	ds_read_b128 v[186:189], v144 offset:22528
	ds_read_b128 v[190:193], v144 offset:23552
	global_load_lds_dwordx4 v128, s[26:27]
	v_lshl_add_u64 v[218:219], s[26:27], 0, v[132:133]
	s_mov_b32 m0, s35
	s_nop 0
	global_load_lds_dwordx4 v132, s[26:27]
	s_waitcnt lgkmcnt(0)
	s_setprio 1
	s_barrier
	v_mfma_f32_16x16x32_bf16 v[60:63], v[146:149], v[162:165], v[60:63]
	v_mfma_f32_16x16x32_bf16 v[56:59], v[154:157], v[162:165], v[56:59]
	v_mfma_f32_16x16x32_bf16 v[52:55], v[146:149], v[170:173], v[52:55]
	v_mfma_f32_16x16x32_bf16 v[44:47], v[154:157], v[170:173], v[44:47]
	v_mfma_f32_16x16x32_bf16 v[36:39], v[146:149], v[178:181], v[36:39]
	v_mfma_f32_16x16x32_bf16 v[28:31], v[154:157], v[178:181], v[28:31]
	v_mfma_f32_16x16x32_bf16 v[20:23], v[146:149], v[186:189], v[20:23]
	v_mfma_f32_16x16x32_bf16 v[12:15], v[154:157], v[186:189], v[12:15]
	v_mfma_f32_16x16x32_bf16 v[60:63], v[150:153], v[166:169], v[60:63]
	v_mfma_f32_16x16x32_bf16 v[56:59], v[158:161], v[166:169], v[56:59]
	v_mfma_f32_16x16x32_bf16 v[52:55], v[150:153], v[174:177], v[52:55]
	v_mfma_f32_16x16x32_bf16 v[44:47], v[158:161], v[174:177], v[44:47]
	v_mfma_f32_16x16x32_bf16 v[36:39], v[150:153], v[182:185], v[36:39]
	v_mfma_f32_16x16x32_bf16 v[28:31], v[158:161], v[182:185], v[28:31]
	v_mfma_f32_16x16x32_bf16 v[20:23], v[150:153], v[190:193], v[20:23]
	v_mfma_f32_16x16x32_bf16 v[12:15], v[158:161], v[190:193], v[12:15]
	s_barrier
	s_setprio 0
	s_add_u32 s60, s24, 0x40000
	s_addc_u32 s61, s25, 0
	s_add_i32 s59, s47, s34
	s_mov_b32 m0, s59
	s_nop 0
	global_load_lds_dwordx4 v130, s[60:61]
	s_add_i32 m0, s59, 0x2000
	s_nop 0
	global_load_lds_dwordx4 v134, s[60:61]
	s_add_u32 s26, s26, 0x40000
	s_addc_u32 s27, s27, 0
	s_mov_b32 m0, s36
	s_nop 0
	global_load_lds_dwordx4 v128, s[26:27]
	s_mov_b32 m0, s37
	s_nop 0
	global_load_lds_dwordx4 v132, s[26:27]
	s_waitcnt vmcnt(10)
	s_setprio 1
	s_barrier
	v_mfma_f32_16x16x32_bf16 v[48:51], v[194:197], v[162:165], v[48:51]
	v_mfma_f32_16x16x32_bf16 v[40:43], v[206:209], v[162:165], v[40:43]
	v_mfma_f32_16x16x32_bf16 v[32:35], v[194:197], v[170:173], v[32:35]
	v_mfma_f32_16x16x32_bf16 v[24:27], v[206:209], v[170:173], v[24:27]
	v_mfma_f32_16x16x32_bf16 v[16:19], v[194:197], v[178:181], v[16:19]
	v_mfma_f32_16x16x32_bf16 v[8:11], v[206:209], v[178:181], v[8:11]
	v_mfma_f32_16x16x32_bf16 v[4:7], v[194:197], v[186:189], v[4:7]
	v_mfma_f32_16x16x32_bf16 v[0:3], v[206:209], v[186:189], v[0:3]
	v_mfma_f32_16x16x32_bf16 v[48:51], v[202:205], v[166:169], v[48:51]
	v_mfma_f32_16x16x32_bf16 v[40:43], v[210:213], v[166:169], v[40:43]
	v_mfma_f32_16x16x32_bf16 v[32:35], v[202:205], v[174:177], v[32:35]
	v_mfma_f32_16x16x32_bf16 v[24:27], v[210:213], v[174:177], v[24:27]
	v_mfma_f32_16x16x32_bf16 v[16:19], v[202:205], v[182:185], v[16:19]
	v_mfma_f32_16x16x32_bf16 v[8:11], v[210:213], v[182:185], v[8:11]
	v_mfma_f32_16x16x32_bf16 v[4:7], v[202:205], v[190:193], v[4:7]
	v_mfma_f32_16x16x32_bf16 v[0:3], v[210:213], v[190:193], v[0:3]
	s_add_i32 s59, 0, 0x18000
	v_add_u32_e32 v158, s59, v142
	s_barrier
	s_setprio 0
	ds_read_b128 v[146:149], v158
	ds_read_b128 v[150:153], v158 offset:1024
	ds_read_b128 v[154:157], v158 offset:2048
	ds_read_b128 v[158:161], v158 offset:3072
	ds_read_b128 v[162:165], v144 offset:32768
	ds_read_b128 v[166:169], v144 offset:33792
	ds_read_b128 v[170:173], v144 offset:34816
	ds_read_b128 v[174:177], v144 offset:35840
	ds_read_b128 v[178:181], v144 offset:36864
	ds_read_b128 v[182:185], v144 offset:37888
	ds_read_b128 v[186:189], v144 offset:38912
	ds_read_b128 v[190:193], v144 offset:39936
	s_waitcnt lgkmcnt(8)
	s_waitcnt vmcnt(8)
	s_waitcnt lgkmcnt(0)
	s_setprio 1
	s_barrier
; #define PG8_STAGE(bufoff, gbase, voff) do { _Pragma("unroll") for (int _i = 0; _i < 2; ++_i) \
;         __builtin_amdgcn_global_load_lds((const unsigned*)((const char*)(gbase) + (voff)[_i]), (LAS unsigned*)(lds + (bufoff) + ldsw + _i * 8192), 16, 0, 0); } while (0)
; #define PG8_LDA(dst, b, h) do { _Pragma("unroll") for (int m = 0; m < 4; ++m) _Pragma("unroll") for (int k = 0; k < 2; ++k) dst[m][k] = *(const LAS bf16x8*)(lds + PG8_SA(b, h) + aoff + m * 2048 + k * 1024); } while (0)
; #define PG8_LDB(dst, b, h) do { _Pragma("unroll") for (int n = 0; n < 2; ++n) _Pragma("unroll") for (int k = 0; k < 2; ++k) dst[n][k] = *(const LAS bf16x8*)(lds + PG8_SB(b, h) + boff + n * 2048 + k * 1024); } while (0)
; #define PG8_MMA(ai, bj, At, Bt) do { __builtin_amdgcn_s_setprio(1); _Pragma("unroll") for (int m = 0; m < 4; ++m) _Pragma("unroll") for (int n = 0; n < 2; ++n) _Pragma("unroll") for (int k = 0; k < 2; ++k) \
;         acc[ai][bj][m][n] = __builtin_amdgcn_mfma_f32_16x16x32_bf16(Bt[n][k], At[m][k], acc[ai][bj][m][n], 0, 0, 0); __builtin_amdgcn_s_setprio(0); } while (0)
; #define PG8_WAIT_V(n) asm volatile("s_waitcnt vmcnt(" #n ")" ::: "memory")
; #define PG8_WAIT_L(n) asm volatile("s_waitcnt lgkmcnt(" #n ")" ::: "memory")
; #define PG8_BAR __builtin_amdgcn_s_barrier()
; #define PG8_SCHED __builtin_amdgcn_sched_barrier(0)
; template <class Epi, class Sched>
; __device__ __forceinline__ void gemm_phase(LAS unsigned char* lds, const Gemm g, const Sched& S, const Epi& E) {
;     ...
;             PG8_WAIT_L(8); PG8_BAR; PG8_WAIT_L(0); PG8_MMA(0, 0, At, B0); PG8_BAR; PG8_SCHED;
;             PG8_LDB(B1, 1, 1); PG8_STAGE(PG8_SB(1, 0), b3, voffB);
;             PG8_BAR; PG8_WAIT_L(0); PG8_MMA(0, 1, At, B1); PG8_BAR;
;             PG8_LDA(At, 1, 1); PG8_STAGE(PG8_SA(1, 0), a3, voffA);
;             PG8_BAR; PG8_WAIT_L(0); PG8_MMA(1, 0, At, B0); PG8_BAR; PG8_SCHED;
;             PG8_STAGE(PG8_SB(1, 1), b3 + hstep, voffB);
;             PG8_WAIT_V(6); PG8_BAR; PG8_MMA(1, 1, At, B1); PG8_BAR;
	v_mfma_f32_16x16x32_bf16 v[124:127], v[146:149], v[162:165], v[124:127]
	v_mfma_f32_16x16x32_bf16 v[120:123], v[154:157], v[162:165], v[120:123]
	v_mfma_f32_16x16x32_bf16 v[116:119], v[146:149], v[170:173], v[116:119]
	v_mfma_f32_16x16x32_bf16 v[108:111], v[154:157], v[170:173], v[108:111]
	v_mfma_f32_16x16x32_bf16 v[100:103], v[146:149], v[178:181], v[100:103]
	v_mfma_f32_16x16x32_bf16 v[92:95], v[154:157], v[178:181], v[92:95]
	v_mfma_f32_16x16x32_bf16 v[84:87], v[146:149], v[186:189], v[84:87]
	v_mfma_f32_16x16x32_bf16 v[76:79], v[154:157], v[186:189], v[76:79]
	v_mfma_f32_16x16x32_bf16 v[124:127], v[150:153], v[166:169], v[124:127]
	v_mfma_f32_16x16x32_bf16 v[120:123], v[158:161], v[166:169], v[120:123]
	v_mfma_f32_16x16x32_bf16 v[116:119], v[150:153], v[174:177], v[116:119]
	v_mfma_f32_16x16x32_bf16 v[108:111], v[158:161], v[174:177], v[108:111]
	v_mfma_f32_16x16x32_bf16 v[100:103], v[150:153], v[182:185], v[100:103]
	v_mfma_f32_16x16x32_bf16 v[92:95], v[158:161], v[182:185], v[92:95]
	v_mfma_f32_16x16x32_bf16 v[84:87], v[150:153], v[190:193], v[84:87]
	v_mfma_f32_16x16x32_bf16 v[76:79], v[158:161], v[190:193], v[76:79]
	s_barrier
	s_setprio 0
	s_add_i32 s26, 0, 0x1c000
	s_add_i32 s27, s59, s34
	v_add_u32_e32 v210, s26, v142
	s_add_u32 s0, s24, 0x80
	s_addc_u32 s1, s25, 0
	s_mov_b32 m0, s27
	ds_read_b128 v[194:197], v210
	ds_read_b128 v[202:205], v210 offset:1024
	ds_read_b128 v[206:209], v210 offset:2048
	ds_read_b128 v[210:213], v210 offset:3072
	global_load_lds_dwordx4 v130, s[0:1]
	s_add_i32 m0, s27, 0x2000
	s_nop 0
	global_load_lds_dwordx4 v134, s[0:1]
	s_waitcnt vmcnt(8)
	s_waitcnt lgkmcnt(0)
	s_setprio 1
	s_barrier
	v_mfma_f32_16x16x32_bf16 v[112:115], v[194:197], v[162:165], v[112:115]
	v_mfma_f32_16x16x32_bf16 v[104:107], v[206:209], v[162:165], v[104:107]
	v_mfma_f32_16x16x32_bf16 v[96:99], v[194:197], v[170:173], v[96:99]
	v_mfma_f32_16x16x32_bf16 v[88:91], v[206:209], v[170:173], v[88:91]
	v_mfma_f32_16x16x32_bf16 v[80:83], v[194:197], v[178:181], v[80:83]
	v_mfma_f32_16x16x32_bf16 v[72:75], v[206:209], v[178:181], v[72:75]
	v_mfma_f32_16x16x32_bf16 v[68:71], v[194:197], v[186:189], v[68:71]
	v_mfma_f32_16x16x32_bf16 v[64:67], v[206:209], v[186:189], v[64:67]
	v_mfma_f32_16x16x32_bf16 v[112:115], v[202:205], v[166:169], v[112:115]
	v_mfma_f32_16x16x32_bf16 v[104:107], v[210:213], v[166:169], v[104:107]
	v_mfma_f32_16x16x32_bf16 v[96:99], v[202:205], v[174:177], v[96:99]
	v_mfma_f32_16x16x32_bf16 v[88:91], v[210:213], v[174:177], v[88:91]
	v_mfma_f32_16x16x32_bf16 v[80:83], v[202:205], v[182:185], v[80:83]
	v_mfma_f32_16x16x32_bf16 v[72:75], v[210:213], v[182:185], v[72:75]
	v_mfma_f32_16x16x32_bf16 v[68:71], v[202:205], v[190:193], v[68:71]
	v_mfma_f32_16x16x32_bf16 v[64:67], v[210:213], v[190:193], v[64:67]
	s_mov_b32 m0, s43
	s_mov_b64 s[0:1], 0x80
	v_lshl_add_u64 v[198:199], v[216:217], 0, s[0:1]
	s_barrier
	s_setprio 0
	ds_read_b128 v[162:165], v144 offset:49152
	ds_read_b128 v[166:169], v144 offset:50176
	ds_read_b128 v[170:173], v144 offset:51200
	ds_read_b128 v[174:177], v144 offset:52224
	ds_read_b128 v[178:181], v144 offset:53248
	ds_read_b128 v[182:185], v144 offset:54272
	ds_read_b128 v[186:189], v144 offset:55296
	ds_read_b128 v[190:193], v144 offset:56320
	global_load_lds_dwordx4 v[198:199], off
	v_lshl_add_u64 v[198:199], v[218:219], 0, s[0:1]
	s_mov_b32 m0, s44
	s_nop 0
	global_load_lds_dwordx4 v[198:199], off
	s_waitcnt lgkmcnt(0)
	s_setprio 1
	s_barrier
	v_mfma_f32_16x16x32_bf16 v[60:63], v[146:149], v[162:165], v[60:63]
	v_mfma_f32_16x16x32_bf16 v[56:59], v[154:157], v[162:165], v[56:59]
	v_mfma_f32_16x16x32_bf16 v[52:55], v[146:149], v[170:173], v[52:55]
	v_mfma_f32_16x16x32_bf16 v[44:47], v[154:157], v[170:173], v[44:47]
	v_mfma_f32_16x16x32_bf16 v[36:39], v[146:149], v[178:181], v[36:39]
	v_mfma_f32_16x16x32_bf16 v[28:31], v[154:157], v[178:181], v[28:31]
	v_mfma_f32_16x16x32_bf16 v[20:23], v[146:149], v[186:189], v[20:23]
	v_mfma_f32_16x16x32_bf16 v[12:15], v[154:157], v[186:189], v[12:15]
	v_mfma_f32_16x16x32_bf16 v[60:63], v[150:153], v[166:169], v[60:63]
	v_mfma_f32_16x16x32_bf16 v[56:59], v[158:161], v[166:169], v[56:59]
	v_mfma_f32_16x16x32_bf16 v[52:55], v[150:153], v[174:177], v[52:55]
	v_mfma_f32_16x16x32_bf16 v[44:47], v[158:161], v[174:177], v[44:47]
	v_mfma_f32_16x16x32_bf16 v[36:39], v[150:153], v[182:185], v[36:39]
	v_mfma_f32_16x16x32_bf16 v[28:31], v[158:161], v[182:185], v[28:31]
	v_mfma_f32_16x16x32_bf16 v[20:23], v[150:153], v[190:193], v[20:23]
	v_mfma_f32_16x16x32_bf16 v[12:15], v[158:161], v[190:193], v[12:15]
	s_barrier
	s_setprio 0
	s_add_u32 s24, s24, 0x40080
	s_addc_u32 s25, s25, 0
	s_add_i32 s26, s26, s34
	s_mov_b32 m0, s26
	s_nop 0
	global_load_lds_dwordx4 v130, s[24:25]
	s_add_i32 m0, s26, 0x2000
	s_nop 0
	global_load_lds_dwordx4 v134, s[24:25]
	s_waitcnt vmcnt(8)
	s_setprio 1
	s_barrier
; __device__ __forceinline__ unsigned cvt_pk_bf16(float lo, float hi) { unsigned r; asm volatile("v_cvt_pk_bf16_f32 %0, %1, %2" : "=v"(r) : "v"(lo), "v"(hi)); return r; }
; #define PG8_WAIT_V(n) asm volatile("s_waitcnt vmcnt(" #n ")" ::: "memory")
; #define PG8_BAR __builtin_amdgcn_s_barrier()
; template <class Epi, class Sched>
; __device__ __forceinline__ void gemm_phase(LAS unsigned char* lds, const Gemm g, const Sched& S, const Epi& E) {
;     ...
;         E(acc, cur, wr, wc, fr, fq);
;         if (!has_next) break;
; #pragma unroll
;         for (int a = 0; a < 2; ++a)
; #pragma unroll
;             for (int b = 0; b < 2; ++b)
; #pragma unroll
;                 for (int m = 0; m < 4; ++m)
; #pragma unroll
;                     for (int n = 0; n < 2; ++n) acc[a][b][m][n] = (f32x4){0.f, 0.f, 0.f, 0.f};
;         cur = nxt; cA = nA; cB = nB; ++ui;
;     }
;     PG8_WAIT_V(0);
;     if (wr == 0) PG8_BAR;
;     PG8_BAR;
;     __device__ __forceinline__ void operator()(const AccT& acc, const Unit& u, int wr, int wc, int fr, int fq) const {
;     ...
;             for (int m = 0; m < 4; ++m) {
;                 const int r = rbase + ai * 128 + m * 16;
; #pragma unroll
;                 for (int bj = 0; bj < 2; ++bj) {
;                     const int t0 = tb + bj * 128;
;                     const f32x4 v0 = acc[ai][bj][m][0], v1 = acc[ai][bj][m][1];
;                     u32x4 w; w.x = cvt_pk_bf16(v0[0], v0[1]); w.y = cvt_pk_bf16(v0[2], v0[3]); w.z = cvt_pk_bf16(v1[0], v1[1]); w.w = cvt_pk_bf16(v1[2], v1[3]);
;                     *(u32x4*)(VT + (size_t)r * NT + t0) = w;
;                 }
;             }
	v_mfma_f32_16x16x32_bf16 v[48:51], v[194:197], v[162:165], v[48:51]
	v_mfma_f32_16x16x32_bf16 v[40:43], v[206:209], v[162:165], v[40:43]
	v_mfma_f32_16x16x32_bf16 v[32:35], v[194:197], v[170:173], v[32:35]
	v_mfma_f32_16x16x32_bf16 v[24:27], v[206:209], v[170:173], v[24:27]
	v_mfma_f32_16x16x32_bf16 v[16:19], v[194:197], v[178:181], v[16:19]
	v_mfma_f32_16x16x32_bf16 v[8:11], v[206:209], v[178:181], v[8:11]
	v_mfma_f32_16x16x32_bf16 v[4:7], v[194:197], v[186:189], v[4:7]
	v_mfma_f32_16x16x32_bf16 v[0:3], v[206:209], v[186:189], v[0:3]
	v_mfma_f32_16x16x32_bf16 v[48:51], v[202:205], v[166:169], v[48:51]
	v_mfma_f32_16x16x32_bf16 v[40:43], v[210:213], v[166:169], v[40:43]
	v_mfma_f32_16x16x32_bf16 v[32:35], v[202:205], v[174:177], v[32:35]
	v_mfma_f32_16x16x32_bf16 v[24:27], v[210:213], v[174:177], v[24:27]
	v_mfma_f32_16x16x32_bf16 v[16:19], v[202:205], v[182:185], v[16:19]
	v_mfma_f32_16x16x32_bf16 v[8:11], v[210:213], v[182:185], v[8:11]
	v_mfma_f32_16x16x32_bf16 v[4:7], v[202:205], v[190:193], v[4:7]
	v_mfma_f32_16x16x32_bf16 v[0:3], v[210:213], v[190:193], v[0:3]
	s_add_i32 s58, s58, 2
	s_add_u32 s22, s22, 0x100
	s_addc_u32 s23, s23, 0
	s_add_u32 s56, s56, 0x100
	s_addc_u32 s57, s57, 0
	s_cmp_gt_u32 s58, 13
	s_barrier
	s_setprio 0
	s_cbranch_scc0 .LBB0_713
	v_mov_b32_e32 v146, v140
	v_mov_b32_e32 v147, v141
	s_lshl_b32 s13, s20, 8
	s_add_i32 s13, s13, s41
	v_add_u32_e32 v146, s13, v146
	s_lshl_b32 s13, s53, 8
	s_or_b32 s13, s13, s42
	v_lshl_add_u32 v148, v147, 3, s13
	v_ashrrev_i32_e32 v147, 31, v146
	v_cvt_pk_bf16_f32 v124, v124, v125
	v_cvt_pk_bf16_f32 v125, v126, v127
	v_cvt_pk_bf16_f32 v126, v120, v121
	v_lshlrev_b64 v[120:121], 14, v[146:147]
	v_lshl_add_u64 v[120:121], s[62:63], 0, v[120:121]
	v_ashrrev_i32_e32 v149, 31, v148
	v_lshl_add_u64 v[120:121], v[148:149], 1, v[120:121]
	s_mov_b32 s13, 0x40000
	v_cvt_pk_bf16_f32 v127, v122, v123
	global_store_dwordx4 v[120:121], v[124:127], off
	v_cvt_pk_bf16_f32 v112, v112, v113
	v_cvt_pk_bf16_f32 v113, v114, v115
	v_cvt_pk_bf16_f32 v114, v104, v105
	v_cvt_pk_bf16_f32 v115, v106, v107
	global_store_dwordx4 v[120:121], v[112:115], off offset:256
	v_cvt_pk_bf16_f32 v104, v116, v117
	v_cvt_pk_bf16_f32 v105, v118, v119
	v_cvt_pk_bf16_f32 v106, v108, v109
	v_cvt_pk_bf16_f32 v107, v110, v111
	s_mov_b64 s[22:23], 0x40000
	v_add_co_u32_e32 v110, vcc, s13, v120
	v_lshl_add_u64 v[108:109], v[120:121], 0, s[22:23]
	s_nop 0
	v_addc_co_u32_e32 v111, vcc, 0, v121, vcc
	s_mov_b32 s13, 0x80000
	global_store_dwordx4 v[110:111], v[104:107], off
	v_cvt_pk_bf16_f32 v96, v96, v97
	v_cvt_pk_bf16_f32 v97, v98, v99
	v_cvt_pk_bf16_f32 v98, v88, v89
	v_cvt_pk_bf16_f32 v99, v90, v91
	global_store_dwordx4 v[108:109], v[96:99], off offset:256
	v_cvt_pk_bf16_f32 v88, v100, v101
	v_cvt_pk_bf16_f32 v89, v102, v103
	v_cvt_pk_bf16_f32 v90, v92, v93
	v_cvt_pk_bf16_f32 v91, v94, v95
	s_mov_b64 s[22:23], 0x80000
	v_add_co_u32_e32 v94, vcc, s13, v120
	v_lshl_add_u64 v[92:93], v[120:121], 0, s[22:23]
	s_nop 0
	v_addc_co_u32_e32 v95, vcc, 0, v121, vcc
	global_store_dwordx4 v[94:95], v[88:91], off
	v_cvt_pk_bf16_f32 v80, v80, v81
	v_cvt_pk_bf16_f32 v81, v82, v83
	v_cvt_pk_bf16_f32 v82, v72, v73
	v_cvt_pk_bf16_f32 v83, v74, v75
	global_store_dwordx4 v[92:93], v[80:83], off offset:256
	v_cvt_pk_bf16_f32 v72, v84, v85
	v_cvt_pk_bf16_f32 v73, v86, v87
	v_cvt_pk_bf16_f32 v74, v76, v77
	v_cvt_pk_bf16_f32 v75, v78, v79
	s_mov_b64 s[22:23], 0xc0000
	v_add_co_u32_e32 v78, vcc, s48, v120
	v_lshl_add_u64 v[76:77], v[120:121], 0, s[22:23]
	s_nop 0
	v_addc_co_u32_e32 v79, vcc, 0, v121, vcc
	global_store_dwordx4 v[78:79], v[72:75], off
	v_cvt_pk_bf16_f32 v68, v68, v69
	v_cvt_pk_bf16_f32 v69, v70, v71
	v_cvt_pk_bf16_f32 v70, v64, v65
	v_cvt_pk_bf16_f32 v71, v66, v67
	global_store_dwordx4 v[76:77], v[68:71], off offset:256
	v_cvt_pk_bf16_f32 v60, v60, v61
	v_cvt_pk_bf16_f32 v61, v62, v63
	v_cvt_pk_bf16_f32 v62, v56, v57
	v_cvt_pk_bf16_f32 v63, v58, v59
	v_add_co_u32_e32 v58, vcc, s49, v120
	v_lshl_add_u64 v[56:57], v[120:121], 0, s[2:3]
	s_nop 0
	v_addc_co_u32_e32 v59, vcc, 0, v121, vcc
	global_store_dwordx4 v[58:59], v[60:63], off
	v_cvt_pk_bf16_f32 v48, v48, v49
	v_cvt_pk_bf16_f32 v49, v50, v51
	v_cvt_pk_bf16_f32 v50, v40, v41
	v_cvt_pk_bf16_f32 v51, v42, v43
	global_store_dwordx4 v[56:57], v[48:51], off offset:256
	v_cvt_pk_bf16_f32 v40, v52, v53
	v_cvt_pk_bf16_f32 v41, v54, v55
	v_cvt_pk_bf16_f32 v42, v44, v45
	v_cvt_pk_bf16_f32 v43, v46, v47
	v_add_co_u32_e32 v46, vcc, s50, v120
	v_lshl_add_u64 v[44:45], v[120:121], 0, s[4:5]
	s_nop 0
	v_addc_co_u32_e32 v47, vcc, 0, v121, vcc
	global_store_dwordx4 v[46:47], v[40:43], off
	v_cvt_pk_bf16_f32 v32, v32, v33
	v_cvt_pk_bf16_f32 v33, v34, v35
	v_cvt_pk_bf16_f32 v34, v24, v25
	v_cvt_pk_bf16_f32 v35, v26, v27
	global_store_dwordx4 v[44:45], v[32:35], off offset:256
	v_cvt_pk_bf16_f32 v24, v36, v37
	v_cvt_pk_bf16_f32 v25, v38, v39
	v_cvt_pk_bf16_f32 v26, v28, v29
	v_cvt_pk_bf16_f32 v27, v30, v31
	v_add_co_u32_e32 v30, vcc, s51, v120
	v_lshl_add_u64 v[28:29], v[120:121], 0, s[6:7]
	s_nop 0
	v_addc_co_u32_e32 v31, vcc, 0, v121, vcc
	global_store_dwordx4 v[30:31], v[24:27], off
	v_cvt_pk_bf16_f32 v16, v16, v17
	v_cvt_pk_bf16_f32 v17, v18, v19
	v_cvt_pk_bf16_f32 v18, v8, v9
	v_cvt_pk_bf16_f32 v19, v10, v11
	global_store_dwordx4 v[28:29], v[16:19], off offset:256
	v_cvt_pk_bf16_f32 v8, v20, v21
	v_cvt_pk_bf16_f32 v9, v22, v23
	v_cvt_pk_bf16_f32 v10, v12, v13
	v_cvt_pk_bf16_f32 v11, v14, v15
	v_add_co_u32_e32 v14, vcc, s52, v120
	v_lshl_add_u64 v[12:13], v[120:121], 0, s[8:9]
	s_nop 0
	v_addc_co_u32_e32 v15, vcc, 0, v121, vcc
	s_and_b64 vcc, exec, s[10:11]
	s_mov_b32 s53, s12
	s_mov_b32 s20, s14
	s_mov_b64 s[24:25], s[18:19]
	s_mov_b64 s[22:23], s[16:17]
	global_store_dwordx4 v[14:15], v[8:11], off
	v_cvt_pk_bf16_f32 v4, v4, v5
	v_cvt_pk_bf16_f32 v5, v6, v7
	v_cvt_pk_bf16_f32 v6, v0, v1
	v_cvt_pk_bf16_f32 v7, v2, v3
	global_store_dwordx4 v[12:13], v[4:7], off offset:256
	s_cbranch_vccz .LBB0_706
	s_waitcnt vmcnt(0)
	s_cmpk_gt_u32 s31, 0xff
	s_cbranch_scc1 .LBB0_717
	s_barrier

; #define PG8_STAGE(bufoff, gbase, voff) do { _Pragma("unroll") for (int _i = 0; _i < 2; ++_i) \
;         __builtin_amdgcn_global_load_lds((const unsigned*)((const char*)(gbase) + (voff)[_i]), (LAS unsigned*)(lds + (bufoff) + ldsw + _i * 8192), 16, 0, 0); } while (0)
; #define PG8_LDA(dst, b, h) do { _Pragma("unroll") for (int m = 0; m < 4; ++m) _Pragma("unroll") for (int k = 0; k < 2; ++k) dst[m][k] = *(const LAS bf16x8*)(lds + PG8_SA(b, h) + aoff + m * 2048 + k * 1024); } while (0)
; #define PG8_LDB(dst, b, h) do { _Pragma("unroll") for (int n = 0; n < 2; ++n) _Pragma("unroll") for (int k = 0; k < 2; ++k) dst[n][k] = *(const LAS bf16x8*)(lds + PG8_SB(b, h) + boff + n * 2048 + k * 1024); } while (0)
; #define PG8_MMA(ai, bj, At, Bt) do { __builtin_amdgcn_s_setprio(1); _Pragma("unroll") for (int m = 0; m < 4; ++m) _Pragma("unroll") for (int n = 0; n < 2; ++n) _Pragma("unroll") for (int k = 0; k < 2; ++k) \
;         acc[ai][bj][m][n] = __builtin_amdgcn_mfma_f32_16x16x32_bf16(Bt[n][k], At[m][k], acc[ai][bj][m][n], 0, 0, 0); __builtin_amdgcn_s_setprio(0); } while (0)
; #define PG8_WAIT_L(n) asm volatile("s_waitcnt lgkmcnt(" #n ")" ::: "memory")
; template <class Epi, class Sched>
; __device__ __forceinline__ void gemm_phase(LAS unsigned char* lds, const Gemm g, const Sched& S, const Epi& E) {
;     ...
;         const bool has_next = S.next(ui + 1, nxt);
;         const char* nA = has_next ? (const char*)g.A + (size_t)nxt.pm * tstep : cA; const char* nB = has_next ? (const char*)g.Bt + (size_t)nxt.pn * tstep : cB;
;         for (int t = 0; t < nt; t += 2) {
;             const bool last = (t == nt - 2);
;             const char* a1 = cA + (size_t)(t + 1) * kstep;
;             const char* a2 = last ? nA : cA + (size_t)(t + 2) * kstep; const char* b2 = last ? nB : cB + (size_t)(t + 2) * kstep;
;             const char* a3 = a2 + kstep; const char* b3 = b2 + kstep;
;             PG8_LDB(B0, 0, 0); PG8_SCHED; PG8_LDA(At, 0, 0); PG8_STAGE(PG8_SA(1, 1), a1 + hstep, voffA);
;             PG8_WAIT_L(8); PG8_BAR; PG8_WAIT_L(0); PG8_MMA(0, 0, At, B0); PG8_BAR; PG8_SCHED;
;             PG8_LDB(B1, 0, 1); PG8_STAGE(PG8_SB(0, 0), b2, voffB);
;             PG8_BAR; PG8_WAIT_L(0); PG8_MMA(0, 1, At, B1); PG8_BAR;
;             PG8_LDA(At, 0, 1); PG8_STAGE(PG8_SA(0, 0), a2, voffA);
;             PG8_BAR; PG8_WAIT_L(0); PG8_MMA(1, 0, At, B0); PG8_BAR; PG8_SCHED;
.LBB0_825:
	s_ashr_i32 s7, s6, 31
	v_cmp_lt_i64_e32 vcc, s[8:9], v[156:157]
	s_lshl_b64 s[8:9], s[6:7], 20
	s_add_u32 s8, s22, s8
	s_addc_u32 s9, s23, s9
	s_and_b64 s[10:11], vcc, exec
	s_cselect_b32 s7, s9, s15
	s_cselect_b32 s39, s8, s14
	s_ashr_i32 s5, s4, 31
	s_lshl_b64 s[10:11], s[4:5], 20
	s_add_u32 s10, s50, s10
	s_addc_u32 s11, s51, s11
	s_and_b64 s[18:19], vcc, exec
	s_cselect_b32 s5, s11, s17
	s_cselect_b32 s40, s10, s16
	s_add_u32 s14, s14, 0x80080
	s_addc_u32 s15, s15, 0
	s_add_u32 s41, s16, 0x100
	s_addc_u32 s42, s17, 0
	s_mov_b32 s43, -2
	ds_read_b128 v[128:131], v168
	ds_read_b128 v[132:135], v168 offset:1024
	ds_read_b128 v[136:139], v168 offset:2048
	ds_read_b128 v[140:143], v168 offset:3072
	s_add_u32 s16, s14, 0xfff80080
	s_addc_u32 s17, s15, -1
	s_cmp_eq_u32 s43, 28
	s_cselect_b32 s19, s7, s17
	s_cselect_b32 s18, s39, s16
	s_cselect_b32 s17, s5, s42
	s_cselect_b32 s16, s40, s41
	s_add_i32 m0, s13, 0xc000
	ds_read_b128 v[162:165], v169
	ds_read_b128 v[172:175], v169 offset:1024
	ds_read_b128 v[176:179], v169 offset:2048
	ds_read_b128 v[180:183], v169 offset:3072
	ds_read_b128 v[184:187], v169 offset:4096
	ds_read_b128 v[188:191], v169 offset:5120
	ds_read_b128 v[192:195], v169 offset:6144
	ds_read_b128 v[196:199], v169 offset:7168
	global_load_lds_dwordx4 v152, s[14:15]
	s_add_i32 m0, s13, 0xe000
	s_nop 0
	global_load_lds_dwordx4 v154, s[14:15]
	s_waitcnt lgkmcnt(8)
	s_waitcnt vmcnt(8)
	s_waitcnt lgkmcnt(0)
	s_setprio 1
	s_barrier
	v_mfma_f32_16x16x32_bf16 v[124:127], v[128:131], v[162:165], 0
	v_mfma_f32_16x16x32_bf16 v[120:123], v[136:139], v[162:165], 0
	v_mfma_f32_16x16x32_bf16 v[116:119], v[128:131], v[176:179], 0
	v_mfma_f32_16x16x32_bf16 v[112:115], v[136:139], v[176:179], 0
	v_mfma_f32_16x16x32_bf16 v[108:111], v[128:131], v[184:187], 0
	v_mfma_f32_16x16x32_bf16 v[100:103], v[136:139], v[184:187], 0
	v_mfma_f32_16x16x32_bf16 v[76:79], v[128:131], v[192:195], 0
	v_mfma_f32_16x16x32_bf16 v[72:75], v[136:139], v[192:195], 0
	v_mfma_f32_16x16x32_bf16 v[124:127], v[132:135], v[172:175], v[124:127]
	v_mfma_f32_16x16x32_bf16 v[120:123], v[140:143], v[172:175], v[120:123]
	v_mfma_f32_16x16x32_bf16 v[116:119], v[132:135], v[180:183], v[116:119]
	v_mfma_f32_16x16x32_bf16 v[112:115], v[140:143], v[180:183], v[112:115]
	v_mfma_f32_16x16x32_bf16 v[108:111], v[132:135], v[188:191], v[108:111]
	v_mfma_f32_16x16x32_bf16 v[100:103], v[140:143], v[188:191], v[100:103]
	v_mfma_f32_16x16x32_bf16 v[76:79], v[132:135], v[196:199], v[76:79]
	v_mfma_f32_16x16x32_bf16 v[72:75], v[140:143], v[196:199], v[72:75]
	s_barrier
	s_setprio 0
	s_add_i32 s44, s35, s24
	s_mov_b32 m0, s44
	ds_read_b128 v[202:205], v170
	ds_read_b128 v[206:209], v170 offset:1024
	ds_read_b128 v[210:213], v170 offset:2048
	ds_read_b128 v[214:217], v170 offset:3072
	global_load_lds_dwordx4 v146, s[16:17]
	s_add_i32 m0, s44, 0x2000
	s_nop 0
	global_load_lds_dwordx4 v150, s[16:17]
	s_waitcnt vmcnt(8)
	s_waitcnt lgkmcnt(0)
	s_setprio 1
	s_barrier
	v_mfma_f32_16x16x32_bf16 v[104:107], v[202:205], v[162:165], 0
	v_mfma_f32_16x16x32_bf16 v[96:99], v[210:213], v[162:165], 0
	v_mfma_f32_16x16x32_bf16 v[92:95], v[202:205], v[176:179], 0
	v_mfma_f32_16x16x32_bf16 v[88:91], v[210:213], v[176:179], 0
	v_mfma_f32_16x16x32_bf16 v[84:87], v[202:205], v[184:187], 0
	v_mfma_f32_16x16x32_bf16 v[80:83], v[210:213], v[184:187], 0
	v_mfma_f32_16x16x32_bf16 v[68:71], v[202:205], v[192:195], 0
	v_mfma_f32_16x16x32_bf16 v[64:67], v[210:213], v[192:195], 0
	v_mfma_f32_16x16x32_bf16 v[104:107], v[206:209], v[172:175], v[104:107]
	v_mfma_f32_16x16x32_bf16 v[96:99], v[214:217], v[172:175], v[96:99]
	v_mfma_f32_16x16x32_bf16 v[92:95], v[206:209], v[180:183], v[92:95]
	v_mfma_f32_16x16x32_bf16 v[88:91], v[214:217], v[180:183], v[88:91]
	v_mfma_f32_16x16x32_bf16 v[84:87], v[206:209], v[188:191], v[84:87]
	v_mfma_f32_16x16x32_bf16 v[80:83], v[214:217], v[188:191], v[80:83]
	v_mfma_f32_16x16x32_bf16 v[68:71], v[206:209], v[196:199], v[68:71]
	v_mfma_f32_16x16x32_bf16 v[64:67], v[214:217], v[196:199], v[64:67]
	s_mov_b32 m0, s13
	v_lshl_add_u64 v[222:223], s[18:19], 0, v[144:145]
	s_barrier
	s_setprio 0
	ds_read_b128 v[162:165], v169 offset:16384
	ds_read_b128 v[172:175], v169 offset:17408
	ds_read_b128 v[176:179], v169 offset:18432
	ds_read_b128 v[180:183], v169 offset:19456
	ds_read_b128 v[184:187], v169 offset:20480
	ds_read_b128 v[188:191], v169 offset:21504
	ds_read_b128 v[192:195], v169 offset:22528
	ds_read_b128 v[196:199], v169 offset:23552
	global_load_lds_dwordx4 v144, s[18:19]
	v_lshl_add_u64 v[224:225], s[18:19], 0, v[148:149]
	s_mov_b32 m0, s25
	s_nop 0
	global_load_lds_dwordx4 v148, s[18:19]
	s_waitcnt lgkmcnt(0)
	s_setprio 1
	s_barrier
	v_mfma_f32_16x16x32_bf16 v[60:63], v[128:131], v[162:165], 0
	v_mfma_f32_16x16x32_bf16 v[56:59], v[136:139], v[162:165], 0
	v_mfma_f32_16x16x32_bf16 v[48:51], v[128:131], v[176:179], 0
	v_mfma_f32_16x16x32_bf16 v[40:43], v[136:139], v[176:179], 0
	v_mfma_f32_16x16x32_bf16 v[32:35], v[128:131], v[184:187], 0
	v_mfma_f32_16x16x32_bf16 v[24:27], v[136:139], v[184:187], 0
	v_mfma_f32_16x16x32_bf16 v[16:19], v[128:131], v[192:195], 0
	v_mfma_f32_16x16x32_bf16 v[8:11], v[136:139], v[192:195], 0
	v_mfma_f32_16x16x32_bf16 v[60:63], v[132:135], v[172:175], v[60:63]
	v_mfma_f32_16x16x32_bf16 v[56:59], v[140:143], v[172:175], v[56:59]
	v_mfma_f32_16x16x32_bf16 v[48:51], v[132:135], v[180:183], v[48:51]
	v_mfma_f32_16x16x32_bf16 v[40:43], v[140:143], v[180:183], v[40:43]
	v_mfma_f32_16x16x32_bf16 v[32:35], v[132:135], v[188:191], v[32:35]
	v_mfma_f32_16x16x32_bf16 v[24:27], v[140:143], v[188:191], v[24:27]
	v_mfma_f32_16x16x32_bf16 v[16:19], v[132:135], v[196:199], v[16:19]
	v_mfma_f32_16x16x32_bf16 v[8:11], v[140:143], v[196:199], v[8:11]
	s_barrier
; #define PG8_STAGE(bufoff, gbase, voff) do { _Pragma("unroll") for (int _i = 0; _i < 2; ++_i) \
;         __builtin_amdgcn_global_load_lds((const unsigned*)((const char*)(gbase) + (voff)[_i]), (LAS unsigned*)(lds + (bufoff) + ldsw + _i * 8192), 16, 0, 0); } while (0)
; #define PG8_LDA(dst, b, h) do { _Pragma("unroll") for (int m = 0; m < 4; ++m) _Pragma("unroll") for (int k = 0; k < 2; ++k) dst[m][k] = *(const LAS bf16x8*)(lds + PG8_SA(b, h) + aoff + m * 2048 + k * 1024); } while (0)
; #define PG8_LDB(dst, b, h) do { _Pragma("unroll") for (int n = 0; n < 2; ++n) _Pragma("unroll") for (int k = 0; k < 2; ++k) dst[n][k] = *(const LAS bf16x8*)(lds + PG8_SB(b, h) + boff + n * 2048 + k * 1024); } while (0)
; #define PG8_MMA(ai, bj, At, Bt) do { __builtin_amdgcn_s_setprio(1); _Pragma("unroll") for (int m = 0; m < 4; ++m) _Pragma("unroll") for (int n = 0; n < 2; ++n) _Pragma("unroll") for (int k = 0; k < 2; ++k) \
;         acc[ai][bj][m][n] = __builtin_amdgcn_mfma_f32_16x16x32_bf16(Bt[n][k], At[m][k], acc[ai][bj][m][n], 0, 0, 0); __builtin_amdgcn_s_setprio(0); } while (0)
; #define PG8_WAIT_V(n) asm volatile("s_waitcnt vmcnt(" #n ")" ::: "memory")
; #define PG8_WAIT_L(n) asm volatile("s_waitcnt lgkmcnt(" #n ")" ::: "memory")
; #define PG8_BAR __builtin_amdgcn_s_barrier()
; #define PG8_SCHED __builtin_amdgcn_sched_barrier(0)
; template <class Epi, class Sched>
; __device__ __forceinline__ void gemm_phase(LAS unsigned char* lds, const Gemm g, const Sched& S, const Epi& E) {
;     ...
;             PG8_STAGE(PG8_SB(0, 1), b2 + hstep, voffB);
;             PG8_WAIT_V(6); PG8_BAR; PG8_MMA(1, 1, At, B1); PG8_BAR;
;             PG8_LDB(B0, 1, 0); PG8_SCHED; PG8_LDA(At, 1, 0); PG8_STAGE(PG8_SA(0, 1), a2 + hstep, voffA);
;             PG8_WAIT_L(8); PG8_BAR; PG8_WAIT_L(0); PG8_MMA(0, 0, At, B0); PG8_BAR; PG8_SCHED;
;             PG8_LDB(B1, 1, 1); PG8_STAGE(PG8_SB(1, 0), b3, voffB);
;             PG8_BAR; PG8_WAIT_L(0); PG8_MMA(0, 1, At, B1); PG8_BAR;
;             PG8_LDA(At, 1, 1); PG8_STAGE(PG8_SA(1, 0), a3, voffA);
	s_setprio 0
	s_add_u32 s44, s16, 0x80000
	s_addc_u32 s45, s17, 0
	s_add_i32 s46, s36, s24
	s_mov_b32 m0, s46
	s_nop 0
	global_load_lds_dwordx4 v146, s[44:45]
	s_add_i32 m0, s46, 0x2000
	s_nop 0
	global_load_lds_dwordx4 v150, s[44:45]
	s_add_u32 s18, s18, 0x80000
	s_addc_u32 s19, s19, 0
	s_mov_b32 m0, s26
	s_nop 0
	global_load_lds_dwordx4 v144, s[18:19]
	s_mov_b32 m0, s27
	s_nop 0
	global_load_lds_dwordx4 v148, s[18:19]
	s_waitcnt vmcnt(10)
	s_setprio 1
	s_barrier
	v_mfma_f32_16x16x32_bf16 v[52:55], v[202:205], v[162:165], 0
	v_mfma_f32_16x16x32_bf16 v[44:47], v[210:213], v[162:165], 0
	v_mfma_f32_16x16x32_bf16 v[36:39], v[202:205], v[176:179], 0
	v_mfma_f32_16x16x32_bf16 v[28:31], v[210:213], v[176:179], 0
	v_mfma_f32_16x16x32_bf16 v[20:23], v[202:205], v[184:187], 0
	v_mfma_f32_16x16x32_bf16 v[12:15], v[210:213], v[184:187], 0
	v_mfma_f32_16x16x32_bf16 v[4:7], v[202:205], v[192:195], 0
	v_mfma_f32_16x16x32_bf16 v[0:3], v[210:213], v[192:195], 0
	v_mfma_f32_16x16x32_bf16 v[52:55], v[206:209], v[172:175], v[52:55]
	v_mfma_f32_16x16x32_bf16 v[44:47], v[214:217], v[172:175], v[44:47]
	v_mfma_f32_16x16x32_bf16 v[36:39], v[206:209], v[180:183], v[36:39]
	v_mfma_f32_16x16x32_bf16 v[28:31], v[214:217], v[180:183], v[28:31]
	v_mfma_f32_16x16x32_bf16 v[20:23], v[206:209], v[188:191], v[20:23]
	v_mfma_f32_16x16x32_bf16 v[12:15], v[214:217], v[188:191], v[12:15]
	v_mfma_f32_16x16x32_bf16 v[4:7], v[206:209], v[196:199], v[4:7]
	v_mfma_f32_16x16x32_bf16 v[0:3], v[214:217], v[196:199], v[0:3]
	s_add_i32 s44, 0, 0x18000
	v_add_u32_e32 v140, s44, v167
	s_barrier
	s_setprio 0
	ds_read_b128 v[128:131], v140
	ds_read_b128 v[132:135], v140 offset:1024
	ds_read_b128 v[136:139], v140 offset:2048
	ds_read_b128 v[140:143], v140 offset:3072
	ds_read_b128 v[162:165], v169 offset:32768
	ds_read_b128 v[172:175], v169 offset:33792
	ds_read_b128 v[176:179], v169 offset:34816
	ds_read_b128 v[180:183], v169 offset:35840
	ds_read_b128 v[184:187], v169 offset:36864
	ds_read_b128 v[188:191], v169 offset:37888
	ds_read_b128 v[192:195], v169 offset:38912
	ds_read_b128 v[196:199], v169 offset:39936
	s_waitcnt lgkmcnt(8)
	s_waitcnt vmcnt(8)
	s_waitcnt lgkmcnt(0)
	s_setprio 1
	s_barrier
	v_mfma_f32_16x16x32_bf16 v[124:127], v[128:131], v[162:165], v[124:127]
	v_mfma_f32_16x16x32_bf16 v[120:123], v[136:139], v[162:165], v[120:123]
	v_mfma_f32_16x16x32_bf16 v[116:119], v[128:131], v[176:179], v[116:119]
	v_mfma_f32_16x16x32_bf16 v[112:115], v[136:139], v[176:179], v[112:115]
	v_mfma_f32_16x16x32_bf16 v[108:111], v[128:131], v[184:187], v[108:111]
	v_mfma_f32_16x16x32_bf16 v[100:103], v[136:139], v[184:187], v[100:103]
	v_mfma_f32_16x16x32_bf16 v[76:79], v[128:131], v[192:195], v[76:79]
	v_mfma_f32_16x16x32_bf16 v[72:75], v[136:139], v[192:195], v[72:75]
	v_mfma_f32_16x16x32_bf16 v[124:127], v[132:135], v[172:175], v[124:127]
	v_mfma_f32_16x16x32_bf16 v[120:123], v[140:143], v[172:175], v[120:123]
	v_mfma_f32_16x16x32_bf16 v[116:119], v[132:135], v[180:183], v[116:119]
	v_mfma_f32_16x16x32_bf16 v[112:115], v[140:143], v[180:183], v[112:115]
	v_mfma_f32_16x16x32_bf16 v[108:111], v[132:135], v[188:191], v[108:111]
	v_mfma_f32_16x16x32_bf16 v[100:103], v[140:143], v[188:191], v[100:103]
	v_mfma_f32_16x16x32_bf16 v[76:79], v[132:135], v[196:199], v[76:79]
	v_mfma_f32_16x16x32_bf16 v[72:75], v[140:143], v[196:199], v[72:75]
	s_barrier
	s_setprio 0
	s_add_i32 s18, 0, 0x1c000
	s_add_i32 s19, s44, s24
	v_add_u32_e32 v160, s18, v167
	s_add_u32 s0, s16, 0x80
	s_addc_u32 s1, s17, 0
	s_mov_b32 m0, s19
	ds_read_b128 v[202:205], v160
	ds_read_b128 v[206:209], v160 offset:1024
	ds_read_b128 v[210:213], v160 offset:2048
	ds_read_b128 v[214:217], v160 offset:3072
	global_load_lds_dwordx4 v146, s[0:1]
	s_add_i32 m0, s19, 0x2000
	s_nop 0
	global_load_lds_dwordx4 v150, s[0:1]
	s_waitcnt vmcnt(8)
	s_waitcnt lgkmcnt(0)
	s_setprio 1
	s_barrier
	v_mfma_f32_16x16x32_bf16 v[104:107], v[202:205], v[162:165], v[104:107]
	v_mfma_f32_16x16x32_bf16 v[96:99], v[210:213], v[162:165], v[96:99]
	v_mfma_f32_16x16x32_bf16 v[92:95], v[202:205], v[176:179], v[92:95]
	v_mfma_f32_16x16x32_bf16 v[88:91], v[210:213], v[176:179], v[88:91]
	v_mfma_f32_16x16x32_bf16 v[84:87], v[202:205], v[184:187], v[84:87]
	v_mfma_f32_16x16x32_bf16 v[80:83], v[210:213], v[184:187], v[80:83]
	v_mfma_f32_16x16x32_bf16 v[68:71], v[202:205], v[192:195], v[68:71]
	v_mfma_f32_16x16x32_bf16 v[64:67], v[210:213], v[192:195], v[64:67]
	v_mfma_f32_16x16x32_bf16 v[104:107], v[206:209], v[172:175], v[104:107]
	v_mfma_f32_16x16x32_bf16 v[96:99], v[214:217], v[172:175], v[96:99]
	v_mfma_f32_16x16x32_bf16 v[92:95], v[206:209], v[180:183], v[92:95]
	v_mfma_f32_16x16x32_bf16 v[88:91], v[214:217], v[180:183], v[88:91]
	v_mfma_f32_16x16x32_bf16 v[84:87], v[206:209], v[188:191], v[84:87]
	v_mfma_f32_16x16x32_bf16 v[80:83], v[214:217], v[188:191], v[80:83]
	v_mfma_f32_16x16x32_bf16 v[68:71], v[206:209], v[196:199], v[68:71]
	v_mfma_f32_16x16x32_bf16 v[64:67], v[214:217], v[196:199], v[64:67]
	s_mov_b32 m0, s31
	s_mov_b64 s[0:1], 0x80
	v_lshl_add_u64 v[218:219], v[222:223], 0, s[0:1]
	s_barrier
	s_setprio 0
	ds_read_b128 v[162:165], v169 offset:49152
	ds_read_b128 v[172:175], v169 offset:50176
	ds_read_b128 v[176:179], v169 offset:51200
	ds_read_b128 v[180:183], v169 offset:52224
	ds_read_b128 v[184:187], v169 offset:53248
	ds_read_b128 v[188:191], v169 offset:54272
	ds_read_b128 v[192:195], v169 offset:55296
	ds_read_b128 v[196:199], v169 offset:56320
	global_load_lds_dwordx4 v[218:219], off
	v_lshl_add_u64 v[218:219], v[224:225], 0, s[0:1]
	s_mov_b32 m0, s33
	s_nop 0
	global_load_lds_dwordx4 v[218:219], off
	s_waitcnt lgkmcnt(0)
	s_setprio 1
	s_barrier
; #define PG8_STAGE(bufoff, gbase, voff) do { _Pragma("unroll") for (int _i = 0; _i < 2; ++_i) \
;         __builtin_amdgcn_global_load_lds((const unsigned*)((const char*)(gbase) + (voff)[_i]), (LAS unsigned*)(lds + (bufoff) + ldsw + _i * 8192), 16, 0, 0); } while (0)
; #define PG8_LDA(dst, b, h) do { _Pragma("unroll") for (int m = 0; m < 4; ++m) _Pragma("unroll") for (int k = 0; k < 2; ++k) dst[m][k] = *(const LAS bf16x8*)(lds + PG8_SA(b, h) + aoff + m * 2048 + k * 1024); } while (0)
; #define PG8_LDB(dst, b, h) do { _Pragma("unroll") for (int n = 0; n < 2; ++n) _Pragma("unroll") for (int k = 0; k < 2; ++k) dst[n][k] = *(const LAS bf16x8*)(lds + PG8_SB(b, h) + boff + n * 2048 + k * 1024); } while (0)
; #define PG8_WAIT_V(n) asm volatile("s_waitcnt vmcnt(" #n ")" ::: "memory")
; #define PG8_WAIT_L(n) asm volatile("s_waitcnt lgkmcnt(" #n ")" ::: "memory")
; #define PG8_BAR __builtin_amdgcn_s_barrier()
; #define PG8_SCHED __builtin_amdgcn_sched_barrier(0)
; template <class Epi, class Sched>
; __device__ __forceinline__ void gemm_phase(LAS unsigned char* lds, const Gemm g, const Sched& S, const Epi& E) {
;     ...
;             PG8_LDB(B0, 0, 0); PG8_SCHED; PG8_LDA(At, 0, 0); PG8_STAGE(PG8_SA(1, 1), a1 + hstep, voffA);
;             PG8_WAIT_L(8); PG8_BAR; PG8_WAIT_L(0); PG8_MMA(0, 0, At, B0); PG8_BAR; PG8_SCHED;
;             PG8_LDB(B1, 0, 1); PG8_STAGE(PG8_SB(0, 0), b2, voffB);
;             PG8_BAR; PG8_WAIT_L(0); PG8_MMA(0, 1, At, B1); PG8_BAR;
;             PG8_LDA(At, 0, 1); PG8_STAGE(PG8_SA(0, 0), a2, voffA);
;             PG8_BAR; PG8_WAIT_L(0); PG8_MMA(1, 0, At, B0); PG8_BAR; PG8_SCHED;
;             PG8_STAGE(PG8_SB(0, 1), b2 + hstep, voffB);
;             PG8_WAIT_V(6); PG8_BAR; PG8_MMA(1, 1, At, B1); PG8_BAR;
;             PG8_LDB(B0, 1, 0); PG8_SCHED; PG8_LDA(At, 1, 0); PG8_STAGE(PG8_SA(0, 1), a2 + hstep, voffA);
;             PG8_WAIT_L(8); PG8_BAR; PG8_WAIT_L(0); PG8_MMA(0, 0, At, B0); PG8_BAR; PG8_SCHED;
;             PG8_LDB(B1, 1, 1); PG8_STAGE(PG8_SB(1, 0), b3, voffB);
;             PG8_BAR; PG8_WAIT_L(0); PG8_MMA(0, 1, At, B1); PG8_BAR;
;             PG8_LDA(At, 1, 1); PG8_STAGE(PG8_SA(1, 0), a3, voffA);
;             PG8_BAR; PG8_WAIT_L(0); PG8_MMA(1, 0, At, B0); PG8_BAR; PG8_SCHED;
;             PG8_STAGE(PG8_SB(1, 1), b3 + hstep, voffB);
;             PG8_WAIT_V(6); PG8_BAR; PG8_MMA(1, 1, At, B1); PG8_BAR;
	v_mfma_f32_16x16x32_bf16 v[60:63], v[128:131], v[162:165], v[60:63]
	v_mfma_f32_16x16x32_bf16 v[56:59], v[136:139], v[162:165], v[56:59]
	v_mfma_f32_16x16x32_bf16 v[48:51], v[128:131], v[176:179], v[48:51]
	v_mfma_f32_16x16x32_bf16 v[40:43], v[136:139], v[176:179], v[40:43]
	v_mfma_f32_16x16x32_bf16 v[32:35], v[128:131], v[184:187], v[32:35]
	v_mfma_f32_16x16x32_bf16 v[24:27], v[136:139], v[184:187], v[24:27]
	v_mfma_f32_16x16x32_bf16 v[16:19], v[128:131], v[192:195], v[16:19]
	v_mfma_f32_16x16x32_bf16 v[8:11], v[136:139], v[192:195], v[8:11]
	v_mfma_f32_16x16x32_bf16 v[60:63], v[132:135], v[172:175], v[60:63]
	v_mfma_f32_16x16x32_bf16 v[56:59], v[140:143], v[172:175], v[56:59]
	v_mfma_f32_16x16x32_bf16 v[48:51], v[132:135], v[180:183], v[48:51]
	v_mfma_f32_16x16x32_bf16 v[40:43], v[140:143], v[180:183], v[40:43]
	v_mfma_f32_16x16x32_bf16 v[32:35], v[132:135], v[188:191], v[32:35]
	v_mfma_f32_16x16x32_bf16 v[24:27], v[140:143], v[188:191], v[24:27]
	v_mfma_f32_16x16x32_bf16 v[16:19], v[132:135], v[196:199], v[16:19]
	v_mfma_f32_16x16x32_bf16 v[8:11], v[140:143], v[196:199], v[8:11]
	s_barrier
	s_setprio 0
	s_add_u32 s16, s16, 0x80080
	s_addc_u32 s17, s17, 0
	s_add_i32 s18, s18, s24
	s_mov_b32 m0, s18
	s_nop 0
	global_load_lds_dwordx4 v146, s[16:17]
	s_add_i32 m0, s18, 0x2000
	s_nop 0
	global_load_lds_dwordx4 v150, s[16:17]
	s_waitcnt vmcnt(8)
	s_setprio 1
	s_barrier
	v_mfma_f32_16x16x32_bf16 v[52:55], v[202:205], v[162:165], v[52:55]
	v_mfma_f32_16x16x32_bf16 v[44:47], v[210:213], v[162:165], v[44:47]
	v_mfma_f32_16x16x32_bf16 v[36:39], v[202:205], v[176:179], v[36:39]
	v_mfma_f32_16x16x32_bf16 v[28:31], v[210:213], v[176:179], v[28:31]
	v_mfma_f32_16x16x32_bf16 v[20:23], v[202:205], v[184:187], v[20:23]
	v_mfma_f32_16x16x32_bf16 v[12:15], v[210:213], v[184:187], v[12:15]
	v_mfma_f32_16x16x32_bf16 v[4:7], v[202:205], v[192:195], v[4:7]
	v_mfma_f32_16x16x32_bf16 v[0:3], v[210:213], v[192:195], v[0:3]
	v_mfma_f32_16x16x32_bf16 v[52:55], v[206:209], v[172:175], v[52:55]
	v_mfma_f32_16x16x32_bf16 v[44:47], v[214:217], v[172:175], v[44:47]
	v_mfma_f32_16x16x32_bf16 v[36:39], v[206:209], v[180:183], v[36:39]
	v_mfma_f32_16x16x32_bf16 v[28:31], v[214:217], v[180:183], v[28:31]
	v_mfma_f32_16x16x32_bf16 v[20:23], v[206:209], v[188:191], v[20:23]
	v_mfma_f32_16x16x32_bf16 v[12:15], v[214:217], v[188:191], v[12:15]
	v_mfma_f32_16x16x32_bf16 v[4:7], v[206:209], v[196:199], v[4:7]
	v_mfma_f32_16x16x32_bf16 v[0:3], v[214:217], v[196:199], v[0:3]
	s_add_i32 s43, s43, 2
	s_add_u32 s14, s14, 0x100
	s_addc_u32 s15, s15, 0
	s_add_u32 s41, s41, 0x100
	s_addc_u32 s42, s42, 0
	s_cmp_gt_u32 s43, 29
	s_barrier
	s_setprio 0
.LBB0_826:
	ds_read_b128 v[128:131], v168
	ds_read_b128 v[132:135], v168 offset:1024
	ds_read_b128 v[136:139], v168 offset:2048
	ds_read_b128 v[140:143], v168 offset:3072
	s_add_u32 s16, s14, 0xfff80080
	s_addc_u32 s17, s15, -1
	s_cmp_eq_u32 s43, 28
	s_cselect_b32 s19, s7, s17
	s_cselect_b32 s18, s39, s16
	s_cselect_b32 s17, s5, s42
	s_cselect_b32 s16, s40, s41
	s_add_i32 m0, s13, 0xc000
	ds_read_b128 v[162:165], v169
	ds_read_b128 v[172:175], v169 offset:1024
	ds_read_b128 v[176:179], v169 offset:2048
	ds_read_b128 v[180:183], v169 offset:3072
	ds_read_b128 v[184:187], v169 offset:4096
	ds_read_b128 v[188:191], v169 offset:5120
	ds_read_b128 v[192:195], v169 offset:6144
	ds_read_b128 v[196:199], v169 offset:7168
	global_load_lds_dwordx4 v152, s[14:15]
	s_add_i32 m0, s13, 0xe000
	s_nop 0
	global_load_lds_dwordx4 v154, s[14:15]
	s_waitcnt lgkmcnt(8)
	s_waitcnt vmcnt(8)
	s_waitcnt lgkmcnt(0)
	s_setprio 1
	s_barrier
	v_mfma_f32_16x16x32_bf16 v[124:127], v[128:131], v[162:165], v[124:127]
	v_mfma_f32_16x16x32_bf16 v[120:123], v[136:139], v[162:165], v[120:123]
	v_mfma_f32_16x16x32_bf16 v[116:119], v[128:131], v[176:179], v[116:119]
	v_mfma_f32_16x16x32_bf16 v[112:115], v[136:139], v[176:179], v[112:115]
	v_mfma_f32_16x16x32_bf16 v[108:111], v[128:131], v[184:187], v[108:111]
	v_mfma_f32_16x16x32_bf16 v[100:103], v[136:139], v[184:187], v[100:103]
	v_mfma_f32_16x16x32_bf16 v[76:79], v[128:131], v[192:195], v[76:79]
	v_mfma_f32_16x16x32_bf16 v[72:75], v[136:139], v[192:195], v[72:75]
	v_mfma_f32_16x16x32_bf16 v[124:127], v[132:135], v[172:175], v[124:127]
	v_mfma_f32_16x16x32_bf16 v[120:123], v[140:143], v[172:175], v[120:123]
	v_mfma_f32_16x16x32_bf16 v[116:119], v[132:135], v[180:183], v[116:119]
	v_mfma_f32_16x16x32_bf16 v[112:115], v[140:143], v[180:183], v[112:115]
	v_mfma_f32_16x16x32_bf16 v[108:111], v[132:135], v[188:191], v[108:111]
	v_mfma_f32_16x16x32_bf16 v[100:103], v[140:143], v[188:191], v[100:103]
	v_mfma_f32_16x16x32_bf16 v[76:79], v[132:135], v[196:199], v[76:79]
	v_mfma_f32_16x16x32_bf16 v[72:75], v[140:143], v[196:199], v[72:75]
	s_barrier
	s_setprio 0
	s_add_i32 s44, s35, s24
	s_mov_b32 m0, s44
	ds_read_b128 v[202:205], v170
	ds_read_b128 v[206:209], v170 offset:1024
	ds_read_b128 v[210:213], v170 offset:2048
	ds_read_b128 v[214:217], v170 offset:3072
	global_load_lds_dwordx4 v146, s[16:17]
	s_add_i32 m0, s44, 0x2000
	s_nop 0
	global_load_lds_dwordx4 v150, s[16:17]
	s_waitcnt vmcnt(8)
	s_waitcnt lgkmcnt(0)
	s_setprio 1
	s_barrier
; #define PG8_STAGE(bufoff, gbase, voff) do { _Pragma("unroll") for (int _i = 0; _i < 2; ++_i) \
;         __builtin_amdgcn_global_load_lds((const unsigned*)((const char*)(gbase) + (voff)[_i]), (LAS unsigned*)(lds + (bufoff) + ldsw + _i * 8192), 16, 0, 0); } while (0)
; #define PG8_LDA(dst, b, h) do { _Pragma("unroll") for (int m = 0; m < 4; ++m) _Pragma("unroll") for (int k = 0; k < 2; ++k) dst[m][k] = *(const LAS bf16x8*)(lds + PG8_SA(b, h) + aoff + m * 2048 + k * 1024); } while (0)
; #define PG8_LDB(dst, b, h) do { _Pragma("unroll") for (int n = 0; n < 2; ++n) _Pragma("unroll") for (int k = 0; k < 2; ++k) dst[n][k] = *(const LAS bf16x8*)(lds + PG8_SB(b, h) + boff + n * 2048 + k * 1024); } while (0)
; #define PG8_MMA(ai, bj, At, Bt) do { __builtin_amdgcn_s_setprio(1); _Pragma("unroll") for (int m = 0; m < 4; ++m) _Pragma("unroll") for (int n = 0; n < 2; ++n) _Pragma("unroll") for (int k = 0; k < 2; ++k) \
;         acc[ai][bj][m][n] = __builtin_amdgcn_mfma_f32_16x16x32_bf16(Bt[n][k], At[m][k], acc[ai][bj][m][n], 0, 0, 0); __builtin_amdgcn_s_setprio(0); } while (0)
; #define PG8_WAIT_V(n) asm volatile("s_waitcnt vmcnt(" #n ")" ::: "memory")
; #define PG8_WAIT_L(n) asm volatile("s_waitcnt lgkmcnt(" #n ")" ::: "memory")
; #define PG8_BAR __builtin_amdgcn_s_barrier()
; #define PG8_SCHED __builtin_amdgcn_sched_barrier(0)
; template <class Epi, class Sched>
; __device__ __forceinline__ void gemm_phase(LAS unsigned char* lds, const Gemm g, const Sched& S, const Epi& E) {
;     ...
;             PG8_BAR; PG8_WAIT_L(0); PG8_MMA(0, 1, At, B1); PG8_BAR;
;             PG8_LDA(At, 0, 1); PG8_STAGE(PG8_SA(0, 0), a2, voffA);
;             PG8_BAR; PG8_WAIT_L(0); PG8_MMA(1, 0, At, B0); PG8_BAR; PG8_SCHED;
;             PG8_STAGE(PG8_SB(0, 1), b2 + hstep, voffB);
;             PG8_WAIT_V(6); PG8_BAR; PG8_MMA(1, 1, At, B1); PG8_BAR;
;             PG8_LDB(B0, 1, 0); PG8_SCHED; PG8_LDA(At, 1, 0); PG8_STAGE(PG8_SA(0, 1), a2 + hstep, voffA);
;             PG8_WAIT_L(8); PG8_BAR; PG8_WAIT_L(0); PG8_MMA(0, 0, At, B0); PG8_BAR; PG8_SCHED;
	v_mfma_f32_16x16x32_bf16 v[104:107], v[202:205], v[162:165], v[104:107]
	v_mfma_f32_16x16x32_bf16 v[96:99], v[210:213], v[162:165], v[96:99]
	v_mfma_f32_16x16x32_bf16 v[92:95], v[202:205], v[176:179], v[92:95]
	v_mfma_f32_16x16x32_bf16 v[88:91], v[210:213], v[176:179], v[88:91]
	v_mfma_f32_16x16x32_bf16 v[84:87], v[202:205], v[184:187], v[84:87]
	v_mfma_f32_16x16x32_bf16 v[80:83], v[210:213], v[184:187], v[80:83]
	v_mfma_f32_16x16x32_bf16 v[68:71], v[202:205], v[192:195], v[68:71]
	v_mfma_f32_16x16x32_bf16 v[64:67], v[210:213], v[192:195], v[64:67]
	v_mfma_f32_16x16x32_bf16 v[104:107], v[206:209], v[172:175], v[104:107]
	v_mfma_f32_16x16x32_bf16 v[96:99], v[214:217], v[172:175], v[96:99]
	v_mfma_f32_16x16x32_bf16 v[92:95], v[206:209], v[180:183], v[92:95]
	v_mfma_f32_16x16x32_bf16 v[88:91], v[214:217], v[180:183], v[88:91]
	v_mfma_f32_16x16x32_bf16 v[84:87], v[206:209], v[188:191], v[84:87]
	v_mfma_f32_16x16x32_bf16 v[80:83], v[214:217], v[188:191], v[80:83]
	v_mfma_f32_16x16x32_bf16 v[68:71], v[206:209], v[196:199], v[68:71]
	v_mfma_f32_16x16x32_bf16 v[64:67], v[214:217], v[196:199], v[64:67]
	s_mov_b32 m0, s13
	v_lshl_add_u64 v[222:223], s[18:19], 0, v[144:145]
	s_barrier
	s_setprio 0
	ds_read_b128 v[162:165], v169 offset:16384
	ds_read_b128 v[172:175], v169 offset:17408
	ds_read_b128 v[176:179], v169 offset:18432
	ds_read_b128 v[180:183], v169 offset:19456
	ds_read_b128 v[184:187], v169 offset:20480
	ds_read_b128 v[188:191], v169 offset:21504
	ds_read_b128 v[192:195], v169 offset:22528
	ds_read_b128 v[196:199], v169 offset:23552
	global_load_lds_dwordx4 v144, s[18:19]
	v_lshl_add_u64 v[224:225], s[18:19], 0, v[148:149]
	s_mov_b32 m0, s25
	s_nop 0
	global_load_lds_dwordx4 v148, s[18:19]
	s_waitcnt lgkmcnt(0)
	s_setprio 1
	s_barrier
	v_mfma_f32_16x16x32_bf16 v[60:63], v[128:131], v[162:165], v[60:63]
	v_mfma_f32_16x16x32_bf16 v[56:59], v[136:139], v[162:165], v[56:59]
	v_mfma_f32_16x16x32_bf16 v[48:51], v[128:131], v[176:179], v[48:51]
	v_mfma_f32_16x16x32_bf16 v[40:43], v[136:139], v[176:179], v[40:43]
	v_mfma_f32_16x16x32_bf16 v[32:35], v[128:131], v[184:187], v[32:35]
	v_mfma_f32_16x16x32_bf16 v[24:27], v[136:139], v[184:187], v[24:27]
	v_mfma_f32_16x16x32_bf16 v[16:19], v[128:131], v[192:195], v[16:19]
	v_mfma_f32_16x16x32_bf16 v[8:11], v[136:139], v[192:195], v[8:11]
	v_mfma_f32_16x16x32_bf16 v[60:63], v[132:135], v[172:175], v[60:63]
	v_mfma_f32_16x16x32_bf16 v[56:59], v[140:143], v[172:175], v[56:59]
	v_mfma_f32_16x16x32_bf16 v[48:51], v[132:135], v[180:183], v[48:51]
	v_mfma_f32_16x16x32_bf16 v[40:43], v[140:143], v[180:183], v[40:43]
	v_mfma_f32_16x16x32_bf16 v[32:35], v[132:135], v[188:191], v[32:35]
	v_mfma_f32_16x16x32_bf16 v[24:27], v[140:143], v[188:191], v[24:27]
	v_mfma_f32_16x16x32_bf16 v[16:19], v[132:135], v[196:199], v[16:19]
	v_mfma_f32_16x16x32_bf16 v[8:11], v[140:143], v[196:199], v[8:11]
	s_barrier
	s_setprio 0
	s_add_u32 s44, s16, 0x80000
	s_addc_u32 s45, s17, 0
	s_add_i32 s46, s36, s24
	s_mov_b32 m0, s46
	s_nop 0
	global_load_lds_dwordx4 v146, s[44:45]
	s_add_i32 m0, s46, 0x2000
	s_nop 0
	global_load_lds_dwordx4 v150, s[44:45]
	s_add_u32 s18, s18, 0x80000
	s_addc_u32 s19, s19, 0
	s_mov_b32 m0, s26
	s_nop 0
	global_load_lds_dwordx4 v144, s[18:19]
	s_mov_b32 m0, s27
	s_nop 0
	global_load_lds_dwordx4 v148, s[18:19]
	s_waitcnt vmcnt(10)
	s_setprio 1
	s_barrier
	v_mfma_f32_16x16x32_bf16 v[52:55], v[202:205], v[162:165], v[52:55]
	v_mfma_f32_16x16x32_bf16 v[44:47], v[210:213], v[162:165], v[44:47]
	v_mfma_f32_16x16x32_bf16 v[36:39], v[202:205], v[176:179], v[36:39]
	v_mfma_f32_16x16x32_bf16 v[28:31], v[210:213], v[176:179], v[28:31]
	v_mfma_f32_16x16x32_bf16 v[20:23], v[202:205], v[184:187], v[20:23]
	v_mfma_f32_16x16x32_bf16 v[12:15], v[210:213], v[184:187], v[12:15]
	v_mfma_f32_16x16x32_bf16 v[4:7], v[202:205], v[192:195], v[4:7]
	v_mfma_f32_16x16x32_bf16 v[0:3], v[210:213], v[192:195], v[0:3]
	v_mfma_f32_16x16x32_bf16 v[52:55], v[206:209], v[172:175], v[52:55]
	v_mfma_f32_16x16x32_bf16 v[44:47], v[214:217], v[172:175], v[44:47]
	v_mfma_f32_16x16x32_bf16 v[36:39], v[206:209], v[180:183], v[36:39]
	v_mfma_f32_16x16x32_bf16 v[28:31], v[214:217], v[180:183], v[28:31]
	v_mfma_f32_16x16x32_bf16 v[20:23], v[206:209], v[188:191], v[20:23]
	v_mfma_f32_16x16x32_bf16 v[12:15], v[214:217], v[188:191], v[12:15]
	v_mfma_f32_16x16x32_bf16 v[4:7], v[206:209], v[196:199], v[4:7]
	v_mfma_f32_16x16x32_bf16 v[0:3], v[214:217], v[196:199], v[0:3]
	s_add_i32 s44, 0, 0x18000
	v_add_u32_e32 v140, s44, v167
	s_barrier
	s_setprio 0
	ds_read_b128 v[128:131], v140
	ds_read_b128 v[132:135], v140 offset:1024
	ds_read_b128 v[136:139], v140 offset:2048
	ds_read_b128 v[140:143], v140 offset:3072
	ds_read_b128 v[162:165], v169 offset:32768
	ds_read_b128 v[172:175], v169 offset:33792
	ds_read_b128 v[176:179], v169 offset:34816
	ds_read_b128 v[180:183], v169 offset:35840
	ds_read_b128 v[184:187], v169 offset:36864
	ds_read_b128 v[188:191], v169 offset:37888
	ds_read_b128 v[192:195], v169 offset:38912
	ds_read_b128 v[196:199], v169 offset:39936
	s_waitcnt lgkmcnt(8)
	s_waitcnt vmcnt(8)
	s_waitcnt lgkmcnt(0)
	s_setprio 1
	s_barrier
; #define PG8_STAGE(bufoff, gbase, voff) do { _Pragma("unroll") for (int _i = 0; _i < 2; ++_i) \
;         __builtin_amdgcn_global_load_lds((const unsigned*)((const char*)(gbase) + (voff)[_i]), (LAS unsigned*)(lds + (bufoff) + ldsw + _i * 8192), 16, 0, 0); } while (0)
; #define PG8_LDA(dst, b, h) do { _Pragma("unroll") for (int m = 0; m < 4; ++m) _Pragma("unroll") for (int k = 0; k < 2; ++k) dst[m][k] = *(const LAS bf16x8*)(lds + PG8_SA(b, h) + aoff + m * 2048 + k * 1024); } while (0)
; #define PG8_LDB(dst, b, h) do { _Pragma("unroll") for (int n = 0; n < 2; ++n) _Pragma("unroll") for (int k = 0; k < 2; ++k) dst[n][k] = *(const LAS bf16x8*)(lds + PG8_SB(b, h) + boff + n * 2048 + k * 1024); } while (0)
; #define PG8_MMA(ai, bj, At, Bt) do { __builtin_amdgcn_s_setprio(1); _Pragma("unroll") for (int m = 0; m < 4; ++m) _Pragma("unroll") for (int n = 0; n < 2; ++n) _Pragma("unroll") for (int k = 0; k < 2; ++k) \
;         acc[ai][bj][m][n] = __builtin_amdgcn_mfma_f32_16x16x32_bf16(Bt[n][k], At[m][k], acc[ai][bj][m][n], 0, 0, 0); __builtin_amdgcn_s_setprio(0); } while (0)
; #define PG8_WAIT_V(n) asm volatile("s_waitcnt vmcnt(" #n ")" ::: "memory")
; #define PG8_WAIT_L(n) asm volatile("s_waitcnt lgkmcnt(" #n ")" ::: "memory")
; #define PG8_BAR __builtin_amdgcn_s_barrier()
; #define PG8_SCHED __builtin_amdgcn_sched_barrier(0)
; template <class Epi, class Sched>
; __device__ __forceinline__ void gemm_phase(LAS unsigned char* lds, const Gemm g, const Sched& S, const Epi& E) {
;     ...
;             PG8_WAIT_L(8); PG8_BAR; PG8_WAIT_L(0); PG8_MMA(0, 0, At, B0); PG8_BAR; PG8_SCHED;
;             PG8_LDB(B1, 1, 1); PG8_STAGE(PG8_SB(1, 0), b3, voffB);
;             PG8_BAR; PG8_WAIT_L(0); PG8_MMA(0, 1, At, B1); PG8_BAR;
;             PG8_LDA(At, 1, 1); PG8_STAGE(PG8_SA(1, 0), a3, voffA);
;             PG8_BAR; PG8_WAIT_L(0); PG8_MMA(1, 0, At, B0); PG8_BAR; PG8_SCHED;
;             PG8_STAGE(PG8_SB(1, 1), b3 + hstep, voffB);
;             PG8_WAIT_V(6); PG8_BAR; PG8_MMA(1, 1, At, B1); PG8_BAR;
	v_mfma_f32_16x16x32_bf16 v[124:127], v[128:131], v[162:165], v[124:127]
	v_mfma_f32_16x16x32_bf16 v[120:123], v[136:139], v[162:165], v[120:123]
	v_mfma_f32_16x16x32_bf16 v[116:119], v[128:131], v[176:179], v[116:119]
	v_mfma_f32_16x16x32_bf16 v[112:115], v[136:139], v[176:179], v[112:115]
	v_mfma_f32_16x16x32_bf16 v[108:111], v[128:131], v[184:187], v[108:111]
	v_mfma_f32_16x16x32_bf16 v[100:103], v[136:139], v[184:187], v[100:103]
	v_mfma_f32_16x16x32_bf16 v[76:79], v[128:131], v[192:195], v[76:79]
	v_mfma_f32_16x16x32_bf16 v[72:75], v[136:139], v[192:195], v[72:75]
	v_mfma_f32_16x16x32_bf16 v[124:127], v[132:135], v[172:175], v[124:127]
	v_mfma_f32_16x16x32_bf16 v[120:123], v[140:143], v[172:175], v[120:123]
	v_mfma_f32_16x16x32_bf16 v[116:119], v[132:135], v[180:183], v[116:119]
	v_mfma_f32_16x16x32_bf16 v[112:115], v[140:143], v[180:183], v[112:115]
	v_mfma_f32_16x16x32_bf16 v[108:111], v[132:135], v[188:191], v[108:111]
	v_mfma_f32_16x16x32_bf16 v[100:103], v[140:143], v[188:191], v[100:103]
	v_mfma_f32_16x16x32_bf16 v[76:79], v[132:135], v[196:199], v[76:79]
	v_mfma_f32_16x16x32_bf16 v[72:75], v[140:143], v[196:199], v[72:75]
	s_barrier
	s_setprio 0
	s_add_i32 s18, 0, 0x1c000
	s_add_i32 s19, s44, s24
	v_add_u32_e32 v160, s18, v167
	s_add_u32 s0, s16, 0x80
	s_addc_u32 s1, s17, 0
	s_mov_b32 m0, s19
	ds_read_b128 v[202:205], v160
	ds_read_b128 v[206:209], v160 offset:1024
	ds_read_b128 v[210:213], v160 offset:2048
	ds_read_b128 v[214:217], v160 offset:3072
	global_load_lds_dwordx4 v146, s[0:1]
	s_add_i32 m0, s19, 0x2000
	s_nop 0
	global_load_lds_dwordx4 v150, s[0:1]
	s_waitcnt vmcnt(8)
	s_waitcnt lgkmcnt(0)
	s_setprio 1
	s_barrier
	v_mfma_f32_16x16x32_bf16 v[104:107], v[202:205], v[162:165], v[104:107]
	v_mfma_f32_16x16x32_bf16 v[96:99], v[210:213], v[162:165], v[96:99]
	v_mfma_f32_16x16x32_bf16 v[92:95], v[202:205], v[176:179], v[92:95]
	v_mfma_f32_16x16x32_bf16 v[88:91], v[210:213], v[176:179], v[88:91]
	v_mfma_f32_16x16x32_bf16 v[84:87], v[202:205], v[184:187], v[84:87]
	v_mfma_f32_16x16x32_bf16 v[80:83], v[210:213], v[184:187], v[80:83]
	v_mfma_f32_16x16x32_bf16 v[68:71], v[202:205], v[192:195], v[68:71]
	v_mfma_f32_16x16x32_bf16 v[64:67], v[210:213], v[192:195], v[64:67]
	v_mfma_f32_16x16x32_bf16 v[104:107], v[206:209], v[172:175], v[104:107]
	v_mfma_f32_16x16x32_bf16 v[96:99], v[214:217], v[172:175], v[96:99]
	v_mfma_f32_16x16x32_bf16 v[92:95], v[206:209], v[180:183], v[92:95]
	v_mfma_f32_16x16x32_bf16 v[88:91], v[214:217], v[180:183], v[88:91]
	v_mfma_f32_16x16x32_bf16 v[84:87], v[206:209], v[188:191], v[84:87]
	v_mfma_f32_16x16x32_bf16 v[80:83], v[214:217], v[188:191], v[80:83]
	v_mfma_f32_16x16x32_bf16 v[68:71], v[206:209], v[196:199], v[68:71]
	v_mfma_f32_16x16x32_bf16 v[64:67], v[214:217], v[196:199], v[64:67]
	s_mov_b32 m0, s31
	s_mov_b64 s[0:1], 0x80
	v_lshl_add_u64 v[218:219], v[222:223], 0, s[0:1]
	s_barrier
	s_setprio 0
	ds_read_b128 v[162:165], v169 offset:49152
	ds_read_b128 v[172:175], v169 offset:50176
	ds_read_b128 v[176:179], v169 offset:51200
	ds_read_b128 v[180:183], v169 offset:52224
	ds_read_b128 v[184:187], v169 offset:53248
	ds_read_b128 v[188:191], v169 offset:54272
	ds_read_b128 v[192:195], v169 offset:55296
	ds_read_b128 v[196:199], v169 offset:56320
	global_load_lds_dwordx4 v[218:219], off
	v_lshl_add_u64 v[218:219], v[224:225], 0, s[0:1]
	s_mov_b32 m0, s33
	s_nop 0
	global_load_lds_dwordx4 v[218:219], off
	s_waitcnt lgkmcnt(0)
	s_setprio 1
	s_barrier
	v_mfma_f32_16x16x32_bf16 v[60:63], v[128:131], v[162:165], v[60:63]
	v_mfma_f32_16x16x32_bf16 v[56:59], v[136:139], v[162:165], v[56:59]
	v_mfma_f32_16x16x32_bf16 v[48:51], v[128:131], v[176:179], v[48:51]
	v_mfma_f32_16x16x32_bf16 v[40:43], v[136:139], v[176:179], v[40:43]
	v_mfma_f32_16x16x32_bf16 v[32:35], v[128:131], v[184:187], v[32:35]
	v_mfma_f32_16x16x32_bf16 v[24:27], v[136:139], v[184:187], v[24:27]
	v_mfma_f32_16x16x32_bf16 v[16:19], v[128:131], v[192:195], v[16:19]
	v_mfma_f32_16x16x32_bf16 v[8:11], v[136:139], v[192:195], v[8:11]
	v_mfma_f32_16x16x32_bf16 v[60:63], v[132:135], v[172:175], v[60:63]
	v_mfma_f32_16x16x32_bf16 v[56:59], v[140:143], v[172:175], v[56:59]
	v_mfma_f32_16x16x32_bf16 v[48:51], v[132:135], v[180:183], v[48:51]
	v_mfma_f32_16x16x32_bf16 v[40:43], v[140:143], v[180:183], v[40:43]
	v_mfma_f32_16x16x32_bf16 v[32:35], v[132:135], v[188:191], v[32:35]
	v_mfma_f32_16x16x32_bf16 v[24:27], v[140:143], v[188:191], v[24:27]
	v_mfma_f32_16x16x32_bf16 v[16:19], v[132:135], v[196:199], v[16:19]
	v_mfma_f32_16x16x32_bf16 v[8:11], v[140:143], v[196:199], v[8:11]
	s_barrier
	s_setprio 0
	s_add_u32 s16, s16, 0x80080
	s_addc_u32 s17, s17, 0
	s_add_i32 s18, s18, s24
	s_mov_b32 m0, s18
	s_nop 0
	global_load_lds_dwordx4 v146, s[16:17]
	s_add_i32 m0, s18, 0x2000
	s_nop 0
	global_load_lds_dwordx4 v150, s[16:17]
	s_waitcnt vmcnt(8)
	s_setprio 1
	s_barrier
	v_mfma_f32_16x16x32_bf16 v[52:55], v[202:205], v[162:165], v[52:55]
	v_mfma_f32_16x16x32_bf16 v[44:47], v[210:213], v[162:165], v[44:47]
	v_mfma_f32_16x16x32_bf16 v[36:39], v[202:205], v[176:179], v[36:39]
	v_mfma_f32_16x16x32_bf16 v[28:31], v[210:213], v[176:179], v[28:31]
	v_mfma_f32_16x16x32_bf16 v[20:23], v[202:205], v[184:187], v[20:23]
	v_mfma_f32_16x16x32_bf16 v[12:15], v[210:213], v[184:187], v[12:15]
	v_mfma_f32_16x16x32_bf16 v[4:7], v[202:205], v[192:195], v[4:7]
	v_mfma_f32_16x16x32_bf16 v[0:3], v[210:213], v[192:195], v[0:3]
	v_mfma_f32_16x16x32_bf16 v[52:55], v[206:209], v[172:175], v[52:55]
	v_mfma_f32_16x16x32_bf16 v[44:47], v[214:217], v[172:175], v[44:47]
	v_mfma_f32_16x16x32_bf16 v[36:39], v[206:209], v[180:183], v[36:39]
	v_mfma_f32_16x16x32_bf16 v[28:31], v[214:217], v[180:183], v[28:31]
	v_mfma_f32_16x16x32_bf16 v[20:23], v[206:209], v[188:191], v[20:23]
	v_mfma_f32_16x16x32_bf16 v[12:15], v[214:217], v[188:191], v[12:15]
	v_mfma_f32_16x16x32_bf16 v[4:7], v[206:209], v[196:199], v[4:7]
	v_mfma_f32_16x16x32_bf16 v[0:3], v[214:217], v[196:199], v[0:3]
	s_add_i32 s43, s43, 2
	s_add_u32 s14, s14, 0x100
	s_addc_u32 s15, s15, 0
	s_add_u32 s41, s41, 0x100
	s_addc_u32 s42, s42, 0
	s_cmp_gt_u32 s43, 29
	s_barrier
; __device__ __forceinline__ unsigned cvt_pk_bf16(float lo, float hi) { unsigned r; asm volatile("v_cvt_pk_bf16_f32 %0, %1, %2" : "=v"(r) : "v"(lo), "v"(hi)); return r; }
;     __device__ __forceinline__ void operator()(const AccT& acc, const Unit& u, int wr, int wc, int fr, int fq) const {
;     ...
;         const int row0 = u.pm * 256 + wr * 64 + fr; const int b = u.pn >> 1, ch0 = (u.pn & 1) * 256 + wc * 32 + 8 * fq;
;         const float sg = (fr & 1) ? -1.0f : 1.0f;
;         f32x4 yh[2][2];
; #pragma unroll
;         for (int bj = 0; bj < 2; ++bj)
; #pragma unroll
;             for (int n = 0; n < 2; ++n) yh[bj][n] = *(const f32x4*)(YCH + b * 512 + ch0 + bj * 128 + 4 * n) * sg;
; #pragma unroll
;         for (int ai = 0; ai < 2; ++ai)
; #pragma unroll
;             for (int m = 0; m < 4; ++m) {
;                 const int k = row0 + ai * 128 + m * 16;
; #pragma unroll
;                 for (int bj = 0; bj < 2; ++bj) {
;                     const f32x4 v0 = acc[ai][bj][m][0] + yh[bj][0], v1 = acc[ai][bj][m][1] + yh[bj][1];
;                     u32x4 w; w.x = cvt_pk_bf16(v0[0], v0[1]); w.y = cvt_pk_bf16(v0[2], v0[3]); w.z = cvt_pk_bf16(v1[0], v1[1]); w.w = cvt_pk_bf16(v1[2], v1[3]);
;                     *(u32x4*)(CAT + (size_t)(b * 2048 + k) * CATW + 1024 + ch0 + bj * 128) = w;
;                 }
	s_setprio 0
	s_cbranch_scc0 .LBB0_826
	s_ashr_i32 s5, s38, 1
	s_lshl_b32 s7, s38, 8
	s_lshl_b32 s14, s5, 9
	s_and_b32 s7, s7, 0x100
	s_ashr_i32 s15, s14, 31
	v_mov_b32_e32 v171, v161
	v_mov_b32_e32 v128, v166
	s_or_b32 s7, s7, s30
	s_lshl_b64 s[14:15], s[14:15], 2
	s_add_u32 s14, s48, s14
	v_lshl_add_u32 v164, v128, 3, s7
	s_addc_u32 s15, s49, s15
	v_ashrrev_i32_e32 v165, 31, v164
	v_lshl_add_u64 v[128:129], v[164:165], 2, s[14:15]
	global_load_dwordx4 v[140:143], v[128:129], off
	global_load_dwordx4 v[136:139], v[128:129], off offset:16
	global_load_dwordx4 v[132:135], v[128:129], off offset:512
	s_nop 0
	global_load_dwordx4 v[128:131], v[128:129], off offset:528
	s_lshl_b32 s7, s12, 8
	s_lshl_b32 s5, s5, 11
	s_add_i32 s7, s7, s29
	v_and_b32_e32 v160, 1, v171
	s_add_i32 s7, s7, s5
	v_mov_b64_e32 v[162:163], s[96:97]
	v_cmp_eq_u32_e32 vcc, 0, v160
	v_add_u32_e32 v171, s7, v171
	v_lshlrev_b64 v[164:165], 1, v[164:165]
	v_cndmask_b32_e64 v160, -1.0, 1.0, vcc
	v_mad_i64_i32 v[172:173], s[14:15], v171, s37, v[162:163]
	v_add_u32_e32 v174, 16, v171
	v_lshl_add_u64 v[172:173], v[172:173], 0, v[164:165]
	v_mad_i64_i32 v[174:175], s[14:15], v174, s37, v[162:163]
	v_add_u32_e32 v176, 32, v171
	v_lshl_add_u64 v[174:175], v[174:175], 0, v[164:165]
	v_mad_i64_i32 v[176:177], s[14:15], v176, s37, v[162:163]
	v_lshl_add_u64 v[176:177], v[176:177], 0, v[164:165]
	v_add_u32_e32 v182, 48, v171
	s_and_b64 vcc, exec, s[2:3]
	s_mov_b32 s38, s4
	s_mov_b32 s12, s6
	s_mov_b64 s[16:17], s[10:11]
	s_waitcnt vmcnt(0)
	v_pk_fma_f32 v[126:127], v[142:143], v[160:161], v[126:127] op_sel_hi:[1,0,1]
	v_pk_fma_f32 v[124:125], v[140:141], v[160:161], v[124:125] op_sel_hi:[1,0,1]
	v_pk_fma_f32 v[122:123], v[138:139], v[160:161], v[122:123] op_sel_hi:[1,0,1]
	v_pk_fma_f32 v[180:181], v[128:129], v[160:161], v[80:81] op_sel_hi:[1,0,1]
	v_cvt_pk_bf16_f32 v80, v124, v125
	v_cvt_pk_bf16_f32 v81, v126, v127
	v_pk_fma_f32 v[120:121], v[136:137], v[160:161], v[120:121] op_sel_hi:[1,0,1]
	v_pk_fma_f32 v[106:107], v[134:135], v[160:161], v[106:107] op_sel_hi:[1,0,1]
	v_pk_fma_f32 v[104:105], v[132:133], v[160:161], v[104:105] op_sel_hi:[1,0,1]
	v_pk_fma_f32 v[178:179], v[130:131], v[160:161], v[82:83] op_sel_hi:[1,0,1]
	v_cvt_pk_bf16_f32 v82, v120, v121
	v_cvt_pk_bf16_f32 v83, v122, v123
	global_store_dwordx4 v[172:173], v[80:83], off offset:2048
	v_pk_fma_f32 v[98:99], v[130:131], v[160:161], v[98:99] op_sel_hi:[1,0,1]
	v_pk_fma_f32 v[96:97], v[128:129], v[160:161], v[96:97] op_sel_hi:[1,0,1]
	v_cvt_pk_bf16_f32 v80, v104, v105
	v_cvt_pk_bf16_f32 v81, v106, v107
	v_pk_fma_f32 v[118:119], v[142:143], v[160:161], v[118:119] op_sel_hi:[1,0,1]
	v_pk_fma_f32 v[116:117], v[140:141], v[160:161], v[116:117] op_sel_hi:[1,0,1]
	v_cvt_pk_bf16_f32 v82, v96, v97
	v_cvt_pk_bf16_f32 v83, v98, v99
	global_store_dwordx4 v[172:173], v[80:83], off offset:2304
	v_pk_fma_f32 v[114:115], v[138:139], v[160:161], v[114:115] op_sel_hi:[1,0,1]
	v_pk_fma_f32 v[112:113], v[136:137], v[160:161], v[112:113] op_sel_hi:[1,0,1]
	v_cvt_pk_bf16_f32 v80, v116, v117
	v_cvt_pk_bf16_f32 v81, v118, v119
	v_pk_fma_f32 v[94:95], v[134:135], v[160:161], v[94:95] op_sel_hi:[1,0,1]
	v_pk_fma_f32 v[92:93], v[132:133], v[160:161], v[92:93] op_sel_hi:[1,0,1]
	v_cvt_pk_bf16_f32 v82, v112, v113
	v_cvt_pk_bf16_f32 v83, v114, v115
	global_store_dwordx4 v[174:175], v[80:83], off offset:2048
	v_pk_fma_f32 v[90:91], v[130:131], v[160:161], v[90:91] op_sel_hi:[1,0,1]
	v_pk_fma_f32 v[88:89], v[128:129], v[160:161], v[88:89] op_sel_hi:[1,0,1]
	v_cvt_pk_bf16_f32 v80, v92, v93
	v_cvt_pk_bf16_f32 v81, v94, v95
	v_pk_fma_f32 v[110:111], v[142:143], v[160:161], v[110:111] op_sel_hi:[1,0,1]
	v_pk_fma_f32 v[108:109], v[140:141], v[160:161], v[108:109] op_sel_hi:[1,0,1]
	v_cvt_pk_bf16_f32 v82, v88, v89
	v_cvt_pk_bf16_f32 v83, v90, v91
	global_store_dwordx4 v[174:175], v[80:83], off offset:2304
	v_pk_fma_f32 v[102:103], v[138:139], v[160:161], v[102:103] op_sel_hi:[1,0,1]
	v_pk_fma_f32 v[100:101], v[136:137], v[160:161], v[100:101] op_sel_hi:[1,0,1]
	v_cvt_pk_bf16_f32 v80, v108, v109
	v_cvt_pk_bf16_f32 v81, v110, v111
	v_pk_fma_f32 v[86:87], v[134:135], v[160:161], v[86:87] op_sel_hi:[1,0,1]
	v_pk_fma_f32 v[84:85], v[132:133], v[160:161], v[84:85] op_sel_hi:[1,0,1]
	v_cvt_pk_bf16_f32 v82, v100, v101
	v_cvt_pk_bf16_f32 v83, v102, v103
	global_store_dwordx4 v[176:177], v[80:83], off offset:2048
	v_pk_fma_f32 v[76:77], v[140:141], v[160:161], v[76:77] op_sel_hi:[1,0,1]
	v_pk_fma_f32 v[78:79], v[142:143], v[160:161], v[78:79] op_sel_hi:[1,0,1]
	v_cvt_pk_bf16_f32 v80, v84, v85
	v_cvt_pk_bf16_f32 v81, v86, v87
	v_cvt_pk_bf16_f32 v82, v180, v181
	v_cvt_pk_bf16_f32 v83, v178, v179
	global_store_dwordx4 v[176:177], v[80:83], off offset:2304
	v_pk_fma_f32 v[70:71], v[134:135], v[160:161], v[70:71] op_sel_hi:[1,0,1]
	v_pk_fma_f32 v[68:69], v[132:133], v[160:161], v[68:69] op_sel_hi:[1,0,1]
	v_pk_fma_f32 v[80:81], v[138:139], v[160:161], v[74:75] op_sel_hi:[1,0,1]
	v_pk_fma_f32 v[74:75], v[136:137], v[160:161], v[72:73] op_sel_hi:[1,0,1]
	v_cvt_pk_bf16_f32 v72, v76, v77
	v_mad_i64_i32 v[76:77], s[14:15], v182, s37, v[162:163]
	v_cvt_pk_bf16_f32 v73, v78, v79
; __device__ __forceinline__ unsigned cvt_pk_bf16(float lo, float hi) { unsigned r; asm volatile("v_cvt_pk_bf16_f32 %0, %1, %2" : "=v"(r) : "v"(lo), "v"(hi)); return r; }
; #define PG8_WAIT_V(n) asm volatile("s_waitcnt vmcnt(" #n ")" ::: "memory")
; #define PG8_BAR __builtin_amdgcn_s_barrier()
; template <class Epi, class Sched>
; __device__ __forceinline__ void gemm_phase(LAS unsigned char* lds, const Gemm g, const Sched& S, const Epi& E) {
;     ...
;         E(acc, cur, wr, wc, fr, fq);
;         if (!has_next) break;
; #pragma unroll
;         for (int a = 0; a < 2; ++a)
; #pragma unroll
;             for (int b = 0; b < 2; ++b)
; #pragma unroll
;                 for (int m = 0; m < 4; ++m)
; #pragma unroll
;                     for (int n = 0; n < 2; ++n) acc[a][b][m][n] = (f32x4){0.f, 0.f, 0.f, 0.f};
;         cur = nxt; cA = nA; cB = nB; ++ui;
;     }
;     PG8_WAIT_V(0);
;     if (wr == 0) PG8_BAR;
;     PG8_BAR;
;     __device__ __forceinline__ void operator()(const AccT& acc, const Unit& u, int wr, int wc, int fr, int fq) const {
;     ...
;                 const int k = row0 + ai * 128 + m * 16;
; #pragma unroll
;                 for (int bj = 0; bj < 2; ++bj) {
;                     const f32x4 v0 = acc[ai][bj][m][0] + yh[bj][0], v1 = acc[ai][bj][m][1] + yh[bj][1];
;                     u32x4 w; w.x = cvt_pk_bf16(v0[0], v0[1]); w.y = cvt_pk_bf16(v0[2], v0[3]); w.z = cvt_pk_bf16(v1[0], v1[1]); w.w = cvt_pk_bf16(v1[2], v1[3]);
;                     *(u32x4*)(CAT + (size_t)(b * 2048 + k) * CATW + 1024 + ch0 + bj * 128) = w;
;                 }
	v_lshl_add_u64 v[76:77], v[76:77], 0, v[164:165]
	v_cvt_pk_bf16_f32 v74, v74, v75
	v_cvt_pk_bf16_f32 v75, v80, v81
	global_store_dwordx4 v[76:77], v[72:75], off offset:2048
	v_pk_fma_f32 v[60:61], v[140:141], v[160:161], v[60:61] op_sel_hi:[1,0,1]
	v_pk_fma_f32 v[62:63], v[142:143], v[160:161], v[62:63] op_sel_hi:[1,0,1]
	v_pk_fma_f32 v[72:73], v[130:131], v[160:161], v[66:67] op_sel_hi:[1,0,1]
	v_pk_fma_f32 v[66:67], v[128:129], v[160:161], v[64:65] op_sel_hi:[1,0,1]
	v_cvt_pk_bf16_f32 v64, v68, v69
	v_cvt_pk_bf16_f32 v65, v70, v71
	v_pk_fma_f32 v[54:55], v[134:135], v[160:161], v[54:55] op_sel_hi:[1,0,1]
	v_cvt_pk_bf16_f32 v66, v66, v67
	v_cvt_pk_bf16_f32 v67, v72, v73
	global_store_dwordx4 v[76:77], v[64:67], off offset:2304
	v_pk_fma_f32 v[52:53], v[132:133], v[160:161], v[52:53] op_sel_hi:[1,0,1]
	v_pk_fma_f32 v[38:39], v[134:135], v[160:161], v[38:39] op_sel_hi:[1,0,1]
	v_add_u32_e32 v66, 0x80, v171
	v_pk_fma_f32 v[64:65], v[138:139], v[160:161], v[58:59] op_sel_hi:[1,0,1]
	v_pk_fma_f32 v[58:59], v[136:137], v[160:161], v[56:57] op_sel_hi:[1,0,1]
	v_cvt_pk_bf16_f32 v56, v60, v61
	v_mad_i64_i32 v[60:61], s[14:15], v66, s37, v[162:163]
	v_cvt_pk_bf16_f32 v57, v62, v63
	v_lshl_add_u64 v[60:61], v[60:61], 0, v[164:165]
	v_cvt_pk_bf16_f32 v58, v58, v59
	v_cvt_pk_bf16_f32 v59, v64, v65
	global_store_dwordx4 v[60:61], v[56:59], off offset:2048
	v_pk_fma_f32 v[36:37], v[132:133], v[160:161], v[36:37] op_sel_hi:[1,0,1]
	v_pk_fma_f32 v[22:23], v[134:135], v[160:161], v[22:23] op_sel_hi:[1,0,1]
	v_pk_fma_f32 v[56:57], v[130:131], v[160:161], v[46:47] op_sel_hi:[1,0,1]
	v_pk_fma_f32 v[46:47], v[128:129], v[160:161], v[44:45] op_sel_hi:[1,0,1]
	v_cvt_pk_bf16_f32 v44, v52, v53
	v_cvt_pk_bf16_f32 v45, v54, v55
	v_add_u32_e32 v52, 0x90, v171
	v_cvt_pk_bf16_f32 v46, v46, v47
	v_cvt_pk_bf16_f32 v47, v56, v57
	global_store_dwordx4 v[60:61], v[44:47], off offset:2304
	v_pk_fma_f32 v[20:21], v[132:133], v[160:161], v[20:21] op_sel_hi:[1,0,1]
	v_pk_fma_f32 v[6:7], v[134:135], v[160:161], v[6:7] op_sel_hi:[1,0,1]
	v_pk_fma_f32 v[44:45], v[142:143], v[160:161], v[50:51] op_sel_hi:[1,0,1]
	v_pk_fma_f32 v[46:47], v[140:141], v[160:161], v[48:49] op_sel_hi:[1,0,1]
	v_pk_fma_f32 v[48:49], v[138:139], v[160:161], v[42:43] op_sel_hi:[1,0,1]
	v_pk_fma_f32 v[42:43], v[136:137], v[160:161], v[40:41] op_sel_hi:[1,0,1]
	v_cvt_pk_bf16_f32 v40, v46, v47
	v_cvt_pk_bf16_f32 v41, v44, v45
	v_mad_i64_i32 v[44:45], s[14:15], v52, s37, v[162:163]
	v_lshl_add_u64 v[44:45], v[44:45], 0, v[164:165]
	v_cvt_pk_bf16_f32 v42, v42, v43
	v_cvt_pk_bf16_f32 v43, v48, v49
	global_store_dwordx4 v[44:45], v[40:43], off offset:2048
	v_pk_fma_f32 v[4:5], v[132:133], v[160:161], v[4:5] op_sel_hi:[1,0,1]
	s_nop 0
	v_pk_fma_f32 v[40:41], v[130:131], v[160:161], v[30:31] op_sel_hi:[1,0,1]
	v_pk_fma_f32 v[30:31], v[128:129], v[160:161], v[28:29] op_sel_hi:[1,0,1]
	v_cvt_pk_bf16_f32 v28, v36, v37
	v_cvt_pk_bf16_f32 v29, v38, v39
	v_add_u32_e32 v36, 0xa0, v171
	v_cvt_pk_bf16_f32 v30, v30, v31
	v_cvt_pk_bf16_f32 v31, v40, v41
	global_store_dwordx4 v[44:45], v[28:31], off offset:2304
	s_nop 1
	v_pk_fma_f32 v[28:29], v[142:143], v[160:161], v[34:35] op_sel_hi:[1,0,1]
	v_pk_fma_f32 v[30:31], v[140:141], v[160:161], v[32:33] op_sel_hi:[1,0,1]
	v_pk_fma_f32 v[32:33], v[138:139], v[160:161], v[26:27] op_sel_hi:[1,0,1]
	v_pk_fma_f32 v[26:27], v[136:137], v[160:161], v[24:25] op_sel_hi:[1,0,1]
	v_cvt_pk_bf16_f32 v24, v30, v31
	v_cvt_pk_bf16_f32 v25, v28, v29
	v_mad_i64_i32 v[28:29], s[14:15], v36, s37, v[162:163]
	v_lshl_add_u64 v[28:29], v[28:29], 0, v[164:165]
	v_cvt_pk_bf16_f32 v26, v26, v27
	v_cvt_pk_bf16_f32 v27, v32, v33
	global_store_dwordx4 v[28:29], v[24:27], off offset:2048
	s_nop 1
	v_pk_fma_f32 v[24:25], v[130:131], v[160:161], v[14:15] op_sel_hi:[1,0,1]
	v_pk_fma_f32 v[14:15], v[128:129], v[160:161], v[12:13] op_sel_hi:[1,0,1]
	v_cvt_pk_bf16_f32 v12, v20, v21
	v_cvt_pk_bf16_f32 v13, v22, v23
	v_add_u32_e32 v20, 0xb0, v171
	v_cvt_pk_bf16_f32 v14, v14, v15
	v_cvt_pk_bf16_f32 v15, v24, v25
	global_store_dwordx4 v[28:29], v[12:15], off offset:2304
	s_nop 1
	v_pk_fma_f32 v[12:13], v[142:143], v[160:161], v[18:19] op_sel_hi:[1,0,1]
	v_pk_fma_f32 v[14:15], v[140:141], v[160:161], v[16:17] op_sel_hi:[1,0,1]
	v_pk_fma_f32 v[16:17], v[138:139], v[160:161], v[10:11] op_sel_hi:[1,0,1]
	v_pk_fma_f32 v[10:11], v[136:137], v[160:161], v[8:9] op_sel_hi:[1,0,1]
	v_cvt_pk_bf16_f32 v8, v14, v15
	v_cvt_pk_bf16_f32 v9, v12, v13
	v_mad_i64_i32 v[12:13], s[14:15], v20, s37, v[162:163]
	v_lshl_add_u64 v[12:13], v[12:13], 0, v[164:165]
	v_cvt_pk_bf16_f32 v10, v10, v11
	v_cvt_pk_bf16_f32 v11, v16, v17
	global_store_dwordx4 v[12:13], v[8:11], off offset:2048
	s_mov_b64 s[14:15], s[8:9]
	s_nop 0
	v_pk_fma_f32 v[8:9], v[130:131], v[160:161], v[2:3] op_sel_hi:[1,0,1]
	v_pk_fma_f32 v[2:3], v[128:129], v[160:161], v[0:1] op_sel_hi:[1,0,1]
	v_cvt_pk_bf16_f32 v0, v4, v5
	v_cvt_pk_bf16_f32 v1, v6, v7
	s_nop 0
	v_cvt_pk_bf16_f32 v2, v2, v3
	v_cvt_pk_bf16_f32 v3, v8, v9
	global_store_dwordx4 v[12:13], v[0:3], off offset:2304
	s_cbranch_vccz .LBB0_819
	s_waitcnt vmcnt(0)
	s_cmpk_gt_u32 s20, 0xff
	s_cbranch_scc1 .LBB0_830
	s_barrier

; #define PG8_STAGE(bufoff, gbase, voff) do { _Pragma("unroll") for (int _i = 0; _i < 2; ++_i) \
;         __builtin_amdgcn_global_load_lds((const unsigned*)((const char*)(gbase) + (voff)[_i]), (LAS unsigned*)(lds + (bufoff) + ldsw + _i * 8192), 16, 0, 0); } while (0)
; #define PG8_LDA(dst, b, h) do { _Pragma("unroll") for (int m = 0; m < 4; ++m) _Pragma("unroll") for (int k = 0; k < 2; ++k) dst[m][k] = *(const LAS bf16x8*)(lds + PG8_SA(b, h) + aoff + m * 2048 + k * 1024); } while (0)
; #define PG8_LDB(dst, b, h) do { _Pragma("unroll") for (int n = 0; n < 2; ++n) _Pragma("unroll") for (int k = 0; k < 2; ++k) dst[n][k] = *(const LAS bf16x8*)(lds + PG8_SB(b, h) + boff + n * 2048 + k * 1024); } while (0)
; #define PG8_WAIT_V(n) asm volatile("s_waitcnt vmcnt(" #n ")" ::: "memory")
; #define PG8_WAIT_L(n) asm volatile("s_waitcnt lgkmcnt(" #n ")" ::: "memory")
; #define PG8_BAR __builtin_amdgcn_s_barrier()
; #define PG8_SCHED __builtin_amdgcn_sched_barrier(0)
; template <class Epi, class Sched>
; __device__ __forceinline__ void gemm_phase(LAS unsigned char* lds, const Gemm g, const Sched& S, const Epi& E) {
;     ...
;         const bool has_next = S.next(ui + 1, nxt);
;         const char* nA = has_next ? (const char*)g.A + (size_t)nxt.pm * tstep : cA; const char* nB = has_next ? (const char*)g.Bt + (size_t)nxt.pn * tstep : cB;
;         for (int t = 0; t < nt; t += 2) {
;             const bool last = (t == nt - 2);
;             const char* a1 = cA + (size_t)(t + 1) * kstep;
;             const char* a2 = last ? nA : cA + (size_t)(t + 2) * kstep; const char* b2 = last ? nB : cB + (size_t)(t + 2) * kstep;
;             const char* a3 = a2 + kstep; const char* b3 = b2 + kstep;
;             PG8_LDB(B0, 0, 0); PG8_SCHED; PG8_LDA(At, 0, 0); PG8_STAGE(PG8_SA(1, 1), a1 + hstep, voffA);
;             PG8_WAIT_L(8); PG8_BAR; PG8_WAIT_L(0); PG8_MMA(0, 0, At, B0); PG8_BAR; PG8_SCHED;
;             PG8_LDB(B1, 0, 1); PG8_STAGE(PG8_SB(0, 0), b2, voffB);
;             PG8_BAR; PG8_WAIT_L(0); PG8_MMA(0, 1, At, B1); PG8_BAR;
;             PG8_LDA(At, 0, 1); PG8_STAGE(PG8_SA(0, 0), a2, voffA);
;             PG8_BAR; PG8_WAIT_L(0); PG8_MMA(1, 0, At, B0); PG8_BAR; PG8_SCHED;
;             PG8_STAGE(PG8_SB(0, 1), b2 + hstep, voffB);
;             PG8_WAIT_V(6); PG8_BAR; PG8_MMA(1, 1, At, B1); PG8_BAR;
.LBB0_901:
	s_add_u32 s56, s26, 0x100
	s_addc_u32 s57, s27, 0
	s_mov_b32 s58, -2
	s_waitcnt vmcnt(0)
	ds_read_b128 v[128:131], v237
	ds_read_b128 v[132:135], v237 offset:1024
	ds_read_b128 v[136:139], v237 offset:2048
	ds_read_b128 v[140:143], v237 offset:3072
	s_add_u32 s26, s24, 0x100
	s_addc_u32 s27, s25, 0
	s_cmp_eq_u32 s58, 20
	s_cselect_b32 s31, s5, s27
	s_cselect_b32 s30, s4, s26
	s_cselect_b32 s29, s7, s57
	s_cselect_b32 s28, s6, s56
	v_lshl_add_u64 v[176:177], s[24:25], 0, v[210:211]
	s_add_i32 m0, s38, 0xc000
	ds_read_b128 v[144:147], v238
	ds_read_b128 v[148:151], v238 offset:1024
	ds_read_b128 v[152:155], v238 offset:2048
	ds_read_b128 v[156:159], v238 offset:3072
	ds_read_b128 v[160:163], v238 offset:4096
	ds_read_b128 v[164:167], v238 offset:5120
	ds_read_b128 v[168:171], v238 offset:6144
	ds_read_b128 v[172:175], v238 offset:7168
	global_load_lds_dwordx4 v[176:177], off
	v_lshl_add_u64 v[176:177], s[24:25], 0, v[212:213]
	s_add_i32 m0, s38, 0xe000
	s_nop 0
	global_load_lds_dwordx4 v[176:177], off
	s_waitcnt lgkmcnt(8)
	s_waitcnt vmcnt(8)
	s_waitcnt lgkmcnt(0)
	s_setprio 1
	s_barrier
	v_mfma_f32_16x16x32_bf16 v[124:127], v[128:131], v[144:147], 0
	v_mfma_f32_16x16x32_bf16 v[120:123], v[136:139], v[144:147], 0
	v_mfma_f32_16x16x32_bf16 v[108:111], v[128:131], v[152:155], 0
	v_mfma_f32_16x16x32_bf16 v[104:107], v[136:139], v[152:155], 0
	v_mfma_f32_16x16x32_bf16 v[92:95], v[128:131], v[160:163], 0
	v_mfma_f32_16x16x32_bf16 v[88:91], v[136:139], v[160:163], 0
	v_mfma_f32_16x16x32_bf16 v[76:79], v[128:131], v[168:171], 0
	v_mfma_f32_16x16x32_bf16 v[72:75], v[136:139], v[168:171], 0
	v_mfma_f32_16x16x32_bf16 v[124:127], v[132:135], v[148:151], v[124:127]
	v_mfma_f32_16x16x32_bf16 v[120:123], v[140:143], v[148:151], v[120:123]
	v_mfma_f32_16x16x32_bf16 v[108:111], v[132:135], v[156:159], v[108:111]
	v_mfma_f32_16x16x32_bf16 v[104:107], v[140:143], v[156:159], v[104:107]
	v_mfma_f32_16x16x32_bf16 v[92:95], v[132:135], v[164:167], v[92:95]
	v_mfma_f32_16x16x32_bf16 v[88:91], v[140:143], v[164:167], v[88:91]
	v_mfma_f32_16x16x32_bf16 v[76:79], v[132:135], v[172:175], v[76:79]
	v_mfma_f32_16x16x32_bf16 v[72:75], v[140:143], v[172:175], v[72:75]
	s_barrier
	s_setprio 0
	s_add_i32 s24, s50, s37
	s_mov_b32 m0, s24
	ds_read_b128 v[176:179], v239
	ds_read_b128 v[180:183], v239 offset:1024
	ds_read_b128 v[184:187], v239 offset:2048
	ds_read_b128 v[188:191], v239 offset:3072
	global_load_lds_dwordx4 v204, s[28:29]
	s_add_i32 m0, s24, 0x2000
	s_nop 0
	global_load_lds_dwordx4 v208, s[28:29]
	s_waitcnt vmcnt(8)
	s_waitcnt lgkmcnt(0)
	s_setprio 1
	s_barrier
	v_mfma_f32_16x16x32_bf16 v[116:119], v[176:179], v[144:147], 0
	v_mfma_f32_16x16x32_bf16 v[112:115], v[184:187], v[144:147], 0
	v_mfma_f32_16x16x32_bf16 v[100:103], v[176:179], v[152:155], 0
	v_mfma_f32_16x16x32_bf16 v[96:99], v[184:187], v[152:155], 0
	v_mfma_f32_16x16x32_bf16 v[84:87], v[176:179], v[160:163], 0
	v_mfma_f32_16x16x32_bf16 v[80:83], v[184:187], v[160:163], 0
	v_mfma_f32_16x16x32_bf16 v[68:71], v[176:179], v[168:171], 0
	v_mfma_f32_16x16x32_bf16 v[64:67], v[184:187], v[168:171], 0
	v_mfma_f32_16x16x32_bf16 v[116:119], v[180:183], v[148:151], v[116:119]
	v_mfma_f32_16x16x32_bf16 v[112:115], v[188:191], v[148:151], v[112:115]
	v_mfma_f32_16x16x32_bf16 v[100:103], v[180:183], v[156:159], v[100:103]
	v_mfma_f32_16x16x32_bf16 v[96:99], v[188:191], v[156:159], v[96:99]
	v_mfma_f32_16x16x32_bf16 v[84:87], v[180:183], v[164:167], v[84:87]
	v_mfma_f32_16x16x32_bf16 v[80:83], v[188:191], v[164:167], v[80:83]
	v_mfma_f32_16x16x32_bf16 v[68:71], v[180:183], v[172:175], v[68:71]
	v_mfma_f32_16x16x32_bf16 v[64:67], v[188:191], v[172:175], v[64:67]
	s_mov_b32 m0, s38
	v_lshl_add_u64 v[196:197], s[30:31], 0, v[202:203]
	s_barrier
	s_setprio 0
	ds_read_b128 v[144:147], v238 offset:16384
	ds_read_b128 v[148:151], v238 offset:17408
	ds_read_b128 v[152:155], v238 offset:18432
	ds_read_b128 v[156:159], v238 offset:19456
	ds_read_b128 v[160:163], v238 offset:20480
	ds_read_b128 v[164:167], v238 offset:21504
	ds_read_b128 v[168:171], v238 offset:22528
	ds_read_b128 v[172:175], v238 offset:23552
	global_load_lds_dwordx4 v202, s[30:31]
	v_lshl_add_u64 v[198:199], s[30:31], 0, v[206:207]
	s_mov_b32 m0, s39
	s_nop 0
	global_load_lds_dwordx4 v206, s[30:31]
	s_waitcnt lgkmcnt(0)
	s_setprio 1
	s_barrier
	v_mfma_f32_16x16x32_bf16 v[60:63], v[128:131], v[144:147], 0
	v_mfma_f32_16x16x32_bf16 v[56:59], v[136:139], v[144:147], 0
	v_mfma_f32_16x16x32_bf16 v[44:47], v[128:131], v[152:155], 0
	v_mfma_f32_16x16x32_bf16 v[40:43], v[136:139], v[152:155], 0
	v_mfma_f32_16x16x32_bf16 v[28:31], v[128:131], v[160:163], 0
	v_mfma_f32_16x16x32_bf16 v[24:27], v[136:139], v[160:163], 0
	v_mfma_f32_16x16x32_bf16 v[12:15], v[128:131], v[168:171], 0
	v_mfma_f32_16x16x32_bf16 v[8:11], v[136:139], v[168:171], 0
	v_mfma_f32_16x16x32_bf16 v[60:63], v[132:135], v[148:151], v[60:63]
	v_mfma_f32_16x16x32_bf16 v[56:59], v[140:143], v[148:151], v[56:59]
	v_mfma_f32_16x16x32_bf16 v[44:47], v[132:135], v[156:159], v[44:47]
	v_mfma_f32_16x16x32_bf16 v[40:43], v[140:143], v[156:159], v[40:43]
	v_mfma_f32_16x16x32_bf16 v[28:31], v[132:135], v[164:167], v[28:31]
	v_mfma_f32_16x16x32_bf16 v[24:27], v[140:143], v[164:167], v[24:27]
	v_mfma_f32_16x16x32_bf16 v[12:15], v[132:135], v[172:175], v[12:15]
	v_mfma_f32_16x16x32_bf16 v[8:11], v[140:143], v[172:175], v[8:11]
	s_barrier
	s_setprio 0
	s_add_u32 s24, s28, 0x60000
	s_addc_u32 s25, s29, 0
	s_add_i32 s59, s51, s37
	s_mov_b32 m0, s59
	s_nop 0
	global_load_lds_dwordx4 v204, s[24:25]
	s_add_i32 m0, s59, 0x2000
	s_nop 0
	global_load_lds_dwordx4 v208, s[24:25]
	s_add_u32 s24, s30, 0x60000
	s_addc_u32 s25, s31, 0
	s_mov_b32 m0, s40
	s_nop 0
	global_load_lds_dwordx4 v202, s[24:25]
	s_mov_b32 m0, s41
	s_nop 0
	global_load_lds_dwordx4 v206, s[24:25]
	s_waitcnt vmcnt(10)
	s_setprio 1
	s_barrier
; #define PG8_STAGE(bufoff, gbase, voff) do { _Pragma("unroll") for (int _i = 0; _i < 2; ++_i) \
;         __builtin_amdgcn_global_load_lds((const unsigned*)((const char*)(gbase) + (voff)[_i]), (LAS unsigned*)(lds + (bufoff) + ldsw + _i * 8192), 16, 0, 0); } while (0)
; #define PG8_LDA(dst, b, h) do { _Pragma("unroll") for (int m = 0; m < 4; ++m) _Pragma("unroll") for (int k = 0; k < 2; ++k) dst[m][k] = *(const LAS bf16x8*)(lds + PG8_SA(b, h) + aoff + m * 2048 + k * 1024); } while (0)
; #define PG8_LDB(dst, b, h) do { _Pragma("unroll") for (int n = 0; n < 2; ++n) _Pragma("unroll") for (int k = 0; k < 2; ++k) dst[n][k] = *(const LAS bf16x8*)(lds + PG8_SB(b, h) + boff + n * 2048 + k * 1024); } while (0)
; #define PG8_WAIT_V(n) asm volatile("s_waitcnt vmcnt(" #n ")" ::: "memory")
; #define PG8_WAIT_L(n) asm volatile("s_waitcnt lgkmcnt(" #n ")" ::: "memory")
; #define PG8_BAR __builtin_amdgcn_s_barrier()
; #define PG8_SCHED __builtin_amdgcn_sched_barrier(0)
; template <class Epi, class Sched>
; __device__ __forceinline__ void gemm_phase(LAS unsigned char* lds, const Gemm g, const Sched& S, const Epi& E) {
;     ...
;             PG8_LDB(B0, 0, 0); PG8_SCHED; PG8_LDA(At, 0, 0); PG8_STAGE(PG8_SA(1, 1), a1 + hstep, voffA);
;             PG8_WAIT_L(8); PG8_BAR; PG8_WAIT_L(0); PG8_MMA(0, 0, At, B0); PG8_BAR; PG8_SCHED;
;             PG8_LDB(B1, 0, 1); PG8_STAGE(PG8_SB(0, 0), b2, voffB);
;             PG8_BAR; PG8_WAIT_L(0); PG8_MMA(0, 1, At, B1); PG8_BAR;
;             PG8_LDA(At, 0, 1); PG8_STAGE(PG8_SA(0, 0), a2, voffA);
;             PG8_BAR; PG8_WAIT_L(0); PG8_MMA(1, 0, At, B0); PG8_BAR; PG8_SCHED;
;             PG8_STAGE(PG8_SB(0, 1), b2 + hstep, voffB);
;             PG8_WAIT_V(6); PG8_BAR; PG8_MMA(1, 1, At, B1); PG8_BAR;
;             PG8_LDB(B0, 1, 0); PG8_SCHED; PG8_LDA(At, 1, 0); PG8_STAGE(PG8_SA(0, 1), a2 + hstep, voffA);
;             PG8_WAIT_L(8); PG8_BAR; PG8_WAIT_L(0); PG8_MMA(0, 0, At, B0); PG8_BAR; PG8_SCHED;
;             PG8_LDB(B1, 1, 1); PG8_STAGE(PG8_SB(1, 0), b3, voffB);
;             PG8_BAR; PG8_WAIT_L(0); PG8_MMA(0, 1, At, B1); PG8_BAR;
;             PG8_LDA(At, 1, 1); PG8_STAGE(PG8_SA(1, 0), a3, voffA);
;             PG8_BAR; PG8_WAIT_L(0); PG8_MMA(1, 0, At, B0); PG8_BAR; PG8_SCHED;
;             PG8_STAGE(PG8_SB(1, 1), b3 + hstep, voffB);
;             PG8_WAIT_V(6); PG8_BAR; PG8_MMA(1, 1, At, B1); PG8_BAR;
	v_mfma_f32_16x16x32_bf16 v[52:55], v[176:179], v[144:147], 0
	v_mfma_f32_16x16x32_bf16 v[48:51], v[184:187], v[144:147], 0
	v_mfma_f32_16x16x32_bf16 v[36:39], v[176:179], v[152:155], 0
	v_mfma_f32_16x16x32_bf16 v[32:35], v[184:187], v[152:155], 0
	v_mfma_f32_16x16x32_bf16 v[20:23], v[176:179], v[160:163], 0
	v_mfma_f32_16x16x32_bf16 v[16:19], v[184:187], v[160:163], 0
	v_mfma_f32_16x16x32_bf16 v[4:7], v[176:179], v[168:171], 0
	v_mfma_f32_16x16x32_bf16 v[0:3], v[184:187], v[168:171], 0
	v_mfma_f32_16x16x32_bf16 v[52:55], v[180:183], v[148:151], v[52:55]
	v_mfma_f32_16x16x32_bf16 v[48:51], v[188:191], v[148:151], v[48:51]
	v_mfma_f32_16x16x32_bf16 v[36:39], v[180:183], v[156:159], v[36:39]
	v_mfma_f32_16x16x32_bf16 v[32:35], v[188:191], v[156:159], v[32:35]
	v_mfma_f32_16x16x32_bf16 v[20:23], v[180:183], v[164:167], v[20:23]
	v_mfma_f32_16x16x32_bf16 v[16:19], v[188:191], v[164:167], v[16:19]
	v_mfma_f32_16x16x32_bf16 v[4:7], v[180:183], v[172:175], v[4:7]
	v_mfma_f32_16x16x32_bf16 v[0:3], v[188:191], v[172:175], v[0:3]
	s_add_i32 s59, 0, 0x18000
	v_add_u32_e32 v140, s59, v236
	s_barrier
	s_setprio 0
	ds_read_b128 v[128:131], v140
	ds_read_b128 v[132:135], v140 offset:1024
	ds_read_b128 v[136:139], v140 offset:2048
	ds_read_b128 v[140:143], v140 offset:3072
	ds_read_b128 v[144:147], v238 offset:32768
	ds_read_b128 v[148:151], v238 offset:33792
	ds_read_b128 v[152:155], v238 offset:34816
	ds_read_b128 v[156:159], v238 offset:35840
	ds_read_b128 v[160:163], v238 offset:36864
	ds_read_b128 v[164:167], v238 offset:37888
	ds_read_b128 v[168:171], v238 offset:38912
	ds_read_b128 v[172:175], v238 offset:39936
	s_waitcnt lgkmcnt(8)
	s_waitcnt vmcnt(8)
	s_waitcnt lgkmcnt(0)
	s_setprio 1
	s_barrier
	v_mfma_f32_16x16x32_bf16 v[124:127], v[128:131], v[144:147], v[124:127]
	v_mfma_f32_16x16x32_bf16 v[120:123], v[136:139], v[144:147], v[120:123]
	v_mfma_f32_16x16x32_bf16 v[108:111], v[128:131], v[152:155], v[108:111]
	v_mfma_f32_16x16x32_bf16 v[104:107], v[136:139], v[152:155], v[104:107]
	v_mfma_f32_16x16x32_bf16 v[92:95], v[128:131], v[160:163], v[92:95]
	v_mfma_f32_16x16x32_bf16 v[88:91], v[136:139], v[160:163], v[88:91]
	v_mfma_f32_16x16x32_bf16 v[76:79], v[128:131], v[168:171], v[76:79]
	v_mfma_f32_16x16x32_bf16 v[72:75], v[136:139], v[168:171], v[72:75]
	v_mfma_f32_16x16x32_bf16 v[124:127], v[132:135], v[148:151], v[124:127]
	v_mfma_f32_16x16x32_bf16 v[120:123], v[140:143], v[148:151], v[120:123]
	v_mfma_f32_16x16x32_bf16 v[108:111], v[132:135], v[156:159], v[108:111]
	v_mfma_f32_16x16x32_bf16 v[104:107], v[140:143], v[156:159], v[104:107]
	v_mfma_f32_16x16x32_bf16 v[92:95], v[132:135], v[164:167], v[92:95]
	v_mfma_f32_16x16x32_bf16 v[88:91], v[140:143], v[164:167], v[88:91]
	v_mfma_f32_16x16x32_bf16 v[76:79], v[132:135], v[172:175], v[76:79]
	v_mfma_f32_16x16x32_bf16 v[72:75], v[140:143], v[172:175], v[72:75]
	s_barrier
	s_setprio 0
	s_add_i32 s30, 0, 0x1c000
	s_add_i32 s24, s59, s37
	v_add_u32_e32 v188, s30, v236
	s_add_u32 s0, s28, 0x80
	s_addc_u32 s1, s29, 0
	s_mov_b32 m0, s24
	ds_read_b128 v[176:179], v188
	ds_read_b128 v[180:183], v188 offset:1024
	ds_read_b128 v[184:187], v188 offset:2048
	ds_read_b128 v[188:191], v188 offset:3072
	global_load_lds_dwordx4 v204, s[0:1]
	s_add_i32 m0, s24, 0x2000
	s_nop 0
	global_load_lds_dwordx4 v208, s[0:1]
	s_waitcnt vmcnt(8)
	s_waitcnt lgkmcnt(0)
	s_setprio 1
	s_barrier
	v_mfma_f32_16x16x32_bf16 v[116:119], v[176:179], v[144:147], v[116:119]
	v_mfma_f32_16x16x32_bf16 v[112:115], v[184:187], v[144:147], v[112:115]
	v_mfma_f32_16x16x32_bf16 v[100:103], v[176:179], v[152:155], v[100:103]
	v_mfma_f32_16x16x32_bf16 v[96:99], v[184:187], v[152:155], v[96:99]
	v_mfma_f32_16x16x32_bf16 v[84:87], v[176:179], v[160:163], v[84:87]
	v_mfma_f32_16x16x32_bf16 v[80:83], v[184:187], v[160:163], v[80:83]
	v_mfma_f32_16x16x32_bf16 v[68:71], v[176:179], v[168:171], v[68:71]
	v_mfma_f32_16x16x32_bf16 v[64:67], v[184:187], v[168:171], v[64:67]
	v_mfma_f32_16x16x32_bf16 v[116:119], v[180:183], v[148:151], v[116:119]
	v_mfma_f32_16x16x32_bf16 v[112:115], v[188:191], v[148:151], v[112:115]
	v_mfma_f32_16x16x32_bf16 v[100:103], v[180:183], v[156:159], v[100:103]
	v_mfma_f32_16x16x32_bf16 v[96:99], v[188:191], v[156:159], v[96:99]
	v_mfma_f32_16x16x32_bf16 v[84:87], v[180:183], v[164:167], v[84:87]
	v_mfma_f32_16x16x32_bf16 v[80:83], v[188:191], v[164:167], v[80:83]
	v_mfma_f32_16x16x32_bf16 v[68:71], v[180:183], v[172:175], v[68:71]
	v_mfma_f32_16x16x32_bf16 v[64:67], v[188:191], v[172:175], v[64:67]
	s_mov_b32 m0, s47
	s_mov_b64 s[0:1], 0x80
	v_lshl_add_u64 v[192:193], v[196:197], 0, s[0:1]
	s_barrier
	s_setprio 0
	ds_read_b128 v[144:147], v238 offset:49152
	ds_read_b128 v[148:151], v238 offset:50176
	ds_read_b128 v[152:155], v238 offset:51200
	ds_read_b128 v[156:159], v238 offset:52224
	ds_read_b128 v[160:163], v238 offset:53248
	ds_read_b128 v[164:167], v238 offset:54272
	ds_read_b128 v[168:171], v238 offset:55296
	ds_read_b128 v[172:175], v238 offset:56320
	global_load_lds_dwordx4 v[192:193], off
	v_lshl_add_u64 v[192:193], v[198:199], 0, s[0:1]
	s_mov_b32 m0, s48
	s_nop 0
	global_load_lds_dwordx4 v[192:193], off
	s_waitcnt lgkmcnt(0)
	s_setprio 1
	s_barrier
; #define PG8_STAGE(bufoff, gbase, voff) do { _Pragma("unroll") for (int _i = 0; _i < 2; ++_i) \
;         __builtin_amdgcn_global_load_lds((const unsigned*)((const char*)(gbase) + (voff)[_i]), (LAS unsigned*)(lds + (bufoff) + ldsw + _i * 8192), 16, 0, 0); } while (0)
; #define PG8_LDA(dst, b, h) do { _Pragma("unroll") for (int m = 0; m < 4; ++m) _Pragma("unroll") for (int k = 0; k < 2; ++k) dst[m][k] = *(const LAS bf16x8*)(lds + PG8_SA(b, h) + aoff + m * 2048 + k * 1024); } while (0)
; #define PG8_WAIT_V(n) asm volatile("s_waitcnt vmcnt(" #n ")" ::: "memory")
; #define PG8_WAIT_L(n) asm volatile("s_waitcnt lgkmcnt(" #n ")" ::: "memory")
; template <class Epi, class Sched>
; __device__ __forceinline__ void gemm_phase(LAS unsigned char* lds, const Gemm g, const Sched& S, const Epi& E) {
;     ...
;         for (int t = 0; t < nt; t += 2) {
;             const bool last = (t == nt - 2);
;             const char* a1 = cA + (size_t)(t + 1) * kstep;
;             const char* a2 = last ? nA : cA + (size_t)(t + 2) * kstep; const char* b2 = last ? nB : cB + (size_t)(t + 2) * kstep;
;             const char* a3 = a2 + kstep; const char* b3 = b2 + kstep;
;             PG8_LDB(B0, 0, 0); PG8_SCHED; PG8_LDA(At, 0, 0); PG8_STAGE(PG8_SA(1, 1), a1 + hstep, voffA);
;             PG8_WAIT_L(8); PG8_BAR; PG8_WAIT_L(0); PG8_MMA(0, 0, At, B0); PG8_BAR; PG8_SCHED;
;             PG8_LDB(B1, 0, 1); PG8_STAGE(PG8_SB(0, 0), b2, voffB);
;             PG8_BAR; PG8_WAIT_L(0); PG8_MMA(0, 1, At, B1); PG8_BAR;
;             PG8_LDA(At, 0, 1); PG8_STAGE(PG8_SA(0, 0), a2, voffA);
;             PG8_BAR; PG8_WAIT_L(0); PG8_MMA(1, 0, At, B0); PG8_BAR; PG8_SCHED;
;             PG8_STAGE(PG8_SB(0, 1), b2 + hstep, voffB);
;             PG8_WAIT_V(6); PG8_BAR; PG8_MMA(1, 1, At, B1); PG8_BAR;
;             PG8_LDB(B0, 1, 0); PG8_SCHED; PG8_LDA(At, 1, 0); PG8_STAGE(PG8_SA(0, 1), a2 + hstep, voffA);
;             PG8_WAIT_L(8); PG8_BAR; PG8_WAIT_L(0); PG8_MMA(0, 0, At, B0); PG8_BAR; PG8_SCHED;
;             PG8_LDB(B1, 1, 1); PG8_STAGE(PG8_SB(1, 0), b3, voffB);
;             PG8_BAR; PG8_WAIT_L(0); PG8_MMA(0, 1, At, B1); PG8_BAR;
;             PG8_LDA(At, 1, 1); PG8_STAGE(PG8_SA(1, 0), a3, voffA);
;             PG8_BAR; PG8_WAIT_L(0); PG8_MMA(1, 0, At, B0); PG8_BAR; PG8_SCHED;
;             PG8_STAGE(PG8_SB(1, 1), b3 + hstep, voffB);
;             PG8_WAIT_V(6); PG8_BAR; PG8_MMA(1, 1, At, B1); PG8_BAR;
	v_mfma_f32_16x16x32_bf16 v[60:63], v[128:131], v[144:147], v[60:63]
	v_mfma_f32_16x16x32_bf16 v[56:59], v[136:139], v[144:147], v[56:59]
	v_mfma_f32_16x16x32_bf16 v[44:47], v[128:131], v[152:155], v[44:47]
	v_mfma_f32_16x16x32_bf16 v[40:43], v[136:139], v[152:155], v[40:43]
	v_mfma_f32_16x16x32_bf16 v[28:31], v[128:131], v[160:163], v[28:31]
	v_mfma_f32_16x16x32_bf16 v[24:27], v[136:139], v[160:163], v[24:27]
	v_mfma_f32_16x16x32_bf16 v[12:15], v[128:131], v[168:171], v[12:15]
	v_mfma_f32_16x16x32_bf16 v[8:11], v[136:139], v[168:171], v[8:11]
	v_mfma_f32_16x16x32_bf16 v[60:63], v[132:135], v[148:151], v[60:63]
	v_mfma_f32_16x16x32_bf16 v[56:59], v[140:143], v[148:151], v[56:59]
	v_mfma_f32_16x16x32_bf16 v[44:47], v[132:135], v[156:159], v[44:47]
	v_mfma_f32_16x16x32_bf16 v[40:43], v[140:143], v[156:159], v[40:43]
	v_mfma_f32_16x16x32_bf16 v[28:31], v[132:135], v[164:167], v[28:31]
	v_mfma_f32_16x16x32_bf16 v[24:27], v[140:143], v[164:167], v[24:27]
	v_mfma_f32_16x16x32_bf16 v[12:15], v[132:135], v[172:175], v[12:15]
	v_mfma_f32_16x16x32_bf16 v[8:11], v[140:143], v[172:175], v[8:11]
	s_barrier
	s_setprio 0
	s_add_u32 s24, s28, 0x60080
	s_addc_u32 s25, s29, 0
	s_add_i32 s28, s30, s37
	s_mov_b32 m0, s28
	s_nop 0
	global_load_lds_dwordx4 v204, s[24:25]
	s_add_i32 m0, s28, 0x2000
	s_nop 0
	global_load_lds_dwordx4 v208, s[24:25]
	s_waitcnt vmcnt(8)
	s_setprio 1
	s_barrier
	v_mfma_f32_16x16x32_bf16 v[52:55], v[176:179], v[144:147], v[52:55]
	v_mfma_f32_16x16x32_bf16 v[48:51], v[184:187], v[144:147], v[48:51]
	v_mfma_f32_16x16x32_bf16 v[36:39], v[176:179], v[152:155], v[36:39]
	v_mfma_f32_16x16x32_bf16 v[32:35], v[184:187], v[152:155], v[32:35]
	v_mfma_f32_16x16x32_bf16 v[20:23], v[176:179], v[160:163], v[20:23]
	v_mfma_f32_16x16x32_bf16 v[16:19], v[184:187], v[160:163], v[16:19]
	v_mfma_f32_16x16x32_bf16 v[4:7], v[176:179], v[168:171], v[4:7]
	v_mfma_f32_16x16x32_bf16 v[0:3], v[184:187], v[168:171], v[0:3]
	v_mfma_f32_16x16x32_bf16 v[52:55], v[180:183], v[148:151], v[52:55]
	v_mfma_f32_16x16x32_bf16 v[48:51], v[188:191], v[148:151], v[48:51]
	v_mfma_f32_16x16x32_bf16 v[36:39], v[180:183], v[156:159], v[36:39]
	v_mfma_f32_16x16x32_bf16 v[32:35], v[188:191], v[156:159], v[32:35]
	v_mfma_f32_16x16x32_bf16 v[20:23], v[180:183], v[164:167], v[20:23]
	v_mfma_f32_16x16x32_bf16 v[16:19], v[188:191], v[164:167], v[16:19]
	v_mfma_f32_16x16x32_bf16 v[4:7], v[180:183], v[172:175], v[4:7]
	v_mfma_f32_16x16x32_bf16 v[0:3], v[188:191], v[172:175], v[0:3]
	s_add_i32 s58, s58, 2
	s_add_u32 s56, s56, 0x100
	s_addc_u32 s57, s57, 0
	s_cmp_gt_u32 s58, 21
	s_mov_b64 s[24:25], s[26:27]
	s_barrier
	s_setprio 0
.LBB0_902:
	ds_read_b128 v[128:131], v237
	ds_read_b128 v[132:135], v237 offset:1024
	ds_read_b128 v[136:139], v237 offset:2048
	ds_read_b128 v[140:143], v237 offset:3072
	s_add_u32 s26, s24, 0x100
	s_addc_u32 s27, s25, 0
	s_cmp_eq_u32 s58, 20
	s_cselect_b32 s31, s5, s27
	s_cselect_b32 s30, s4, s26
	s_cselect_b32 s29, s7, s57
	s_cselect_b32 s28, s6, s56
	v_lshl_add_u64 v[176:177], s[24:25], 0, v[210:211]
	s_add_i32 m0, s38, 0xc000
	ds_read_b128 v[144:147], v238
	ds_read_b128 v[148:151], v238 offset:1024
	ds_read_b128 v[152:155], v238 offset:2048
	ds_read_b128 v[156:159], v238 offset:3072
	ds_read_b128 v[160:163], v238 offset:4096
	ds_read_b128 v[164:167], v238 offset:5120
	ds_read_b128 v[168:171], v238 offset:6144
	ds_read_b128 v[172:175], v238 offset:7168
	global_load_lds_dwordx4 v[176:177], off
	v_lshl_add_u64 v[176:177], s[24:25], 0, v[212:213]
	s_add_i32 m0, s38, 0xe000
	s_nop 0
	global_load_lds_dwordx4 v[176:177], off
	s_waitcnt lgkmcnt(8)
	s_waitcnt vmcnt(8)
	s_waitcnt lgkmcnt(0)
	s_setprio 1
	s_barrier
	v_mfma_f32_16x16x32_bf16 v[124:127], v[128:131], v[144:147], v[124:127]
	v_mfma_f32_16x16x32_bf16 v[120:123], v[136:139], v[144:147], v[120:123]
	v_mfma_f32_16x16x32_bf16 v[108:111], v[128:131], v[152:155], v[108:111]
	v_mfma_f32_16x16x32_bf16 v[104:107], v[136:139], v[152:155], v[104:107]
	v_mfma_f32_16x16x32_bf16 v[92:95], v[128:131], v[160:163], v[92:95]
	v_mfma_f32_16x16x32_bf16 v[88:91], v[136:139], v[160:163], v[88:91]
	v_mfma_f32_16x16x32_bf16 v[76:79], v[128:131], v[168:171], v[76:79]
	v_mfma_f32_16x16x32_bf16 v[72:75], v[136:139], v[168:171], v[72:75]
	v_mfma_f32_16x16x32_bf16 v[124:127], v[132:135], v[148:151], v[124:127]
	v_mfma_f32_16x16x32_bf16 v[120:123], v[140:143], v[148:151], v[120:123]
	v_mfma_f32_16x16x32_bf16 v[108:111], v[132:135], v[156:159], v[108:111]
	v_mfma_f32_16x16x32_bf16 v[104:107], v[140:143], v[156:159], v[104:107]
	v_mfma_f32_16x16x32_bf16 v[92:95], v[132:135], v[164:167], v[92:95]
	v_mfma_f32_16x16x32_bf16 v[88:91], v[140:143], v[164:167], v[88:91]
	v_mfma_f32_16x16x32_bf16 v[76:79], v[132:135], v[172:175], v[76:79]
	v_mfma_f32_16x16x32_bf16 v[72:75], v[140:143], v[172:175], v[72:75]
	s_barrier
	s_setprio 0
	s_add_i32 s24, s50, s37
	s_mov_b32 m0, s24
	ds_read_b128 v[176:179], v239
	ds_read_b128 v[180:183], v239 offset:1024
	ds_read_b128 v[184:187], v239 offset:2048
	ds_read_b128 v[188:191], v239 offset:3072
	global_load_lds_dwordx4 v204, s[28:29]
	s_add_i32 m0, s24, 0x2000
	s_nop 0
	global_load_lds_dwordx4 v208, s[28:29]
	s_waitcnt vmcnt(8)
	s_waitcnt lgkmcnt(0)
	s_setprio 1
	s_barrier
; #define PG8_STAGE(bufoff, gbase, voff) do { _Pragma("unroll") for (int _i = 0; _i < 2; ++_i) \
;         __builtin_amdgcn_global_load_lds((const unsigned*)((const char*)(gbase) + (voff)[_i]), (LAS unsigned*)(lds + (bufoff) + ldsw + _i * 8192), 16, 0, 0); } while (0)
; #define PG8_LDA(dst, b, h) do { _Pragma("unroll") for (int m = 0; m < 4; ++m) _Pragma("unroll") for (int k = 0; k < 2; ++k) dst[m][k] = *(const LAS bf16x8*)(lds + PG8_SA(b, h) + aoff + m * 2048 + k * 1024); } while (0)
; #define PG8_LDB(dst, b, h) do { _Pragma("unroll") for (int n = 0; n < 2; ++n) _Pragma("unroll") for (int k = 0; k < 2; ++k) dst[n][k] = *(const LAS bf16x8*)(lds + PG8_SB(b, h) + boff + n * 2048 + k * 1024); } while (0)
; #define PG8_MMA(ai, bj, At, Bt) do { __builtin_amdgcn_s_setprio(1); _Pragma("unroll") for (int m = 0; m < 4; ++m) _Pragma("unroll") for (int n = 0; n < 2; ++n) _Pragma("unroll") for (int k = 0; k < 2; ++k) \
;         acc[ai][bj][m][n] = __builtin_amdgcn_mfma_f32_16x16x32_bf16(Bt[n][k], At[m][k], acc[ai][bj][m][n], 0, 0, 0); __builtin_amdgcn_s_setprio(0); } while (0)
; template <class Epi, class Sched>
; __device__ __forceinline__ void gemm_phase(LAS unsigned char* lds, const Gemm g, const Sched& S, const Epi& E) {
;     ...
;             PG8_WAIT_L(8); PG8_BAR; PG8_WAIT_L(0); PG8_MMA(0, 0, At, B0); PG8_BAR; PG8_SCHED;
;             PG8_LDB(B1, 0, 1); PG8_STAGE(PG8_SB(0, 0), b2, voffB);
;             PG8_BAR; PG8_WAIT_L(0); PG8_MMA(0, 1, At, B1); PG8_BAR;
;             PG8_LDA(At, 0, 1); PG8_STAGE(PG8_SA(0, 0), a2, voffA);
;             PG8_BAR; PG8_WAIT_L(0); PG8_MMA(1, 0, At, B0); PG8_BAR; PG8_SCHED;
;             PG8_STAGE(PG8_SB(0, 1), b2 + hstep, voffB);
;             PG8_WAIT_V(6); PG8_BAR; PG8_MMA(1, 1, At, B1); PG8_BAR;
;             PG8_LDB(B0, 1, 0); PG8_SCHED; PG8_LDA(At, 1, 0); PG8_STAGE(PG8_SA(0, 1), a2 + hstep, voffA);
;             PG8_WAIT_L(8); PG8_BAR; PG8_WAIT_L(0); PG8_MMA(0, 0, At, B0); PG8_BAR; PG8_SCHED;
;             PG8_LDB(B1, 1, 1); PG8_STAGE(PG8_SB(1, 0), b3, voffB);
;             PG8_BAR; PG8_WAIT_L(0); PG8_MMA(0, 1, At, B1); PG8_BAR;
;             PG8_LDA(At, 1, 1); PG8_STAGE(PG8_SA(1, 0), a3, voffA);
;             PG8_BAR; PG8_WAIT_L(0); PG8_MMA(1, 0, At, B0); PG8_BAR; PG8_SCHED;
;             PG8_STAGE(PG8_SB(1, 1), b3 + hstep, voffB);
;             PG8_WAIT_V(6); PG8_BAR; PG8_MMA(1, 1, At, B1); PG8_BAR;
	v_mfma_f32_16x16x32_bf16 v[116:119], v[176:179], v[144:147], v[116:119]
	v_mfma_f32_16x16x32_bf16 v[112:115], v[184:187], v[144:147], v[112:115]
	v_mfma_f32_16x16x32_bf16 v[100:103], v[176:179], v[152:155], v[100:103]
	v_mfma_f32_16x16x32_bf16 v[96:99], v[184:187], v[152:155], v[96:99]
	v_mfma_f32_16x16x32_bf16 v[84:87], v[176:179], v[160:163], v[84:87]
	v_mfma_f32_16x16x32_bf16 v[80:83], v[184:187], v[160:163], v[80:83]
	v_mfma_f32_16x16x32_bf16 v[68:71], v[176:179], v[168:171], v[68:71]
	v_mfma_f32_16x16x32_bf16 v[64:67], v[184:187], v[168:171], v[64:67]
	v_mfma_f32_16x16x32_bf16 v[116:119], v[180:183], v[148:151], v[116:119]
	v_mfma_f32_16x16x32_bf16 v[112:115], v[188:191], v[148:151], v[112:115]
	v_mfma_f32_16x16x32_bf16 v[100:103], v[180:183], v[156:159], v[100:103]
	v_mfma_f32_16x16x32_bf16 v[96:99], v[188:191], v[156:159], v[96:99]
	v_mfma_f32_16x16x32_bf16 v[84:87], v[180:183], v[164:167], v[84:87]
	v_mfma_f32_16x16x32_bf16 v[80:83], v[188:191], v[164:167], v[80:83]
	v_mfma_f32_16x16x32_bf16 v[68:71], v[180:183], v[172:175], v[68:71]
	v_mfma_f32_16x16x32_bf16 v[64:67], v[188:191], v[172:175], v[64:67]
	s_mov_b32 m0, s38
	v_lshl_add_u64 v[196:197], s[30:31], 0, v[202:203]
	s_barrier
	s_setprio 0
	ds_read_b128 v[144:147], v238 offset:16384
	ds_read_b128 v[148:151], v238 offset:17408
	ds_read_b128 v[152:155], v238 offset:18432
	ds_read_b128 v[156:159], v238 offset:19456
	ds_read_b128 v[160:163], v238 offset:20480
	ds_read_b128 v[164:167], v238 offset:21504
	ds_read_b128 v[168:171], v238 offset:22528
	ds_read_b128 v[172:175], v238 offset:23552
	global_load_lds_dwordx4 v202, s[30:31]
	v_lshl_add_u64 v[198:199], s[30:31], 0, v[206:207]
	s_mov_b32 m0, s39
	s_nop 0
	global_load_lds_dwordx4 v206, s[30:31]
	s_waitcnt lgkmcnt(0)
	s_setprio 1
	s_barrier
	v_mfma_f32_16x16x32_bf16 v[60:63], v[128:131], v[144:147], v[60:63]
	v_mfma_f32_16x16x32_bf16 v[56:59], v[136:139], v[144:147], v[56:59]
	v_mfma_f32_16x16x32_bf16 v[44:47], v[128:131], v[152:155], v[44:47]
	v_mfma_f32_16x16x32_bf16 v[40:43], v[136:139], v[152:155], v[40:43]
	v_mfma_f32_16x16x32_bf16 v[28:31], v[128:131], v[160:163], v[28:31]
	v_mfma_f32_16x16x32_bf16 v[24:27], v[136:139], v[160:163], v[24:27]
	v_mfma_f32_16x16x32_bf16 v[12:15], v[128:131], v[168:171], v[12:15]
	v_mfma_f32_16x16x32_bf16 v[8:11], v[136:139], v[168:171], v[8:11]
	v_mfma_f32_16x16x32_bf16 v[60:63], v[132:135], v[148:151], v[60:63]
	v_mfma_f32_16x16x32_bf16 v[56:59], v[140:143], v[148:151], v[56:59]
	v_mfma_f32_16x16x32_bf16 v[44:47], v[132:135], v[156:159], v[44:47]
	v_mfma_f32_16x16x32_bf16 v[40:43], v[140:143], v[156:159], v[40:43]
	v_mfma_f32_16x16x32_bf16 v[28:31], v[132:135], v[164:167], v[28:31]
	v_mfma_f32_16x16x32_bf16 v[24:27], v[140:143], v[164:167], v[24:27]
	v_mfma_f32_16x16x32_bf16 v[12:15], v[132:135], v[172:175], v[12:15]
	v_mfma_f32_16x16x32_bf16 v[8:11], v[140:143], v[172:175], v[8:11]
	s_barrier
	s_setprio 0
	s_add_u32 s24, s28, 0x60000
	s_addc_u32 s25, s29, 0
	s_add_i32 s59, s51, s37
	s_mov_b32 m0, s59
	s_nop 0
	global_load_lds_dwordx4 v204, s[24:25]
	s_add_i32 m0, s59, 0x2000
	s_nop 0
	global_load_lds_dwordx4 v208, s[24:25]
	s_add_u32 s24, s30, 0x60000
	s_addc_u32 s25, s31, 0
	s_mov_b32 m0, s40
	s_nop 0
	global_load_lds_dwordx4 v202, s[24:25]
	s_mov_b32 m0, s41
	s_nop 0
	global_load_lds_dwordx4 v206, s[24:25]
	s_waitcnt vmcnt(10)
	s_setprio 1
	s_barrier
	v_mfma_f32_16x16x32_bf16 v[52:55], v[176:179], v[144:147], v[52:55]
	v_mfma_f32_16x16x32_bf16 v[48:51], v[184:187], v[144:147], v[48:51]
	v_mfma_f32_16x16x32_bf16 v[36:39], v[176:179], v[152:155], v[36:39]
	v_mfma_f32_16x16x32_bf16 v[32:35], v[184:187], v[152:155], v[32:35]
	v_mfma_f32_16x16x32_bf16 v[20:23], v[176:179], v[160:163], v[20:23]
	v_mfma_f32_16x16x32_bf16 v[16:19], v[184:187], v[160:163], v[16:19]
	v_mfma_f32_16x16x32_bf16 v[4:7], v[176:179], v[168:171], v[4:7]
	v_mfma_f32_16x16x32_bf16 v[0:3], v[184:187], v[168:171], v[0:3]
	v_mfma_f32_16x16x32_bf16 v[52:55], v[180:183], v[148:151], v[52:55]
	v_mfma_f32_16x16x32_bf16 v[48:51], v[188:191], v[148:151], v[48:51]
	v_mfma_f32_16x16x32_bf16 v[36:39], v[180:183], v[156:159], v[36:39]
	v_mfma_f32_16x16x32_bf16 v[32:35], v[188:191], v[156:159], v[32:35]
	v_mfma_f32_16x16x32_bf16 v[20:23], v[180:183], v[164:167], v[20:23]
	v_mfma_f32_16x16x32_bf16 v[16:19], v[188:191], v[164:167], v[16:19]
	v_mfma_f32_16x16x32_bf16 v[4:7], v[180:183], v[172:175], v[4:7]
	v_mfma_f32_16x16x32_bf16 v[0:3], v[188:191], v[172:175], v[0:3]
	s_add_i32 s59, 0, 0x18000
	v_add_u32_e32 v140, s59, v236
	s_barrier
	s_setprio 0
	ds_read_b128 v[128:131], v140
	ds_read_b128 v[132:135], v140 offset:1024
	ds_read_b128 v[136:139], v140 offset:2048
	ds_read_b128 v[140:143], v140 offset:3072
	ds_read_b128 v[144:147], v238 offset:32768
	ds_read_b128 v[148:151], v238 offset:33792
	ds_read_b128 v[152:155], v238 offset:34816
	ds_read_b128 v[156:159], v238 offset:35840
	ds_read_b128 v[160:163], v238 offset:36864
	ds_read_b128 v[164:167], v238 offset:37888
	ds_read_b128 v[168:171], v238 offset:38912
	ds_read_b128 v[172:175], v238 offset:39936
	s_waitcnt lgkmcnt(8)
	s_waitcnt vmcnt(8)
	s_waitcnt lgkmcnt(0)
	s_setprio 1
	s_barrier
; #define PG8_STAGE(bufoff, gbase, voff) do { _Pragma("unroll") for (int _i = 0; _i < 2; ++_i) \
;         __builtin_amdgcn_global_load_lds((const unsigned*)((const char*)(gbase) + (voff)[_i]), (LAS unsigned*)(lds + (bufoff) + ldsw + _i * 8192), 16, 0, 0); } while (0)
; #define PG8_LDA(dst, b, h) do { _Pragma("unroll") for (int m = 0; m < 4; ++m) _Pragma("unroll") for (int k = 0; k < 2; ++k) dst[m][k] = *(const LAS bf16x8*)(lds + PG8_SA(b, h) + aoff + m * 2048 + k * 1024); } while (0)
; #define PG8_LDB(dst, b, h) do { _Pragma("unroll") for (int n = 0; n < 2; ++n) _Pragma("unroll") for (int k = 0; k < 2; ++k) dst[n][k] = *(const LAS bf16x8*)(lds + PG8_SB(b, h) + boff + n * 2048 + k * 1024); } while (0)
; #define PG8_MMA(ai, bj, At, Bt) do { __builtin_amdgcn_s_setprio(1); _Pragma("unroll") for (int m = 0; m < 4; ++m) _Pragma("unroll") for (int n = 0; n < 2; ++n) _Pragma("unroll") for (int k = 0; k < 2; ++k) \
;         acc[ai][bj][m][n] = __builtin_amdgcn_mfma_f32_16x16x32_bf16(Bt[n][k], At[m][k], acc[ai][bj][m][n], 0, 0, 0); __builtin_amdgcn_s_setprio(0); } while (0)
; #define PG8_WAIT_V(n) asm volatile("s_waitcnt vmcnt(" #n ")" ::: "memory")
; #define PG8_WAIT_L(n) asm volatile("s_waitcnt lgkmcnt(" #n ")" ::: "memory")
; #define PG8_BAR __builtin_amdgcn_s_barrier()
; #define PG8_SCHED __builtin_amdgcn_sched_barrier(0)
; template <class Epi, class Sched>
; __device__ __forceinline__ void gemm_phase(LAS unsigned char* lds, const Gemm g, const Sched& S, const Epi& E) {
;     ...
;             PG8_BAR; PG8_WAIT_L(0); PG8_MMA(1, 0, At, B0); PG8_BAR; PG8_SCHED;
;             PG8_STAGE(PG8_SB(0, 1), b2 + hstep, voffB);
;             PG8_WAIT_V(6); PG8_BAR; PG8_MMA(1, 1, At, B1); PG8_BAR;
;             PG8_LDB(B0, 1, 0); PG8_SCHED; PG8_LDA(At, 1, 0); PG8_STAGE(PG8_SA(0, 1), a2 + hstep, voffA);
;             PG8_WAIT_L(8); PG8_BAR; PG8_WAIT_L(0); PG8_MMA(0, 0, At, B0); PG8_BAR; PG8_SCHED;
;             PG8_LDB(B1, 1, 1); PG8_STAGE(PG8_SB(1, 0), b3, voffB);
;             PG8_BAR; PG8_WAIT_L(0); PG8_MMA(0, 1, At, B1); PG8_BAR;
;             PG8_LDA(At, 1, 1); PG8_STAGE(PG8_SA(1, 0), a3, voffA);
;             PG8_BAR; PG8_WAIT_L(0); PG8_MMA(1, 0, At, B0); PG8_BAR; PG8_SCHED;
;             PG8_STAGE(PG8_SB(1, 1), b3 + hstep, voffB);
;             PG8_WAIT_V(6); PG8_BAR; PG8_MMA(1, 1, At, B1); PG8_BAR;
	v_mfma_f32_16x16x32_bf16 v[124:127], v[128:131], v[144:147], v[124:127]
	v_mfma_f32_16x16x32_bf16 v[120:123], v[136:139], v[144:147], v[120:123]
	v_mfma_f32_16x16x32_bf16 v[108:111], v[128:131], v[152:155], v[108:111]
	v_mfma_f32_16x16x32_bf16 v[104:107], v[136:139], v[152:155], v[104:107]
	v_mfma_f32_16x16x32_bf16 v[92:95], v[128:131], v[160:163], v[92:95]
	v_mfma_f32_16x16x32_bf16 v[88:91], v[136:139], v[160:163], v[88:91]
	v_mfma_f32_16x16x32_bf16 v[76:79], v[128:131], v[168:171], v[76:79]
	v_mfma_f32_16x16x32_bf16 v[72:75], v[136:139], v[168:171], v[72:75]
	v_mfma_f32_16x16x32_bf16 v[124:127], v[132:135], v[148:151], v[124:127]
	v_mfma_f32_16x16x32_bf16 v[120:123], v[140:143], v[148:151], v[120:123]
	v_mfma_f32_16x16x32_bf16 v[108:111], v[132:135], v[156:159], v[108:111]
	v_mfma_f32_16x16x32_bf16 v[104:107], v[140:143], v[156:159], v[104:107]
	v_mfma_f32_16x16x32_bf16 v[92:95], v[132:135], v[164:167], v[92:95]
	v_mfma_f32_16x16x32_bf16 v[88:91], v[140:143], v[164:167], v[88:91]
	v_mfma_f32_16x16x32_bf16 v[76:79], v[132:135], v[172:175], v[76:79]
	v_mfma_f32_16x16x32_bf16 v[72:75], v[140:143], v[172:175], v[72:75]
	s_barrier
	s_setprio 0
	s_add_i32 s30, 0, 0x1c000
	s_add_i32 s24, s59, s37
	v_add_u32_e32 v188, s30, v236
	s_add_u32 s0, s28, 0x80
	s_addc_u32 s1, s29, 0
	s_mov_b32 m0, s24
	ds_read_b128 v[176:179], v188
	ds_read_b128 v[180:183], v188 offset:1024
	ds_read_b128 v[184:187], v188 offset:2048
	ds_read_b128 v[188:191], v188 offset:3072
	global_load_lds_dwordx4 v204, s[0:1]
	s_add_i32 m0, s24, 0x2000
	s_nop 0
	global_load_lds_dwordx4 v208, s[0:1]
	s_waitcnt vmcnt(8)
	s_waitcnt lgkmcnt(0)
	s_setprio 1
	s_barrier
	v_mfma_f32_16x16x32_bf16 v[116:119], v[176:179], v[144:147], v[116:119]
	v_mfma_f32_16x16x32_bf16 v[112:115], v[184:187], v[144:147], v[112:115]
	v_mfma_f32_16x16x32_bf16 v[100:103], v[176:179], v[152:155], v[100:103]
	v_mfma_f32_16x16x32_bf16 v[96:99], v[184:187], v[152:155], v[96:99]
	v_mfma_f32_16x16x32_bf16 v[84:87], v[176:179], v[160:163], v[84:87]
	v_mfma_f32_16x16x32_bf16 v[80:83], v[184:187], v[160:163], v[80:83]
	v_mfma_f32_16x16x32_bf16 v[68:71], v[176:179], v[168:171], v[68:71]
	v_mfma_f32_16x16x32_bf16 v[64:67], v[184:187], v[168:171], v[64:67]
	v_mfma_f32_16x16x32_bf16 v[116:119], v[180:183], v[148:151], v[116:119]
	v_mfma_f32_16x16x32_bf16 v[112:115], v[188:191], v[148:151], v[112:115]
	v_mfma_f32_16x16x32_bf16 v[100:103], v[180:183], v[156:159], v[100:103]
	v_mfma_f32_16x16x32_bf16 v[96:99], v[188:191], v[156:159], v[96:99]
	v_mfma_f32_16x16x32_bf16 v[84:87], v[180:183], v[164:167], v[84:87]
	v_mfma_f32_16x16x32_bf16 v[80:83], v[188:191], v[164:167], v[80:83]
	v_mfma_f32_16x16x32_bf16 v[68:71], v[180:183], v[172:175], v[68:71]
	v_mfma_f32_16x16x32_bf16 v[64:67], v[188:191], v[172:175], v[64:67]
	s_mov_b32 m0, s47
	s_mov_b64 s[0:1], 0x80
	v_lshl_add_u64 v[192:193], v[196:197], 0, s[0:1]
	s_barrier
	s_setprio 0
	ds_read_b128 v[144:147], v238 offset:49152
	ds_read_b128 v[148:151], v238 offset:50176
	ds_read_b128 v[152:155], v238 offset:51200
	ds_read_b128 v[156:159], v238 offset:52224
	ds_read_b128 v[160:163], v238 offset:53248
	ds_read_b128 v[164:167], v238 offset:54272
	ds_read_b128 v[168:171], v238 offset:55296
	ds_read_b128 v[172:175], v238 offset:56320
	global_load_lds_dwordx4 v[192:193], off
	v_lshl_add_u64 v[192:193], v[198:199], 0, s[0:1]
	s_mov_b32 m0, s48
	s_nop 0
	global_load_lds_dwordx4 v[192:193], off
	s_waitcnt lgkmcnt(0)
	s_setprio 1
	s_barrier
	v_mfma_f32_16x16x32_bf16 v[60:63], v[128:131], v[144:147], v[60:63]
	v_mfma_f32_16x16x32_bf16 v[56:59], v[136:139], v[144:147], v[56:59]
	v_mfma_f32_16x16x32_bf16 v[44:47], v[128:131], v[152:155], v[44:47]
	v_mfma_f32_16x16x32_bf16 v[40:43], v[136:139], v[152:155], v[40:43]
	v_mfma_f32_16x16x32_bf16 v[28:31], v[128:131], v[160:163], v[28:31]
	v_mfma_f32_16x16x32_bf16 v[24:27], v[136:139], v[160:163], v[24:27]
	v_mfma_f32_16x16x32_bf16 v[12:15], v[128:131], v[168:171], v[12:15]
	v_mfma_f32_16x16x32_bf16 v[8:11], v[136:139], v[168:171], v[8:11]
	v_mfma_f32_16x16x32_bf16 v[60:63], v[132:135], v[148:151], v[60:63]
	v_mfma_f32_16x16x32_bf16 v[56:59], v[140:143], v[148:151], v[56:59]
	v_mfma_f32_16x16x32_bf16 v[44:47], v[132:135], v[156:159], v[44:47]
	v_mfma_f32_16x16x32_bf16 v[40:43], v[140:143], v[156:159], v[40:43]
	v_mfma_f32_16x16x32_bf16 v[28:31], v[132:135], v[164:167], v[28:31]
	v_mfma_f32_16x16x32_bf16 v[24:27], v[140:143], v[164:167], v[24:27]
	v_mfma_f32_16x16x32_bf16 v[12:15], v[132:135], v[172:175], v[12:15]
	v_mfma_f32_16x16x32_bf16 v[8:11], v[140:143], v[172:175], v[8:11]
	s_barrier
	s_setprio 0
	s_add_u32 s24, s28, 0x60080
	s_addc_u32 s25, s29, 0
	s_add_i32 s28, s30, s37
	s_mov_b32 m0, s28
	s_nop 0
	global_load_lds_dwordx4 v204, s[24:25]
	s_add_i32 m0, s28, 0x2000
	s_nop 0
	global_load_lds_dwordx4 v208, s[24:25]
	s_waitcnt vmcnt(8)
	s_setprio 1
	s_barrier
	v_mfma_f32_16x16x32_bf16 v[52:55], v[176:179], v[144:147], v[52:55]
	v_mfma_f32_16x16x32_bf16 v[48:51], v[184:187], v[144:147], v[48:51]
	v_mfma_f32_16x16x32_bf16 v[36:39], v[176:179], v[152:155], v[36:39]
	v_mfma_f32_16x16x32_bf16 v[32:35], v[184:187], v[152:155], v[32:35]
	v_mfma_f32_16x16x32_bf16 v[20:23], v[176:179], v[160:163], v[20:23]
	v_mfma_f32_16x16x32_bf16 v[16:19], v[184:187], v[160:163], v[16:19]
	v_mfma_f32_16x16x32_bf16 v[4:7], v[176:179], v[168:171], v[4:7]
	v_mfma_f32_16x16x32_bf16 v[0:3], v[184:187], v[168:171], v[0:3]
	v_mfma_f32_16x16x32_bf16 v[52:55], v[180:183], v[148:151], v[52:55]
	v_mfma_f32_16x16x32_bf16 v[48:51], v[188:191], v[148:151], v[48:51]
	v_mfma_f32_16x16x32_bf16 v[36:39], v[180:183], v[156:159], v[36:39]
	v_mfma_f32_16x16x32_bf16 v[32:35], v[188:191], v[156:159], v[32:35]
	v_mfma_f32_16x16x32_bf16 v[20:23], v[180:183], v[164:167], v[20:23]
	v_mfma_f32_16x16x32_bf16 v[16:19], v[188:191], v[164:167], v[16:19]
	v_mfma_f32_16x16x32_bf16 v[4:7], v[180:183], v[172:175], v[4:7]
	v_mfma_f32_16x16x32_bf16 v[0:3], v[188:191], v[172:175], v[0:3]
	s_add_i32 s58, s58, 2
	s_add_u32 s56, s56, 0x100
	s_addc_u32 s57, s57, 0
	s_cmp_gt_u32 s58, 21
	s_mov_b64 s[24:25], s[26:27]
	s_barrier
; __device__ __forceinline__ unsigned cvt_pk_bf16(float lo, float hi) { unsigned r; asm volatile("v_cvt_pk_bf16_f32 %0, %1, %2" : "=v"(r) : "v"(lo), "v"(hi)); return r; }
; __device__ __forceinline__ float bf_lo(unsigned u) { return __uint_as_float(u << 16); }
; __device__ __forceinline__ float bf_hi(unsigned u) { return __uint_as_float(u & 0xffff0000u); }
;     __device__ __forceinline__ void operator()(const AccT& acc, const Unit& u, int wr, int wc, int fr, int fq) const {
;         asm volatile("" : "+v"(fr), "+v"(fq));
;         const int rowt = u.pm * 256; const int b = rowt >> 11;
;         const bf16_t* res = res_b + (size_t)rowt * DM; bf16_t* out = hb + (size_t)rowt * DM;
;         const int col0 = u.pn * 256 + wc * 32 + 8 * fq;
;         f32x4 gv[2][2];
; #pragma unroll
;         for (int bj = 0; bj < 2; ++bj)
; #pragma unroll
;             for (int n = 0; n < 2; ++n) gv[bj][n] = *(const f32x4*)(gate + (size_t)b * NMOD + col0 + bj * 128 + n * 4) * gs;
;         u32x4 r[2][4][2];
; #pragma unroll
;         for (int ai = 0; ai < 2; ++ai)
; #pragma unroll
;             for (int m = 0; m < 4; ++m)
; #pragma unroll
;                 for (int bj = 0; bj < 2; ++bj) r[ai][m][bj] = *(const u32x4*)(res + (size_t)(wr * 64 + fr + ai * 128 + m * 16) * DM + col0 + bj * 128);
; #pragma unroll
;         for (int ai = 0; ai < 2; ++ai)
; #pragma unroll
;             for (int m = 0; m < 4; ++m)
; #pragma unroll
;                 for (int bj = 0; bj < 2; ++bj) {
;                     const u32x4 q = r[ai][m][bj];
;                     const f32x4 r0 = {bf_lo(q.x), bf_hi(q.x), bf_lo(q.y), bf_hi(q.y)}, r1 = {bf_lo(q.z), bf_hi(q.z), bf_lo(q.w), bf_hi(q.w)};
;                     const f32x4 h0 = r0 + gv[bj][0] * acc[ai][bj][m][0], h1 = r1 + gv[bj][1] * acc[ai][bj][m][1];
;                     u32x4 w; w.x = cvt_pk_bf16(h0[0], h0[1]); w.y = cvt_pk_bf16(h0[2], h0[3]); w.z = cvt_pk_bf16(h1[0], h1[1]); w.w = cvt_pk_bf16(h1[2], h1[3]);
;                     *(u32x4*)(out + (size_t)(wr * 64 + fr + ai * 128 + m * 16) * DM + col0 + bj * 128) = w;
;                 }
	s_setprio 0
	s_cbranch_scc0 .LBB0_902
	s_lshl_b32 s27, s55, 8
	v_mov_b32_e32 v146, v235
	v_mov_b32_e32 v128, v234
	s_lshl_b32 s24, s54, 8
	s_ashr_i32 s26, s54, 3
	s_or_b32 s27, s27, s46
	s_ashr_i32 s25, s24, 31
	v_lshl_add_u32 v144, v128, 3, s27
	s_mul_hi_i32 s27, s26, 0x9000
	s_mul_i32 s26, s26, 0x9000
	s_add_u32 s26, s43, s26
	s_addc_u32 s27, s44, s27
	v_ashrrev_i32_e32 v145, 31, v144
	s_lshl_b64 s[24:25], s[24:25], 11
	v_lshl_add_u64 v[132:133], v[144:145], 2, s[26:27]
	s_add_u32 s26, s62, s24
	v_add_u32_e32 v146, s45, v146
	s_addc_u32 s27, s63, s25
	v_lshlrev_b64 v[222:223], 1, v[144:145]
	v_ashrrev_i32_e32 v147, 31, v146
	v_lshl_add_u64 v[144:145], s[26:27], 0, v[222:223]
	v_lshlrev_b64 v[248:249], 11, v[146:147]
	v_lshl_add_u64 v[146:147], v[144:145], 0, v[248:249]
	global_load_dwordx4 v[136:139], v[132:133], off offset:16
	global_load_dwordx4 v[140:143], v[132:133], off
	global_load_dwordx4 v[128:131], v[132:133], off offset:528
	s_nop 0
	global_load_dwordx4 v[132:135], v[132:133], off offset:512
	s_nop 0
	global_load_dwordx4 v[240:243], v[146:147], off
	global_load_dwordx4 v[244:247], v[146:147], off offset:256
	v_lshl_add_u64 v[232:233], v[248:249], 0, s[10:11]
	v_lshl_add_u64 v[146:147], v[144:145], 0, v[232:233]
	global_load_dwordx4 v[196:199], v[146:147], off
	global_load_dwordx4 v[192:195], v[146:147], off offset:256
	v_lshl_add_u64 v[230:231], v[248:249], 0, s[12:13]
	v_lshl_add_u64 v[146:147], v[144:145], 0, v[230:231]
	global_load_dwordx4 v[188:191], v[146:147], off
	global_load_dwordx4 v[184:187], v[146:147], off offset:256
	v_lshl_add_u64 v[228:229], v[248:249], 0, s[14:15]
	v_lshl_add_u64 v[146:147], v[144:145], 0, v[228:229]
	global_load_dwordx4 v[180:183], v[146:147], off
	global_load_dwordx4 v[176:179], v[146:147], off offset:256
	v_lshl_add_u64 v[226:227], v[248:249], 0, s[16:17]
	v_lshl_add_u64 v[146:147], v[144:145], 0, v[226:227]
	global_load_dwordx4 v[172:175], v[146:147], off
	global_load_dwordx4 v[168:171], v[146:147], off offset:256
	v_lshl_add_u64 v[224:225], v[248:249], 0, s[18:19]
	v_lshl_add_u64 v[146:147], v[144:145], 0, v[224:225]
	global_load_dwordx4 v[164:167], v[146:147], off
	global_load_dwordx4 v[160:163], v[146:147], off offset:256
	v_lshl_add_u64 v[220:221], v[248:249], 0, s[20:21]
	v_lshl_add_u64 v[146:147], v[144:145], 0, v[220:221]
	global_load_dwordx4 v[156:159], v[146:147], off
	global_load_dwordx4 v[152:155], v[146:147], off offset:256
	v_lshl_add_u64 v[218:219], v[248:249], 0, s[22:23]
	v_lshl_add_u64 v[144:145], v[144:145], 0, v[218:219]
	global_load_dwordx4 v[148:151], v[144:145], off
	s_nop 0
	global_load_dwordx4 v[144:147], v[144:145], off offset:256
	s_add_u32 s24, s80, s24
	s_addc_u32 s25, s81, s25
	v_lshl_add_u64 v[222:223], s[24:25], 0, v[222:223]
	v_lshl_add_u64 v[248:249], v[222:223], 0, v[248:249]
	s_and_b64 vcc, exec, s[2:3]
	s_mov_b32 s55, s52
	s_mov_b32 s54, s53
	s_mov_b64 s[26:27], s[6:7]
	s_mov_b64 s[24:25], s[4:5]
	s_waitcnt vmcnt(0)
	v_lshlrev_b32_e32 v250, 16, v240
	v_and_b32_e32 v251, 0xffff0000, v240
	v_lshlrev_b32_e32 v240, 16, v241
	v_and_b32_e32 v241, 0xffff0000, v241
	v_lshlrev_b32_e32 v252, 16, v242
	v_and_b32_e32 v253, 0xffff0000, v242
	v_lshlrev_b32_e32 v242, 16, v243
	v_and_b32_e32 v243, 0xffff0000, v243
	v_pk_fma_f32 v[126:127], v[126:127], v[142:143], v[240:241]
	v_pk_fma_f32 v[124:125], v[124:125], v[140:141], v[250:251]
	v_pk_fma_f32 v[240:241], v[122:123], v[138:139], v[242:243]
	v_pk_fma_f32 v[122:123], v[120:121], v[136:137], v[252:253]
	v_cvt_pk_bf16_f32 v120, v124, v125
	v_cvt_pk_bf16_f32 v121, v126, v127
	v_lshlrev_b32_e32 v124, 16, v246
	v_cvt_pk_bf16_f32 v122, v122, v123
	v_cvt_pk_bf16_f32 v123, v240, v241
	global_store_dwordx4 v[248:249], v[120:123], off
	v_and_b32_e32 v125, 0xffff0000, v246
	v_lshlrev_b32_e32 v126, 16, v247
	v_lshlrev_b32_e32 v120, 16, v244
	v_and_b32_e32 v121, 0xffff0000, v244
	v_and_b32_e32 v127, 0xffff0000, v247
	v_lshlrev_b32_e32 v122, 16, v245
	v_and_b32_e32 v123, 0xffff0000, v245
	v_pk_fma_f32 v[116:117], v[116:117], v[132:133], v[120:121]
	v_pk_fma_f32 v[120:121], v[114:115], v[130:131], v[126:127]
	v_pk_fma_f32 v[114:115], v[112:113], v[128:129], v[124:125]
	v_pk_fma_f32 v[118:119], v[118:119], v[134:135], v[122:123]
	v_cvt_pk_bf16_f32 v112, v116, v117
	v_lshlrev_b32_e32 v116, 16, v197
	v_cvt_pk_bf16_f32 v113, v118, v119
	v_cvt_pk_bf16_f32 v114, v114, v115
	v_cvt_pk_bf16_f32 v115, v120, v121
	global_store_dwordx4 v[248:249], v[112:115], off offset:256
	v_and_b32_e32 v117, 0xffff0000, v197
	v_lshlrev_b32_e32 v118, 16, v198
	v_lshlrev_b32_e32 v114, 16, v196
	v_and_b32_e32 v115, 0xffff0000, v196
	v_and_b32_e32 v119, 0xffff0000, v198
	v_lshlrev_b32_e32 v120, 16, v199
	v_and_b32_e32 v121, 0xffff0000, v199
	v_lshl_add_u64 v[112:113], v[222:223], 0, v[232:233]
	v_pk_fma_f32 v[110:111], v[110:111], v[142:143], v[116:117]
	v_pk_fma_f32 v[108:109], v[108:109], v[140:141], v[114:115]
	v_pk_fma_f32 v[114:115], v[106:107], v[138:139], v[120:121]
	v_pk_fma_f32 v[106:107], v[104:105], v[136:137], v[118:119]
	v_cvt_pk_bf16_f32 v104, v108, v109
	v_cvt_pk_bf16_f32 v105, v110, v111
	v_lshlrev_b32_e32 v108, 16, v194
	v_cvt_pk_bf16_f32 v106, v106, v107
	v_cvt_pk_bf16_f32 v107, v114, v115
	global_store_dwordx4 v[112:113], v[104:107], off
	v_and_b32_e32 v109, 0xffff0000, v194
	v_lshlrev_b32_e32 v110, 16, v195
	v_lshlrev_b32_e32 v104, 16, v192
	v_and_b32_e32 v105, 0xffff0000, v192
	v_and_b32_e32 v111, 0xffff0000, v195
	v_lshlrev_b32_e32 v106, 16, v193
	v_and_b32_e32 v107, 0xffff0000, v193
	v_pk_fma_f32 v[100:101], v[100:101], v[132:133], v[104:105]
	v_pk_fma_f32 v[104:105], v[98:99], v[130:131], v[110:111]
	v_pk_fma_f32 v[98:99], v[96:97], v[128:129], v[108:109]
; __device__ __forceinline__ unsigned cvt_pk_bf16(float lo, float hi) { unsigned r; asm volatile("v_cvt_pk_bf16_f32 %0, %1, %2" : "=v"(r) : "v"(lo), "v"(hi)); return r; }
; __device__ __forceinline__ float bf_lo(unsigned u) { return __uint_as_float(u << 16); }
; __device__ __forceinline__ float bf_hi(unsigned u) { return __uint_as_float(u & 0xffff0000u); }
;     __device__ __forceinline__ void operator()(const AccT& acc, const Unit& u, int wr, int wc, int fr, int fq) const {
;     ...
;         for (int ai = 0; ai < 2; ++ai)
; #pragma unroll
;             for (int m = 0; m < 4; ++m)
; #pragma unroll
;                 for (int bj = 0; bj < 2; ++bj) {
;                     const u32x4 q = r[ai][m][bj];
;                     const f32x4 r0 = {bf_lo(q.x), bf_hi(q.x), bf_lo(q.y), bf_hi(q.y)}, r1 = {bf_lo(q.z), bf_hi(q.z), bf_lo(q.w), bf_hi(q.w)};
;                     const f32x4 h0 = r0 + gv[bj][0] * acc[ai][bj][m][0], h1 = r1 + gv[bj][1] * acc[ai][bj][m][1];
;                     u32x4 w; w.x = cvt_pk_bf16(h0[0], h0[1]); w.y = cvt_pk_bf16(h0[2], h0[3]); w.z = cvt_pk_bf16(h1[0], h1[1]); w.w = cvt_pk_bf16(h1[2], h1[3]);
;                     *(u32x4*)(out + (size_t)(wr * 64 + fr + ai * 128 + m * 16) * DM + col0 + bj * 128) = w;
;                 }
	v_pk_fma_f32 v[102:103], v[102:103], v[134:135], v[106:107]
	v_cvt_pk_bf16_f32 v96, v100, v101
	v_lshlrev_b32_e32 v100, 16, v189
	v_cvt_pk_bf16_f32 v97, v102, v103
	v_cvt_pk_bf16_f32 v98, v98, v99
	v_cvt_pk_bf16_f32 v99, v104, v105
	global_store_dwordx4 v[112:113], v[96:99], off offset:256
	v_and_b32_e32 v101, 0xffff0000, v189
	v_lshlrev_b32_e32 v102, 16, v190
	v_lshlrev_b32_e32 v98, 16, v188
	v_and_b32_e32 v99, 0xffff0000, v188
	v_and_b32_e32 v103, 0xffff0000, v190
	v_lshlrev_b32_e32 v104, 16, v191
	v_and_b32_e32 v105, 0xffff0000, v191
	v_lshl_add_u64 v[96:97], v[222:223], 0, v[230:231]
	v_pk_fma_f32 v[94:95], v[94:95], v[142:143], v[100:101]
	v_pk_fma_f32 v[92:93], v[92:93], v[140:141], v[98:99]
	v_pk_fma_f32 v[98:99], v[90:91], v[138:139], v[104:105]
	v_pk_fma_f32 v[90:91], v[88:89], v[136:137], v[102:103]
	v_cvt_pk_bf16_f32 v88, v92, v93
	v_cvt_pk_bf16_f32 v89, v94, v95
	v_lshlrev_b32_e32 v92, 16, v186
	v_cvt_pk_bf16_f32 v90, v90, v91
	v_cvt_pk_bf16_f32 v91, v98, v99
	global_store_dwordx4 v[96:97], v[88:91], off
	v_and_b32_e32 v93, 0xffff0000, v186
	v_lshlrev_b32_e32 v94, 16, v187
	v_lshlrev_b32_e32 v88, 16, v184
	v_and_b32_e32 v89, 0xffff0000, v184
	v_and_b32_e32 v95, 0xffff0000, v187
	v_lshlrev_b32_e32 v90, 16, v185
	v_and_b32_e32 v91, 0xffff0000, v185
	v_pk_fma_f32 v[84:85], v[84:85], v[132:133], v[88:89]
	v_pk_fma_f32 v[88:89], v[82:83], v[130:131], v[94:95]
	v_pk_fma_f32 v[82:83], v[80:81], v[128:129], v[92:93]
	v_pk_fma_f32 v[86:87], v[86:87], v[134:135], v[90:91]
	v_cvt_pk_bf16_f32 v80, v84, v85
	v_lshlrev_b32_e32 v84, 16, v181
	v_cvt_pk_bf16_f32 v81, v86, v87
	v_cvt_pk_bf16_f32 v82, v82, v83
	v_cvt_pk_bf16_f32 v83, v88, v89
	global_store_dwordx4 v[96:97], v[80:83], off offset:256
	v_and_b32_e32 v85, 0xffff0000, v181
	v_lshlrev_b32_e32 v86, 16, v182
	v_lshlrev_b32_e32 v82, 16, v180
	v_and_b32_e32 v83, 0xffff0000, v180
	v_and_b32_e32 v87, 0xffff0000, v182
	v_lshlrev_b32_e32 v88, 16, v183
	v_and_b32_e32 v89, 0xffff0000, v183
	v_lshl_add_u64 v[80:81], v[222:223], 0, v[228:229]
	v_pk_fma_f32 v[78:79], v[78:79], v[142:143], v[84:85]
	v_pk_fma_f32 v[76:77], v[76:77], v[140:141], v[82:83]
	v_pk_fma_f32 v[82:83], v[74:75], v[138:139], v[88:89]
	v_pk_fma_f32 v[74:75], v[72:73], v[136:137], v[86:87]
	v_cvt_pk_bf16_f32 v72, v76, v77
	v_cvt_pk_bf16_f32 v73, v78, v79
	v_lshlrev_b32_e32 v76, 16, v178
	v_cvt_pk_bf16_f32 v74, v74, v75
	v_cvt_pk_bf16_f32 v75, v82, v83
	global_store_dwordx4 v[80:81], v[72:75], off
	v_and_b32_e32 v77, 0xffff0000, v178
	v_lshlrev_b32_e32 v78, 16, v179
	v_lshlrev_b32_e32 v72, 16, v176
	v_and_b32_e32 v73, 0xffff0000, v176
	v_and_b32_e32 v79, 0xffff0000, v179
	v_lshlrev_b32_e32 v74, 16, v177
	v_and_b32_e32 v75, 0xffff0000, v177
	v_pk_fma_f32 v[68:69], v[68:69], v[132:133], v[72:73]
	v_pk_fma_f32 v[72:73], v[66:67], v[130:131], v[78:79]
	v_pk_fma_f32 v[66:67], v[64:65], v[128:129], v[76:77]
	v_pk_fma_f32 v[70:71], v[70:71], v[134:135], v[74:75]
	v_cvt_pk_bf16_f32 v64, v68, v69
	v_lshlrev_b32_e32 v68, 16, v173
	v_cvt_pk_bf16_f32 v65, v70, v71
	v_cvt_pk_bf16_f32 v66, v66, v67
	v_cvt_pk_bf16_f32 v67, v72, v73
	global_store_dwordx4 v[80:81], v[64:67], off offset:256
	v_and_b32_e32 v69, 0xffff0000, v173
	v_lshlrev_b32_e32 v70, 16, v174
	v_lshlrev_b32_e32 v66, 16, v172
	v_and_b32_e32 v67, 0xffff0000, v172
	v_and_b32_e32 v71, 0xffff0000, v174
	v_lshlrev_b32_e32 v72, 16, v175
	v_and_b32_e32 v73, 0xffff0000, v175
	v_lshl_add_u64 v[64:65], v[222:223], 0, v[226:227]
	v_pk_fma_f32 v[62:63], v[62:63], v[142:143], v[68:69]
	v_pk_fma_f32 v[60:61], v[60:61], v[140:141], v[66:67]
	v_pk_fma_f32 v[66:67], v[58:59], v[138:139], v[72:73]
	v_pk_fma_f32 v[58:59], v[56:57], v[136:137], v[70:71]
	v_cvt_pk_bf16_f32 v56, v60, v61
	v_cvt_pk_bf16_f32 v57, v62, v63
	v_lshlrev_b32_e32 v60, 16, v170
	v_cvt_pk_bf16_f32 v58, v58, v59
	v_cvt_pk_bf16_f32 v59, v66, v67
	global_store_dwordx4 v[64:65], v[56:59], off
	v_and_b32_e32 v61, 0xffff0000, v170
	v_lshlrev_b32_e32 v62, 16, v171
	v_lshlrev_b32_e32 v56, 16, v168
	v_and_b32_e32 v57, 0xffff0000, v168
	v_and_b32_e32 v63, 0xffff0000, v171
	v_lshlrev_b32_e32 v58, 16, v169
	v_and_b32_e32 v59, 0xffff0000, v169
	v_pk_fma_f32 v[52:53], v[52:53], v[132:133], v[56:57]
	v_pk_fma_f32 v[56:57], v[50:51], v[130:131], v[62:63]
	v_pk_fma_f32 v[50:51], v[48:49], v[128:129], v[60:61]
	v_pk_fma_f32 v[54:55], v[54:55], v[134:135], v[58:59]
	v_cvt_pk_bf16_f32 v48, v52, v53
	v_lshlrev_b32_e32 v52, 16, v165
	v_cvt_pk_bf16_f32 v49, v54, v55
; __device__ __forceinline__ unsigned cvt_pk_bf16(float lo, float hi) { unsigned r; asm volatile("v_cvt_pk_bf16_f32 %0, %1, %2" : "=v"(r) : "v"(lo), "v"(hi)); return r; }
; __device__ __forceinline__ float bf_lo(unsigned u) { return __uint_as_float(u << 16); }
; __device__ __forceinline__ float bf_hi(unsigned u) { return __uint_as_float(u & 0xffff0000u); }
; #define PG8_WAIT_V(n) asm volatile("s_waitcnt vmcnt(" #n ")" ::: "memory")
; #define PG8_BAR __builtin_amdgcn_s_barrier()
; template <class Epi, class Sched>
; __device__ __forceinline__ void gemm_phase(LAS unsigned char* lds, const Gemm g, const Sched& S, const Epi& E) {
;     ...
;         if (!has_next) break;
; #pragma unroll
;         for (int a = 0; a < 2; ++a)
; #pragma unroll
;             for (int b = 0; b < 2; ++b)
; #pragma unroll
;                 for (int m = 0; m < 4; ++m)
; #pragma unroll
;                     for (int n = 0; n < 2; ++n) acc[a][b][m][n] = (f32x4){0.f, 0.f, 0.f, 0.f};
;         cur = nxt; cA = nA; cB = nB; ++ui;
;     }
;     PG8_WAIT_V(0);
;     if (wr == 0) PG8_BAR;
;     PG8_BAR;
;     __device__ __forceinline__ void operator()(const AccT& acc, const Unit& u, int wr, int wc, int fr, int fq) const {
;     ...
;         for (int ai = 0; ai < 2; ++ai)
; #pragma unroll
;             for (int m = 0; m < 4; ++m)
; #pragma unroll
;                 for (int bj = 0; bj < 2; ++bj) {
;                     const u32x4 q = r[ai][m][bj];
;                     const f32x4 r0 = {bf_lo(q.x), bf_hi(q.x), bf_lo(q.y), bf_hi(q.y)}, r1 = {bf_lo(q.z), bf_hi(q.z), bf_lo(q.w), bf_hi(q.w)};
;                     const f32x4 h0 = r0 + gv[bj][0] * acc[ai][bj][m][0], h1 = r1 + gv[bj][1] * acc[ai][bj][m][1];
;                     u32x4 w; w.x = cvt_pk_bf16(h0[0], h0[1]); w.y = cvt_pk_bf16(h0[2], h0[3]); w.z = cvt_pk_bf16(h1[0], h1[1]); w.w = cvt_pk_bf16(h1[2], h1[3]);
;                     *(u32x4*)(out + (size_t)(wr * 64 + fr + ai * 128 + m * 16) * DM + col0 + bj * 128) = w;
;                 }
	v_cvt_pk_bf16_f32 v50, v50, v51
	v_cvt_pk_bf16_f32 v51, v56, v57
	global_store_dwordx4 v[64:65], v[48:51], off offset:256
	v_and_b32_e32 v53, 0xffff0000, v165
	v_lshlrev_b32_e32 v54, 16, v166
	v_lshlrev_b32_e32 v50, 16, v164
	v_and_b32_e32 v51, 0xffff0000, v164
	v_and_b32_e32 v55, 0xffff0000, v166
	v_lshlrev_b32_e32 v56, 16, v167
	v_and_b32_e32 v57, 0xffff0000, v167
	v_lshl_add_u64 v[48:49], v[222:223], 0, v[224:225]
	v_pk_fma_f32 v[46:47], v[46:47], v[142:143], v[52:53]
	v_pk_fma_f32 v[44:45], v[44:45], v[140:141], v[50:51]
	v_pk_fma_f32 v[50:51], v[42:43], v[138:139], v[56:57]
	v_pk_fma_f32 v[42:43], v[40:41], v[136:137], v[54:55]
	v_cvt_pk_bf16_f32 v40, v44, v45
	v_cvt_pk_bf16_f32 v41, v46, v47
	v_lshlrev_b32_e32 v44, 16, v162
	v_cvt_pk_bf16_f32 v42, v42, v43
	v_cvt_pk_bf16_f32 v43, v50, v51
	global_store_dwordx4 v[48:49], v[40:43], off
	v_and_b32_e32 v45, 0xffff0000, v162
	v_lshlrev_b32_e32 v46, 16, v163
	v_lshlrev_b32_e32 v40, 16, v160
	v_and_b32_e32 v41, 0xffff0000, v160
	v_and_b32_e32 v47, 0xffff0000, v163
	v_lshlrev_b32_e32 v42, 16, v161
	v_and_b32_e32 v43, 0xffff0000, v161
	v_pk_fma_f32 v[36:37], v[36:37], v[132:133], v[40:41]
	v_pk_fma_f32 v[40:41], v[34:35], v[130:131], v[46:47]
	v_pk_fma_f32 v[34:35], v[32:33], v[128:129], v[44:45]
	v_pk_fma_f32 v[38:39], v[38:39], v[134:135], v[42:43]
	v_cvt_pk_bf16_f32 v32, v36, v37
	v_lshlrev_b32_e32 v36, 16, v157
	v_cvt_pk_bf16_f32 v33, v38, v39
	v_cvt_pk_bf16_f32 v34, v34, v35
	v_cvt_pk_bf16_f32 v35, v40, v41
	global_store_dwordx4 v[48:49], v[32:35], off offset:256
	v_and_b32_e32 v37, 0xffff0000, v157
	v_lshlrev_b32_e32 v38, 16, v158
	v_lshlrev_b32_e32 v34, 16, v156
	v_and_b32_e32 v35, 0xffff0000, v156
	v_and_b32_e32 v39, 0xffff0000, v158
	v_lshlrev_b32_e32 v40, 16, v159
	v_and_b32_e32 v41, 0xffff0000, v159
	v_lshl_add_u64 v[32:33], v[222:223], 0, v[220:221]
	v_pk_fma_f32 v[30:31], v[30:31], v[142:143], v[36:37]
	v_pk_fma_f32 v[28:29], v[28:29], v[140:141], v[34:35]
	v_pk_fma_f32 v[34:35], v[26:27], v[138:139], v[40:41]
	v_pk_fma_f32 v[26:27], v[24:25], v[136:137], v[38:39]
	v_cvt_pk_bf16_f32 v24, v28, v29
	v_cvt_pk_bf16_f32 v25, v30, v31
	v_lshlrev_b32_e32 v28, 16, v154
	v_cvt_pk_bf16_f32 v26, v26, v27
	v_cvt_pk_bf16_f32 v27, v34, v35
	global_store_dwordx4 v[32:33], v[24:27], off
	v_and_b32_e32 v29, 0xffff0000, v154
	v_lshlrev_b32_e32 v30, 16, v155
	v_lshlrev_b32_e32 v24, 16, v152
	v_and_b32_e32 v25, 0xffff0000, v152
	v_and_b32_e32 v31, 0xffff0000, v155
	v_lshlrev_b32_e32 v26, 16, v153
	v_and_b32_e32 v27, 0xffff0000, v153
	v_pk_fma_f32 v[20:21], v[20:21], v[132:133], v[24:25]
	v_pk_fma_f32 v[24:25], v[18:19], v[130:131], v[30:31]
	v_pk_fma_f32 v[18:19], v[16:17], v[128:129], v[28:29]
	v_pk_fma_f32 v[22:23], v[22:23], v[134:135], v[26:27]
	v_cvt_pk_bf16_f32 v16, v20, v21
	v_lshlrev_b32_e32 v20, 16, v149
	v_cvt_pk_bf16_f32 v17, v22, v23
	v_cvt_pk_bf16_f32 v18, v18, v19
	v_cvt_pk_bf16_f32 v19, v24, v25
	global_store_dwordx4 v[32:33], v[16:19], off offset:256
	v_and_b32_e32 v21, 0xffff0000, v149
	v_lshlrev_b32_e32 v22, 16, v150
	v_lshlrev_b32_e32 v18, 16, v148
	v_and_b32_e32 v19, 0xffff0000, v148
	v_and_b32_e32 v23, 0xffff0000, v150
	v_lshlrev_b32_e32 v24, 16, v151
	v_and_b32_e32 v25, 0xffff0000, v151
	v_lshl_add_u64 v[16:17], v[222:223], 0, v[218:219]
	v_pk_fma_f32 v[14:15], v[14:15], v[142:143], v[20:21]
	v_pk_fma_f32 v[12:13], v[12:13], v[140:141], v[18:19]
	v_pk_fma_f32 v[18:19], v[10:11], v[138:139], v[24:25]
	v_pk_fma_f32 v[10:11], v[8:9], v[136:137], v[22:23]
	v_cvt_pk_bf16_f32 v8, v12, v13
	v_cvt_pk_bf16_f32 v9, v14, v15
	v_lshlrev_b32_e32 v12, 16, v146
	v_cvt_pk_bf16_f32 v10, v10, v11
	v_cvt_pk_bf16_f32 v11, v18, v19
	global_store_dwordx4 v[16:17], v[8:11], off
	v_and_b32_e32 v13, 0xffff0000, v146
	v_lshlrev_b32_e32 v14, 16, v147
	v_lshlrev_b32_e32 v8, 16, v144
	v_and_b32_e32 v9, 0xffff0000, v144
	v_and_b32_e32 v15, 0xffff0000, v147
	v_lshlrev_b32_e32 v10, 16, v145
	v_and_b32_e32 v11, 0xffff0000, v145
	v_pk_fma_f32 v[4:5], v[4:5], v[132:133], v[8:9]
	v_pk_fma_f32 v[8:9], v[2:3], v[130:131], v[14:15]
	v_pk_fma_f32 v[2:3], v[0:1], v[128:129], v[12:13]
	v_pk_fma_f32 v[6:7], v[6:7], v[134:135], v[10:11]
	v_cvt_pk_bf16_f32 v0, v4, v5
	s_nop 0
	v_cvt_pk_bf16_f32 v1, v6, v7
	v_cvt_pk_bf16_f32 v2, v2, v3
	v_cvt_pk_bf16_f32 v3, v8, v9
	global_store_dwordx4 v[16:17], v[0:3], off offset:256
	s_cbranch_vccz .LBB0_891
	s_waitcnt vmcnt(0)
	s_cmpk_gt_u32 s33, 0xff
	s_cbranch_scc1 .LBB0_906
	s_barrier

; #define PG8_STAGE(bufoff, gbase, voff) do { _Pragma("unroll") for (int _i = 0; _i < 2; ++_i) \
;         __builtin_amdgcn_global_load_lds((const unsigned*)((const char*)(gbase) + (voff)[_i]), (LAS unsigned*)(lds + (bufoff) + ldsw + _i * 8192), 16, 0, 0); } while (0)
; #define PG8_LDA(dst, b, h) do { _Pragma("unroll") for (int m = 0; m < 4; ++m) _Pragma("unroll") for (int k = 0; k < 2; ++k) dst[m][k] = *(const LAS bf16x8*)(lds + PG8_SA(b, h) + aoff + m * 2048 + k * 1024); } while (0)
; #define PG8_LDB(dst, b, h) do { _Pragma("unroll") for (int n = 0; n < 2; ++n) _Pragma("unroll") for (int k = 0; k < 2; ++k) dst[n][k] = *(const LAS bf16x8*)(lds + PG8_SB(b, h) + boff + n * 2048 + k * 1024); } while (0)
; #define PG8_WAIT_V(n) asm volatile("s_waitcnt vmcnt(" #n ")" ::: "memory")
; #define PG8_WAIT_L(n) asm volatile("s_waitcnt lgkmcnt(" #n ")" ::: "memory")
; #define PG8_BAR __builtin_amdgcn_s_barrier()
; #define PG8_SCHED __builtin_amdgcn_sched_barrier(0)
; template <class Epi, class Sched>
; __device__ __forceinline__ void gemm_phase(LAS unsigned char* lds, const Gemm g, const Sched& S, const Epi& E) {
;     ...
;         const bool has_next = S.next(ui + 1, nxt);
;         const char* nA = has_next ? (const char*)g.A + (size_t)nxt.pm * tstep : cA; const char* nB = has_next ? (const char*)g.Bt + (size_t)nxt.pn * tstep : cB;
;         for (int t = 0; t < nt; t += 2) {
;             const bool last = (t == nt - 2);
;             const char* a1 = cA + (size_t)(t + 1) * kstep;
;             const char* a2 = last ? nA : cA + (size_t)(t + 2) * kstep; const char* b2 = last ? nB : cB + (size_t)(t + 2) * kstep;
;             const char* a3 = a2 + kstep; const char* b3 = b2 + kstep;
;             PG8_LDB(B0, 0, 0); PG8_SCHED; PG8_LDA(At, 0, 0); PG8_STAGE(PG8_SA(1, 1), a1 + hstep, voffA);
;             PG8_WAIT_L(8); PG8_BAR; PG8_WAIT_L(0); PG8_MMA(0, 0, At, B0); PG8_BAR; PG8_SCHED;
;             PG8_LDB(B1, 0, 1); PG8_STAGE(PG8_SB(0, 0), b2, voffB);
;             PG8_BAR; PG8_WAIT_L(0); PG8_MMA(0, 1, At, B1); PG8_BAR;
;             PG8_LDA(At, 0, 1); PG8_STAGE(PG8_SA(0, 0), a2, voffA);
;             PG8_BAR; PG8_WAIT_L(0); PG8_MMA(1, 0, At, B0); PG8_BAR; PG8_SCHED;
;             PG8_STAGE(PG8_SB(0, 1), b2 + hstep, voffB);
;             PG8_WAIT_V(6); PG8_BAR; PG8_MMA(1, 1, At, B1); PG8_BAR;
.LBB0_1020:
	s_ashr_i32 s7, s6, 31
	v_cmp_lt_i64_e32 vcc, s[10:11], v[140:141]
	s_lshl_b64 s[10:11], s[6:7], 19
	s_add_u32 s10, s96, s10
	s_addc_u32 s11, s97, s11
	s_and_b64 s[12:13], vcc, exec
	s_cselect_b32 s7, s11, s17
	s_cselect_b32 s42, s10, s16
	s_ashr_i32 s5, s4, 31
	s_lshl_b64 s[12:13], s[4:5], 19
	s_add_u32 s12, s23, s12
	s_addc_u32 s13, s24, s13
	s_and_b64 s[20:21], vcc, exec
	s_cselect_b32 s5, s13, s19
	s_cselect_b32 s43, s12, s18
	s_add_u32 s16, s16, 0x40080
	s_addc_u32 s17, s17, 0
	s_add_u32 s44, s18, 0x100
	s_addc_u32 s45, s19, 0
	s_mov_b32 s46, -2
	ds_read_b128 v[150:153], v147
	ds_read_b128 v[154:157], v147 offset:1024
	ds_read_b128 v[158:161], v147 offset:2048
	ds_read_b128 v[162:165], v147 offset:3072
	s_add_u32 s18, s16, 0xfffc0080
	s_addc_u32 s19, s17, -1
	s_cmp_eq_u32 s46, 12
	s_cselect_b32 s21, s7, s19
	s_cselect_b32 s20, s42, s18
	s_cselect_b32 s19, s5, s45
	s_cselect_b32 s18, s43, s44
	s_add_i32 m0, s15, 0xc000
	ds_read_b128 v[166:169], v148
	ds_read_b128 v[170:173], v148 offset:1024
	ds_read_b128 v[174:177], v148 offset:2048
	ds_read_b128 v[178:181], v148 offset:3072
	ds_read_b128 v[182:185], v148 offset:4096
	ds_read_b128 v[186:189], v148 offset:5120
	ds_read_b128 v[190:193], v148 offset:6144
	ds_read_b128 v[194:197], v148 offset:7168
	global_load_lds_dwordx4 v136, s[16:17]
	s_add_i32 m0, s15, 0xe000
	s_nop 0
	global_load_lds_dwordx4 v138, s[16:17]
	s_waitcnt lgkmcnt(8)
	s_waitcnt vmcnt(8)
	s_waitcnt lgkmcnt(0)
	s_setprio 1
	s_barrier
	v_mfma_f32_16x16x32_bf16 v[124:127], v[150:153], v[166:169], 0
	v_mfma_f32_16x16x32_bf16 v[116:119], v[158:161], v[166:169], 0
	v_mfma_f32_16x16x32_bf16 v[108:111], v[150:153], v[174:177], 0
	v_mfma_f32_16x16x32_bf16 v[100:103], v[158:161], v[174:177], 0
	v_mfma_f32_16x16x32_bf16 v[92:95], v[150:153], v[182:185], 0
	v_mfma_f32_16x16x32_bf16 v[84:87], v[158:161], v[182:185], 0
	v_mfma_f32_16x16x32_bf16 v[76:79], v[150:153], v[190:193], 0
	v_mfma_f32_16x16x32_bf16 v[68:71], v[158:161], v[190:193], 0
	v_mfma_f32_16x16x32_bf16 v[124:127], v[154:157], v[170:173], v[124:127]
	v_mfma_f32_16x16x32_bf16 v[116:119], v[162:165], v[170:173], v[116:119]
	v_mfma_f32_16x16x32_bf16 v[108:111], v[154:157], v[178:181], v[108:111]
	v_mfma_f32_16x16x32_bf16 v[100:103], v[162:165], v[178:181], v[100:103]
	v_mfma_f32_16x16x32_bf16 v[92:95], v[154:157], v[186:189], v[92:95]
	v_mfma_f32_16x16x32_bf16 v[84:87], v[162:165], v[186:189], v[84:87]
	v_mfma_f32_16x16x32_bf16 v[76:79], v[154:157], v[194:197], v[76:79]
	v_mfma_f32_16x16x32_bf16 v[68:71], v[162:165], v[194:197], v[68:71]
	s_barrier
	s_setprio 0
	s_add_i32 s47, s38, s25
	s_mov_b32 m0, s47
	ds_read_b128 v[202:205], v149
	ds_read_b128 v[206:209], v149 offset:1024
	ds_read_b128 v[210:213], v149 offset:2048
	ds_read_b128 v[214:217], v149 offset:3072
	global_load_lds_dwordx4 v132, s[18:19]
	s_add_i32 m0, s47, 0x2000
	s_nop 0
	global_load_lds_dwordx4 v128, s[18:19]
	s_waitcnt vmcnt(8)
	s_waitcnt lgkmcnt(0)
	s_setprio 1
	s_barrier
	v_mfma_f32_16x16x32_bf16 v[120:123], v[202:205], v[166:169], 0
	v_mfma_f32_16x16x32_bf16 v[112:115], v[210:213], v[166:169], 0
	v_mfma_f32_16x16x32_bf16 v[104:107], v[202:205], v[174:177], 0
	v_mfma_f32_16x16x32_bf16 v[96:99], v[210:213], v[174:177], 0
	v_mfma_f32_16x16x32_bf16 v[88:91], v[202:205], v[182:185], 0
	v_mfma_f32_16x16x32_bf16 v[80:83], v[210:213], v[182:185], 0
	v_mfma_f32_16x16x32_bf16 v[72:75], v[202:205], v[190:193], 0
	v_mfma_f32_16x16x32_bf16 v[64:67], v[210:213], v[190:193], 0
	v_mfma_f32_16x16x32_bf16 v[120:123], v[206:209], v[170:173], v[120:123]
	v_mfma_f32_16x16x32_bf16 v[112:115], v[214:217], v[170:173], v[112:115]
	v_mfma_f32_16x16x32_bf16 v[104:107], v[206:209], v[178:181], v[104:107]
	v_mfma_f32_16x16x32_bf16 v[96:99], v[214:217], v[178:181], v[96:99]
	v_mfma_f32_16x16x32_bf16 v[88:91], v[206:209], v[186:189], v[88:91]
	v_mfma_f32_16x16x32_bf16 v[80:83], v[214:217], v[186:189], v[80:83]
	v_mfma_f32_16x16x32_bf16 v[72:75], v[206:209], v[194:197], v[72:75]
	v_mfma_f32_16x16x32_bf16 v[64:67], v[214:217], v[194:197], v[64:67]
	s_mov_b32 m0, s15
	v_lshl_add_u64 v[220:221], s[20:21], 0, v[134:135]
	s_barrier
	s_setprio 0
	ds_read_b128 v[166:169], v148 offset:16384
	ds_read_b128 v[170:173], v148 offset:17408
	ds_read_b128 v[174:177], v148 offset:18432
	ds_read_b128 v[178:181], v148 offset:19456
	ds_read_b128 v[182:185], v148 offset:20480
	ds_read_b128 v[186:189], v148 offset:21504
	ds_read_b128 v[190:193], v148 offset:22528
	ds_read_b128 v[194:197], v148 offset:23552
	global_load_lds_dwordx4 v134, s[20:21]
	v_lshl_add_u64 v[222:223], s[20:21], 0, v[130:131]
	s_mov_b32 m0, s28
	s_nop 0
	global_load_lds_dwordx4 v130, s[20:21]
	s_waitcnt lgkmcnt(0)
	s_setprio 1
	s_barrier
	v_mfma_f32_16x16x32_bf16 v[60:63], v[150:153], v[166:169], 0
	v_mfma_f32_16x16x32_bf16 v[56:59], v[158:161], v[166:169], 0
	v_mfma_f32_16x16x32_bf16 v[44:47], v[150:153], v[174:177], 0
	v_mfma_f32_16x16x32_bf16 v[40:43], v[158:161], v[174:177], 0
	v_mfma_f32_16x16x32_bf16 v[28:31], v[150:153], v[182:185], 0
	v_mfma_f32_16x16x32_bf16 v[24:27], v[158:161], v[182:185], 0
	v_mfma_f32_16x16x32_bf16 v[12:15], v[150:153], v[190:193], 0
	v_mfma_f32_16x16x32_bf16 v[8:11], v[158:161], v[190:193], 0
	v_mfma_f32_16x16x32_bf16 v[60:63], v[154:157], v[170:173], v[60:63]
	v_mfma_f32_16x16x32_bf16 v[56:59], v[162:165], v[170:173], v[56:59]
	v_mfma_f32_16x16x32_bf16 v[44:47], v[154:157], v[178:181], v[44:47]
	v_mfma_f32_16x16x32_bf16 v[40:43], v[162:165], v[178:181], v[40:43]
	v_mfma_f32_16x16x32_bf16 v[28:31], v[154:157], v[186:189], v[28:31]
	v_mfma_f32_16x16x32_bf16 v[24:27], v[162:165], v[186:189], v[24:27]
	v_mfma_f32_16x16x32_bf16 v[12:15], v[154:157], v[194:197], v[12:15]
	v_mfma_f32_16x16x32_bf16 v[8:11], v[162:165], v[194:197], v[8:11]
	s_barrier
; #define PG8_STAGE(bufoff, gbase, voff) do { _Pragma("unroll") for (int _i = 0; _i < 2; ++_i) \
;         __builtin_amdgcn_global_load_lds((const unsigned*)((const char*)(gbase) + (voff)[_i]), (LAS unsigned*)(lds + (bufoff) + ldsw + _i * 8192), 16, 0, 0); } while (0)
; #define PG8_LDA(dst, b, h) do { _Pragma("unroll") for (int m = 0; m < 4; ++m) _Pragma("unroll") for (int k = 0; k < 2; ++k) dst[m][k] = *(const LAS bf16x8*)(lds + PG8_SA(b, h) + aoff + m * 2048 + k * 1024); } while (0)
; #define PG8_LDB(dst, b, h) do { _Pragma("unroll") for (int n = 0; n < 2; ++n) _Pragma("unroll") for (int k = 0; k < 2; ++k) dst[n][k] = *(const LAS bf16x8*)(lds + PG8_SB(b, h) + boff + n * 2048 + k * 1024); } while (0)
; #define PG8_MMA(ai, bj, At, Bt) do { __builtin_amdgcn_s_setprio(1); _Pragma("unroll") for (int m = 0; m < 4; ++m) _Pragma("unroll") for (int n = 0; n < 2; ++n) _Pragma("unroll") for (int k = 0; k < 2; ++k) \
;         acc[ai][bj][m][n] = __builtin_amdgcn_mfma_f32_16x16x32_bf16(Bt[n][k], At[m][k], acc[ai][bj][m][n], 0, 0, 0); __builtin_amdgcn_s_setprio(0); } while (0)
; #define PG8_WAIT_V(n) asm volatile("s_waitcnt vmcnt(" #n ")" ::: "memory")
; #define PG8_WAIT_L(n) asm volatile("s_waitcnt lgkmcnt(" #n ")" ::: "memory")
; #define PG8_BAR __builtin_amdgcn_s_barrier()
; #define PG8_SCHED __builtin_amdgcn_sched_barrier(0)
; template <class Epi, class Sched>
; __device__ __forceinline__ void gemm_phase(LAS unsigned char* lds, const Gemm g, const Sched& S, const Epi& E) {
;     ...
;             PG8_STAGE(PG8_SB(0, 1), b2 + hstep, voffB);
;             PG8_WAIT_V(6); PG8_BAR; PG8_MMA(1, 1, At, B1); PG8_BAR;
;             PG8_LDB(B0, 1, 0); PG8_SCHED; PG8_LDA(At, 1, 0); PG8_STAGE(PG8_SA(0, 1), a2 + hstep, voffA);
;             PG8_WAIT_L(8); PG8_BAR; PG8_WAIT_L(0); PG8_MMA(0, 0, At, B0); PG8_BAR; PG8_SCHED;
;             PG8_LDB(B1, 1, 1); PG8_STAGE(PG8_SB(1, 0), b3, voffB);
;             PG8_BAR; PG8_WAIT_L(0); PG8_MMA(0, 1, At, B1); PG8_BAR;
;             PG8_LDA(At, 1, 1); PG8_STAGE(PG8_SA(1, 0), a3, voffA);
;             PG8_BAR; PG8_WAIT_L(0); PG8_MMA(1, 0, At, B0); PG8_BAR; PG8_SCHED;
;             PG8_STAGE(PG8_SB(1, 1), b3 + hstep, voffB);
;             PG8_WAIT_V(6); PG8_BAR; PG8_MMA(1, 1, At, B1); PG8_BAR;
	s_setprio 0
	s_add_u32 s48, s18, 0x40000
	s_addc_u32 s49, s19, 0
	s_add_i32 s47, s39, s25
	s_mov_b32 m0, s47
	s_nop 0
	global_load_lds_dwordx4 v132, s[48:49]
	s_add_i32 m0, s47, 0x2000
	s_nop 0
	global_load_lds_dwordx4 v128, s[48:49]
	s_add_u32 s20, s20, 0x40000
	s_addc_u32 s21, s21, 0
	s_mov_b32 m0, s29
	s_nop 0
	global_load_lds_dwordx4 v134, s[20:21]
	s_mov_b32 m0, s30
	s_nop 0
	global_load_lds_dwordx4 v130, s[20:21]
	s_waitcnt vmcnt(10)
	s_setprio 1
	s_barrier
	v_mfma_f32_16x16x32_bf16 v[52:55], v[202:205], v[166:169], 0
	v_mfma_f32_16x16x32_bf16 v[48:51], v[210:213], v[166:169], 0
	v_mfma_f32_16x16x32_bf16 v[36:39], v[202:205], v[174:177], 0
	v_mfma_f32_16x16x32_bf16 v[32:35], v[210:213], v[174:177], 0
	v_mfma_f32_16x16x32_bf16 v[20:23], v[202:205], v[182:185], 0
	v_mfma_f32_16x16x32_bf16 v[16:19], v[210:213], v[182:185], 0
	v_mfma_f32_16x16x32_bf16 v[4:7], v[202:205], v[190:193], 0
	v_mfma_f32_16x16x32_bf16 v[0:3], v[210:213], v[190:193], 0
	v_mfma_f32_16x16x32_bf16 v[52:55], v[206:209], v[170:173], v[52:55]
	v_mfma_f32_16x16x32_bf16 v[48:51], v[214:217], v[170:173], v[48:51]
	v_mfma_f32_16x16x32_bf16 v[36:39], v[206:209], v[178:181], v[36:39]
	v_mfma_f32_16x16x32_bf16 v[32:35], v[214:217], v[178:181], v[32:35]
	v_mfma_f32_16x16x32_bf16 v[20:23], v[206:209], v[186:189], v[20:23]
	v_mfma_f32_16x16x32_bf16 v[16:19], v[214:217], v[186:189], v[16:19]
	v_mfma_f32_16x16x32_bf16 v[4:7], v[206:209], v[194:197], v[4:7]
	v_mfma_f32_16x16x32_bf16 v[0:3], v[214:217], v[194:197], v[0:3]
	s_add_i32 s47, 0, 0x18000
	v_add_u32_e32 v162, s47, v146
	s_barrier
	s_setprio 0
	ds_read_b128 v[150:153], v162
	ds_read_b128 v[154:157], v162 offset:1024
	ds_read_b128 v[158:161], v162 offset:2048
	ds_read_b128 v[162:165], v162 offset:3072
	ds_read_b128 v[166:169], v148 offset:32768
	ds_read_b128 v[170:173], v148 offset:33792
	ds_read_b128 v[174:177], v148 offset:34816
	ds_read_b128 v[178:181], v148 offset:35840
	ds_read_b128 v[182:185], v148 offset:36864
	ds_read_b128 v[186:189], v148 offset:37888
	ds_read_b128 v[190:193], v148 offset:38912
	ds_read_b128 v[194:197], v148 offset:39936
	s_waitcnt lgkmcnt(8)
	s_waitcnt vmcnt(8)
	s_waitcnt lgkmcnt(0)
	s_setprio 1
	s_barrier
	v_mfma_f32_16x16x32_bf16 v[124:127], v[150:153], v[166:169], v[124:127]
	v_mfma_f32_16x16x32_bf16 v[116:119], v[158:161], v[166:169], v[116:119]
	v_mfma_f32_16x16x32_bf16 v[108:111], v[150:153], v[174:177], v[108:111]
	v_mfma_f32_16x16x32_bf16 v[100:103], v[158:161], v[174:177], v[100:103]
	v_mfma_f32_16x16x32_bf16 v[92:95], v[150:153], v[182:185], v[92:95]
	v_mfma_f32_16x16x32_bf16 v[84:87], v[158:161], v[182:185], v[84:87]
	v_mfma_f32_16x16x32_bf16 v[76:79], v[150:153], v[190:193], v[76:79]
	v_mfma_f32_16x16x32_bf16 v[68:71], v[158:161], v[190:193], v[68:71]
	v_mfma_f32_16x16x32_bf16 v[124:127], v[154:157], v[170:173], v[124:127]
	v_mfma_f32_16x16x32_bf16 v[116:119], v[162:165], v[170:173], v[116:119]
	v_mfma_f32_16x16x32_bf16 v[108:111], v[154:157], v[178:181], v[108:111]
	v_mfma_f32_16x16x32_bf16 v[100:103], v[162:165], v[178:181], v[100:103]
	v_mfma_f32_16x16x32_bf16 v[92:95], v[154:157], v[186:189], v[92:95]
	v_mfma_f32_16x16x32_bf16 v[84:87], v[162:165], v[186:189], v[84:87]
	v_mfma_f32_16x16x32_bf16 v[76:79], v[154:157], v[194:197], v[76:79]
	v_mfma_f32_16x16x32_bf16 v[68:71], v[162:165], v[194:197], v[68:71]
	s_barrier
	s_setprio 0
	s_add_i32 s20, 0, 0x1c000
	s_add_i32 s21, s47, s25
	v_add_u32_e32 v214, s20, v146
	s_add_u32 s0, s18, 0x80
	s_addc_u32 s1, s19, 0
	s_mov_b32 m0, s21
	ds_read_b128 v[202:205], v214
	ds_read_b128 v[206:209], v214 offset:1024
	ds_read_b128 v[210:213], v214 offset:2048
	ds_read_b128 v[214:217], v214 offset:3072
	global_load_lds_dwordx4 v132, s[0:1]
	s_add_i32 m0, s21, 0x2000
	s_nop 0
	global_load_lds_dwordx4 v128, s[0:1]
	s_waitcnt vmcnt(8)
	s_waitcnt lgkmcnt(0)
	s_setprio 1
	s_barrier
	v_mfma_f32_16x16x32_bf16 v[120:123], v[202:205], v[166:169], v[120:123]
	v_mfma_f32_16x16x32_bf16 v[112:115], v[210:213], v[166:169], v[112:115]
	v_mfma_f32_16x16x32_bf16 v[104:107], v[202:205], v[174:177], v[104:107]
	v_mfma_f32_16x16x32_bf16 v[96:99], v[210:213], v[174:177], v[96:99]
	v_mfma_f32_16x16x32_bf16 v[88:91], v[202:205], v[182:185], v[88:91]
	v_mfma_f32_16x16x32_bf16 v[80:83], v[210:213], v[182:185], v[80:83]
	v_mfma_f32_16x16x32_bf16 v[72:75], v[202:205], v[190:193], v[72:75]
	v_mfma_f32_16x16x32_bf16 v[64:67], v[210:213], v[190:193], v[64:67]
	v_mfma_f32_16x16x32_bf16 v[120:123], v[206:209], v[170:173], v[120:123]
	v_mfma_f32_16x16x32_bf16 v[112:115], v[214:217], v[170:173], v[112:115]
	v_mfma_f32_16x16x32_bf16 v[104:107], v[206:209], v[178:181], v[104:107]
	v_mfma_f32_16x16x32_bf16 v[96:99], v[214:217], v[178:181], v[96:99]
	v_mfma_f32_16x16x32_bf16 v[88:91], v[206:209], v[186:189], v[88:91]
	v_mfma_f32_16x16x32_bf16 v[80:83], v[214:217], v[186:189], v[80:83]
	v_mfma_f32_16x16x32_bf16 v[72:75], v[206:209], v[194:197], v[72:75]
	v_mfma_f32_16x16x32_bf16 v[64:67], v[214:217], v[194:197], v[64:67]
	s_mov_b32 m0, s35
	s_mov_b64 s[0:1], 0x80
	v_lshl_add_u64 v[198:199], v[220:221], 0, s[0:1]
	s_barrier
	s_setprio 0
	ds_read_b128 v[166:169], v148 offset:49152
	ds_read_b128 v[170:173], v148 offset:50176
	ds_read_b128 v[174:177], v148 offset:51200
	ds_read_b128 v[178:181], v148 offset:52224
	ds_read_b128 v[182:185], v148 offset:53248
	ds_read_b128 v[186:189], v148 offset:54272
	ds_read_b128 v[190:193], v148 offset:55296
	ds_read_b128 v[194:197], v148 offset:56320
	global_load_lds_dwordx4 v[198:199], off
	v_lshl_add_u64 v[198:199], v[222:223], 0, s[0:1]
	s_mov_b32 m0, s36
	s_nop 0
	global_load_lds_dwordx4 v[198:199], off
	s_waitcnt lgkmcnt(0)
	s_setprio 1
	s_barrier
; #define PG8_STAGE(bufoff, gbase, voff) do { _Pragma("unroll") for (int _i = 0; _i < 2; ++_i) \
;         __builtin_amdgcn_global_load_lds((const unsigned*)((const char*)(gbase) + (voff)[_i]), (LAS unsigned*)(lds + (bufoff) + ldsw + _i * 8192), 16, 0, 0); } while (0)
; #define PG8_LDA(dst, b, h) do { _Pragma("unroll") for (int m = 0; m < 4; ++m) _Pragma("unroll") for (int k = 0; k < 2; ++k) dst[m][k] = *(const LAS bf16x8*)(lds + PG8_SA(b, h) + aoff + m * 2048 + k * 1024); } while (0)
; #define PG8_WAIT_V(n) asm volatile("s_waitcnt vmcnt(" #n ")" ::: "memory")
; #define PG8_WAIT_L(n) asm volatile("s_waitcnt lgkmcnt(" #n ")" ::: "memory")
; template <class Epi, class Sched>
; __device__ __forceinline__ void gemm_phase(LAS unsigned char* lds, const Gemm g, const Sched& S, const Epi& E) {
;     ...
;         for (int t = 0; t < nt; t += 2) {
;             const bool last = (t == nt - 2);
;             const char* a1 = cA + (size_t)(t + 1) * kstep;
;             const char* a2 = last ? nA : cA + (size_t)(t + 2) * kstep; const char* b2 = last ? nB : cB + (size_t)(t + 2) * kstep;
;             const char* a3 = a2 + kstep; const char* b3 = b2 + kstep;
;             PG8_LDB(B0, 0, 0); PG8_SCHED; PG8_LDA(At, 0, 0); PG8_STAGE(PG8_SA(1, 1), a1 + hstep, voffA);
;             PG8_WAIT_L(8); PG8_BAR; PG8_WAIT_L(0); PG8_MMA(0, 0, At, B0); PG8_BAR; PG8_SCHED;
;             PG8_LDB(B1, 0, 1); PG8_STAGE(PG8_SB(0, 0), b2, voffB);
;             PG8_BAR; PG8_WAIT_L(0); PG8_MMA(0, 1, At, B1); PG8_BAR;
;             PG8_LDA(At, 0, 1); PG8_STAGE(PG8_SA(0, 0), a2, voffA);
;             PG8_BAR; PG8_WAIT_L(0); PG8_MMA(1, 0, At, B0); PG8_BAR; PG8_SCHED;
;             PG8_STAGE(PG8_SB(0, 1), b2 + hstep, voffB);
;             PG8_WAIT_V(6); PG8_BAR; PG8_MMA(1, 1, At, B1); PG8_BAR;
;             PG8_LDB(B0, 1, 0); PG8_SCHED; PG8_LDA(At, 1, 0); PG8_STAGE(PG8_SA(0, 1), a2 + hstep, voffA);
;             PG8_WAIT_L(8); PG8_BAR; PG8_WAIT_L(0); PG8_MMA(0, 0, At, B0); PG8_BAR; PG8_SCHED;
;             PG8_LDB(B1, 1, 1); PG8_STAGE(PG8_SB(1, 0), b3, voffB);
;             PG8_BAR; PG8_WAIT_L(0); PG8_MMA(0, 1, At, B1); PG8_BAR;
;             PG8_LDA(At, 1, 1); PG8_STAGE(PG8_SA(1, 0), a3, voffA);
;             PG8_BAR; PG8_WAIT_L(0); PG8_MMA(1, 0, At, B0); PG8_BAR; PG8_SCHED;
;             PG8_STAGE(PG8_SB(1, 1), b3 + hstep, voffB);
;             PG8_WAIT_V(6); PG8_BAR; PG8_MMA(1, 1, At, B1); PG8_BAR;
	v_mfma_f32_16x16x32_bf16 v[60:63], v[150:153], v[166:169], v[60:63]
	v_mfma_f32_16x16x32_bf16 v[56:59], v[158:161], v[166:169], v[56:59]
	v_mfma_f32_16x16x32_bf16 v[44:47], v[150:153], v[174:177], v[44:47]
	v_mfma_f32_16x16x32_bf16 v[40:43], v[158:161], v[174:177], v[40:43]
	v_mfma_f32_16x16x32_bf16 v[28:31], v[150:153], v[182:185], v[28:31]
	v_mfma_f32_16x16x32_bf16 v[24:27], v[158:161], v[182:185], v[24:27]
	v_mfma_f32_16x16x32_bf16 v[12:15], v[150:153], v[190:193], v[12:15]
	v_mfma_f32_16x16x32_bf16 v[8:11], v[158:161], v[190:193], v[8:11]
	v_mfma_f32_16x16x32_bf16 v[60:63], v[154:157], v[170:173], v[60:63]
	v_mfma_f32_16x16x32_bf16 v[56:59], v[162:165], v[170:173], v[56:59]
	v_mfma_f32_16x16x32_bf16 v[44:47], v[154:157], v[178:181], v[44:47]
	v_mfma_f32_16x16x32_bf16 v[40:43], v[162:165], v[178:181], v[40:43]
	v_mfma_f32_16x16x32_bf16 v[28:31], v[154:157], v[186:189], v[28:31]
	v_mfma_f32_16x16x32_bf16 v[24:27], v[162:165], v[186:189], v[24:27]
	v_mfma_f32_16x16x32_bf16 v[12:15], v[154:157], v[194:197], v[12:15]
	v_mfma_f32_16x16x32_bf16 v[8:11], v[162:165], v[194:197], v[8:11]
	s_barrier
	s_setprio 0
	s_add_u32 s18, s18, 0x40080
	s_addc_u32 s19, s19, 0
	s_add_i32 s20, s20, s25
	s_mov_b32 m0, s20
	s_nop 0
	global_load_lds_dwordx4 v132, s[18:19]
	s_add_i32 m0, s20, 0x2000
	s_nop 0
	global_load_lds_dwordx4 v128, s[18:19]
	s_waitcnt vmcnt(8)
	s_setprio 1
	s_barrier
	v_mfma_f32_16x16x32_bf16 v[52:55], v[202:205], v[166:169], v[52:55]
	v_mfma_f32_16x16x32_bf16 v[48:51], v[210:213], v[166:169], v[48:51]
	v_mfma_f32_16x16x32_bf16 v[36:39], v[202:205], v[174:177], v[36:39]
	v_mfma_f32_16x16x32_bf16 v[32:35], v[210:213], v[174:177], v[32:35]
	v_mfma_f32_16x16x32_bf16 v[20:23], v[202:205], v[182:185], v[20:23]
	v_mfma_f32_16x16x32_bf16 v[16:19], v[210:213], v[182:185], v[16:19]
	v_mfma_f32_16x16x32_bf16 v[4:7], v[202:205], v[190:193], v[4:7]
	v_mfma_f32_16x16x32_bf16 v[0:3], v[210:213], v[190:193], v[0:3]
	v_mfma_f32_16x16x32_bf16 v[52:55], v[206:209], v[170:173], v[52:55]
	v_mfma_f32_16x16x32_bf16 v[48:51], v[214:217], v[170:173], v[48:51]
	v_mfma_f32_16x16x32_bf16 v[36:39], v[206:209], v[178:181], v[36:39]
	v_mfma_f32_16x16x32_bf16 v[32:35], v[214:217], v[178:181], v[32:35]
	v_mfma_f32_16x16x32_bf16 v[20:23], v[206:209], v[186:189], v[20:23]
	v_mfma_f32_16x16x32_bf16 v[16:19], v[214:217], v[186:189], v[16:19]
	v_mfma_f32_16x16x32_bf16 v[4:7], v[206:209], v[194:197], v[4:7]
	v_mfma_f32_16x16x32_bf16 v[0:3], v[214:217], v[194:197], v[0:3]
	s_add_i32 s46, s46, 2
	s_add_u32 s16, s16, 0x100
	s_addc_u32 s17, s17, 0
	s_add_u32 s44, s44, 0x100
	s_addc_u32 s45, s45, 0
	s_cmp_gt_u32 s46, 13
	s_barrier
	s_setprio 0
.LBB0_1021:
	ds_read_b128 v[150:153], v147
	ds_read_b128 v[154:157], v147 offset:1024
	ds_read_b128 v[158:161], v147 offset:2048
	ds_read_b128 v[162:165], v147 offset:3072
	s_add_u32 s18, s16, 0xfffc0080
	s_addc_u32 s19, s17, -1
	s_cmp_eq_u32 s46, 12
	s_cselect_b32 s21, s7, s19
	s_cselect_b32 s20, s42, s18
	s_cselect_b32 s19, s5, s45
	s_cselect_b32 s18, s43, s44
	s_add_i32 m0, s15, 0xc000
	ds_read_b128 v[166:169], v148
	ds_read_b128 v[170:173], v148 offset:1024
	ds_read_b128 v[174:177], v148 offset:2048
	ds_read_b128 v[178:181], v148 offset:3072
	ds_read_b128 v[182:185], v148 offset:4096
	ds_read_b128 v[186:189], v148 offset:5120
	ds_read_b128 v[190:193], v148 offset:6144
	ds_read_b128 v[194:197], v148 offset:7168
	global_load_lds_dwordx4 v136, s[16:17]
	s_add_i32 m0, s15, 0xe000
	s_nop 0
	global_load_lds_dwordx4 v138, s[16:17]
	s_waitcnt lgkmcnt(8)
	s_waitcnt vmcnt(8)
	s_waitcnt lgkmcnt(0)
	s_setprio 1
	s_barrier
	v_mfma_f32_16x16x32_bf16 v[124:127], v[150:153], v[166:169], v[124:127]
	v_mfma_f32_16x16x32_bf16 v[116:119], v[158:161], v[166:169], v[116:119]
	v_mfma_f32_16x16x32_bf16 v[108:111], v[150:153], v[174:177], v[108:111]
	v_mfma_f32_16x16x32_bf16 v[100:103], v[158:161], v[174:177], v[100:103]
	v_mfma_f32_16x16x32_bf16 v[92:95], v[150:153], v[182:185], v[92:95]
	v_mfma_f32_16x16x32_bf16 v[84:87], v[158:161], v[182:185], v[84:87]
	v_mfma_f32_16x16x32_bf16 v[76:79], v[150:153], v[190:193], v[76:79]
	v_mfma_f32_16x16x32_bf16 v[68:71], v[158:161], v[190:193], v[68:71]
	v_mfma_f32_16x16x32_bf16 v[124:127], v[154:157], v[170:173], v[124:127]
	v_mfma_f32_16x16x32_bf16 v[116:119], v[162:165], v[170:173], v[116:119]
	v_mfma_f32_16x16x32_bf16 v[108:111], v[154:157], v[178:181], v[108:111]
	v_mfma_f32_16x16x32_bf16 v[100:103], v[162:165], v[178:181], v[100:103]
	v_mfma_f32_16x16x32_bf16 v[92:95], v[154:157], v[186:189], v[92:95]
	v_mfma_f32_16x16x32_bf16 v[84:87], v[162:165], v[186:189], v[84:87]
	v_mfma_f32_16x16x32_bf16 v[76:79], v[154:157], v[194:197], v[76:79]
	v_mfma_f32_16x16x32_bf16 v[68:71], v[162:165], v[194:197], v[68:71]
	s_barrier
	s_setprio 0
	s_add_i32 s47, s38, s25
	s_mov_b32 m0, s47
	ds_read_b128 v[202:205], v149
	ds_read_b128 v[206:209], v149 offset:1024
	ds_read_b128 v[210:213], v149 offset:2048
	ds_read_b128 v[214:217], v149 offset:3072
	global_load_lds_dwordx4 v132, s[18:19]
	s_add_i32 m0, s47, 0x2000
	s_nop 0
	global_load_lds_dwordx4 v128, s[18:19]
	s_waitcnt vmcnt(8)
	s_waitcnt lgkmcnt(0)
	s_setprio 1
	s_barrier
; #define PG8_STAGE(bufoff, gbase, voff) do { _Pragma("unroll") for (int _i = 0; _i < 2; ++_i) \
;         __builtin_amdgcn_global_load_lds((const unsigned*)((const char*)(gbase) + (voff)[_i]), (LAS unsigned*)(lds + (bufoff) + ldsw + _i * 8192), 16, 0, 0); } while (0)
; #define PG8_LDA(dst, b, h) do { _Pragma("unroll") for (int m = 0; m < 4; ++m) _Pragma("unroll") for (int k = 0; k < 2; ++k) dst[m][k] = *(const LAS bf16x8*)(lds + PG8_SA(b, h) + aoff + m * 2048 + k * 1024); } while (0)
; #define PG8_LDB(dst, b, h) do { _Pragma("unroll") for (int n = 0; n < 2; ++n) _Pragma("unroll") for (int k = 0; k < 2; ++k) dst[n][k] = *(const LAS bf16x8*)(lds + PG8_SB(b, h) + boff + n * 2048 + k * 1024); } while (0)
; #define PG8_MMA(ai, bj, At, Bt) do { __builtin_amdgcn_s_setprio(1); _Pragma("unroll") for (int m = 0; m < 4; ++m) _Pragma("unroll") for (int n = 0; n < 2; ++n) _Pragma("unroll") for (int k = 0; k < 2; ++k) \
;         acc[ai][bj][m][n] = __builtin_amdgcn_mfma_f32_16x16x32_bf16(Bt[n][k], At[m][k], acc[ai][bj][m][n], 0, 0, 0); __builtin_amdgcn_s_setprio(0); } while (0)
; #define PG8_WAIT_V(n) asm volatile("s_waitcnt vmcnt(" #n ")" ::: "memory")
; #define PG8_WAIT_L(n) asm volatile("s_waitcnt lgkmcnt(" #n ")" ::: "memory")
; #define PG8_BAR __builtin_amdgcn_s_barrier()
; #define PG8_SCHED __builtin_amdgcn_sched_barrier(0)
; template <class Epi, class Sched>
; __device__ __forceinline__ void gemm_phase(LAS unsigned char* lds, const Gemm g, const Sched& S, const Epi& E) {
;     ...
;             PG8_WAIT_L(8); PG8_BAR; PG8_WAIT_L(0); PG8_MMA(0, 0, At, B0); PG8_BAR; PG8_SCHED;
;             PG8_LDB(B1, 0, 1); PG8_STAGE(PG8_SB(0, 0), b2, voffB);
;             PG8_BAR; PG8_WAIT_L(0); PG8_MMA(0, 1, At, B1); PG8_BAR;
;             PG8_LDA(At, 0, 1); PG8_STAGE(PG8_SA(0, 0), a2, voffA);
;             PG8_BAR; PG8_WAIT_L(0); PG8_MMA(1, 0, At, B0); PG8_BAR; PG8_SCHED;
;             PG8_STAGE(PG8_SB(0, 1), b2 + hstep, voffB);
;             PG8_WAIT_V(6); PG8_BAR; PG8_MMA(1, 1, At, B1); PG8_BAR;
;             PG8_LDB(B0, 1, 0); PG8_SCHED; PG8_LDA(At, 1, 0); PG8_STAGE(PG8_SA(0, 1), a2 + hstep, voffA);
;             PG8_WAIT_L(8); PG8_BAR; PG8_WAIT_L(0); PG8_MMA(0, 0, At, B0); PG8_BAR; PG8_SCHED;
	v_mfma_f32_16x16x32_bf16 v[120:123], v[202:205], v[166:169], v[120:123]
	v_mfma_f32_16x16x32_bf16 v[112:115], v[210:213], v[166:169], v[112:115]
	v_mfma_f32_16x16x32_bf16 v[104:107], v[202:205], v[174:177], v[104:107]
	v_mfma_f32_16x16x32_bf16 v[96:99], v[210:213], v[174:177], v[96:99]
	v_mfma_f32_16x16x32_bf16 v[88:91], v[202:205], v[182:185], v[88:91]
	v_mfma_f32_16x16x32_bf16 v[80:83], v[210:213], v[182:185], v[80:83]
	v_mfma_f32_16x16x32_bf16 v[72:75], v[202:205], v[190:193], v[72:75]
	v_mfma_f32_16x16x32_bf16 v[64:67], v[210:213], v[190:193], v[64:67]
	v_mfma_f32_16x16x32_bf16 v[120:123], v[206:209], v[170:173], v[120:123]
	v_mfma_f32_16x16x32_bf16 v[112:115], v[214:217], v[170:173], v[112:115]
	v_mfma_f32_16x16x32_bf16 v[104:107], v[206:209], v[178:181], v[104:107]
	v_mfma_f32_16x16x32_bf16 v[96:99], v[214:217], v[178:181], v[96:99]
	v_mfma_f32_16x16x32_bf16 v[88:91], v[206:209], v[186:189], v[88:91]
	v_mfma_f32_16x16x32_bf16 v[80:83], v[214:217], v[186:189], v[80:83]
	v_mfma_f32_16x16x32_bf16 v[72:75], v[206:209], v[194:197], v[72:75]
	v_mfma_f32_16x16x32_bf16 v[64:67], v[214:217], v[194:197], v[64:67]
	s_mov_b32 m0, s15
	v_lshl_add_u64 v[220:221], s[20:21], 0, v[134:135]
	s_barrier
	s_setprio 0
	ds_read_b128 v[166:169], v148 offset:16384
	ds_read_b128 v[170:173], v148 offset:17408
	ds_read_b128 v[174:177], v148 offset:18432
	ds_read_b128 v[178:181], v148 offset:19456
	ds_read_b128 v[182:185], v148 offset:20480
	ds_read_b128 v[186:189], v148 offset:21504
	ds_read_b128 v[190:193], v148 offset:22528
	ds_read_b128 v[194:197], v148 offset:23552
	global_load_lds_dwordx4 v134, s[20:21]
	v_lshl_add_u64 v[222:223], s[20:21], 0, v[130:131]
	s_mov_b32 m0, s28
	s_nop 0
	global_load_lds_dwordx4 v130, s[20:21]
	s_waitcnt lgkmcnt(0)
	s_setprio 1
	s_barrier
	v_mfma_f32_16x16x32_bf16 v[60:63], v[150:153], v[166:169], v[60:63]
	v_mfma_f32_16x16x32_bf16 v[56:59], v[158:161], v[166:169], v[56:59]
	v_mfma_f32_16x16x32_bf16 v[44:47], v[150:153], v[174:177], v[44:47]
	v_mfma_f32_16x16x32_bf16 v[40:43], v[158:161], v[174:177], v[40:43]
	v_mfma_f32_16x16x32_bf16 v[28:31], v[150:153], v[182:185], v[28:31]
	v_mfma_f32_16x16x32_bf16 v[24:27], v[158:161], v[182:185], v[24:27]
	v_mfma_f32_16x16x32_bf16 v[12:15], v[150:153], v[190:193], v[12:15]
	v_mfma_f32_16x16x32_bf16 v[8:11], v[158:161], v[190:193], v[8:11]
	v_mfma_f32_16x16x32_bf16 v[60:63], v[154:157], v[170:173], v[60:63]
	v_mfma_f32_16x16x32_bf16 v[56:59], v[162:165], v[170:173], v[56:59]
	v_mfma_f32_16x16x32_bf16 v[44:47], v[154:157], v[178:181], v[44:47]
	v_mfma_f32_16x16x32_bf16 v[40:43], v[162:165], v[178:181], v[40:43]
	v_mfma_f32_16x16x32_bf16 v[28:31], v[154:157], v[186:189], v[28:31]
	v_mfma_f32_16x16x32_bf16 v[24:27], v[162:165], v[186:189], v[24:27]
	v_mfma_f32_16x16x32_bf16 v[12:15], v[154:157], v[194:197], v[12:15]
	v_mfma_f32_16x16x32_bf16 v[8:11], v[162:165], v[194:197], v[8:11]
	s_barrier
	s_setprio 0
	s_add_u32 s48, s18, 0x40000
	s_addc_u32 s49, s19, 0
	s_add_i32 s47, s39, s25
	s_mov_b32 m0, s47
	s_nop 0
	global_load_lds_dwordx4 v132, s[48:49]
	s_add_i32 m0, s47, 0x2000
	s_nop 0
	global_load_lds_dwordx4 v128, s[48:49]
	s_add_u32 s20, s20, 0x40000
	s_addc_u32 s21, s21, 0
	s_mov_b32 m0, s29
	s_nop 0
	global_load_lds_dwordx4 v134, s[20:21]
	s_mov_b32 m0, s30
	s_nop 0
	global_load_lds_dwordx4 v130, s[20:21]
	s_waitcnt vmcnt(10)
	s_setprio 1
	s_barrier
	v_mfma_f32_16x16x32_bf16 v[52:55], v[202:205], v[166:169], v[52:55]
	v_mfma_f32_16x16x32_bf16 v[48:51], v[210:213], v[166:169], v[48:51]
	v_mfma_f32_16x16x32_bf16 v[36:39], v[202:205], v[174:177], v[36:39]
	v_mfma_f32_16x16x32_bf16 v[32:35], v[210:213], v[174:177], v[32:35]
	v_mfma_f32_16x16x32_bf16 v[20:23], v[202:205], v[182:185], v[20:23]
	v_mfma_f32_16x16x32_bf16 v[16:19], v[210:213], v[182:185], v[16:19]
	v_mfma_f32_16x16x32_bf16 v[4:7], v[202:205], v[190:193], v[4:7]
	v_mfma_f32_16x16x32_bf16 v[0:3], v[210:213], v[190:193], v[0:3]
	v_mfma_f32_16x16x32_bf16 v[52:55], v[206:209], v[170:173], v[52:55]
	v_mfma_f32_16x16x32_bf16 v[48:51], v[214:217], v[170:173], v[48:51]
	v_mfma_f32_16x16x32_bf16 v[36:39], v[206:209], v[178:181], v[36:39]
	v_mfma_f32_16x16x32_bf16 v[32:35], v[214:217], v[178:181], v[32:35]
	v_mfma_f32_16x16x32_bf16 v[20:23], v[206:209], v[186:189], v[20:23]
	v_mfma_f32_16x16x32_bf16 v[16:19], v[214:217], v[186:189], v[16:19]
	v_mfma_f32_16x16x32_bf16 v[4:7], v[206:209], v[194:197], v[4:7]
	v_mfma_f32_16x16x32_bf16 v[0:3], v[214:217], v[194:197], v[0:3]
	s_add_i32 s47, 0, 0x18000
	v_add_u32_e32 v162, s47, v146
	s_barrier
	s_setprio 0
	ds_read_b128 v[150:153], v162
	ds_read_b128 v[154:157], v162 offset:1024
	ds_read_b128 v[158:161], v162 offset:2048
	ds_read_b128 v[162:165], v162 offset:3072
	ds_read_b128 v[166:169], v148 offset:32768
	ds_read_b128 v[170:173], v148 offset:33792
	ds_read_b128 v[174:177], v148 offset:34816
	ds_read_b128 v[178:181], v148 offset:35840
	ds_read_b128 v[182:185], v148 offset:36864
	ds_read_b128 v[186:189], v148 offset:37888
	ds_read_b128 v[190:193], v148 offset:38912
	ds_read_b128 v[194:197], v148 offset:39936
	s_waitcnt lgkmcnt(8)
	s_waitcnt vmcnt(8)
	s_waitcnt lgkmcnt(0)
	s_setprio 1
	s_barrier
; #define PG8_STAGE(bufoff, gbase, voff) do { _Pragma("unroll") for (int _i = 0; _i < 2; ++_i) \
;         __builtin_amdgcn_global_load_lds((const unsigned*)((const char*)(gbase) + (voff)[_i]), (LAS unsigned*)(lds + (bufoff) + ldsw + _i * 8192), 16, 0, 0); } while (0)
; #define PG8_LDA(dst, b, h) do { _Pragma("unroll") for (int m = 0; m < 4; ++m) _Pragma("unroll") for (int k = 0; k < 2; ++k) dst[m][k] = *(const LAS bf16x8*)(lds + PG8_SA(b, h) + aoff + m * 2048 + k * 1024); } while (0)
; #define PG8_LDB(dst, b, h) do { _Pragma("unroll") for (int n = 0; n < 2; ++n) _Pragma("unroll") for (int k = 0; k < 2; ++k) dst[n][k] = *(const LAS bf16x8*)(lds + PG8_SB(b, h) + boff + n * 2048 + k * 1024); } while (0)
; #define PG8_MMA(ai, bj, At, Bt) do { __builtin_amdgcn_s_setprio(1); _Pragma("unroll") for (int m = 0; m < 4; ++m) _Pragma("unroll") for (int n = 0; n < 2; ++n) _Pragma("unroll") for (int k = 0; k < 2; ++k) \
;         acc[ai][bj][m][n] = __builtin_amdgcn_mfma_f32_16x16x32_bf16(Bt[n][k], At[m][k], acc[ai][bj][m][n], 0, 0, 0); __builtin_amdgcn_s_setprio(0); } while (0)
; #define PG8_WAIT_V(n) asm volatile("s_waitcnt vmcnt(" #n ")" ::: "memory")
; #define PG8_WAIT_L(n) asm volatile("s_waitcnt lgkmcnt(" #n ")" ::: "memory")
; #define PG8_BAR __builtin_amdgcn_s_barrier()
; #define PG8_SCHED __builtin_amdgcn_sched_barrier(0)
; template <class Epi, class Sched>
; __device__ __forceinline__ void gemm_phase(LAS unsigned char* lds, const Gemm g, const Sched& S, const Epi& E) {
;     ...
;             PG8_WAIT_L(8); PG8_BAR; PG8_WAIT_L(0); PG8_MMA(0, 0, At, B0); PG8_BAR; PG8_SCHED;
;             PG8_LDB(B1, 1, 1); PG8_STAGE(PG8_SB(1, 0), b3, voffB);
;             PG8_BAR; PG8_WAIT_L(0); PG8_MMA(0, 1, At, B1); PG8_BAR;
;             PG8_LDA(At, 1, 1); PG8_STAGE(PG8_SA(1, 0), a3, voffA);
;             PG8_BAR; PG8_WAIT_L(0); PG8_MMA(1, 0, At, B0); PG8_BAR; PG8_SCHED;
;             PG8_STAGE(PG8_SB(1, 1), b3 + hstep, voffB);
;             PG8_WAIT_V(6); PG8_BAR; PG8_MMA(1, 1, At, B1); PG8_BAR;
;         }
	v_mfma_f32_16x16x32_bf16 v[124:127], v[150:153], v[166:169], v[124:127]
	v_mfma_f32_16x16x32_bf16 v[116:119], v[158:161], v[166:169], v[116:119]
	v_mfma_f32_16x16x32_bf16 v[108:111], v[150:153], v[174:177], v[108:111]
	v_mfma_f32_16x16x32_bf16 v[100:103], v[158:161], v[174:177], v[100:103]
	v_mfma_f32_16x16x32_bf16 v[92:95], v[150:153], v[182:185], v[92:95]
	v_mfma_f32_16x16x32_bf16 v[84:87], v[158:161], v[182:185], v[84:87]
	v_mfma_f32_16x16x32_bf16 v[76:79], v[150:153], v[190:193], v[76:79]
	v_mfma_f32_16x16x32_bf16 v[68:71], v[158:161], v[190:193], v[68:71]
	v_mfma_f32_16x16x32_bf16 v[124:127], v[154:157], v[170:173], v[124:127]
	v_mfma_f32_16x16x32_bf16 v[116:119], v[162:165], v[170:173], v[116:119]
	v_mfma_f32_16x16x32_bf16 v[108:111], v[154:157], v[178:181], v[108:111]
	v_mfma_f32_16x16x32_bf16 v[100:103], v[162:165], v[178:181], v[100:103]
	v_mfma_f32_16x16x32_bf16 v[92:95], v[154:157], v[186:189], v[92:95]
	v_mfma_f32_16x16x32_bf16 v[84:87], v[162:165], v[186:189], v[84:87]
	v_mfma_f32_16x16x32_bf16 v[76:79], v[154:157], v[194:197], v[76:79]
	v_mfma_f32_16x16x32_bf16 v[68:71], v[162:165], v[194:197], v[68:71]
	s_barrier
	s_setprio 0
	s_add_i32 s20, 0, 0x1c000
	s_add_i32 s21, s47, s25
	v_add_u32_e32 v214, s20, v146
	s_add_u32 s0, s18, 0x80
	s_addc_u32 s1, s19, 0
	s_mov_b32 m0, s21
	ds_read_b128 v[202:205], v214
	ds_read_b128 v[206:209], v214 offset:1024
	ds_read_b128 v[210:213], v214 offset:2048
	ds_read_b128 v[214:217], v214 offset:3072
	global_load_lds_dwordx4 v132, s[0:1]
	s_add_i32 m0, s21, 0x2000
	s_nop 0
	global_load_lds_dwordx4 v128, s[0:1]
	s_waitcnt vmcnt(8)
	s_waitcnt lgkmcnt(0)
	s_setprio 1
	s_barrier
	v_mfma_f32_16x16x32_bf16 v[120:123], v[202:205], v[166:169], v[120:123]
	v_mfma_f32_16x16x32_bf16 v[112:115], v[210:213], v[166:169], v[112:115]
	v_mfma_f32_16x16x32_bf16 v[104:107], v[202:205], v[174:177], v[104:107]
	v_mfma_f32_16x16x32_bf16 v[96:99], v[210:213], v[174:177], v[96:99]
	v_mfma_f32_16x16x32_bf16 v[88:91], v[202:205], v[182:185], v[88:91]
	v_mfma_f32_16x16x32_bf16 v[80:83], v[210:213], v[182:185], v[80:83]
	v_mfma_f32_16x16x32_bf16 v[72:75], v[202:205], v[190:193], v[72:75]
	v_mfma_f32_16x16x32_bf16 v[64:67], v[210:213], v[190:193], v[64:67]
	v_mfma_f32_16x16x32_bf16 v[120:123], v[206:209], v[170:173], v[120:123]
	v_mfma_f32_16x16x32_bf16 v[112:115], v[214:217], v[170:173], v[112:115]
	v_mfma_f32_16x16x32_bf16 v[104:107], v[206:209], v[178:181], v[104:107]
	v_mfma_f32_16x16x32_bf16 v[96:99], v[214:217], v[178:181], v[96:99]
	v_mfma_f32_16x16x32_bf16 v[88:91], v[206:209], v[186:189], v[88:91]
	v_mfma_f32_16x16x32_bf16 v[80:83], v[214:217], v[186:189], v[80:83]
	v_mfma_f32_16x16x32_bf16 v[72:75], v[206:209], v[194:197], v[72:75]
	v_mfma_f32_16x16x32_bf16 v[64:67], v[214:217], v[194:197], v[64:67]
	s_mov_b32 m0, s35
	s_mov_b64 s[0:1], 0x80
	v_lshl_add_u64 v[198:199], v[220:221], 0, s[0:1]
	s_barrier
	s_setprio 0
	ds_read_b128 v[166:169], v148 offset:49152
	ds_read_b128 v[170:173], v148 offset:50176
	ds_read_b128 v[174:177], v148 offset:51200
	ds_read_b128 v[178:181], v148 offset:52224
	ds_read_b128 v[182:185], v148 offset:53248
	ds_read_b128 v[186:189], v148 offset:54272
	ds_read_b128 v[190:193], v148 offset:55296
	ds_read_b128 v[194:197], v148 offset:56320
	global_load_lds_dwordx4 v[198:199], off
	v_lshl_add_u64 v[198:199], v[222:223], 0, s[0:1]
	s_mov_b32 m0, s36
	s_nop 0
	global_load_lds_dwordx4 v[198:199], off
	s_waitcnt lgkmcnt(0)
	s_setprio 1
	s_barrier
	v_mfma_f32_16x16x32_bf16 v[60:63], v[150:153], v[166:169], v[60:63]
	v_mfma_f32_16x16x32_bf16 v[56:59], v[158:161], v[166:169], v[56:59]
	v_mfma_f32_16x16x32_bf16 v[44:47], v[150:153], v[174:177], v[44:47]
	v_mfma_f32_16x16x32_bf16 v[40:43], v[158:161], v[174:177], v[40:43]
	v_mfma_f32_16x16x32_bf16 v[28:31], v[150:153], v[182:185], v[28:31]
	v_mfma_f32_16x16x32_bf16 v[24:27], v[158:161], v[182:185], v[24:27]
	v_mfma_f32_16x16x32_bf16 v[12:15], v[150:153], v[190:193], v[12:15]
	v_mfma_f32_16x16x32_bf16 v[8:11], v[158:161], v[190:193], v[8:11]
	v_mfma_f32_16x16x32_bf16 v[60:63], v[154:157], v[170:173], v[60:63]
	v_mfma_f32_16x16x32_bf16 v[56:59], v[162:165], v[170:173], v[56:59]
	v_mfma_f32_16x16x32_bf16 v[44:47], v[154:157], v[178:181], v[44:47]
	v_mfma_f32_16x16x32_bf16 v[40:43], v[162:165], v[178:181], v[40:43]
	v_mfma_f32_16x16x32_bf16 v[28:31], v[154:157], v[186:189], v[28:31]
	v_mfma_f32_16x16x32_bf16 v[24:27], v[162:165], v[186:189], v[24:27]
	v_mfma_f32_16x16x32_bf16 v[12:15], v[154:157], v[194:197], v[12:15]
	v_mfma_f32_16x16x32_bf16 v[8:11], v[162:165], v[194:197], v[8:11]
	s_barrier
	s_setprio 0
	s_add_u32 s18, s18, 0x40080
	s_addc_u32 s19, s19, 0
	s_add_i32 s20, s20, s25
	s_mov_b32 m0, s20
	s_nop 0
	global_load_lds_dwordx4 v132, s[18:19]
	s_add_i32 m0, s20, 0x2000
	s_nop 0
	global_load_lds_dwordx4 v128, s[18:19]
	s_waitcnt vmcnt(8)
	s_setprio 1
	s_barrier
	v_mfma_f32_16x16x32_bf16 v[52:55], v[202:205], v[166:169], v[52:55]
	v_mfma_f32_16x16x32_bf16 v[48:51], v[210:213], v[166:169], v[48:51]
	v_mfma_f32_16x16x32_bf16 v[36:39], v[202:205], v[174:177], v[36:39]
	v_mfma_f32_16x16x32_bf16 v[32:35], v[210:213], v[174:177], v[32:35]
	v_mfma_f32_16x16x32_bf16 v[20:23], v[202:205], v[182:185], v[20:23]
	v_mfma_f32_16x16x32_bf16 v[16:19], v[210:213], v[182:185], v[16:19]
	v_mfma_f32_16x16x32_bf16 v[4:7], v[202:205], v[190:193], v[4:7]
	v_mfma_f32_16x16x32_bf16 v[0:3], v[210:213], v[190:193], v[0:3]
	v_mfma_f32_16x16x32_bf16 v[52:55], v[206:209], v[170:173], v[52:55]
	v_mfma_f32_16x16x32_bf16 v[48:51], v[214:217], v[170:173], v[48:51]
	v_mfma_f32_16x16x32_bf16 v[36:39], v[206:209], v[178:181], v[36:39]
	v_mfma_f32_16x16x32_bf16 v[32:35], v[214:217], v[178:181], v[32:35]
	v_mfma_f32_16x16x32_bf16 v[20:23], v[206:209], v[186:189], v[20:23]
	v_mfma_f32_16x16x32_bf16 v[16:19], v[214:217], v[186:189], v[16:19]
	v_mfma_f32_16x16x32_bf16 v[4:7], v[206:209], v[194:197], v[4:7]
	v_mfma_f32_16x16x32_bf16 v[0:3], v[214:217], v[194:197], v[0:3]
	s_setprio 0
	s_add_i32 s46, s46, 2
	s_add_u32 s16, s16, 0x100
	s_addc_u32 s17, s17, 0
	s_add_u32 s44, s44, 0x100
	s_addc_u32 s45, s45, 0
	s_cmp_gt_u32 s46, 13
	s_cbranch_scc1 .Lconc_last_g11
	s_barrier
	s_branch .LBB0_1021

; #define PG8_STAGE(bufoff, gbase, voff) do { _Pragma("unroll") for (int _i = 0; _i < 2; ++_i) \
;         __builtin_amdgcn_global_load_lds((const unsigned*)((const char*)(gbase) + (voff)[_i]), (LAS unsigned*)(lds + (bufoff) + ldsw + _i * 8192), 16, 0, 0); } while (0)
; #define PG8_LDA(dst, b, h) do { _Pragma("unroll") for (int m = 0; m < 4; ++m) _Pragma("unroll") for (int k = 0; k < 2; ++k) dst[m][k] = *(const LAS bf16x8*)(lds + PG8_SA(b, h) + aoff + m * 2048 + k * 1024); } while (0)
; #define PG8_LDB(dst, b, h) do { _Pragma("unroll") for (int n = 0; n < 2; ++n) _Pragma("unroll") for (int k = 0; k < 2; ++k) dst[n][k] = *(const LAS bf16x8*)(lds + PG8_SB(b, h) + boff + n * 2048 + k * 1024); } while (0)
; #define PG8_WAIT_V(n) asm volatile("s_waitcnt vmcnt(" #n ")" ::: "memory")
; #define PG8_WAIT_L(n) asm volatile("s_waitcnt lgkmcnt(" #n ")" ::: "memory")
; #define PG8_BAR __builtin_amdgcn_s_barrier()
; #define PG8_SCHED __builtin_amdgcn_sched_barrier(0)
; template <class Epi, class Sched>
; __device__ __forceinline__ void gemm_phase(LAS unsigned char* lds, const Gemm g, const Sched& S, const Epi& E) {
;     ...
;         const bool has_next = S.next(ui + 1, nxt);
;         const char* nA = has_next ? (const char*)g.A + (size_t)nxt.pm * tstep : cA; const char* nB = has_next ? (const char*)g.Bt + (size_t)nxt.pn * tstep : cB;
;         for (int t = 0; t < nt; t += 2) {
;             const bool last = (t == nt - 2);
;             const char* a1 = cA + (size_t)(t + 1) * kstep;
;             const char* a2 = last ? nA : cA + (size_t)(t + 2) * kstep; const char* b2 = last ? nB : cB + (size_t)(t + 2) * kstep;
;             const char* a3 = a2 + kstep; const char* b3 = b2 + kstep;
;             PG8_LDB(B0, 0, 0); PG8_SCHED; PG8_LDA(At, 0, 0); PG8_STAGE(PG8_SA(1, 1), a1 + hstep, voffA);
;             PG8_WAIT_L(8); PG8_BAR; PG8_WAIT_L(0); PG8_MMA(0, 0, At, B0); PG8_BAR; PG8_SCHED;
;             PG8_LDB(B1, 0, 1); PG8_STAGE(PG8_SB(0, 0), b2, voffB);
;             PG8_BAR; PG8_WAIT_L(0); PG8_MMA(0, 1, At, B1); PG8_BAR;
;             PG8_LDA(At, 0, 1); PG8_STAGE(PG8_SA(0, 0), a2, voffA);
;             PG8_BAR; PG8_WAIT_L(0); PG8_MMA(1, 0, At, B0); PG8_BAR; PG8_SCHED;
;             PG8_STAGE(PG8_SB(0, 1), b2 + hstep, voffB);
;             PG8_WAIT_V(6); PG8_BAR; PG8_MMA(1, 1, At, B1); PG8_BAR;
.LBB0_1096:
	s_add_u32 s54, s24, 0x100
	s_addc_u32 s55, s25, 0
	s_mov_b32 s56, -2
	ds_read_b128 v[128:131], v241
	ds_read_b128 v[132:135], v241 offset:1024
	ds_read_b128 v[136:139], v241 offset:2048
	ds_read_b128 v[140:143], v241 offset:3072
	s_add_u32 s24, s22, 0x100
	s_addc_u32 s25, s23, 0
	s_cmp_eq_u32 s56, 40
	s_cselect_b32 s29, s5, s25
	s_cselect_b32 s28, s4, s24
	s_cselect_b32 s27, s7, s55
	s_cselect_b32 s26, s6, s54
	v_lshl_add_u64 v[176:177], s[22:23], 0, v[196:197]
	s_add_i32 m0, s35, 0xc000
	ds_read_b128 v[144:147], v242
	ds_read_b128 v[148:151], v242 offset:1024
	ds_read_b128 v[152:155], v242 offset:2048
	ds_read_b128 v[156:159], v242 offset:3072
	ds_read_b128 v[160:163], v242 offset:4096
	ds_read_b128 v[164:167], v242 offset:5120
	ds_read_b128 v[168:171], v242 offset:6144
	ds_read_b128 v[172:175], v242 offset:7168
	global_load_lds_dwordx4 v[176:177], off
	v_lshl_add_u64 v[176:177], s[22:23], 0, v[198:199]
	s_add_i32 m0, s35, 0xe000
	s_nop 0
	global_load_lds_dwordx4 v[176:177], off
	s_waitcnt lgkmcnt(8)
	s_waitcnt vmcnt(8)
	s_waitcnt lgkmcnt(0)
	s_setprio 1
	s_barrier
	v_mfma_f32_16x16x32_bf16 v[124:127], v[128:131], v[144:147], 0
	v_mfma_f32_16x16x32_bf16 v[120:123], v[136:139], v[144:147], 0
	v_mfma_f32_16x16x32_bf16 v[108:111], v[128:131], v[152:155], 0
	v_mfma_f32_16x16x32_bf16 v[104:107], v[136:139], v[152:155], 0
	v_mfma_f32_16x16x32_bf16 v[92:95], v[128:131], v[160:163], 0
	v_mfma_f32_16x16x32_bf16 v[88:91], v[136:139], v[160:163], 0
	v_mfma_f32_16x16x32_bf16 v[76:79], v[128:131], v[168:171], 0
	v_mfma_f32_16x16x32_bf16 v[72:75], v[136:139], v[168:171], 0
	v_mfma_f32_16x16x32_bf16 v[124:127], v[132:135], v[148:151], v[124:127]
	v_mfma_f32_16x16x32_bf16 v[120:123], v[140:143], v[148:151], v[120:123]
	v_mfma_f32_16x16x32_bf16 v[108:111], v[132:135], v[156:159], v[108:111]
	v_mfma_f32_16x16x32_bf16 v[104:107], v[140:143], v[156:159], v[104:107]
	v_mfma_f32_16x16x32_bf16 v[92:95], v[132:135], v[164:167], v[92:95]
	v_mfma_f32_16x16x32_bf16 v[88:91], v[140:143], v[164:167], v[88:91]
	v_mfma_f32_16x16x32_bf16 v[76:79], v[132:135], v[172:175], v[76:79]
	v_mfma_f32_16x16x32_bf16 v[72:75], v[140:143], v[172:175], v[72:75]
	s_barrier
	s_setprio 0
	s_add_i32 s22, s48, s34
	s_mov_b32 m0, s22
	ds_read_b128 v[176:179], v243
	ds_read_b128 v[180:183], v243 offset:1024
	ds_read_b128 v[184:187], v243 offset:2048
	ds_read_b128 v[206:209], v243 offset:3072
	global_load_lds_dwordx4 v190, s[26:27]
	s_add_i32 m0, s22, 0x2000
	s_nop 0
	global_load_lds_dwordx4 v194, s[26:27]
	s_waitcnt vmcnt(8)
	s_waitcnt lgkmcnt(0)
	s_setprio 1
	s_barrier
	v_mfma_f32_16x16x32_bf16 v[116:119], v[176:179], v[144:147], 0
	v_mfma_f32_16x16x32_bf16 v[112:115], v[184:187], v[144:147], 0
	v_mfma_f32_16x16x32_bf16 v[100:103], v[176:179], v[152:155], 0
	v_mfma_f32_16x16x32_bf16 v[96:99], v[184:187], v[152:155], 0
	v_mfma_f32_16x16x32_bf16 v[84:87], v[176:179], v[160:163], 0
	v_mfma_f32_16x16x32_bf16 v[80:83], v[184:187], v[160:163], 0
	v_mfma_f32_16x16x32_bf16 v[68:71], v[176:179], v[168:171], 0
	v_mfma_f32_16x16x32_bf16 v[64:67], v[184:187], v[168:171], 0
	v_mfma_f32_16x16x32_bf16 v[116:119], v[180:183], v[148:151], v[116:119]
	v_mfma_f32_16x16x32_bf16 v[112:115], v[206:209], v[148:151], v[112:115]
	v_mfma_f32_16x16x32_bf16 v[100:103], v[180:183], v[156:159], v[100:103]
	v_mfma_f32_16x16x32_bf16 v[96:99], v[206:209], v[156:159], v[96:99]
	v_mfma_f32_16x16x32_bf16 v[84:87], v[180:183], v[164:167], v[84:87]
	v_mfma_f32_16x16x32_bf16 v[80:83], v[206:209], v[164:167], v[80:83]
	v_mfma_f32_16x16x32_bf16 v[68:71], v[180:183], v[172:175], v[68:71]
	v_mfma_f32_16x16x32_bf16 v[64:67], v[206:209], v[172:175], v[64:67]
	s_mov_b32 m0, s35
	v_lshl_add_u64 v[214:215], s[28:29], 0, v[188:189]
	s_barrier
	s_setprio 0
	ds_read_b128 v[144:147], v242 offset:16384
	ds_read_b128 v[148:151], v242 offset:17408
	ds_read_b128 v[152:155], v242 offset:18432
	ds_read_b128 v[156:159], v242 offset:19456
	ds_read_b128 v[160:163], v242 offset:20480
	ds_read_b128 v[164:167], v242 offset:21504
	ds_read_b128 v[168:171], v242 offset:22528
	ds_read_b128 v[172:175], v242 offset:23552
	global_load_lds_dwordx4 v188, s[28:29]
	v_lshl_add_u64 v[216:217], s[28:29], 0, v[192:193]
	s_mov_b32 m0, s36
	s_nop 0
	global_load_lds_dwordx4 v192, s[28:29]
	s_waitcnt lgkmcnt(0)
	s_setprio 1
	s_barrier
	v_mfma_f32_16x16x32_bf16 v[60:63], v[128:131], v[144:147], 0
	v_mfma_f32_16x16x32_bf16 v[56:59], v[136:139], v[144:147], 0
	v_mfma_f32_16x16x32_bf16 v[44:47], v[128:131], v[152:155], 0
	v_mfma_f32_16x16x32_bf16 v[40:43], v[136:139], v[152:155], 0
	v_mfma_f32_16x16x32_bf16 v[28:31], v[128:131], v[160:163], 0
	v_mfma_f32_16x16x32_bf16 v[24:27], v[136:139], v[160:163], 0
	v_mfma_f32_16x16x32_bf16 v[12:15], v[128:131], v[168:171], 0
	v_mfma_f32_16x16x32_bf16 v[8:11], v[136:139], v[168:171], 0
	v_mfma_f32_16x16x32_bf16 v[60:63], v[132:135], v[148:151], v[60:63]
	v_mfma_f32_16x16x32_bf16 v[56:59], v[140:143], v[148:151], v[56:59]
	v_mfma_f32_16x16x32_bf16 v[44:47], v[132:135], v[156:159], v[44:47]
	v_mfma_f32_16x16x32_bf16 v[40:43], v[140:143], v[156:159], v[40:43]
	v_mfma_f32_16x16x32_bf16 v[28:31], v[132:135], v[164:167], v[28:31]
	v_mfma_f32_16x16x32_bf16 v[24:27], v[140:143], v[164:167], v[24:27]
	v_mfma_f32_16x16x32_bf16 v[12:15], v[132:135], v[172:175], v[12:15]
	v_mfma_f32_16x16x32_bf16 v[8:11], v[140:143], v[172:175], v[8:11]
	s_barrier
	s_setprio 0
	s_add_u32 s22, s26, 0xb0000
	s_addc_u32 s23, s27, 0
	s_add_i32 s57, s49, s34
	s_mov_b32 m0, s57
	s_nop 0
	global_load_lds_dwordx4 v190, s[22:23]
	s_add_i32 m0, s57, 0x2000
	s_nop 0
	global_load_lds_dwordx4 v194, s[22:23]
	s_add_u32 s22, s28, 0xb0000
	s_addc_u32 s23, s29, 0
	s_mov_b32 m0, s37
	s_nop 0
	global_load_lds_dwordx4 v188, s[22:23]
	s_mov_b32 m0, s38
	s_nop 0
	global_load_lds_dwordx4 v192, s[22:23]
	s_waitcnt vmcnt(10)
	s_setprio 1
	s_barrier
; #define PG8_STAGE(bufoff, gbase, voff) do { _Pragma("unroll") for (int _i = 0; _i < 2; ++_i) \
;         __builtin_amdgcn_global_load_lds((const unsigned*)((const char*)(gbase) + (voff)[_i]), (LAS unsigned*)(lds + (bufoff) + ldsw + _i * 8192), 16, 0, 0); } while (0)
; #define PG8_LDA(dst, b, h) do { _Pragma("unroll") for (int m = 0; m < 4; ++m) _Pragma("unroll") for (int k = 0; k < 2; ++k) dst[m][k] = *(const LAS bf16x8*)(lds + PG8_SA(b, h) + aoff + m * 2048 + k * 1024); } while (0)
; #define PG8_LDB(dst, b, h) do { _Pragma("unroll") for (int n = 0; n < 2; ++n) _Pragma("unroll") for (int k = 0; k < 2; ++k) dst[n][k] = *(const LAS bf16x8*)(lds + PG8_SB(b, h) + boff + n * 2048 + k * 1024); } while (0)
; #define PG8_MMA(ai, bj, At, Bt) do { __builtin_amdgcn_s_setprio(1); _Pragma("unroll") for (int m = 0; m < 4; ++m) _Pragma("unroll") for (int n = 0; n < 2; ++n) _Pragma("unroll") for (int k = 0; k < 2; ++k) \
;         acc[ai][bj][m][n] = __builtin_amdgcn_mfma_f32_16x16x32_bf16(Bt[n][k], At[m][k], acc[ai][bj][m][n], 0, 0, 0); __builtin_amdgcn_s_setprio(0); } while (0)
; #define PG8_WAIT_V(n) asm volatile("s_waitcnt vmcnt(" #n ")" ::: "memory")
; #define PG8_WAIT_L(n) asm volatile("s_waitcnt lgkmcnt(" #n ")" ::: "memory")
; #define PG8_BAR __builtin_amdgcn_s_barrier()
; #define PG8_SCHED __builtin_amdgcn_sched_barrier(0)
; template <class Epi, class Sched>
; __device__ __forceinline__ void gemm_phase(LAS unsigned char* lds, const Gemm g, const Sched& S, const Epi& E) {
;     ...
;             PG8_WAIT_V(6); PG8_BAR; PG8_MMA(1, 1, At, B1); PG8_BAR;
;             PG8_LDB(B0, 1, 0); PG8_SCHED; PG8_LDA(At, 1, 0); PG8_STAGE(PG8_SA(0, 1), a2 + hstep, voffA);
;             PG8_WAIT_L(8); PG8_BAR; PG8_WAIT_L(0); PG8_MMA(0, 0, At, B0); PG8_BAR; PG8_SCHED;
;             PG8_LDB(B1, 1, 1); PG8_STAGE(PG8_SB(1, 0), b3, voffB);
;             PG8_BAR; PG8_WAIT_L(0); PG8_MMA(0, 1, At, B1); PG8_BAR;
;             PG8_LDA(At, 1, 1); PG8_STAGE(PG8_SA(1, 0), a3, voffA);
;             PG8_BAR; PG8_WAIT_L(0); PG8_MMA(1, 0, At, B0); PG8_BAR; PG8_SCHED;
	v_mfma_f32_16x16x32_bf16 v[52:55], v[176:179], v[144:147], 0
	v_mfma_f32_16x16x32_bf16 v[48:51], v[184:187], v[144:147], 0
	v_mfma_f32_16x16x32_bf16 v[36:39], v[176:179], v[152:155], 0
	v_mfma_f32_16x16x32_bf16 v[32:35], v[184:187], v[152:155], 0
	v_mfma_f32_16x16x32_bf16 v[20:23], v[176:179], v[160:163], 0
	v_mfma_f32_16x16x32_bf16 v[16:19], v[184:187], v[160:163], 0
	v_mfma_f32_16x16x32_bf16 v[4:7], v[176:179], v[168:171], 0
	v_mfma_f32_16x16x32_bf16 v[0:3], v[184:187], v[168:171], 0
	v_mfma_f32_16x16x32_bf16 v[52:55], v[180:183], v[148:151], v[52:55]
	v_mfma_f32_16x16x32_bf16 v[48:51], v[206:209], v[148:151], v[48:51]
	v_mfma_f32_16x16x32_bf16 v[36:39], v[180:183], v[156:159], v[36:39]
	v_mfma_f32_16x16x32_bf16 v[32:35], v[206:209], v[156:159], v[32:35]
	v_mfma_f32_16x16x32_bf16 v[20:23], v[180:183], v[164:167], v[20:23]
	v_mfma_f32_16x16x32_bf16 v[16:19], v[206:209], v[164:167], v[16:19]
	v_mfma_f32_16x16x32_bf16 v[4:7], v[180:183], v[172:175], v[4:7]
	v_mfma_f32_16x16x32_bf16 v[0:3], v[206:209], v[172:175], v[0:3]
	s_add_i32 s57, 0, 0x18000
	v_add_u32_e32 v140, s57, v240
	s_barrier
	s_setprio 0
	ds_read_b128 v[128:131], v140
	ds_read_b128 v[132:135], v140 offset:1024
	ds_read_b128 v[136:139], v140 offset:2048
	ds_read_b128 v[140:143], v140 offset:3072
	ds_read_b128 v[144:147], v242 offset:32768
	ds_read_b128 v[148:151], v242 offset:33792
	ds_read_b128 v[152:155], v242 offset:34816
	ds_read_b128 v[156:159], v242 offset:35840
	ds_read_b128 v[160:163], v242 offset:36864
	ds_read_b128 v[164:167], v242 offset:37888
	ds_read_b128 v[168:171], v242 offset:38912
	ds_read_b128 v[172:175], v242 offset:39936
	s_waitcnt lgkmcnt(8)
	s_waitcnt vmcnt(8)
	s_waitcnt lgkmcnt(0)
	s_setprio 1
	s_barrier
	v_mfma_f32_16x16x32_bf16 v[124:127], v[128:131], v[144:147], v[124:127]
	v_mfma_f32_16x16x32_bf16 v[120:123], v[136:139], v[144:147], v[120:123]
	v_mfma_f32_16x16x32_bf16 v[108:111], v[128:131], v[152:155], v[108:111]
	v_mfma_f32_16x16x32_bf16 v[104:107], v[136:139], v[152:155], v[104:107]
	v_mfma_f32_16x16x32_bf16 v[92:95], v[128:131], v[160:163], v[92:95]
	v_mfma_f32_16x16x32_bf16 v[88:91], v[136:139], v[160:163], v[88:91]
	v_mfma_f32_16x16x32_bf16 v[76:79], v[128:131], v[168:171], v[76:79]
	v_mfma_f32_16x16x32_bf16 v[72:75], v[136:139], v[168:171], v[72:75]
	v_mfma_f32_16x16x32_bf16 v[124:127], v[132:135], v[148:151], v[124:127]
	v_mfma_f32_16x16x32_bf16 v[120:123], v[140:143], v[148:151], v[120:123]
	v_mfma_f32_16x16x32_bf16 v[108:111], v[132:135], v[156:159], v[108:111]
	v_mfma_f32_16x16x32_bf16 v[104:107], v[140:143], v[156:159], v[104:107]
	v_mfma_f32_16x16x32_bf16 v[92:95], v[132:135], v[164:167], v[92:95]
	v_mfma_f32_16x16x32_bf16 v[88:91], v[140:143], v[164:167], v[88:91]
	v_mfma_f32_16x16x32_bf16 v[76:79], v[132:135], v[172:175], v[76:79]
	v_mfma_f32_16x16x32_bf16 v[72:75], v[140:143], v[172:175], v[72:75]
	s_barrier
	s_setprio 0
	s_add_i32 s28, 0, 0x1c000
	s_add_i32 s22, s57, s34
	v_add_u32_e32 v206, s28, v240
	s_add_u32 s0, s26, 0x80
	s_addc_u32 s1, s27, 0
	s_mov_b32 m0, s22
	ds_read_b128 v[176:179], v206
	ds_read_b128 v[180:183], v206 offset:1024
	ds_read_b128 v[184:187], v206 offset:2048
	ds_read_b128 v[206:209], v206 offset:3072
	global_load_lds_dwordx4 v190, s[0:1]
	s_add_i32 m0, s22, 0x2000
	s_nop 0
	global_load_lds_dwordx4 v194, s[0:1]
	s_waitcnt vmcnt(8)
	s_waitcnt lgkmcnt(0)
	s_setprio 1
	s_barrier
	v_mfma_f32_16x16x32_bf16 v[116:119], v[176:179], v[144:147], v[116:119]
	v_mfma_f32_16x16x32_bf16 v[112:115], v[184:187], v[144:147], v[112:115]
	v_mfma_f32_16x16x32_bf16 v[100:103], v[176:179], v[152:155], v[100:103]
	v_mfma_f32_16x16x32_bf16 v[96:99], v[184:187], v[152:155], v[96:99]
	v_mfma_f32_16x16x32_bf16 v[84:87], v[176:179], v[160:163], v[84:87]
	v_mfma_f32_16x16x32_bf16 v[80:83], v[184:187], v[160:163], v[80:83]
	v_mfma_f32_16x16x32_bf16 v[68:71], v[176:179], v[168:171], v[68:71]
	v_mfma_f32_16x16x32_bf16 v[64:67], v[184:187], v[168:171], v[64:67]
	v_mfma_f32_16x16x32_bf16 v[116:119], v[180:183], v[148:151], v[116:119]
	v_mfma_f32_16x16x32_bf16 v[112:115], v[206:209], v[148:151], v[112:115]
	v_mfma_f32_16x16x32_bf16 v[100:103], v[180:183], v[156:159], v[100:103]
	v_mfma_f32_16x16x32_bf16 v[96:99], v[206:209], v[156:159], v[96:99]
	v_mfma_f32_16x16x32_bf16 v[84:87], v[180:183], v[164:167], v[84:87]
	v_mfma_f32_16x16x32_bf16 v[80:83], v[206:209], v[164:167], v[80:83]
	v_mfma_f32_16x16x32_bf16 v[68:71], v[180:183], v[172:175], v[68:71]
	v_mfma_f32_16x16x32_bf16 v[64:67], v[206:209], v[172:175], v[64:67]
	s_mov_b32 m0, s44
	s_mov_b64 s[0:1], 0x80
	v_lshl_add_u64 v[210:211], v[214:215], 0, s[0:1]
	s_barrier
	s_setprio 0
	ds_read_b128 v[144:147], v242 offset:49152
	ds_read_b128 v[148:151], v242 offset:50176
	ds_read_b128 v[152:155], v242 offset:51200
	ds_read_b128 v[156:159], v242 offset:52224
	ds_read_b128 v[160:163], v242 offset:53248
	ds_read_b128 v[164:167], v242 offset:54272
	ds_read_b128 v[168:171], v242 offset:55296
	ds_read_b128 v[172:175], v242 offset:56320
	global_load_lds_dwordx4 v[210:211], off
	v_lshl_add_u64 v[210:211], v[216:217], 0, s[0:1]
	s_mov_b32 m0, s45
	s_nop 0
	global_load_lds_dwordx4 v[210:211], off
	s_waitcnt lgkmcnt(0)
	s_setprio 1
	s_barrier
; #define PG8_STAGE(bufoff, gbase, voff) do { _Pragma("unroll") for (int _i = 0; _i < 2; ++_i) \
;         __builtin_amdgcn_global_load_lds((const unsigned*)((const char*)(gbase) + (voff)[_i]), (LAS unsigned*)(lds + (bufoff) + ldsw + _i * 8192), 16, 0, 0); } while (0)
; #define PG8_LDA(dst, b, h) do { _Pragma("unroll") for (int m = 0; m < 4; ++m) _Pragma("unroll") for (int k = 0; k < 2; ++k) dst[m][k] = *(const LAS bf16x8*)(lds + PG8_SA(b, h) + aoff + m * 2048 + k * 1024); } while (0)
; #define PG8_WAIT_V(n) asm volatile("s_waitcnt vmcnt(" #n ")" ::: "memory")
; #define PG8_WAIT_L(n) asm volatile("s_waitcnt lgkmcnt(" #n ")" ::: "memory")
; template <class Epi, class Sched>
; __device__ __forceinline__ void gemm_phase(LAS unsigned char* lds, const Gemm g, const Sched& S, const Epi& E) {
;     ...
;         for (int t = 0; t < nt; t += 2) {
;             const bool last = (t == nt - 2);
;             const char* a1 = cA + (size_t)(t + 1) * kstep;
;             const char* a2 = last ? nA : cA + (size_t)(t + 2) * kstep; const char* b2 = last ? nB : cB + (size_t)(t + 2) * kstep;
;             const char* a3 = a2 + kstep; const char* b3 = b2 + kstep;
;             PG8_LDB(B0, 0, 0); PG8_SCHED; PG8_LDA(At, 0, 0); PG8_STAGE(PG8_SA(1, 1), a1 + hstep, voffA);
;             PG8_WAIT_L(8); PG8_BAR; PG8_WAIT_L(0); PG8_MMA(0, 0, At, B0); PG8_BAR; PG8_SCHED;
;             PG8_LDB(B1, 0, 1); PG8_STAGE(PG8_SB(0, 0), b2, voffB);
;             PG8_BAR; PG8_WAIT_L(0); PG8_MMA(0, 1, At, B1); PG8_BAR;
;             PG8_LDA(At, 0, 1); PG8_STAGE(PG8_SA(0, 0), a2, voffA);
;             PG8_BAR; PG8_WAIT_L(0); PG8_MMA(1, 0, At, B0); PG8_BAR; PG8_SCHED;
;             PG8_STAGE(PG8_SB(0, 1), b2 + hstep, voffB);
;             PG8_WAIT_V(6); PG8_BAR; PG8_MMA(1, 1, At, B1); PG8_BAR;
;             PG8_LDB(B0, 1, 0); PG8_SCHED; PG8_LDA(At, 1, 0); PG8_STAGE(PG8_SA(0, 1), a2 + hstep, voffA);
;             PG8_WAIT_L(8); PG8_BAR; PG8_WAIT_L(0); PG8_MMA(0, 0, At, B0); PG8_BAR; PG8_SCHED;
;             PG8_LDB(B1, 1, 1); PG8_STAGE(PG8_SB(1, 0), b3, voffB);
;             PG8_BAR; PG8_WAIT_L(0); PG8_MMA(0, 1, At, B1); PG8_BAR;
;             PG8_LDA(At, 1, 1); PG8_STAGE(PG8_SA(1, 0), a3, voffA);
;             PG8_BAR; PG8_WAIT_L(0); PG8_MMA(1, 0, At, B0); PG8_BAR; PG8_SCHED;
;             PG8_STAGE(PG8_SB(1, 1), b3 + hstep, voffB);
;             PG8_WAIT_V(6); PG8_BAR; PG8_MMA(1, 1, At, B1); PG8_BAR;
	v_mfma_f32_16x16x32_bf16 v[60:63], v[128:131], v[144:147], v[60:63]
	v_mfma_f32_16x16x32_bf16 v[56:59], v[136:139], v[144:147], v[56:59]
	v_mfma_f32_16x16x32_bf16 v[44:47], v[128:131], v[152:155], v[44:47]
	v_mfma_f32_16x16x32_bf16 v[40:43], v[136:139], v[152:155], v[40:43]
	v_mfma_f32_16x16x32_bf16 v[28:31], v[128:131], v[160:163], v[28:31]
	v_mfma_f32_16x16x32_bf16 v[24:27], v[136:139], v[160:163], v[24:27]
	v_mfma_f32_16x16x32_bf16 v[12:15], v[128:131], v[168:171], v[12:15]
	v_mfma_f32_16x16x32_bf16 v[8:11], v[136:139], v[168:171], v[8:11]
	v_mfma_f32_16x16x32_bf16 v[60:63], v[132:135], v[148:151], v[60:63]
	v_mfma_f32_16x16x32_bf16 v[56:59], v[140:143], v[148:151], v[56:59]
	v_mfma_f32_16x16x32_bf16 v[44:47], v[132:135], v[156:159], v[44:47]
	v_mfma_f32_16x16x32_bf16 v[40:43], v[140:143], v[156:159], v[40:43]
	v_mfma_f32_16x16x32_bf16 v[28:31], v[132:135], v[164:167], v[28:31]
	v_mfma_f32_16x16x32_bf16 v[24:27], v[140:143], v[164:167], v[24:27]
	v_mfma_f32_16x16x32_bf16 v[12:15], v[132:135], v[172:175], v[12:15]
	v_mfma_f32_16x16x32_bf16 v[8:11], v[140:143], v[172:175], v[8:11]
	s_barrier
	s_setprio 0
	s_add_u32 s22, s26, 0xb0080
	s_addc_u32 s23, s27, 0
	s_add_i32 s26, s28, s34
	s_mov_b32 m0, s26
	s_nop 0
	global_load_lds_dwordx4 v190, s[22:23]
	s_add_i32 m0, s26, 0x2000
	s_nop 0
	global_load_lds_dwordx4 v194, s[22:23]
	s_waitcnt vmcnt(8)
	s_setprio 1
	s_barrier
	v_mfma_f32_16x16x32_bf16 v[52:55], v[176:179], v[144:147], v[52:55]
	v_mfma_f32_16x16x32_bf16 v[48:51], v[184:187], v[144:147], v[48:51]
	v_mfma_f32_16x16x32_bf16 v[36:39], v[176:179], v[152:155], v[36:39]
	v_mfma_f32_16x16x32_bf16 v[32:35], v[184:187], v[152:155], v[32:35]
	v_mfma_f32_16x16x32_bf16 v[20:23], v[176:179], v[160:163], v[20:23]
	v_mfma_f32_16x16x32_bf16 v[16:19], v[184:187], v[160:163], v[16:19]
	v_mfma_f32_16x16x32_bf16 v[4:7], v[176:179], v[168:171], v[4:7]
	v_mfma_f32_16x16x32_bf16 v[0:3], v[184:187], v[168:171], v[0:3]
	v_mfma_f32_16x16x32_bf16 v[52:55], v[180:183], v[148:151], v[52:55]
	v_mfma_f32_16x16x32_bf16 v[48:51], v[206:209], v[148:151], v[48:51]
	v_mfma_f32_16x16x32_bf16 v[36:39], v[180:183], v[156:159], v[36:39]
	v_mfma_f32_16x16x32_bf16 v[32:35], v[206:209], v[156:159], v[32:35]
	v_mfma_f32_16x16x32_bf16 v[20:23], v[180:183], v[164:167], v[20:23]
	v_mfma_f32_16x16x32_bf16 v[16:19], v[206:209], v[164:167], v[16:19]
	v_mfma_f32_16x16x32_bf16 v[4:7], v[180:183], v[172:175], v[4:7]
	v_mfma_f32_16x16x32_bf16 v[0:3], v[206:209], v[172:175], v[0:3]
	s_add_i32 s56, s56, 2
	s_add_u32 s54, s54, 0x100
	s_addc_u32 s55, s55, 0
	s_cmp_gt_u32 s56, 41
	s_mov_b64 s[22:23], s[24:25]
	s_barrier
	s_setprio 0
.LBB0_1097:
	ds_read_b128 v[128:131], v241
	ds_read_b128 v[132:135], v241 offset:1024
	ds_read_b128 v[136:139], v241 offset:2048
	ds_read_b128 v[140:143], v241 offset:3072
	s_add_u32 s24, s22, 0x100
	s_addc_u32 s25, s23, 0
	s_cmp_eq_u32 s56, 40
	s_cselect_b32 s29, s5, s25
	s_cselect_b32 s28, s4, s24
	s_cselect_b32 s27, s7, s55
	s_cselect_b32 s26, s6, s54
	v_lshl_add_u64 v[176:177], s[22:23], 0, v[196:197]
	s_add_i32 m0, s35, 0xc000
	ds_read_b128 v[144:147], v242
	ds_read_b128 v[148:151], v242 offset:1024
	ds_read_b128 v[152:155], v242 offset:2048
	ds_read_b128 v[156:159], v242 offset:3072
	ds_read_b128 v[160:163], v242 offset:4096
	ds_read_b128 v[164:167], v242 offset:5120
	ds_read_b128 v[168:171], v242 offset:6144
	ds_read_b128 v[172:175], v242 offset:7168
	global_load_lds_dwordx4 v[176:177], off
	v_lshl_add_u64 v[176:177], s[22:23], 0, v[198:199]
	s_add_i32 m0, s35, 0xe000
	s_nop 0
	global_load_lds_dwordx4 v[176:177], off
	s_waitcnt lgkmcnt(8)
	s_waitcnt vmcnt(8)
	s_waitcnt lgkmcnt(0)
	s_setprio 1
	s_barrier
	v_mfma_f32_16x16x32_bf16 v[124:127], v[128:131], v[144:147], v[124:127]
	v_mfma_f32_16x16x32_bf16 v[120:123], v[136:139], v[144:147], v[120:123]
	v_mfma_f32_16x16x32_bf16 v[108:111], v[128:131], v[152:155], v[108:111]
	v_mfma_f32_16x16x32_bf16 v[104:107], v[136:139], v[152:155], v[104:107]
	v_mfma_f32_16x16x32_bf16 v[92:95], v[128:131], v[160:163], v[92:95]
	v_mfma_f32_16x16x32_bf16 v[88:91], v[136:139], v[160:163], v[88:91]
	v_mfma_f32_16x16x32_bf16 v[76:79], v[128:131], v[168:171], v[76:79]
	v_mfma_f32_16x16x32_bf16 v[72:75], v[136:139], v[168:171], v[72:75]
	v_mfma_f32_16x16x32_bf16 v[124:127], v[132:135], v[148:151], v[124:127]
	v_mfma_f32_16x16x32_bf16 v[120:123], v[140:143], v[148:151], v[120:123]
	v_mfma_f32_16x16x32_bf16 v[108:111], v[132:135], v[156:159], v[108:111]
	v_mfma_f32_16x16x32_bf16 v[104:107], v[140:143], v[156:159], v[104:107]
	v_mfma_f32_16x16x32_bf16 v[92:95], v[132:135], v[164:167], v[92:95]
	v_mfma_f32_16x16x32_bf16 v[88:91], v[140:143], v[164:167], v[88:91]
	v_mfma_f32_16x16x32_bf16 v[76:79], v[132:135], v[172:175], v[76:79]
	v_mfma_f32_16x16x32_bf16 v[72:75], v[140:143], v[172:175], v[72:75]
	s_barrier
	s_setprio 0
	s_add_i32 s22, s48, s34
	s_mov_b32 m0, s22
	ds_read_b128 v[176:179], v243
	ds_read_b128 v[180:183], v243 offset:1024
	ds_read_b128 v[184:187], v243 offset:2048
	ds_read_b128 v[206:209], v243 offset:3072
	global_load_lds_dwordx4 v190, s[26:27]
	s_add_i32 m0, s22, 0x2000
	s_nop 0
	global_load_lds_dwordx4 v194, s[26:27]
	s_waitcnt vmcnt(8)
	s_waitcnt lgkmcnt(0)
	s_setprio 1
	s_barrier
; #define PG8_STAGE(bufoff, gbase, voff) do { _Pragma("unroll") for (int _i = 0; _i < 2; ++_i) \
;         __builtin_amdgcn_global_load_lds((const unsigned*)((const char*)(gbase) + (voff)[_i]), (LAS unsigned*)(lds + (bufoff) + ldsw + _i * 8192), 16, 0, 0); } while (0)
; #define PG8_LDA(dst, b, h) do { _Pragma("unroll") for (int m = 0; m < 4; ++m) _Pragma("unroll") for (int k = 0; k < 2; ++k) dst[m][k] = *(const LAS bf16x8*)(lds + PG8_SA(b, h) + aoff + m * 2048 + k * 1024); } while (0)
; #define PG8_LDB(dst, b, h) do { _Pragma("unroll") for (int n = 0; n < 2; ++n) _Pragma("unroll") for (int k = 0; k < 2; ++k) dst[n][k] = *(const LAS bf16x8*)(lds + PG8_SB(b, h) + boff + n * 2048 + k * 1024); } while (0)
; #define PG8_MMA(ai, bj, At, Bt) do { __builtin_amdgcn_s_setprio(1); _Pragma("unroll") for (int m = 0; m < 4; ++m) _Pragma("unroll") for (int n = 0; n < 2; ++n) _Pragma("unroll") for (int k = 0; k < 2; ++k) \
;         acc[ai][bj][m][n] = __builtin_amdgcn_mfma_f32_16x16x32_bf16(Bt[n][k], At[m][k], acc[ai][bj][m][n], 0, 0, 0); __builtin_amdgcn_s_setprio(0); } while (0)
; #define PG8_WAIT_V(n) asm volatile("s_waitcnt vmcnt(" #n ")" ::: "memory")
; #define PG8_WAIT_L(n) asm volatile("s_waitcnt lgkmcnt(" #n ")" ::: "memory")
; #define PG8_BAR __builtin_amdgcn_s_barrier()
; #define PG8_SCHED __builtin_amdgcn_sched_barrier(0)
; template <class Epi, class Sched>
; __device__ __forceinline__ void gemm_phase(LAS unsigned char* lds, const Gemm g, const Sched& S, const Epi& E) {
;     ...
;             PG8_LDB(B1, 0, 1); PG8_STAGE(PG8_SB(0, 0), b2, voffB);
;             PG8_BAR; PG8_WAIT_L(0); PG8_MMA(0, 1, At, B1); PG8_BAR;
;             PG8_LDA(At, 0, 1); PG8_STAGE(PG8_SA(0, 0), a2, voffA);
;             PG8_BAR; PG8_WAIT_L(0); PG8_MMA(1, 0, At, B0); PG8_BAR; PG8_SCHED;
;             PG8_STAGE(PG8_SB(0, 1), b2 + hstep, voffB);
;             PG8_WAIT_V(6); PG8_BAR; PG8_MMA(1, 1, At, B1); PG8_BAR;
;             PG8_LDB(B0, 1, 0); PG8_SCHED; PG8_LDA(At, 1, 0); PG8_STAGE(PG8_SA(0, 1), a2 + hstep, voffA);
;             PG8_WAIT_L(8); PG8_BAR; PG8_WAIT_L(0); PG8_MMA(0, 0, At, B0); PG8_BAR; PG8_SCHED;
	v_mfma_f32_16x16x32_bf16 v[116:119], v[176:179], v[144:147], v[116:119]
	v_mfma_f32_16x16x32_bf16 v[112:115], v[184:187], v[144:147], v[112:115]
	v_mfma_f32_16x16x32_bf16 v[100:103], v[176:179], v[152:155], v[100:103]
	v_mfma_f32_16x16x32_bf16 v[96:99], v[184:187], v[152:155], v[96:99]
	v_mfma_f32_16x16x32_bf16 v[84:87], v[176:179], v[160:163], v[84:87]
	v_mfma_f32_16x16x32_bf16 v[80:83], v[184:187], v[160:163], v[80:83]
	v_mfma_f32_16x16x32_bf16 v[68:71], v[176:179], v[168:171], v[68:71]
	v_mfma_f32_16x16x32_bf16 v[64:67], v[184:187], v[168:171], v[64:67]
	v_mfma_f32_16x16x32_bf16 v[116:119], v[180:183], v[148:151], v[116:119]
	v_mfma_f32_16x16x32_bf16 v[112:115], v[206:209], v[148:151], v[112:115]
	v_mfma_f32_16x16x32_bf16 v[100:103], v[180:183], v[156:159], v[100:103]
	v_mfma_f32_16x16x32_bf16 v[96:99], v[206:209], v[156:159], v[96:99]
	v_mfma_f32_16x16x32_bf16 v[84:87], v[180:183], v[164:167], v[84:87]
	v_mfma_f32_16x16x32_bf16 v[80:83], v[206:209], v[164:167], v[80:83]
	v_mfma_f32_16x16x32_bf16 v[68:71], v[180:183], v[172:175], v[68:71]
	v_mfma_f32_16x16x32_bf16 v[64:67], v[206:209], v[172:175], v[64:67]
	s_mov_b32 m0, s35
	v_lshl_add_u64 v[214:215], s[28:29], 0, v[188:189]
	s_barrier
	s_setprio 0
	ds_read_b128 v[144:147], v242 offset:16384
	ds_read_b128 v[148:151], v242 offset:17408
	ds_read_b128 v[152:155], v242 offset:18432
	ds_read_b128 v[156:159], v242 offset:19456
	ds_read_b128 v[160:163], v242 offset:20480
	ds_read_b128 v[164:167], v242 offset:21504
	ds_read_b128 v[168:171], v242 offset:22528
	ds_read_b128 v[172:175], v242 offset:23552
	global_load_lds_dwordx4 v188, s[28:29]
	v_lshl_add_u64 v[216:217], s[28:29], 0, v[192:193]
	s_mov_b32 m0, s36
	s_nop 0
	global_load_lds_dwordx4 v192, s[28:29]
	s_waitcnt lgkmcnt(0)
	s_setprio 1
	s_barrier
	v_mfma_f32_16x16x32_bf16 v[60:63], v[128:131], v[144:147], v[60:63]
	v_mfma_f32_16x16x32_bf16 v[56:59], v[136:139], v[144:147], v[56:59]
	v_mfma_f32_16x16x32_bf16 v[44:47], v[128:131], v[152:155], v[44:47]
	v_mfma_f32_16x16x32_bf16 v[40:43], v[136:139], v[152:155], v[40:43]
	v_mfma_f32_16x16x32_bf16 v[28:31], v[128:131], v[160:163], v[28:31]
	v_mfma_f32_16x16x32_bf16 v[24:27], v[136:139], v[160:163], v[24:27]
	v_mfma_f32_16x16x32_bf16 v[12:15], v[128:131], v[168:171], v[12:15]
	v_mfma_f32_16x16x32_bf16 v[8:11], v[136:139], v[168:171], v[8:11]
	v_mfma_f32_16x16x32_bf16 v[60:63], v[132:135], v[148:151], v[60:63]
	v_mfma_f32_16x16x32_bf16 v[56:59], v[140:143], v[148:151], v[56:59]
	v_mfma_f32_16x16x32_bf16 v[44:47], v[132:135], v[156:159], v[44:47]
	v_mfma_f32_16x16x32_bf16 v[40:43], v[140:143], v[156:159], v[40:43]
	v_mfma_f32_16x16x32_bf16 v[28:31], v[132:135], v[164:167], v[28:31]
	v_mfma_f32_16x16x32_bf16 v[24:27], v[140:143], v[164:167], v[24:27]
	v_mfma_f32_16x16x32_bf16 v[12:15], v[132:135], v[172:175], v[12:15]
	v_mfma_f32_16x16x32_bf16 v[8:11], v[140:143], v[172:175], v[8:11]
	s_barrier
	s_setprio 0
	s_add_u32 s22, s26, 0xb0000
	s_addc_u32 s23, s27, 0
	s_add_i32 s57, s49, s34
	s_mov_b32 m0, s57
	s_nop 0
	global_load_lds_dwordx4 v190, s[22:23]
	s_add_i32 m0, s57, 0x2000
	s_nop 0
	global_load_lds_dwordx4 v194, s[22:23]
	s_add_u32 s22, s28, 0xb0000
	s_addc_u32 s23, s29, 0
	s_mov_b32 m0, s37
	s_nop 0
	global_load_lds_dwordx4 v188, s[22:23]
	s_mov_b32 m0, s38
	s_nop 0
	global_load_lds_dwordx4 v192, s[22:23]
	s_waitcnt vmcnt(10)
	s_setprio 1
	s_barrier
	v_mfma_f32_16x16x32_bf16 v[52:55], v[176:179], v[144:147], v[52:55]
	v_mfma_f32_16x16x32_bf16 v[48:51], v[184:187], v[144:147], v[48:51]
	v_mfma_f32_16x16x32_bf16 v[36:39], v[176:179], v[152:155], v[36:39]
	v_mfma_f32_16x16x32_bf16 v[32:35], v[184:187], v[152:155], v[32:35]
	v_mfma_f32_16x16x32_bf16 v[20:23], v[176:179], v[160:163], v[20:23]
	v_mfma_f32_16x16x32_bf16 v[16:19], v[184:187], v[160:163], v[16:19]
	v_mfma_f32_16x16x32_bf16 v[4:7], v[176:179], v[168:171], v[4:7]
	v_mfma_f32_16x16x32_bf16 v[0:3], v[184:187], v[168:171], v[0:3]
	v_mfma_f32_16x16x32_bf16 v[52:55], v[180:183], v[148:151], v[52:55]
	v_mfma_f32_16x16x32_bf16 v[48:51], v[206:209], v[148:151], v[48:51]
	v_mfma_f32_16x16x32_bf16 v[36:39], v[180:183], v[156:159], v[36:39]
	v_mfma_f32_16x16x32_bf16 v[32:35], v[206:209], v[156:159], v[32:35]
	v_mfma_f32_16x16x32_bf16 v[20:23], v[180:183], v[164:167], v[20:23]
	v_mfma_f32_16x16x32_bf16 v[16:19], v[206:209], v[164:167], v[16:19]
	v_mfma_f32_16x16x32_bf16 v[4:7], v[180:183], v[172:175], v[4:7]
	v_mfma_f32_16x16x32_bf16 v[0:3], v[206:209], v[172:175], v[0:3]
	s_add_i32 s57, 0, 0x18000
	v_add_u32_e32 v140, s57, v240
	s_barrier
	s_setprio 0
	ds_read_b128 v[128:131], v140
	ds_read_b128 v[132:135], v140 offset:1024
	ds_read_b128 v[136:139], v140 offset:2048
	ds_read_b128 v[140:143], v140 offset:3072
	ds_read_b128 v[144:147], v242 offset:32768
	ds_read_b128 v[148:151], v242 offset:33792
	ds_read_b128 v[152:155], v242 offset:34816
	ds_read_b128 v[156:159], v242 offset:35840
	ds_read_b128 v[160:163], v242 offset:36864
	ds_read_b128 v[164:167], v242 offset:37888
	ds_read_b128 v[168:171], v242 offset:38912
	ds_read_b128 v[172:175], v242 offset:39936
	s_waitcnt lgkmcnt(8)
	s_waitcnt vmcnt(8)
	s_waitcnt lgkmcnt(0)
	s_setprio 1
	s_barrier
; #define PG8_STAGE(bufoff, gbase, voff) do { _Pragma("unroll") for (int _i = 0; _i < 2; ++_i) \
;         __builtin_amdgcn_global_load_lds((const unsigned*)((const char*)(gbase) + (voff)[_i]), (LAS unsigned*)(lds + (bufoff) + ldsw + _i * 8192), 16, 0, 0); } while (0)
; #define PG8_LDA(dst, b, h) do { _Pragma("unroll") for (int m = 0; m < 4; ++m) _Pragma("unroll") for (int k = 0; k < 2; ++k) dst[m][k] = *(const LAS bf16x8*)(lds + PG8_SA(b, h) + aoff + m * 2048 + k * 1024); } while (0)
; #define PG8_LDB(dst, b, h) do { _Pragma("unroll") for (int n = 0; n < 2; ++n) _Pragma("unroll") for (int k = 0; k < 2; ++k) dst[n][k] = *(const LAS bf16x8*)(lds + PG8_SB(b, h) + boff + n * 2048 + k * 1024); } while (0)
; #define PG8_MMA(ai, bj, At, Bt) do { __builtin_amdgcn_s_setprio(1); _Pragma("unroll") for (int m = 0; m < 4; ++m) _Pragma("unroll") for (int n = 0; n < 2; ++n) _Pragma("unroll") for (int k = 0; k < 2; ++k) \
;         acc[ai][bj][m][n] = __builtin_amdgcn_mfma_f32_16x16x32_bf16(Bt[n][k], At[m][k], acc[ai][bj][m][n], 0, 0, 0); __builtin_amdgcn_s_setprio(0); } while (0)
; #define PG8_WAIT_V(n) asm volatile("s_waitcnt vmcnt(" #n ")" ::: "memory")
; #define PG8_WAIT_L(n) asm volatile("s_waitcnt lgkmcnt(" #n ")" ::: "memory")
; #define PG8_BAR __builtin_amdgcn_s_barrier()
; #define PG8_SCHED __builtin_amdgcn_sched_barrier(0)
; template <class Epi, class Sched>
; __device__ __forceinline__ void gemm_phase(LAS unsigned char* lds, const Gemm g, const Sched& S, const Epi& E) {
;     ...
;             PG8_WAIT_L(8); PG8_BAR; PG8_WAIT_L(0); PG8_MMA(0, 0, At, B0); PG8_BAR; PG8_SCHED;
;             PG8_LDB(B1, 1, 1); PG8_STAGE(PG8_SB(1, 0), b3, voffB);
;             PG8_BAR; PG8_WAIT_L(0); PG8_MMA(0, 1, At, B1); PG8_BAR;
;             PG8_LDA(At, 1, 1); PG8_STAGE(PG8_SA(1, 0), a3, voffA);
;             PG8_BAR; PG8_WAIT_L(0); PG8_MMA(1, 0, At, B0); PG8_BAR; PG8_SCHED;
;             PG8_STAGE(PG8_SB(1, 1), b3 + hstep, voffB);
;             PG8_WAIT_V(6); PG8_BAR; PG8_MMA(1, 1, At, B1); PG8_BAR;
	v_mfma_f32_16x16x32_bf16 v[124:127], v[128:131], v[144:147], v[124:127]
	v_mfma_f32_16x16x32_bf16 v[120:123], v[136:139], v[144:147], v[120:123]
	v_mfma_f32_16x16x32_bf16 v[108:111], v[128:131], v[152:155], v[108:111]
	v_mfma_f32_16x16x32_bf16 v[104:107], v[136:139], v[152:155], v[104:107]
	v_mfma_f32_16x16x32_bf16 v[92:95], v[128:131], v[160:163], v[92:95]
	v_mfma_f32_16x16x32_bf16 v[88:91], v[136:139], v[160:163], v[88:91]
	v_mfma_f32_16x16x32_bf16 v[76:79], v[128:131], v[168:171], v[76:79]
	v_mfma_f32_16x16x32_bf16 v[72:75], v[136:139], v[168:171], v[72:75]
	v_mfma_f32_16x16x32_bf16 v[124:127], v[132:135], v[148:151], v[124:127]
	v_mfma_f32_16x16x32_bf16 v[120:123], v[140:143], v[148:151], v[120:123]
	v_mfma_f32_16x16x32_bf16 v[108:111], v[132:135], v[156:159], v[108:111]
	v_mfma_f32_16x16x32_bf16 v[104:107], v[140:143], v[156:159], v[104:107]
	v_mfma_f32_16x16x32_bf16 v[92:95], v[132:135], v[164:167], v[92:95]
	v_mfma_f32_16x16x32_bf16 v[88:91], v[140:143], v[164:167], v[88:91]
	v_mfma_f32_16x16x32_bf16 v[76:79], v[132:135], v[172:175], v[76:79]
	v_mfma_f32_16x16x32_bf16 v[72:75], v[140:143], v[172:175], v[72:75]
	s_barrier
	s_setprio 0
	s_add_i32 s28, 0, 0x1c000
	s_add_i32 s22, s57, s34
	v_add_u32_e32 v206, s28, v240
	s_add_u32 s0, s26, 0x80
	s_addc_u32 s1, s27, 0
	s_mov_b32 m0, s22
	ds_read_b128 v[176:179], v206
	ds_read_b128 v[180:183], v206 offset:1024
	ds_read_b128 v[184:187], v206 offset:2048
	ds_read_b128 v[206:209], v206 offset:3072
	global_load_lds_dwordx4 v190, s[0:1]
	s_add_i32 m0, s22, 0x2000
	s_nop 0
	global_load_lds_dwordx4 v194, s[0:1]
	s_waitcnt vmcnt(8)
	s_waitcnt lgkmcnt(0)
	s_setprio 1
	s_barrier
	v_mfma_f32_16x16x32_bf16 v[116:119], v[176:179], v[144:147], v[116:119]
	v_mfma_f32_16x16x32_bf16 v[112:115], v[184:187], v[144:147], v[112:115]
	v_mfma_f32_16x16x32_bf16 v[100:103], v[176:179], v[152:155], v[100:103]
	v_mfma_f32_16x16x32_bf16 v[96:99], v[184:187], v[152:155], v[96:99]
	v_mfma_f32_16x16x32_bf16 v[84:87], v[176:179], v[160:163], v[84:87]
	v_mfma_f32_16x16x32_bf16 v[80:83], v[184:187], v[160:163], v[80:83]
	v_mfma_f32_16x16x32_bf16 v[68:71], v[176:179], v[168:171], v[68:71]
	v_mfma_f32_16x16x32_bf16 v[64:67], v[184:187], v[168:171], v[64:67]
	v_mfma_f32_16x16x32_bf16 v[116:119], v[180:183], v[148:151], v[116:119]
	v_mfma_f32_16x16x32_bf16 v[112:115], v[206:209], v[148:151], v[112:115]
	v_mfma_f32_16x16x32_bf16 v[100:103], v[180:183], v[156:159], v[100:103]
	v_mfma_f32_16x16x32_bf16 v[96:99], v[206:209], v[156:159], v[96:99]
	v_mfma_f32_16x16x32_bf16 v[84:87], v[180:183], v[164:167], v[84:87]
	v_mfma_f32_16x16x32_bf16 v[80:83], v[206:209], v[164:167], v[80:83]
	v_mfma_f32_16x16x32_bf16 v[68:71], v[180:183], v[172:175], v[68:71]
	v_mfma_f32_16x16x32_bf16 v[64:67], v[206:209], v[172:175], v[64:67]
	s_mov_b32 m0, s44
	s_mov_b64 s[0:1], 0x80
	v_lshl_add_u64 v[210:211], v[214:215], 0, s[0:1]
	s_barrier
	s_setprio 0
	ds_read_b128 v[144:147], v242 offset:49152
	ds_read_b128 v[148:151], v242 offset:50176
	ds_read_b128 v[152:155], v242 offset:51200
	ds_read_b128 v[156:159], v242 offset:52224
	ds_read_b128 v[160:163], v242 offset:53248
	ds_read_b128 v[164:167], v242 offset:54272
	ds_read_b128 v[168:171], v242 offset:55296
	ds_read_b128 v[172:175], v242 offset:56320
	global_load_lds_dwordx4 v[210:211], off
	v_lshl_add_u64 v[210:211], v[216:217], 0, s[0:1]
	s_mov_b32 m0, s45
	s_nop 0
	global_load_lds_dwordx4 v[210:211], off
	s_waitcnt lgkmcnt(0)
	s_setprio 1
	s_barrier
	v_mfma_f32_16x16x32_bf16 v[60:63], v[128:131], v[144:147], v[60:63]
	v_mfma_f32_16x16x32_bf16 v[56:59], v[136:139], v[144:147], v[56:59]
	v_mfma_f32_16x16x32_bf16 v[44:47], v[128:131], v[152:155], v[44:47]
	v_mfma_f32_16x16x32_bf16 v[40:43], v[136:139], v[152:155], v[40:43]
	v_mfma_f32_16x16x32_bf16 v[28:31], v[128:131], v[160:163], v[28:31]
	v_mfma_f32_16x16x32_bf16 v[24:27], v[136:139], v[160:163], v[24:27]
	v_mfma_f32_16x16x32_bf16 v[12:15], v[128:131], v[168:171], v[12:15]
	v_mfma_f32_16x16x32_bf16 v[8:11], v[136:139], v[168:171], v[8:11]
	v_mfma_f32_16x16x32_bf16 v[60:63], v[132:135], v[148:151], v[60:63]
	v_mfma_f32_16x16x32_bf16 v[56:59], v[140:143], v[148:151], v[56:59]
	v_mfma_f32_16x16x32_bf16 v[44:47], v[132:135], v[156:159], v[44:47]
	v_mfma_f32_16x16x32_bf16 v[40:43], v[140:143], v[156:159], v[40:43]
	v_mfma_f32_16x16x32_bf16 v[28:31], v[132:135], v[164:167], v[28:31]
	v_mfma_f32_16x16x32_bf16 v[24:27], v[140:143], v[164:167], v[24:27]
	v_mfma_f32_16x16x32_bf16 v[12:15], v[132:135], v[172:175], v[12:15]
	v_mfma_f32_16x16x32_bf16 v[8:11], v[140:143], v[172:175], v[8:11]
	s_barrier
	s_setprio 0
	s_add_u32 s22, s26, 0xb0080
	s_addc_u32 s23, s27, 0
	s_add_i32 s26, s28, s34
	s_mov_b32 m0, s26
	s_nop 0
	global_load_lds_dwordx4 v190, s[22:23]
	s_add_i32 m0, s26, 0x2000
	s_nop 0
	global_load_lds_dwordx4 v194, s[22:23]
	s_waitcnt vmcnt(8)
	s_setprio 1
	s_barrier
	v_mfma_f32_16x16x32_bf16 v[52:55], v[176:179], v[144:147], v[52:55]
	v_mfma_f32_16x16x32_bf16 v[48:51], v[184:187], v[144:147], v[48:51]
	v_mfma_f32_16x16x32_bf16 v[36:39], v[176:179], v[152:155], v[36:39]
	v_mfma_f32_16x16x32_bf16 v[32:35], v[184:187], v[152:155], v[32:35]
	v_mfma_f32_16x16x32_bf16 v[20:23], v[176:179], v[160:163], v[20:23]
	v_mfma_f32_16x16x32_bf16 v[16:19], v[184:187], v[160:163], v[16:19]
	v_mfma_f32_16x16x32_bf16 v[4:7], v[176:179], v[168:171], v[4:7]
	v_mfma_f32_16x16x32_bf16 v[0:3], v[184:187], v[168:171], v[0:3]
	v_mfma_f32_16x16x32_bf16 v[52:55], v[180:183], v[148:151], v[52:55]
	v_mfma_f32_16x16x32_bf16 v[48:51], v[206:209], v[148:151], v[48:51]
	v_mfma_f32_16x16x32_bf16 v[36:39], v[180:183], v[156:159], v[36:39]
	v_mfma_f32_16x16x32_bf16 v[32:35], v[206:209], v[156:159], v[32:35]
	v_mfma_f32_16x16x32_bf16 v[20:23], v[180:183], v[164:167], v[20:23]
	v_mfma_f32_16x16x32_bf16 v[16:19], v[206:209], v[164:167], v[16:19]
	v_mfma_f32_16x16x32_bf16 v[4:7], v[180:183], v[172:175], v[4:7]
	v_mfma_f32_16x16x32_bf16 v[0:3], v[206:209], v[172:175], v[0:3]
	s_add_i32 s56, s56, 2
	s_add_u32 s54, s54, 0x100
	s_addc_u32 s55, s55, 0
	s_cmp_gt_u32 s56, 41
	s_mov_b64 s[22:23], s[24:25]
	s_barrier
; __device__ __forceinline__ unsigned cvt_pk_bf16(float lo, float hi) { unsigned r; asm volatile("v_cvt_pk_bf16_f32 %0, %1, %2" : "=v"(r) : "v"(lo), "v"(hi)); return r; }
; __device__ __forceinline__ float bf_lo(unsigned u) { return __uint_as_float(u << 16); }
; __device__ __forceinline__ float bf_hi(unsigned u) { return __uint_as_float(u & 0xffff0000u); }
;     __device__ __forceinline__ void operator()(const AccT& acc, const Unit& u, int wr, int wc, int fr, int fq) const {
;         asm volatile("" : "+v"(fr), "+v"(fq));
;         const int rowt = u.pm * 256; const int b = rowt >> 11;
;         const bf16_t* res = res_b + (size_t)rowt * DM; bf16_t* out = hb + (size_t)rowt * DM;
;         const int col0 = u.pn * 256 + wc * 32 + 8 * fq;
;         f32x4 gv[2][2];
; #pragma unroll
;         for (int bj = 0; bj < 2; ++bj)
; #pragma unroll
;             for (int n = 0; n < 2; ++n) gv[bj][n] = *(const f32x4*)(gate + (size_t)b * NMOD + col0 + bj * 128 + n * 4) * gs;
;         u32x4 r[2][4][2];
; #pragma unroll
;         for (int ai = 0; ai < 2; ++ai)
; #pragma unroll
;             for (int m = 0; m < 4; ++m)
; #pragma unroll
;                 for (int bj = 0; bj < 2; ++bj) r[ai][m][bj] = *(const u32x4*)(res + (size_t)(wr * 64 + fr + ai * 128 + m * 16) * DM + col0 + bj * 128);
; #pragma unroll
;         for (int ai = 0; ai < 2; ++ai)
; #pragma unroll
;             for (int m = 0; m < 4; ++m)
; #pragma unroll
;                 for (int bj = 0; bj < 2; ++bj) {
;                     const u32x4 q = r[ai][m][bj];
;                     const f32x4 r0 = {bf_lo(q.x), bf_hi(q.x), bf_lo(q.y), bf_hi(q.y)}, r1 = {bf_lo(q.z), bf_hi(q.z), bf_lo(q.w), bf_hi(q.w)};
;                     const f32x4 h0 = r0 + gv[bj][0] * acc[ai][bj][m][0], h1 = r1 + gv[bj][1] * acc[ai][bj][m][1];
;                     u32x4 w; w.x = cvt_pk_bf16(h0[0], h0[1]); w.y = cvt_pk_bf16(h0[2], h0[3]); w.z = cvt_pk_bf16(h1[0], h1[1]); w.w = cvt_pk_bf16(h1[2], h1[3]);
;                     *(u32x4*)(out + (size_t)(wr * 64 + fr + ai * 128 + m * 16) * DM + col0 + bj * 128) = w;
;                 }
	s_setprio 0
	s_cbranch_scc0 .LBB0_1097
	s_lshl_b32 s25, s52, 8
	v_mov_b32_e32 v140, v239
	v_mov_b32_e32 v128, v238
	s_lshl_b32 s22, s53, 8
	s_ashr_i32 s24, s53, 3
	s_or_b32 s25, s25, s43
	s_ashr_i32 s23, s22, 31
	v_lshl_add_u32 v136, v128, 3, s25
	s_mul_hi_i32 s25, s24, 0x9000
	s_mul_i32 s24, s24, 0x9000
	s_add_u32 s24, s40, s24
	s_addc_u32 s25, s41, s25
	v_ashrrev_i32_e32 v137, 31, v136
	v_lshl_add_u64 v[138:139], v[136:137], 2, s[24:25]
	global_load_dwordx4 v[128:131], v[138:139], off offset:16
	global_load_dwordx4 v[132:135], v[138:139], off
	s_lshl_b64 s[22:23], s[22:23], 11
	s_add_u32 s24, s80, s22
	s_addc_u32 s25, s81, s23
	v_lshlrev_b64 v[226:227], 1, v[136:137]
	s_add_u32 s22, s96, s22
	s_addc_u32 s23, s97, s23
	s_and_b64 vcc, exec, s[2:3]
	s_mov_b32 s52, s50
	s_mov_b32 s53, s51
	s_waitcnt vmcnt(0)
	v_pk_mul_f32 v[216:217], v[130:131], 0.5 op_sel_hi:[1,0]
	v_pk_mul_f32 v[220:221], v[134:135], 0.5 op_sel_hi:[1,0]
	v_pk_mul_f32 v[218:219], v[132:133], 0.5 op_sel_hi:[1,0]
	v_pk_mul_f32 v[214:215], v[128:129], 0.5 op_sel_hi:[1,0]
	global_load_dwordx4 v[128:131], v[138:139], off offset:528
	global_load_dwordx4 v[132:135], v[138:139], off offset:512
	s_waitcnt vmcnt(0)
	v_pk_mul_f32 v[206:207], v[128:129], 0.5 op_sel_hi:[1,0]
	v_add_u32_e32 v128, s42, v140
	v_ashrrev_i32_e32 v129, 31, v128
	v_pk_mul_f32 v[208:209], v[130:131], 0.5 op_sel_hi:[1,0]
	v_lshl_add_u64 v[130:131], s[24:25], 0, v[226:227]
	v_lshlrev_b64 v[248:249], 11, v[128:129]
	v_lshl_add_u64 v[128:129], v[130:131], 0, v[248:249]
	global_load_dwordx4 v[244:247], v[128:129], off
	global_load_dwordx4 v[184:187], v[128:129], off offset:256
	v_lshl_add_u64 v[236:237], v[248:249], 0, s[8:9]
	v_lshl_add_u64 v[128:129], v[130:131], 0, v[236:237]
	global_load_dwordx4 v[180:183], v[128:129], off
	global_load_dwordx4 v[176:179], v[128:129], off offset:256
	v_lshl_add_u64 v[234:235], v[248:249], 0, s[10:11]
	v_lshl_add_u64 v[128:129], v[130:131], 0, v[234:235]
	global_load_dwordx4 v[172:175], v[128:129], off
	global_load_dwordx4 v[168:171], v[128:129], off offset:256
	v_lshl_add_u64 v[232:233], v[248:249], 0, s[12:13]
	v_lshl_add_u64 v[128:129], v[130:131], 0, v[232:233]
	global_load_dwordx4 v[164:167], v[128:129], off
	global_load_dwordx4 v[160:163], v[128:129], off offset:256
	v_lshl_add_u64 v[230:231], v[248:249], 0, s[14:15]
	v_lshl_add_u64 v[128:129], v[130:131], 0, v[230:231]
	global_load_dwordx4 v[156:159], v[128:129], off
	global_load_dwordx4 v[152:155], v[128:129], off offset:256
	v_lshl_add_u64 v[228:229], v[248:249], 0, s[16:17]
	v_lshl_add_u64 v[128:129], v[130:131], 0, v[228:229]
	global_load_dwordx4 v[148:151], v[128:129], off
	global_load_dwordx4 v[144:147], v[128:129], off offset:256
	v_lshl_add_u64 v[224:225], v[248:249], 0, s[18:19]
	v_lshl_add_u64 v[128:129], v[130:131], 0, v[224:225]
	global_load_dwordx4 v[140:143], v[128:129], off
	global_load_dwordx4 v[136:139], v[128:129], off offset:256
	v_lshl_add_u64 v[222:223], v[248:249], 0, s[20:21]
	v_lshl_add_u64 v[128:129], v[130:131], 0, v[222:223]
	v_pk_mul_f32 v[212:213], v[134:135], 0.5 op_sel_hi:[1,0]
	v_pk_mul_f32 v[210:211], v[132:133], 0.5 op_sel_hi:[1,0]
	global_load_dwordx4 v[132:135], v[128:129], off
	s_nop 0
	global_load_dwordx4 v[128:131], v[128:129], off offset:256
	v_lshl_add_u64 v[226:227], s[22:23], 0, v[226:227]
	v_lshl_add_u64 v[248:249], v[226:227], 0, v[248:249]
	s_mov_b64 s[24:25], s[6:7]
	s_mov_b64 s[22:23], s[4:5]
	s_waitcnt vmcnt(0)
	v_lshlrev_b32_e32 v250, 16, v244
	v_and_b32_e32 v251, 0xffff0000, v244
	v_lshlrev_b32_e32 v244, 16, v245
	v_and_b32_e32 v245, 0xffff0000, v245
	v_lshlrev_b32_e32 v252, 16, v246
	v_and_b32_e32 v253, 0xffff0000, v246
	v_lshlrev_b32_e32 v246, 16, v247
	v_and_b32_e32 v247, 0xffff0000, v247
	v_pk_fma_f32 v[126:127], v[126:127], v[220:221], v[244:245]
	v_pk_fma_f32 v[124:125], v[124:125], v[218:219], v[250:251]
	v_pk_fma_f32 v[244:245], v[122:123], v[216:217], v[246:247]
	v_pk_fma_f32 v[122:123], v[120:121], v[214:215], v[252:253]
	v_cvt_pk_bf16_f32 v120, v124, v125
	v_cvt_pk_bf16_f32 v121, v126, v127
	v_lshlrev_b32_e32 v124, 16, v186
	v_cvt_pk_bf16_f32 v122, v122, v123
	v_cvt_pk_bf16_f32 v123, v244, v245
	global_store_dwordx4 v[248:249], v[120:123], off
	v_and_b32_e32 v125, 0xffff0000, v186
	v_lshlrev_b32_e32 v126, 16, v187
	v_lshlrev_b32_e32 v120, 16, v184
	v_and_b32_e32 v121, 0xffff0000, v184
	v_and_b32_e32 v127, 0xffff0000, v187
	v_lshlrev_b32_e32 v122, 16, v185
	v_and_b32_e32 v123, 0xffff0000, v185
	v_pk_fma_f32 v[116:117], v[116:117], v[210:211], v[120:121]
	v_pk_fma_f32 v[120:121], v[114:115], v[208:209], v[126:127]
	v_pk_fma_f32 v[114:115], v[112:113], v[206:207], v[124:125]
	v_pk_fma_f32 v[118:119], v[118:119], v[212:213], v[122:123]
	v_cvt_pk_bf16_f32 v112, v116, v117
	v_lshlrev_b32_e32 v116, 16, v181
	v_cvt_pk_bf16_f32 v113, v118, v119
	v_cvt_pk_bf16_f32 v114, v114, v115
	v_cvt_pk_bf16_f32 v115, v120, v121
	global_store_dwordx4 v[248:249], v[112:115], off offset:256
	v_and_b32_e32 v117, 0xffff0000, v181
	v_lshlrev_b32_e32 v118, 16, v182
	v_lshlrev_b32_e32 v114, 16, v180
	v_and_b32_e32 v115, 0xffff0000, v180
	v_and_b32_e32 v119, 0xffff0000, v182
	v_lshlrev_b32_e32 v120, 16, v183
	v_and_b32_e32 v121, 0xffff0000, v183
	v_lshl_add_u64 v[112:113], v[226:227], 0, v[236:237]
	v_pk_fma_f32 v[110:111], v[110:111], v[220:221], v[116:117]
	v_pk_fma_f32 v[108:109], v[108:109], v[218:219], v[114:115]
	v_pk_fma_f32 v[114:115], v[106:107], v[216:217], v[120:121]
	v_pk_fma_f32 v[106:107], v[104:105], v[214:215], v[118:119]
	v_cvt_pk_bf16_f32 v104, v108, v109
	v_cvt_pk_bf16_f32 v105, v110, v111
	v_lshlrev_b32_e32 v108, 16, v178
	v_cvt_pk_bf16_f32 v106, v106, v107
; __device__ __forceinline__ unsigned cvt_pk_bf16(float lo, float hi) { unsigned r; asm volatile("v_cvt_pk_bf16_f32 %0, %1, %2" : "=v"(r) : "v"(lo), "v"(hi)); return r; }
; __device__ __forceinline__ float bf_lo(unsigned u) { return __uint_as_float(u << 16); }
; __device__ __forceinline__ float bf_hi(unsigned u) { return __uint_as_float(u & 0xffff0000u); }
;     __device__ __forceinline__ void operator()(const AccT& acc, const Unit& u, int wr, int wc, int fr, int fq) const {
;     ...
;         for (int ai = 0; ai < 2; ++ai)
; #pragma unroll
;             for (int m = 0; m < 4; ++m)
; #pragma unroll
;                 for (int bj = 0; bj < 2; ++bj) {
;                     const u32x4 q = r[ai][m][bj];
;                     const f32x4 r0 = {bf_lo(q.x), bf_hi(q.x), bf_lo(q.y), bf_hi(q.y)}, r1 = {bf_lo(q.z), bf_hi(q.z), bf_lo(q.w), bf_hi(q.w)};
;                     const f32x4 h0 = r0 + gv[bj][0] * acc[ai][bj][m][0], h1 = r1 + gv[bj][1] * acc[ai][bj][m][1];
;                     u32x4 w; w.x = cvt_pk_bf16(h0[0], h0[1]); w.y = cvt_pk_bf16(h0[2], h0[3]); w.z = cvt_pk_bf16(h1[0], h1[1]); w.w = cvt_pk_bf16(h1[2], h1[3]);
;                     *(u32x4*)(out + (size_t)(wr * 64 + fr + ai * 128 + m * 16) * DM + col0 + bj * 128) = w;
;                 }
	v_cvt_pk_bf16_f32 v107, v114, v115
	global_store_dwordx4 v[112:113], v[104:107], off
	v_and_b32_e32 v109, 0xffff0000, v178
	v_lshlrev_b32_e32 v110, 16, v179
	v_lshlrev_b32_e32 v104, 16, v176
	v_and_b32_e32 v105, 0xffff0000, v176
	v_and_b32_e32 v111, 0xffff0000, v179
	v_lshlrev_b32_e32 v106, 16, v177
	v_and_b32_e32 v107, 0xffff0000, v177
	v_pk_fma_f32 v[100:101], v[100:101], v[210:211], v[104:105]
	v_pk_fma_f32 v[104:105], v[98:99], v[208:209], v[110:111]
	v_pk_fma_f32 v[98:99], v[96:97], v[206:207], v[108:109]
	v_pk_fma_f32 v[102:103], v[102:103], v[212:213], v[106:107]
	v_cvt_pk_bf16_f32 v96, v100, v101
	v_lshlrev_b32_e32 v100, 16, v173
	v_cvt_pk_bf16_f32 v97, v102, v103
	v_cvt_pk_bf16_f32 v98, v98, v99
	v_cvt_pk_bf16_f32 v99, v104, v105
	global_store_dwordx4 v[112:113], v[96:99], off offset:256
	v_and_b32_e32 v101, 0xffff0000, v173
	v_lshlrev_b32_e32 v102, 16, v174
	v_lshlrev_b32_e32 v98, 16, v172
	v_and_b32_e32 v99, 0xffff0000, v172
	v_and_b32_e32 v103, 0xffff0000, v174
	v_lshlrev_b32_e32 v104, 16, v175
	v_and_b32_e32 v105, 0xffff0000, v175
	v_lshl_add_u64 v[96:97], v[226:227], 0, v[234:235]
	v_pk_fma_f32 v[94:95], v[94:95], v[220:221], v[100:101]
	v_pk_fma_f32 v[92:93], v[92:93], v[218:219], v[98:99]
	v_pk_fma_f32 v[98:99], v[90:91], v[216:217], v[104:105]
	v_pk_fma_f32 v[90:91], v[88:89], v[214:215], v[102:103]
	v_cvt_pk_bf16_f32 v88, v92, v93
	v_cvt_pk_bf16_f32 v89, v94, v95
	v_lshlrev_b32_e32 v92, 16, v170
	v_cvt_pk_bf16_f32 v90, v90, v91
	v_cvt_pk_bf16_f32 v91, v98, v99
	global_store_dwordx4 v[96:97], v[88:91], off
	v_and_b32_e32 v93, 0xffff0000, v170
	v_lshlrev_b32_e32 v94, 16, v171
	v_lshlrev_b32_e32 v88, 16, v168
	v_and_b32_e32 v89, 0xffff0000, v168
	v_and_b32_e32 v95, 0xffff0000, v171
	v_lshlrev_b32_e32 v90, 16, v169
	v_and_b32_e32 v91, 0xffff0000, v169
	v_pk_fma_f32 v[84:85], v[84:85], v[210:211], v[88:89]
	v_pk_fma_f32 v[88:89], v[82:83], v[208:209], v[94:95]
	v_pk_fma_f32 v[82:83], v[80:81], v[206:207], v[92:93]
	v_pk_fma_f32 v[86:87], v[86:87], v[212:213], v[90:91]
	v_cvt_pk_bf16_f32 v80, v84, v85
	v_lshlrev_b32_e32 v84, 16, v165
	v_cvt_pk_bf16_f32 v81, v86, v87
	v_cvt_pk_bf16_f32 v82, v82, v83
	v_cvt_pk_bf16_f32 v83, v88, v89
	global_store_dwordx4 v[96:97], v[80:83], off offset:256
	v_and_b32_e32 v85, 0xffff0000, v165
	v_lshlrev_b32_e32 v86, 16, v166
	v_lshlrev_b32_e32 v82, 16, v164
	v_and_b32_e32 v83, 0xffff0000, v164
	v_and_b32_e32 v87, 0xffff0000, v166
	v_lshlrev_b32_e32 v88, 16, v167
	v_and_b32_e32 v89, 0xffff0000, v167
	v_lshl_add_u64 v[80:81], v[226:227], 0, v[232:233]
	v_pk_fma_f32 v[78:79], v[78:79], v[220:221], v[84:85]
	v_pk_fma_f32 v[76:77], v[76:77], v[218:219], v[82:83]
	v_pk_fma_f32 v[82:83], v[74:75], v[216:217], v[88:89]
	v_pk_fma_f32 v[74:75], v[72:73], v[214:215], v[86:87]
	v_cvt_pk_bf16_f32 v72, v76, v77
	v_cvt_pk_bf16_f32 v73, v78, v79
	v_lshlrev_b32_e32 v76, 16, v162
	v_cvt_pk_bf16_f32 v74, v74, v75
	v_cvt_pk_bf16_f32 v75, v82, v83
	global_store_dwordx4 v[80:81], v[72:75], off
	v_and_b32_e32 v77, 0xffff0000, v162
	v_lshlrev_b32_e32 v78, 16, v163
	v_lshlrev_b32_e32 v72, 16, v160
	v_and_b32_e32 v73, 0xffff0000, v160
	v_and_b32_e32 v79, 0xffff0000, v163
	v_lshlrev_b32_e32 v74, 16, v161
	v_and_b32_e32 v75, 0xffff0000, v161
	v_pk_fma_f32 v[68:69], v[68:69], v[210:211], v[72:73]
	v_pk_fma_f32 v[72:73], v[66:67], v[208:209], v[78:79]
	v_pk_fma_f32 v[66:67], v[64:65], v[206:207], v[76:77]
	v_pk_fma_f32 v[70:71], v[70:71], v[212:213], v[74:75]
	v_cvt_pk_bf16_f32 v64, v68, v69
	v_lshlrev_b32_e32 v68, 16, v157
	v_cvt_pk_bf16_f32 v65, v70, v71
	v_cvt_pk_bf16_f32 v66, v66, v67
	v_cvt_pk_bf16_f32 v67, v72, v73
	global_store_dwordx4 v[80:81], v[64:67], off offset:256
	v_and_b32_e32 v69, 0xffff0000, v157
	v_lshlrev_b32_e32 v70, 16, v158
	v_lshlrev_b32_e32 v66, 16, v156
	v_and_b32_e32 v67, 0xffff0000, v156
	v_and_b32_e32 v71, 0xffff0000, v158
	v_lshlrev_b32_e32 v72, 16, v159
	v_and_b32_e32 v73, 0xffff0000, v159
	v_lshl_add_u64 v[64:65], v[226:227], 0, v[230:231]
	v_pk_fma_f32 v[62:63], v[62:63], v[220:221], v[68:69]
	v_pk_fma_f32 v[60:61], v[60:61], v[218:219], v[66:67]
	v_pk_fma_f32 v[66:67], v[58:59], v[216:217], v[72:73]
	v_pk_fma_f32 v[58:59], v[56:57], v[214:215], v[70:71]
	v_cvt_pk_bf16_f32 v56, v60, v61
	v_cvt_pk_bf16_f32 v57, v62, v63
	v_lshlrev_b32_e32 v60, 16, v154
	v_cvt_pk_bf16_f32 v58, v58, v59
	v_cvt_pk_bf16_f32 v59, v66, v67
	global_store_dwordx4 v[64:65], v[56:59], off
	v_and_b32_e32 v61, 0xffff0000, v154
	v_lshlrev_b32_e32 v62, 16, v155
	v_lshlrev_b32_e32 v56, 16, v152
	v_and_b32_e32 v57, 0xffff0000, v152
	v_and_b32_e32 v63, 0xffff0000, v155
	v_lshlrev_b32_e32 v58, 16, v153
	v_and_b32_e32 v59, 0xffff0000, v153
	v_pk_fma_f32 v[52:53], v[52:53], v[210:211], v[56:57]
; __device__ __forceinline__ unsigned cvt_pk_bf16(float lo, float hi) { unsigned r; asm volatile("v_cvt_pk_bf16_f32 %0, %1, %2" : "=v"(r) : "v"(lo), "v"(hi)); return r; }
; __device__ __forceinline__ float bf_lo(unsigned u) { return __uint_as_float(u << 16); }
; __device__ __forceinline__ float bf_hi(unsigned u) { return __uint_as_float(u & 0xffff0000u); }
; #define PG8_WAIT_V(n) asm volatile("s_waitcnt vmcnt(" #n ")" ::: "memory")
; #define PG8_BAR __builtin_amdgcn_s_barrier()
; template <class Epi, class Sched>
; __device__ __forceinline__ void gemm_phase(LAS unsigned char* lds, const Gemm g, const Sched& S, const Epi& E) {
;     ...
;         E(acc, cur, wr, wc, fr, fq);
;         if (!has_next) break;
; #pragma unroll
;         for (int a = 0; a < 2; ++a)
; #pragma unroll
;             for (int b = 0; b < 2; ++b)
; #pragma unroll
;                 for (int m = 0; m < 4; ++m)
; #pragma unroll
;                     for (int n = 0; n < 2; ++n) acc[a][b][m][n] = (f32x4){0.f, 0.f, 0.f, 0.f};
;         cur = nxt; cA = nA; cB = nB; ++ui;
;     }
;     PG8_WAIT_V(0);
;     if (wr == 0) PG8_BAR;
;     PG8_BAR;
;     __device__ __forceinline__ void operator()(const AccT& acc, const Unit& u, int wr, int wc, int fr, int fq) const {
;     ...
;         for (int ai = 0; ai < 2; ++ai)
; #pragma unroll
;             for (int m = 0; m < 4; ++m)
; #pragma unroll
;                 for (int bj = 0; bj < 2; ++bj) {
;                     const u32x4 q = r[ai][m][bj];
;                     const f32x4 r0 = {bf_lo(q.x), bf_hi(q.x), bf_lo(q.y), bf_hi(q.y)}, r1 = {bf_lo(q.z), bf_hi(q.z), bf_lo(q.w), bf_hi(q.w)};
;                     const f32x4 h0 = r0 + gv[bj][0] * acc[ai][bj][m][0], h1 = r1 + gv[bj][1] * acc[ai][bj][m][1];
;                     u32x4 w; w.x = cvt_pk_bf16(h0[0], h0[1]); w.y = cvt_pk_bf16(h0[2], h0[3]); w.z = cvt_pk_bf16(h1[0], h1[1]); w.w = cvt_pk_bf16(h1[2], h1[3]);
;                     *(u32x4*)(out + (size_t)(wr * 64 + fr + ai * 128 + m * 16) * DM + col0 + bj * 128) = w;
;                 }
	v_pk_fma_f32 v[56:57], v[50:51], v[208:209], v[62:63]
	v_pk_fma_f32 v[50:51], v[48:49], v[206:207], v[60:61]
	v_pk_fma_f32 v[54:55], v[54:55], v[212:213], v[58:59]
	v_cvt_pk_bf16_f32 v48, v52, v53
	v_lshlrev_b32_e32 v52, 16, v149
	v_cvt_pk_bf16_f32 v49, v54, v55
	v_cvt_pk_bf16_f32 v50, v50, v51
	v_cvt_pk_bf16_f32 v51, v56, v57
	global_store_dwordx4 v[64:65], v[48:51], off offset:256
	v_and_b32_e32 v53, 0xffff0000, v149
	v_lshlrev_b32_e32 v54, 16, v150
	v_lshlrev_b32_e32 v50, 16, v148
	v_and_b32_e32 v51, 0xffff0000, v148
	v_and_b32_e32 v55, 0xffff0000, v150
	v_lshlrev_b32_e32 v56, 16, v151
	v_and_b32_e32 v57, 0xffff0000, v151
	v_lshl_add_u64 v[48:49], v[226:227], 0, v[228:229]
	v_pk_fma_f32 v[46:47], v[46:47], v[220:221], v[52:53]
	v_pk_fma_f32 v[44:45], v[44:45], v[218:219], v[50:51]
	v_pk_fma_f32 v[50:51], v[42:43], v[216:217], v[56:57]
	v_pk_fma_f32 v[42:43], v[40:41], v[214:215], v[54:55]
	v_cvt_pk_bf16_f32 v40, v44, v45
	v_cvt_pk_bf16_f32 v41, v46, v47
	v_lshlrev_b32_e32 v44, 16, v146
	v_cvt_pk_bf16_f32 v42, v42, v43
	v_cvt_pk_bf16_f32 v43, v50, v51
	global_store_dwordx4 v[48:49], v[40:43], off
	v_and_b32_e32 v45, 0xffff0000, v146
	v_lshlrev_b32_e32 v46, 16, v147
	v_lshlrev_b32_e32 v40, 16, v144
	v_and_b32_e32 v41, 0xffff0000, v144
	v_and_b32_e32 v47, 0xffff0000, v147
	v_lshlrev_b32_e32 v42, 16, v145
	v_and_b32_e32 v43, 0xffff0000, v145
	v_pk_fma_f32 v[36:37], v[36:37], v[210:211], v[40:41]
	v_pk_fma_f32 v[40:41], v[34:35], v[208:209], v[46:47]
	v_pk_fma_f32 v[34:35], v[32:33], v[206:207], v[44:45]
	v_pk_fma_f32 v[38:39], v[38:39], v[212:213], v[42:43]
	v_cvt_pk_bf16_f32 v32, v36, v37
	v_lshlrev_b32_e32 v36, 16, v141
	v_cvt_pk_bf16_f32 v33, v38, v39
	v_cvt_pk_bf16_f32 v34, v34, v35
	v_cvt_pk_bf16_f32 v35, v40, v41
	global_store_dwordx4 v[48:49], v[32:35], off offset:256
	v_and_b32_e32 v37, 0xffff0000, v141
	v_lshlrev_b32_e32 v38, 16, v142
	v_lshlrev_b32_e32 v34, 16, v140
	v_and_b32_e32 v35, 0xffff0000, v140
	v_and_b32_e32 v39, 0xffff0000, v142
	v_lshlrev_b32_e32 v40, 16, v143
	v_and_b32_e32 v41, 0xffff0000, v143
	v_lshl_add_u64 v[32:33], v[226:227], 0, v[224:225]
	v_pk_fma_f32 v[30:31], v[30:31], v[220:221], v[36:37]
	v_pk_fma_f32 v[28:29], v[28:29], v[218:219], v[34:35]
	v_pk_fma_f32 v[34:35], v[26:27], v[216:217], v[40:41]
	v_pk_fma_f32 v[26:27], v[24:25], v[214:215], v[38:39]
	v_cvt_pk_bf16_f32 v24, v28, v29
	v_cvt_pk_bf16_f32 v25, v30, v31
	v_lshlrev_b32_e32 v28, 16, v138
	v_cvt_pk_bf16_f32 v26, v26, v27
	v_cvt_pk_bf16_f32 v27, v34, v35
	global_store_dwordx4 v[32:33], v[24:27], off
	v_and_b32_e32 v29, 0xffff0000, v138
	v_lshlrev_b32_e32 v30, 16, v139
	v_lshlrev_b32_e32 v24, 16, v136
	v_and_b32_e32 v25, 0xffff0000, v136
	v_and_b32_e32 v31, 0xffff0000, v139
	v_lshlrev_b32_e32 v26, 16, v137
	v_and_b32_e32 v27, 0xffff0000, v137
	v_pk_fma_f32 v[20:21], v[20:21], v[210:211], v[24:25]
	v_pk_fma_f32 v[24:25], v[18:19], v[208:209], v[30:31]
	v_pk_fma_f32 v[18:19], v[16:17], v[206:207], v[28:29]
	v_pk_fma_f32 v[22:23], v[22:23], v[212:213], v[26:27]
	v_cvt_pk_bf16_f32 v16, v20, v21
	v_lshlrev_b32_e32 v20, 16, v133
	v_cvt_pk_bf16_f32 v17, v22, v23
	v_cvt_pk_bf16_f32 v18, v18, v19
	v_cvt_pk_bf16_f32 v19, v24, v25
	global_store_dwordx4 v[32:33], v[16:19], off offset:256
	v_and_b32_e32 v21, 0xffff0000, v133
	v_lshlrev_b32_e32 v22, 16, v134
	v_lshlrev_b32_e32 v18, 16, v132
	v_and_b32_e32 v19, 0xffff0000, v132
	v_and_b32_e32 v23, 0xffff0000, v134
	v_lshlrev_b32_e32 v24, 16, v135
	v_and_b32_e32 v25, 0xffff0000, v135
	v_lshl_add_u64 v[16:17], v[226:227], 0, v[222:223]
	v_pk_fma_f32 v[14:15], v[14:15], v[220:221], v[20:21]
	v_pk_fma_f32 v[12:13], v[12:13], v[218:219], v[18:19]
	v_pk_fma_f32 v[18:19], v[10:11], v[216:217], v[24:25]
	v_pk_fma_f32 v[10:11], v[8:9], v[214:215], v[22:23]
	v_cvt_pk_bf16_f32 v8, v12, v13
	v_cvt_pk_bf16_f32 v9, v14, v15
	v_lshlrev_b32_e32 v12, 16, v130
	v_cvt_pk_bf16_f32 v10, v10, v11
	v_cvt_pk_bf16_f32 v11, v18, v19
	global_store_dwordx4 v[16:17], v[8:11], off
	v_and_b32_e32 v13, 0xffff0000, v130
	v_lshlrev_b32_e32 v14, 16, v131
	v_lshlrev_b32_e32 v8, 16, v128
	v_and_b32_e32 v9, 0xffff0000, v128
	v_and_b32_e32 v15, 0xffff0000, v131
	v_lshlrev_b32_e32 v10, 16, v129
	v_and_b32_e32 v11, 0xffff0000, v129
	v_pk_fma_f32 v[4:5], v[4:5], v[210:211], v[8:9]
	v_pk_fma_f32 v[8:9], v[2:3], v[208:209], v[14:15]
	v_pk_fma_f32 v[2:3], v[0:1], v[206:207], v[12:13]
	v_pk_fma_f32 v[6:7], v[6:7], v[212:213], v[10:11]
	v_cvt_pk_bf16_f32 v0, v4, v5
	s_nop 0
	v_cvt_pk_bf16_f32 v1, v6, v7
	v_cvt_pk_bf16_f32 v2, v2, v3
	v_cvt_pk_bf16_f32 v3, v8, v9
	global_store_dwordx4 v[16:17], v[0:3], off offset:256
	s_cbranch_vccz .LBB0_1086
	s_waitcnt vmcnt(0)
	s_cmpk_gt_u32 s30, 0xff
	s_cbranch_scc1 .LBB0_1101
	s_barrier
